# k21 + FFT code: 110 SGPR-pair twiddle constants used directly as packed-f32 operands (v_mov_b64 to a VGPR pair deleted)
# speedup vs baseline: 1.0022x; 1.0022x over previous
.LBB0_1267:
	s_or_b64 exec, exec, s[0:1]
	s_waitcnt lgkmcnt(1)
	ds_read_b64 v[40:41], v144 offset:19584
	ds_read_b64 v[62:63], v149 offset:19584
	s_and_saveexec_b64 s[0:1], s[4:5]
	s_xor_b64 s[0:1], exec, s[0:1]
	s_cbranch_execz .LBB0_1269
	s_mov_b32 s6, s19
	s_mov_b32 s7, s57
	s_waitcnt lgkmcnt(2)
	v_pk_mul_f32 v[64:65], v[38:39], s[6:7] op_sel:[0,0] op_sel_hi:[0,1]
	s_waitcnt lgkmcnt(0)
	v_sub_f32_e32 v40, v62, v40
	v_pk_fma_f32 v[60:61], v[38:39], s[6:7], v[64:65] op_sel:[1,1,0] op_sel_hi:[1,0,1] neg_lo:[0,1,0]
	s_nop 0
	v_pk_mul_f32 v[60:61], v[40:41], v[60:61] op_sel_hi:[0,1]

.LBB0_1271:
	s_or_b64 exec, exec, s[0:1]
	s_waitcnt lgkmcnt(1)
	ds_read_b64 v[40:41], v144 offset:21760
	ds_read_b64 v[64:65], v149 offset:21760
	s_and_saveexec_b64 s[0:1], s[4:5]
	s_xor_b64 s[0:1], exec, s[0:1]
	s_cbranch_execz .LBB0_1273
	s_mov_b32 s6, s21
	s_mov_b32 s7, s55
	s_waitcnt lgkmcnt(2)
	v_pk_mul_f32 v[66:67], v[38:39], s[6:7] op_sel:[0,0] op_sel_hi:[0,1]
	s_waitcnt lgkmcnt(0)
	v_sub_f32_e32 v40, v64, v40
	v_pk_fma_f32 v[62:63], v[38:39], s[6:7], v[66:67] op_sel:[1,1,0] op_sel_hi:[1,0,1] neg_lo:[0,1,0]
	s_nop 0
	v_pk_mul_f32 v[62:63], v[40:41], v[62:63] op_sel_hi:[0,1]

.LBB0_1275:
	s_or_b64 exec, exec, s[0:1]
	s_waitcnt lgkmcnt(1)
	ds_read_b64 v[40:41], v144 offset:23936
	ds_read_b64 v[66:67], v149 offset:23936
	s_and_saveexec_b64 s[0:1], s[4:5]
	s_xor_b64 s[0:1], exec, s[0:1]
	s_cbranch_execz .LBB0_1277
	s_mov_b32 s6, s23
	s_mov_b32 s7, s53
	s_waitcnt lgkmcnt(2)
	v_pk_mul_f32 v[68:69], v[38:39], s[6:7] op_sel:[0,0] op_sel_hi:[0,1]
	s_waitcnt lgkmcnt(0)
	v_sub_f32_e32 v40, v66, v40
	v_pk_fma_f32 v[64:65], v[38:39], s[6:7], v[68:69] op_sel:[1,1,0] op_sel_hi:[1,0,1] neg_lo:[0,1,0]
	s_nop 0
	v_pk_mul_f32 v[64:65], v[40:41], v[64:65] op_sel_hi:[0,1]

.LBB0_1279:
	s_or_b64 exec, exec, s[0:1]
	s_waitcnt lgkmcnt(1)
	ds_read_b64 v[40:41], v144 offset:26112
	ds_read_b64 v[68:69], v149 offset:26112
	s_and_saveexec_b64 s[0:1], s[4:5]
	s_xor_b64 s[0:1], exec, s[0:1]
	s_cbranch_execz .LBB0_1281
	s_mov_b32 s6, s51
	s_mov_b32 s7, s51
	s_waitcnt lgkmcnt(2)
	v_pk_mul_f32 v[70:71], v[38:39], s[6:7] op_sel:[0,0] op_sel_hi:[0,1]
	s_waitcnt lgkmcnt(0)
	v_sub_f32_e32 v40, v68, v40
	v_pk_fma_f32 v[66:67], v[38:39], s[6:7], v[70:71] op_sel:[1,1,0] op_sel_hi:[1,0,1] neg_lo:[0,1,0]
	s_nop 0
	v_pk_mul_f32 v[66:67], v[40:41], v[66:67] op_sel_hi:[0,1]

.LBB0_1283:
	s_or_b64 exec, exec, s[0:1]
	s_waitcnt lgkmcnt(1)
	ds_read_b64 v[40:41], v144 offset:28288
	ds_read_b64 v[70:71], v149 offset:28288
	s_and_saveexec_b64 s[0:1], s[4:5]
	s_xor_b64 s[0:1], exec, s[0:1]
	s_cbranch_execz .LBB0_1285
	s_mov_b32 s6, s53
	s_mov_b32 s7, s23
	s_waitcnt lgkmcnt(2)
	v_pk_mul_f32 v[72:73], v[38:39], s[6:7] op_sel:[0,0] op_sel_hi:[0,1]
	s_waitcnt lgkmcnt(0)
	v_sub_f32_e32 v40, v70, v40
	v_pk_fma_f32 v[68:69], v[38:39], s[6:7], v[72:73] op_sel:[1,1,0] op_sel_hi:[1,0,1] neg_lo:[0,1,0]
	s_nop 0
	v_pk_mul_f32 v[68:69], v[40:41], v[68:69] op_sel_hi:[0,1]

.LBB0_1287:
	s_or_b64 exec, exec, s[0:1]
	s_waitcnt lgkmcnt(1)
	ds_read_b64 v[40:41], v144 offset:30464
	ds_read_b64 v[72:73], v149 offset:30464
	s_and_saveexec_b64 s[0:1], s[4:5]
	s_xor_b64 s[0:1], exec, s[0:1]
	s_cbranch_execz .LBB0_1289
	s_mov_b32 s6, s55
	s_mov_b32 s7, s21
	s_waitcnt lgkmcnt(2)
	v_pk_mul_f32 v[74:75], v[38:39], s[6:7] op_sel:[0,0] op_sel_hi:[0,1]
	s_waitcnt lgkmcnt(0)
	v_sub_f32_e32 v40, v72, v40
	v_pk_fma_f32 v[70:71], v[38:39], s[6:7], v[74:75] op_sel:[1,1,0] op_sel_hi:[1,0,1] neg_lo:[0,1,0]
	s_nop 0
	v_pk_mul_f32 v[70:71], v[40:41], v[70:71] op_sel_hi:[0,1]

.LBB0_1291:
	s_or_b64 exec, exec, s[0:1]
	s_waitcnt lgkmcnt(1)
	ds_read_b64 v[40:41], v144 offset:32640
	ds_read_b64 v[74:75], v149 offset:32640
	s_and_saveexec_b64 s[0:1], s[4:5]
	s_xor_b64 s[0:1], exec, s[0:1]
	s_cbranch_execz .LBB0_1293
	s_mov_b32 s6, s57
	s_mov_b32 s7, s19
	s_waitcnt lgkmcnt(2)
	s_waitcnt lgkmcnt(0)
	v_sub_f32_e32 v40, v74, v40
	v_pk_mul_f32 v[78:79], v[38:39], s[6:7] op_sel:[0,0] op_sel_hi:[0,1]
	s_nop 0
	v_pk_fma_f32 v[38:39], v[38:39], s[6:7], v[78:79] op_sel:[1,1,0] op_sel_hi:[1,0,1] neg_lo:[0,1,0]
	s_nop 0
	v_pk_mul_f32 v[72:73], v[40:41], v[38:39] op_sel_hi:[0,1]

.LBB0_1295:
	s_or_b64 exec, exec, s[0:1]
	v_mul_u32_u24_e32 v38, 0x88, v138
	s_waitcnt lgkmcnt(0)
	v_pk_add_f32 v[74:75], v[42:43], v[58:59]
	v_pk_add_f32 v[42:43], v[42:43], v[58:59] neg_lo:[0,1] neg_hi:[0,1]
	v_pk_add_f32 v[58:59], v[50:51], v[66:67]
	v_pk_add_f32 v[50:51], v[50:51], v[66:67] neg_lo:[0,1] neg_hi:[0,1]
	v_lshl_add_u32 v146, v143, 11, v77
	v_add_u32_e32 v147, v76, v38
	v_pk_add_f32 v[66:67], v[74:75], v[58:59]
	v_pk_add_f32 v[58:59], v[74:75], v[58:59] neg_lo:[0,1] neg_hi:[0,1]
	v_pk_add_f32 v[74:75], v[42:43], v[50:51] op_sel:[0,1] op_sel_hi:[1,0] neg_hi:[0,1]
	v_pk_add_f32 v[76:77], v[42:43], v[50:51] op_sel:[0,1] op_sel_hi:[1,0] neg_lo:[0,1]
	v_pk_add_f32 v[42:43], v[44:45], v[60:61]
	v_pk_add_f32 v[44:45], v[44:45], v[60:61] neg_lo:[0,1] neg_hi:[0,1]
	v_pk_add_f32 v[50:51], v[52:53], v[68:69]
	v_pk_add_f32 v[52:53], v[52:53], v[68:69] neg_lo:[0,1] neg_hi:[0,1]
	v_pk_add_f32 v[60:61], v[42:43], v[50:51]
	v_pk_add_f32 v[50:51], v[42:43], v[50:51] neg_lo:[0,1] neg_hi:[0,1]
	v_pk_add_f32 v[42:43], v[44:45], v[52:53] op_sel:[0,1] op_sel_hi:[1,0] neg_hi:[0,1]
	v_pk_add_f32 v[52:53], v[44:45], v[52:53] op_sel:[0,1] op_sel_hi:[1,0] neg_lo:[0,1]
	v_pk_add_f32 v[44:45], v[46:47], v[62:63]
	v_pk_add_f32 v[46:47], v[46:47], v[62:63] neg_lo:[0,1] neg_hi:[0,1]
	v_pk_add_f32 v[62:63], v[54:55], v[70:71]
	v_pk_add_f32 v[54:55], v[54:55], v[70:71] neg_lo:[0,1] neg_hi:[0,1]
	v_pk_add_f32 v[68:69], v[44:45], v[62:63]
	v_pk_add_f32 v[62:63], v[44:45], v[62:63] neg_lo:[0,1] neg_hi:[0,1]
	v_pk_add_f32 v[70:71], v[46:47], v[54:55] op_sel:[0,1] op_sel_hi:[1,0] neg_hi:[0,1]
	v_pk_add_f32 v[54:55], v[46:47], v[54:55] op_sel:[0,1] op_sel_hi:[1,0] neg_lo:[0,1]
	v_pk_add_f32 v[44:45], v[48:49], v[64:65]
	v_pk_add_f32 v[46:47], v[48:49], v[64:65] neg_lo:[0,1] neg_hi:[0,1]
	v_pk_add_f32 v[48:49], v[56:57], v[72:73]
	v_pk_add_f32 v[56:57], v[56:57], v[72:73] neg_lo:[0,1] neg_hi:[0,1]
	v_pk_add_f32 v[64:65], v[44:45], v[48:49]
	v_pk_add_f32 v[72:73], v[44:45], v[48:49] neg_lo:[0,1] neg_hi:[0,1]
	v_pk_mul_f32 v[44:45], v[42:43], s[20:21] op_sel:[0,0] op_sel_hi:[0,1]
	v_pk_add_f32 v[78:79], v[46:47], v[56:57] op_sel:[0,1] op_sel_hi:[1,0] neg_hi:[0,1]
	v_pk_add_f32 v[56:57], v[46:47], v[56:57] op_sel:[0,1] op_sel_hi:[1,0] neg_lo:[0,1]
	v_and_b32_e32 v38, 15, v145
	v_pk_fma_f32 v[80:81], v[42:43], s[20:21], v[44:45] op_sel:[1,1,0] op_sel_hi:[1,0,1] neg_lo:[0,1,0]
	v_pk_mul_f32 v[42:43], v[70:71], s[50:51] op_sel:[0,0] op_sel_hi:[0,1]
	v_mul_f32_e32 v34, 0x39800000, v34
	v_pk_fma_f32 v[70:71], v[70:71], s[50:51], v[42:43] op_sel:[1,1,0] op_sel_hi:[1,0,1] neg_lo:[0,1,0]
	v_mov_b64_e32 v[42:43], s[54:55]
	v_pk_mul_f32 v[46:47], v[78:79], v[42:43] op_sel:[0,0] op_sel_hi:[0,1]
	v_cvt_f32_ubyte0_e32 v38, v38
	v_pk_fma_f32 v[78:79], v[78:79], v[42:43], v[46:47] op_sel:[1,1,0] op_sel_hi:[1,0,1] neg_lo:[0,1,0]
	v_pk_mul_f32 v[46:47], v[50:51], s[50:51] op_sel:[0,0] op_sel_hi:[0,1]
	v_mul_f32_e32 v39, 0x3b800000, v38
	v_pk_fma_f32 v[82:83], v[50:51], s[50:51], v[46:47] op_sel:[1,1,0] op_sel_hi:[1,0,1] neg_lo:[0,1,0]
	v_mov_b64_e32 v[50:51], s[14:15]
	v_pk_mul_f32 v[46:47], v[62:63], v[50:51] op_sel:[0,0] op_sel_hi:[0,1]
	v_cos_f32_e32 v38, v34
	v_pk_fma_f32 v[62:63], v[62:63], v[50:51], v[46:47] op_sel:[1,1,0] op_sel_hi:[1,0,1] neg_lo:[0,1,0]
	v_mov_b64_e32 v[46:47], s[58:59]
	v_pk_mul_f32 v[84:85], v[72:73], v[46:47] op_sel:[0,0] op_sel_hi:[0,1]
	v_sin_f32_e32 v34, v34
	v_pk_fma_f32 v[72:73], v[72:73], v[46:47], v[84:85] op_sel:[1,1,0] op_sel_hi:[1,0,1] neg_lo:[0,1,0]
	v_pk_mul_f32 v[84:85], v[52:53], v[42:43] op_sel:[0,0] op_sel_hi:[0,1]
	v_cos_f32_e32 v40, v39
	v_pk_fma_f32 v[84:85], v[52:53], v[42:43], v[84:85] op_sel:[1,1,0] op_sel_hi:[1,0,1] neg_lo:[0,1,0]
	v_pk_mul_f32 v[52:53], v[54:55], v[46:47] op_sel:[0,0] op_sel_hi:[0,1]
	v_sin_f32_e32 v41, v39
	v_pk_fma_f32 v[54:55], v[54:55], v[46:47], v[52:53] op_sel:[1,1,0] op_sel_hi:[1,0,1] neg_lo:[0,1,0]
	v_mov_b64_e32 v[52:53], s[60:61]
	v_pk_mul_f32 v[86:87], v[56:57], v[52:53] op_sel:[0,0] op_sel_hi:[0,1]
	v_xor_b32_e32 v39, 0x80000000, v34
	v_pk_fma_f32 v[56:57], v[56:57], v[52:53], v[86:87] op_sel:[1,1,0] op_sel_hi:[1,0,1] neg_lo:[0,1,0]
	v_pk_add_f32 v[86:87], v[66:67], v[68:69]
	v_pk_add_f32 v[66:67], v[66:67], v[68:69] neg_lo:[0,1] neg_hi:[0,1]
	v_pk_add_f32 v[68:69], v[60:61], v[64:65]
	v_pk_add_f32 v[60:61], v[60:61], v[64:65] neg_lo:[0,1] neg_hi:[0,1]
	v_pk_add_f32 v[64:65], v[86:87], v[68:69]
	v_pk_add_f32 v[68:69], v[86:87], v[68:69] neg_lo:[0,1] neg_hi:[0,1]
	v_pk_add_f32 v[86:87], v[66:67], v[60:61] op_sel:[0,1] op_sel_hi:[1,0] neg_hi:[0,1]
	v_pk_add_f32 v[60:61], v[66:67], v[60:61] op_sel:[0,1] op_sel_hi:[1,0] neg_lo:[0,1]
	v_pk_add_f32 v[66:67], v[74:75], v[70:71]
	v_pk_add_f32 v[70:71], v[74:75], v[70:71] neg_lo:[0,1] neg_hi:[0,1]
	v_pk_add_f32 v[74:75], v[80:81], v[78:79]
	v_pk_add_f32 v[78:79], v[80:81], v[78:79] neg_lo:[0,1] neg_hi:[0,1]
	v_pk_add_f32 v[80:81], v[66:67], v[74:75]
	v_pk_add_f32 v[66:67], v[66:67], v[74:75] neg_lo:[0,1] neg_hi:[0,1]
	v_pk_add_f32 v[74:75], v[70:71], v[78:79] op_sel:[0,1] op_sel_hi:[1,0] neg_hi:[0,1]
	v_pk_add_f32 v[70:71], v[70:71], v[78:79] op_sel:[0,1] op_sel_hi:[1,0] neg_lo:[0,1]
	v_pk_add_f32 v[78:79], v[58:59], v[62:63]
	v_pk_add_f32 v[58:59], v[58:59], v[62:63] neg_lo:[0,1] neg_hi:[0,1]
	v_pk_add_f32 v[62:63], v[82:83], v[72:73]
	v_pk_add_f32 v[72:73], v[82:83], v[72:73] neg_lo:[0,1] neg_hi:[0,1]
	v_pk_add_f32 v[82:83], v[78:79], v[62:63]
	v_pk_add_f32 v[62:63], v[78:79], v[62:63] neg_lo:[0,1] neg_hi:[0,1]
	v_pk_add_f32 v[78:79], v[58:59], v[72:73] op_sel:[0,1] op_sel_hi:[1,0] neg_hi:[0,1]
	v_pk_add_f32 v[58:59], v[58:59], v[72:73] op_sel:[0,1] op_sel_hi:[1,0] neg_lo:[0,1]
	v_pk_add_f32 v[72:73], v[76:77], v[54:55]
	v_pk_add_f32 v[54:55], v[76:77], v[54:55] neg_lo:[0,1] neg_hi:[0,1]
	v_pk_add_f32 v[76:77], v[84:85], v[56:57]
	v_pk_add_f32 v[56:57], v[84:85], v[56:57] neg_lo:[0,1] neg_hi:[0,1]
	v_pk_add_f32 v[84:85], v[72:73], v[76:77]
	v_pk_add_f32 v[72:73], v[72:73], v[76:77] neg_lo:[0,1] neg_hi:[0,1]
	v_pk_add_f32 v[76:77], v[54:55], v[56:57] op_sel:[0,1] op_sel_hi:[1,0] neg_hi:[0,1]
	v_pk_add_f32 v[54:55], v[54:55], v[56:57] op_sel:[0,1] op_sel_hi:[1,0] neg_lo:[0,1]
	v_mov_b32_e32 v56, v38
	v_mov_b32_e32 v57, v39
	s_barrier
	ds_write_b64 v144, v[64:65]
	v_pk_mul_f32 v[64:65], v[80:81], v[56:57] op_sel:[0,0] op_sel_hi:[0,1]
	v_xor_b32_e32 v41, 0x80000000, v41
	v_pk_fma_f32 v[64:65], v[80:81], v[56:57], v[64:65] op_sel:[1,1,0] op_sel_hi:[1,0,1] neg_lo:[0,1,0]
	ds_write_b64 v144, v[64:65] offset:2176
	v_pk_mul_f32 v[64:65], v[56:57], v[56:57] op_sel:[0,0] op_sel_hi:[0,1]
	s_add_u32 s0, s89, s82
	v_pk_fma_f32 v[64:65], v[56:57], v[56:57], v[64:65] op_sel:[1,1,0] op_sel_hi:[1,0,1] neg_lo:[0,1,0]
	s_addc_u32 s1, s88, s83
	v_pk_mul_f32 v[80:81], v[82:83], v[64:65] op_sel:[0,0] op_sel_hi:[0,1]
	s_add_u32 s6, s0, 0x2000000
	v_pk_fma_f32 v[80:81], v[82:83], v[64:65], v[80:81] op_sel:[1,1,0] op_sel_hi:[1,0,1] neg_lo:[0,1,0]
	ds_write_b64 v144, v[80:81] offset:4352
	v_pk_mul_f32 v[80:81], v[64:65], v[56:57] op_sel:[0,0] op_sel_hi:[0,1]
	s_addc_u32 s7, s1, 0
	v_pk_fma_f32 v[64:65], v[64:65], v[56:57], v[80:81] op_sel:[1,1,0] op_sel_hi:[1,0,1] neg_lo:[0,1,0]
	v_pk_mul_f32 v[80:81], v[84:85], v[64:65] op_sel:[0,0] op_sel_hi:[0,1]
	v_pk_fma_f32 v[80:81], v[84:85], v[64:65], v[80:81] op_sel:[1,1,0] op_sel_hi:[1,0,1] neg_lo:[0,1,0]
	ds_write_b64 v144, v[80:81] offset:6528
	v_pk_mul_f32 v[80:81], v[64:65], v[56:57] op_sel:[0,0] op_sel_hi:[0,1]
	v_pk_fma_f32 v[64:65], v[64:65], v[56:57], v[80:81] op_sel:[1,1,0] op_sel_hi:[1,0,1] neg_lo:[0,1,0]
	v_pk_mul_f32 v[80:81], v[86:87], v[64:65] op_sel:[0,0] op_sel_hi:[0,1]
	v_pk_fma_f32 v[80:81], v[86:87], v[64:65], v[80:81] op_sel:[1,1,0] op_sel_hi:[1,0,1] neg_lo:[0,1,0]
	ds_write_b64 v144, v[80:81] offset:8704
	v_pk_mul_f32 v[80:81], v[64:65], v[56:57] op_sel:[0,0] op_sel_hi:[0,1]
	v_pk_fma_f32 v[64:65], v[64:65], v[56:57], v[80:81] op_sel:[1,1,0] op_sel_hi:[1,0,1] neg_lo:[0,1,0]
	v_pk_mul_f32 v[80:81], v[74:75], v[64:65] op_sel:[0,0] op_sel_hi:[0,1]
	v_pk_fma_f32 v[74:75], v[74:75], v[64:65], v[80:81] op_sel:[1,1,0] op_sel_hi:[1,0,1] neg_lo:[0,1,0]
	ds_write_b64 v144, v[74:75] offset:10880
	v_pk_mul_f32 v[74:75], v[64:65], v[56:57] op_sel:[0,0] op_sel_hi:[0,1]
	v_pk_fma_f32 v[64:65], v[64:65], v[56:57], v[74:75] op_sel:[1,1,0] op_sel_hi:[1,0,1] neg_lo:[0,1,0]
	v_pk_mul_f32 v[74:75], v[78:79], v[64:65] op_sel:[0,0] op_sel_hi:[0,1]
	v_pk_fma_f32 v[74:75], v[78:79], v[64:65], v[74:75] op_sel:[1,1,0] op_sel_hi:[1,0,1] neg_lo:[0,1,0]
	ds_write_b64 v144, v[74:75] offset:13056
	v_pk_mul_f32 v[74:75], v[64:65], v[56:57] op_sel:[0,0] op_sel_hi:[0,1]
	v_pk_fma_f32 v[64:65], v[64:65], v[56:57], v[74:75] op_sel:[1,1,0] op_sel_hi:[1,0,1] neg_lo:[0,1,0]
	v_pk_mul_f32 v[74:75], v[76:77], v[64:65] op_sel:[0,0] op_sel_hi:[0,1]
	v_pk_fma_f32 v[74:75], v[76:77], v[64:65], v[74:75] op_sel:[1,1,0] op_sel_hi:[1,0,1] neg_lo:[0,1,0]
	ds_write_b64 v144, v[74:75] offset:15232
	v_pk_mul_f32 v[74:75], v[64:65], v[56:57] op_sel:[0,0] op_sel_hi:[0,1]
	v_pk_fma_f32 v[64:65], v[64:65], v[56:57], v[74:75] op_sel:[1,1,0] op_sel_hi:[1,0,1] neg_lo:[0,1,0]
	v_pk_mul_f32 v[74:75], v[68:69], v[64:65] op_sel:[0,0] op_sel_hi:[0,1]
	v_pk_fma_f32 v[68:69], v[68:69], v[64:65], v[74:75] op_sel:[1,1,0] op_sel_hi:[1,0,1] neg_lo:[0,1,0]
	ds_write_b64 v144, v[68:69] offset:17408
	v_pk_mul_f32 v[68:69], v[64:65], v[56:57] op_sel:[0,0] op_sel_hi:[0,1]
	v_pk_fma_f32 v[64:65], v[64:65], v[56:57], v[68:69] op_sel:[1,1,0] op_sel_hi:[1,0,1] neg_lo:[0,1,0]
	v_pk_mul_f32 v[68:69], v[66:67], v[64:65] op_sel:[0,0] op_sel_hi:[0,1]
	v_pk_fma_f32 v[66:67], v[66:67], v[64:65], v[68:69] op_sel:[1,1,0] op_sel_hi:[1,0,1] neg_lo:[0,1,0]
	ds_write_b64 v144, v[66:67] offset:19584
	v_pk_mul_f32 v[66:67], v[64:65], v[56:57] op_sel:[0,0] op_sel_hi:[0,1]
	v_pk_fma_f32 v[64:65], v[64:65], v[56:57], v[66:67] op_sel:[1,1,0] op_sel_hi:[1,0,1] neg_lo:[0,1,0]
	v_pk_mul_f32 v[66:67], v[62:63], v[64:65] op_sel:[0,0] op_sel_hi:[0,1]
	v_pk_fma_f32 v[62:63], v[62:63], v[64:65], v[66:67] op_sel:[1,1,0] op_sel_hi:[1,0,1] neg_lo:[0,1,0]
	ds_write_b64 v144, v[62:63] offset:21760
	v_pk_mul_f32 v[62:63], v[64:65], v[56:57] op_sel:[0,0] op_sel_hi:[0,1]
	v_pk_fma_f32 v[62:63], v[64:65], v[56:57], v[62:63] op_sel:[1,1,0] op_sel_hi:[1,0,1] neg_lo:[0,1,0]
	v_pk_mul_f32 v[64:65], v[72:73], v[62:63] op_sel:[0,0] op_sel_hi:[0,1]
	v_pk_fma_f32 v[64:65], v[72:73], v[62:63], v[64:65] op_sel:[1,1,0] op_sel_hi:[1,0,1] neg_lo:[0,1,0]
	ds_write_b64 v144, v[64:65] offset:23936
	v_pk_mul_f32 v[64:65], v[62:63], v[56:57] op_sel:[0,0] op_sel_hi:[0,1]
	v_pk_fma_f32 v[62:63], v[62:63], v[56:57], v[64:65] op_sel:[1,1,0] op_sel_hi:[1,0,1] neg_lo:[0,1,0]
	v_pk_mul_f32 v[64:65], v[60:61], v[62:63] op_sel:[0,0] op_sel_hi:[0,1]
	v_pk_fma_f32 v[60:61], v[60:61], v[62:63], v[64:65] op_sel:[1,1,0] op_sel_hi:[1,0,1] neg_lo:[0,1,0]
	ds_write_b64 v144, v[60:61] offset:26112
	v_pk_mul_f32 v[60:61], v[62:63], v[56:57] op_sel:[0,0] op_sel_hi:[0,1]
	v_pk_fma_f32 v[60:61], v[62:63], v[56:57], v[60:61] op_sel:[1,1,0] op_sel_hi:[1,0,1] neg_lo:[0,1,0]
	v_pk_mul_f32 v[62:63], v[70:71], v[60:61] op_sel:[0,0] op_sel_hi:[0,1]
	v_pk_fma_f32 v[62:63], v[70:71], v[60:61], v[62:63] op_sel:[1,1,0] op_sel_hi:[1,0,1] neg_lo:[0,1,0]
	ds_write_b64 v144, v[62:63] offset:28288
	v_pk_mul_f32 v[62:63], v[60:61], v[56:57] op_sel:[0,0] op_sel_hi:[0,1]
	v_pk_fma_f32 v[60:61], v[60:61], v[56:57], v[62:63] op_sel:[1,1,0] op_sel_hi:[1,0,1] neg_lo:[0,1,0]
	v_pk_mul_f32 v[62:63], v[58:59], v[60:61] op_sel:[0,0] op_sel_hi:[0,1]
	v_pk_fma_f32 v[58:59], v[58:59], v[60:61], v[62:63] op_sel:[1,1,0] op_sel_hi:[1,0,1] neg_lo:[0,1,0]
	ds_write_b64 v144, v[58:59] offset:30464
	v_pk_mul_f32 v[58:59], v[60:61], v[56:57] op_sel:[0,0] op_sel_hi:[0,1]
	v_pk_fma_f32 v[56:57], v[60:61], v[56:57], v[58:59] op_sel:[1,1,0] op_sel_hi:[1,0,1] neg_lo:[0,1,0]
	v_pk_mul_f32 v[58:59], v[54:55], v[56:57] op_sel:[0,0] op_sel_hi:[0,1]
	v_pk_fma_f32 v[54:55], v[54:55], v[56:57], v[58:59] op_sel:[1,1,0] op_sel_hi:[1,0,1] neg_lo:[0,1,0]
	ds_write_b64 v144, v[54:55] offset:32640
	s_waitcnt lgkmcnt(0)
	s_barrier
	ds_read2_b64 v[54:57], v146 offset1:17
	ds_read2_b64 v[58:61], v146 offset0:34 offset1:51
	ds_read2_b64 v[62:65], v146 offset0:68 offset1:85
	ds_read2_b64 v[66:69], v146 offset0:136 offset1:153
	ds_read2_b64 v[70:73], v146 offset0:102 offset1:119
	ds_read2_b64 v[74:77], v146 offset0:204 offset1:221
	ds_read2_b64 v[78:81], v146 offset0:170 offset1:187
	ds_read2_b64 v[82:85], v146 offset0:238 offset1:255
	s_waitcnt lgkmcnt(4)
	v_pk_add_f32 v[86:87], v[54:55], v[66:67]
	v_pk_add_f32 v[54:55], v[54:55], v[66:67] neg_lo:[0,1] neg_hi:[0,1]
	s_waitcnt lgkmcnt(2)
	v_pk_add_f32 v[66:67], v[62:63], v[74:75]
	v_pk_add_f32 v[62:63], v[62:63], v[74:75] neg_lo:[0,1] neg_hi:[0,1]
	v_pk_add_f32 v[74:75], v[86:87], v[66:67]
	v_pk_add_f32 v[66:67], v[86:87], v[66:67] neg_lo:[0,1] neg_hi:[0,1]
	v_pk_add_f32 v[86:87], v[54:55], v[62:63] op_sel:[0,1] op_sel_hi:[1,0] neg_hi:[0,1]
	v_pk_add_f32 v[54:55], v[54:55], v[62:63] op_sel:[0,1] op_sel_hi:[1,0] neg_lo:[0,1]
	v_pk_add_f32 v[62:63], v[56:57], v[68:69]
	v_pk_add_f32 v[56:57], v[56:57], v[68:69] neg_lo:[0,1] neg_hi:[0,1]
	v_pk_add_f32 v[68:69], v[64:65], v[76:77]
	v_pk_add_f32 v[64:65], v[64:65], v[76:77] neg_lo:[0,1] neg_hi:[0,1]
	v_pk_add_f32 v[76:77], v[62:63], v[68:69]
	v_pk_add_f32 v[62:63], v[62:63], v[68:69] neg_lo:[0,1] neg_hi:[0,1]
	v_pk_add_f32 v[68:69], v[56:57], v[64:65] op_sel:[0,1] op_sel_hi:[1,0] neg_hi:[0,1]
	v_pk_add_f32 v[56:57], v[56:57], v[64:65] op_sel:[0,1] op_sel_hi:[1,0] neg_lo:[0,1]
	s_waitcnt lgkmcnt(1)
	v_pk_add_f32 v[64:65], v[58:59], v[78:79]
	v_pk_add_f32 v[58:59], v[58:59], v[78:79] neg_lo:[0,1] neg_hi:[0,1]
	s_waitcnt lgkmcnt(0)
	v_pk_add_f32 v[78:79], v[70:71], v[82:83]
	v_pk_add_f32 v[70:71], v[70:71], v[82:83] neg_lo:[0,1] neg_hi:[0,1]
	v_pk_add_f32 v[82:83], v[64:65], v[78:79]
	v_pk_add_f32 v[64:65], v[64:65], v[78:79] neg_lo:[0,1] neg_hi:[0,1]
	v_pk_add_f32 v[78:79], v[58:59], v[70:71] op_sel:[0,1] op_sel_hi:[1,0] neg_hi:[0,1]
	v_pk_add_f32 v[58:59], v[58:59], v[70:71] op_sel:[0,1] op_sel_hi:[1,0] neg_lo:[0,1]
	v_pk_add_f32 v[70:71], v[60:61], v[80:81]
	v_pk_add_f32 v[60:61], v[60:61], v[80:81] neg_lo:[0,1] neg_hi:[0,1]
	v_pk_add_f32 v[80:81], v[72:73], v[84:85]
	v_pk_add_f32 v[72:73], v[72:73], v[84:85] neg_lo:[0,1] neg_hi:[0,1]
	v_pk_add_f32 v[84:85], v[70:71], v[80:81]
	v_pk_add_f32 v[70:71], v[70:71], v[80:81] neg_lo:[0,1] neg_hi:[0,1]
	v_pk_add_f32 v[80:81], v[60:61], v[72:73] op_sel:[0,1] op_sel_hi:[1,0] neg_hi:[0,1]
	v_pk_add_f32 v[60:61], v[60:61], v[72:73] op_sel:[0,1] op_sel_hi:[1,0] neg_lo:[0,1]
	v_pk_mul_f32 v[72:73], v[68:69], s[20:21] op_sel:[0,0] op_sel_hi:[0,1]
	v_pk_fma_f32 v[68:69], v[68:69], s[20:21], v[72:73] op_sel:[1,1,0] op_sel_hi:[1,0,1] neg_lo:[0,1,0]
	v_pk_mul_f32 v[72:73], v[78:79], s[50:51] op_sel:[0,0] op_sel_hi:[0,1]
	v_pk_fma_f32 v[72:73], v[78:79], s[50:51], v[72:73] op_sel:[1,1,0] op_sel_hi:[1,0,1] neg_lo:[0,1,0]
	v_pk_mul_f32 v[78:79], v[80:81], v[42:43] op_sel:[0,0] op_sel_hi:[0,1]
	v_pk_fma_f32 v[78:79], v[80:81], v[42:43], v[78:79] op_sel:[1,1,0] op_sel_hi:[1,0,1] neg_lo:[0,1,0]
	v_pk_mul_f32 v[80:81], v[62:63], s[50:51] op_sel:[0,0] op_sel_hi:[0,1]
	v_pk_fma_f32 v[62:63], v[62:63], s[50:51], v[80:81] op_sel:[1,1,0] op_sel_hi:[1,0,1] neg_lo:[0,1,0]
	v_pk_mul_f32 v[80:81], v[64:65], v[50:51] op_sel:[0,0] op_sel_hi:[0,1]
	v_pk_fma_f32 v[64:65], v[64:65], v[50:51], v[80:81] op_sel:[1,1,0] op_sel_hi:[1,0,1] neg_lo:[0,1,0]
	v_pk_mul_f32 v[80:81], v[70:71], v[46:47] op_sel:[0,0] op_sel_hi:[0,1]
	v_pk_fma_f32 v[70:71], v[70:71], v[46:47], v[80:81] op_sel:[1,1,0] op_sel_hi:[1,0,1] neg_lo:[0,1,0]
	v_pk_mul_f32 v[80:81], v[56:57], v[42:43] op_sel:[0,0] op_sel_hi:[0,1]
	v_pk_fma_f32 v[56:57], v[56:57], v[42:43], v[80:81] op_sel:[1,1,0] op_sel_hi:[1,0,1] neg_lo:[0,1,0]
	v_pk_mul_f32 v[80:81], v[58:59], v[46:47] op_sel:[0,0] op_sel_hi:[0,1]
	v_pk_fma_f32 v[58:59], v[58:59], v[46:47], v[80:81] op_sel:[1,1,0] op_sel_hi:[1,0,1] neg_lo:[0,1,0]
	v_pk_mul_f32 v[80:81], v[60:61], v[52:53] op_sel:[0,0] op_sel_hi:[0,1]
	v_pk_fma_f32 v[60:61], v[60:61], v[52:53], v[80:81] op_sel:[1,1,0] op_sel_hi:[1,0,1] neg_lo:[0,1,0]
	v_pk_add_f32 v[80:81], v[74:75], v[82:83]
	v_pk_add_f32 v[74:75], v[74:75], v[82:83] neg_lo:[0,1] neg_hi:[0,1]
	v_pk_add_f32 v[82:83], v[76:77], v[84:85]
	v_pk_add_f32 v[76:77], v[76:77], v[84:85] neg_lo:[0,1] neg_hi:[0,1]
	v_pk_add_f32 v[84:85], v[80:81], v[82:83]
	v_pk_add_f32 v[80:81], v[80:81], v[82:83] neg_lo:[0,1] neg_hi:[0,1]
	v_pk_add_f32 v[82:83], v[74:75], v[76:77] op_sel:[0,1] op_sel_hi:[1,0] neg_hi:[0,1]
	v_pk_add_f32 v[74:75], v[74:75], v[76:77] op_sel:[0,1] op_sel_hi:[1,0] neg_lo:[0,1]
	v_pk_add_f32 v[76:77], v[86:87], v[72:73]
	v_pk_add_f32 v[72:73], v[86:87], v[72:73] neg_lo:[0,1] neg_hi:[0,1]
	v_pk_add_f32 v[86:87], v[68:69], v[78:79]
	v_pk_add_f32 v[68:69], v[68:69], v[78:79] neg_lo:[0,1] neg_hi:[0,1]
	v_pk_add_f32 v[78:79], v[76:77], v[86:87]
	v_pk_add_f32 v[76:77], v[76:77], v[86:87] neg_lo:[0,1] neg_hi:[0,1]
	v_pk_add_f32 v[86:87], v[72:73], v[68:69] op_sel:[0,1] op_sel_hi:[1,0] neg_hi:[0,1]
	v_pk_add_f32 v[68:69], v[72:73], v[68:69] op_sel:[0,1] op_sel_hi:[1,0] neg_lo:[0,1]
	v_pk_add_f32 v[72:73], v[66:67], v[64:65]
	v_pk_add_f32 v[64:65], v[66:67], v[64:65] neg_lo:[0,1] neg_hi:[0,1]
	v_pk_add_f32 v[66:67], v[62:63], v[70:71]
	v_pk_add_f32 v[62:63], v[62:63], v[70:71] neg_lo:[0,1] neg_hi:[0,1]
	v_pk_add_f32 v[70:71], v[72:73], v[66:67]
	v_pk_add_f32 v[66:67], v[72:73], v[66:67] neg_lo:[0,1] neg_hi:[0,1]
	v_pk_add_f32 v[72:73], v[64:65], v[62:63] op_sel:[0,1] op_sel_hi:[1,0] neg_hi:[0,1]
	v_pk_add_f32 v[62:63], v[64:65], v[62:63] op_sel:[0,1] op_sel_hi:[1,0] neg_lo:[0,1]
	v_pk_add_f32 v[64:65], v[54:55], v[58:59]
	v_pk_add_f32 v[54:55], v[54:55], v[58:59] neg_lo:[0,1] neg_hi:[0,1]
	v_pk_add_f32 v[58:59], v[56:57], v[60:61]
	v_pk_add_f32 v[56:57], v[56:57], v[60:61] neg_lo:[0,1] neg_hi:[0,1]
	v_pk_add_f32 v[60:61], v[64:65], v[58:59]
	v_pk_add_f32 v[58:59], v[64:65], v[58:59] neg_lo:[0,1] neg_hi:[0,1]
	v_pk_add_f32 v[64:65], v[54:55], v[56:57] op_sel:[0,1] op_sel_hi:[1,0] neg_hi:[0,1]
	v_pk_add_f32 v[54:55], v[54:55], v[56:57] op_sel:[0,1] op_sel_hi:[1,0] neg_lo:[0,1]
	v_mov_b32_e32 v56, v40
	v_mov_b32_e32 v57, v41
	s_nop 0
	v_pk_mul_f32 v[88:89], v[78:79], v[56:57] op_sel:[0,0] op_sel_hi:[0,1]
	v_pk_fma_f32 v[78:79], v[78:79], v[56:57], v[88:89] op_sel:[1,1,0] op_sel_hi:[1,0,1] neg_lo:[0,1,0]
	ds_write2_b64 v146, v[84:85], v[78:79] offset1:17
	v_pk_mul_f32 v[78:79], v[56:57], v[56:57] op_sel:[0,0] op_sel_hi:[0,1]
	v_pk_fma_f32 v[78:79], v[56:57], v[56:57], v[78:79] op_sel:[1,1,0] op_sel_hi:[1,0,1] neg_lo:[0,1,0]
	v_pk_mul_f32 v[84:85], v[70:71], v[78:79] op_sel:[0,0] op_sel_hi:[0,1]
	v_pk_fma_f32 v[70:71], v[70:71], v[78:79], v[84:85] op_sel:[1,1,0] op_sel_hi:[1,0,1] neg_lo:[0,1,0]
	v_pk_mul_f32 v[84:85], v[78:79], v[56:57] op_sel:[0,0] op_sel_hi:[0,1]
	v_pk_fma_f32 v[78:79], v[78:79], v[56:57], v[84:85] op_sel:[1,1,0] op_sel_hi:[1,0,1] neg_lo:[0,1,0]
	v_pk_mul_f32 v[84:85], v[60:61], v[78:79] op_sel:[0,0] op_sel_hi:[0,1]
	v_pk_fma_f32 v[60:61], v[60:61], v[78:79], v[84:85] op_sel:[1,1,0] op_sel_hi:[1,0,1] neg_lo:[0,1,0]
	ds_write2_b64 v146, v[70:71], v[60:61] offset0:34 offset1:51
	v_pk_mul_f32 v[60:61], v[78:79], v[56:57] op_sel:[0,0] op_sel_hi:[0,1]
	v_pk_fma_f32 v[60:61], v[78:79], v[56:57], v[60:61] op_sel:[1,1,0] op_sel_hi:[1,0,1] neg_lo:[0,1,0]
	v_pk_mul_f32 v[70:71], v[82:83], v[60:61] op_sel:[0,0] op_sel_hi:[0,1]
	v_pk_mul_f32 v[78:79], v[60:61], v[56:57] op_sel:[0,0] op_sel_hi:[0,1]
	v_pk_fma_f32 v[70:71], v[82:83], v[60:61], v[70:71] op_sel:[1,1,0] op_sel_hi:[1,0,1] neg_lo:[0,1,0]
	v_pk_fma_f32 v[60:61], v[60:61], v[56:57], v[78:79] op_sel:[1,1,0] op_sel_hi:[1,0,1] neg_lo:[0,1,0]
	v_pk_mul_f32 v[78:79], v[86:87], v[60:61] op_sel:[0,0] op_sel_hi:[0,1]
	v_pk_fma_f32 v[78:79], v[86:87], v[60:61], v[78:79] op_sel:[1,1,0] op_sel_hi:[1,0,1] neg_lo:[0,1,0]
	ds_write2_b64 v146, v[70:71], v[78:79] offset0:68 offset1:85
	v_pk_mul_f32 v[70:71], v[60:61], v[56:57] op_sel:[0,0] op_sel_hi:[0,1]
	v_pk_fma_f32 v[60:61], v[60:61], v[56:57], v[70:71] op_sel:[1,1,0] op_sel_hi:[1,0,1] neg_lo:[0,1,0]
	v_pk_mul_f32 v[70:71], v[72:73], v[60:61] op_sel:[0,0] op_sel_hi:[0,1]
	v_pk_fma_f32 v[70:71], v[72:73], v[60:61], v[70:71] op_sel:[1,1,0] op_sel_hi:[1,0,1] neg_lo:[0,1,0]
	v_pk_mul_f32 v[72:73], v[60:61], v[56:57] op_sel:[0,0] op_sel_hi:[0,1]
	v_pk_fma_f32 v[60:61], v[60:61], v[56:57], v[72:73] op_sel:[1,1,0] op_sel_hi:[1,0,1] neg_lo:[0,1,0]
	v_pk_mul_f32 v[72:73], v[64:65], v[60:61] op_sel:[0,0] op_sel_hi:[0,1]
	v_pk_fma_f32 v[64:65], v[64:65], v[60:61], v[72:73] op_sel:[1,1,0] op_sel_hi:[1,0,1] neg_lo:[0,1,0]
	ds_write2_b64 v146, v[70:71], v[64:65] offset0:102 offset1:119
	v_pk_mul_f32 v[64:65], v[60:61], v[56:57] op_sel:[0,0] op_sel_hi:[0,1]
	v_pk_fma_f32 v[60:61], v[60:61], v[56:57], v[64:65] op_sel:[1,1,0] op_sel_hi:[1,0,1] neg_lo:[0,1,0]
	v_pk_mul_f32 v[64:65], v[80:81], v[60:61] op_sel:[0,0] op_sel_hi:[0,1]
	v_pk_mul_f32 v[70:71], v[60:61], v[56:57] op_sel:[0,0] op_sel_hi:[0,1]
	v_pk_fma_f32 v[64:65], v[80:81], v[60:61], v[64:65] op_sel:[1,1,0] op_sel_hi:[1,0,1] neg_lo:[0,1,0]
	v_pk_fma_f32 v[60:61], v[60:61], v[56:57], v[70:71] op_sel:[1,1,0] op_sel_hi:[1,0,1] neg_lo:[0,1,0]
	v_pk_mul_f32 v[70:71], v[76:77], v[60:61] op_sel:[0,0] op_sel_hi:[0,1]
	v_pk_fma_f32 v[70:71], v[76:77], v[60:61], v[70:71] op_sel:[1,1,0] op_sel_hi:[1,0,1] neg_lo:[0,1,0]
	ds_write2_b64 v146, v[64:65], v[70:71] offset0:136 offset1:153
	v_pk_mul_f32 v[64:65], v[60:61], v[56:57] op_sel:[0,0] op_sel_hi:[0,1]
	v_pk_fma_f32 v[60:61], v[60:61], v[56:57], v[64:65] op_sel:[1,1,0] op_sel_hi:[1,0,1] neg_lo:[0,1,0]
	v_pk_mul_f32 v[64:65], v[66:67], v[60:61] op_sel:[0,0] op_sel_hi:[0,1]
	v_pk_fma_f32 v[64:65], v[66:67], v[60:61], v[64:65] op_sel:[1,1,0] op_sel_hi:[1,0,1] neg_lo:[0,1,0]
	v_pk_mul_f32 v[66:67], v[60:61], v[56:57] op_sel:[0,0] op_sel_hi:[0,1]
	v_pk_fma_f32 v[60:61], v[60:61], v[56:57], v[66:67] op_sel:[1,1,0] op_sel_hi:[1,0,1] neg_lo:[0,1,0]
	v_pk_mul_f32 v[66:67], v[58:59], v[60:61] op_sel:[0,0] op_sel_hi:[0,1]
	v_pk_fma_f32 v[58:59], v[58:59], v[60:61], v[66:67] op_sel:[1,1,0] op_sel_hi:[1,0,1] neg_lo:[0,1,0]
	ds_write2_b64 v146, v[64:65], v[58:59] offset0:170 offset1:187
	v_pk_mul_f32 v[58:59], v[60:61], v[56:57] op_sel:[0,0] op_sel_hi:[0,1]
	v_pk_fma_f32 v[58:59], v[60:61], v[56:57], v[58:59] op_sel:[1,1,0] op_sel_hi:[1,0,1] neg_lo:[0,1,0]
	v_pk_mul_f32 v[60:61], v[74:75], v[58:59] op_sel:[0,0] op_sel_hi:[0,1]
	v_pk_mul_f32 v[64:65], v[58:59], v[56:57] op_sel:[0,0] op_sel_hi:[0,1]
	v_pk_fma_f32 v[60:61], v[74:75], v[58:59], v[60:61] op_sel:[1,1,0] op_sel_hi:[1,0,1] neg_lo:[0,1,0]
	v_pk_fma_f32 v[58:59], v[58:59], v[56:57], v[64:65] op_sel:[1,1,0] op_sel_hi:[1,0,1] neg_lo:[0,1,0]
	v_pk_mul_f32 v[64:65], v[68:69], v[58:59] op_sel:[0,0] op_sel_hi:[0,1]
	v_pk_fma_f32 v[64:65], v[68:69], v[58:59], v[64:65] op_sel:[1,1,0] op_sel_hi:[1,0,1] neg_lo:[0,1,0]
	ds_write2_b64 v146, v[60:61], v[64:65] offset0:204 offset1:221
	v_pk_mul_f32 v[60:61], v[58:59], v[56:57] op_sel:[0,0] op_sel_hi:[0,1]
	v_pk_fma_f32 v[58:59], v[58:59], v[56:57], v[60:61] op_sel:[1,1,0] op_sel_hi:[1,0,1] neg_lo:[0,1,0]
	v_pk_mul_f32 v[60:61], v[62:63], v[58:59] op_sel:[0,0] op_sel_hi:[0,1]
	v_pk_fma_f32 v[60:61], v[62:63], v[58:59], v[60:61] op_sel:[1,1,0] op_sel_hi:[1,0,1] neg_lo:[0,1,0]
	v_pk_mul_f32 v[62:63], v[58:59], v[56:57] op_sel:[0,0] op_sel_hi:[0,1]
	v_pk_fma_f32 v[56:57], v[58:59], v[56:57], v[62:63] op_sel:[1,1,0] op_sel_hi:[1,0,1] neg_lo:[0,1,0]
	v_pk_mul_f32 v[58:59], v[54:55], v[56:57] op_sel:[0,0] op_sel_hi:[0,1]
	v_pk_fma_f32 v[54:55], v[54:55], v[56:57], v[58:59] op_sel:[1,1,0] op_sel_hi:[1,0,1] neg_lo:[0,1,0]
	ds_write2_b64 v146, v[60:61], v[54:55] offset0:238 offset1:255
	s_waitcnt lgkmcnt(0)
	s_barrier
	ds_read2_b64 v[54:57], v147 offset1:1
	ds_read2_b64 v[58:61], v147 offset0:2 offset1:3
	ds_read2_b64 v[62:65], v147 offset0:8 offset1:9
	ds_read2_b64 v[66:69], v147 offset0:4 offset1:5
	ds_read2_b64 v[82:85], v147 offset0:6 offset1:7
	ds_read2_b64 v[78:81], v147 offset0:12 offset1:13
	ds_read2_b64 v[86:89], v147 offset0:10 offset1:11
	ds_read2_b64 v[90:93], v147 offset0:14 offset1:15
	s_waitcnt lgkmcnt(5)
	v_pk_add_f32 v[70:71], v[54:55], v[62:63]
	v_pk_add_f32 v[54:55], v[54:55], v[62:63] neg_lo:[0,1] neg_hi:[0,1]
	s_waitcnt lgkmcnt(2)
	v_pk_add_f32 v[62:63], v[66:67], v[78:79]
	v_pk_add_f32 v[66:67], v[66:67], v[78:79] neg_lo:[0,1] neg_hi:[0,1]
	v_pk_add_f32 v[78:79], v[70:71], v[62:63]
	v_pk_add_f32 v[72:73], v[70:71], v[62:63] neg_lo:[0,1] neg_hi:[0,1]
	v_pk_add_f32 v[76:77], v[54:55], v[66:67] op_sel:[0,1] op_sel_hi:[1,0] neg_hi:[0,1]
	v_pk_add_f32 v[74:75], v[54:55], v[66:67] op_sel:[0,1] op_sel_hi:[1,0] neg_lo:[0,1]
	v_pk_add_f32 v[54:55], v[56:57], v[64:65]
	v_pk_add_f32 v[56:57], v[56:57], v[64:65] neg_lo:[0,1] neg_hi:[0,1]
	v_pk_add_f32 v[62:63], v[68:69], v[80:81]
	v_pk_add_f32 v[64:65], v[68:69], v[80:81] neg_lo:[0,1] neg_hi:[0,1]
	v_pk_add_f32 v[80:81], v[54:55], v[62:63]
	v_pk_add_f32 v[54:55], v[54:55], v[62:63] neg_lo:[0,1] neg_hi:[0,1]
	v_pk_add_f32 v[62:63], v[56:57], v[64:65] op_sel:[0,1] op_sel_hi:[1,0] neg_hi:[0,1]
	v_pk_add_f32 v[56:57], v[56:57], v[64:65] op_sel:[0,1] op_sel_hi:[1,0] neg_lo:[0,1]
	s_waitcnt lgkmcnt(1)
	v_pk_add_f32 v[64:65], v[58:59], v[86:87]
	v_pk_add_f32 v[58:59], v[58:59], v[86:87] neg_lo:[0,1] neg_hi:[0,1]
	s_waitcnt lgkmcnt(0)
	v_pk_add_f32 v[66:67], v[82:83], v[90:91]
	v_pk_add_f32 v[68:69], v[82:83], v[90:91] neg_lo:[0,1] neg_hi:[0,1]
	v_pk_add_f32 v[82:83], v[64:65], v[66:67]
	v_pk_add_f32 v[64:65], v[64:65], v[66:67] neg_lo:[0,1] neg_hi:[0,1]
	v_pk_add_f32 v[66:67], v[58:59], v[68:69] op_sel:[0,1] op_sel_hi:[1,0] neg_hi:[0,1]
	v_pk_add_f32 v[58:59], v[58:59], v[68:69] op_sel:[0,1] op_sel_hi:[1,0] neg_lo:[0,1]
	v_pk_add_f32 v[68:69], v[60:61], v[88:89]
	v_pk_add_f32 v[60:61], v[60:61], v[88:89] neg_lo:[0,1] neg_hi:[0,1]
	v_pk_add_f32 v[70:71], v[84:85], v[92:93]
	v_pk_add_f32 v[84:85], v[84:85], v[92:93] neg_lo:[0,1] neg_hi:[0,1]
	v_pk_add_f32 v[86:87], v[68:69], v[70:71]
	v_pk_add_f32 v[68:69], v[68:69], v[70:71] neg_lo:[0,1] neg_hi:[0,1]
	v_pk_add_f32 v[70:71], v[60:61], v[84:85] op_sel:[0,1] op_sel_hi:[1,0] neg_hi:[0,1]
	v_pk_add_f32 v[60:61], v[60:61], v[84:85] op_sel:[0,1] op_sel_hi:[1,0] neg_lo:[0,1]
	v_pk_mul_f32 v[84:85], v[62:63], s[20:21] op_sel:[0,0] op_sel_hi:[0,1]
	v_pk_fma_f32 v[90:91], v[62:63], s[20:21], v[84:85] op_sel:[1,1,0] op_sel_hi:[1,0,1] neg_lo:[0,1,0]
	v_pk_mul_f32 v[48:49], v[66:67], s[50:51] op_sel:[0,0] op_sel_hi:[0,1]
	s_barrier
	v_pk_fma_f32 v[94:95], v[66:67], s[50:51], v[48:49] op_sel:[1,1,0] op_sel_hi:[1,0,1] neg_lo:[0,1,0]
	v_pk_mul_f32 v[48:49], v[70:71], v[42:43] op_sel:[0,0] op_sel_hi:[0,1]
	v_pk_fma_f32 v[110:111], v[70:71], v[42:43], v[48:49] op_sel:[1,1,0] op_sel_hi:[1,0,1] neg_lo:[0,1,0]
	v_pk_mul_f32 v[48:49], v[54:55], s[50:51] op_sel:[0,0] op_sel_hi:[0,1]
	v_pk_fma_f32 v[108:109], v[54:55], s[50:51], v[48:49] op_sel:[1,1,0] op_sel_hi:[1,0,1] neg_lo:[0,1,0]
	v_pk_mul_f32 v[44:45], v[64:65], v[50:51] op_sel:[0,0] op_sel_hi:[0,1]
	v_pk_fma_f32 v[112:113], v[64:65], v[50:51], v[44:45] op_sel:[1,1,0] op_sel_hi:[1,0,1] neg_lo:[0,1,0]
	v_pk_mul_f32 v[44:45], v[68:69], v[46:47] op_sel:[0,0] op_sel_hi:[0,1]
	v_pk_fma_f32 v[116:117], v[68:69], v[46:47], v[44:45] op_sel:[1,1,0] op_sel_hi:[1,0,1] neg_lo:[0,1,0]
	v_pk_mul_f32 v[44:45], v[56:57], v[42:43] op_sel:[0,0] op_sel_hi:[0,1]
	v_pk_fma_f32 v[92:93], v[56:57], v[42:43], v[44:45] op_sel:[1,1,0] op_sel_hi:[1,0,1] neg_lo:[0,1,0]
	v_pk_mul_f32 v[42:43], v[58:59], v[46:47] op_sel:[0,0] op_sel_hi:[0,1]
	v_pk_add_f32 v[44:45], v[80:81], v[86:87] neg_lo:[0,1] neg_hi:[0,1]
	v_pk_fma_f32 v[118:119], v[58:59], v[46:47], v[42:43] op_sel:[1,1,0] op_sel_hi:[1,0,1] neg_lo:[0,1,0]
	v_pk_mul_f32 v[42:43], v[60:61], v[52:53] op_sel:[0,0] op_sel_hi:[0,1]
	v_pk_fma_f32 v[114:115], v[60:61], v[52:53], v[42:43] op_sel:[1,1,0] op_sel_hi:[1,0,1] neg_lo:[0,1,0]
	v_pk_add_f32 v[42:43], v[78:79], v[82:83] neg_lo:[0,1] neg_hi:[0,1]
	s_nop 0
	v_pk_add_f32 v[84:85], v[42:43], v[44:45] op_sel:[0,1] op_sel_hi:[1,0] neg_hi:[0,1]
	v_pk_add_f32 v[88:89], v[42:43], v[44:45] op_sel:[0,1] op_sel_hi:[1,0] neg_lo:[0,1]
	v_pk_add_f32 v[42:43], v[76:77], v[94:95] neg_lo:[0,1] neg_hi:[0,1]
	v_pk_add_f32 v[44:45], v[90:91], v[110:111] neg_lo:[0,1] neg_hi:[0,1]
	s_nop 0
	v_pk_add_f32 v[96:97], v[42:43], v[44:45] op_sel:[0,1] op_sel_hi:[1,0] neg_hi:[0,1]
	v_pk_add_f32 v[98:99], v[42:43], v[44:45] op_sel:[0,1] op_sel_hi:[1,0] neg_lo:[0,1]
	v_pk_add_f32 v[42:43], v[72:73], v[112:113] neg_lo:[0,1] neg_hi:[0,1]
	v_pk_add_f32 v[44:45], v[108:109], v[116:117] neg_lo:[0,1] neg_hi:[0,1]
	s_nop 0
	v_pk_add_f32 v[100:101], v[42:43], v[44:45] op_sel:[0,1] op_sel_hi:[1,0] neg_hi:[0,1]
	v_pk_add_f32 v[102:103], v[42:43], v[44:45] op_sel:[0,1] op_sel_hi:[1,0] neg_lo:[0,1]
	v_pk_add_f32 v[42:43], v[74:75], v[118:119] neg_lo:[0,1] neg_hi:[0,1]
	v_pk_add_f32 v[44:45], v[92:93], v[114:115] neg_lo:[0,1] neg_hi:[0,1]
	s_nop 0
	v_pk_add_f32 v[104:105], v[42:43], v[44:45] op_sel:[0,1] op_sel_hi:[1,0] neg_hi:[0,1]
	v_pk_add_f32 v[106:107], v[42:43], v[44:45] op_sel:[0,1] op_sel_hi:[1,0] neg_lo:[0,1]
	v_mov_b32_e32 v43, v138
	v_mov_b32_e32 v42, 0
	v_sub_u32_e32 v34, 0x1000, v43
	v_cndmask_b32_e32 v44, v34, v43, vcc
	v_cmp_gt_i32_e64 s[0:1], s33, v44
	v_mov_b32_e32 v34, 0
	s_and_saveexec_b64 s[82:83], s[0:1]
	s_cbranch_execz .LBB0_1297
	v_add_u32_e32 v44, v44, v120
	v_ashrrev_i32_e32 v45, 31, v44
	v_lshl_add_u64 v[44:45], v[44:45], 2, s[6:7]
	global_load_dword v34, v[44:45], off

.LBB0_1331:
	v_mov_b32_e32 v120, v30
	v_mov_b32_e32 v121, v26
	v_mov_b32_e32 v26, v31
	v_mov_b32_e32 v30, v32
	v_mov_b32_e32 v31, v28
	v_mov_b32_e32 v28, v33
	v_pk_add_f32 v[26:27], v[120:121], v[26:27]
	v_pk_add_f32 v[28:29], v[30:31], v[28:29]
	v_pk_add_f32 v[32:33], v[90:91], v[110:111]
	v_pk_add_f32 v[26:27], v[26:27], v[28:29]
	v_pk_add_f32 v[28:29], v[80:81], v[86:87]
	v_add_f32_e32 v43, v26, v27
	v_add_f32_e32 v43, 0x358637bd, v43
	v_mul_f32_e32 v43, 0x46000000, v43
	v_div_scale_f32 v45, s[0:1], v43, v43, 1.0
	v_rcp_f32_e32 v47, v45
	v_pk_add_f32 v[26:27], v[78:79], v[82:83]
	v_fma_f32 v49, -v45, v47, 1.0
	v_fmac_f32_e32 v47, v49, v47
	v_div_scale_f32 v49, vcc, 1.0, v43, 1.0
	v_mul_f32_e32 v51, v49, v47
	v_fma_f32 v53, -v45, v51, v49
	v_pk_add_f32 v[30:31], v[26:27], v[28:29]
	v_pk_add_f32 v[26:27], v[26:27], v[28:29] neg_lo:[0,1] neg_hi:[0,1]
	v_pk_add_f32 v[28:29], v[76:77], v[94:95]
	v_fmac_f32_e32 v51, v53, v47
	v_pk_add_f32 v[76:77], v[28:29], v[32:33]
	v_pk_add_f32 v[28:29], v[28:29], v[32:33] neg_lo:[0,1] neg_hi:[0,1]
	v_pk_add_f32 v[32:33], v[72:73], v[112:113]
	v_pk_add_f32 v[72:73], v[108:109], v[116:117]
	v_fma_f32 v45, -v45, v51, v49
	v_pk_add_f32 v[78:79], v[32:33], v[72:73]
	v_pk_add_f32 v[32:33], v[32:33], v[72:73] neg_lo:[0,1] neg_hi:[0,1]
	v_pk_add_f32 v[72:73], v[74:75], v[118:119]
	v_pk_add_f32 v[74:75], v[92:93], v[114:115]
	v_div_fmas_f32 v45, v45, v47, v51
	v_pk_add_f32 v[108:109], v[72:73], v[74:75]
	v_pk_add_f32 v[110:111], v[72:73], v[74:75] neg_lo:[0,1] neg_hi:[0,1]
	v_div_fixup_f32 v112, v45, v43, 1.0
	v_pk_mul_f32 v[94:95], v[112:113], v[30:31] op_sel_hi:[0,1]
	v_pk_mul_f32 v[92:93], v[112:113], v[84:85] op_sel_hi:[0,1]
	v_pk_mul_f32 v[90:91], v[112:113], v[26:27] op_sel_hi:[0,1]
	v_pk_mul_f32 v[88:89], v[112:113], v[88:89] op_sel_hi:[0,1]
	v_pk_mul_f32 v[86:87], v[112:113], v[76:77] op_sel_hi:[0,1]
	v_pk_mul_f32 v[84:85], v[112:113], v[96:97] op_sel_hi:[0,1]
	v_pk_mul_f32 v[82:83], v[112:113], v[28:29] op_sel_hi:[0,1]
	v_pk_mul_f32 v[80:81], v[112:113], v[98:99] op_sel_hi:[0,1]
	v_pk_mul_f32 v[78:79], v[112:113], v[78:79] op_sel_hi:[0,1]
	v_pk_mul_f32 v[76:77], v[112:113], v[100:101] op_sel_hi:[0,1]
	v_pk_mul_f32 v[74:75], v[112:113], v[32:33] op_sel_hi:[0,1]
	v_pk_mul_f32 v[72:73], v[112:113], v[102:103] op_sel_hi:[0,1]
	v_pk_mul_f32 v[32:33], v[112:113], v[108:109] op_sel_hi:[0,1]
	v_pk_mul_f32 v[30:31], v[112:113], v[104:105] op_sel_hi:[0,1]
	v_pk_mul_f32 v[28:29], v[112:113], v[110:111] op_sel_hi:[0,1]
	v_pk_mul_f32 v[26:27], v[112:113], v[106:107] op_sel_hi:[0,1]
	ds_read_b64 v[96:97], v144
	ds_read_b64 v[98:99], v144 offset:2176
	ds_read_b64 v[100:101], v144 offset:4352
	ds_read_b64 v[102:103], v144 offset:6528
	ds_read_b64 v[104:105], v144 offset:8704
	ds_read_b64 v[106:107], v144 offset:10880
	ds_read_b64 v[108:109], v144 offset:13056
	ds_read_b64 v[110:111], v144 offset:15232
	ds_read_b64 v[112:113], v144 offset:17408
	ds_read_b64 v[114:115], v144 offset:19584
	ds_read_b64 v[116:117], v144 offset:21760
	ds_read_b64 v[118:119], v144 offset:23936
	ds_read_b64 v[120:121], v144 offset:26112
	ds_read_b64 v[122:123], v144 offset:28288
	ds_read_b64 v[154:155], v144 offset:30464
	ds_read_b64 v[156:157], v144 offset:32640
	s_waitcnt lgkmcnt(7)
	v_pk_add_f32 v[158:159], v[96:97], v[112:113]
	v_pk_add_f32 v[96:97], v[96:97], v[112:113] neg_lo:[0,1] neg_hi:[0,1]
	s_waitcnt lgkmcnt(3)
	v_pk_add_f32 v[112:113], v[104:105], v[120:121]
	v_pk_add_f32 v[104:105], v[104:105], v[120:121] neg_lo:[0,1] neg_hi:[0,1]
	v_pk_add_f32 v[120:121], v[158:159], v[112:113]
	v_pk_add_f32 v[112:113], v[158:159], v[112:113] neg_lo:[0,1] neg_hi:[0,1]
	v_pk_add_f32 v[158:159], v[96:97], v[104:105] op_sel:[0,1] op_sel_hi:[1,0] neg_hi:[0,1]
	v_pk_add_f32 v[160:161], v[96:97], v[104:105] op_sel:[0,1] op_sel_hi:[1,0] neg_lo:[0,1]
	v_pk_add_f32 v[96:97], v[98:99], v[114:115]
	v_pk_add_f32 v[98:99], v[98:99], v[114:115] neg_lo:[0,1] neg_hi:[0,1]
	s_waitcnt lgkmcnt(2)
	v_pk_add_f32 v[104:105], v[106:107], v[122:123]
	v_pk_add_f32 v[106:107], v[106:107], v[122:123] neg_lo:[0,1] neg_hi:[0,1]
	v_pk_add_f32 v[114:115], v[96:97], v[104:105]
	v_pk_add_f32 v[104:105], v[96:97], v[104:105] neg_lo:[0,1] neg_hi:[0,1]
	v_pk_add_f32 v[96:97], v[98:99], v[106:107] op_sel:[0,1] op_sel_hi:[1,0] neg_hi:[0,1]
	v_pk_add_f32 v[106:107], v[98:99], v[106:107] op_sel:[0,1] op_sel_hi:[1,0] neg_lo:[0,1]
	v_pk_add_f32 v[98:99], v[100:101], v[116:117]
	v_pk_add_f32 v[100:101], v[100:101], v[116:117] neg_lo:[0,1] neg_hi:[0,1]
	s_waitcnt lgkmcnt(1)
	v_pk_add_f32 v[116:117], v[108:109], v[154:155]
	v_pk_add_f32 v[108:109], v[108:109], v[154:155] neg_lo:[0,1] neg_hi:[0,1]
	v_pk_add_f32 v[122:123], v[98:99], v[116:117]
	v_pk_add_f32 v[116:117], v[98:99], v[116:117] neg_lo:[0,1] neg_hi:[0,1]
	v_pk_add_f32 v[154:155], v[100:101], v[108:109] op_sel:[0,1] op_sel_hi:[1,0] neg_hi:[0,1]
	v_pk_add_f32 v[108:109], v[100:101], v[108:109] op_sel:[0,1] op_sel_hi:[1,0] neg_lo:[0,1]
	v_pk_add_f32 v[98:99], v[102:103], v[118:119]
	v_pk_add_f32 v[100:101], v[102:103], v[118:119] neg_lo:[0,1] neg_hi:[0,1]
	s_waitcnt lgkmcnt(0)
	v_pk_add_f32 v[102:103], v[110:111], v[156:157]
	v_pk_add_f32 v[110:111], v[110:111], v[156:157] neg_lo:[0,1] neg_hi:[0,1]
	v_pk_add_f32 v[118:119], v[98:99], v[102:103]
	v_pk_add_f32 v[156:157], v[98:99], v[102:103] neg_lo:[0,1] neg_hi:[0,1]
	v_pk_mul_f32 v[98:99], v[96:97], s[20:21] op_sel:[0,0] op_sel_hi:[0,1]
	v_pk_add_f32 v[162:163], v[100:101], v[110:111] op_sel:[0,1] op_sel_hi:[1,0] neg_hi:[0,1]
	v_pk_add_f32 v[110:111], v[100:101], v[110:111] op_sel:[0,1] op_sel_hi:[1,0] neg_lo:[0,1]
	v_pk_fma_f32 v[164:165], v[96:97], s[20:21], v[98:99] op_sel:[1,1,0] op_sel_hi:[1,0,1] neg_lo:[0,1,0]
	v_pk_mul_f32 v[96:97], v[154:155], s[50:51] op_sel:[0,0] op_sel_hi:[0,1]
	v_pk_fma_f32 v[154:155], v[154:155], s[50:51], v[96:97] op_sel:[1,1,0] op_sel_hi:[1,0,1] neg_lo:[0,1,0]
	v_pk_mul_f32 v[100:101], v[162:163], s[54:55] op_sel:[0,0] op_sel_hi:[0,1]
	v_pk_fma_f32 v[162:163], v[162:163], s[54:55], v[100:101] op_sel:[1,1,0] op_sel_hi:[1,0,1] neg_lo:[0,1,0]
	v_pk_mul_f32 v[100:101], v[104:105], s[50:51] op_sel:[0,0] op_sel_hi:[0,1]
	v_pk_fma_f32 v[166:167], v[104:105], s[50:51], v[100:101] op_sel:[1,1,0] op_sel_hi:[1,0,1] neg_lo:[0,1,0]
	v_pk_mul_f32 v[100:101], v[116:117], s[14:15] op_sel:[0,0] op_sel_hi:[0,1]
	v_pk_fma_f32 v[116:117], v[116:117], s[14:15], v[100:101] op_sel:[1,1,0] op_sel_hi:[1,0,1] neg_lo:[0,1,0]
	v_pk_mul_f32 v[168:169], v[156:157], s[58:59] op_sel:[0,0] op_sel_hi:[0,1]
	v_pk_fma_f32 v[156:157], v[156:157], s[58:59], v[168:169] op_sel:[1,1,0] op_sel_hi:[1,0,1] neg_lo:[0,1,0]
	v_pk_mul_f32 v[168:169], v[106:107], s[54:55] op_sel:[0,0] op_sel_hi:[0,1]
	v_pk_fma_f32 v[168:169], v[106:107], s[54:55], v[168:169] op_sel:[1,1,0] op_sel_hi:[1,0,1] neg_lo:[0,1,0]
	v_pk_mul_f32 v[106:107], v[108:109], s[58:59] op_sel:[0,0] op_sel_hi:[0,1]
	v_pk_fma_f32 v[108:109], v[108:109], s[58:59], v[106:107] op_sel:[1,1,0] op_sel_hi:[1,0,1] neg_lo:[0,1,0]
	v_pk_mul_f32 v[170:171], v[110:111], s[60:61] op_sel:[0,0] op_sel_hi:[0,1]
	v_pk_fma_f32 v[110:111], v[110:111], s[60:61], v[170:171] op_sel:[1,1,0] op_sel_hi:[1,0,1] neg_lo:[0,1,0]
	v_pk_add_f32 v[170:171], v[120:121], v[122:123]
	v_pk_add_f32 v[120:121], v[120:121], v[122:123] neg_lo:[0,1] neg_hi:[0,1]
	v_pk_add_f32 v[122:123], v[114:115], v[118:119]
	v_pk_add_f32 v[114:115], v[114:115], v[118:119] neg_lo:[0,1] neg_hi:[0,1]
	v_pk_add_f32 v[118:119], v[170:171], v[122:123]
	v_pk_add_f32 v[122:123], v[170:171], v[122:123] neg_lo:[0,1] neg_hi:[0,1]
	v_pk_add_f32 v[170:171], v[120:121], v[114:115] op_sel:[0,1] op_sel_hi:[1,0] neg_hi:[0,1]
	v_pk_add_f32 v[114:115], v[120:121], v[114:115] op_sel:[0,1] op_sel_hi:[1,0] neg_lo:[0,1]
	v_pk_add_f32 v[120:121], v[158:159], v[154:155]
	v_pk_add_f32 v[154:155], v[158:159], v[154:155] neg_lo:[0,1] neg_hi:[0,1]
	v_pk_add_f32 v[158:159], v[164:165], v[162:163]
	v_pk_add_f32 v[162:163], v[164:165], v[162:163] neg_lo:[0,1] neg_hi:[0,1]
	v_pk_add_f32 v[164:165], v[120:121], v[158:159]
	v_pk_add_f32 v[120:121], v[120:121], v[158:159] neg_lo:[0,1] neg_hi:[0,1]
	v_pk_add_f32 v[158:159], v[154:155], v[162:163] op_sel:[0,1] op_sel_hi:[1,0] neg_hi:[0,1]
	v_pk_add_f32 v[154:155], v[154:155], v[162:163] op_sel:[0,1] op_sel_hi:[1,0] neg_lo:[0,1]
	v_pk_add_f32 v[162:163], v[112:113], v[116:117]
	v_pk_add_f32 v[112:113], v[112:113], v[116:117] neg_lo:[0,1] neg_hi:[0,1]
	v_pk_add_f32 v[116:117], v[166:167], v[156:157]
	v_pk_add_f32 v[156:157], v[166:167], v[156:157] neg_lo:[0,1] neg_hi:[0,1]
	v_pk_add_f32 v[166:167], v[162:163], v[116:117]
	v_pk_add_f32 v[116:117], v[162:163], v[116:117] neg_lo:[0,1] neg_hi:[0,1]
	v_pk_add_f32 v[162:163], v[112:113], v[156:157] op_sel:[0,1] op_sel_hi:[1,0] neg_hi:[0,1]
	v_pk_add_f32 v[112:113], v[112:113], v[156:157] op_sel:[0,1] op_sel_hi:[1,0] neg_lo:[0,1]
	v_pk_add_f32 v[156:157], v[160:161], v[108:109]
	v_pk_add_f32 v[108:109], v[160:161], v[108:109] neg_lo:[0,1] neg_hi:[0,1]
	v_pk_add_f32 v[160:161], v[168:169], v[110:111]
	v_pk_add_f32 v[110:111], v[168:169], v[110:111] neg_lo:[0,1] neg_hi:[0,1]
	v_pk_add_f32 v[168:169], v[156:157], v[160:161]
	v_pk_add_f32 v[156:157], v[156:157], v[160:161] neg_lo:[0,1] neg_hi:[0,1]
	v_pk_add_f32 v[160:161], v[108:109], v[110:111] op_sel:[0,1] op_sel_hi:[1,0] neg_hi:[0,1]
	v_pk_add_f32 v[108:109], v[108:109], v[110:111] op_sel:[0,1] op_sel_hi:[1,0] neg_lo:[0,1]
	v_mov_b32_e32 v110, v38
	v_mov_b32_e32 v111, v39
	ds_write_b64 v144, v[118:119]
	v_pk_mul_f32 v[118:119], v[164:165], v[110:111] op_sel:[0,0] op_sel_hi:[0,1]
	v_pk_fma_f32 v[118:119], v[164:165], v[110:111], v[118:119] op_sel:[1,1,0] op_sel_hi:[1,0,1] neg_lo:[0,1,0]
	ds_write_b64 v144, v[118:119] offset:2176
	v_pk_mul_f32 v[118:119], v[110:111], v[110:111] op_sel:[0,0] op_sel_hi:[0,1]
	v_pk_fma_f32 v[118:119], v[110:111], v[110:111], v[118:119] op_sel:[1,1,0] op_sel_hi:[1,0,1] neg_lo:[0,1,0]
	v_pk_mul_f32 v[164:165], v[166:167], v[118:119] op_sel:[0,0] op_sel_hi:[0,1]
	v_pk_fma_f32 v[164:165], v[166:167], v[118:119], v[164:165] op_sel:[1,1,0] op_sel_hi:[1,0,1] neg_lo:[0,1,0]
	ds_write_b64 v144, v[164:165] offset:4352
	v_pk_mul_f32 v[164:165], v[118:119], v[110:111] op_sel:[0,0] op_sel_hi:[0,1]
	v_pk_fma_f32 v[118:119], v[118:119], v[110:111], v[164:165] op_sel:[1,1,0] op_sel_hi:[1,0,1] neg_lo:[0,1,0]
	v_pk_mul_f32 v[164:165], v[168:169], v[118:119] op_sel:[0,0] op_sel_hi:[0,1]
	v_pk_fma_f32 v[164:165], v[168:169], v[118:119], v[164:165] op_sel:[1,1,0] op_sel_hi:[1,0,1] neg_lo:[0,1,0]
	ds_write_b64 v144, v[164:165] offset:6528
	v_pk_mul_f32 v[164:165], v[118:119], v[110:111] op_sel:[0,0] op_sel_hi:[0,1]
	v_pk_fma_f32 v[118:119], v[118:119], v[110:111], v[164:165] op_sel:[1,1,0] op_sel_hi:[1,0,1] neg_lo:[0,1,0]
	v_pk_mul_f32 v[164:165], v[170:171], v[118:119] op_sel:[0,0] op_sel_hi:[0,1]
	v_pk_fma_f32 v[164:165], v[170:171], v[118:119], v[164:165] op_sel:[1,1,0] op_sel_hi:[1,0,1] neg_lo:[0,1,0]
	ds_write_b64 v144, v[164:165] offset:8704
	v_pk_mul_f32 v[164:165], v[118:119], v[110:111] op_sel:[0,0] op_sel_hi:[0,1]
	v_pk_fma_f32 v[118:119], v[118:119], v[110:111], v[164:165] op_sel:[1,1,0] op_sel_hi:[1,0,1] neg_lo:[0,1,0]
	v_pk_mul_f32 v[164:165], v[158:159], v[118:119] op_sel:[0,0] op_sel_hi:[0,1]
	v_pk_fma_f32 v[158:159], v[158:159], v[118:119], v[164:165] op_sel:[1,1,0] op_sel_hi:[1,0,1] neg_lo:[0,1,0]
	ds_write_b64 v144, v[158:159] offset:10880
	v_pk_mul_f32 v[158:159], v[118:119], v[110:111] op_sel:[0,0] op_sel_hi:[0,1]
	v_pk_fma_f32 v[118:119], v[118:119], v[110:111], v[158:159] op_sel:[1,1,0] op_sel_hi:[1,0,1] neg_lo:[0,1,0]
	v_pk_mul_f32 v[158:159], v[162:163], v[118:119] op_sel:[0,0] op_sel_hi:[0,1]
	v_pk_fma_f32 v[158:159], v[162:163], v[118:119], v[158:159] op_sel:[1,1,0] op_sel_hi:[1,0,1] neg_lo:[0,1,0]
	ds_write_b64 v144, v[158:159] offset:13056
	v_pk_mul_f32 v[158:159], v[118:119], v[110:111] op_sel:[0,0] op_sel_hi:[0,1]
	v_pk_fma_f32 v[118:119], v[118:119], v[110:111], v[158:159] op_sel:[1,1,0] op_sel_hi:[1,0,1] neg_lo:[0,1,0]
	v_pk_mul_f32 v[158:159], v[160:161], v[118:119] op_sel:[0,0] op_sel_hi:[0,1]
	v_pk_fma_f32 v[158:159], v[160:161], v[118:119], v[158:159] op_sel:[1,1,0] op_sel_hi:[1,0,1] neg_lo:[0,1,0]
	ds_write_b64 v144, v[158:159] offset:15232
	v_pk_mul_f32 v[158:159], v[118:119], v[110:111] op_sel:[0,0] op_sel_hi:[0,1]
	v_pk_fma_f32 v[118:119], v[118:119], v[110:111], v[158:159] op_sel:[1,1,0] op_sel_hi:[1,0,1] neg_lo:[0,1,0]
	v_pk_mul_f32 v[158:159], v[122:123], v[118:119] op_sel:[0,0] op_sel_hi:[0,1]
	v_pk_fma_f32 v[122:123], v[122:123], v[118:119], v[158:159] op_sel:[1,1,0] op_sel_hi:[1,0,1] neg_lo:[0,1,0]
	ds_write_b64 v144, v[122:123] offset:17408
	v_pk_mul_f32 v[122:123], v[118:119], v[110:111] op_sel:[0,0] op_sel_hi:[0,1]
	v_pk_fma_f32 v[118:119], v[118:119], v[110:111], v[122:123] op_sel:[1,1,0] op_sel_hi:[1,0,1] neg_lo:[0,1,0]
	v_pk_mul_f32 v[122:123], v[120:121], v[118:119] op_sel:[0,0] op_sel_hi:[0,1]
	v_pk_fma_f32 v[120:121], v[120:121], v[118:119], v[122:123] op_sel:[1,1,0] op_sel_hi:[1,0,1] neg_lo:[0,1,0]
	ds_write_b64 v144, v[120:121] offset:19584
	v_pk_mul_f32 v[120:121], v[118:119], v[110:111] op_sel:[0,0] op_sel_hi:[0,1]
	v_pk_fma_f32 v[118:119], v[118:119], v[110:111], v[120:121] op_sel:[1,1,0] op_sel_hi:[1,0,1] neg_lo:[0,1,0]
	v_pk_mul_f32 v[120:121], v[116:117], v[118:119] op_sel:[0,0] op_sel_hi:[0,1]
	v_pk_fma_f32 v[116:117], v[116:117], v[118:119], v[120:121] op_sel:[1,1,0] op_sel_hi:[1,0,1] neg_lo:[0,1,0]
	ds_write_b64 v144, v[116:117] offset:21760
	v_pk_mul_f32 v[116:117], v[118:119], v[110:111] op_sel:[0,0] op_sel_hi:[0,1]
	v_pk_fma_f32 v[116:117], v[118:119], v[110:111], v[116:117] op_sel:[1,1,0] op_sel_hi:[1,0,1] neg_lo:[0,1,0]
	v_pk_mul_f32 v[118:119], v[156:157], v[116:117] op_sel:[0,0] op_sel_hi:[0,1]
	v_pk_fma_f32 v[118:119], v[156:157], v[116:117], v[118:119] op_sel:[1,1,0] op_sel_hi:[1,0,1] neg_lo:[0,1,0]
	ds_write_b64 v144, v[118:119] offset:23936
	v_pk_mul_f32 v[118:119], v[116:117], v[110:111] op_sel:[0,0] op_sel_hi:[0,1]
	v_pk_fma_f32 v[116:117], v[116:117], v[110:111], v[118:119] op_sel:[1,1,0] op_sel_hi:[1,0,1] neg_lo:[0,1,0]
	v_pk_mul_f32 v[118:119], v[114:115], v[116:117] op_sel:[0,0] op_sel_hi:[0,1]
	v_pk_fma_f32 v[114:115], v[114:115], v[116:117], v[118:119] op_sel:[1,1,0] op_sel_hi:[1,0,1] neg_lo:[0,1,0]
	ds_write_b64 v144, v[114:115] offset:26112
	v_pk_mul_f32 v[114:115], v[116:117], v[110:111] op_sel:[0,0] op_sel_hi:[0,1]
	v_pk_fma_f32 v[114:115], v[116:117], v[110:111], v[114:115] op_sel:[1,1,0] op_sel_hi:[1,0,1] neg_lo:[0,1,0]
	v_pk_mul_f32 v[116:117], v[154:155], v[114:115] op_sel:[0,0] op_sel_hi:[0,1]
	v_pk_fma_f32 v[116:117], v[154:155], v[114:115], v[116:117] op_sel:[1,1,0] op_sel_hi:[1,0,1] neg_lo:[0,1,0]
	ds_write_b64 v144, v[116:117] offset:28288
	v_pk_mul_f32 v[116:117], v[114:115], v[110:111] op_sel:[0,0] op_sel_hi:[0,1]
	v_pk_fma_f32 v[114:115], v[114:115], v[110:111], v[116:117] op_sel:[1,1,0] op_sel_hi:[1,0,1] neg_lo:[0,1,0]
	v_pk_mul_f32 v[116:117], v[112:113], v[114:115] op_sel:[0,0] op_sel_hi:[0,1]
	v_pk_fma_f32 v[112:113], v[112:113], v[114:115], v[116:117] op_sel:[1,1,0] op_sel_hi:[1,0,1] neg_lo:[0,1,0]
	ds_write_b64 v144, v[112:113] offset:30464
	v_pk_mul_f32 v[112:113], v[114:115], v[110:111] op_sel:[0,0] op_sel_hi:[0,1]
	v_pk_fma_f32 v[110:111], v[114:115], v[110:111], v[112:113] op_sel:[1,1,0] op_sel_hi:[1,0,1] neg_lo:[0,1,0]
	v_pk_mul_f32 v[112:113], v[108:109], v[110:111] op_sel:[0,0] op_sel_hi:[0,1]
	v_pk_fma_f32 v[108:109], v[108:109], v[110:111], v[112:113] op_sel:[1,1,0] op_sel_hi:[1,0,1] neg_lo:[0,1,0]
	ds_write_b64 v144, v[108:109] offset:32640
	s_waitcnt lgkmcnt(0)
	s_barrier
	ds_read2_b64 v[108:111], v146 offset1:17
	ds_read2_b64 v[112:115], v146 offset0:34 offset1:51
	ds_read2_b64 v[116:119], v146 offset0:68 offset1:85
	ds_read2_b64 v[120:123], v146 offset0:136 offset1:153
	ds_read2_b64 v[154:157], v146 offset0:102 offset1:119
	ds_read2_b64 v[158:161], v146 offset0:204 offset1:221
	ds_read2_b64 v[162:165], v146 offset0:170 offset1:187
	ds_read2_b64 v[166:169], v146 offset0:238 offset1:255
	s_waitcnt lgkmcnt(4)
	v_pk_add_f32 v[170:171], v[108:109], v[120:121]
	v_pk_add_f32 v[108:109], v[108:109], v[120:121] neg_lo:[0,1] neg_hi:[0,1]
	s_waitcnt lgkmcnt(2)
	v_pk_add_f32 v[120:121], v[116:117], v[158:159]
	v_pk_add_f32 v[116:117], v[116:117], v[158:159] neg_lo:[0,1] neg_hi:[0,1]
	v_pk_add_f32 v[158:159], v[170:171], v[120:121]
	v_pk_add_f32 v[120:121], v[170:171], v[120:121] neg_lo:[0,1] neg_hi:[0,1]
	v_pk_add_f32 v[170:171], v[108:109], v[116:117] op_sel:[0,1] op_sel_hi:[1,0] neg_hi:[0,1]
	v_pk_add_f32 v[108:109], v[108:109], v[116:117] op_sel:[0,1] op_sel_hi:[1,0] neg_lo:[0,1]
	v_pk_add_f32 v[116:117], v[110:111], v[122:123]
	v_pk_add_f32 v[110:111], v[110:111], v[122:123] neg_lo:[0,1] neg_hi:[0,1]
	v_pk_add_f32 v[122:123], v[118:119], v[160:161]
	v_pk_add_f32 v[118:119], v[118:119], v[160:161] neg_lo:[0,1] neg_hi:[0,1]
	v_pk_add_f32 v[160:161], v[116:117], v[122:123]
	v_pk_add_f32 v[116:117], v[116:117], v[122:123] neg_lo:[0,1] neg_hi:[0,1]
	v_pk_add_f32 v[122:123], v[110:111], v[118:119] op_sel:[0,1] op_sel_hi:[1,0] neg_hi:[0,1]
	v_pk_add_f32 v[110:111], v[110:111], v[118:119] op_sel:[0,1] op_sel_hi:[1,0] neg_lo:[0,1]
	s_waitcnt lgkmcnt(1)
	v_pk_add_f32 v[118:119], v[112:113], v[162:163]
	v_pk_add_f32 v[112:113], v[112:113], v[162:163] neg_lo:[0,1] neg_hi:[0,1]
	s_waitcnt lgkmcnt(0)
	v_pk_add_f32 v[162:163], v[154:155], v[166:167]
	v_pk_add_f32 v[154:155], v[154:155], v[166:167] neg_lo:[0,1] neg_hi:[0,1]
	v_pk_add_f32 v[166:167], v[118:119], v[162:163]
	v_pk_add_f32 v[118:119], v[118:119], v[162:163] neg_lo:[0,1] neg_hi:[0,1]
	v_pk_add_f32 v[162:163], v[112:113], v[154:155] op_sel:[0,1] op_sel_hi:[1,0] neg_hi:[0,1]
	v_pk_add_f32 v[112:113], v[112:113], v[154:155] op_sel:[0,1] op_sel_hi:[1,0] neg_lo:[0,1]
	v_pk_add_f32 v[154:155], v[114:115], v[164:165]
	v_pk_add_f32 v[114:115], v[114:115], v[164:165] neg_lo:[0,1] neg_hi:[0,1]
	v_pk_add_f32 v[164:165], v[156:157], v[168:169]
	v_pk_add_f32 v[156:157], v[156:157], v[168:169] neg_lo:[0,1] neg_hi:[0,1]
	v_pk_add_f32 v[168:169], v[154:155], v[164:165]
	v_pk_add_f32 v[154:155], v[154:155], v[164:165] neg_lo:[0,1] neg_hi:[0,1]
	v_pk_add_f32 v[164:165], v[114:115], v[156:157] op_sel:[0,1] op_sel_hi:[1,0] neg_hi:[0,1]
	v_pk_add_f32 v[114:115], v[114:115], v[156:157] op_sel:[0,1] op_sel_hi:[1,0] neg_lo:[0,1]
	v_pk_mul_f32 v[156:157], v[122:123], s[20:21] op_sel:[0,0] op_sel_hi:[0,1]
	v_pk_fma_f32 v[122:123], v[122:123], s[20:21], v[156:157] op_sel:[1,1,0] op_sel_hi:[1,0,1] neg_lo:[0,1,0]
	v_pk_mul_f32 v[156:157], v[162:163], s[50:51] op_sel:[0,0] op_sel_hi:[0,1]
	v_pk_fma_f32 v[156:157], v[162:163], s[50:51], v[156:157] op_sel:[1,1,0] op_sel_hi:[1,0,1] neg_lo:[0,1,0]
	v_pk_mul_f32 v[162:163], v[164:165], s[54:55] op_sel:[0,0] op_sel_hi:[0,1]
	v_pk_fma_f32 v[162:163], v[164:165], s[54:55], v[162:163] op_sel:[1,1,0] op_sel_hi:[1,0,1] neg_lo:[0,1,0]
	v_pk_mul_f32 v[164:165], v[116:117], s[50:51] op_sel:[0,0] op_sel_hi:[0,1]
	v_pk_fma_f32 v[116:117], v[116:117], s[50:51], v[164:165] op_sel:[1,1,0] op_sel_hi:[1,0,1] neg_lo:[0,1,0]
	v_pk_mul_f32 v[164:165], v[118:119], s[14:15] op_sel:[0,0] op_sel_hi:[0,1]
	v_pk_fma_f32 v[118:119], v[118:119], s[14:15], v[164:165] op_sel:[1,1,0] op_sel_hi:[1,0,1] neg_lo:[0,1,0]
	v_pk_mul_f32 v[164:165], v[154:155], s[58:59] op_sel:[0,0] op_sel_hi:[0,1]
	v_pk_fma_f32 v[154:155], v[154:155], s[58:59], v[164:165] op_sel:[1,1,0] op_sel_hi:[1,0,1] neg_lo:[0,1,0]
	v_pk_mul_f32 v[164:165], v[110:111], s[54:55] op_sel:[0,0] op_sel_hi:[0,1]
	v_pk_fma_f32 v[110:111], v[110:111], s[54:55], v[164:165] op_sel:[1,1,0] op_sel_hi:[1,0,1] neg_lo:[0,1,0]
	v_pk_mul_f32 v[164:165], v[112:113], s[58:59] op_sel:[0,0] op_sel_hi:[0,1]
	v_pk_fma_f32 v[112:113], v[112:113], s[58:59], v[164:165] op_sel:[1,1,0] op_sel_hi:[1,0,1] neg_lo:[0,1,0]
	v_pk_mul_f32 v[164:165], v[114:115], s[60:61] op_sel:[0,0] op_sel_hi:[0,1]
	v_pk_fma_f32 v[114:115], v[114:115], s[60:61], v[164:165] op_sel:[1,1,0] op_sel_hi:[1,0,1] neg_lo:[0,1,0]
	v_pk_add_f32 v[164:165], v[158:159], v[166:167]
	v_pk_add_f32 v[158:159], v[158:159], v[166:167] neg_lo:[0,1] neg_hi:[0,1]
	v_pk_add_f32 v[166:167], v[160:161], v[168:169]
	v_pk_add_f32 v[160:161], v[160:161], v[168:169] neg_lo:[0,1] neg_hi:[0,1]
	v_pk_add_f32 v[168:169], v[164:165], v[166:167]
	v_pk_add_f32 v[164:165], v[164:165], v[166:167] neg_lo:[0,1] neg_hi:[0,1]
	v_pk_add_f32 v[166:167], v[158:159], v[160:161] op_sel:[0,1] op_sel_hi:[1,0] neg_hi:[0,1]
	v_pk_add_f32 v[158:159], v[158:159], v[160:161] op_sel:[0,1] op_sel_hi:[1,0] neg_lo:[0,1]
	v_pk_add_f32 v[160:161], v[170:171], v[156:157]
	v_pk_add_f32 v[156:157], v[170:171], v[156:157] neg_lo:[0,1] neg_hi:[0,1]
	v_pk_add_f32 v[170:171], v[122:123], v[162:163]
	v_pk_add_f32 v[122:123], v[122:123], v[162:163] neg_lo:[0,1] neg_hi:[0,1]
	v_pk_add_f32 v[162:163], v[160:161], v[170:171]
	v_pk_add_f32 v[160:161], v[160:161], v[170:171] neg_lo:[0,1] neg_hi:[0,1]
	v_pk_add_f32 v[170:171], v[156:157], v[122:123] op_sel:[0,1] op_sel_hi:[1,0] neg_hi:[0,1]
	v_pk_add_f32 v[122:123], v[156:157], v[122:123] op_sel:[0,1] op_sel_hi:[1,0] neg_lo:[0,1]
	v_pk_add_f32 v[156:157], v[120:121], v[118:119]
	v_pk_add_f32 v[118:119], v[120:121], v[118:119] neg_lo:[0,1] neg_hi:[0,1]
	v_pk_add_f32 v[120:121], v[116:117], v[154:155]
	v_pk_add_f32 v[116:117], v[116:117], v[154:155] neg_lo:[0,1] neg_hi:[0,1]
	v_pk_add_f32 v[154:155], v[156:157], v[120:121]
	v_pk_add_f32 v[120:121], v[156:157], v[120:121] neg_lo:[0,1] neg_hi:[0,1]
	v_pk_add_f32 v[156:157], v[118:119], v[116:117] op_sel:[0,1] op_sel_hi:[1,0] neg_hi:[0,1]
	v_pk_add_f32 v[116:117], v[118:119], v[116:117] op_sel:[0,1] op_sel_hi:[1,0] neg_lo:[0,1]
	v_pk_add_f32 v[118:119], v[108:109], v[112:113]
	v_pk_add_f32 v[108:109], v[108:109], v[112:113] neg_lo:[0,1] neg_hi:[0,1]
	v_pk_add_f32 v[112:113], v[110:111], v[114:115]
	v_pk_add_f32 v[110:111], v[110:111], v[114:115] neg_lo:[0,1] neg_hi:[0,1]
	v_pk_add_f32 v[114:115], v[118:119], v[112:113]
	v_pk_add_f32 v[112:113], v[118:119], v[112:113] neg_lo:[0,1] neg_hi:[0,1]
	v_pk_add_f32 v[118:119], v[108:109], v[110:111] op_sel:[0,1] op_sel_hi:[1,0] neg_hi:[0,1]
	v_pk_add_f32 v[108:109], v[108:109], v[110:111] op_sel:[0,1] op_sel_hi:[1,0] neg_lo:[0,1]
	v_mov_b32_e32 v110, v40
	v_mov_b32_e32 v111, v41
	s_nop 0
	v_pk_mul_f32 v[172:173], v[162:163], v[110:111] op_sel:[0,0] op_sel_hi:[0,1]
	v_pk_fma_f32 v[162:163], v[162:163], v[110:111], v[172:173] op_sel:[1,1,0] op_sel_hi:[1,0,1] neg_lo:[0,1,0]
	ds_write2_b64 v146, v[168:169], v[162:163] offset1:17
	v_pk_mul_f32 v[162:163], v[110:111], v[110:111] op_sel:[0,0] op_sel_hi:[0,1]
	v_pk_fma_f32 v[162:163], v[110:111], v[110:111], v[162:163] op_sel:[1,1,0] op_sel_hi:[1,0,1] neg_lo:[0,1,0]
	v_pk_mul_f32 v[168:169], v[154:155], v[162:163] op_sel:[0,0] op_sel_hi:[0,1]
	v_pk_fma_f32 v[154:155], v[154:155], v[162:163], v[168:169] op_sel:[1,1,0] op_sel_hi:[1,0,1] neg_lo:[0,1,0]
	v_pk_mul_f32 v[168:169], v[162:163], v[110:111] op_sel:[0,0] op_sel_hi:[0,1]
	v_pk_fma_f32 v[162:163], v[162:163], v[110:111], v[168:169] op_sel:[1,1,0] op_sel_hi:[1,0,1] neg_lo:[0,1,0]
	v_pk_mul_f32 v[168:169], v[114:115], v[162:163] op_sel:[0,0] op_sel_hi:[0,1]
	v_pk_fma_f32 v[114:115], v[114:115], v[162:163], v[168:169] op_sel:[1,1,0] op_sel_hi:[1,0,1] neg_lo:[0,1,0]
	ds_write2_b64 v146, v[154:155], v[114:115] offset0:34 offset1:51
	v_pk_mul_f32 v[114:115], v[162:163], v[110:111] op_sel:[0,0] op_sel_hi:[0,1]
	v_pk_fma_f32 v[114:115], v[162:163], v[110:111], v[114:115] op_sel:[1,1,0] op_sel_hi:[1,0,1] neg_lo:[0,1,0]
	v_pk_mul_f32 v[154:155], v[166:167], v[114:115] op_sel:[0,0] op_sel_hi:[0,1]
	v_pk_mul_f32 v[162:163], v[114:115], v[110:111] op_sel:[0,0] op_sel_hi:[0,1]
	v_pk_fma_f32 v[154:155], v[166:167], v[114:115], v[154:155] op_sel:[1,1,0] op_sel_hi:[1,0,1] neg_lo:[0,1,0]
	v_pk_fma_f32 v[114:115], v[114:115], v[110:111], v[162:163] op_sel:[1,1,0] op_sel_hi:[1,0,1] neg_lo:[0,1,0]
	v_pk_mul_f32 v[162:163], v[170:171], v[114:115] op_sel:[0,0] op_sel_hi:[0,1]
	v_pk_fma_f32 v[162:163], v[170:171], v[114:115], v[162:163] op_sel:[1,1,0] op_sel_hi:[1,0,1] neg_lo:[0,1,0]
	ds_write2_b64 v146, v[154:155], v[162:163] offset0:68 offset1:85
	v_pk_mul_f32 v[154:155], v[114:115], v[110:111] op_sel:[0,0] op_sel_hi:[0,1]
	v_pk_fma_f32 v[114:115], v[114:115], v[110:111], v[154:155] op_sel:[1,1,0] op_sel_hi:[1,0,1] neg_lo:[0,1,0]
	v_pk_mul_f32 v[154:155], v[156:157], v[114:115] op_sel:[0,0] op_sel_hi:[0,1]
	v_pk_fma_f32 v[154:155], v[156:157], v[114:115], v[154:155] op_sel:[1,1,0] op_sel_hi:[1,0,1] neg_lo:[0,1,0]
	v_pk_mul_f32 v[156:157], v[114:115], v[110:111] op_sel:[0,0] op_sel_hi:[0,1]
	v_pk_fma_f32 v[114:115], v[114:115], v[110:111], v[156:157] op_sel:[1,1,0] op_sel_hi:[1,0,1] neg_lo:[0,1,0]
	v_pk_mul_f32 v[156:157], v[118:119], v[114:115] op_sel:[0,0] op_sel_hi:[0,1]
	v_pk_fma_f32 v[118:119], v[118:119], v[114:115], v[156:157] op_sel:[1,1,0] op_sel_hi:[1,0,1] neg_lo:[0,1,0]
	ds_write2_b64 v146, v[154:155], v[118:119] offset0:102 offset1:119
	v_pk_mul_f32 v[118:119], v[114:115], v[110:111] op_sel:[0,0] op_sel_hi:[0,1]
	v_pk_fma_f32 v[114:115], v[114:115], v[110:111], v[118:119] op_sel:[1,1,0] op_sel_hi:[1,0,1] neg_lo:[0,1,0]
	v_pk_mul_f32 v[118:119], v[164:165], v[114:115] op_sel:[0,0] op_sel_hi:[0,1]
	v_pk_mul_f32 v[154:155], v[114:115], v[110:111] op_sel:[0,0] op_sel_hi:[0,1]
	v_pk_fma_f32 v[118:119], v[164:165], v[114:115], v[118:119] op_sel:[1,1,0] op_sel_hi:[1,0,1] neg_lo:[0,1,0]
	v_pk_fma_f32 v[114:115], v[114:115], v[110:111], v[154:155] op_sel:[1,1,0] op_sel_hi:[1,0,1] neg_lo:[0,1,0]
	v_pk_mul_f32 v[154:155], v[160:161], v[114:115] op_sel:[0,0] op_sel_hi:[0,1]
	v_pk_fma_f32 v[154:155], v[160:161], v[114:115], v[154:155] op_sel:[1,1,0] op_sel_hi:[1,0,1] neg_lo:[0,1,0]
	ds_write2_b64 v146, v[118:119], v[154:155] offset0:136 offset1:153
	v_pk_mul_f32 v[118:119], v[114:115], v[110:111] op_sel:[0,0] op_sel_hi:[0,1]
	v_pk_fma_f32 v[114:115], v[114:115], v[110:111], v[118:119] op_sel:[1,1,0] op_sel_hi:[1,0,1] neg_lo:[0,1,0]
	v_pk_mul_f32 v[118:119], v[120:121], v[114:115] op_sel:[0,0] op_sel_hi:[0,1]
	v_pk_fma_f32 v[118:119], v[120:121], v[114:115], v[118:119] op_sel:[1,1,0] op_sel_hi:[1,0,1] neg_lo:[0,1,0]
	v_pk_mul_f32 v[120:121], v[114:115], v[110:111] op_sel:[0,0] op_sel_hi:[0,1]
	v_pk_fma_f32 v[114:115], v[114:115], v[110:111], v[120:121] op_sel:[1,1,0] op_sel_hi:[1,0,1] neg_lo:[0,1,0]
	v_pk_mul_f32 v[120:121], v[112:113], v[114:115] op_sel:[0,0] op_sel_hi:[0,1]
	v_pk_fma_f32 v[112:113], v[112:113], v[114:115], v[120:121] op_sel:[1,1,0] op_sel_hi:[1,0,1] neg_lo:[0,1,0]
	ds_write2_b64 v146, v[118:119], v[112:113] offset0:170 offset1:187
	v_pk_mul_f32 v[112:113], v[114:115], v[110:111] op_sel:[0,0] op_sel_hi:[0,1]
	v_pk_fma_f32 v[112:113], v[114:115], v[110:111], v[112:113] op_sel:[1,1,0] op_sel_hi:[1,0,1] neg_lo:[0,1,0]
	v_pk_mul_f32 v[114:115], v[158:159], v[112:113] op_sel:[0,0] op_sel_hi:[0,1]
	v_pk_mul_f32 v[118:119], v[112:113], v[110:111] op_sel:[0,0] op_sel_hi:[0,1]
	v_pk_fma_f32 v[114:115], v[158:159], v[112:113], v[114:115] op_sel:[1,1,0] op_sel_hi:[1,0,1] neg_lo:[0,1,0]
	v_pk_fma_f32 v[112:113], v[112:113], v[110:111], v[118:119] op_sel:[1,1,0] op_sel_hi:[1,0,1] neg_lo:[0,1,0]
	v_pk_mul_f32 v[118:119], v[122:123], v[112:113] op_sel:[0,0] op_sel_hi:[0,1]
	v_pk_fma_f32 v[118:119], v[122:123], v[112:113], v[118:119] op_sel:[1,1,0] op_sel_hi:[1,0,1] neg_lo:[0,1,0]
	ds_write2_b64 v146, v[114:115], v[118:119] offset0:204 offset1:221
	v_pk_mul_f32 v[114:115], v[112:113], v[110:111] op_sel:[0,0] op_sel_hi:[0,1]
	v_pk_fma_f32 v[112:113], v[112:113], v[110:111], v[114:115] op_sel:[1,1,0] op_sel_hi:[1,0,1] neg_lo:[0,1,0]
	v_pk_mul_f32 v[114:115], v[116:117], v[112:113] op_sel:[0,0] op_sel_hi:[0,1]
	v_pk_fma_f32 v[114:115], v[116:117], v[112:113], v[114:115] op_sel:[1,1,0] op_sel_hi:[1,0,1] neg_lo:[0,1,0]
	v_pk_mul_f32 v[116:117], v[112:113], v[110:111] op_sel:[0,0] op_sel_hi:[0,1]
	v_pk_fma_f32 v[110:111], v[112:113], v[110:111], v[116:117] op_sel:[1,1,0] op_sel_hi:[1,0,1] neg_lo:[0,1,0]
	v_pk_mul_f32 v[112:113], v[108:109], v[110:111] op_sel:[0,0] op_sel_hi:[0,1]
	v_pk_fma_f32 v[108:109], v[108:109], v[110:111], v[112:113] op_sel:[1,1,0] op_sel_hi:[1,0,1] neg_lo:[0,1,0]
	ds_write2_b64 v146, v[114:115], v[108:109] offset0:238 offset1:255
	s_waitcnt lgkmcnt(0)
	s_barrier
	ds_read2_b64 v[108:111], v147 offset1:1
	ds_read2_b64 v[112:115], v147 offset0:2 offset1:3
	ds_read2_b64 v[116:119], v147 offset0:8 offset1:9
	ds_read2_b64 v[120:123], v147 offset0:4 offset1:5
	ds_read2_b64 v[154:157], v147 offset0:6 offset1:7
	ds_read2_b64 v[158:161], v147 offset0:12 offset1:13
	ds_read2_b64 v[162:165], v147 offset0:10 offset1:11
	ds_read2_b64 v[166:169], v147 offset0:14 offset1:15
	s_waitcnt lgkmcnt(5)
	v_pk_add_f32 v[170:171], v[108:109], v[116:117]
	v_pk_add_f32 v[108:109], v[108:109], v[116:117] neg_lo:[0,1] neg_hi:[0,1]
	s_waitcnt lgkmcnt(2)
	v_pk_add_f32 v[116:117], v[120:121], v[158:159]
	v_pk_add_f32 v[120:121], v[120:121], v[158:159] neg_lo:[0,1] neg_hi:[0,1]
	v_pk_add_f32 v[158:159], v[170:171], v[116:117]
	v_pk_add_f32 v[116:117], v[170:171], v[116:117] neg_lo:[0,1] neg_hi:[0,1]
	v_pk_add_f32 v[170:171], v[108:109], v[120:121] op_sel:[0,1] op_sel_hi:[1,0] neg_hi:[0,1]
	v_pk_add_f32 v[108:109], v[108:109], v[120:121] op_sel:[0,1] op_sel_hi:[1,0] neg_lo:[0,1]
	v_pk_add_f32 v[120:121], v[110:111], v[118:119]
	v_pk_add_f32 v[110:111], v[110:111], v[118:119] neg_lo:[0,1] neg_hi:[0,1]
	v_pk_add_f32 v[118:119], v[122:123], v[160:161]
	v_pk_add_f32 v[122:123], v[122:123], v[160:161] neg_lo:[0,1] neg_hi:[0,1]
	v_pk_add_f32 v[160:161], v[120:121], v[118:119]
	v_pk_add_f32 v[118:119], v[120:121], v[118:119] neg_lo:[0,1] neg_hi:[0,1]
	v_pk_add_f32 v[120:121], v[110:111], v[122:123] op_sel:[0,1] op_sel_hi:[1,0] neg_hi:[0,1]
	v_pk_add_f32 v[110:111], v[110:111], v[122:123] op_sel:[0,1] op_sel_hi:[1,0] neg_lo:[0,1]
	s_waitcnt lgkmcnt(1)
	v_pk_add_f32 v[122:123], v[112:113], v[162:163]
	v_pk_add_f32 v[112:113], v[112:113], v[162:163] neg_lo:[0,1] neg_hi:[0,1]
	s_waitcnt lgkmcnt(0)
	v_pk_add_f32 v[162:163], v[154:155], v[166:167]
	v_pk_add_f32 v[154:155], v[154:155], v[166:167] neg_lo:[0,1] neg_hi:[0,1]
	v_pk_add_f32 v[166:167], v[122:123], v[162:163]
	v_pk_add_f32 v[122:123], v[122:123], v[162:163] neg_lo:[0,1] neg_hi:[0,1]
	v_pk_add_f32 v[162:163], v[112:113], v[154:155] op_sel:[0,1] op_sel_hi:[1,0] neg_hi:[0,1]
	v_pk_add_f32 v[112:113], v[112:113], v[154:155] op_sel:[0,1] op_sel_hi:[1,0] neg_lo:[0,1]
	v_pk_add_f32 v[154:155], v[114:115], v[164:165]
	v_pk_add_f32 v[114:115], v[114:115], v[164:165] neg_lo:[0,1] neg_hi:[0,1]
	v_pk_add_f32 v[164:165], v[156:157], v[168:169]
	v_pk_add_f32 v[156:157], v[156:157], v[168:169] neg_lo:[0,1] neg_hi:[0,1]
	v_pk_add_f32 v[168:169], v[154:155], v[164:165]
	v_pk_add_f32 v[154:155], v[154:155], v[164:165] neg_lo:[0,1] neg_hi:[0,1]
	v_pk_add_f32 v[164:165], v[114:115], v[156:157] op_sel:[0,1] op_sel_hi:[1,0] neg_hi:[0,1]
	v_pk_add_f32 v[114:115], v[114:115], v[156:157] op_sel:[0,1] op_sel_hi:[1,0] neg_lo:[0,1]
	v_pk_mul_f32 v[156:157], v[120:121], s[20:21] op_sel:[0,0] op_sel_hi:[0,1]
	v_pk_fma_f32 v[102:103], v[120:121], s[20:21], v[156:157] op_sel:[1,1,0] op_sel_hi:[1,0,1] neg_lo:[0,1,0]
	v_pk_mul_f32 v[120:121], v[162:163], s[50:51] op_sel:[0,0] op_sel_hi:[0,1]
	v_pk_mul_f32 v[156:157], v[164:165], s[54:55] op_sel:[0,0] op_sel_hi:[0,1]
	v_pk_fma_f32 v[120:121], v[162:163], s[50:51], v[120:121] op_sel:[1,1,0] op_sel_hi:[1,0,1] neg_lo:[0,1,0]
	v_pk_mul_f32 v[162:163], v[118:119], s[50:51] op_sel:[0,0] op_sel_hi:[0,1]
	v_pk_fma_f32 v[156:157], v[164:165], s[54:55], v[156:157] op_sel:[1,1,0] op_sel_hi:[1,0,1] neg_lo:[0,1,0]
	v_pk_fma_f32 v[98:99], v[118:119], s[50:51], v[162:163] op_sel:[1,1,0] op_sel_hi:[1,0,1] neg_lo:[0,1,0]
	v_pk_mul_f32 v[118:119], v[122:123], s[14:15] op_sel:[0,0] op_sel_hi:[0,1]
	v_pk_fma_f32 v[104:105], v[122:123], s[14:15], v[118:119] op_sel:[1,1,0] op_sel_hi:[1,0,1] neg_lo:[0,1,0]
	v_pk_mul_f32 v[118:119], v[154:155], s[58:59] op_sel:[0,0] op_sel_hi:[0,1]
	v_pk_mul_f32 v[122:123], v[110:111], s[54:55] op_sel:[0,0] op_sel_hi:[0,1]
	v_pk_fma_f32 v[96:97], v[110:111], s[54:55], v[122:123] op_sel:[1,1,0] op_sel_hi:[1,0,1] neg_lo:[0,1,0]
	v_pk_mul_f32 v[110:111], v[112:113], s[58:59] op_sel:[0,0] op_sel_hi:[0,1]
	v_pk_fma_f32 v[118:119], v[154:155], s[58:59], v[118:119] op_sel:[1,1,0] op_sel_hi:[1,0,1] neg_lo:[0,1,0]
	v_pk_add_f32 v[122:123], v[160:161], v[168:169] neg_lo:[0,1] neg_hi:[0,1]
	v_pk_fma_f32 v[100:101], v[112:113], s[58:59], v[110:111] op_sel:[1,1,0] op_sel_hi:[1,0,1] neg_lo:[0,1,0]
	v_pk_mul_f32 v[110:111], v[114:115], s[60:61] op_sel:[0,0] op_sel_hi:[0,1]
	v_pk_add_f32 v[112:113], v[158:159], v[166:167] neg_lo:[0,1] neg_hi:[0,1]
	v_pk_fma_f32 v[106:107], v[114:115], s[60:61], v[110:111] op_sel:[1,1,0] op_sel_hi:[1,0,1] neg_lo:[0,1,0]
	v_pk_add_f32 v[110:111], v[158:159], v[166:167]
	v_pk_add_f32 v[114:115], v[160:161], v[168:169]
	v_pk_add_f32 v[158:159], v[102:103], v[156:157]
	v_pk_add_f32 v[154:155], v[110:111], v[114:115]
	v_pk_add_f32 v[110:111], v[110:111], v[114:115] neg_lo:[0,1] neg_hi:[0,1]
	v_pk_add_f32 v[114:115], v[112:113], v[122:123] op_sel:[0,1] op_sel_hi:[1,0] neg_hi:[0,1]
	v_pk_add_f32 v[112:113], v[112:113], v[122:123] op_sel:[0,1] op_sel_hi:[1,0] neg_lo:[0,1]
	v_pk_add_f32 v[122:123], v[170:171], v[120:121]
	v_pk_add_f32 v[120:121], v[170:171], v[120:121] neg_lo:[0,1] neg_hi:[0,1]
	v_pk_add_f32 v[102:103], v[102:103], v[156:157] neg_lo:[0,1] neg_hi:[0,1]
	v_pk_add_f32 v[156:157], v[122:123], v[158:159]
	v_pk_add_f32 v[122:123], v[122:123], v[158:159] neg_lo:[0,1] neg_hi:[0,1]
	v_pk_add_f32 v[158:159], v[120:121], v[102:103] op_sel:[0,1] op_sel_hi:[1,0] neg_hi:[0,1]
	v_pk_add_f32 v[102:103], v[120:121], v[102:103] op_sel:[0,1] op_sel_hi:[1,0] neg_lo:[0,1]
	v_pk_add_f32 v[120:121], v[116:117], v[104:105]
	v_pk_add_f32 v[104:105], v[116:117], v[104:105] neg_lo:[0,1] neg_hi:[0,1]
	v_pk_add_f32 v[116:117], v[98:99], v[118:119]
	v_pk_add_f32 v[98:99], v[98:99], v[118:119] neg_lo:[0,1] neg_hi:[0,1]
	v_pk_add_f32 v[118:119], v[120:121], v[116:117]
	v_pk_add_f32 v[116:117], v[120:121], v[116:117] neg_lo:[0,1] neg_hi:[0,1]
	v_pk_add_f32 v[120:121], v[104:105], v[98:99] op_sel:[0,1] op_sel_hi:[1,0] neg_hi:[0,1]
	v_pk_add_f32 v[98:99], v[104:105], v[98:99] op_sel:[0,1] op_sel_hi:[1,0] neg_lo:[0,1]
	v_pk_add_f32 v[104:105], v[108:109], v[100:101]
	v_pk_add_f32 v[100:101], v[108:109], v[100:101] neg_lo:[0,1] neg_hi:[0,1]
	v_pk_add_f32 v[108:109], v[96:97], v[106:107]
	v_pk_add_f32 v[96:97], v[96:97], v[106:107] neg_lo:[0,1] neg_hi:[0,1]
	v_pk_add_f32 v[106:107], v[104:105], v[108:109]
	v_pk_add_f32 v[104:105], v[104:105], v[108:109] neg_lo:[0,1] neg_hi:[0,1]
	v_pk_add_f32 v[108:109], v[100:101], v[96:97] op_sel:[0,1] op_sel_hi:[1,0] neg_hi:[0,1]
	v_pk_add_f32 v[96:97], v[100:101], v[96:97] op_sel:[0,1] op_sel_hi:[1,0] neg_lo:[0,1]
	v_pk_mul_f32 v[100:101], v[154:155], v[94:95] op_sel:[0,0] op_sel_hi:[0,1]
	v_pk_fma_f32 v[94:95], v[154:155], v[94:95], v[100:101] op_sel:[1,1,0] op_sel_hi:[1,0,1] neg_lo:[0,1,0]
	v_pk_mul_f32 v[100:101], v[114:115], v[92:93] op_sel:[0,0] op_sel_hi:[0,1]
	v_pk_fma_f32 v[92:93], v[114:115], v[92:93], v[100:101] op_sel:[1,1,0] op_sel_hi:[1,0,1] neg_lo:[0,1,0]
	v_pk_mul_f32 v[100:101], v[110:111], v[90:91] op_sel:[0,0] op_sel_hi:[0,1]
	v_pk_fma_f32 v[90:91], v[110:111], v[90:91], v[100:101] op_sel:[1,1,0] op_sel_hi:[1,0,1] neg_lo:[0,1,0]
	v_pk_mul_f32 v[100:101], v[112:113], v[88:89] op_sel:[0,0] op_sel_hi:[0,1]
	v_pk_fma_f32 v[88:89], v[112:113], v[88:89], v[100:101] op_sel:[1,1,0] op_sel_hi:[1,0,1] neg_lo:[0,1,0]
	v_pk_mul_f32 v[100:101], v[156:157], v[86:87] op_sel:[0,0] op_sel_hi:[0,1]
	v_pk_fma_f32 v[86:87], v[156:157], v[86:87], v[100:101] op_sel:[1,1,0] op_sel_hi:[1,0,1] neg_lo:[0,1,0]
	v_pk_mul_f32 v[100:101], v[158:159], v[84:85] op_sel:[0,0] op_sel_hi:[0,1]
	v_pk_fma_f32 v[84:85], v[158:159], v[84:85], v[100:101] op_sel:[1,1,0] op_sel_hi:[1,0,1] neg_lo:[0,1,0]
	v_pk_mul_f32 v[100:101], v[122:123], v[82:83] op_sel:[0,0] op_sel_hi:[0,1]
	v_pk_fma_f32 v[82:83], v[122:123], v[82:83], v[100:101] op_sel:[1,1,0] op_sel_hi:[1,0,1] neg_lo:[0,1,0]
	v_pk_mul_f32 v[100:101], v[102:103], v[80:81] op_sel:[0,0] op_sel_hi:[0,1]
	v_pk_fma_f32 v[80:81], v[102:103], v[80:81], v[100:101] op_sel:[1,1,0] op_sel_hi:[1,0,1] neg_lo:[0,1,0]
	v_pk_mul_f32 v[100:101], v[118:119], v[78:79] op_sel:[0,0] op_sel_hi:[0,1]
	v_pk_fma_f32 v[78:79], v[118:119], v[78:79], v[100:101] op_sel:[1,1,0] op_sel_hi:[1,0,1] neg_lo:[0,1,0]
	v_pk_mul_f32 v[100:101], v[120:121], v[76:77] op_sel:[0,0] op_sel_hi:[0,1]
	v_pk_fma_f32 v[76:77], v[120:121], v[76:77], v[100:101] op_sel:[1,1,0] op_sel_hi:[1,0,1] neg_lo:[0,1,0]
	v_pk_mul_f32 v[100:101], v[116:117], v[74:75] op_sel:[0,0] op_sel_hi:[0,1]
	v_pk_fma_f32 v[74:75], v[116:117], v[74:75], v[100:101] op_sel:[1,1,0] op_sel_hi:[1,0,1] neg_lo:[0,1,0]
	v_pk_mul_f32 v[100:101], v[98:99], v[72:73] op_sel:[0,0] op_sel_hi:[0,1]
	v_pk_fma_f32 v[72:73], v[98:99], v[72:73], v[100:101] op_sel:[1,1,0] op_sel_hi:[1,0,1] neg_lo:[0,1,0]
	v_pk_mul_f32 v[98:99], v[106:107], v[32:33] op_sel:[0,0] op_sel_hi:[0,1]
	v_pk_fma_f32 v[32:33], v[106:107], v[32:33], v[98:99] op_sel:[1,1,0] op_sel_hi:[1,0,1] neg_lo:[0,1,0]
	v_pk_mul_f32 v[98:99], v[108:109], v[30:31] op_sel:[0,0] op_sel_hi:[0,1]
	v_pk_fma_f32 v[30:31], v[108:109], v[30:31], v[98:99] op_sel:[1,1,0] op_sel_hi:[1,0,1] neg_lo:[0,1,0]
	v_pk_mul_f32 v[98:99], v[104:105], v[28:29] op_sel:[0,0] op_sel_hi:[0,1]
	v_pk_fma_f32 v[28:29], v[104:105], v[28:29], v[98:99] op_sel:[1,1,0] op_sel_hi:[1,0,1] neg_lo:[0,1,0]
	v_pk_mul_f32 v[98:99], v[96:97], v[26:27] op_sel:[0,0] op_sel_hi:[0,1]
	v_pk_fma_f32 v[26:27], v[96:97], v[26:27], v[98:99] op_sel:[1,1,0] op_sel_hi:[1,0,1] neg_lo:[0,1,0]
	v_pk_add_f32 v[96:97], v[94:95], v[90:91]
	v_pk_add_f32 v[90:91], v[94:95], v[90:91] neg_lo:[0,1] neg_hi:[0,1]
	v_pk_add_f32 v[94:95], v[92:93], v[88:89]
	v_pk_add_f32 v[88:89], v[92:93], v[88:89] neg_lo:[0,1] neg_hi:[0,1]
	v_pk_add_f32 v[92:93], v[96:97], v[94:95]
	v_pk_add_f32 v[94:95], v[96:97], v[94:95] neg_lo:[0,1] neg_hi:[0,1]
	v_pk_add_f32 v[96:97], v[90:91], v[88:89] op_sel:[0,1] op_sel_hi:[1,0] neg_lo:[0,1]
	v_pk_add_f32 v[88:89], v[90:91], v[88:89] op_sel:[0,1] op_sel_hi:[1,0] neg_hi:[0,1]
	v_pk_add_f32 v[90:91], v[86:87], v[82:83]
	v_pk_add_f32 v[82:83], v[86:87], v[82:83] neg_lo:[0,1] neg_hi:[0,1]
	v_pk_add_f32 v[86:87], v[84:85], v[80:81]
	v_pk_add_f32 v[80:81], v[84:85], v[80:81] neg_lo:[0,1] neg_hi:[0,1]
	v_pk_add_f32 v[84:85], v[90:91], v[86:87]
	v_pk_add_f32 v[86:87], v[90:91], v[86:87] neg_lo:[0,1] neg_hi:[0,1]
	v_pk_add_f32 v[90:91], v[82:83], v[80:81] op_sel:[0,1] op_sel_hi:[1,0] neg_lo:[0,1]
	v_pk_add_f32 v[80:81], v[82:83], v[80:81] op_sel:[0,1] op_sel_hi:[1,0] neg_hi:[0,1]
	v_pk_add_f32 v[82:83], v[78:79], v[74:75]
	v_pk_add_f32 v[74:75], v[78:79], v[74:75] neg_lo:[0,1] neg_hi:[0,1]
	v_pk_add_f32 v[78:79], v[76:77], v[72:73]
	v_pk_add_f32 v[72:73], v[76:77], v[72:73] neg_lo:[0,1] neg_hi:[0,1]
	v_pk_add_f32 v[76:77], v[82:83], v[78:79]
	v_pk_add_f32 v[78:79], v[82:83], v[78:79] neg_lo:[0,1] neg_hi:[0,1]
	v_pk_add_f32 v[82:83], v[74:75], v[72:73] op_sel:[0,1] op_sel_hi:[1,0] neg_lo:[0,1]
	v_pk_add_f32 v[74:75], v[74:75], v[72:73] op_sel:[0,1] op_sel_hi:[1,0] neg_hi:[0,1]
	v_pk_add_f32 v[72:73], v[32:33], v[28:29]
	v_pk_add_f32 v[28:29], v[32:33], v[28:29] neg_lo:[0,1] neg_hi:[0,1]
	v_pk_add_f32 v[32:33], v[30:31], v[26:27]
	v_pk_add_f32 v[26:27], v[30:31], v[26:27] neg_lo:[0,1] neg_hi:[0,1]
	v_pk_add_f32 v[98:99], v[72:73], v[32:33]
	v_pk_add_f32 v[100:101], v[72:73], v[32:33] neg_lo:[0,1] neg_hi:[0,1]
	v_pk_add_f32 v[30:31], v[28:29], v[26:27] op_sel:[0,1] op_sel_hi:[1,0] neg_lo:[0,1]
	v_pk_add_f32 v[102:103], v[28:29], v[26:27] op_sel:[0,1] op_sel_hi:[1,0] neg_hi:[0,1]
	v_pk_mul_f32 v[26:27], v[90:91], s[62:63] op_sel:[0,0] op_sel_hi:[0,1]
	v_pk_fma_f32 v[90:91], v[90:91], s[62:63], v[26:27] op_sel:[1,1,0] op_sel_hi:[1,0,1] neg_lo:[0,1,0]
	v_pk_mul_f32 v[26:27], v[82:83], s[64:65] op_sel:[0,0] op_sel_hi:[0,1]
	v_pk_fma_f32 v[82:83], v[82:83], s[64:65], v[26:27] op_sel:[1,1,0] op_sel_hi:[1,0,1] neg_lo:[0,1,0]
	v_pk_mul_f32 v[72:73], v[30:31], s[66:67] op_sel:[0,0] op_sel_hi:[0,1]
	v_pk_fma_f32 v[104:105], v[30:31], s[66:67], v[72:73] op_sel:[1,1,0] op_sel_hi:[1,0,1] neg_lo:[0,1,0]
	v_pk_mul_f32 v[30:31], v[86:87], s[64:65] op_sel:[0,0] op_sel_hi:[0,1]
	v_pk_fma_f32 v[86:87], v[86:87], s[64:65], v[30:31] op_sel:[1,1,0] op_sel_hi:[1,0,1] neg_lo:[0,1,0]
	v_pk_mul_f32 v[30:31], v[78:79], s[68:69] op_sel:[0,0] op_sel_hi:[0,1]
	v_pk_fma_f32 v[78:79], v[78:79], s[68:69], v[30:31] op_sel:[1,1,0] op_sel_hi:[1,0,1] neg_lo:[0,1,0]
	v_pk_mul_f32 v[106:107], v[100:101], s[70:71] op_sel:[0,0] op_sel_hi:[0,1]
	v_pk_fma_f32 v[100:101], v[100:101], s[70:71], v[106:107] op_sel:[1,1,0] op_sel_hi:[1,0,1] neg_lo:[0,1,0]
	v_pk_mul_f32 v[106:107], v[80:81], s[66:67] op_sel:[0,0] op_sel_hi:[0,1]
	v_pk_fma_f32 v[80:81], v[80:81], s[66:67], v[106:107] op_sel:[1,1,0] op_sel_hi:[1,0,1] neg_lo:[0,1,0]
	v_pk_mul_f32 v[106:107], v[74:75], s[70:71] op_sel:[0,0] op_sel_hi:[0,1]
	v_pk_fma_f32 v[106:107], v[74:75], s[70:71], v[106:107] op_sel:[1,1,0] op_sel_hi:[1,0,1] neg_lo:[0,1,0]
	v_pk_mul_f32 v[108:109], v[102:103], s[72:73] op_sel:[0,0] op_sel_hi:[0,1]
	v_pk_fma_f32 v[102:103], v[102:103], s[72:73], v[108:109] op_sel:[1,1,0] op_sel_hi:[1,0,1] neg_lo:[0,1,0]
	v_pk_add_f32 v[108:109], v[92:93], v[76:77]
	v_pk_add_f32 v[76:77], v[92:93], v[76:77] neg_lo:[0,1] neg_hi:[0,1]
	v_pk_add_f32 v[92:93], v[84:85], v[98:99]
	v_pk_add_f32 v[84:85], v[84:85], v[98:99] neg_lo:[0,1] neg_hi:[0,1]
	v_pk_add_f32 v[98:99], v[108:109], v[92:93]
	v_pk_add_f32 v[92:93], v[108:109], v[92:93] neg_lo:[0,1] neg_hi:[0,1]
	v_pk_add_f32 v[108:109], v[76:77], v[84:85] op_sel:[0,1] op_sel_hi:[1,0] neg_lo:[0,1]
	v_pk_add_f32 v[76:77], v[76:77], v[84:85] op_sel:[0,1] op_sel_hi:[1,0] neg_hi:[0,1]
	v_pk_add_f32 v[84:85], v[96:97], v[82:83]
	v_pk_add_f32 v[82:83], v[96:97], v[82:83] neg_lo:[0,1] neg_hi:[0,1]
	v_pk_add_f32 v[96:97], v[90:91], v[104:105]
	v_pk_add_f32 v[90:91], v[90:91], v[104:105] neg_lo:[0,1] neg_hi:[0,1]
	v_pk_add_f32 v[104:105], v[84:85], v[96:97]
	v_pk_add_f32 v[84:85], v[84:85], v[96:97] neg_lo:[0,1] neg_hi:[0,1]
	v_pk_add_f32 v[96:97], v[82:83], v[90:91] op_sel:[0,1] op_sel_hi:[1,0] neg_lo:[0,1]
	v_pk_add_f32 v[82:83], v[82:83], v[90:91] op_sel:[0,1] op_sel_hi:[1,0] neg_hi:[0,1]
	v_pk_add_f32 v[90:91], v[94:95], v[78:79]
	v_pk_add_f32 v[78:79], v[94:95], v[78:79] neg_lo:[0,1] neg_hi:[0,1]
	v_pk_add_f32 v[94:95], v[86:87], v[100:101]
	v_pk_add_f32 v[86:87], v[86:87], v[100:101] neg_lo:[0,1] neg_hi:[0,1]
	v_pk_add_f32 v[100:101], v[90:91], v[94:95]
	v_pk_add_f32 v[90:91], v[90:91], v[94:95] neg_lo:[0,1] neg_hi:[0,1]
	v_pk_add_f32 v[94:95], v[78:79], v[86:87] op_sel:[0,1] op_sel_hi:[1,0] neg_lo:[0,1]
	v_pk_add_f32 v[78:79], v[78:79], v[86:87] op_sel:[0,1] op_sel_hi:[1,0] neg_hi:[0,1]
	v_pk_add_f32 v[86:87], v[88:89], v[106:107]
	v_pk_add_f32 v[88:89], v[88:89], v[106:107] neg_lo:[0,1] neg_hi:[0,1]
	v_pk_add_f32 v[106:107], v[80:81], v[102:103]
	v_pk_add_f32 v[80:81], v[80:81], v[102:103] neg_lo:[0,1] neg_hi:[0,1]
	v_pk_add_f32 v[102:103], v[86:87], v[106:107]
	v_pk_add_f32 v[86:87], v[86:87], v[106:107] neg_lo:[0,1] neg_hi:[0,1]
	v_pk_add_f32 v[106:107], v[88:89], v[80:81] op_sel:[0,1] op_sel_hi:[1,0] neg_lo:[0,1]
	v_pk_add_f32 v[80:81], v[88:89], v[80:81] op_sel:[0,1] op_sel_hi:[1,0] neg_hi:[0,1]
	ds_write2_b64 v147, v[98:99], v[104:105] offset1:1
	ds_write2_b64 v147, v[100:101], v[102:103] offset0:2 offset1:3
	ds_write2_b64 v147, v[108:109], v[96:97] offset0:4 offset1:5
	ds_write2_b64 v147, v[94:95], v[106:107] offset0:6 offset1:7
	ds_write2_b64 v147, v[92:93], v[84:85] offset0:8 offset1:9
	ds_write2_b64 v147, v[90:91], v[86:87] offset0:10 offset1:11
	ds_write2_b64 v147, v[76:77], v[82:83] offset0:12 offset1:13
	ds_write2_b64 v147, v[78:79], v[80:81] offset0:14 offset1:15
	v_mov_b32_e32 v86, v40
	v_mov_b32_e32 v87, v41
	s_waitcnt lgkmcnt(0)
	s_barrier
	ds_read2_b64 v[76:79], v146 offset1:17
	ds_read2_b64 v[80:83], v146 offset0:34 offset1:51
	s_waitcnt lgkmcnt(1)
	v_pk_mul_f32 v[84:85], v[78:79], v[86:87] op_sel:[0,0] op_sel_hi:[0,1] neg_hi:[0,1]
	v_pk_fma_f32 v[88:89], v[78:79], v[86:87], v[84:85] op_sel:[1,1,0] op_sel_hi:[1,0,1]
	v_pk_mul_f32 v[78:79], v[86:87], v[86:87] op_sel:[0,0] op_sel_hi:[0,1]
	v_pk_fma_f32 v[78:79], v[86:87], v[86:87], v[78:79] op_sel:[1,1,0] op_sel_hi:[1,0,1] neg_lo:[0,1,0]
	s_waitcnt lgkmcnt(0)
	v_pk_mul_f32 v[84:85], v[80:81], v[78:79] op_sel:[0,0] op_sel_hi:[0,1] neg_hi:[0,1]
	v_pk_fma_f32 v[90:91], v[80:81], v[78:79], v[84:85] op_sel:[1,1,0] op_sel_hi:[1,0,1]
	v_pk_mul_f32 v[80:81], v[78:79], v[86:87] op_sel:[0,0] op_sel_hi:[0,1]
	v_pk_fma_f32 v[84:85], v[78:79], v[86:87], v[80:81] op_sel:[1,1,0] op_sel_hi:[1,0,1] neg_lo:[0,1,0]
	ds_read2_b64 v[78:81], v146 offset0:68 offset1:85
	v_pk_mul_f32 v[92:93], v[82:83], v[84:85] op_sel:[0,0] op_sel_hi:[0,1] neg_hi:[0,1]
	v_pk_fma_f32 v[92:93], v[82:83], v[84:85], v[92:93] op_sel:[1,1,0] op_sel_hi:[1,0,1]
	v_pk_mul_f32 v[82:83], v[84:85], v[86:87] op_sel:[0,0] op_sel_hi:[0,1]
	v_pk_fma_f32 v[82:83], v[84:85], v[86:87], v[82:83] op_sel:[1,1,0] op_sel_hi:[1,0,1] neg_lo:[0,1,0]
	s_waitcnt lgkmcnt(0)
	v_pk_mul_f32 v[84:85], v[78:79], v[82:83] op_sel:[0,0] op_sel_hi:[0,1] neg_hi:[0,1]
	v_pk_fma_f32 v[94:95], v[78:79], v[82:83], v[84:85] op_sel:[1,1,0] op_sel_hi:[1,0,1]
	v_pk_mul_f32 v[78:79], v[82:83], v[86:87] op_sel:[0,0] op_sel_hi:[0,1]
	v_pk_fma_f32 v[78:79], v[82:83], v[86:87], v[78:79] op_sel:[1,1,0] op_sel_hi:[1,0,1] neg_lo:[0,1,0]
	ds_read2_b64 v[82:85], v146 offset0:102 offset1:119
	v_pk_mul_f32 v[96:97], v[80:81], v[78:79] op_sel:[0,0] op_sel_hi:[0,1] neg_hi:[0,1]
	v_pk_fma_f32 v[96:97], v[80:81], v[78:79], v[96:97] op_sel:[1,1,0] op_sel_hi:[1,0,1]
	v_pk_mul_f32 v[80:81], v[78:79], v[86:87] op_sel:[0,0] op_sel_hi:[0,1]
	v_pk_fma_f32 v[78:79], v[78:79], v[86:87], v[80:81] op_sel:[1,1,0] op_sel_hi:[1,0,1] neg_lo:[0,1,0]
	s_waitcnt lgkmcnt(0)
	v_pk_mul_f32 v[80:81], v[82:83], v[78:79] op_sel:[0,0] op_sel_hi:[0,1] neg_hi:[0,1]
	v_pk_fma_f32 v[98:99], v[82:83], v[78:79], v[80:81] op_sel:[1,1,0] op_sel_hi:[1,0,1]
	v_pk_mul_f32 v[80:81], v[78:79], v[86:87] op_sel:[0,0] op_sel_hi:[0,1]
	v_pk_fma_f32 v[82:83], v[78:79], v[86:87], v[80:81] op_sel:[1,1,0] op_sel_hi:[1,0,1] neg_lo:[0,1,0]
	ds_read2_b64 v[78:81], v146 offset0:136 offset1:153
	v_pk_mul_f32 v[100:101], v[84:85], v[82:83] op_sel:[0,0] op_sel_hi:[0,1] neg_hi:[0,1]
	v_pk_fma_f32 v[100:101], v[84:85], v[82:83], v[100:101] op_sel:[1,1,0] op_sel_hi:[1,0,1]
	v_pk_mul_f32 v[84:85], v[82:83], v[86:87] op_sel:[0,0] op_sel_hi:[0,1]
	v_pk_fma_f32 v[82:83], v[82:83], v[86:87], v[84:85] op_sel:[1,1,0] op_sel_hi:[1,0,1] neg_lo:[0,1,0]
	s_waitcnt lgkmcnt(0)
	v_pk_mul_f32 v[84:85], v[78:79], v[82:83] op_sel:[0,0] op_sel_hi:[0,1] neg_hi:[0,1]
	v_pk_fma_f32 v[102:103], v[78:79], v[82:83], v[84:85] op_sel:[1,1,0] op_sel_hi:[1,0,1]
	v_pk_mul_f32 v[78:79], v[82:83], v[86:87] op_sel:[0,0] op_sel_hi:[0,1]
	v_pk_fma_f32 v[78:79], v[82:83], v[86:87], v[78:79] op_sel:[1,1,0] op_sel_hi:[1,0,1] neg_lo:[0,1,0]
	ds_read2_b64 v[82:85], v146 offset0:170 offset1:187
	v_pk_mul_f32 v[104:105], v[80:81], v[78:79] op_sel:[0,0] op_sel_hi:[0,1] neg_hi:[0,1]
	v_pk_fma_f32 v[104:105], v[80:81], v[78:79], v[104:105] op_sel:[1,1,0] op_sel_hi:[1,0,1]
	v_pk_mul_f32 v[80:81], v[78:79], v[86:87] op_sel:[0,0] op_sel_hi:[0,1]
	v_pk_fma_f32 v[78:79], v[78:79], v[86:87], v[80:81] op_sel:[1,1,0] op_sel_hi:[1,0,1] neg_lo:[0,1,0]
	s_waitcnt lgkmcnt(0)
	v_pk_mul_f32 v[80:81], v[82:83], v[78:79] op_sel:[0,0] op_sel_hi:[0,1] neg_hi:[0,1]
	v_pk_fma_f32 v[106:107], v[82:83], v[78:79], v[80:81] op_sel:[1,1,0] op_sel_hi:[1,0,1]
	v_pk_mul_f32 v[80:81], v[78:79], v[86:87] op_sel:[0,0] op_sel_hi:[0,1]
	v_pk_fma_f32 v[82:83], v[78:79], v[86:87], v[80:81] op_sel:[1,1,0] op_sel_hi:[1,0,1] neg_lo:[0,1,0]
	ds_read2_b64 v[78:81], v146 offset0:204 offset1:221
	v_pk_mul_f32 v[108:109], v[84:85], v[82:83] op_sel:[0,0] op_sel_hi:[0,1] neg_hi:[0,1]
	v_pk_fma_f32 v[108:109], v[84:85], v[82:83], v[108:109] op_sel:[1,1,0] op_sel_hi:[1,0,1]
	v_pk_mul_f32 v[84:85], v[82:83], v[86:87] op_sel:[0,0] op_sel_hi:[0,1]
	v_pk_fma_f32 v[82:83], v[82:83], v[86:87], v[84:85] op_sel:[1,1,0] op_sel_hi:[1,0,1] neg_lo:[0,1,0]
	s_waitcnt lgkmcnt(0)
	v_pk_mul_f32 v[84:85], v[78:79], v[82:83] op_sel:[0,0] op_sel_hi:[0,1] neg_hi:[0,1]
	v_pk_fma_f32 v[78:79], v[78:79], v[82:83], v[84:85] op_sel:[1,1,0] op_sel_hi:[1,0,1]
	v_pk_mul_f32 v[84:85], v[82:83], v[86:87] op_sel:[0,0] op_sel_hi:[0,1]
	v_pk_fma_f32 v[110:111], v[82:83], v[86:87], v[84:85] op_sel:[1,1,0] op_sel_hi:[1,0,1] neg_lo:[0,1,0]
	ds_read2_b64 v[82:85], v146 offset0:238 offset1:255
	v_pk_mul_f32 v[112:113], v[80:81], v[110:111] op_sel:[0,0] op_sel_hi:[0,1] neg_hi:[0,1]
	v_pk_fma_f32 v[80:81], v[80:81], v[110:111], v[112:113] op_sel:[1,1,0] op_sel_hi:[1,0,1]
	v_pk_mul_f32 v[112:113], v[110:111], v[86:87] op_sel:[0,0] op_sel_hi:[0,1]
	v_pk_fma_f32 v[110:111], v[110:111], v[86:87], v[112:113] op_sel:[1,1,0] op_sel_hi:[1,0,1] neg_lo:[0,1,0]
	s_waitcnt lgkmcnt(0)
	v_pk_mul_f32 v[112:113], v[82:83], v[110:111] op_sel:[0,0] op_sel_hi:[0,1] neg_hi:[0,1]
	v_pk_fma_f32 v[82:83], v[82:83], v[110:111], v[112:113] op_sel:[1,1,0] op_sel_hi:[1,0,1]
	v_pk_mul_f32 v[112:113], v[110:111], v[86:87] op_sel:[0,0] op_sel_hi:[0,1]
	v_pk_fma_f32 v[86:87], v[110:111], v[86:87], v[112:113] op_sel:[1,1,0] op_sel_hi:[1,0,1] neg_lo:[0,1,0]
	v_pk_mul_f32 v[110:111], v[84:85], v[86:87] op_sel:[0,0] op_sel_hi:[0,1] neg_hi:[0,1]
	v_pk_fma_f32 v[84:85], v[84:85], v[86:87], v[110:111] op_sel:[1,1,0] op_sel_hi:[1,0,1]
	v_pk_add_f32 v[86:87], v[76:77], v[102:103]
	v_pk_add_f32 v[76:77], v[76:77], v[102:103] neg_lo:[0,1] neg_hi:[0,1]
	v_pk_add_f32 v[102:103], v[94:95], v[78:79]
	v_pk_add_f32 v[78:79], v[94:95], v[78:79] neg_lo:[0,1] neg_hi:[0,1]
	v_pk_add_f32 v[94:95], v[86:87], v[102:103]
	v_pk_add_f32 v[86:87], v[86:87], v[102:103] neg_lo:[0,1] neg_hi:[0,1]
	v_pk_add_f32 v[102:103], v[76:77], v[78:79] op_sel:[0,1] op_sel_hi:[1,0] neg_lo:[0,1]
	v_pk_add_f32 v[76:77], v[76:77], v[78:79] op_sel:[0,1] op_sel_hi:[1,0] neg_hi:[0,1]
	v_pk_add_f32 v[78:79], v[88:89], v[104:105]
	v_pk_add_f32 v[88:89], v[88:89], v[104:105] neg_lo:[0,1] neg_hi:[0,1]
	v_pk_add_f32 v[104:105], v[96:97], v[80:81]
	v_pk_add_f32 v[80:81], v[96:97], v[80:81] neg_lo:[0,1] neg_hi:[0,1]
	v_pk_add_f32 v[96:97], v[78:79], v[104:105]
	v_pk_add_f32 v[78:79], v[78:79], v[104:105] neg_lo:[0,1] neg_hi:[0,1]
	v_pk_add_f32 v[104:105], v[88:89], v[80:81] op_sel:[0,1] op_sel_hi:[1,0] neg_lo:[0,1]
	v_pk_add_f32 v[80:81], v[88:89], v[80:81] op_sel:[0,1] op_sel_hi:[1,0] neg_hi:[0,1]
	v_pk_add_f32 v[88:89], v[90:91], v[106:107]
	v_pk_add_f32 v[90:91], v[90:91], v[106:107] neg_lo:[0,1] neg_hi:[0,1]
	v_pk_add_f32 v[106:107], v[98:99], v[82:83]
	v_pk_add_f32 v[82:83], v[98:99], v[82:83] neg_lo:[0,1] neg_hi:[0,1]
	v_pk_add_f32 v[98:99], v[88:89], v[106:107]
	v_pk_add_f32 v[88:89], v[88:89], v[106:107] neg_lo:[0,1] neg_hi:[0,1]
	v_pk_add_f32 v[106:107], v[90:91], v[82:83] op_sel:[0,1] op_sel_hi:[1,0] neg_lo:[0,1]
	v_pk_add_f32 v[82:83], v[90:91], v[82:83] op_sel:[0,1] op_sel_hi:[1,0] neg_hi:[0,1]
	v_pk_add_f32 v[90:91], v[92:93], v[108:109]
	v_pk_add_f32 v[92:93], v[92:93], v[108:109] neg_lo:[0,1] neg_hi:[0,1]
	v_pk_add_f32 v[108:109], v[100:101], v[84:85]
	v_pk_add_f32 v[84:85], v[100:101], v[84:85] neg_lo:[0,1] neg_hi:[0,1]
	v_pk_add_f32 v[100:101], v[90:91], v[108:109]
	v_pk_add_f32 v[90:91], v[90:91], v[108:109] neg_lo:[0,1] neg_hi:[0,1]
	v_pk_add_f32 v[108:109], v[92:93], v[84:85] op_sel:[0,1] op_sel_hi:[1,0] neg_lo:[0,1]
	v_pk_add_f32 v[84:85], v[92:93], v[84:85] op_sel:[0,1] op_sel_hi:[1,0] neg_hi:[0,1]
	v_pk_mul_f32 v[92:93], v[104:105], s[62:63] op_sel:[0,0] op_sel_hi:[0,1]
	v_pk_fma_f32 v[92:93], v[104:105], s[62:63], v[92:93] op_sel:[1,1,0] op_sel_hi:[1,0,1] neg_lo:[0,1,0]
	v_pk_mul_f32 v[104:105], v[106:107], s[64:65] op_sel:[0,0] op_sel_hi:[0,1]
	v_pk_fma_f32 v[104:105], v[106:107], s[64:65], v[104:105] op_sel:[1,1,0] op_sel_hi:[1,0,1] neg_lo:[0,1,0]
	v_pk_mul_f32 v[106:107], v[108:109], s[66:67] op_sel:[0,0] op_sel_hi:[0,1]
	v_pk_fma_f32 v[106:107], v[108:109], s[66:67], v[106:107] op_sel:[1,1,0] op_sel_hi:[1,0,1] neg_lo:[0,1,0]
	v_pk_mul_f32 v[108:109], v[78:79], s[64:65] op_sel:[0,0] op_sel_hi:[0,1]
	v_pk_fma_f32 v[78:79], v[78:79], s[64:65], v[108:109] op_sel:[1,1,0] op_sel_hi:[1,0,1] neg_lo:[0,1,0]
	v_pk_mul_f32 v[108:109], v[88:89], s[68:69] op_sel:[0,0] op_sel_hi:[0,1]
	v_pk_fma_f32 v[88:89], v[88:89], s[68:69], v[108:109] op_sel:[1,1,0] op_sel_hi:[1,0,1] neg_lo:[0,1,0]
	v_pk_mul_f32 v[108:109], v[90:91], s[70:71] op_sel:[0,0] op_sel_hi:[0,1]
	v_pk_fma_f32 v[90:91], v[90:91], s[70:71], v[108:109] op_sel:[1,1,0] op_sel_hi:[1,0,1] neg_lo:[0,1,0]
	v_pk_mul_f32 v[108:109], v[80:81], s[66:67] op_sel:[0,0] op_sel_hi:[0,1]
	v_pk_fma_f32 v[80:81], v[80:81], s[66:67], v[108:109] op_sel:[1,1,0] op_sel_hi:[1,0,1] neg_lo:[0,1,0]
	v_pk_mul_f32 v[108:109], v[82:83], s[70:71] op_sel:[0,0] op_sel_hi:[0,1]
	v_pk_fma_f32 v[82:83], v[82:83], s[70:71], v[108:109] op_sel:[1,1,0] op_sel_hi:[1,0,1] neg_lo:[0,1,0]
	v_pk_mul_f32 v[108:109], v[84:85], s[72:73] op_sel:[0,0] op_sel_hi:[0,1]
	v_pk_fma_f32 v[84:85], v[84:85], s[72:73], v[108:109] op_sel:[1,1,0] op_sel_hi:[1,0,1] neg_lo:[0,1,0]
	v_pk_add_f32 v[108:109], v[94:95], v[98:99]
	v_pk_add_f32 v[94:95], v[94:95], v[98:99] neg_lo:[0,1] neg_hi:[0,1]
	v_pk_add_f32 v[98:99], v[96:97], v[100:101]
	v_pk_add_f32 v[96:97], v[96:97], v[100:101] neg_lo:[0,1] neg_hi:[0,1]
	v_pk_add_f32 v[100:101], v[108:109], v[98:99]
	v_pk_add_f32 v[98:99], v[108:109], v[98:99] neg_lo:[0,1] neg_hi:[0,1]
	v_pk_add_f32 v[108:109], v[94:95], v[96:97] op_sel:[0,1] op_sel_hi:[1,0] neg_lo:[0,1]
	v_pk_add_f32 v[94:95], v[94:95], v[96:97] op_sel:[0,1] op_sel_hi:[1,0] neg_hi:[0,1]
	v_pk_add_f32 v[96:97], v[102:103], v[104:105]
	v_pk_add_f32 v[102:103], v[102:103], v[104:105] neg_lo:[0,1] neg_hi:[0,1]
	v_pk_add_f32 v[104:105], v[92:93], v[106:107]
	v_pk_add_f32 v[92:93], v[92:93], v[106:107] neg_lo:[0,1] neg_hi:[0,1]
	v_pk_add_f32 v[106:107], v[96:97], v[104:105]
	v_pk_add_f32 v[96:97], v[96:97], v[104:105] neg_lo:[0,1] neg_hi:[0,1]
	v_pk_add_f32 v[104:105], v[102:103], v[92:93] op_sel:[0,1] op_sel_hi:[1,0] neg_lo:[0,1]
	v_pk_add_f32 v[92:93], v[102:103], v[92:93] op_sel:[0,1] op_sel_hi:[1,0] neg_hi:[0,1]
	v_pk_add_f32 v[102:103], v[86:87], v[88:89]
	v_pk_add_f32 v[86:87], v[86:87], v[88:89] neg_lo:[0,1] neg_hi:[0,1]
	v_pk_add_f32 v[88:89], v[78:79], v[90:91]
	v_pk_add_f32 v[78:79], v[78:79], v[90:91] neg_lo:[0,1] neg_hi:[0,1]
	v_pk_add_f32 v[90:91], v[102:103], v[88:89]
	v_pk_add_f32 v[88:89], v[102:103], v[88:89] neg_lo:[0,1] neg_hi:[0,1]
	v_pk_add_f32 v[102:103], v[86:87], v[78:79] op_sel:[0,1] op_sel_hi:[1,0] neg_lo:[0,1]
	v_pk_add_f32 v[78:79], v[86:87], v[78:79] op_sel:[0,1] op_sel_hi:[1,0] neg_hi:[0,1]
	v_pk_add_f32 v[86:87], v[76:77], v[82:83]
	v_pk_add_f32 v[76:77], v[76:77], v[82:83] neg_lo:[0,1] neg_hi:[0,1]
	v_pk_add_f32 v[82:83], v[80:81], v[84:85]
	v_pk_add_f32 v[80:81], v[80:81], v[84:85] neg_lo:[0,1] neg_hi:[0,1]
	v_pk_add_f32 v[84:85], v[86:87], v[82:83]
	v_pk_add_f32 v[82:83], v[86:87], v[82:83] neg_lo:[0,1] neg_hi:[0,1]
	v_pk_add_f32 v[86:87], v[76:77], v[80:81] op_sel:[0,1] op_sel_hi:[1,0] neg_lo:[0,1]
	v_pk_add_f32 v[76:77], v[76:77], v[80:81] op_sel:[0,1] op_sel_hi:[1,0] neg_hi:[0,1]
	ds_write2_b64 v146, v[100:101], v[106:107] offset1:17
	ds_write2_b64 v146, v[90:91], v[84:85] offset0:34 offset1:51
	ds_write2_b64 v146, v[108:109], v[104:105] offset0:68 offset1:85
	ds_write2_b64 v146, v[102:103], v[86:87] offset0:102 offset1:119
	ds_write2_b64 v146, v[98:99], v[96:97] offset0:136 offset1:153
	ds_write2_b64 v146, v[88:89], v[82:83] offset0:170 offset1:187
	ds_write2_b64 v146, v[94:95], v[92:93] offset0:204 offset1:221
	ds_write2_b64 v146, v[78:79], v[76:77] offset0:238 offset1:255
	v_mov_b32_e32 v77, v39
	v_mov_b32_e32 v76, v38
	s_waitcnt lgkmcnt(0)
	s_barrier
	ds_read_b64 v[78:79], v144 offset:2176
	ds_read_b64 v[80:81], v144 offset:4352
	ds_read_b64 v[82:83], v144 offset:6528
	ds_read_b64 v[84:85], v144
	s_waitcnt lgkmcnt(3)
	v_pk_mul_f32 v[86:87], v[78:79], v[76:77] op_sel:[0,0] op_sel_hi:[0,1] neg_hi:[0,1]
	v_pk_fma_f32 v[78:79], v[78:79], v[76:77], v[86:87] op_sel:[1,1,0] op_sel_hi:[1,0,1]
	v_pk_mul_f32 v[86:87], v[76:77], v[76:77] op_sel:[0,0] op_sel_hi:[0,1]
	ds_read_b64 v[90:91], v144 offset:8704
	v_pk_fma_f32 v[86:87], v[76:77], v[76:77], v[86:87] op_sel:[1,1,0] op_sel_hi:[1,0,1] neg_lo:[0,1,0]
	s_waitcnt lgkmcnt(3)
	v_pk_mul_f32 v[88:89], v[80:81], v[86:87] op_sel:[0,0] op_sel_hi:[0,1] neg_hi:[0,1]
	v_pk_fma_f32 v[80:81], v[80:81], v[86:87], v[88:89] op_sel:[1,1,0] op_sel_hi:[1,0,1]
	v_pk_mul_f32 v[88:89], v[86:87], v[76:77] op_sel:[0,0] op_sel_hi:[0,1]
	v_pk_fma_f32 v[86:87], v[86:87], v[76:77], v[88:89] op_sel:[1,1,0] op_sel_hi:[1,0,1] neg_lo:[0,1,0]
	s_waitcnt lgkmcnt(2)
	v_pk_mul_f32 v[88:89], v[82:83], v[86:87] op_sel:[0,0] op_sel_hi:[0,1] neg_hi:[0,1]
	v_pk_fma_f32 v[82:83], v[82:83], v[86:87], v[88:89] op_sel:[1,1,0] op_sel_hi:[1,0,1]
	v_pk_mul_f32 v[88:89], v[86:87], v[76:77] op_sel:[0,0] op_sel_hi:[0,1]
	v_pk_fma_f32 v[86:87], v[86:87], v[76:77], v[88:89] op_sel:[1,1,0] op_sel_hi:[1,0,1] neg_lo:[0,1,0]
	ds_read_b64 v[88:89], v144 offset:10880
	ds_read_b64 v[92:93], v144 offset:13056
	ds_read_b64 v[94:95], v144 offset:15232
	s_waitcnt lgkmcnt(3)
	v_pk_mul_f32 v[96:97], v[90:91], v[86:87] op_sel:[0,0] op_sel_hi:[0,1] neg_hi:[0,1]
	ds_read_b64 v[98:99], v144 offset:17408
	v_pk_fma_f32 v[90:91], v[90:91], v[86:87], v[96:97] op_sel:[1,1,0] op_sel_hi:[1,0,1]
	v_pk_mul_f32 v[96:97], v[86:87], v[76:77] op_sel:[0,0] op_sel_hi:[0,1]
	v_pk_fma_f32 v[86:87], v[86:87], v[76:77], v[96:97] op_sel:[1,1,0] op_sel_hi:[1,0,1] neg_lo:[0,1,0]
	s_waitcnt lgkmcnt(3)
	v_pk_mul_f32 v[96:97], v[88:89], v[86:87] op_sel:[0,0] op_sel_hi:[0,1] neg_hi:[0,1]
	v_pk_fma_f32 v[88:89], v[88:89], v[86:87], v[96:97] op_sel:[1,1,0] op_sel_hi:[1,0,1]
	v_pk_mul_f32 v[96:97], v[86:87], v[76:77] op_sel:[0,0] op_sel_hi:[0,1]
	v_pk_fma_f32 v[86:87], v[86:87], v[76:77], v[96:97] op_sel:[1,1,0] op_sel_hi:[1,0,1] neg_lo:[0,1,0]
	s_waitcnt lgkmcnt(2)
	v_pk_mul_f32 v[96:97], v[92:93], v[86:87] op_sel:[0,0] op_sel_hi:[0,1] neg_hi:[0,1]
	v_pk_fma_f32 v[92:93], v[92:93], v[86:87], v[96:97] op_sel:[1,1,0] op_sel_hi:[1,0,1]
	v_pk_mul_f32 v[96:97], v[86:87], v[76:77] op_sel:[0,0] op_sel_hi:[0,1]
	v_pk_fma_f32 v[86:87], v[86:87], v[76:77], v[96:97] op_sel:[1,1,0] op_sel_hi:[1,0,1] neg_lo:[0,1,0]
	s_waitcnt lgkmcnt(1)
	v_pk_mul_f32 v[96:97], v[94:95], v[86:87] op_sel:[0,0] op_sel_hi:[0,1] neg_hi:[0,1]
	v_pk_fma_f32 v[94:95], v[94:95], v[86:87], v[96:97] op_sel:[1,1,0] op_sel_hi:[1,0,1]
	v_pk_mul_f32 v[96:97], v[86:87], v[76:77] op_sel:[0,0] op_sel_hi:[0,1]
	v_pk_fma_f32 v[86:87], v[86:87], v[76:77], v[96:97] op_sel:[1,1,0] op_sel_hi:[1,0,1] neg_lo:[0,1,0]
	ds_read_b64 v[96:97], v144 offset:19584
	ds_read_b64 v[100:101], v144 offset:21760
	ds_read_b64 v[102:103], v144 offset:23936
	s_waitcnt lgkmcnt(3)
	v_pk_mul_f32 v[104:105], v[98:99], v[86:87] op_sel:[0,0] op_sel_hi:[0,1] neg_hi:[0,1]
	ds_read_b64 v[106:107], v144 offset:26112
	v_pk_fma_f32 v[98:99], v[98:99], v[86:87], v[104:105] op_sel:[1,1,0] op_sel_hi:[1,0,1]
	v_pk_mul_f32 v[104:105], v[86:87], v[76:77] op_sel:[0,0] op_sel_hi:[0,1]
	v_pk_fma_f32 v[86:87], v[86:87], v[76:77], v[104:105] op_sel:[1,1,0] op_sel_hi:[1,0,1] neg_lo:[0,1,0]
	s_waitcnt lgkmcnt(3)
	v_pk_mul_f32 v[104:105], v[96:97], v[86:87] op_sel:[0,0] op_sel_hi:[0,1] neg_hi:[0,1]
	v_pk_fma_f32 v[96:97], v[96:97], v[86:87], v[104:105] op_sel:[1,1,0] op_sel_hi:[1,0,1]
	v_pk_mul_f32 v[104:105], v[86:87], v[76:77] op_sel:[0,0] op_sel_hi:[0,1]
	v_pk_fma_f32 v[86:87], v[86:87], v[76:77], v[104:105] op_sel:[1,1,0] op_sel_hi:[1,0,1] neg_lo:[0,1,0]
	s_waitcnt lgkmcnt(2)
	v_pk_mul_f32 v[104:105], v[100:101], v[86:87] op_sel:[0,0] op_sel_hi:[0,1] neg_hi:[0,1]
	v_pk_fma_f32 v[100:101], v[100:101], v[86:87], v[104:105] op_sel:[1,1,0] op_sel_hi:[1,0,1]
	v_pk_mul_f32 v[104:105], v[86:87], v[76:77] op_sel:[0,0] op_sel_hi:[0,1]
	v_pk_fma_f32 v[86:87], v[86:87], v[76:77], v[104:105] op_sel:[1,1,0] op_sel_hi:[1,0,1] neg_lo:[0,1,0]
	s_waitcnt lgkmcnt(1)
	v_pk_mul_f32 v[104:105], v[102:103], v[86:87] op_sel:[0,0] op_sel_hi:[0,1] neg_hi:[0,1]
	v_pk_fma_f32 v[102:103], v[102:103], v[86:87], v[104:105] op_sel:[1,1,0] op_sel_hi:[1,0,1]
	v_pk_mul_f32 v[104:105], v[86:87], v[76:77] op_sel:[0,0] op_sel_hi:[0,1]
	v_pk_fma_f32 v[86:87], v[86:87], v[76:77], v[104:105] op_sel:[1,1,0] op_sel_hi:[1,0,1] neg_lo:[0,1,0]
	ds_read_b64 v[104:105], v144 offset:28288
	ds_read_b64 v[108:109], v144 offset:30464
	ds_read_b64 v[110:111], v144 offset:32640
	s_waitcnt lgkmcnt(3)
	v_pk_mul_f32 v[112:113], v[106:107], v[86:87] op_sel:[0,0] op_sel_hi:[0,1] neg_hi:[0,1]
	v_pk_fma_f32 v[106:107], v[106:107], v[86:87], v[112:113] op_sel:[1,1,0] op_sel_hi:[1,0,1]
	v_pk_mul_f32 v[112:113], v[86:87], v[76:77] op_sel:[0,0] op_sel_hi:[0,1]
	v_pk_fma_f32 v[86:87], v[86:87], v[76:77], v[112:113] op_sel:[1,1,0] op_sel_hi:[1,0,1] neg_lo:[0,1,0]
	s_waitcnt lgkmcnt(2)
	v_pk_mul_f32 v[112:113], v[104:105], v[86:87] op_sel:[0,0] op_sel_hi:[0,1] neg_hi:[0,1]
	v_pk_fma_f32 v[104:105], v[104:105], v[86:87], v[112:113] op_sel:[1,1,0] op_sel_hi:[1,0,1]
	v_pk_mul_f32 v[112:113], v[86:87], v[76:77] op_sel:[0,0] op_sel_hi:[0,1]
	v_pk_fma_f32 v[86:87], v[86:87], v[76:77], v[112:113] op_sel:[1,1,0] op_sel_hi:[1,0,1] neg_lo:[0,1,0]
	s_waitcnt lgkmcnt(1)
	v_pk_mul_f32 v[112:113], v[108:109], v[86:87] op_sel:[0,0] op_sel_hi:[0,1] neg_hi:[0,1]
	v_pk_fma_f32 v[108:109], v[108:109], v[86:87], v[112:113] op_sel:[1,1,0] op_sel_hi:[1,0,1]
	v_pk_mul_f32 v[112:113], v[86:87], v[76:77] op_sel:[0,0] op_sel_hi:[0,1]
	v_pk_fma_f32 v[76:77], v[86:87], v[76:77], v[112:113] op_sel:[1,1,0] op_sel_hi:[1,0,1] neg_lo:[0,1,0]
	s_waitcnt lgkmcnt(0)
	v_pk_mul_f32 v[86:87], v[110:111], v[76:77] op_sel:[0,0] op_sel_hi:[0,1] neg_hi:[0,1]
	v_pk_fma_f32 v[76:77], v[110:111], v[76:77], v[86:87] op_sel:[1,1,0] op_sel_hi:[1,0,1]
	v_pk_add_f32 v[86:87], v[84:85], v[98:99]
	v_pk_add_f32 v[84:85], v[84:85], v[98:99] neg_lo:[0,1] neg_hi:[0,1]
	v_pk_add_f32 v[98:99], v[90:91], v[106:107]
	v_pk_add_f32 v[90:91], v[90:91], v[106:107] neg_lo:[0,1] neg_hi:[0,1]
	v_pk_add_f32 v[106:107], v[86:87], v[98:99]
	v_pk_add_f32 v[98:99], v[86:87], v[98:99] neg_lo:[0,1] neg_hi:[0,1]
	v_pk_add_f32 v[86:87], v[84:85], v[90:91] op_sel:[0,1] op_sel_hi:[1,0] neg_lo:[0,1]
	v_pk_add_f32 v[110:111], v[84:85], v[90:91] op_sel:[0,1] op_sel_hi:[1,0] neg_hi:[0,1]
	v_pk_add_f32 v[84:85], v[78:79], v[96:97]
	v_pk_add_f32 v[78:79], v[78:79], v[96:97] neg_lo:[0,1] neg_hi:[0,1]
	v_pk_add_f32 v[90:91], v[88:89], v[104:105]
	v_pk_add_f32 v[88:89], v[88:89], v[104:105] neg_lo:[0,1] neg_hi:[0,1]
	v_pk_add_f32 v[96:97], v[84:85], v[90:91]
	v_pk_add_f32 v[84:85], v[84:85], v[90:91] neg_lo:[0,1] neg_hi:[0,1]
	v_pk_add_f32 v[90:91], v[78:79], v[88:89] op_sel:[0,1] op_sel_hi:[1,0] neg_lo:[0,1]
	v_pk_add_f32 v[78:79], v[78:79], v[88:89] op_sel:[0,1] op_sel_hi:[1,0] neg_hi:[0,1]
	v_pk_add_f32 v[88:89], v[80:81], v[100:101]
	v_pk_add_f32 v[80:81], v[80:81], v[100:101] neg_lo:[0,1] neg_hi:[0,1]
	v_pk_add_f32 v[100:101], v[92:93], v[108:109]
	v_pk_add_f32 v[92:93], v[92:93], v[108:109] neg_lo:[0,1] neg_hi:[0,1]
	v_pk_add_f32 v[104:105], v[88:89], v[100:101]
	v_pk_add_f32 v[88:89], v[88:89], v[100:101] neg_lo:[0,1] neg_hi:[0,1]
	v_pk_add_f32 v[100:101], v[80:81], v[92:93] op_sel:[0,1] op_sel_hi:[1,0] neg_lo:[0,1]
	v_pk_add_f32 v[80:81], v[80:81], v[92:93] op_sel:[0,1] op_sel_hi:[1,0] neg_hi:[0,1]
	v_pk_add_f32 v[92:93], v[82:83], v[102:103]
	v_pk_add_f32 v[82:83], v[82:83], v[102:103] neg_lo:[0,1] neg_hi:[0,1]
	v_pk_add_f32 v[102:103], v[94:95], v[76:77]
	v_pk_add_f32 v[76:77], v[94:95], v[76:77] neg_lo:[0,1] neg_hi:[0,1]
	v_pk_add_f32 v[94:95], v[92:93], v[102:103]
	v_pk_add_f32 v[92:93], v[92:93], v[102:103] neg_lo:[0,1] neg_hi:[0,1]
	v_pk_add_f32 v[102:103], v[82:83], v[76:77] op_sel:[0,1] op_sel_hi:[1,0] neg_lo:[0,1]
	v_pk_add_f32 v[76:77], v[82:83], v[76:77] op_sel:[0,1] op_sel_hi:[1,0] neg_hi:[0,1]
	v_pk_mul_f32 v[82:83], v[90:91], s[62:63] op_sel:[0,0] op_sel_hi:[0,1]
	v_pk_fma_f32 v[32:33], v[90:91], s[62:63], v[82:83] op_sel:[1,1,0] op_sel_hi:[1,0,1] neg_lo:[0,1,0]
	v_pk_mul_f32 v[82:83], v[100:101], s[64:65] op_sel:[0,0] op_sel_hi:[0,1]
	v_pk_mul_f32 v[90:91], v[102:103], s[66:67] op_sel:[0,0] op_sel_hi:[0,1]
	v_pk_fma_f32 v[82:83], v[100:101], s[64:65], v[82:83] op_sel:[1,1,0] op_sel_hi:[1,0,1] neg_lo:[0,1,0]
	v_pk_mul_f32 v[100:101], v[84:85], s[64:65] op_sel:[0,0] op_sel_hi:[0,1]
	v_pk_fma_f32 v[90:91], v[102:103], s[66:67], v[90:91] op_sel:[1,1,0] op_sel_hi:[1,0,1] neg_lo:[0,1,0]
	v_pk_fma_f32 v[108:109], v[84:85], s[64:65], v[100:101] op_sel:[1,1,0] op_sel_hi:[1,0,1] neg_lo:[0,1,0]
	v_pk_mul_f32 v[28:29], v[88:89], s[68:69] op_sel:[0,0] op_sel_hi:[0,1]
	v_pk_add_f32 v[84:85], v[32:33], v[90:91]
	v_pk_fma_f32 v[72:73], v[88:89], s[68:69], v[28:29] op_sel:[1,1,0] op_sel_hi:[1,0,1] neg_lo:[0,1,0]
	v_pk_mul_f32 v[28:29], v[92:93], s[70:71] op_sel:[0,0] op_sel_hi:[0,1]
	v_pk_fma_f32 v[88:89], v[92:93], s[70:71], v[28:29] op_sel:[1,1,0] op_sel_hi:[1,0,1] neg_lo:[0,1,0]
	v_pk_mul_f32 v[28:29], v[78:79], s[66:67] op_sel:[0,0] op_sel_hi:[0,1]
	v_pk_fma_f32 v[112:113], v[78:79], s[66:67], v[28:29] op_sel:[1,1,0] op_sel_hi:[1,0,1] neg_lo:[0,1,0]
	v_pk_mul_f32 v[26:27], v[80:81], s[70:71] op_sel:[0,0] op_sel_hi:[0,1]
	v_pk_add_f32 v[28:29], v[96:97], v[94:95] neg_lo:[0,1] neg_hi:[0,1]
	v_pk_fma_f32 v[114:115], v[80:81], s[70:71], v[26:27] op_sel:[1,1,0] op_sel_hi:[1,0,1] neg_lo:[0,1,0]
	v_pk_mul_f32 v[26:27], v[76:77], s[72:73] op_sel:[0,0] op_sel_hi:[0,1]
	v_pk_add_f32 v[30:31], v[32:33], v[90:91] neg_lo:[0,1] neg_hi:[0,1]
	v_pk_fma_f32 v[116:117], v[76:77], s[72:73], v[26:27] op_sel:[1,1,0] op_sel_hi:[1,0,1] neg_lo:[0,1,0]
	v_pk_add_f32 v[26:27], v[106:107], v[104:105] neg_lo:[0,1] neg_hi:[0,1]
	v_pk_add_f32 v[80:81], v[86:87], v[82:83]
	v_pk_add_f32 v[76:77], v[26:27], v[28:29] op_sel:[0,1] op_sel_hi:[1,0] neg_lo:[0,1]
	v_pk_add_f32 v[26:27], v[26:27], v[28:29] op_sel:[0,1] op_sel_hi:[1,0] neg_hi:[0,1]
	v_pk_add_f32 v[28:29], v[86:87], v[82:83] neg_lo:[0,1] neg_hi:[0,1]
	v_pk_add_f32 v[32:33], v[108:109], v[88:89] neg_lo:[0,1] neg_hi:[0,1]
	v_pk_add_f32 v[82:83], v[28:29], v[30:31] op_sel:[0,1] op_sel_hi:[1,0] neg_lo:[0,1]
	v_pk_add_f32 v[28:29], v[28:29], v[30:31] op_sel:[0,1] op_sel_hi:[1,0] neg_hi:[0,1]
	v_pk_add_f32 v[30:31], v[98:99], v[72:73] neg_lo:[0,1] neg_hi:[0,1]
	v_pk_add_f32 v[74:75], v[106:107], v[104:105]
	v_pk_add_f32 v[78:79], v[96:97], v[94:95]
	v_pk_add_f32 v[86:87], v[98:99], v[72:73]
	v_pk_add_f32 v[90:91], v[108:109], v[88:89]
	v_pk_add_f32 v[88:89], v[30:31], v[32:33] op_sel:[0,1] op_sel_hi:[1,0] neg_lo:[0,1]
	v_pk_add_f32 v[30:31], v[30:31], v[32:33] op_sel:[0,1] op_sel_hi:[1,0] neg_hi:[0,1]
	v_pk_add_f32 v[92:93], v[110:111], v[114:115]
	v_pk_add_f32 v[32:33], v[110:111], v[114:115] neg_lo:[0,1] neg_hi:[0,1]
	v_pk_add_f32 v[96:97], v[112:113], v[116:117]
	v_pk_add_f32 v[72:73], v[112:113], v[116:117] neg_lo:[0,1] neg_hi:[0,1]
	v_pk_add_f32 v[100:101], v[74:75], v[78:79]
	v_pk_add_f32 v[102:103], v[80:81], v[84:85]
	v_pk_add_f32 v[104:105], v[86:87], v[90:91]
	v_pk_add_f32 v[98:99], v[92:93], v[96:97]
	v_pk_add_f32 v[94:95], v[32:33], v[72:73] op_sel:[0,1] op_sel_hi:[1,0] neg_lo:[0,1]
	v_pk_add_f32 v[32:33], v[32:33], v[72:73] op_sel:[0,1] op_sel_hi:[1,0] neg_hi:[0,1]
	v_mov_b32_e32 v72, v36
	v_mov_b32_e32 v73, v37
	s_and_saveexec_b64 s[0:1], s[4:5]
	s_xor_b64 s[0:1], exec, s[0:1]
	s_cbranch_execz .LBB0_1333
	v_mov_b64_e32 v[106:107], s[16:17]
	v_pk_mul_f32 v[108:109], v[72:73], v[106:107] op_sel:[0,0] op_sel_hi:[0,1]
	v_pk_fma_f32 v[106:107], v[72:73], v[106:107], v[108:109] op_sel:[1,1,0] op_sel_hi:[1,0,1] neg_lo:[0,1,0]
	v_pk_mul_f32 v[108:109], v[100:101], v[106:107] op_sel:[0,0] op_sel_hi:[0,1] neg_hi:[0,1]
	v_pk_fma_f32 v[100:101], v[100:101], v[106:107], v[108:109] op_sel:[1,1,0] op_sel_hi:[1,0,1]
	v_pk_mul_f32 v[108:109], v[72:73], s[18:19] op_sel:[0,0] op_sel_hi:[0,1]
	v_pk_fma_f32 v[106:107], v[72:73], s[18:19], v[108:109] op_sel:[1,1,0] op_sel_hi:[1,0,1] neg_lo:[0,1,0]
	v_pk_mul_f32 v[108:109], v[102:103], v[106:107] op_sel:[0,0] op_sel_hi:[0,1] neg_hi:[0,1]
	v_pk_fma_f32 v[102:103], v[102:103], v[106:107], v[108:109] op_sel:[1,1,0] op_sel_hi:[1,0,1]
	v_pk_mul_f32 v[108:109], v[72:73], s[20:21] op_sel:[0,0] op_sel_hi:[0,1]
	v_pk_fma_f32 v[106:107], v[72:73], s[20:21], v[108:109] op_sel:[1,1,0] op_sel_hi:[1,0,1] neg_lo:[0,1,0]
	v_pk_mul_f32 v[108:109], v[104:105], v[106:107] op_sel:[0,0] op_sel_hi:[0,1] neg_hi:[0,1]
	v_pk_fma_f32 v[104:105], v[104:105], v[106:107], v[108:109] op_sel:[1,1,0] op_sel_hi:[1,0,1]
	v_pk_mul_f32 v[108:109], v[72:73], s[22:23] op_sel:[0,0] op_sel_hi:[0,1]
	v_pk_fma_f32 v[106:107], v[72:73], s[22:23], v[108:109] op_sel:[1,1,0] op_sel_hi:[1,0,1] neg_lo:[0,1,0]
	v_pk_mul_f32 v[108:109], v[98:99], v[106:107] op_sel:[0,0] op_sel_hi:[0,1] neg_hi:[0,1]
	v_pk_fma_f32 v[98:99], v[98:99], v[106:107], v[108:109] op_sel:[1,1,0] op_sel_hi:[1,0,1]
	ds_write_b64 v144, v[100:101]
	ds_write_b64 v144, v[102:103] offset:2176
	ds_write_b64 v144, v[104:105] offset:4352
	ds_write_b64 v144, v[98:99] offset:6528
	v_mov_b64_e32 v[98:99], s[50:51]
	v_pk_mul_f32 v[100:101], v[72:73], v[98:99] op_sel:[0,0] op_sel_hi:[0,1]
	s_nop 0
	v_pk_fma_f32 v[98:99], v[72:73], v[98:99], v[100:101] op_sel:[1,1,0] op_sel_hi:[1,0,1] neg_lo:[0,1,0]
	v_pk_mul_f32 v[100:101], v[76:77], v[98:99] op_sel:[0,0] op_sel_hi:[0,1] neg_hi:[0,1]
	v_pk_fma_f32 v[76:77], v[76:77], v[98:99], v[100:101] op_sel:[1,1,0] op_sel_hi:[1,0,1]
	v_pk_mul_f32 v[100:101], v[72:73], s[52:53] op_sel:[0,0] op_sel_hi:[0,1]
	v_pk_fma_f32 v[98:99], v[72:73], s[52:53], v[100:101] op_sel:[1,1,0] op_sel_hi:[1,0,1] neg_lo:[0,1,0]
	v_pk_mul_f32 v[100:101], v[82:83], v[98:99] op_sel:[0,0] op_sel_hi:[0,1] neg_hi:[0,1]
	v_pk_fma_f32 v[82:83], v[82:83], v[98:99], v[100:101] op_sel:[1,1,0] op_sel_hi:[1,0,1]
	v_pk_mul_f32 v[100:101], v[72:73], s[54:55] op_sel:[0,0] op_sel_hi:[0,1]
	v_pk_fma_f32 v[98:99], v[72:73], s[54:55], v[100:101] op_sel:[1,1,0] op_sel_hi:[1,0,1] neg_lo:[0,1,0]
	v_pk_mul_f32 v[100:101], v[88:89], v[98:99] op_sel:[0,0] op_sel_hi:[0,1] neg_hi:[0,1]
	v_pk_fma_f32 v[88:89], v[88:89], v[98:99], v[100:101] op_sel:[1,1,0] op_sel_hi:[1,0,1]
	v_pk_mul_f32 v[100:101], v[72:73], s[56:57] op_sel:[0,0] op_sel_hi:[0,1]
	v_pk_fma_f32 v[98:99], v[72:73], s[56:57], v[100:101] op_sel:[1,1,0] op_sel_hi:[1,0,1] neg_lo:[0,1,0]
	v_pk_mul_f32 v[100:101], v[94:95], v[98:99] op_sel:[0,0] op_sel_hi:[0,1] neg_hi:[0,1]
	s_nop 0
	v_pk_fma_f32 v[94:95], v[94:95], v[98:99], v[100:101] op_sel:[1,1,0] op_sel_hi:[1,0,1]

.LBB0_1335:
	s_or_b64 exec, exec, s[0:1]
	v_pk_add_f32 v[98:99], v[74:75], v[78:79] neg_lo:[0,1] neg_hi:[0,1]
	v_pk_add_f32 v[80:81], v[80:81], v[84:85] neg_lo:[0,1] neg_hi:[0,1]
	v_pk_add_f32 v[78:79], v[86:87], v[90:91] neg_lo:[0,1] neg_hi:[0,1]
	v_pk_add_f32 v[74:75], v[92:93], v[96:97] neg_lo:[0,1] neg_hi:[0,1]
	ds_write_b64 v144, v[76:77] offset:8704
	ds_write_b64 v144, v[82:83] offset:10880
	ds_write_b64 v144, v[88:89] offset:13056
	ds_write_b64 v144, v[94:95] offset:15232
	s_and_saveexec_b64 s[0:1], s[4:5]
	s_xor_b64 s[0:1], exec, s[0:1]
	s_cbranch_execz .LBB0_1337
	v_mov_b64_e32 v[76:77], s[14:15]
	v_pk_mul_f32 v[82:83], v[72:73], v[76:77] op_sel:[0,0] op_sel_hi:[0,1]
	s_mov_b32 s6, s19
	v_pk_fma_f32 v[76:77], v[72:73], v[76:77], v[82:83] op_sel:[1,1,0] op_sel_hi:[1,0,1] neg_lo:[0,1,0]
	s_mov_b32 s7, s57
	v_pk_mul_f32 v[82:83], v[98:99], v[76:77] op_sel:[0,0] op_sel_hi:[0,1] neg_hi:[0,1]
	v_pk_fma_f32 v[76:77], v[98:99], v[76:77], v[82:83] op_sel:[1,1,0] op_sel_hi:[1,0,1]
	v_mov_b64_e32 v[82:83], s[6:7]
	v_pk_mul_f32 v[84:85], v[72:73], v[82:83] op_sel:[0,0] op_sel_hi:[0,1]
	s_mov_b32 s6, s21
	v_pk_fma_f32 v[82:83], v[72:73], v[82:83], v[84:85] op_sel:[1,1,0] op_sel_hi:[1,0,1] neg_lo:[0,1,0]
	s_mov_b32 s7, s55
	v_pk_mul_f32 v[84:85], v[80:81], v[82:83] op_sel:[0,0] op_sel_hi:[0,1] neg_hi:[0,1]
	s_nop 0
	v_pk_fma_f32 v[80:81], v[80:81], v[82:83], v[84:85] op_sel:[1,1,0] op_sel_hi:[1,0,1]
	v_mov_b64_e32 v[82:83], s[6:7]
	v_pk_mul_f32 v[84:85], v[72:73], v[82:83] op_sel:[0,0] op_sel_hi:[0,1]
	s_mov_b32 s6, s23
	v_pk_fma_f32 v[82:83], v[72:73], v[82:83], v[84:85] op_sel:[1,1,0] op_sel_hi:[1,0,1] neg_lo:[0,1,0]
	s_mov_b32 s7, s53
	v_pk_mul_f32 v[84:85], v[78:79], v[82:83] op_sel:[0,0] op_sel_hi:[0,1] neg_hi:[0,1]
	v_pk_fma_f32 v[78:79], v[78:79], v[82:83], v[84:85] op_sel:[1,1,0] op_sel_hi:[1,0,1]
	v_mov_b64_e32 v[82:83], s[6:7]
	v_pk_mul_f32 v[84:85], v[72:73], v[82:83] op_sel:[0,0] op_sel_hi:[0,1]
	s_mov_b32 s6, s53
	v_pk_fma_f32 v[82:83], v[72:73], v[82:83], v[84:85] op_sel:[1,1,0] op_sel_hi:[1,0,1] neg_lo:[0,1,0]
	s_mov_b32 s7, s23
	v_pk_mul_f32 v[84:85], v[74:75], v[82:83] op_sel:[0,0] op_sel_hi:[0,1] neg_hi:[0,1]
	v_pk_fma_f32 v[74:75], v[74:75], v[82:83], v[84:85] op_sel:[1,1,0] op_sel_hi:[1,0,1]
	ds_write_b64 v144, v[76:77] offset:17408
	ds_write_b64 v144, v[80:81] offset:19584
	ds_write_b64 v144, v[78:79] offset:21760
	ds_write_b64 v144, v[74:75] offset:23936
	v_mov_b64_e32 v[74:75], s[58:59]
	v_pk_mul_f32 v[76:77], v[72:73], v[74:75] op_sel:[0,0] op_sel_hi:[0,1]
	s_nop 0
	v_pk_fma_f32 v[74:75], v[72:73], v[74:75], v[76:77] op_sel:[1,1,0] op_sel_hi:[1,0,1] neg_lo:[0,1,0]
	v_pk_mul_f32 v[76:77], v[26:27], v[74:75] op_sel:[0,0] op_sel_hi:[0,1] neg_hi:[0,1]
	v_pk_fma_f32 v[26:27], v[26:27], v[74:75], v[76:77] op_sel:[1,1,0] op_sel_hi:[1,0,1]
	v_mov_b64_e32 v[74:75], s[6:7]
	v_pk_mul_f32 v[76:77], v[72:73], v[74:75] op_sel:[0,0] op_sel_hi:[0,1]
	s_mov_b32 s6, s57
	v_pk_fma_f32 v[74:75], v[72:73], v[74:75], v[76:77] op_sel:[1,1,0] op_sel_hi:[1,0,1] neg_lo:[0,1,0]
	s_mov_b32 s7, s19
	v_pk_mul_f32 v[76:77], v[28:29], v[74:75] op_sel:[0,0] op_sel_hi:[0,1] neg_hi:[0,1]
	v_pk_fma_f32 v[28:29], v[28:29], v[74:75], v[76:77] op_sel:[1,1,0] op_sel_hi:[1,0,1]
	v_pk_mul_f32 v[76:77], v[72:73], s[72:73] op_sel:[0,0] op_sel_hi:[0,1]
	v_pk_fma_f32 v[74:75], v[72:73], s[72:73], v[76:77] op_sel:[1,1,0] op_sel_hi:[1,0,1] neg_lo:[0,1,0]
	v_pk_mul_f32 v[76:77], v[30:31], v[74:75] op_sel:[0,0] op_sel_hi:[0,1] neg_hi:[0,1]
	v_pk_fma_f32 v[30:31], v[30:31], v[74:75], v[76:77] op_sel:[1,1,0] op_sel_hi:[1,0,1]
	v_pk_mul_f32 v[76:77], v[72:73], s[6:7] op_sel:[0,0] op_sel_hi:[0,1]
	v_pk_fma_f32 v[72:73], v[72:73], s[6:7], v[76:77] op_sel:[1,1,0] op_sel_hi:[1,0,1] neg_lo:[0,1,0]
	v_pk_mul_f32 v[74:75], v[32:33], v[72:73] op_sel:[0,0] op_sel_hi:[0,1] neg_hi:[0,1]
	s_nop 0
	v_pk_fma_f32 v[32:33], v[32:33], v[72:73], v[74:75] op_sel:[1,1,0] op_sel_hi:[1,0,1]

.LBB0_1407:
	s_or_b64 exec, exec, s[0:1]
	v_pk_add_f32 v[44:45], v[42:43], v[60:61]
	v_pk_add_f32 v[42:43], v[42:43], v[60:61] neg_lo:[0,1] neg_hi:[0,1]
	v_pk_add_f32 v[60:61], v[52:53], v[68:69]
	v_pk_add_f32 v[52:53], v[52:53], v[68:69] neg_lo:[0,1] neg_hi:[0,1]
	v_pk_add_f32 v[68:69], v[44:45], v[60:61]
	v_pk_add_f32 v[60:61], v[44:45], v[60:61] neg_lo:[0,1] neg_hi:[0,1]
	s_waitcnt lgkmcnt(1)
	v_pk_add_f32 v[76:77], v[42:43], v[52:53] op_sel:[0,1] op_sel_hi:[1,0] neg_hi:[0,1]
	s_waitcnt lgkmcnt(0)
	v_pk_add_f32 v[78:79], v[42:43], v[52:53] op_sel:[0,1] op_sel_hi:[1,0] neg_lo:[0,1]
	v_pk_add_f32 v[42:43], v[46:47], v[62:63]
	v_pk_add_f32 v[44:45], v[46:47], v[62:63] neg_lo:[0,1] neg_hi:[0,1]
	v_pk_add_f32 v[46:47], v[54:55], v[70:71]
	v_pk_add_f32 v[52:53], v[54:55], v[70:71] neg_lo:[0,1] neg_hi:[0,1]
	v_pk_add_f32 v[54:55], v[42:43], v[46:47]
	v_pk_add_f32 v[46:47], v[42:43], v[46:47] neg_lo:[0,1] neg_hi:[0,1]
	v_pk_add_f32 v[42:43], v[44:45], v[52:53] op_sel:[0,1] op_sel_hi:[1,0] neg_hi:[0,1]
	v_pk_add_f32 v[52:53], v[44:45], v[52:53] op_sel:[0,1] op_sel_hi:[1,0] neg_lo:[0,1]
	v_pk_add_f32 v[44:45], v[48:49], v[64:65]
	v_pk_add_f32 v[48:49], v[48:49], v[64:65] neg_lo:[0,1] neg_hi:[0,1]
	v_pk_add_f32 v[62:63], v[56:57], v[72:73]
	v_pk_add_f32 v[56:57], v[56:57], v[72:73] neg_lo:[0,1] neg_hi:[0,1]
	v_pk_add_f32 v[64:65], v[44:45], v[62:63]
	v_pk_add_f32 v[62:63], v[44:45], v[62:63] neg_lo:[0,1] neg_hi:[0,1]
	v_pk_add_f32 v[70:71], v[48:49], v[56:57] op_sel:[0,1] op_sel_hi:[1,0] neg_hi:[0,1]
	v_pk_add_f32 v[56:57], v[48:49], v[56:57] op_sel:[0,1] op_sel_hi:[1,0] neg_lo:[0,1]
	v_pk_add_f32 v[44:45], v[50:51], v[66:67]
	v_pk_add_f32 v[48:49], v[50:51], v[66:67] neg_lo:[0,1] neg_hi:[0,1]
	v_pk_add_f32 v[50:51], v[58:59], v[74:75]
	v_pk_add_f32 v[58:59], v[58:59], v[74:75] neg_lo:[0,1] neg_hi:[0,1]
	v_pk_add_f32 v[66:67], v[44:45], v[50:51]
	v_pk_add_f32 v[72:73], v[44:45], v[50:51] neg_lo:[0,1] neg_hi:[0,1]
	v_pk_add_f32 v[50:51], v[48:49], v[58:59] op_sel:[0,1] op_sel_hi:[1,0] neg_hi:[0,1]
	v_pk_add_f32 v[58:59], v[48:49], v[58:59] op_sel:[0,1] op_sel_hi:[1,0] neg_lo:[0,1]
	v_pk_mul_f32 v[44:45], v[42:43], s[20:21] op_sel:[0,0] op_sel_hi:[0,1]
	v_pk_fma_f32 v[74:75], v[42:43], s[20:21], v[44:45] op_sel:[1,1,0] op_sel_hi:[1,0,1] neg_lo:[0,1,0]
	v_mov_b64_e32 v[44:45], s[50:51]
	v_pk_mul_f32 v[42:43], v[70:71], v[44:45] op_sel:[0,0] op_sel_hi:[0,1]
	s_barrier
	v_pk_fma_f32 v[70:71], v[70:71], v[44:45], v[42:43] op_sel:[1,1,0] op_sel_hi:[1,0,1] neg_lo:[0,1,0]
	v_mov_b64_e32 v[42:43], s[54:55]
	v_pk_mul_f32 v[80:81], v[50:51], v[42:43] op_sel:[0,0] op_sel_hi:[0,1]
	v_pk_fma_f32 v[80:81], v[50:51], v[42:43], v[80:81] op_sel:[1,1,0] op_sel_hi:[1,0,1] neg_lo:[0,1,0]
	v_pk_mul_f32 v[50:51], v[46:47], v[44:45] op_sel:[0,0] op_sel_hi:[0,1]
	s_mov_b32 s28, 0
	v_pk_fma_f32 v[82:83], v[46:47], v[44:45], v[50:51] op_sel:[1,1,0] op_sel_hi:[1,0,1] neg_lo:[0,1,0]
	v_pk_mul_f32 v[46:47], v[62:63], s[14:15] op_sel:[0,0] op_sel_hi:[0,1]
	v_mov_b32_e32 v34, v144
	v_pk_fma_f32 v[62:63], v[62:63], s[14:15], v[46:47] op_sel:[1,1,0] op_sel_hi:[1,0,1] neg_lo:[0,1,0]
	v_pk_mul_f32 v[84:85], v[72:73], s[58:59] op_sel:[0,0] op_sel_hi:[0,1]
	v_pk_fma_f32 v[72:73], v[72:73], s[58:59], v[84:85] op_sel:[1,1,0] op_sel_hi:[1,0,1] neg_lo:[0,1,0]
	v_pk_mul_f32 v[84:85], v[52:53], v[42:43] op_sel:[0,0] op_sel_hi:[0,1]
	v_pk_fma_f32 v[84:85], v[52:53], v[42:43], v[84:85] op_sel:[1,1,0] op_sel_hi:[1,0,1] neg_lo:[0,1,0]
	v_pk_mul_f32 v[52:53], v[56:57], s[58:59] op_sel:[0,0] op_sel_hi:[0,1]
	v_pk_fma_f32 v[56:57], v[56:57], s[58:59], v[52:53] op_sel:[1,1,0] op_sel_hi:[1,0,1] neg_lo:[0,1,0]
	v_pk_mul_f32 v[86:87], v[58:59], s[60:61] op_sel:[0,0] op_sel_hi:[0,1]
	v_pk_fma_f32 v[58:59], v[58:59], s[60:61], v[86:87] op_sel:[1,1,0] op_sel_hi:[1,0,1] neg_lo:[0,1,0]
	v_pk_add_f32 v[86:87], v[68:69], v[64:65]
	v_pk_add_f32 v[64:65], v[68:69], v[64:65] neg_lo:[0,1] neg_hi:[0,1]
	v_pk_add_f32 v[68:69], v[54:55], v[66:67]
	v_pk_add_f32 v[54:55], v[54:55], v[66:67] neg_lo:[0,1] neg_hi:[0,1]
	v_pk_add_f32 v[66:67], v[86:87], v[68:69]
	v_pk_add_f32 v[68:69], v[86:87], v[68:69] neg_lo:[0,1] neg_hi:[0,1]
	v_pk_add_f32 v[86:87], v[64:65], v[54:55] op_sel:[0,1] op_sel_hi:[1,0] neg_hi:[0,1]
	v_pk_add_f32 v[54:55], v[64:65], v[54:55] op_sel:[0,1] op_sel_hi:[1,0] neg_lo:[0,1]
	v_pk_add_f32 v[64:65], v[76:77], v[70:71]
	v_pk_add_f32 v[70:71], v[76:77], v[70:71] neg_lo:[0,1] neg_hi:[0,1]
	v_pk_add_f32 v[76:77], v[74:75], v[80:81]
	v_pk_add_f32 v[74:75], v[74:75], v[80:81] neg_lo:[0,1] neg_hi:[0,1]
	v_pk_add_f32 v[80:81], v[64:65], v[76:77]
	v_pk_add_f32 v[64:65], v[64:65], v[76:77] neg_lo:[0,1] neg_hi:[0,1]
	v_pk_add_f32 v[76:77], v[70:71], v[74:75] op_sel:[0,1] op_sel_hi:[1,0] neg_hi:[0,1]
	v_pk_add_f32 v[70:71], v[70:71], v[74:75] op_sel:[0,1] op_sel_hi:[1,0] neg_lo:[0,1]
	v_pk_add_f32 v[74:75], v[60:61], v[62:63]
	v_pk_add_f32 v[60:61], v[60:61], v[62:63] neg_lo:[0,1] neg_hi:[0,1]
	v_pk_add_f32 v[62:63], v[82:83], v[72:73]
	v_pk_add_f32 v[72:73], v[82:83], v[72:73] neg_lo:[0,1] neg_hi:[0,1]
	v_pk_add_f32 v[82:83], v[74:75], v[62:63]
	v_pk_add_f32 v[62:63], v[74:75], v[62:63] neg_lo:[0,1] neg_hi:[0,1]
	v_pk_add_f32 v[74:75], v[60:61], v[72:73] op_sel:[0,1] op_sel_hi:[1,0] neg_hi:[0,1]
	v_pk_add_f32 v[60:61], v[60:61], v[72:73] op_sel:[0,1] op_sel_hi:[1,0] neg_lo:[0,1]
	v_pk_add_f32 v[72:73], v[78:79], v[56:57]
	v_pk_add_f32 v[56:57], v[78:79], v[56:57] neg_lo:[0,1] neg_hi:[0,1]
	v_pk_add_f32 v[78:79], v[84:85], v[58:59]
	v_pk_add_f32 v[58:59], v[84:85], v[58:59] neg_lo:[0,1] neg_hi:[0,1]
	v_pk_add_f32 v[84:85], v[72:73], v[78:79]
	v_pk_add_f32 v[72:73], v[72:73], v[78:79] neg_lo:[0,1] neg_hi:[0,1]
	v_pk_add_f32 v[78:79], v[56:57], v[58:59] op_sel:[0,1] op_sel_hi:[1,0] neg_hi:[0,1]
	v_pk_add_f32 v[56:57], v[56:57], v[58:59] op_sel:[0,1] op_sel_hi:[1,0] neg_lo:[0,1]
	v_mov_b32_e32 v59, v39
	v_mov_b32_e32 v58, v38
	ds_write_b64 v144, v[66:67]
	v_pk_mul_f32 v[66:67], v[80:81], v[58:59] op_sel:[0,0] op_sel_hi:[0,1]
	v_pk_fma_f32 v[66:67], v[80:81], v[58:59], v[66:67] op_sel:[1,1,0] op_sel_hi:[1,0,1] neg_lo:[0,1,0]
	ds_write_b64 v144, v[66:67] offset:2176
	v_pk_mul_f32 v[66:67], v[58:59], v[58:59] op_sel:[0,0] op_sel_hi:[0,1]
	v_pk_fma_f32 v[66:67], v[58:59], v[58:59], v[66:67] op_sel:[1,1,0] op_sel_hi:[1,0,1] neg_lo:[0,1,0]
	v_pk_mul_f32 v[80:81], v[82:83], v[66:67] op_sel:[0,0] op_sel_hi:[0,1]
	v_pk_fma_f32 v[80:81], v[82:83], v[66:67], v[80:81] op_sel:[1,1,0] op_sel_hi:[1,0,1] neg_lo:[0,1,0]
	ds_write_b64 v144, v[80:81] offset:4352
	v_pk_mul_f32 v[80:81], v[66:67], v[58:59] op_sel:[0,0] op_sel_hi:[0,1]
	v_pk_fma_f32 v[66:67], v[66:67], v[58:59], v[80:81] op_sel:[1,1,0] op_sel_hi:[1,0,1] neg_lo:[0,1,0]
	v_pk_mul_f32 v[80:81], v[84:85], v[66:67] op_sel:[0,0] op_sel_hi:[0,1]
	v_pk_fma_f32 v[80:81], v[84:85], v[66:67], v[80:81] op_sel:[1,1,0] op_sel_hi:[1,0,1] neg_lo:[0,1,0]
	ds_write_b64 v144, v[80:81] offset:6528
	v_pk_mul_f32 v[80:81], v[66:67], v[58:59] op_sel:[0,0] op_sel_hi:[0,1]
	v_pk_fma_f32 v[66:67], v[66:67], v[58:59], v[80:81] op_sel:[1,1,0] op_sel_hi:[1,0,1] neg_lo:[0,1,0]
	v_pk_mul_f32 v[80:81], v[86:87], v[66:67] op_sel:[0,0] op_sel_hi:[0,1]
	v_pk_fma_f32 v[80:81], v[86:87], v[66:67], v[80:81] op_sel:[1,1,0] op_sel_hi:[1,0,1] neg_lo:[0,1,0]
	ds_write_b64 v144, v[80:81] offset:8704
	v_pk_mul_f32 v[80:81], v[66:67], v[58:59] op_sel:[0,0] op_sel_hi:[0,1]
	v_pk_fma_f32 v[66:67], v[66:67], v[58:59], v[80:81] op_sel:[1,1,0] op_sel_hi:[1,0,1] neg_lo:[0,1,0]
	v_pk_mul_f32 v[80:81], v[76:77], v[66:67] op_sel:[0,0] op_sel_hi:[0,1]
	v_pk_fma_f32 v[76:77], v[76:77], v[66:67], v[80:81] op_sel:[1,1,0] op_sel_hi:[1,0,1] neg_lo:[0,1,0]
	ds_write_b64 v144, v[76:77] offset:10880
	v_pk_mul_f32 v[76:77], v[66:67], v[58:59] op_sel:[0,0] op_sel_hi:[0,1]
	v_pk_fma_f32 v[66:67], v[66:67], v[58:59], v[76:77] op_sel:[1,1,0] op_sel_hi:[1,0,1] neg_lo:[0,1,0]
	v_pk_mul_f32 v[76:77], v[74:75], v[66:67] op_sel:[0,0] op_sel_hi:[0,1]
	v_pk_fma_f32 v[74:75], v[74:75], v[66:67], v[76:77] op_sel:[1,1,0] op_sel_hi:[1,0,1] neg_lo:[0,1,0]
	ds_write_b64 v144, v[74:75] offset:13056
	v_pk_mul_f32 v[74:75], v[66:67], v[58:59] op_sel:[0,0] op_sel_hi:[0,1]
	v_pk_fma_f32 v[66:67], v[66:67], v[58:59], v[74:75] op_sel:[1,1,0] op_sel_hi:[1,0,1] neg_lo:[0,1,0]
	v_pk_mul_f32 v[74:75], v[78:79], v[66:67] op_sel:[0,0] op_sel_hi:[0,1]
	v_pk_fma_f32 v[74:75], v[78:79], v[66:67], v[74:75] op_sel:[1,1,0] op_sel_hi:[1,0,1] neg_lo:[0,1,0]
	ds_write_b64 v144, v[74:75] offset:15232
	v_pk_mul_f32 v[74:75], v[66:67], v[58:59] op_sel:[0,0] op_sel_hi:[0,1]
	v_pk_fma_f32 v[66:67], v[66:67], v[58:59], v[74:75] op_sel:[1,1,0] op_sel_hi:[1,0,1] neg_lo:[0,1,0]
	v_pk_mul_f32 v[74:75], v[68:69], v[66:67] op_sel:[0,0] op_sel_hi:[0,1]
	v_pk_fma_f32 v[68:69], v[68:69], v[66:67], v[74:75] op_sel:[1,1,0] op_sel_hi:[1,0,1] neg_lo:[0,1,0]
	ds_write_b64 v144, v[68:69] offset:17408
	v_pk_mul_f32 v[68:69], v[66:67], v[58:59] op_sel:[0,0] op_sel_hi:[0,1]
	v_pk_fma_f32 v[66:67], v[66:67], v[58:59], v[68:69] op_sel:[1,1,0] op_sel_hi:[1,0,1] neg_lo:[0,1,0]
	v_pk_mul_f32 v[68:69], v[64:65], v[66:67] op_sel:[0,0] op_sel_hi:[0,1]
	v_pk_fma_f32 v[64:65], v[64:65], v[66:67], v[68:69] op_sel:[1,1,0] op_sel_hi:[1,0,1] neg_lo:[0,1,0]
	ds_write_b64 v144, v[64:65] offset:19584
	v_pk_mul_f32 v[64:65], v[66:67], v[58:59] op_sel:[0,0] op_sel_hi:[0,1]
	v_pk_fma_f32 v[64:65], v[66:67], v[58:59], v[64:65] op_sel:[1,1,0] op_sel_hi:[1,0,1] neg_lo:[0,1,0]
	v_pk_mul_f32 v[66:67], v[62:63], v[64:65] op_sel:[0,0] op_sel_hi:[0,1]
	v_pk_fma_f32 v[62:63], v[62:63], v[64:65], v[66:67] op_sel:[1,1,0] op_sel_hi:[1,0,1] neg_lo:[0,1,0]
	ds_write_b64 v144, v[62:63] offset:21760
	v_pk_mul_f32 v[62:63], v[64:65], v[58:59] op_sel:[0,0] op_sel_hi:[0,1]
	v_pk_fma_f32 v[62:63], v[64:65], v[58:59], v[62:63] op_sel:[1,1,0] op_sel_hi:[1,0,1] neg_lo:[0,1,0]
	v_pk_mul_f32 v[64:65], v[72:73], v[62:63] op_sel:[0,0] op_sel_hi:[0,1]
	v_pk_fma_f32 v[64:65], v[72:73], v[62:63], v[64:65] op_sel:[1,1,0] op_sel_hi:[1,0,1] neg_lo:[0,1,0]
	ds_write_b64 v144, v[64:65] offset:23936
	v_pk_mul_f32 v[64:65], v[62:63], v[58:59] op_sel:[0,0] op_sel_hi:[0,1]
	v_pk_fma_f32 v[62:63], v[62:63], v[58:59], v[64:65] op_sel:[1,1,0] op_sel_hi:[1,0,1] neg_lo:[0,1,0]
	v_pk_mul_f32 v[64:65], v[54:55], v[62:63] op_sel:[0,0] op_sel_hi:[0,1]
	v_pk_fma_f32 v[54:55], v[54:55], v[62:63], v[64:65] op_sel:[1,1,0] op_sel_hi:[1,0,1] neg_lo:[0,1,0]
	ds_write_b64 v144, v[54:55] offset:26112
	v_pk_mul_f32 v[54:55], v[62:63], v[58:59] op_sel:[0,0] op_sel_hi:[0,1]
	v_pk_fma_f32 v[54:55], v[62:63], v[58:59], v[54:55] op_sel:[1,1,0] op_sel_hi:[1,0,1] neg_lo:[0,1,0]
	v_pk_mul_f32 v[62:63], v[70:71], v[54:55] op_sel:[0,0] op_sel_hi:[0,1]
	v_pk_fma_f32 v[62:63], v[70:71], v[54:55], v[62:63] op_sel:[1,1,0] op_sel_hi:[1,0,1] neg_lo:[0,1,0]
	ds_write_b64 v144, v[62:63] offset:28288
	v_pk_mul_f32 v[62:63], v[54:55], v[58:59] op_sel:[0,0] op_sel_hi:[0,1]
	v_pk_fma_f32 v[54:55], v[54:55], v[58:59], v[62:63] op_sel:[1,1,0] op_sel_hi:[1,0,1] neg_lo:[0,1,0]
	v_pk_mul_f32 v[62:63], v[60:61], v[54:55] op_sel:[0,0] op_sel_hi:[0,1]
	v_pk_fma_f32 v[60:61], v[60:61], v[54:55], v[62:63] op_sel:[1,1,0] op_sel_hi:[1,0,1] neg_lo:[0,1,0]
	ds_write_b64 v144, v[60:61] offset:30464
	v_pk_mul_f32 v[60:61], v[54:55], v[58:59] op_sel:[0,0] op_sel_hi:[0,1]
	v_pk_fma_f32 v[54:55], v[54:55], v[58:59], v[60:61] op_sel:[1,1,0] op_sel_hi:[1,0,1] neg_lo:[0,1,0]
	v_pk_mul_f32 v[58:59], v[56:57], v[54:55] op_sel:[0,0] op_sel_hi:[0,1]
	v_pk_fma_f32 v[54:55], v[56:57], v[54:55], v[58:59] op_sel:[1,1,0] op_sel_hi:[1,0,1] neg_lo:[0,1,0]
	ds_write_b64 v144, v[54:55] offset:32640
	s_waitcnt lgkmcnt(0)
	s_barrier
	ds_read2_b64 v[54:57], v146 offset1:17
	ds_read2_b64 v[58:61], v146 offset0:34 offset1:51
	ds_read2_b64 v[62:65], v146 offset0:68 offset1:85
	ds_read2_b64 v[66:69], v146 offset0:136 offset1:153
	ds_read2_b64 v[70:73], v146 offset0:102 offset1:119
	ds_read2_b64 v[74:77], v146 offset0:204 offset1:221
	ds_read2_b64 v[78:81], v146 offset0:170 offset1:187
	ds_read2_b64 v[82:85], v146 offset0:238 offset1:255
	s_waitcnt lgkmcnt(4)
	v_pk_add_f32 v[86:87], v[54:55], v[66:67]
	v_pk_add_f32 v[54:55], v[54:55], v[66:67] neg_lo:[0,1] neg_hi:[0,1]
	s_waitcnt lgkmcnt(2)
	v_pk_add_f32 v[66:67], v[62:63], v[74:75]
	v_pk_add_f32 v[62:63], v[62:63], v[74:75] neg_lo:[0,1] neg_hi:[0,1]
	v_pk_add_f32 v[74:75], v[86:87], v[66:67]
	v_pk_add_f32 v[66:67], v[86:87], v[66:67] neg_lo:[0,1] neg_hi:[0,1]
	v_pk_add_f32 v[86:87], v[54:55], v[62:63] op_sel:[0,1] op_sel_hi:[1,0] neg_hi:[0,1]
	v_pk_add_f32 v[54:55], v[54:55], v[62:63] op_sel:[0,1] op_sel_hi:[1,0] neg_lo:[0,1]
	v_pk_add_f32 v[62:63], v[56:57], v[68:69]
	v_pk_add_f32 v[56:57], v[56:57], v[68:69] neg_lo:[0,1] neg_hi:[0,1]
	v_pk_add_f32 v[68:69], v[64:65], v[76:77]
	v_pk_add_f32 v[64:65], v[64:65], v[76:77] neg_lo:[0,1] neg_hi:[0,1]
	v_pk_add_f32 v[76:77], v[62:63], v[68:69]
	v_pk_add_f32 v[62:63], v[62:63], v[68:69] neg_lo:[0,1] neg_hi:[0,1]
	v_pk_add_f32 v[68:69], v[56:57], v[64:65] op_sel:[0,1] op_sel_hi:[1,0] neg_hi:[0,1]
	v_pk_add_f32 v[56:57], v[56:57], v[64:65] op_sel:[0,1] op_sel_hi:[1,0] neg_lo:[0,1]
	s_waitcnt lgkmcnt(1)
	v_pk_add_f32 v[64:65], v[58:59], v[78:79]
	v_pk_add_f32 v[58:59], v[58:59], v[78:79] neg_lo:[0,1] neg_hi:[0,1]
	s_waitcnt lgkmcnt(0)
	v_pk_add_f32 v[78:79], v[70:71], v[82:83]
	v_pk_add_f32 v[70:71], v[70:71], v[82:83] neg_lo:[0,1] neg_hi:[0,1]
	v_pk_add_f32 v[82:83], v[64:65], v[78:79]
	v_pk_add_f32 v[64:65], v[64:65], v[78:79] neg_lo:[0,1] neg_hi:[0,1]
	v_pk_add_f32 v[78:79], v[58:59], v[70:71] op_sel:[0,1] op_sel_hi:[1,0] neg_hi:[0,1]
	v_pk_add_f32 v[58:59], v[58:59], v[70:71] op_sel:[0,1] op_sel_hi:[1,0] neg_lo:[0,1]
	v_pk_add_f32 v[70:71], v[60:61], v[80:81]
	v_pk_add_f32 v[60:61], v[60:61], v[80:81] neg_lo:[0,1] neg_hi:[0,1]
	v_pk_add_f32 v[80:81], v[72:73], v[84:85]
	v_pk_add_f32 v[72:73], v[72:73], v[84:85] neg_lo:[0,1] neg_hi:[0,1]
	v_pk_add_f32 v[84:85], v[70:71], v[80:81]
	v_pk_add_f32 v[70:71], v[70:71], v[80:81] neg_lo:[0,1] neg_hi:[0,1]
	v_pk_add_f32 v[80:81], v[60:61], v[72:73] op_sel:[0,1] op_sel_hi:[1,0] neg_hi:[0,1]
	v_pk_add_f32 v[60:61], v[60:61], v[72:73] op_sel:[0,1] op_sel_hi:[1,0] neg_lo:[0,1]
	v_pk_mul_f32 v[72:73], v[68:69], s[20:21] op_sel:[0,0] op_sel_hi:[0,1]
	v_pk_fma_f32 v[68:69], v[68:69], s[20:21], v[72:73] op_sel:[1,1,0] op_sel_hi:[1,0,1] neg_lo:[0,1,0]
	v_pk_mul_f32 v[72:73], v[78:79], v[44:45] op_sel:[0,0] op_sel_hi:[0,1]
	v_pk_fma_f32 v[72:73], v[78:79], v[44:45], v[72:73] op_sel:[1,1,0] op_sel_hi:[1,0,1] neg_lo:[0,1,0]
	v_pk_mul_f32 v[78:79], v[80:81], v[42:43] op_sel:[0,0] op_sel_hi:[0,1]
	v_pk_fma_f32 v[78:79], v[80:81], v[42:43], v[78:79] op_sel:[1,1,0] op_sel_hi:[1,0,1] neg_lo:[0,1,0]
	v_pk_mul_f32 v[80:81], v[62:63], v[44:45] op_sel:[0,0] op_sel_hi:[0,1]
	v_pk_fma_f32 v[62:63], v[62:63], v[44:45], v[80:81] op_sel:[1,1,0] op_sel_hi:[1,0,1] neg_lo:[0,1,0]
	v_pk_mul_f32 v[80:81], v[64:65], s[14:15] op_sel:[0,0] op_sel_hi:[0,1]
	v_pk_fma_f32 v[64:65], v[64:65], s[14:15], v[80:81] op_sel:[1,1,0] op_sel_hi:[1,0,1] neg_lo:[0,1,0]
	v_pk_mul_f32 v[80:81], v[70:71], s[58:59] op_sel:[0,0] op_sel_hi:[0,1]
	v_pk_fma_f32 v[70:71], v[70:71], s[58:59], v[80:81] op_sel:[1,1,0] op_sel_hi:[1,0,1] neg_lo:[0,1,0]
	v_pk_mul_f32 v[80:81], v[56:57], v[42:43] op_sel:[0,0] op_sel_hi:[0,1]
	v_pk_fma_f32 v[56:57], v[56:57], v[42:43], v[80:81] op_sel:[1,1,0] op_sel_hi:[1,0,1] neg_lo:[0,1,0]
	v_pk_mul_f32 v[80:81], v[58:59], s[58:59] op_sel:[0,0] op_sel_hi:[0,1]
	v_pk_fma_f32 v[58:59], v[58:59], s[58:59], v[80:81] op_sel:[1,1,0] op_sel_hi:[1,0,1] neg_lo:[0,1,0]
	v_pk_mul_f32 v[80:81], v[60:61], s[60:61] op_sel:[0,0] op_sel_hi:[0,1]
	v_pk_fma_f32 v[60:61], v[60:61], s[60:61], v[80:81] op_sel:[1,1,0] op_sel_hi:[1,0,1] neg_lo:[0,1,0]
	v_pk_add_f32 v[80:81], v[74:75], v[82:83]
	v_pk_add_f32 v[74:75], v[74:75], v[82:83] neg_lo:[0,1] neg_hi:[0,1]
	v_pk_add_f32 v[82:83], v[76:77], v[84:85]
	v_pk_add_f32 v[76:77], v[76:77], v[84:85] neg_lo:[0,1] neg_hi:[0,1]
	v_pk_add_f32 v[84:85], v[80:81], v[82:83]
	v_pk_add_f32 v[80:81], v[80:81], v[82:83] neg_lo:[0,1] neg_hi:[0,1]
	v_pk_add_f32 v[82:83], v[74:75], v[76:77] op_sel:[0,1] op_sel_hi:[1,0] neg_hi:[0,1]
	v_pk_add_f32 v[74:75], v[74:75], v[76:77] op_sel:[0,1] op_sel_hi:[1,0] neg_lo:[0,1]
	v_pk_add_f32 v[76:77], v[86:87], v[72:73]
	v_pk_add_f32 v[72:73], v[86:87], v[72:73] neg_lo:[0,1] neg_hi:[0,1]
	v_pk_add_f32 v[86:87], v[68:69], v[78:79]
	v_pk_add_f32 v[68:69], v[68:69], v[78:79] neg_lo:[0,1] neg_hi:[0,1]
	v_pk_add_f32 v[78:79], v[76:77], v[86:87]
	v_pk_add_f32 v[76:77], v[76:77], v[86:87] neg_lo:[0,1] neg_hi:[0,1]
	v_pk_add_f32 v[86:87], v[72:73], v[68:69] op_sel:[0,1] op_sel_hi:[1,0] neg_hi:[0,1]
	v_pk_add_f32 v[68:69], v[72:73], v[68:69] op_sel:[0,1] op_sel_hi:[1,0] neg_lo:[0,1]
	v_pk_add_f32 v[72:73], v[66:67], v[64:65]
	v_pk_add_f32 v[64:65], v[66:67], v[64:65] neg_lo:[0,1] neg_hi:[0,1]
	v_pk_add_f32 v[66:67], v[62:63], v[70:71]
	v_pk_add_f32 v[62:63], v[62:63], v[70:71] neg_lo:[0,1] neg_hi:[0,1]
	v_pk_add_f32 v[70:71], v[72:73], v[66:67]
	v_pk_add_f32 v[66:67], v[72:73], v[66:67] neg_lo:[0,1] neg_hi:[0,1]
	v_pk_add_f32 v[72:73], v[64:65], v[62:63] op_sel:[0,1] op_sel_hi:[1,0] neg_hi:[0,1]
	v_pk_add_f32 v[62:63], v[64:65], v[62:63] op_sel:[0,1] op_sel_hi:[1,0] neg_lo:[0,1]
	v_pk_add_f32 v[64:65], v[54:55], v[58:59]
	v_pk_add_f32 v[54:55], v[54:55], v[58:59] neg_lo:[0,1] neg_hi:[0,1]
	v_pk_add_f32 v[58:59], v[56:57], v[60:61]
	v_pk_add_f32 v[56:57], v[56:57], v[60:61] neg_lo:[0,1] neg_hi:[0,1]
	v_pk_add_f32 v[60:61], v[64:65], v[58:59]
	v_pk_add_f32 v[58:59], v[64:65], v[58:59] neg_lo:[0,1] neg_hi:[0,1]
	v_pk_add_f32 v[64:65], v[54:55], v[56:57] op_sel:[0,1] op_sel_hi:[1,0] neg_hi:[0,1]
	v_pk_add_f32 v[54:55], v[54:55], v[56:57] op_sel:[0,1] op_sel_hi:[1,0] neg_lo:[0,1]
	v_mov_b32_e32 v57, v41
	v_mov_b32_e32 v56, v40
	s_nop 0
	v_pk_mul_f32 v[88:89], v[78:79], v[56:57] op_sel:[0,0] op_sel_hi:[0,1]
	v_pk_fma_f32 v[78:79], v[78:79], v[56:57], v[88:89] op_sel:[1,1,0] op_sel_hi:[1,0,1] neg_lo:[0,1,0]
	ds_write2_b64 v146, v[84:85], v[78:79] offset1:17
	v_pk_mul_f32 v[78:79], v[56:57], v[56:57] op_sel:[0,0] op_sel_hi:[0,1]
	v_pk_fma_f32 v[78:79], v[56:57], v[56:57], v[78:79] op_sel:[1,1,0] op_sel_hi:[1,0,1] neg_lo:[0,1,0]
	v_pk_mul_f32 v[84:85], v[70:71], v[78:79] op_sel:[0,0] op_sel_hi:[0,1]
	v_pk_fma_f32 v[70:71], v[70:71], v[78:79], v[84:85] op_sel:[1,1,0] op_sel_hi:[1,0,1] neg_lo:[0,1,0]
	v_pk_mul_f32 v[84:85], v[78:79], v[56:57] op_sel:[0,0] op_sel_hi:[0,1]
	v_pk_fma_f32 v[78:79], v[78:79], v[56:57], v[84:85] op_sel:[1,1,0] op_sel_hi:[1,0,1] neg_lo:[0,1,0]
	v_pk_mul_f32 v[84:85], v[60:61], v[78:79] op_sel:[0,0] op_sel_hi:[0,1]
	v_pk_fma_f32 v[60:61], v[60:61], v[78:79], v[84:85] op_sel:[1,1,0] op_sel_hi:[1,0,1] neg_lo:[0,1,0]
	ds_write2_b64 v146, v[70:71], v[60:61] offset0:34 offset1:51
	v_pk_mul_f32 v[60:61], v[78:79], v[56:57] op_sel:[0,0] op_sel_hi:[0,1]
	v_pk_fma_f32 v[60:61], v[78:79], v[56:57], v[60:61] op_sel:[1,1,0] op_sel_hi:[1,0,1] neg_lo:[0,1,0]
	v_pk_mul_f32 v[70:71], v[82:83], v[60:61] op_sel:[0,0] op_sel_hi:[0,1]
	v_pk_mul_f32 v[78:79], v[60:61], v[56:57] op_sel:[0,0] op_sel_hi:[0,1]
	v_pk_fma_f32 v[70:71], v[82:83], v[60:61], v[70:71] op_sel:[1,1,0] op_sel_hi:[1,0,1] neg_lo:[0,1,0]
	v_pk_fma_f32 v[60:61], v[60:61], v[56:57], v[78:79] op_sel:[1,1,0] op_sel_hi:[1,0,1] neg_lo:[0,1,0]
	v_pk_mul_f32 v[78:79], v[86:87], v[60:61] op_sel:[0,0] op_sel_hi:[0,1]
	v_pk_fma_f32 v[78:79], v[86:87], v[60:61], v[78:79] op_sel:[1,1,0] op_sel_hi:[1,0,1] neg_lo:[0,1,0]
	ds_write2_b64 v146, v[70:71], v[78:79] offset0:68 offset1:85
	v_pk_mul_f32 v[70:71], v[60:61], v[56:57] op_sel:[0,0] op_sel_hi:[0,1]
	v_pk_fma_f32 v[60:61], v[60:61], v[56:57], v[70:71] op_sel:[1,1,0] op_sel_hi:[1,0,1] neg_lo:[0,1,0]
	v_pk_mul_f32 v[70:71], v[72:73], v[60:61] op_sel:[0,0] op_sel_hi:[0,1]
	v_pk_fma_f32 v[70:71], v[72:73], v[60:61], v[70:71] op_sel:[1,1,0] op_sel_hi:[1,0,1] neg_lo:[0,1,0]
	v_pk_mul_f32 v[72:73], v[60:61], v[56:57] op_sel:[0,0] op_sel_hi:[0,1]
	v_pk_fma_f32 v[60:61], v[60:61], v[56:57], v[72:73] op_sel:[1,1,0] op_sel_hi:[1,0,1] neg_lo:[0,1,0]
	v_pk_mul_f32 v[72:73], v[64:65], v[60:61] op_sel:[0,0] op_sel_hi:[0,1]
	v_pk_fma_f32 v[64:65], v[64:65], v[60:61], v[72:73] op_sel:[1,1,0] op_sel_hi:[1,0,1] neg_lo:[0,1,0]
	ds_write2_b64 v146, v[70:71], v[64:65] offset0:102 offset1:119
	v_pk_mul_f32 v[64:65], v[60:61], v[56:57] op_sel:[0,0] op_sel_hi:[0,1]
	v_pk_fma_f32 v[60:61], v[60:61], v[56:57], v[64:65] op_sel:[1,1,0] op_sel_hi:[1,0,1] neg_lo:[0,1,0]
	v_pk_mul_f32 v[64:65], v[80:81], v[60:61] op_sel:[0,0] op_sel_hi:[0,1]
	v_pk_mul_f32 v[70:71], v[60:61], v[56:57] op_sel:[0,0] op_sel_hi:[0,1]
	v_pk_fma_f32 v[64:65], v[80:81], v[60:61], v[64:65] op_sel:[1,1,0] op_sel_hi:[1,0,1] neg_lo:[0,1,0]
	v_pk_fma_f32 v[60:61], v[60:61], v[56:57], v[70:71] op_sel:[1,1,0] op_sel_hi:[1,0,1] neg_lo:[0,1,0]
	v_pk_mul_f32 v[70:71], v[76:77], v[60:61] op_sel:[0,0] op_sel_hi:[0,1]
	v_pk_fma_f32 v[70:71], v[76:77], v[60:61], v[70:71] op_sel:[1,1,0] op_sel_hi:[1,0,1] neg_lo:[0,1,0]
	ds_write2_b64 v146, v[64:65], v[70:71] offset0:136 offset1:153
	v_pk_mul_f32 v[64:65], v[60:61], v[56:57] op_sel:[0,0] op_sel_hi:[0,1]
	v_pk_fma_f32 v[60:61], v[60:61], v[56:57], v[64:65] op_sel:[1,1,0] op_sel_hi:[1,0,1] neg_lo:[0,1,0]
	v_pk_mul_f32 v[64:65], v[66:67], v[60:61] op_sel:[0,0] op_sel_hi:[0,1]
	v_pk_fma_f32 v[64:65], v[66:67], v[60:61], v[64:65] op_sel:[1,1,0] op_sel_hi:[1,0,1] neg_lo:[0,1,0]
	v_pk_mul_f32 v[66:67], v[60:61], v[56:57] op_sel:[0,0] op_sel_hi:[0,1]
	v_pk_fma_f32 v[60:61], v[60:61], v[56:57], v[66:67] op_sel:[1,1,0] op_sel_hi:[1,0,1] neg_lo:[0,1,0]
	v_pk_mul_f32 v[66:67], v[58:59], v[60:61] op_sel:[0,0] op_sel_hi:[0,1]
	v_pk_fma_f32 v[58:59], v[58:59], v[60:61], v[66:67] op_sel:[1,1,0] op_sel_hi:[1,0,1] neg_lo:[0,1,0]
	ds_write2_b64 v146, v[64:65], v[58:59] offset0:170 offset1:187
	v_pk_mul_f32 v[58:59], v[60:61], v[56:57] op_sel:[0,0] op_sel_hi:[0,1]
	v_pk_fma_f32 v[58:59], v[60:61], v[56:57], v[58:59] op_sel:[1,1,0] op_sel_hi:[1,0,1] neg_lo:[0,1,0]
	v_pk_mul_f32 v[60:61], v[74:75], v[58:59] op_sel:[0,0] op_sel_hi:[0,1]
	v_pk_mul_f32 v[64:65], v[58:59], v[56:57] op_sel:[0,0] op_sel_hi:[0,1]
	v_pk_fma_f32 v[60:61], v[74:75], v[58:59], v[60:61] op_sel:[1,1,0] op_sel_hi:[1,0,1] neg_lo:[0,1,0]
	v_pk_fma_f32 v[58:59], v[58:59], v[56:57], v[64:65] op_sel:[1,1,0] op_sel_hi:[1,0,1] neg_lo:[0,1,0]
	v_pk_mul_f32 v[64:65], v[68:69], v[58:59] op_sel:[0,0] op_sel_hi:[0,1]
	v_pk_fma_f32 v[64:65], v[68:69], v[58:59], v[64:65] op_sel:[1,1,0] op_sel_hi:[1,0,1] neg_lo:[0,1,0]
	ds_write2_b64 v146, v[60:61], v[64:65] offset0:204 offset1:221
	v_pk_mul_f32 v[60:61], v[58:59], v[56:57] op_sel:[0,0] op_sel_hi:[0,1]
	v_pk_fma_f32 v[58:59], v[58:59], v[56:57], v[60:61] op_sel:[1,1,0] op_sel_hi:[1,0,1] neg_lo:[0,1,0]
	v_pk_mul_f32 v[60:61], v[62:63], v[58:59] op_sel:[0,0] op_sel_hi:[0,1]
	v_pk_fma_f32 v[60:61], v[62:63], v[58:59], v[60:61] op_sel:[1,1,0] op_sel_hi:[1,0,1] neg_lo:[0,1,0]
	v_pk_mul_f32 v[62:63], v[58:59], v[56:57] op_sel:[0,0] op_sel_hi:[0,1]
	v_pk_fma_f32 v[56:57], v[58:59], v[56:57], v[62:63] op_sel:[1,1,0] op_sel_hi:[1,0,1] neg_lo:[0,1,0]
	v_pk_mul_f32 v[58:59], v[54:55], v[56:57] op_sel:[0,0] op_sel_hi:[0,1]
	v_pk_fma_f32 v[54:55], v[54:55], v[56:57], v[58:59] op_sel:[1,1,0] op_sel_hi:[1,0,1] neg_lo:[0,1,0]
	ds_write2_b64 v146, v[60:61], v[54:55] offset0:238 offset1:255
	s_waitcnt lgkmcnt(0)
	s_barrier
	ds_read2_b64 v[60:63], v147 offset1:1
	ds_read2_b64 v[64:67], v147 offset0:2 offset1:3
	ds_read2_b64 v[68:71], v147 offset0:8 offset1:9
	ds_read2_b64 v[72:75], v147 offset0:4 offset1:5
	ds_read2_b64 v[76:79], v147 offset0:6 offset1:7
	ds_read2_b64 v[80:83], v147 offset0:12 offset1:13
	ds_read2_b64 v[84:87], v147 offset0:10 offset1:11
	ds_read2_b64 v[88:91], v147 offset0:14 offset1:15
	s_waitcnt lgkmcnt(5)
	v_pk_add_f32 v[54:55], v[60:61], v[68:69]
	v_pk_add_f32 v[68:69], v[60:61], v[68:69] neg_lo:[0,1] neg_hi:[0,1]
	s_waitcnt lgkmcnt(2)
	v_pk_add_f32 v[56:57], v[72:73], v[80:81]
	v_pk_add_f32 v[72:73], v[72:73], v[80:81] neg_lo:[0,1] neg_hi:[0,1]
	v_pk_add_f32 v[60:61], v[54:55], v[56:57]
	v_pk_add_f32 v[56:57], v[54:55], v[56:57] neg_lo:[0,1] neg_hi:[0,1]
	v_pk_add_f32 v[58:59], v[68:69], v[72:73] op_sel:[0,1] op_sel_hi:[1,0] neg_hi:[0,1]
	v_pk_add_f32 v[54:55], v[68:69], v[72:73] op_sel:[0,1] op_sel_hi:[1,0] neg_lo:[0,1]
	v_pk_add_f32 v[68:69], v[62:63], v[70:71]
	v_pk_add_f32 v[70:71], v[62:63], v[70:71] neg_lo:[0,1] neg_hi:[0,1]
	v_pk_add_f32 v[72:73], v[74:75], v[82:83]
	v_pk_add_f32 v[74:75], v[74:75], v[82:83] neg_lo:[0,1] neg_hi:[0,1]
	v_pk_add_f32 v[62:63], v[68:69], v[72:73]
	v_pk_add_f32 v[68:69], v[68:69], v[72:73] neg_lo:[0,1] neg_hi:[0,1]
	v_pk_add_f32 v[72:73], v[70:71], v[74:75] op_sel:[0,1] op_sel_hi:[1,0] neg_hi:[0,1]
	v_pk_add_f32 v[70:71], v[70:71], v[74:75] op_sel:[0,1] op_sel_hi:[1,0] neg_lo:[0,1]
	s_waitcnt lgkmcnt(1)
	v_pk_add_f32 v[74:75], v[64:65], v[84:85]
	v_pk_add_f32 v[80:81], v[64:65], v[84:85] neg_lo:[0,1] neg_hi:[0,1]
	s_waitcnt lgkmcnt(0)
	v_pk_add_f32 v[82:83], v[76:77], v[88:89]
	v_pk_add_f32 v[76:77], v[76:77], v[88:89] neg_lo:[0,1] neg_hi:[0,1]
	v_pk_add_f32 v[64:65], v[74:75], v[82:83]
	v_pk_add_f32 v[74:75], v[74:75], v[82:83] neg_lo:[0,1] neg_hi:[0,1]
	v_pk_add_f32 v[82:83], v[80:81], v[76:77] op_sel:[0,1] op_sel_hi:[1,0] neg_hi:[0,1]
	v_pk_add_f32 v[76:77], v[80:81], v[76:77] op_sel:[0,1] op_sel_hi:[1,0] neg_lo:[0,1]
	v_pk_add_f32 v[80:81], v[66:67], v[86:87]
	v_pk_add_f32 v[84:85], v[66:67], v[86:87] neg_lo:[0,1] neg_hi:[0,1]
	v_pk_add_f32 v[86:87], v[78:79], v[90:91]
	v_pk_add_f32 v[78:79], v[78:79], v[90:91] neg_lo:[0,1] neg_hi:[0,1]
	v_pk_add_f32 v[66:67], v[80:81], v[86:87]
	v_pk_add_f32 v[86:87], v[80:81], v[86:87] neg_lo:[0,1] neg_hi:[0,1]
	v_pk_add_f32 v[80:81], v[84:85], v[78:79] op_sel:[0,1] op_sel_hi:[1,0] neg_hi:[0,1]
	v_pk_add_f32 v[90:91], v[84:85], v[78:79] op_sel:[0,1] op_sel_hi:[1,0] neg_lo:[0,1]
	v_pk_mul_f32 v[78:79], v[72:73], s[20:21] op_sel:[0,0] op_sel_hi:[0,1]
	v_pk_fma_f32 v[48:49], v[72:73], s[20:21], v[78:79] op_sel:[1,1,0] op_sel_hi:[1,0,1] neg_lo:[0,1,0]
	v_pk_mul_f32 v[72:73], v[82:83], v[44:45] op_sel:[0,0] op_sel_hi:[0,1]
	s_barrier
	v_pk_fma_f32 v[78:79], v[82:83], v[44:45], v[72:73] op_sel:[1,1,0] op_sel_hi:[1,0,1] neg_lo:[0,1,0]
	v_pk_mul_f32 v[72:73], v[80:81], v[42:43] op_sel:[0,0] op_sel_hi:[0,1]
	v_pk_fma_f32 v[80:81], v[80:81], v[42:43], v[72:73] op_sel:[1,1,0] op_sel_hi:[1,0,1] neg_lo:[0,1,0]
	v_pk_mul_f32 v[72:73], v[68:69], v[44:45] op_sel:[0,0] op_sel_hi:[0,1]
	v_pk_fma_f32 v[44:45], v[68:69], v[44:45], v[72:73] op_sel:[1,1,0] op_sel_hi:[1,0,1] neg_lo:[0,1,0]
	v_pk_mul_f32 v[68:69], v[74:75], s[14:15] op_sel:[0,0] op_sel_hi:[0,1]
	v_pk_fma_f32 v[84:85], v[74:75], s[14:15], v[68:69] op_sel:[1,1,0] op_sel_hi:[1,0,1] neg_lo:[0,1,0]
	v_pk_mul_f32 v[50:51], v[86:87], s[58:59] op_sel:[0,0] op_sel_hi:[0,1]
	v_pk_add_f32 v[68:69], v[58:59], v[78:79] neg_lo:[0,1] neg_hi:[0,1]
	v_pk_fma_f32 v[88:89], v[86:87], s[58:59], v[50:51] op_sel:[1,1,0] op_sel_hi:[1,0,1] neg_lo:[0,1,0]
	v_pk_mul_f32 v[50:51], v[70:71], v[42:43] op_sel:[0,0] op_sel_hi:[0,1]
	v_pk_add_f32 v[72:73], v[56:57], v[84:85] neg_lo:[0,1] neg_hi:[0,1]
	v_pk_fma_f32 v[82:83], v[70:71], v[42:43], v[50:51] op_sel:[1,1,0] op_sel_hi:[1,0,1] neg_lo:[0,1,0]
	v_pk_mul_f32 v[42:43], v[76:77], s[58:59] op_sel:[0,0] op_sel_hi:[0,1]
	v_pk_add_f32 v[50:51], v[62:63], v[66:67] neg_lo:[0,1] neg_hi:[0,1]
	v_pk_fma_f32 v[86:87], v[76:77], s[58:59], v[42:43] op_sel:[1,1,0] op_sel_hi:[1,0,1] neg_lo:[0,1,0]
	v_pk_mul_f32 v[42:43], v[90:91], s[60:61] op_sel:[0,0] op_sel_hi:[0,1]
	v_pk_add_f32 v[46:47], v[60:61], v[64:65] neg_lo:[0,1] neg_hi:[0,1]
	v_pk_fma_f32 v[52:53], v[90:91], s[60:61], v[42:43] op_sel:[1,1,0] op_sel_hi:[1,0,1] neg_lo:[0,1,0]
	v_pk_add_f32 v[70:71], v[48:49], v[80:81] neg_lo:[0,1] neg_hi:[0,1]
	v_pk_add_f32 v[74:75], v[44:45], v[88:89] neg_lo:[0,1] neg_hi:[0,1]
	v_pk_add_f32 v[76:77], v[54:55], v[86:87] neg_lo:[0,1] neg_hi:[0,1]
	v_pk_add_f32 v[90:91], v[82:83], v[52:53] neg_lo:[0,1] neg_hi:[0,1]
	v_pk_add_f32 v[42:43], v[46:47], v[50:51] op_sel:[0,1] op_sel_hi:[1,0] neg_hi:[0,1]
	v_pk_add_f32 v[46:47], v[46:47], v[50:51] op_sel:[0,1] op_sel_hi:[1,0] neg_lo:[0,1]
	v_pk_add_f32 v[50:51], v[68:69], v[70:71] op_sel:[0,1] op_sel_hi:[1,0] neg_hi:[0,1]
	v_pk_add_f32 v[68:69], v[68:69], v[70:71] op_sel:[0,1] op_sel_hi:[1,0] neg_lo:[0,1]
	v_pk_add_f32 v[70:71], v[72:73], v[74:75] op_sel:[0,1] op_sel_hi:[1,0] neg_hi:[0,1]
	v_pk_add_f32 v[72:73], v[72:73], v[74:75] op_sel:[0,1] op_sel_hi:[1,0] neg_lo:[0,1]
	v_pk_add_f32 v[74:75], v[76:77], v[90:91] op_sel:[0,1] op_sel_hi:[1,0] neg_hi:[0,1]
	v_pk_add_f32 v[76:77], v[76:77], v[90:91] op_sel:[0,1] op_sel_hi:[1,0] neg_lo:[0,1]
	v_mov_b32_e32 v90, v36
	v_mov_b32_e32 v91, v37
	s_branch .LBB0_1409

.LBB0_1411:
	v_mov_b32_e32 v90, v30
	v_mov_b32_e32 v91, v26
	v_mov_b32_e32 v26, v31
	v_mov_b32_e32 v30, v32
	v_mov_b32_e32 v31, v28
	v_mov_b32_e32 v28, v33
	v_pk_add_f32 v[26:27], v[90:91], v[26:27]
	v_pk_add_f32 v[28:29], v[30:31], v[28:29]
	v_pk_add_f32 v[30:31], v[62:63], v[66:67]
	v_pk_add_f32 v[26:27], v[26:27], v[28:29]
	v_pk_add_f32 v[28:29], v[60:61], v[64:65]
	v_add_f32_e32 v34, v26, v27
	v_add_f32_e32 v34, 0x358637bd, v34
	v_mul_f32_e32 v34, 0x46000000, v34
	v_pk_add_f32 v[60:61], v[48:49], v[80:81]
	v_div_scale_f32 v48, s[0:1], v34, v34, 1.0
	v_rcp_f32_e32 v49, v48
	v_pk_add_f32 v[62:63], v[56:57], v[84:85]
	v_pk_add_f32 v[58:59], v[58:59], v[78:79]
	v_pk_add_f32 v[44:45], v[44:45], v[88:89]
	v_fma_f32 v56, -v48, v49, 1.0
	v_fmac_f32_e32 v49, v56, v49
	v_div_scale_f32 v56, vcc, 1.0, v34, 1.0
	v_mul_f32_e32 v57, v56, v49
	v_fma_f32 v78, -v48, v57, v56
	v_fmac_f32_e32 v57, v78, v49
	v_fma_f32 v48, -v48, v57, v56
	v_pk_add_f32 v[54:55], v[54:55], v[86:87]
	v_pk_add_f32 v[52:53], v[82:83], v[52:53]
	v_div_fmas_f32 v48, v48, v49, v57
	v_pk_add_f32 v[26:27], v[28:29], v[30:31]
	v_pk_add_f32 v[32:33], v[58:59], v[60:61]
	v_pk_add_f32 v[64:65], v[62:63], v[44:45]
	v_pk_add_f32 v[66:67], v[54:55], v[52:53]
	v_div_fixup_f32 v34, v48, v34, 1.0
	v_pk_add_f32 v[28:29], v[28:29], v[30:31] neg_lo:[0,1] neg_hi:[0,1]
	v_pk_add_f32 v[30:31], v[58:59], v[60:61] neg_lo:[0,1] neg_hi:[0,1]
	v_pk_add_f32 v[54:55], v[54:55], v[52:53] neg_lo:[0,1] neg_hi:[0,1]
	v_pk_mul_f32 v[56:57], v[34:35], v[26:27] op_sel_hi:[0,1]
	v_pk_mul_f32 v[48:49], v[34:35], v[32:33] op_sel_hi:[0,1]
	v_pk_mul_f32 v[32:33], v[34:35], v[64:65] op_sel_hi:[0,1]
	v_pk_mul_f32 v[26:27], v[34:35], v[66:67] op_sel_hi:[0,1]
	v_pk_add_f32 v[44:45], v[62:63], v[44:45] neg_lo:[0,1] neg_hi:[0,1]
	v_pk_mul_f32 v[60:61], v[34:35], v[28:29] op_sel_hi:[0,1]
	v_pk_mul_f32 v[52:53], v[34:35], v[30:31] op_sel_hi:[0,1]
	v_pk_mul_f32 v[28:29], v[34:35], v[54:55] op_sel_hi:[0,1]
	v_pk_mul_f32 v[64:65], v[34:35], v[42:43] op_sel_hi:[0,1]
	v_pk_mul_f32 v[62:63], v[34:35], v[46:47] op_sel_hi:[0,1]
	v_pk_mul_f32 v[58:59], v[34:35], v[50:51] op_sel_hi:[0,1]
	v_pk_mul_f32 v[54:55], v[34:35], v[68:69] op_sel_hi:[0,1]
	v_pk_mul_f32 v[50:51], v[34:35], v[70:71] op_sel_hi:[0,1]
	v_pk_mul_f32 v[46:47], v[34:35], v[72:73] op_sel_hi:[0,1]
	v_pk_mul_f32 v[42:43], v[34:35], v[74:75] op_sel_hi:[0,1]
	v_pk_mul_f32 v[30:31], v[34:35], v[76:77] op_sel_hi:[0,1]
	ds_read_b64 v[66:67], v144
	ds_read_b64 v[68:69], v144 offset:2176
	ds_read_b64 v[70:71], v144 offset:4352
	ds_read_b64 v[72:73], v144 offset:6528
	ds_read_b64 v[74:75], v144 offset:8704
	ds_read_b64 v[76:77], v144 offset:10880
	ds_read_b64 v[78:79], v144 offset:13056
	ds_read_b64 v[80:81], v144 offset:15232
	ds_read_b64 v[82:83], v144 offset:17408
	ds_read_b64 v[84:85], v144 offset:19584
	ds_read_b64 v[86:87], v144 offset:21760
	ds_read_b64 v[88:89], v144 offset:23936
	ds_read_b64 v[90:91], v144 offset:26112
	ds_read_b64 v[92:93], v144 offset:28288
	ds_read_b64 v[96:97], v144 offset:30464
	ds_read_b64 v[98:99], v144 offset:32640
	s_waitcnt lgkmcnt(7)
	v_pk_add_f32 v[100:101], v[66:67], v[82:83]
	v_pk_add_f32 v[66:67], v[66:67], v[82:83] neg_lo:[0,1] neg_hi:[0,1]
	s_waitcnt lgkmcnt(3)
	v_pk_add_f32 v[82:83], v[74:75], v[90:91]
	v_pk_add_f32 v[74:75], v[74:75], v[90:91] neg_lo:[0,1] neg_hi:[0,1]
	v_pk_add_f32 v[90:91], v[100:101], v[82:83]
	v_pk_add_f32 v[82:83], v[100:101], v[82:83] neg_lo:[0,1] neg_hi:[0,1]
	v_pk_add_f32 v[100:101], v[66:67], v[74:75] op_sel:[0,1] op_sel_hi:[1,0] neg_hi:[0,1]
	v_pk_add_f32 v[102:103], v[66:67], v[74:75] op_sel:[0,1] op_sel_hi:[1,0] neg_lo:[0,1]
	v_pk_add_f32 v[66:67], v[68:69], v[84:85]
	v_pk_add_f32 v[68:69], v[68:69], v[84:85] neg_lo:[0,1] neg_hi:[0,1]
	s_waitcnt lgkmcnt(2)
	v_pk_add_f32 v[74:75], v[76:77], v[92:93]
	v_pk_add_f32 v[76:77], v[76:77], v[92:93] neg_lo:[0,1] neg_hi:[0,1]
	v_pk_add_f32 v[84:85], v[66:67], v[74:75]
	v_pk_add_f32 v[74:75], v[66:67], v[74:75] neg_lo:[0,1] neg_hi:[0,1]
	v_pk_add_f32 v[66:67], v[68:69], v[76:77] op_sel:[0,1] op_sel_hi:[1,0] neg_hi:[0,1]
	v_pk_add_f32 v[76:77], v[68:69], v[76:77] op_sel:[0,1] op_sel_hi:[1,0] neg_lo:[0,1]
	v_pk_add_f32 v[68:69], v[70:71], v[86:87]
	v_pk_add_f32 v[70:71], v[70:71], v[86:87] neg_lo:[0,1] neg_hi:[0,1]
	s_waitcnt lgkmcnt(1)
	v_pk_add_f32 v[86:87], v[78:79], v[96:97]
	v_pk_add_f32 v[78:79], v[78:79], v[96:97] neg_lo:[0,1] neg_hi:[0,1]
	v_pk_add_f32 v[92:93], v[68:69], v[86:87]
	v_pk_add_f32 v[86:87], v[68:69], v[86:87] neg_lo:[0,1] neg_hi:[0,1]
	v_pk_add_f32 v[96:97], v[70:71], v[78:79] op_sel:[0,1] op_sel_hi:[1,0] neg_hi:[0,1]
	v_pk_add_f32 v[78:79], v[70:71], v[78:79] op_sel:[0,1] op_sel_hi:[1,0] neg_lo:[0,1]
	v_pk_add_f32 v[68:69], v[72:73], v[88:89]
	v_pk_add_f32 v[70:71], v[72:73], v[88:89] neg_lo:[0,1] neg_hi:[0,1]
	s_waitcnt lgkmcnt(0)
	v_pk_add_f32 v[72:73], v[80:81], v[98:99]
	v_pk_add_f32 v[80:81], v[80:81], v[98:99] neg_lo:[0,1] neg_hi:[0,1]
	v_pk_add_f32 v[88:89], v[68:69], v[72:73]
	v_pk_add_f32 v[98:99], v[68:69], v[72:73] neg_lo:[0,1] neg_hi:[0,1]
	v_pk_mul_f32 v[68:69], v[66:67], s[20:21] op_sel:[0,0] op_sel_hi:[0,1]
	v_pk_add_f32 v[104:105], v[70:71], v[80:81] op_sel:[0,1] op_sel_hi:[1,0] neg_hi:[0,1]
	v_pk_add_f32 v[80:81], v[70:71], v[80:81] op_sel:[0,1] op_sel_hi:[1,0] neg_lo:[0,1]
	s_add_i32 s82, s74, s24
	v_pk_fma_f32 v[106:107], v[66:67], s[20:21], v[68:69] op_sel:[1,1,0] op_sel_hi:[1,0,1] neg_lo:[0,1,0]
	v_pk_mul_f32 v[66:67], v[96:97], s[50:51] op_sel:[0,0] op_sel_hi:[0,1]
	s_cmpk_gt_i32 s82, 0x3ff
	v_pk_fma_f32 v[96:97], v[96:97], s[50:51], v[66:67] op_sel:[1,1,0] op_sel_hi:[1,0,1] neg_lo:[0,1,0]
	v_pk_mul_f32 v[70:71], v[104:105], s[54:55] op_sel:[0,0] op_sel_hi:[0,1]
	v_pk_mul_f32 v[44:45], v[34:35], v[44:45] op_sel_hi:[0,1]
	v_pk_fma_f32 v[104:105], v[104:105], s[54:55], v[70:71] op_sel:[1,1,0] op_sel_hi:[1,0,1] neg_lo:[0,1,0]
	v_pk_mul_f32 v[70:71], v[74:75], s[50:51] op_sel:[0,0] op_sel_hi:[0,1]
	s_cselect_b64 s[80:81], -1, 0
	v_pk_fma_f32 v[108:109], v[74:75], s[50:51], v[70:71] op_sel:[1,1,0] op_sel_hi:[1,0,1] neg_lo:[0,1,0]
	v_mov_b64_e32 v[74:75], s[14:15]
	v_pk_mul_f32 v[70:71], v[86:87], v[74:75] op_sel:[0,0] op_sel_hi:[0,1]
	s_cmpk_lt_i32 s82, 0x400
	v_pk_fma_f32 v[86:87], v[86:87], v[74:75], v[70:71] op_sel:[1,1,0] op_sel_hi:[1,0,1] neg_lo:[0,1,0]
	v_mov_b64_e32 v[70:71], s[58:59]
	v_pk_mul_f32 v[110:111], v[98:99], v[70:71] op_sel:[0,0] op_sel_hi:[0,1]
	s_cselect_b32 s0, s82, -1
	v_pk_fma_f32 v[98:99], v[98:99], v[70:71], v[110:111] op_sel:[1,1,0] op_sel_hi:[1,0,1] neg_lo:[0,1,0]
	v_pk_mul_f32 v[110:111], v[76:77], s[54:55] op_sel:[0,0] op_sel_hi:[0,1]
	s_cmp_lt_i32 s0, 0
	v_pk_fma_f32 v[110:111], v[76:77], s[54:55], v[110:111] op_sel:[1,1,0] op_sel_hi:[1,0,1] neg_lo:[0,1,0]
	v_pk_mul_f32 v[76:77], v[78:79], v[70:71] op_sel:[0,0] op_sel_hi:[0,1]
	v_pk_fma_f32 v[78:79], v[78:79], v[70:71], v[76:77] op_sel:[1,1,0] op_sel_hi:[1,0,1] neg_lo:[0,1,0]
	v_pk_mul_f32 v[112:113], v[80:81], s[60:61] op_sel:[0,0] op_sel_hi:[0,1]
	v_pk_fma_f32 v[80:81], v[80:81], s[60:61], v[112:113] op_sel:[1,1,0] op_sel_hi:[1,0,1] neg_lo:[0,1,0]
	v_pk_add_f32 v[112:113], v[90:91], v[92:93]
	v_pk_add_f32 v[90:91], v[90:91], v[92:93] neg_lo:[0,1] neg_hi:[0,1]
	v_pk_add_f32 v[92:93], v[84:85], v[88:89]
	v_pk_add_f32 v[84:85], v[84:85], v[88:89] neg_lo:[0,1] neg_hi:[0,1]
	v_pk_add_f32 v[88:89], v[112:113], v[92:93]
	v_pk_add_f32 v[92:93], v[112:113], v[92:93] neg_lo:[0,1] neg_hi:[0,1]
	v_pk_add_f32 v[112:113], v[90:91], v[84:85] op_sel:[0,1] op_sel_hi:[1,0] neg_hi:[0,1]
	v_pk_add_f32 v[84:85], v[90:91], v[84:85] op_sel:[0,1] op_sel_hi:[1,0] neg_lo:[0,1]
	v_pk_add_f32 v[90:91], v[100:101], v[96:97]
	v_pk_add_f32 v[96:97], v[100:101], v[96:97] neg_lo:[0,1] neg_hi:[0,1]
	v_pk_add_f32 v[100:101], v[106:107], v[104:105]
	v_pk_add_f32 v[104:105], v[106:107], v[104:105] neg_lo:[0,1] neg_hi:[0,1]
	v_pk_add_f32 v[106:107], v[90:91], v[100:101]
	v_pk_add_f32 v[90:91], v[90:91], v[100:101] neg_lo:[0,1] neg_hi:[0,1]
	v_pk_add_f32 v[100:101], v[96:97], v[104:105] op_sel:[0,1] op_sel_hi:[1,0] neg_hi:[0,1]
	v_pk_add_f32 v[96:97], v[96:97], v[104:105] op_sel:[0,1] op_sel_hi:[1,0] neg_lo:[0,1]
	v_pk_add_f32 v[104:105], v[82:83], v[86:87]
	v_pk_add_f32 v[82:83], v[82:83], v[86:87] neg_lo:[0,1] neg_hi:[0,1]
	v_pk_add_f32 v[86:87], v[108:109], v[98:99]
	v_pk_add_f32 v[98:99], v[108:109], v[98:99] neg_lo:[0,1] neg_hi:[0,1]
	v_pk_add_f32 v[108:109], v[104:105], v[86:87]
	v_pk_add_f32 v[86:87], v[104:105], v[86:87] neg_lo:[0,1] neg_hi:[0,1]
	v_pk_add_f32 v[104:105], v[82:83], v[98:99] op_sel:[0,1] op_sel_hi:[1,0] neg_hi:[0,1]
	v_pk_add_f32 v[82:83], v[82:83], v[98:99] op_sel:[0,1] op_sel_hi:[1,0] neg_lo:[0,1]
	v_pk_add_f32 v[98:99], v[102:103], v[78:79]
	v_pk_add_f32 v[78:79], v[102:103], v[78:79] neg_lo:[0,1] neg_hi:[0,1]
	v_pk_add_f32 v[102:103], v[110:111], v[80:81]
	v_pk_add_f32 v[80:81], v[110:111], v[80:81] neg_lo:[0,1] neg_hi:[0,1]
	v_pk_add_f32 v[110:111], v[98:99], v[102:103]
	v_pk_add_f32 v[98:99], v[98:99], v[102:103] neg_lo:[0,1] neg_hi:[0,1]
	v_pk_add_f32 v[102:103], v[78:79], v[80:81] op_sel:[0,1] op_sel_hi:[1,0] neg_hi:[0,1]
	v_pk_add_f32 v[78:79], v[78:79], v[80:81] op_sel:[0,1] op_sel_hi:[1,0] neg_lo:[0,1]
	v_mov_b32_e32 v80, v38
	v_mov_b32_e32 v81, v39
	ds_write_b64 v144, v[88:89]
	v_pk_mul_f32 v[88:89], v[106:107], v[80:81] op_sel:[0,0] op_sel_hi:[0,1]
	v_pk_fma_f32 v[88:89], v[106:107], v[80:81], v[88:89] op_sel:[1,1,0] op_sel_hi:[1,0,1] neg_lo:[0,1,0]
	ds_write_b64 v144, v[88:89] offset:2176
	v_pk_mul_f32 v[88:89], v[80:81], v[80:81] op_sel:[0,0] op_sel_hi:[0,1]
	v_pk_fma_f32 v[88:89], v[80:81], v[80:81], v[88:89] op_sel:[1,1,0] op_sel_hi:[1,0,1] neg_lo:[0,1,0]
	v_pk_mul_f32 v[106:107], v[108:109], v[88:89] op_sel:[0,0] op_sel_hi:[0,1]
	v_pk_fma_f32 v[106:107], v[108:109], v[88:89], v[106:107] op_sel:[1,1,0] op_sel_hi:[1,0,1] neg_lo:[0,1,0]
	ds_write_b64 v144, v[106:107] offset:4352
	v_pk_mul_f32 v[106:107], v[88:89], v[80:81] op_sel:[0,0] op_sel_hi:[0,1]
	v_pk_fma_f32 v[88:89], v[88:89], v[80:81], v[106:107] op_sel:[1,1,0] op_sel_hi:[1,0,1] neg_lo:[0,1,0]
	v_pk_mul_f32 v[106:107], v[110:111], v[88:89] op_sel:[0,0] op_sel_hi:[0,1]
	v_pk_fma_f32 v[106:107], v[110:111], v[88:89], v[106:107] op_sel:[1,1,0] op_sel_hi:[1,0,1] neg_lo:[0,1,0]
	ds_write_b64 v144, v[106:107] offset:6528
	v_pk_mul_f32 v[106:107], v[88:89], v[80:81] op_sel:[0,0] op_sel_hi:[0,1]
	v_pk_fma_f32 v[88:89], v[88:89], v[80:81], v[106:107] op_sel:[1,1,0] op_sel_hi:[1,0,1] neg_lo:[0,1,0]
	v_pk_mul_f32 v[106:107], v[112:113], v[88:89] op_sel:[0,0] op_sel_hi:[0,1]
	v_pk_fma_f32 v[106:107], v[112:113], v[88:89], v[106:107] op_sel:[1,1,0] op_sel_hi:[1,0,1] neg_lo:[0,1,0]
	ds_write_b64 v144, v[106:107] offset:8704
	v_pk_mul_f32 v[106:107], v[88:89], v[80:81] op_sel:[0,0] op_sel_hi:[0,1]
	v_pk_fma_f32 v[88:89], v[88:89], v[80:81], v[106:107] op_sel:[1,1,0] op_sel_hi:[1,0,1] neg_lo:[0,1,0]
	v_pk_mul_f32 v[106:107], v[100:101], v[88:89] op_sel:[0,0] op_sel_hi:[0,1]
	v_pk_fma_f32 v[100:101], v[100:101], v[88:89], v[106:107] op_sel:[1,1,0] op_sel_hi:[1,0,1] neg_lo:[0,1,0]
	ds_write_b64 v144, v[100:101] offset:10880
	v_pk_mul_f32 v[100:101], v[88:89], v[80:81] op_sel:[0,0] op_sel_hi:[0,1]
	v_pk_fma_f32 v[88:89], v[88:89], v[80:81], v[100:101] op_sel:[1,1,0] op_sel_hi:[1,0,1] neg_lo:[0,1,0]
	v_pk_mul_f32 v[100:101], v[104:105], v[88:89] op_sel:[0,0] op_sel_hi:[0,1]
	v_pk_fma_f32 v[100:101], v[104:105], v[88:89], v[100:101] op_sel:[1,1,0] op_sel_hi:[1,0,1] neg_lo:[0,1,0]
	ds_write_b64 v144, v[100:101] offset:13056
	v_pk_mul_f32 v[100:101], v[88:89], v[80:81] op_sel:[0,0] op_sel_hi:[0,1]
	v_pk_fma_f32 v[88:89], v[88:89], v[80:81], v[100:101] op_sel:[1,1,0] op_sel_hi:[1,0,1] neg_lo:[0,1,0]
	v_pk_mul_f32 v[100:101], v[102:103], v[88:89] op_sel:[0,0] op_sel_hi:[0,1]
	v_pk_fma_f32 v[100:101], v[102:103], v[88:89], v[100:101] op_sel:[1,1,0] op_sel_hi:[1,0,1] neg_lo:[0,1,0]
	ds_write_b64 v144, v[100:101] offset:15232
	v_pk_mul_f32 v[100:101], v[88:89], v[80:81] op_sel:[0,0] op_sel_hi:[0,1]
	v_pk_fma_f32 v[88:89], v[88:89], v[80:81], v[100:101] op_sel:[1,1,0] op_sel_hi:[1,0,1] neg_lo:[0,1,0]
	v_pk_mul_f32 v[100:101], v[92:93], v[88:89] op_sel:[0,0] op_sel_hi:[0,1]
	v_pk_fma_f32 v[92:93], v[92:93], v[88:89], v[100:101] op_sel:[1,1,0] op_sel_hi:[1,0,1] neg_lo:[0,1,0]
	ds_write_b64 v144, v[92:93] offset:17408
	v_pk_mul_f32 v[92:93], v[88:89], v[80:81] op_sel:[0,0] op_sel_hi:[0,1]
	v_pk_fma_f32 v[88:89], v[88:89], v[80:81], v[92:93] op_sel:[1,1,0] op_sel_hi:[1,0,1] neg_lo:[0,1,0]
	v_pk_mul_f32 v[92:93], v[90:91], v[88:89] op_sel:[0,0] op_sel_hi:[0,1]
	v_pk_fma_f32 v[90:91], v[90:91], v[88:89], v[92:93] op_sel:[1,1,0] op_sel_hi:[1,0,1] neg_lo:[0,1,0]
	ds_write_b64 v144, v[90:91] offset:19584
	v_pk_mul_f32 v[90:91], v[88:89], v[80:81] op_sel:[0,0] op_sel_hi:[0,1]
	v_pk_fma_f32 v[88:89], v[88:89], v[80:81], v[90:91] op_sel:[1,1,0] op_sel_hi:[1,0,1] neg_lo:[0,1,0]
	v_pk_mul_f32 v[90:91], v[86:87], v[88:89] op_sel:[0,0] op_sel_hi:[0,1]
	v_pk_fma_f32 v[86:87], v[86:87], v[88:89], v[90:91] op_sel:[1,1,0] op_sel_hi:[1,0,1] neg_lo:[0,1,0]
	ds_write_b64 v144, v[86:87] offset:21760
	v_pk_mul_f32 v[86:87], v[88:89], v[80:81] op_sel:[0,0] op_sel_hi:[0,1]
	v_pk_fma_f32 v[86:87], v[88:89], v[80:81], v[86:87] op_sel:[1,1,0] op_sel_hi:[1,0,1] neg_lo:[0,1,0]
	v_pk_mul_f32 v[88:89], v[98:99], v[86:87] op_sel:[0,0] op_sel_hi:[0,1]
	v_pk_fma_f32 v[88:89], v[98:99], v[86:87], v[88:89] op_sel:[1,1,0] op_sel_hi:[1,0,1] neg_lo:[0,1,0]
	ds_write_b64 v144, v[88:89] offset:23936
	v_pk_mul_f32 v[88:89], v[86:87], v[80:81] op_sel:[0,0] op_sel_hi:[0,1]
	v_pk_fma_f32 v[86:87], v[86:87], v[80:81], v[88:89] op_sel:[1,1,0] op_sel_hi:[1,0,1] neg_lo:[0,1,0]
	v_pk_mul_f32 v[88:89], v[84:85], v[86:87] op_sel:[0,0] op_sel_hi:[0,1]
	v_pk_fma_f32 v[84:85], v[84:85], v[86:87], v[88:89] op_sel:[1,1,0] op_sel_hi:[1,0,1] neg_lo:[0,1,0]
	ds_write_b64 v144, v[84:85] offset:26112
	v_pk_mul_f32 v[84:85], v[86:87], v[80:81] op_sel:[0,0] op_sel_hi:[0,1]
	v_pk_fma_f32 v[84:85], v[86:87], v[80:81], v[84:85] op_sel:[1,1,0] op_sel_hi:[1,0,1] neg_lo:[0,1,0]
	v_pk_mul_f32 v[86:87], v[96:97], v[84:85] op_sel:[0,0] op_sel_hi:[0,1]
	v_pk_fma_f32 v[86:87], v[96:97], v[84:85], v[86:87] op_sel:[1,1,0] op_sel_hi:[1,0,1] neg_lo:[0,1,0]
	ds_write_b64 v144, v[86:87] offset:28288
	v_pk_mul_f32 v[86:87], v[84:85], v[80:81] op_sel:[0,0] op_sel_hi:[0,1]
	v_pk_fma_f32 v[84:85], v[84:85], v[80:81], v[86:87] op_sel:[1,1,0] op_sel_hi:[1,0,1] neg_lo:[0,1,0]
	v_pk_mul_f32 v[86:87], v[82:83], v[84:85] op_sel:[0,0] op_sel_hi:[0,1]
	v_pk_fma_f32 v[82:83], v[82:83], v[84:85], v[86:87] op_sel:[1,1,0] op_sel_hi:[1,0,1] neg_lo:[0,1,0]
	ds_write_b64 v144, v[82:83] offset:30464
	v_pk_mul_f32 v[82:83], v[84:85], v[80:81] op_sel:[0,0] op_sel_hi:[0,1]
	v_pk_fma_f32 v[80:81], v[84:85], v[80:81], v[82:83] op_sel:[1,1,0] op_sel_hi:[1,0,1] neg_lo:[0,1,0]
	v_pk_mul_f32 v[82:83], v[78:79], v[80:81] op_sel:[0,0] op_sel_hi:[0,1]
	v_pk_fma_f32 v[78:79], v[78:79], v[80:81], v[82:83] op_sel:[1,1,0] op_sel_hi:[1,0,1] neg_lo:[0,1,0]
	ds_write_b64 v144, v[78:79] offset:32640
	s_waitcnt lgkmcnt(0)
	s_barrier
	ds_read2_b64 v[78:81], v146 offset1:17
	ds_read2_b64 v[82:85], v146 offset0:34 offset1:51
	ds_read2_b64 v[86:89], v146 offset0:68 offset1:85
	ds_read2_b64 v[90:93], v146 offset0:136 offset1:153
	ds_read2_b64 v[96:99], v146 offset0:102 offset1:119
	ds_read2_b64 v[100:103], v146 offset0:204 offset1:221
	ds_read2_b64 v[104:107], v146 offset0:170 offset1:187
	ds_read2_b64 v[108:111], v146 offset0:238 offset1:255
	s_waitcnt lgkmcnt(4)
	v_pk_add_f32 v[112:113], v[78:79], v[90:91]
	v_pk_add_f32 v[78:79], v[78:79], v[90:91] neg_lo:[0,1] neg_hi:[0,1]
	s_waitcnt lgkmcnt(2)
	v_pk_add_f32 v[90:91], v[86:87], v[100:101]
	v_pk_add_f32 v[86:87], v[86:87], v[100:101] neg_lo:[0,1] neg_hi:[0,1]
	v_pk_add_f32 v[100:101], v[112:113], v[90:91]
	v_pk_add_f32 v[90:91], v[112:113], v[90:91] neg_lo:[0,1] neg_hi:[0,1]
	v_pk_add_f32 v[112:113], v[78:79], v[86:87] op_sel:[0,1] op_sel_hi:[1,0] neg_hi:[0,1]
	v_pk_add_f32 v[78:79], v[78:79], v[86:87] op_sel:[0,1] op_sel_hi:[1,0] neg_lo:[0,1]
	v_pk_add_f32 v[86:87], v[80:81], v[92:93]
	v_pk_add_f32 v[80:81], v[80:81], v[92:93] neg_lo:[0,1] neg_hi:[0,1]
	v_pk_add_f32 v[92:93], v[88:89], v[102:103]
	v_pk_add_f32 v[88:89], v[88:89], v[102:103] neg_lo:[0,1] neg_hi:[0,1]
	v_pk_add_f32 v[102:103], v[86:87], v[92:93]
	v_pk_add_f32 v[86:87], v[86:87], v[92:93] neg_lo:[0,1] neg_hi:[0,1]
	v_pk_add_f32 v[92:93], v[80:81], v[88:89] op_sel:[0,1] op_sel_hi:[1,0] neg_hi:[0,1]
	v_pk_add_f32 v[80:81], v[80:81], v[88:89] op_sel:[0,1] op_sel_hi:[1,0] neg_lo:[0,1]
	s_waitcnt lgkmcnt(1)
	v_pk_add_f32 v[88:89], v[82:83], v[104:105]
	v_pk_add_f32 v[82:83], v[82:83], v[104:105] neg_lo:[0,1] neg_hi:[0,1]
	s_waitcnt lgkmcnt(0)
	v_pk_add_f32 v[104:105], v[96:97], v[108:109]
	v_pk_add_f32 v[96:97], v[96:97], v[108:109] neg_lo:[0,1] neg_hi:[0,1]
	v_pk_add_f32 v[108:109], v[88:89], v[104:105]
	v_pk_add_f32 v[88:89], v[88:89], v[104:105] neg_lo:[0,1] neg_hi:[0,1]
	v_pk_add_f32 v[104:105], v[82:83], v[96:97] op_sel:[0,1] op_sel_hi:[1,0] neg_hi:[0,1]
	v_pk_add_f32 v[82:83], v[82:83], v[96:97] op_sel:[0,1] op_sel_hi:[1,0] neg_lo:[0,1]
	v_pk_add_f32 v[96:97], v[84:85], v[106:107]
	v_pk_add_f32 v[84:85], v[84:85], v[106:107] neg_lo:[0,1] neg_hi:[0,1]
	v_pk_add_f32 v[106:107], v[98:99], v[110:111]
	v_pk_add_f32 v[98:99], v[98:99], v[110:111] neg_lo:[0,1] neg_hi:[0,1]
	v_pk_add_f32 v[110:111], v[96:97], v[106:107]
	v_pk_add_f32 v[96:97], v[96:97], v[106:107] neg_lo:[0,1] neg_hi:[0,1]
	v_pk_add_f32 v[106:107], v[84:85], v[98:99] op_sel:[0,1] op_sel_hi:[1,0] neg_hi:[0,1]
	v_pk_add_f32 v[84:85], v[84:85], v[98:99] op_sel:[0,1] op_sel_hi:[1,0] neg_lo:[0,1]
	v_pk_mul_f32 v[98:99], v[92:93], s[20:21] op_sel:[0,0] op_sel_hi:[0,1]
	v_pk_fma_f32 v[92:93], v[92:93], s[20:21], v[98:99] op_sel:[1,1,0] op_sel_hi:[1,0,1] neg_lo:[0,1,0]
	v_pk_mul_f32 v[98:99], v[104:105], s[50:51] op_sel:[0,0] op_sel_hi:[0,1]
	v_pk_fma_f32 v[98:99], v[104:105], s[50:51], v[98:99] op_sel:[1,1,0] op_sel_hi:[1,0,1] neg_lo:[0,1,0]
	v_pk_mul_f32 v[104:105], v[106:107], s[54:55] op_sel:[0,0] op_sel_hi:[0,1]
	v_pk_fma_f32 v[104:105], v[106:107], s[54:55], v[104:105] op_sel:[1,1,0] op_sel_hi:[1,0,1] neg_lo:[0,1,0]
	v_pk_mul_f32 v[106:107], v[86:87], s[50:51] op_sel:[0,0] op_sel_hi:[0,1]
	v_pk_fma_f32 v[86:87], v[86:87], s[50:51], v[106:107] op_sel:[1,1,0] op_sel_hi:[1,0,1] neg_lo:[0,1,0]
	v_pk_mul_f32 v[106:107], v[88:89], v[74:75] op_sel:[0,0] op_sel_hi:[0,1]
	v_pk_fma_f32 v[88:89], v[88:89], v[74:75], v[106:107] op_sel:[1,1,0] op_sel_hi:[1,0,1] neg_lo:[0,1,0]
	v_pk_mul_f32 v[106:107], v[96:97], v[70:71] op_sel:[0,0] op_sel_hi:[0,1]
	v_pk_fma_f32 v[96:97], v[96:97], v[70:71], v[106:107] op_sel:[1,1,0] op_sel_hi:[1,0,1] neg_lo:[0,1,0]
	v_pk_mul_f32 v[106:107], v[80:81], s[54:55] op_sel:[0,0] op_sel_hi:[0,1]
	v_pk_fma_f32 v[80:81], v[80:81], s[54:55], v[106:107] op_sel:[1,1,0] op_sel_hi:[1,0,1] neg_lo:[0,1,0]
	v_pk_mul_f32 v[106:107], v[82:83], v[70:71] op_sel:[0,0] op_sel_hi:[0,1]
	v_pk_fma_f32 v[82:83], v[82:83], v[70:71], v[106:107] op_sel:[1,1,0] op_sel_hi:[1,0,1] neg_lo:[0,1,0]
	v_pk_mul_f32 v[106:107], v[84:85], s[60:61] op_sel:[0,0] op_sel_hi:[0,1]
	v_pk_fma_f32 v[84:85], v[84:85], s[60:61], v[106:107] op_sel:[1,1,0] op_sel_hi:[1,0,1] neg_lo:[0,1,0]
	v_pk_add_f32 v[106:107], v[100:101], v[108:109]
	v_pk_add_f32 v[100:101], v[100:101], v[108:109] neg_lo:[0,1] neg_hi:[0,1]
	v_pk_add_f32 v[108:109], v[102:103], v[110:111]
	v_pk_add_f32 v[102:103], v[102:103], v[110:111] neg_lo:[0,1] neg_hi:[0,1]
	v_pk_add_f32 v[110:111], v[106:107], v[108:109]
	v_pk_add_f32 v[106:107], v[106:107], v[108:109] neg_lo:[0,1] neg_hi:[0,1]
	v_pk_add_f32 v[108:109], v[100:101], v[102:103] op_sel:[0,1] op_sel_hi:[1,0] neg_hi:[0,1]
	v_pk_add_f32 v[100:101], v[100:101], v[102:103] op_sel:[0,1] op_sel_hi:[1,0] neg_lo:[0,1]
	v_pk_add_f32 v[102:103], v[112:113], v[98:99]
	v_pk_add_f32 v[98:99], v[112:113], v[98:99] neg_lo:[0,1] neg_hi:[0,1]
	v_pk_add_f32 v[112:113], v[92:93], v[104:105]
	v_pk_add_f32 v[92:93], v[92:93], v[104:105] neg_lo:[0,1] neg_hi:[0,1]
	v_pk_add_f32 v[104:105], v[102:103], v[112:113]
	v_pk_add_f32 v[102:103], v[102:103], v[112:113] neg_lo:[0,1] neg_hi:[0,1]
	v_pk_add_f32 v[112:113], v[98:99], v[92:93] op_sel:[0,1] op_sel_hi:[1,0] neg_hi:[0,1]
	v_pk_add_f32 v[92:93], v[98:99], v[92:93] op_sel:[0,1] op_sel_hi:[1,0] neg_lo:[0,1]
	v_pk_add_f32 v[98:99], v[90:91], v[88:89]
	v_pk_add_f32 v[88:89], v[90:91], v[88:89] neg_lo:[0,1] neg_hi:[0,1]
	v_pk_add_f32 v[90:91], v[86:87], v[96:97]
	v_pk_add_f32 v[86:87], v[86:87], v[96:97] neg_lo:[0,1] neg_hi:[0,1]
	v_pk_add_f32 v[96:97], v[98:99], v[90:91]
	v_pk_add_f32 v[90:91], v[98:99], v[90:91] neg_lo:[0,1] neg_hi:[0,1]
	v_pk_add_f32 v[98:99], v[88:89], v[86:87] op_sel:[0,1] op_sel_hi:[1,0] neg_hi:[0,1]
	v_pk_add_f32 v[86:87], v[88:89], v[86:87] op_sel:[0,1] op_sel_hi:[1,0] neg_lo:[0,1]
	v_pk_add_f32 v[88:89], v[78:79], v[82:83]
	v_pk_add_f32 v[78:79], v[78:79], v[82:83] neg_lo:[0,1] neg_hi:[0,1]
	v_pk_add_f32 v[82:83], v[80:81], v[84:85]
	v_pk_add_f32 v[80:81], v[80:81], v[84:85] neg_lo:[0,1] neg_hi:[0,1]
	v_pk_add_f32 v[84:85], v[88:89], v[82:83]
	v_pk_add_f32 v[82:83], v[88:89], v[82:83] neg_lo:[0,1] neg_hi:[0,1]
	v_pk_add_f32 v[88:89], v[78:79], v[80:81] op_sel:[0,1] op_sel_hi:[1,0] neg_hi:[0,1]
	v_pk_add_f32 v[78:79], v[78:79], v[80:81] op_sel:[0,1] op_sel_hi:[1,0] neg_lo:[0,1]
	v_mov_b32_e32 v80, v40
	v_mov_b32_e32 v81, v41
	s_nop 0
	v_pk_mul_f32 v[114:115], v[104:105], v[80:81] op_sel:[0,0] op_sel_hi:[0,1]
	v_pk_fma_f32 v[104:105], v[104:105], v[80:81], v[114:115] op_sel:[1,1,0] op_sel_hi:[1,0,1] neg_lo:[0,1,0]
	ds_write2_b64 v146, v[110:111], v[104:105] offset1:17
	v_pk_mul_f32 v[104:105], v[80:81], v[80:81] op_sel:[0,0] op_sel_hi:[0,1]
	v_pk_fma_f32 v[104:105], v[80:81], v[80:81], v[104:105] op_sel:[1,1,0] op_sel_hi:[1,0,1] neg_lo:[0,1,0]
	v_pk_mul_f32 v[110:111], v[96:97], v[104:105] op_sel:[0,0] op_sel_hi:[0,1]
	v_pk_fma_f32 v[96:97], v[96:97], v[104:105], v[110:111] op_sel:[1,1,0] op_sel_hi:[1,0,1] neg_lo:[0,1,0]
	v_pk_mul_f32 v[110:111], v[104:105], v[80:81] op_sel:[0,0] op_sel_hi:[0,1]
	v_pk_fma_f32 v[104:105], v[104:105], v[80:81], v[110:111] op_sel:[1,1,0] op_sel_hi:[1,0,1] neg_lo:[0,1,0]
	v_pk_mul_f32 v[110:111], v[84:85], v[104:105] op_sel:[0,0] op_sel_hi:[0,1]
	v_pk_fma_f32 v[84:85], v[84:85], v[104:105], v[110:111] op_sel:[1,1,0] op_sel_hi:[1,0,1] neg_lo:[0,1,0]
	ds_write2_b64 v146, v[96:97], v[84:85] offset0:34 offset1:51
	v_pk_mul_f32 v[84:85], v[104:105], v[80:81] op_sel:[0,0] op_sel_hi:[0,1]
	v_pk_fma_f32 v[84:85], v[104:105], v[80:81], v[84:85] op_sel:[1,1,0] op_sel_hi:[1,0,1] neg_lo:[0,1,0]
	v_pk_mul_f32 v[96:97], v[108:109], v[84:85] op_sel:[0,0] op_sel_hi:[0,1]
	v_pk_mul_f32 v[104:105], v[84:85], v[80:81] op_sel:[0,0] op_sel_hi:[0,1]
	v_pk_fma_f32 v[96:97], v[108:109], v[84:85], v[96:97] op_sel:[1,1,0] op_sel_hi:[1,0,1] neg_lo:[0,1,0]
	v_pk_fma_f32 v[84:85], v[84:85], v[80:81], v[104:105] op_sel:[1,1,0] op_sel_hi:[1,0,1] neg_lo:[0,1,0]
	v_pk_mul_f32 v[104:105], v[112:113], v[84:85] op_sel:[0,0] op_sel_hi:[0,1]
	v_pk_fma_f32 v[104:105], v[112:113], v[84:85], v[104:105] op_sel:[1,1,0] op_sel_hi:[1,0,1] neg_lo:[0,1,0]
	ds_write2_b64 v146, v[96:97], v[104:105] offset0:68 offset1:85
	v_pk_mul_f32 v[96:97], v[84:85], v[80:81] op_sel:[0,0] op_sel_hi:[0,1]
	v_pk_fma_f32 v[84:85], v[84:85], v[80:81], v[96:97] op_sel:[1,1,0] op_sel_hi:[1,0,1] neg_lo:[0,1,0]
	v_pk_mul_f32 v[96:97], v[98:99], v[84:85] op_sel:[0,0] op_sel_hi:[0,1]
	v_pk_fma_f32 v[96:97], v[98:99], v[84:85], v[96:97] op_sel:[1,1,0] op_sel_hi:[1,0,1] neg_lo:[0,1,0]
	v_pk_mul_f32 v[98:99], v[84:85], v[80:81] op_sel:[0,0] op_sel_hi:[0,1]
	v_pk_fma_f32 v[84:85], v[84:85], v[80:81], v[98:99] op_sel:[1,1,0] op_sel_hi:[1,0,1] neg_lo:[0,1,0]
	v_pk_mul_f32 v[98:99], v[88:89], v[84:85] op_sel:[0,0] op_sel_hi:[0,1]
	v_pk_fma_f32 v[88:89], v[88:89], v[84:85], v[98:99] op_sel:[1,1,0] op_sel_hi:[1,0,1] neg_lo:[0,1,0]
	ds_write2_b64 v146, v[96:97], v[88:89] offset0:102 offset1:119
	v_pk_mul_f32 v[88:89], v[84:85], v[80:81] op_sel:[0,0] op_sel_hi:[0,1]
	v_pk_fma_f32 v[84:85], v[84:85], v[80:81], v[88:89] op_sel:[1,1,0] op_sel_hi:[1,0,1] neg_lo:[0,1,0]
	v_pk_mul_f32 v[88:89], v[106:107], v[84:85] op_sel:[0,0] op_sel_hi:[0,1]
	v_pk_mul_f32 v[96:97], v[84:85], v[80:81] op_sel:[0,0] op_sel_hi:[0,1]
	v_pk_fma_f32 v[88:89], v[106:107], v[84:85], v[88:89] op_sel:[1,1,0] op_sel_hi:[1,0,1] neg_lo:[0,1,0]
	v_pk_fma_f32 v[84:85], v[84:85], v[80:81], v[96:97] op_sel:[1,1,0] op_sel_hi:[1,0,1] neg_lo:[0,1,0]
	v_pk_mul_f32 v[96:97], v[102:103], v[84:85] op_sel:[0,0] op_sel_hi:[0,1]
	v_pk_fma_f32 v[96:97], v[102:103], v[84:85], v[96:97] op_sel:[1,1,0] op_sel_hi:[1,0,1] neg_lo:[0,1,0]
	ds_write2_b64 v146, v[88:89], v[96:97] offset0:136 offset1:153
	v_pk_mul_f32 v[88:89], v[84:85], v[80:81] op_sel:[0,0] op_sel_hi:[0,1]
	v_pk_fma_f32 v[84:85], v[84:85], v[80:81], v[88:89] op_sel:[1,1,0] op_sel_hi:[1,0,1] neg_lo:[0,1,0]
	v_pk_mul_f32 v[88:89], v[90:91], v[84:85] op_sel:[0,0] op_sel_hi:[0,1]
	v_pk_fma_f32 v[88:89], v[90:91], v[84:85], v[88:89] op_sel:[1,1,0] op_sel_hi:[1,0,1] neg_lo:[0,1,0]
	v_pk_mul_f32 v[90:91], v[84:85], v[80:81] op_sel:[0,0] op_sel_hi:[0,1]
	v_pk_fma_f32 v[84:85], v[84:85], v[80:81], v[90:91] op_sel:[1,1,0] op_sel_hi:[1,0,1] neg_lo:[0,1,0]
	v_pk_mul_f32 v[90:91], v[82:83], v[84:85] op_sel:[0,0] op_sel_hi:[0,1]
	v_pk_fma_f32 v[82:83], v[82:83], v[84:85], v[90:91] op_sel:[1,1,0] op_sel_hi:[1,0,1] neg_lo:[0,1,0]
	ds_write2_b64 v146, v[88:89], v[82:83] offset0:170 offset1:187
	v_pk_mul_f32 v[82:83], v[84:85], v[80:81] op_sel:[0,0] op_sel_hi:[0,1]
	v_pk_fma_f32 v[82:83], v[84:85], v[80:81], v[82:83] op_sel:[1,1,0] op_sel_hi:[1,0,1] neg_lo:[0,1,0]
	v_pk_mul_f32 v[84:85], v[100:101], v[82:83] op_sel:[0,0] op_sel_hi:[0,1]
	v_pk_mul_f32 v[88:89], v[82:83], v[80:81] op_sel:[0,0] op_sel_hi:[0,1]
	v_pk_fma_f32 v[84:85], v[100:101], v[82:83], v[84:85] op_sel:[1,1,0] op_sel_hi:[1,0,1] neg_lo:[0,1,0]
	v_pk_fma_f32 v[82:83], v[82:83], v[80:81], v[88:89] op_sel:[1,1,0] op_sel_hi:[1,0,1] neg_lo:[0,1,0]
	v_pk_mul_f32 v[88:89], v[92:93], v[82:83] op_sel:[0,0] op_sel_hi:[0,1]
	v_pk_fma_f32 v[88:89], v[92:93], v[82:83], v[88:89] op_sel:[1,1,0] op_sel_hi:[1,0,1] neg_lo:[0,1,0]
	ds_write2_b64 v146, v[84:85], v[88:89] offset0:204 offset1:221
	v_pk_mul_f32 v[84:85], v[82:83], v[80:81] op_sel:[0,0] op_sel_hi:[0,1]
	v_pk_fma_f32 v[82:83], v[82:83], v[80:81], v[84:85] op_sel:[1,1,0] op_sel_hi:[1,0,1] neg_lo:[0,1,0]
	v_pk_mul_f32 v[84:85], v[86:87], v[82:83] op_sel:[0,0] op_sel_hi:[0,1]
	v_pk_fma_f32 v[84:85], v[86:87], v[82:83], v[84:85] op_sel:[1,1,0] op_sel_hi:[1,0,1] neg_lo:[0,1,0]
	v_pk_mul_f32 v[86:87], v[82:83], v[80:81] op_sel:[0,0] op_sel_hi:[0,1]
	v_pk_fma_f32 v[80:81], v[82:83], v[80:81], v[86:87] op_sel:[1,1,0] op_sel_hi:[1,0,1] neg_lo:[0,1,0]
	v_pk_mul_f32 v[82:83], v[78:79], v[80:81] op_sel:[0,0] op_sel_hi:[0,1]
	v_pk_fma_f32 v[78:79], v[78:79], v[80:81], v[82:83] op_sel:[1,1,0] op_sel_hi:[1,0,1] neg_lo:[0,1,0]
	ds_write2_b64 v146, v[84:85], v[78:79] offset0:238 offset1:255
	s_waitcnt lgkmcnt(0)
	s_barrier
	ds_read2_b64 v[78:81], v147 offset1:1
	ds_read2_b64 v[82:85], v147 offset0:2 offset1:3
	ds_read2_b64 v[86:89], v147 offset0:8 offset1:9
	ds_read2_b64 v[90:93], v147 offset0:4 offset1:5
	ds_read2_b64 v[96:99], v147 offset0:6 offset1:7
	ds_read2_b64 v[100:103], v147 offset0:12 offset1:13
	ds_read2_b64 v[104:107], v147 offset0:10 offset1:11
	ds_read2_b64 v[108:111], v147 offset0:14 offset1:15
	s_waitcnt lgkmcnt(5)
	v_pk_add_f32 v[112:113], v[78:79], v[86:87]
	v_pk_add_f32 v[78:79], v[78:79], v[86:87] neg_lo:[0,1] neg_hi:[0,1]
	s_waitcnt lgkmcnt(2)
	v_pk_add_f32 v[86:87], v[90:91], v[100:101]
	v_pk_add_f32 v[90:91], v[90:91], v[100:101] neg_lo:[0,1] neg_hi:[0,1]
	v_pk_add_f32 v[100:101], v[112:113], v[86:87]
	v_pk_add_f32 v[86:87], v[112:113], v[86:87] neg_lo:[0,1] neg_hi:[0,1]
	v_pk_add_f32 v[112:113], v[78:79], v[90:91] op_sel:[0,1] op_sel_hi:[1,0] neg_hi:[0,1]
	v_pk_add_f32 v[78:79], v[78:79], v[90:91] op_sel:[0,1] op_sel_hi:[1,0] neg_lo:[0,1]
	v_pk_add_f32 v[90:91], v[80:81], v[88:89]
	v_pk_add_f32 v[80:81], v[80:81], v[88:89] neg_lo:[0,1] neg_hi:[0,1]
	v_pk_add_f32 v[88:89], v[92:93], v[102:103]
	v_pk_add_f32 v[92:93], v[92:93], v[102:103] neg_lo:[0,1] neg_hi:[0,1]
	v_pk_add_f32 v[102:103], v[90:91], v[88:89]
	v_pk_add_f32 v[88:89], v[90:91], v[88:89] neg_lo:[0,1] neg_hi:[0,1]
	v_pk_add_f32 v[90:91], v[80:81], v[92:93] op_sel:[0,1] op_sel_hi:[1,0] neg_hi:[0,1]
	v_pk_add_f32 v[80:81], v[80:81], v[92:93] op_sel:[0,1] op_sel_hi:[1,0] neg_lo:[0,1]
	s_waitcnt lgkmcnt(1)
	v_pk_add_f32 v[92:93], v[82:83], v[104:105]
	v_pk_add_f32 v[82:83], v[82:83], v[104:105] neg_lo:[0,1] neg_hi:[0,1]
	s_waitcnt lgkmcnt(0)
	v_pk_add_f32 v[104:105], v[96:97], v[108:109]
	v_pk_add_f32 v[96:97], v[96:97], v[108:109] neg_lo:[0,1] neg_hi:[0,1]
	v_pk_add_f32 v[108:109], v[92:93], v[104:105]
	v_pk_add_f32 v[92:93], v[92:93], v[104:105] neg_lo:[0,1] neg_hi:[0,1]
	v_pk_add_f32 v[104:105], v[82:83], v[96:97] op_sel:[0,1] op_sel_hi:[1,0] neg_hi:[0,1]
	v_pk_add_f32 v[82:83], v[82:83], v[96:97] op_sel:[0,1] op_sel_hi:[1,0] neg_lo:[0,1]
	v_pk_add_f32 v[96:97], v[84:85], v[106:107]
	v_pk_add_f32 v[84:85], v[84:85], v[106:107] neg_lo:[0,1] neg_hi:[0,1]
	v_pk_add_f32 v[106:107], v[98:99], v[110:111]
	v_pk_add_f32 v[98:99], v[98:99], v[110:111] neg_lo:[0,1] neg_hi:[0,1]
	v_pk_add_f32 v[110:111], v[96:97], v[106:107]
	v_pk_add_f32 v[96:97], v[96:97], v[106:107] neg_lo:[0,1] neg_hi:[0,1]
	v_pk_add_f32 v[106:107], v[84:85], v[98:99] op_sel:[0,1] op_sel_hi:[1,0] neg_hi:[0,1]
	v_pk_add_f32 v[84:85], v[84:85], v[98:99] op_sel:[0,1] op_sel_hi:[1,0] neg_lo:[0,1]
	v_pk_mul_f32 v[98:99], v[90:91], s[20:21] op_sel:[0,0] op_sel_hi:[0,1]
	v_pk_fma_f32 v[72:73], v[90:91], s[20:21], v[98:99] op_sel:[1,1,0] op_sel_hi:[1,0,1] neg_lo:[0,1,0]
	v_pk_mul_f32 v[90:91], v[104:105], s[50:51] op_sel:[0,0] op_sel_hi:[0,1]
	v_pk_mul_f32 v[98:99], v[106:107], s[54:55] op_sel:[0,0] op_sel_hi:[0,1]
	v_pk_fma_f32 v[90:91], v[104:105], s[50:51], v[90:91] op_sel:[1,1,0] op_sel_hi:[1,0,1] neg_lo:[0,1,0]
	v_pk_mul_f32 v[104:105], v[88:89], s[50:51] op_sel:[0,0] op_sel_hi:[0,1]
	v_pk_fma_f32 v[98:99], v[106:107], s[54:55], v[98:99] op_sel:[1,1,0] op_sel_hi:[1,0,1] neg_lo:[0,1,0]
	v_pk_fma_f32 v[68:69], v[88:89], s[50:51], v[104:105] op_sel:[1,1,0] op_sel_hi:[1,0,1] neg_lo:[0,1,0]
	v_pk_mul_f32 v[88:89], v[92:93], v[74:75] op_sel:[0,0] op_sel_hi:[0,1]
	v_pk_fma_f32 v[74:75], v[92:93], v[74:75], v[88:89] op_sel:[1,1,0] op_sel_hi:[1,0,1] neg_lo:[0,1,0]
	v_pk_mul_f32 v[88:89], v[96:97], v[70:71] op_sel:[0,0] op_sel_hi:[0,1]
	v_pk_mul_f32 v[92:93], v[80:81], s[54:55] op_sel:[0,0] op_sel_hi:[0,1]
	v_pk_fma_f32 v[66:67], v[80:81], s[54:55], v[92:93] op_sel:[1,1,0] op_sel_hi:[1,0,1] neg_lo:[0,1,0]
	v_pk_mul_f32 v[80:81], v[82:83], v[70:71] op_sel:[0,0] op_sel_hi:[0,1]
	v_pk_fma_f32 v[88:89], v[96:97], v[70:71], v[88:89] op_sel:[1,1,0] op_sel_hi:[1,0,1] neg_lo:[0,1,0]
	v_pk_add_f32 v[92:93], v[102:103], v[110:111] neg_lo:[0,1] neg_hi:[0,1]
	v_pk_fma_f32 v[70:71], v[82:83], v[70:71], v[80:81] op_sel:[1,1,0] op_sel_hi:[1,0,1] neg_lo:[0,1,0]
	v_pk_mul_f32 v[80:81], v[84:85], s[60:61] op_sel:[0,0] op_sel_hi:[0,1]
	v_pk_add_f32 v[82:83], v[100:101], v[108:109] neg_lo:[0,1] neg_hi:[0,1]
	v_pk_fma_f32 v[76:77], v[84:85], s[60:61], v[80:81] op_sel:[1,1,0] op_sel_hi:[1,0,1] neg_lo:[0,1,0]
	v_pk_add_f32 v[80:81], v[100:101], v[108:109]
	v_pk_add_f32 v[84:85], v[102:103], v[110:111]
	v_pk_add_f32 v[100:101], v[72:73], v[98:99]
	v_pk_add_f32 v[96:97], v[80:81], v[84:85]
	v_pk_add_f32 v[80:81], v[80:81], v[84:85] neg_lo:[0,1] neg_hi:[0,1]
	v_pk_add_f32 v[84:85], v[82:83], v[92:93] op_sel:[0,1] op_sel_hi:[1,0] neg_hi:[0,1]
	v_pk_add_f32 v[82:83], v[82:83], v[92:93] op_sel:[0,1] op_sel_hi:[1,0] neg_lo:[0,1]
	v_pk_add_f32 v[92:93], v[112:113], v[90:91]
	v_pk_add_f32 v[90:91], v[112:113], v[90:91] neg_lo:[0,1] neg_hi:[0,1]
	v_pk_add_f32 v[72:73], v[72:73], v[98:99] neg_lo:[0,1] neg_hi:[0,1]
	v_pk_add_f32 v[98:99], v[92:93], v[100:101]
	v_pk_add_f32 v[92:93], v[92:93], v[100:101] neg_lo:[0,1] neg_hi:[0,1]
	v_pk_add_f32 v[100:101], v[90:91], v[72:73] op_sel:[0,1] op_sel_hi:[1,0] neg_hi:[0,1]
	v_pk_add_f32 v[72:73], v[90:91], v[72:73] op_sel:[0,1] op_sel_hi:[1,0] neg_lo:[0,1]
	v_pk_add_f32 v[90:91], v[86:87], v[74:75]
	v_pk_add_f32 v[74:75], v[86:87], v[74:75] neg_lo:[0,1] neg_hi:[0,1]
	v_pk_add_f32 v[86:87], v[68:69], v[88:89]
	v_pk_add_f32 v[68:69], v[68:69], v[88:89] neg_lo:[0,1] neg_hi:[0,1]
	v_pk_add_f32 v[88:89], v[90:91], v[86:87]
	v_pk_add_f32 v[86:87], v[90:91], v[86:87] neg_lo:[0,1] neg_hi:[0,1]
	v_pk_add_f32 v[90:91], v[74:75], v[68:69] op_sel:[0,1] op_sel_hi:[1,0] neg_hi:[0,1]
	v_pk_add_f32 v[68:69], v[74:75], v[68:69] op_sel:[0,1] op_sel_hi:[1,0] neg_lo:[0,1]
	v_pk_add_f32 v[74:75], v[78:79], v[70:71]
	v_pk_add_f32 v[70:71], v[78:79], v[70:71] neg_lo:[0,1] neg_hi:[0,1]
	v_pk_add_f32 v[78:79], v[66:67], v[76:77]
	v_pk_add_f32 v[66:67], v[66:67], v[76:77] neg_lo:[0,1] neg_hi:[0,1]
	v_pk_add_f32 v[76:77], v[74:75], v[78:79]
	v_pk_add_f32 v[74:75], v[74:75], v[78:79] neg_lo:[0,1] neg_hi:[0,1]
	v_pk_add_f32 v[78:79], v[70:71], v[66:67] op_sel:[0,1] op_sel_hi:[1,0] neg_hi:[0,1]
	v_pk_add_f32 v[66:67], v[70:71], v[66:67] op_sel:[0,1] op_sel_hi:[1,0] neg_lo:[0,1]
	v_pk_mul_f32 v[70:71], v[96:97], v[56:57] op_sel:[0,0] op_sel_hi:[0,1]
	v_pk_fma_f32 v[56:57], v[96:97], v[56:57], v[70:71] op_sel:[1,1,0] op_sel_hi:[1,0,1] neg_lo:[0,1,0]
	v_pk_mul_f32 v[70:71], v[84:85], v[64:65] op_sel:[0,0] op_sel_hi:[0,1]
	v_pk_fma_f32 v[64:65], v[84:85], v[64:65], v[70:71] op_sel:[1,1,0] op_sel_hi:[1,0,1] neg_lo:[0,1,0]
	v_pk_mul_f32 v[70:71], v[80:81], v[60:61] op_sel:[0,0] op_sel_hi:[0,1]
	v_pk_fma_f32 v[60:61], v[80:81], v[60:61], v[70:71] op_sel:[1,1,0] op_sel_hi:[1,0,1] neg_lo:[0,1,0]
	v_pk_mul_f32 v[70:71], v[82:83], v[62:63] op_sel:[0,0] op_sel_hi:[0,1]
	v_pk_fma_f32 v[62:63], v[82:83], v[62:63], v[70:71] op_sel:[1,1,0] op_sel_hi:[1,0,1] neg_lo:[0,1,0]
	v_pk_mul_f32 v[70:71], v[98:99], v[48:49] op_sel:[0,0] op_sel_hi:[0,1]
	v_pk_fma_f32 v[48:49], v[98:99], v[48:49], v[70:71] op_sel:[1,1,0] op_sel_hi:[1,0,1] neg_lo:[0,1,0]
	v_pk_mul_f32 v[70:71], v[100:101], v[58:59] op_sel:[0,0] op_sel_hi:[0,1]
	v_pk_fma_f32 v[58:59], v[100:101], v[58:59], v[70:71] op_sel:[1,1,0] op_sel_hi:[1,0,1] neg_lo:[0,1,0]
	v_pk_mul_f32 v[70:71], v[92:93], v[52:53] op_sel:[0,0] op_sel_hi:[0,1]
	v_pk_fma_f32 v[52:53], v[92:93], v[52:53], v[70:71] op_sel:[1,1,0] op_sel_hi:[1,0,1] neg_lo:[0,1,0]
	v_pk_mul_f32 v[70:71], v[72:73], v[54:55] op_sel:[0,0] op_sel_hi:[0,1]
	v_pk_fma_f32 v[54:55], v[72:73], v[54:55], v[70:71] op_sel:[1,1,0] op_sel_hi:[1,0,1] neg_lo:[0,1,0]
	v_pk_mul_f32 v[70:71], v[88:89], v[32:33] op_sel:[0,0] op_sel_hi:[0,1]
	v_pk_fma_f32 v[32:33], v[88:89], v[32:33], v[70:71] op_sel:[1,1,0] op_sel_hi:[1,0,1] neg_lo:[0,1,0]
	v_pk_mul_f32 v[70:71], v[90:91], v[50:51] op_sel:[0,0] op_sel_hi:[0,1]
	v_pk_fma_f32 v[50:51], v[90:91], v[50:51], v[70:71] op_sel:[1,1,0] op_sel_hi:[1,0,1] neg_lo:[0,1,0]
	v_pk_mul_f32 v[70:71], v[86:87], v[44:45] op_sel:[0,0] op_sel_hi:[0,1]
	v_pk_fma_f32 v[44:45], v[86:87], v[44:45], v[70:71] op_sel:[1,1,0] op_sel_hi:[1,0,1] neg_lo:[0,1,0]
	v_pk_mul_f32 v[70:71], v[68:69], v[46:47] op_sel:[0,0] op_sel_hi:[0,1]
	v_pk_fma_f32 v[46:47], v[68:69], v[46:47], v[70:71] op_sel:[1,1,0] op_sel_hi:[1,0,1] neg_lo:[0,1,0]
	v_pk_mul_f32 v[68:69], v[76:77], v[26:27] op_sel:[0,0] op_sel_hi:[0,1]
	v_pk_fma_f32 v[26:27], v[76:77], v[26:27], v[68:69] op_sel:[1,1,0] op_sel_hi:[1,0,1] neg_lo:[0,1,0]
	v_pk_mul_f32 v[68:69], v[78:79], v[42:43] op_sel:[0,0] op_sel_hi:[0,1]
	v_pk_fma_f32 v[42:43], v[78:79], v[42:43], v[68:69] op_sel:[1,1,0] op_sel_hi:[1,0,1] neg_lo:[0,1,0]
	v_pk_mul_f32 v[68:69], v[74:75], v[28:29] op_sel:[0,0] op_sel_hi:[0,1]
	v_pk_fma_f32 v[28:29], v[74:75], v[28:29], v[68:69] op_sel:[1,1,0] op_sel_hi:[1,0,1] neg_lo:[0,1,0]
	v_pk_mul_f32 v[68:69], v[66:67], v[30:31] op_sel:[0,0] op_sel_hi:[0,1]
	v_pk_fma_f32 v[30:31], v[66:67], v[30:31], v[68:69] op_sel:[1,1,0] op_sel_hi:[1,0,1] neg_lo:[0,1,0]
	s_cbranch_scc1 .LBB0_1413
	s_mul_i32 s83, s0, 0x4400
	s_mul_hi_u32 s1, s0, 0x4400
	s_add_u32 s28, s11, s83
	s_addc_u32 s29, s10, s1
	s_add_i32 s1, s0, 0x400
	s_add_i32 s87, s83, 0x1100000
	s_mul_hi_u32 s1, s1, 0x4400
	v_lshlrev_b32_e32 v2, 3, v145
	s_add_u32 s92, s11, s87
	v_ashrrev_i32_e32 v3, 31, v2
	s_addc_u32 s93, s10, s1
	s_addk_i32 s0, 0x800
	s_add_i32 s83, s83, 0x2200000
	v_lshlrev_b64 v[18:19], 1, v[2:3]
	v_add_u32_e32 v2, 0x1000, v2
	s_mul_hi_u32 s1, s0, 0x4400
	s_add_u32 s0, s11, s83
	v_ashrrev_i32_e32 v3, 31, v2
	s_addc_u32 s1, s10, s1
	v_lshlrev_b64 v[20:21], 1, v[2:3]
	v_lshl_add_u64 v[4:5], s[28:29], 0, v[18:19]
	v_lshl_add_u64 v[6:7], s[28:29], 0, v[20:21]
	v_lshl_add_u64 v[10:11], s[92:93], 0, v[18:19]
	v_lshl_add_u64 v[14:15], s[92:93], 0, v[20:21]
	v_lshl_add_u64 v[18:19], s[0:1], 0, v[18:19]
	v_lshl_add_u64 v[22:23], s[0:1], 0, v[20:21]
	global_load_dwordx4 v[2:5], v[4:5], off
	s_nop 0
	global_load_dwordx4 v[6:9], v[6:7], off
	s_nop 0
	global_load_dwordx4 v[10:13], v[10:11], off
	s_nop 0
	global_load_dwordx4 v[14:17], v[14:15], off
	s_nop 0
	global_load_dwordx4 v[18:21], v[18:19], off
	s_nop 0
	global_load_dwordx4 v[22:25], v[22:23], off
.LBB0_1413:
	v_pk_add_f32 v[66:67], v[56:57], v[60:61]
	v_pk_add_f32 v[56:57], v[56:57], v[60:61] neg_lo:[0,1] neg_hi:[0,1]
	v_pk_add_f32 v[60:61], v[64:65], v[62:63]
	v_pk_add_f32 v[62:63], v[64:65], v[62:63] neg_lo:[0,1] neg_hi:[0,1]
	v_pk_add_f32 v[64:65], v[66:67], v[60:61]
	v_pk_add_f32 v[60:61], v[66:67], v[60:61] neg_lo:[0,1] neg_hi:[0,1]
	v_pk_add_f32 v[66:67], v[56:57], v[62:63] op_sel:[0,1] op_sel_hi:[1,0] neg_lo:[0,1]
	v_pk_add_f32 v[56:57], v[56:57], v[62:63] op_sel:[0,1] op_sel_hi:[1,0] neg_hi:[0,1]
	v_pk_add_f32 v[62:63], v[48:49], v[52:53]
	v_pk_add_f32 v[48:49], v[48:49], v[52:53] neg_lo:[0,1] neg_hi:[0,1]
	v_pk_add_f32 v[52:53], v[58:59], v[54:55]
	v_pk_add_f32 v[54:55], v[58:59], v[54:55] neg_lo:[0,1] neg_hi:[0,1]
	v_pk_add_f32 v[58:59], v[62:63], v[52:53]
	v_pk_add_f32 v[52:53], v[62:63], v[52:53] neg_lo:[0,1] neg_hi:[0,1]
	v_pk_add_f32 v[62:63], v[48:49], v[54:55] op_sel:[0,1] op_sel_hi:[1,0] neg_lo:[0,1]
	v_pk_add_f32 v[48:49], v[48:49], v[54:55] op_sel:[0,1] op_sel_hi:[1,0] neg_hi:[0,1]
	v_pk_add_f32 v[54:55], v[32:33], v[44:45]
	v_pk_add_f32 v[32:33], v[32:33], v[44:45] neg_lo:[0,1] neg_hi:[0,1]
	v_pk_add_f32 v[44:45], v[50:51], v[46:47]
	v_pk_add_f32 v[46:47], v[50:51], v[46:47] neg_lo:[0,1] neg_hi:[0,1]
	v_pk_add_f32 v[50:51], v[54:55], v[44:45]
	v_pk_add_f32 v[44:45], v[54:55], v[44:45] neg_lo:[0,1] neg_hi:[0,1]
	v_pk_add_f32 v[54:55], v[32:33], v[46:47] op_sel:[0,1] op_sel_hi:[1,0] neg_lo:[0,1]
	v_pk_add_f32 v[46:47], v[32:33], v[46:47] op_sel:[0,1] op_sel_hi:[1,0] neg_hi:[0,1]
	v_pk_add_f32 v[32:33], v[26:27], v[28:29]
	v_pk_add_f32 v[26:27], v[26:27], v[28:29] neg_lo:[0,1] neg_hi:[0,1]
	v_pk_add_f32 v[28:29], v[42:43], v[30:31]
	v_pk_add_f32 v[30:31], v[42:43], v[30:31] neg_lo:[0,1] neg_hi:[0,1]
	v_pk_add_f32 v[68:69], v[32:33], v[28:29]
	v_pk_add_f32 v[70:71], v[32:33], v[28:29] neg_lo:[0,1] neg_hi:[0,1]
	v_pk_add_f32 v[42:43], v[26:27], v[30:31] op_sel:[0,1] op_sel_hi:[1,0] neg_lo:[0,1]
	v_pk_add_f32 v[72:73], v[26:27], v[30:31] op_sel:[0,1] op_sel_hi:[1,0] neg_hi:[0,1]
	v_pk_mul_f32 v[26:27], v[62:63], s[62:63] op_sel:[0,0] op_sel_hi:[0,1]
	v_pk_fma_f32 v[62:63], v[62:63], s[62:63], v[26:27] op_sel:[1,1,0] op_sel_hi:[1,0,1] neg_lo:[0,1,0]
	v_pk_mul_f32 v[26:27], v[54:55], s[64:65] op_sel:[0,0] op_sel_hi:[0,1]
	v_pk_fma_f32 v[54:55], v[54:55], s[64:65], v[26:27] op_sel:[1,1,0] op_sel_hi:[1,0,1] neg_lo:[0,1,0]
	v_pk_mul_f32 v[30:31], v[42:43], s[66:67] op_sel:[0,0] op_sel_hi:[0,1]
	v_pk_fma_f32 v[74:75], v[42:43], s[66:67], v[30:31] op_sel:[1,1,0] op_sel_hi:[1,0,1] neg_lo:[0,1,0]
	v_pk_mul_f32 v[30:31], v[52:53], s[64:65] op_sel:[0,0] op_sel_hi:[0,1]
	v_pk_fma_f32 v[52:53], v[52:53], s[64:65], v[30:31] op_sel:[1,1,0] op_sel_hi:[1,0,1] neg_lo:[0,1,0]
	v_pk_mul_f32 v[30:31], v[44:45], s[68:69] op_sel:[0,0] op_sel_hi:[0,1]
	v_pk_fma_f32 v[76:77], v[44:45], s[68:69], v[30:31] op_sel:[1,1,0] op_sel_hi:[1,0,1] neg_lo:[0,1,0]
	v_pk_mul_f32 v[44:45], v[70:71], s[70:71] op_sel:[0,0] op_sel_hi:[0,1]
	v_pk_fma_f32 v[70:71], v[70:71], s[70:71], v[44:45] op_sel:[1,1,0] op_sel_hi:[1,0,1] neg_lo:[0,1,0]
	v_pk_mul_f32 v[44:45], v[48:49], s[66:67] op_sel:[0,0] op_sel_hi:[0,1]
	v_pk_fma_f32 v[48:49], v[48:49], s[66:67], v[44:45] op_sel:[1,1,0] op_sel_hi:[1,0,1] neg_lo:[0,1,0]
	v_pk_mul_f32 v[44:45], v[46:47], s[70:71] op_sel:[0,0] op_sel_hi:[0,1]
	v_pk_fma_f32 v[46:47], v[46:47], s[70:71], v[44:45] op_sel:[1,1,0] op_sel_hi:[1,0,1] neg_lo:[0,1,0]
	v_pk_mul_f32 v[78:79], v[72:73], s[72:73] op_sel:[0,0] op_sel_hi:[0,1]
	v_pk_fma_f32 v[72:73], v[72:73], s[72:73], v[78:79] op_sel:[1,1,0] op_sel_hi:[1,0,1] neg_lo:[0,1,0]
	v_pk_add_f32 v[78:79], v[64:65], v[50:51]
	v_pk_add_f32 v[50:51], v[64:65], v[50:51] neg_lo:[0,1] neg_hi:[0,1]
	v_pk_add_f32 v[64:65], v[58:59], v[68:69]
	v_pk_add_f32 v[58:59], v[58:59], v[68:69] neg_lo:[0,1] neg_hi:[0,1]
	v_pk_add_f32 v[68:69], v[78:79], v[64:65]
	v_pk_add_f32 v[64:65], v[78:79], v[64:65] neg_lo:[0,1] neg_hi:[0,1]
	v_pk_add_f32 v[78:79], v[50:51], v[58:59] op_sel:[0,1] op_sel_hi:[1,0] neg_lo:[0,1]
	v_pk_add_f32 v[50:51], v[50:51], v[58:59] op_sel:[0,1] op_sel_hi:[1,0] neg_hi:[0,1]
	v_pk_add_f32 v[58:59], v[66:67], v[54:55]
	v_pk_add_f32 v[54:55], v[66:67], v[54:55] neg_lo:[0,1] neg_hi:[0,1]
	v_pk_add_f32 v[66:67], v[62:63], v[74:75]
	v_pk_add_f32 v[62:63], v[62:63], v[74:75] neg_lo:[0,1] neg_hi:[0,1]
	v_pk_add_f32 v[74:75], v[58:59], v[66:67]
	v_pk_add_f32 v[58:59], v[58:59], v[66:67] neg_lo:[0,1] neg_hi:[0,1]
	v_pk_add_f32 v[66:67], v[54:55], v[62:63] op_sel:[0,1] op_sel_hi:[1,0] neg_lo:[0,1]
	v_pk_add_f32 v[54:55], v[54:55], v[62:63] op_sel:[0,1] op_sel_hi:[1,0] neg_hi:[0,1]
	v_pk_add_f32 v[62:63], v[60:61], v[76:77]
	v_pk_add_f32 v[60:61], v[60:61], v[76:77] neg_lo:[0,1] neg_hi:[0,1]
	v_pk_add_f32 v[76:77], v[52:53], v[70:71]
	v_pk_add_f32 v[52:53], v[52:53], v[70:71] neg_lo:[0,1] neg_hi:[0,1]
	v_pk_add_f32 v[70:71], v[62:63], v[76:77]
	v_pk_add_f32 v[62:63], v[62:63], v[76:77] neg_lo:[0,1] neg_hi:[0,1]
	v_pk_add_f32 v[76:77], v[60:61], v[52:53] op_sel:[0,1] op_sel_hi:[1,0] neg_lo:[0,1]
	v_pk_add_f32 v[52:53], v[60:61], v[52:53] op_sel:[0,1] op_sel_hi:[1,0] neg_hi:[0,1]
	v_pk_add_f32 v[60:61], v[56:57], v[46:47]
	v_pk_add_f32 v[46:47], v[56:57], v[46:47] neg_lo:[0,1] neg_hi:[0,1]
	v_pk_add_f32 v[56:57], v[48:49], v[72:73]
	v_pk_add_f32 v[48:49], v[48:49], v[72:73] neg_lo:[0,1] neg_hi:[0,1]
	v_pk_add_f32 v[72:73], v[60:61], v[56:57]
	v_pk_add_f32 v[56:57], v[60:61], v[56:57] neg_lo:[0,1] neg_hi:[0,1]
	v_pk_add_f32 v[60:61], v[46:47], v[48:49] op_sel:[0,1] op_sel_hi:[1,0] neg_lo:[0,1]
	v_pk_add_f32 v[46:47], v[46:47], v[48:49] op_sel:[0,1] op_sel_hi:[1,0] neg_hi:[0,1]
	ds_write2_b64 v147, v[68:69], v[74:75] offset1:1
	ds_write2_b64 v147, v[70:71], v[72:73] offset0:2 offset1:3
	ds_write2_b64 v147, v[78:79], v[66:67] offset0:4 offset1:5
	ds_write2_b64 v147, v[76:77], v[60:61] offset0:6 offset1:7
	ds_write2_b64 v147, v[64:65], v[58:59] offset0:8 offset1:9
	ds_write2_b64 v147, v[62:63], v[56:57] offset0:10 offset1:11
	ds_write2_b64 v147, v[50:51], v[54:55] offset0:12 offset1:13
	ds_write2_b64 v147, v[52:53], v[46:47] offset0:14 offset1:15
	s_waitcnt lgkmcnt(0)
	s_barrier
	ds_read2_b64 v[46:49], v146 offset1:17
	ds_read2_b64 v[50:53], v146 offset0:34 offset1:51
	s_waitcnt lgkmcnt(1)
	v_pk_mul_f32 v[54:55], v[48:49], v[40:41] op_sel:[0,0] op_sel_hi:[0,1] neg_hi:[0,1]
	v_pk_fma_f32 v[56:57], v[48:49], v[40:41], v[54:55] op_sel:[1,1,0] op_sel_hi:[1,0,1]
	v_pk_mul_f32 v[48:49], v[40:41], v[40:41] op_sel:[0,0] op_sel_hi:[0,1]
	v_pk_fma_f32 v[48:49], v[40:41], v[40:41], v[48:49] op_sel:[1,1,0] op_sel_hi:[1,0,1] neg_lo:[0,1,0]
	s_waitcnt lgkmcnt(0)
	v_pk_mul_f32 v[54:55], v[50:51], v[48:49] op_sel:[0,0] op_sel_hi:[0,1] neg_hi:[0,1]
	v_pk_fma_f32 v[58:59], v[50:51], v[48:49], v[54:55] op_sel:[1,1,0] op_sel_hi:[1,0,1]
	v_pk_mul_f32 v[50:51], v[48:49], v[40:41] op_sel:[0,0] op_sel_hi:[0,1]
	v_pk_fma_f32 v[54:55], v[48:49], v[40:41], v[50:51] op_sel:[1,1,0] op_sel_hi:[1,0,1] neg_lo:[0,1,0]
	ds_read2_b64 v[48:51], v146 offset0:68 offset1:85
	v_pk_mul_f32 v[60:61], v[52:53], v[54:55] op_sel:[0,0] op_sel_hi:[0,1] neg_hi:[0,1]
	v_pk_fma_f32 v[60:61], v[52:53], v[54:55], v[60:61] op_sel:[1,1,0] op_sel_hi:[1,0,1]
	v_pk_mul_f32 v[52:53], v[54:55], v[40:41] op_sel:[0,0] op_sel_hi:[0,1]
	v_pk_fma_f32 v[52:53], v[54:55], v[40:41], v[52:53] op_sel:[1,1,0] op_sel_hi:[1,0,1] neg_lo:[0,1,0]
	s_waitcnt lgkmcnt(0)
	v_pk_mul_f32 v[54:55], v[48:49], v[52:53] op_sel:[0,0] op_sel_hi:[0,1] neg_hi:[0,1]
	v_pk_fma_f32 v[62:63], v[48:49], v[52:53], v[54:55] op_sel:[1,1,0] op_sel_hi:[1,0,1]
	v_pk_mul_f32 v[48:49], v[52:53], v[40:41] op_sel:[0,0] op_sel_hi:[0,1]
	v_pk_fma_f32 v[48:49], v[52:53], v[40:41], v[48:49] op_sel:[1,1,0] op_sel_hi:[1,0,1] neg_lo:[0,1,0]
	ds_read2_b64 v[52:55], v146 offset0:102 offset1:119
	v_pk_mul_f32 v[64:65], v[50:51], v[48:49] op_sel:[0,0] op_sel_hi:[0,1] neg_hi:[0,1]
	v_pk_fma_f32 v[64:65], v[50:51], v[48:49], v[64:65] op_sel:[1,1,0] op_sel_hi:[1,0,1]
	v_pk_mul_f32 v[50:51], v[48:49], v[40:41] op_sel:[0,0] op_sel_hi:[0,1]
	v_pk_fma_f32 v[48:49], v[48:49], v[40:41], v[50:51] op_sel:[1,1,0] op_sel_hi:[1,0,1] neg_lo:[0,1,0]
	s_waitcnt lgkmcnt(0)
	v_pk_mul_f32 v[50:51], v[52:53], v[48:49] op_sel:[0,0] op_sel_hi:[0,1] neg_hi:[0,1]
	v_pk_fma_f32 v[66:67], v[52:53], v[48:49], v[50:51] op_sel:[1,1,0] op_sel_hi:[1,0,1]
	v_pk_mul_f32 v[50:51], v[48:49], v[40:41] op_sel:[0,0] op_sel_hi:[0,1]
	v_pk_fma_f32 v[52:53], v[48:49], v[40:41], v[50:51] op_sel:[1,1,0] op_sel_hi:[1,0,1] neg_lo:[0,1,0]
	ds_read2_b64 v[48:51], v146 offset0:136 offset1:153
	v_pk_mul_f32 v[68:69], v[54:55], v[52:53] op_sel:[0,0] op_sel_hi:[0,1] neg_hi:[0,1]
	v_pk_fma_f32 v[68:69], v[54:55], v[52:53], v[68:69] op_sel:[1,1,0] op_sel_hi:[1,0,1]
	v_pk_mul_f32 v[54:55], v[52:53], v[40:41] op_sel:[0,0] op_sel_hi:[0,1]
	v_pk_fma_f32 v[52:53], v[52:53], v[40:41], v[54:55] op_sel:[1,1,0] op_sel_hi:[1,0,1] neg_lo:[0,1,0]
	s_waitcnt lgkmcnt(0)
	v_pk_mul_f32 v[54:55], v[48:49], v[52:53] op_sel:[0,0] op_sel_hi:[0,1] neg_hi:[0,1]
	v_pk_fma_f32 v[70:71], v[48:49], v[52:53], v[54:55] op_sel:[1,1,0] op_sel_hi:[1,0,1]
	v_pk_mul_f32 v[48:49], v[52:53], v[40:41] op_sel:[0,0] op_sel_hi:[0,1]
	v_pk_fma_f32 v[48:49], v[52:53], v[40:41], v[48:49] op_sel:[1,1,0] op_sel_hi:[1,0,1] neg_lo:[0,1,0]
	ds_read2_b64 v[52:55], v146 offset0:170 offset1:187
	v_pk_mul_f32 v[72:73], v[50:51], v[48:49] op_sel:[0,0] op_sel_hi:[0,1] neg_hi:[0,1]
	v_pk_fma_f32 v[72:73], v[50:51], v[48:49], v[72:73] op_sel:[1,1,0] op_sel_hi:[1,0,1]
	v_pk_mul_f32 v[50:51], v[48:49], v[40:41] op_sel:[0,0] op_sel_hi:[0,1]
	v_pk_fma_f32 v[48:49], v[48:49], v[40:41], v[50:51] op_sel:[1,1,0] op_sel_hi:[1,0,1] neg_lo:[0,1,0]
	s_waitcnt lgkmcnt(0)
	v_pk_mul_f32 v[50:51], v[52:53], v[48:49] op_sel:[0,0] op_sel_hi:[0,1] neg_hi:[0,1]
	v_pk_fma_f32 v[74:75], v[52:53], v[48:49], v[50:51] op_sel:[1,1,0] op_sel_hi:[1,0,1]
	v_pk_mul_f32 v[50:51], v[48:49], v[40:41] op_sel:[0,0] op_sel_hi:[0,1]
	v_pk_fma_f32 v[52:53], v[48:49], v[40:41], v[50:51] op_sel:[1,1,0] op_sel_hi:[1,0,1] neg_lo:[0,1,0]
	ds_read2_b64 v[48:51], v146 offset0:204 offset1:221
	v_pk_mul_f32 v[76:77], v[54:55], v[52:53] op_sel:[0,0] op_sel_hi:[0,1] neg_hi:[0,1]
	v_pk_fma_f32 v[76:77], v[54:55], v[52:53], v[76:77] op_sel:[1,1,0] op_sel_hi:[1,0,1]
	v_pk_mul_f32 v[54:55], v[52:53], v[40:41] op_sel:[0,0] op_sel_hi:[0,1]
	v_pk_fma_f32 v[52:53], v[52:53], v[40:41], v[54:55] op_sel:[1,1,0] op_sel_hi:[1,0,1] neg_lo:[0,1,0]
	s_waitcnt lgkmcnt(0)
	v_pk_mul_f32 v[54:55], v[48:49], v[52:53] op_sel:[0,0] op_sel_hi:[0,1] neg_hi:[0,1]
	v_pk_fma_f32 v[48:49], v[48:49], v[52:53], v[54:55] op_sel:[1,1,0] op_sel_hi:[1,0,1]
	v_pk_mul_f32 v[54:55], v[52:53], v[40:41] op_sel:[0,0] op_sel_hi:[0,1]
	v_pk_fma_f32 v[78:79], v[52:53], v[40:41], v[54:55] op_sel:[1,1,0] op_sel_hi:[1,0,1] neg_lo:[0,1,0]
	ds_read2_b64 v[52:55], v146 offset0:238 offset1:255
	v_pk_mul_f32 v[80:81], v[50:51], v[78:79] op_sel:[0,0] op_sel_hi:[0,1] neg_hi:[0,1]
	v_pk_fma_f32 v[50:51], v[50:51], v[78:79], v[80:81] op_sel:[1,1,0] op_sel_hi:[1,0,1]
	v_pk_mul_f32 v[80:81], v[78:79], v[40:41] op_sel:[0,0] op_sel_hi:[0,1]
	v_pk_fma_f32 v[78:79], v[78:79], v[40:41], v[80:81] op_sel:[1,1,0] op_sel_hi:[1,0,1] neg_lo:[0,1,0]
	s_waitcnt lgkmcnt(0)
	v_pk_mul_f32 v[80:81], v[52:53], v[78:79] op_sel:[0,0] op_sel_hi:[0,1] neg_hi:[0,1]
	v_pk_fma_f32 v[52:53], v[52:53], v[78:79], v[80:81] op_sel:[1,1,0] op_sel_hi:[1,0,1]
	v_pk_mul_f32 v[80:81], v[78:79], v[40:41] op_sel:[0,0] op_sel_hi:[0,1]
	v_pk_fma_f32 v[40:41], v[78:79], v[40:41], v[80:81] op_sel:[1,1,0] op_sel_hi:[1,0,1] neg_lo:[0,1,0]
	v_pk_mul_f32 v[78:79], v[54:55], v[40:41] op_sel:[0,0] op_sel_hi:[0,1] neg_hi:[0,1]
	v_pk_fma_f32 v[40:41], v[54:55], v[40:41], v[78:79] op_sel:[1,1,0] op_sel_hi:[1,0,1]
	v_pk_add_f32 v[54:55], v[46:47], v[70:71]
	v_pk_add_f32 v[46:47], v[46:47], v[70:71] neg_lo:[0,1] neg_hi:[0,1]
	v_pk_add_f32 v[70:71], v[62:63], v[48:49]
	v_pk_add_f32 v[48:49], v[62:63], v[48:49] neg_lo:[0,1] neg_hi:[0,1]
	v_pk_add_f32 v[62:63], v[54:55], v[70:71]
	v_pk_add_f32 v[54:55], v[54:55], v[70:71] neg_lo:[0,1] neg_hi:[0,1]
	v_pk_add_f32 v[70:71], v[46:47], v[48:49] op_sel:[0,1] op_sel_hi:[1,0] neg_lo:[0,1]
	v_pk_add_f32 v[46:47], v[46:47], v[48:49] op_sel:[0,1] op_sel_hi:[1,0] neg_hi:[0,1]
	v_pk_add_f32 v[48:49], v[56:57], v[72:73]
	v_pk_add_f32 v[56:57], v[56:57], v[72:73] neg_lo:[0,1] neg_hi:[0,1]
	v_pk_add_f32 v[72:73], v[64:65], v[50:51]
	v_pk_add_f32 v[50:51], v[64:65], v[50:51] neg_lo:[0,1] neg_hi:[0,1]
	v_pk_add_f32 v[64:65], v[48:49], v[72:73]
	v_pk_add_f32 v[48:49], v[48:49], v[72:73] neg_lo:[0,1] neg_hi:[0,1]
	v_pk_add_f32 v[72:73], v[56:57], v[50:51] op_sel:[0,1] op_sel_hi:[1,0] neg_lo:[0,1]
	v_pk_add_f32 v[50:51], v[56:57], v[50:51] op_sel:[0,1] op_sel_hi:[1,0] neg_hi:[0,1]
	v_pk_add_f32 v[56:57], v[58:59], v[74:75]
	v_pk_add_f32 v[58:59], v[58:59], v[74:75] neg_lo:[0,1] neg_hi:[0,1]
	v_pk_add_f32 v[74:75], v[66:67], v[52:53]
	v_pk_add_f32 v[52:53], v[66:67], v[52:53] neg_lo:[0,1] neg_hi:[0,1]
	v_pk_add_f32 v[66:67], v[56:57], v[74:75]
	v_pk_add_f32 v[56:57], v[56:57], v[74:75] neg_lo:[0,1] neg_hi:[0,1]
	v_pk_add_f32 v[74:75], v[58:59], v[52:53] op_sel:[0,1] op_sel_hi:[1,0] neg_lo:[0,1]
	v_pk_add_f32 v[52:53], v[58:59], v[52:53] op_sel:[0,1] op_sel_hi:[1,0] neg_hi:[0,1]
	v_pk_add_f32 v[58:59], v[60:61], v[76:77]
	v_pk_add_f32 v[60:61], v[60:61], v[76:77] neg_lo:[0,1] neg_hi:[0,1]
	v_pk_add_f32 v[76:77], v[68:69], v[40:41]
	v_pk_add_f32 v[40:41], v[68:69], v[40:41] neg_lo:[0,1] neg_hi:[0,1]
	v_pk_add_f32 v[68:69], v[58:59], v[76:77]
	v_pk_add_f32 v[58:59], v[58:59], v[76:77] neg_lo:[0,1] neg_hi:[0,1]
	v_pk_add_f32 v[76:77], v[60:61], v[40:41] op_sel:[0,1] op_sel_hi:[1,0] neg_lo:[0,1]
	v_pk_add_f32 v[40:41], v[60:61], v[40:41] op_sel:[0,1] op_sel_hi:[1,0] neg_hi:[0,1]
	v_pk_mul_f32 v[60:61], v[72:73], s[62:63] op_sel:[0,0] op_sel_hi:[0,1]
	v_pk_fma_f32 v[60:61], v[72:73], s[62:63], v[60:61] op_sel:[1,1,0] op_sel_hi:[1,0,1] neg_lo:[0,1,0]
	v_pk_mul_f32 v[72:73], v[74:75], s[64:65] op_sel:[0,0] op_sel_hi:[0,1]
	v_pk_fma_f32 v[72:73], v[74:75], s[64:65], v[72:73] op_sel:[1,1,0] op_sel_hi:[1,0,1] neg_lo:[0,1,0]
	v_pk_mul_f32 v[74:75], v[76:77], s[66:67] op_sel:[0,0] op_sel_hi:[0,1]
	v_pk_fma_f32 v[74:75], v[76:77], s[66:67], v[74:75] op_sel:[1,1,0] op_sel_hi:[1,0,1] neg_lo:[0,1,0]
	v_pk_mul_f32 v[76:77], v[48:49], s[64:65] op_sel:[0,0] op_sel_hi:[0,1]
	v_pk_fma_f32 v[48:49], v[48:49], s[64:65], v[76:77] op_sel:[1,1,0] op_sel_hi:[1,0,1] neg_lo:[0,1,0]
	v_pk_mul_f32 v[76:77], v[56:57], s[68:69] op_sel:[0,0] op_sel_hi:[0,1]
	v_pk_fma_f32 v[56:57], v[56:57], s[68:69], v[76:77] op_sel:[1,1,0] op_sel_hi:[1,0,1] neg_lo:[0,1,0]
	v_pk_mul_f32 v[76:77], v[58:59], s[70:71] op_sel:[0,0] op_sel_hi:[0,1]
	v_pk_fma_f32 v[58:59], v[58:59], s[70:71], v[76:77] op_sel:[1,1,0] op_sel_hi:[1,0,1] neg_lo:[0,1,0]
	v_pk_mul_f32 v[76:77], v[50:51], s[66:67] op_sel:[0,0] op_sel_hi:[0,1]
	v_pk_fma_f32 v[50:51], v[50:51], s[66:67], v[76:77] op_sel:[1,1,0] op_sel_hi:[1,0,1] neg_lo:[0,1,0]
	v_pk_mul_f32 v[76:77], v[52:53], s[70:71] op_sel:[0,0] op_sel_hi:[0,1]
	v_pk_fma_f32 v[52:53], v[52:53], s[70:71], v[76:77] op_sel:[1,1,0] op_sel_hi:[1,0,1] neg_lo:[0,1,0]
	v_pk_mul_f32 v[76:77], v[40:41], s[72:73] op_sel:[0,0] op_sel_hi:[0,1]
	v_pk_fma_f32 v[40:41], v[40:41], s[72:73], v[76:77] op_sel:[1,1,0] op_sel_hi:[1,0,1] neg_lo:[0,1,0]
	v_pk_add_f32 v[76:77], v[62:63], v[66:67]
	v_pk_add_f32 v[62:63], v[62:63], v[66:67] neg_lo:[0,1] neg_hi:[0,1]
	v_pk_add_f32 v[66:67], v[64:65], v[68:69]
	v_pk_add_f32 v[64:65], v[64:65], v[68:69] neg_lo:[0,1] neg_hi:[0,1]
	v_pk_add_f32 v[68:69], v[76:77], v[66:67]
	v_pk_add_f32 v[66:67], v[76:77], v[66:67] neg_lo:[0,1] neg_hi:[0,1]
	v_pk_add_f32 v[76:77], v[62:63], v[64:65] op_sel:[0,1] op_sel_hi:[1,0] neg_lo:[0,1]
	v_pk_add_f32 v[62:63], v[62:63], v[64:65] op_sel:[0,1] op_sel_hi:[1,0] neg_hi:[0,1]
	v_pk_add_f32 v[64:65], v[70:71], v[72:73]
	v_pk_add_f32 v[70:71], v[70:71], v[72:73] neg_lo:[0,1] neg_hi:[0,1]
	v_pk_add_f32 v[72:73], v[60:61], v[74:75]
	v_pk_add_f32 v[60:61], v[60:61], v[74:75] neg_lo:[0,1] neg_hi:[0,1]
	v_pk_add_f32 v[74:75], v[64:65], v[72:73]
	v_pk_add_f32 v[64:65], v[64:65], v[72:73] neg_lo:[0,1] neg_hi:[0,1]
	v_pk_add_f32 v[72:73], v[70:71], v[60:61] op_sel:[0,1] op_sel_hi:[1,0] neg_lo:[0,1]
	v_pk_add_f32 v[60:61], v[70:71], v[60:61] op_sel:[0,1] op_sel_hi:[1,0] neg_hi:[0,1]
	v_pk_add_f32 v[70:71], v[54:55], v[56:57]
	v_pk_add_f32 v[54:55], v[54:55], v[56:57] neg_lo:[0,1] neg_hi:[0,1]
	v_pk_add_f32 v[56:57], v[48:49], v[58:59]
	v_pk_add_f32 v[48:49], v[48:49], v[58:59] neg_lo:[0,1] neg_hi:[0,1]
	v_pk_add_f32 v[58:59], v[70:71], v[56:57]
	v_pk_add_f32 v[56:57], v[70:71], v[56:57] neg_lo:[0,1] neg_hi:[0,1]
	v_pk_add_f32 v[70:71], v[54:55], v[48:49] op_sel:[0,1] op_sel_hi:[1,0] neg_lo:[0,1]
	v_pk_add_f32 v[48:49], v[54:55], v[48:49] op_sel:[0,1] op_sel_hi:[1,0] neg_hi:[0,1]
	v_pk_add_f32 v[54:55], v[46:47], v[52:53]
	v_pk_add_f32 v[46:47], v[46:47], v[52:53] neg_lo:[0,1] neg_hi:[0,1]
	v_pk_add_f32 v[52:53], v[50:51], v[40:41]
	v_pk_add_f32 v[40:41], v[50:51], v[40:41] neg_lo:[0,1] neg_hi:[0,1]
	v_pk_add_f32 v[50:51], v[54:55], v[52:53]
	v_pk_add_f32 v[52:53], v[54:55], v[52:53] neg_lo:[0,1] neg_hi:[0,1]
	v_pk_add_f32 v[54:55], v[46:47], v[40:41] op_sel:[0,1] op_sel_hi:[1,0] neg_lo:[0,1]
	v_pk_add_f32 v[40:41], v[46:47], v[40:41] op_sel:[0,1] op_sel_hi:[1,0] neg_hi:[0,1]
	ds_write2_b64 v146, v[68:69], v[74:75] offset1:17
	ds_write2_b64 v146, v[58:59], v[50:51] offset0:34 offset1:51
	ds_write2_b64 v146, v[76:77], v[72:73] offset0:68 offset1:85
	ds_write2_b64 v146, v[70:71], v[54:55] offset0:102 offset1:119
	ds_write2_b64 v146, v[66:67], v[64:65] offset0:136 offset1:153
	ds_write2_b64 v146, v[56:57], v[52:53] offset0:170 offset1:187
	ds_write2_b64 v146, v[62:63], v[60:61] offset0:204 offset1:221
	ds_write2_b64 v146, v[48:49], v[40:41] offset0:238 offset1:255
	s_waitcnt lgkmcnt(0)
	s_barrier
	ds_read_b64 v[40:41], v144 offset:2176
	ds_read_b64 v[46:47], v144 offset:4352
	ds_read_b64 v[48:49], v144 offset:6528
	ds_read_b64 v[50:51], v144
	s_waitcnt lgkmcnt(3)
	v_pk_mul_f32 v[52:53], v[40:41], v[38:39] op_sel:[0,0] op_sel_hi:[0,1] neg_hi:[0,1]
	v_pk_fma_f32 v[40:41], v[40:41], v[38:39], v[52:53] op_sel:[1,1,0] op_sel_hi:[1,0,1]
	v_pk_mul_f32 v[52:53], v[38:39], v[38:39] op_sel:[0,0] op_sel_hi:[0,1]
	ds_read_b64 v[56:57], v144 offset:8704
	v_pk_fma_f32 v[52:53], v[38:39], v[38:39], v[52:53] op_sel:[1,1,0] op_sel_hi:[1,0,1] neg_lo:[0,1,0]
	s_waitcnt lgkmcnt(3)
	v_pk_mul_f32 v[54:55], v[46:47], v[52:53] op_sel:[0,0] op_sel_hi:[0,1] neg_hi:[0,1]
	v_pk_fma_f32 v[46:47], v[46:47], v[52:53], v[54:55] op_sel:[1,1,0] op_sel_hi:[1,0,1]
	v_pk_mul_f32 v[54:55], v[52:53], v[38:39] op_sel:[0,0] op_sel_hi:[0,1]
	v_pk_fma_f32 v[52:53], v[52:53], v[38:39], v[54:55] op_sel:[1,1,0] op_sel_hi:[1,0,1] neg_lo:[0,1,0]
	s_waitcnt lgkmcnt(2)
	v_pk_mul_f32 v[54:55], v[48:49], v[52:53] op_sel:[0,0] op_sel_hi:[0,1] neg_hi:[0,1]
	v_pk_fma_f32 v[48:49], v[48:49], v[52:53], v[54:55] op_sel:[1,1,0] op_sel_hi:[1,0,1]
	v_pk_mul_f32 v[54:55], v[52:53], v[38:39] op_sel:[0,0] op_sel_hi:[0,1]
	v_pk_fma_f32 v[52:53], v[52:53], v[38:39], v[54:55] op_sel:[1,1,0] op_sel_hi:[1,0,1] neg_lo:[0,1,0]
	ds_read_b64 v[54:55], v144 offset:10880
	ds_read_b64 v[58:59], v144 offset:13056
	ds_read_b64 v[60:61], v144 offset:15232
	s_waitcnt lgkmcnt(3)
	v_pk_mul_f32 v[62:63], v[56:57], v[52:53] op_sel:[0,0] op_sel_hi:[0,1] neg_hi:[0,1]
	ds_read_b64 v[64:65], v144 offset:17408
	v_pk_fma_f32 v[56:57], v[56:57], v[52:53], v[62:63] op_sel:[1,1,0] op_sel_hi:[1,0,1]
	v_pk_mul_f32 v[62:63], v[52:53], v[38:39] op_sel:[0,0] op_sel_hi:[0,1]
	v_pk_fma_f32 v[52:53], v[52:53], v[38:39], v[62:63] op_sel:[1,1,0] op_sel_hi:[1,0,1] neg_lo:[0,1,0]
	s_waitcnt lgkmcnt(3)
	v_pk_mul_f32 v[62:63], v[54:55], v[52:53] op_sel:[0,0] op_sel_hi:[0,1] neg_hi:[0,1]
	v_pk_fma_f32 v[54:55], v[54:55], v[52:53], v[62:63] op_sel:[1,1,0] op_sel_hi:[1,0,1]
	v_pk_mul_f32 v[62:63], v[52:53], v[38:39] op_sel:[0,0] op_sel_hi:[0,1]
	v_pk_fma_f32 v[52:53], v[52:53], v[38:39], v[62:63] op_sel:[1,1,0] op_sel_hi:[1,0,1] neg_lo:[0,1,0]
	s_waitcnt lgkmcnt(2)
	v_pk_mul_f32 v[62:63], v[58:59], v[52:53] op_sel:[0,0] op_sel_hi:[0,1] neg_hi:[0,1]
	v_pk_fma_f32 v[58:59], v[58:59], v[52:53], v[62:63] op_sel:[1,1,0] op_sel_hi:[1,0,1]
	v_pk_mul_f32 v[62:63], v[52:53], v[38:39] op_sel:[0,0] op_sel_hi:[0,1]
	v_pk_fma_f32 v[52:53], v[52:53], v[38:39], v[62:63] op_sel:[1,1,0] op_sel_hi:[1,0,1] neg_lo:[0,1,0]
	s_waitcnt lgkmcnt(1)
	v_pk_mul_f32 v[62:63], v[60:61], v[52:53] op_sel:[0,0] op_sel_hi:[0,1] neg_hi:[0,1]
	v_pk_fma_f32 v[60:61], v[60:61], v[52:53], v[62:63] op_sel:[1,1,0] op_sel_hi:[1,0,1]
	v_pk_mul_f32 v[62:63], v[52:53], v[38:39] op_sel:[0,0] op_sel_hi:[0,1]
	v_pk_fma_f32 v[52:53], v[52:53], v[38:39], v[62:63] op_sel:[1,1,0] op_sel_hi:[1,0,1] neg_lo:[0,1,0]
	ds_read_b64 v[62:63], v144 offset:19584
	ds_read_b64 v[66:67], v144 offset:21760
	ds_read_b64 v[68:69], v144 offset:23936
	s_waitcnt lgkmcnt(3)
	v_pk_mul_f32 v[70:71], v[64:65], v[52:53] op_sel:[0,0] op_sel_hi:[0,1] neg_hi:[0,1]
	ds_read_b64 v[72:73], v144 offset:26112
	v_pk_fma_f32 v[64:65], v[64:65], v[52:53], v[70:71] op_sel:[1,1,0] op_sel_hi:[1,0,1]
	v_pk_mul_f32 v[70:71], v[52:53], v[38:39] op_sel:[0,0] op_sel_hi:[0,1]
	v_pk_fma_f32 v[52:53], v[52:53], v[38:39], v[70:71] op_sel:[1,1,0] op_sel_hi:[1,0,1] neg_lo:[0,1,0]
	s_waitcnt lgkmcnt(3)
	v_pk_mul_f32 v[70:71], v[62:63], v[52:53] op_sel:[0,0] op_sel_hi:[0,1] neg_hi:[0,1]
	v_pk_fma_f32 v[62:63], v[62:63], v[52:53], v[70:71] op_sel:[1,1,0] op_sel_hi:[1,0,1]
	v_pk_mul_f32 v[70:71], v[52:53], v[38:39] op_sel:[0,0] op_sel_hi:[0,1]
	v_pk_fma_f32 v[52:53], v[52:53], v[38:39], v[70:71] op_sel:[1,1,0] op_sel_hi:[1,0,1] neg_lo:[0,1,0]
	s_waitcnt lgkmcnt(2)
	v_pk_mul_f32 v[70:71], v[66:67], v[52:53] op_sel:[0,0] op_sel_hi:[0,1] neg_hi:[0,1]
	v_pk_fma_f32 v[66:67], v[66:67], v[52:53], v[70:71] op_sel:[1,1,0] op_sel_hi:[1,0,1]
	v_pk_mul_f32 v[70:71], v[52:53], v[38:39] op_sel:[0,0] op_sel_hi:[0,1]
	v_pk_fma_f32 v[52:53], v[52:53], v[38:39], v[70:71] op_sel:[1,1,0] op_sel_hi:[1,0,1] neg_lo:[0,1,0]
	s_waitcnt lgkmcnt(1)
	v_pk_mul_f32 v[70:71], v[68:69], v[52:53] op_sel:[0,0] op_sel_hi:[0,1] neg_hi:[0,1]
	v_pk_fma_f32 v[68:69], v[68:69], v[52:53], v[70:71] op_sel:[1,1,0] op_sel_hi:[1,0,1]
	v_pk_mul_f32 v[70:71], v[52:53], v[38:39] op_sel:[0,0] op_sel_hi:[0,1]
	v_pk_fma_f32 v[52:53], v[52:53], v[38:39], v[70:71] op_sel:[1,1,0] op_sel_hi:[1,0,1] neg_lo:[0,1,0]
	ds_read_b64 v[70:71], v144 offset:28288
	ds_read_b64 v[74:75], v144 offset:30464
	ds_read_b64 v[76:77], v144 offset:32640
	s_waitcnt lgkmcnt(3)
	v_pk_mul_f32 v[78:79], v[72:73], v[52:53] op_sel:[0,0] op_sel_hi:[0,1] neg_hi:[0,1]
	s_nop 0
	v_pk_fma_f32 v[72:73], v[72:73], v[52:53], v[78:79] op_sel:[1,1,0] op_sel_hi:[1,0,1]
	v_pk_mul_f32 v[78:79], v[52:53], v[38:39] op_sel:[0,0] op_sel_hi:[0,1]
	v_pk_fma_f32 v[52:53], v[52:53], v[38:39], v[78:79] op_sel:[1,1,0] op_sel_hi:[1,0,1] neg_lo:[0,1,0]
	s_waitcnt lgkmcnt(2)
	v_pk_mul_f32 v[78:79], v[70:71], v[52:53] op_sel:[0,0] op_sel_hi:[0,1] neg_hi:[0,1]
	v_pk_fma_f32 v[70:71], v[70:71], v[52:53], v[78:79] op_sel:[1,1,0] op_sel_hi:[1,0,1]
	v_pk_mul_f32 v[78:79], v[52:53], v[38:39] op_sel:[0,0] op_sel_hi:[0,1]
	v_pk_fma_f32 v[52:53], v[52:53], v[38:39], v[78:79] op_sel:[1,1,0] op_sel_hi:[1,0,1] neg_lo:[0,1,0]
	s_waitcnt lgkmcnt(1)
	v_pk_mul_f32 v[78:79], v[74:75], v[52:53] op_sel:[0,0] op_sel_hi:[0,1] neg_hi:[0,1]
	v_pk_fma_f32 v[74:75], v[74:75], v[52:53], v[78:79] op_sel:[1,1,0] op_sel_hi:[1,0,1]
	v_pk_mul_f32 v[78:79], v[52:53], v[38:39] op_sel:[0,0] op_sel_hi:[0,1]
	v_pk_fma_f32 v[38:39], v[52:53], v[38:39], v[78:79] op_sel:[1,1,0] op_sel_hi:[1,0,1] neg_lo:[0,1,0]
	s_waitcnt lgkmcnt(0)
	v_pk_mul_f32 v[52:53], v[76:77], v[38:39] op_sel:[0,0] op_sel_hi:[0,1] neg_hi:[0,1]
	v_pk_fma_f32 v[38:39], v[76:77], v[38:39], v[52:53] op_sel:[1,1,0] op_sel_hi:[1,0,1]
	v_pk_add_f32 v[52:53], v[50:51], v[64:65]
	v_pk_add_f32 v[50:51], v[50:51], v[64:65] neg_lo:[0,1] neg_hi:[0,1]
	v_pk_add_f32 v[64:65], v[56:57], v[72:73]
	v_pk_add_f32 v[56:57], v[56:57], v[72:73] neg_lo:[0,1] neg_hi:[0,1]
	v_pk_add_f32 v[72:73], v[52:53], v[64:65]
	v_pk_add_f32 v[76:77], v[50:51], v[56:57] op_sel:[0,1] op_sel_hi:[1,0] neg_lo:[0,1]
	v_pk_add_f32 v[78:79], v[50:51], v[56:57] op_sel:[0,1] op_sel_hi:[1,0] neg_hi:[0,1]
	v_pk_add_f32 v[50:51], v[40:41], v[62:63]
	v_pk_add_f32 v[40:41], v[40:41], v[62:63] neg_lo:[0,1] neg_hi:[0,1]
	v_pk_add_f32 v[56:57], v[54:55], v[70:71]
	v_pk_add_f32 v[54:55], v[54:55], v[70:71] neg_lo:[0,1] neg_hi:[0,1]
	v_pk_add_f32 v[52:53], v[52:53], v[64:65] neg_lo:[0,1] neg_hi:[0,1]
	v_pk_add_f32 v[62:63], v[50:51], v[56:57]
	v_pk_add_f32 v[50:51], v[50:51], v[56:57] neg_lo:[0,1] neg_hi:[0,1]
	v_pk_add_f32 v[56:57], v[40:41], v[54:55] op_sel:[0,1] op_sel_hi:[1,0] neg_lo:[0,1]
	v_pk_add_f32 v[40:41], v[40:41], v[54:55] op_sel:[0,1] op_sel_hi:[1,0] neg_hi:[0,1]
	v_pk_add_f32 v[54:55], v[46:47], v[66:67]
	v_pk_add_f32 v[46:47], v[46:47], v[66:67] neg_lo:[0,1] neg_hi:[0,1]
	v_pk_add_f32 v[64:65], v[58:59], v[74:75]
	v_pk_add_f32 v[58:59], v[58:59], v[74:75] neg_lo:[0,1] neg_hi:[0,1]
	v_pk_add_f32 v[66:67], v[54:55], v[64:65]
	v_pk_add_f32 v[54:55], v[54:55], v[64:65] neg_lo:[0,1] neg_hi:[0,1]
	v_pk_add_f32 v[64:65], v[46:47], v[58:59] op_sel:[0,1] op_sel_hi:[1,0] neg_lo:[0,1]
	v_pk_add_f32 v[46:47], v[46:47], v[58:59] op_sel:[0,1] op_sel_hi:[1,0] neg_hi:[0,1]
	v_pk_add_f32 v[58:59], v[48:49], v[68:69]
	v_pk_add_f32 v[48:49], v[48:49], v[68:69] neg_lo:[0,1] neg_hi:[0,1]
	v_pk_add_f32 v[68:69], v[60:61], v[38:39]
	v_pk_add_f32 v[38:39], v[60:61], v[38:39] neg_lo:[0,1] neg_hi:[0,1]
	v_pk_add_f32 v[60:61], v[58:59], v[68:69]
	v_pk_add_f32 v[58:59], v[58:59], v[68:69] neg_lo:[0,1] neg_hi:[0,1]
	v_pk_add_f32 v[68:69], v[48:49], v[38:39] op_sel:[0,1] op_sel_hi:[1,0] neg_lo:[0,1]
	v_pk_add_f32 v[38:39], v[48:49], v[38:39] op_sel:[0,1] op_sel_hi:[1,0] neg_hi:[0,1]
	v_pk_mul_f32 v[48:49], v[56:57], s[62:63] op_sel:[0,0] op_sel_hi:[0,1]
	v_pk_fma_f32 v[32:33], v[56:57], s[62:63], v[48:49] op_sel:[1,1,0] op_sel_hi:[1,0,1] neg_lo:[0,1,0]
	v_pk_mul_f32 v[48:49], v[64:65], s[64:65] op_sel:[0,0] op_sel_hi:[0,1]
	v_pk_mul_f32 v[56:57], v[68:69], s[66:67] op_sel:[0,0] op_sel_hi:[0,1]
	v_pk_fma_f32 v[48:49], v[64:65], s[64:65], v[48:49] op_sel:[1,1,0] op_sel_hi:[1,0,1] neg_lo:[0,1,0]
	v_pk_fma_f32 v[56:57], v[68:69], s[66:67], v[56:57] op_sel:[1,1,0] op_sel_hi:[1,0,1] neg_lo:[0,1,0]
	v_pk_mul_f32 v[64:65], v[50:51], s[64:65] op_sel:[0,0] op_sel_hi:[0,1]
	v_pk_fma_f32 v[68:69], v[50:51], s[64:65], v[64:65] op_sel:[1,1,0] op_sel_hi:[1,0,1] neg_lo:[0,1,0]
	v_pk_mul_f32 v[28:29], v[54:55], s[68:69] op_sel:[0,0] op_sel_hi:[0,1]
	v_pk_fma_f32 v[54:55], v[54:55], s[68:69], v[28:29] op_sel:[1,1,0] op_sel_hi:[1,0,1] neg_lo:[0,1,0]
	v_pk_mul_f32 v[28:29], v[58:59], s[70:71] op_sel:[0,0] op_sel_hi:[0,1]
	v_pk_add_f32 v[42:43], v[62:63], v[60:61]
	v_pk_fma_f32 v[58:59], v[58:59], s[70:71], v[28:29] op_sel:[1,1,0] op_sel_hi:[1,0,1] neg_lo:[0,1,0]
	v_pk_mul_f32 v[28:29], v[40:41], s[66:67] op_sel:[0,0] op_sel_hi:[0,1]
	v_pk_add_f32 v[50:51], v[52:53], v[54:55]
	v_pk_fma_f32 v[70:71], v[40:41], s[66:67], v[28:29] op_sel:[1,1,0] op_sel_hi:[1,0,1] neg_lo:[0,1,0]
	v_pk_mul_f32 v[26:27], v[46:47], s[70:71] op_sel:[0,0] op_sel_hi:[0,1]
	v_pk_add_f32 v[28:29], v[62:63], v[60:61] neg_lo:[0,1] neg_hi:[0,1]
	v_pk_fma_f32 v[74:75], v[46:47], s[70:71], v[26:27] op_sel:[1,1,0] op_sel_hi:[1,0,1] neg_lo:[0,1,0]
	v_pk_mul_f32 v[26:27], v[38:39], s[72:73] op_sel:[0,0] op_sel_hi:[0,1]
	v_pk_add_f32 v[30:31], v[32:33], v[56:57] neg_lo:[0,1] neg_hi:[0,1]
	v_pk_fma_f32 v[80:81], v[38:39], s[72:73], v[26:27] op_sel:[1,1,0] op_sel_hi:[1,0,1] neg_lo:[0,1,0]
	v_pk_add_f32 v[26:27], v[72:73], v[66:67] neg_lo:[0,1] neg_hi:[0,1]
	v_pk_add_f32 v[38:39], v[72:73], v[66:67]
	v_pk_add_f32 v[40:41], v[26:27], v[28:29] op_sel:[0,1] op_sel_hi:[1,0] neg_lo:[0,1]
	v_pk_add_f32 v[26:27], v[26:27], v[28:29] op_sel:[0,1] op_sel_hi:[1,0] neg_hi:[0,1]
	v_pk_add_f32 v[28:29], v[76:77], v[48:49] neg_lo:[0,1] neg_hi:[0,1]
	v_pk_add_f32 v[44:45], v[76:77], v[48:49]
	v_pk_add_f32 v[48:49], v[32:33], v[56:57]
	v_pk_add_f32 v[46:47], v[28:29], v[30:31] op_sel:[0,1] op_sel_hi:[1,0] neg_lo:[0,1]
	v_pk_add_f32 v[28:29], v[28:29], v[30:31] op_sel:[0,1] op_sel_hi:[1,0] neg_hi:[0,1]
	v_pk_add_f32 v[30:31], v[52:53], v[54:55] neg_lo:[0,1] neg_hi:[0,1]
	v_pk_add_f32 v[54:55], v[68:69], v[58:59]
	v_pk_add_f32 v[32:33], v[68:69], v[58:59] neg_lo:[0,1] neg_hi:[0,1]
	v_pk_add_f32 v[56:57], v[78:79], v[74:75]
	v_pk_add_f32 v[60:61], v[70:71], v[80:81]
	v_pk_add_f32 v[64:65], v[38:39], v[42:43]
	v_pk_add_f32 v[66:67], v[44:45], v[48:49]
	v_pk_add_f32 v[68:69], v[50:51], v[54:55]
	v_pk_add_f32 v[52:53], v[30:31], v[32:33] op_sel:[0,1] op_sel_hi:[1,0] neg_lo:[0,1]
	v_pk_add_f32 v[30:31], v[30:31], v[32:33] op_sel:[0,1] op_sel_hi:[1,0] neg_hi:[0,1]
	v_pk_add_f32 v[32:33], v[78:79], v[74:75] neg_lo:[0,1] neg_hi:[0,1]
	v_pk_add_f32 v[62:63], v[56:57], v[60:61]
	v_pk_add_f32 v[70:71], v[70:71], v[80:81] neg_lo:[0,1] neg_hi:[0,1]
	s_nop 0
	v_pk_add_f32 v[58:59], v[32:33], v[70:71] op_sel:[0,1] op_sel_hi:[1,0] neg_lo:[0,1]
	v_pk_add_f32 v[32:33], v[32:33], v[70:71] op_sel:[0,1] op_sel_hi:[1,0] neg_hi:[0,1]
	s_and_saveexec_b64 s[0:1], s[4:5]
	s_xor_b64 s[0:1], exec, s[0:1]
	s_cbranch_execz .LBB0_1415
	v_mov_b64_e32 v[70:71], s[16:17]
	v_pk_mul_f32 v[72:73], v[36:37], v[70:71] op_sel:[0,0] op_sel_hi:[0,1]
	v_pk_fma_f32 v[70:71], v[36:37], v[70:71], v[72:73] op_sel:[1,1,0] op_sel_hi:[1,0,1] neg_lo:[0,1,0]
	v_pk_mul_f32 v[72:73], v[64:65], v[70:71] op_sel:[0,0] op_sel_hi:[0,1] neg_hi:[0,1]
	v_pk_fma_f32 v[64:65], v[64:65], v[70:71], v[72:73] op_sel:[1,1,0] op_sel_hi:[1,0,1]
	v_pk_mul_f32 v[72:73], v[36:37], s[18:19] op_sel:[0,0] op_sel_hi:[0,1]
	v_pk_fma_f32 v[70:71], v[36:37], s[18:19], v[72:73] op_sel:[1,1,0] op_sel_hi:[1,0,1] neg_lo:[0,1,0]
	v_pk_mul_f32 v[72:73], v[66:67], v[70:71] op_sel:[0,0] op_sel_hi:[0,1] neg_hi:[0,1]
	v_pk_fma_f32 v[66:67], v[66:67], v[70:71], v[72:73] op_sel:[1,1,0] op_sel_hi:[1,0,1]
	v_pk_mul_f32 v[72:73], v[36:37], s[20:21] op_sel:[0,0] op_sel_hi:[0,1]
	v_pk_fma_f32 v[70:71], v[36:37], s[20:21], v[72:73] op_sel:[1,1,0] op_sel_hi:[1,0,1] neg_lo:[0,1,0]
	v_pk_mul_f32 v[72:73], v[68:69], v[70:71] op_sel:[0,0] op_sel_hi:[0,1] neg_hi:[0,1]
	v_pk_fma_f32 v[68:69], v[68:69], v[70:71], v[72:73] op_sel:[1,1,0] op_sel_hi:[1,0,1]
	v_pk_mul_f32 v[72:73], v[36:37], s[22:23] op_sel:[0,0] op_sel_hi:[0,1]
	v_pk_fma_f32 v[70:71], v[36:37], s[22:23], v[72:73] op_sel:[1,1,0] op_sel_hi:[1,0,1] neg_lo:[0,1,0]
	v_pk_mul_f32 v[72:73], v[62:63], v[70:71] op_sel:[0,0] op_sel_hi:[0,1] neg_hi:[0,1]
	v_pk_fma_f32 v[62:63], v[62:63], v[70:71], v[72:73] op_sel:[1,1,0] op_sel_hi:[1,0,1]
	ds_write_b64 v144, v[64:65]
	ds_write_b64 v144, v[66:67] offset:2176
	ds_write_b64 v144, v[68:69] offset:4352
	ds_write_b64 v144, v[62:63] offset:6528
	v_mov_b64_e32 v[62:63], s[50:51]
	v_pk_mul_f32 v[64:65], v[36:37], v[62:63] op_sel:[0,0] op_sel_hi:[0,1]
	s_nop 0
	v_pk_fma_f32 v[62:63], v[36:37], v[62:63], v[64:65] op_sel:[1,1,0] op_sel_hi:[1,0,1] neg_lo:[0,1,0]
	v_pk_mul_f32 v[64:65], v[40:41], v[62:63] op_sel:[0,0] op_sel_hi:[0,1] neg_hi:[0,1]
	v_pk_fma_f32 v[40:41], v[40:41], v[62:63], v[64:65] op_sel:[1,1,0] op_sel_hi:[1,0,1]
	v_pk_mul_f32 v[64:65], v[36:37], s[52:53] op_sel:[0,0] op_sel_hi:[0,1]
	v_pk_fma_f32 v[62:63], v[36:37], s[52:53], v[64:65] op_sel:[1,1,0] op_sel_hi:[1,0,1] neg_lo:[0,1,0]
	v_pk_mul_f32 v[64:65], v[46:47], v[62:63] op_sel:[0,0] op_sel_hi:[0,1] neg_hi:[0,1]
	v_pk_fma_f32 v[46:47], v[46:47], v[62:63], v[64:65] op_sel:[1,1,0] op_sel_hi:[1,0,1]
	v_pk_mul_f32 v[64:65], v[36:37], s[54:55] op_sel:[0,0] op_sel_hi:[0,1]
	v_pk_fma_f32 v[62:63], v[36:37], s[54:55], v[64:65] op_sel:[1,1,0] op_sel_hi:[1,0,1] neg_lo:[0,1,0]
	v_pk_mul_f32 v[64:65], v[52:53], v[62:63] op_sel:[0,0] op_sel_hi:[0,1] neg_hi:[0,1]
	v_pk_fma_f32 v[52:53], v[52:53], v[62:63], v[64:65] op_sel:[1,1,0] op_sel_hi:[1,0,1]
	v_pk_mul_f32 v[64:65], v[36:37], s[56:57] op_sel:[0,0] op_sel_hi:[0,1]
	v_pk_fma_f32 v[62:63], v[36:37], s[56:57], v[64:65] op_sel:[1,1,0] op_sel_hi:[1,0,1] neg_lo:[0,1,0]
	v_pk_mul_f32 v[64:65], v[58:59], v[62:63] op_sel:[0,0] op_sel_hi:[0,1] neg_hi:[0,1]
	s_nop 0
	v_pk_fma_f32 v[58:59], v[58:59], v[62:63], v[64:65] op_sel:[1,1,0] op_sel_hi:[1,0,1]

.LBB0_1417:
	s_or_b64 exec, exec, s[0:1]
	v_pk_add_f32 v[62:63], v[38:39], v[42:43] neg_lo:[0,1] neg_hi:[0,1]
	v_pk_add_f32 v[44:45], v[44:45], v[48:49] neg_lo:[0,1] neg_hi:[0,1]
	v_pk_add_f32 v[42:43], v[50:51], v[54:55] neg_lo:[0,1] neg_hi:[0,1]
	v_pk_add_f32 v[38:39], v[56:57], v[60:61] neg_lo:[0,1] neg_hi:[0,1]
	ds_write_b64 v144, v[40:41] offset:8704
	ds_write_b64 v144, v[46:47] offset:10880
	ds_write_b64 v144, v[52:53] offset:13056
	ds_write_b64 v144, v[58:59] offset:15232
	s_and_saveexec_b64 s[0:1], s[4:5]
	s_xor_b64 s[0:1], exec, s[0:1]
	s_cbranch_execz .LBB0_1419
	v_mov_b64_e32 v[40:41], s[14:15]
	v_pk_mul_f32 v[46:47], v[36:37], v[40:41] op_sel:[0,0] op_sel_hi:[0,1]
	s_mov_b32 s4, s19
	v_pk_fma_f32 v[40:41], v[36:37], v[40:41], v[46:47] op_sel:[1,1,0] op_sel_hi:[1,0,1] neg_lo:[0,1,0]
	s_mov_b32 s5, s57
	v_pk_mul_f32 v[46:47], v[62:63], v[40:41] op_sel:[0,0] op_sel_hi:[0,1] neg_hi:[0,1]
	v_pk_fma_f32 v[40:41], v[62:63], v[40:41], v[46:47] op_sel:[1,1,0] op_sel_hi:[1,0,1]
	v_mov_b64_e32 v[46:47], s[4:5]
	v_pk_mul_f32 v[48:49], v[36:37], v[46:47] op_sel:[0,0] op_sel_hi:[0,1]
	s_mov_b32 s4, s21
	v_pk_fma_f32 v[46:47], v[36:37], v[46:47], v[48:49] op_sel:[1,1,0] op_sel_hi:[1,0,1] neg_lo:[0,1,0]
	s_mov_b32 s5, s55
	v_pk_mul_f32 v[48:49], v[44:45], v[46:47] op_sel:[0,0] op_sel_hi:[0,1] neg_hi:[0,1]
	s_nop 0
	v_pk_fma_f32 v[44:45], v[44:45], v[46:47], v[48:49] op_sel:[1,1,0] op_sel_hi:[1,0,1]
	v_mov_b64_e32 v[46:47], s[4:5]
	v_pk_mul_f32 v[48:49], v[36:37], v[46:47] op_sel:[0,0] op_sel_hi:[0,1]
	s_mov_b32 s4, s23
	v_pk_fma_f32 v[46:47], v[36:37], v[46:47], v[48:49] op_sel:[1,1,0] op_sel_hi:[1,0,1] neg_lo:[0,1,0]
	s_mov_b32 s5, s53
	v_pk_mul_f32 v[48:49], v[42:43], v[46:47] op_sel:[0,0] op_sel_hi:[0,1] neg_hi:[0,1]
	v_pk_fma_f32 v[42:43], v[42:43], v[46:47], v[48:49] op_sel:[1,1,0] op_sel_hi:[1,0,1]
	v_mov_b64_e32 v[46:47], s[4:5]
	v_pk_mul_f32 v[48:49], v[36:37], v[46:47] op_sel:[0,0] op_sel_hi:[0,1]
	s_mov_b32 s4, s53
	v_pk_fma_f32 v[46:47], v[36:37], v[46:47], v[48:49] op_sel:[1,1,0] op_sel_hi:[1,0,1] neg_lo:[0,1,0]
	s_mov_b32 s5, s23
	v_pk_mul_f32 v[48:49], v[38:39], v[46:47] op_sel:[0,0] op_sel_hi:[0,1] neg_hi:[0,1]
	v_pk_fma_f32 v[38:39], v[38:39], v[46:47], v[48:49] op_sel:[1,1,0] op_sel_hi:[1,0,1]
	ds_write_b64 v144, v[40:41] offset:17408
	ds_write_b64 v144, v[44:45] offset:19584
	ds_write_b64 v144, v[42:43] offset:21760
	ds_write_b64 v144, v[38:39] offset:23936
	v_mov_b64_e32 v[38:39], s[58:59]
	v_pk_mul_f32 v[40:41], v[36:37], v[38:39] op_sel:[0,0] op_sel_hi:[0,1]
	s_nop 0
	v_pk_fma_f32 v[38:39], v[36:37], v[38:39], v[40:41] op_sel:[1,1,0] op_sel_hi:[1,0,1] neg_lo:[0,1,0]
	v_pk_mul_f32 v[40:41], v[26:27], v[38:39] op_sel:[0,0] op_sel_hi:[0,1] neg_hi:[0,1]
	v_pk_fma_f32 v[26:27], v[26:27], v[38:39], v[40:41] op_sel:[1,1,0] op_sel_hi:[1,0,1]
	v_mov_b64_e32 v[38:39], s[4:5]
	v_pk_mul_f32 v[40:41], v[36:37], v[38:39] op_sel:[0,0] op_sel_hi:[0,1]
	s_mov_b32 s4, s57
	v_pk_fma_f32 v[38:39], v[36:37], v[38:39], v[40:41] op_sel:[1,1,0] op_sel_hi:[1,0,1] neg_lo:[0,1,0]
	s_mov_b32 s5, s19
	v_pk_mul_f32 v[40:41], v[28:29], v[38:39] op_sel:[0,0] op_sel_hi:[0,1] neg_hi:[0,1]
	v_pk_fma_f32 v[28:29], v[28:29], v[38:39], v[40:41] op_sel:[1,1,0] op_sel_hi:[1,0,1]
	v_pk_mul_f32 v[40:41], v[36:37], s[72:73] op_sel:[0,0] op_sel_hi:[0,1]
	v_pk_fma_f32 v[38:39], v[36:37], s[72:73], v[40:41] op_sel:[1,1,0] op_sel_hi:[1,0,1] neg_lo:[0,1,0]
	v_pk_mul_f32 v[40:41], v[30:31], v[38:39] op_sel:[0,0] op_sel_hi:[0,1] neg_hi:[0,1]
	v_pk_fma_f32 v[30:31], v[30:31], v[38:39], v[40:41] op_sel:[1,1,0] op_sel_hi:[1,0,1]
	v_pk_mul_f32 v[40:41], v[36:37], s[4:5] op_sel:[0,0] op_sel_hi:[0,1]
	v_pk_fma_f32 v[36:37], v[36:37], s[4:5], v[40:41] op_sel:[1,1,0] op_sel_hi:[1,0,1] neg_lo:[0,1,0]
	v_pk_mul_f32 v[38:39], v[32:33], v[36:37] op_sel:[0,0] op_sel_hi:[0,1] neg_hi:[0,1]
	s_nop 0
	v_pk_fma_f32 v[32:33], v[32:33], v[36:37], v[38:39] op_sel:[1,1,0] op_sel_hi:[1,0,1]

.LBB0_1709:
	v_ashrrev_i32_e32 v37, 8, v18
	v_and_b32_e32 v34, 0xff, v18
	v_lshlrev_b32_e32 v19, 13, v37
	v_lshlrev_b32_e32 v20, 1, v34
	v_add3_u32 v38, s25, v19, v20
	v_add3_u32 v19, s54, v19, v20
	ds_read_u16 v20, v38
	ds_read_u16 v22, v38 offset:512
	ds_read_u16 v24, v38 offset:1024
	ds_read_u16 v26, v38 offset:1536
	ds_read_u16 v28, v38 offset:2048
	ds_read_u16 v39, v38 offset:2560
	ds_read_u16 v42, v38 offset:3072
	ds_read_u16 v44, v38 offset:3584
	ds_read_u16 v21, v19
	ds_read_u16 v23, v19 offset:512
	ds_read_u16 v25, v19 offset:1024
	ds_read_u16 v27, v19 offset:1536
	ds_read_u16 v29, v19 offset:2048
	ds_read_u16 v41, v19 offset:2560
	ds_read_u16 v43, v19 offset:3072
	ds_read_u16 v45, v19 offset:3584
	s_waitcnt lgkmcnt(7)
	v_lshlrev_b32_e32 v21, 16, v21
	v_lshlrev_b32_e32 v40, 16, v39
	s_waitcnt lgkmcnt(2)
	v_lshlrev_b32_e32 v39, 16, v41
	v_xor_b32_e32 v41, 0x80000000, v39
	s_waitcnt lgkmcnt(1)
	v_lshlrev_b32_e32 v39, 16, v43
	v_xor_b32_e32 v43, 0x80000000, v39
	s_waitcnt lgkmcnt(0)
	v_lshlrev_b32_e32 v39, 16, v45
	v_xor_b32_e32 v45, 0x80000000, v39
	ds_read_u16 v39, v38 offset:4096
	ds_read_u16 v48, v38 offset:4608
	ds_read_u16 v50, v38 offset:5120
	ds_read_u16 v52, v38 offset:5632
	ds_read_u16 v54, v38 offset:6144
	ds_read_u16 v56, v38 offset:6656
	ds_read_u16 v58, v38 offset:7168
	ds_read_u16 v38, v38 offset:7680
	s_waitcnt lgkmcnt(7)
	v_lshlrev_b32_e32 v46, 16, v39
	ds_read_u16 v39, v19 offset:4096
	ds_read_u16 v49, v19 offset:4608
	ds_read_u16 v51, v19 offset:5120
	ds_read_u16 v53, v19 offset:5632
	ds_read_u16 v55, v19 offset:6144
	ds_read_u16 v57, v19 offset:6656
	ds_read_u16 v59, v19 offset:7168
	ds_read_u16 v19, v19 offset:7680
	s_waitcnt lgkmcnt(7)
	v_lshlrev_b32_e32 v39, 16, v39
	v_xor_b32_e32 v47, 0x80000000, v39
	s_waitcnt lgkmcnt(6)
	v_lshlrev_b32_e32 v39, 16, v49
	v_xor_b32_e32 v49, 0x80000000, v39
	s_waitcnt lgkmcnt(5)
	v_lshlrev_b32_e32 v39, 16, v51
	v_xor_b32_e32 v51, 0x80000000, v39
	s_waitcnt lgkmcnt(4)
	v_lshlrev_b32_e32 v39, 16, v53
	v_lshlrev_b32_e32 v29, 16, v29
	v_xor_b32_e32 v53, 0x80000000, v39
	s_waitcnt lgkmcnt(3)
	v_lshlrev_b32_e32 v39, 16, v55
	v_lshlrev_b32_e32 v20, 16, v20
	v_xor_b32_e32 v21, 0x80000000, v21
	v_lshlrev_b32_e32 v23, 16, v23
	v_lshlrev_b32_e32 v28, 16, v28
	v_xor_b32_e32 v29, 0x80000000, v29
	v_lshlrev_b32_e32 v54, 16, v54
	v_xor_b32_e32 v55, 0x80000000, v39
	s_waitcnt lgkmcnt(2)
	v_lshlrev_b32_e32 v39, 16, v57
	s_waitcnt lgkmcnt(0)
	v_lshlrev_b32_e32 v19, 16, v19
	v_lshlrev_b32_e32 v22, 16, v22
	v_xor_b32_e32 v23, 0x80000000, v23
	v_lshlrev_b32_e32 v25, 16, v25
	v_lshlrev_b32_e32 v48, 16, v48
	v_lshlrev_b32_e32 v56, 16, v56
	v_xor_b32_e32 v57, 0x80000000, v39
	v_lshlrev_b32_e32 v39, 16, v59
	v_lshlrev_b32_e32 v60, 16, v38
	v_xor_b32_e32 v61, 0x80000000, v19
	v_bfe_u32 v38, v18, 4, 4
	v_pk_add_f32 v[18:19], v[20:21], v[46:47]
	v_pk_add_f32 v[20:21], v[20:21], v[46:47] neg_lo:[0,1] neg_hi:[0,1]
	v_pk_add_f32 v[46:47], v[28:29], v[54:55]
	v_pk_add_f32 v[28:29], v[28:29], v[54:55] neg_lo:[0,1] neg_hi:[0,1]
	v_lshlrev_b32_e32 v24, 16, v24
	v_xor_b32_e32 v25, 0x80000000, v25
	v_lshlrev_b32_e32 v27, 16, v27
	v_lshlrev_b32_e32 v42, 16, v42
	v_lshlrev_b32_e32 v50, 16, v50
	v_lshlrev_b32_e32 v58, 16, v58
	v_xor_b32_e32 v59, 0x80000000, v39
	v_pk_add_f32 v[54:55], v[18:19], v[46:47]
	v_pk_add_f32 v[46:47], v[18:19], v[46:47] neg_lo:[0,1] neg_hi:[0,1]
	v_pk_add_f32 v[62:63], v[20:21], v[28:29] op_sel:[0,1] op_sel_hi:[1,0] neg_hi:[0,1]
	v_pk_add_f32 v[64:65], v[20:21], v[28:29] op_sel:[0,1] op_sel_hi:[1,0] neg_lo:[0,1]
	v_pk_add_f32 v[18:19], v[22:23], v[48:49]
	v_pk_add_f32 v[20:21], v[22:23], v[48:49] neg_lo:[0,1] neg_hi:[0,1]
	v_pk_add_f32 v[22:23], v[40:41], v[56:57]
	v_pk_add_f32 v[28:29], v[40:41], v[56:57] neg_lo:[0,1] neg_hi:[0,1]
	v_lshlrev_b32_e32 v26, 16, v26
	v_xor_b32_e32 v27, 0x80000000, v27
	v_lshlrev_b32_e32 v44, 16, v44
	v_lshlrev_b32_e32 v52, 16, v52
	v_pk_add_f32 v[40:41], v[18:19], v[22:23]
	v_pk_add_f32 v[22:23], v[18:19], v[22:23] neg_lo:[0,1] neg_hi:[0,1]
	v_pk_add_f32 v[18:19], v[20:21], v[28:29] op_sel:[0,1] op_sel_hi:[1,0] neg_hi:[0,1]
	v_pk_add_f32 v[28:29], v[20:21], v[28:29] op_sel:[0,1] op_sel_hi:[1,0] neg_lo:[0,1]
	v_pk_add_f32 v[20:21], v[24:25], v[50:51]
	v_pk_add_f32 v[24:25], v[24:25], v[50:51] neg_lo:[0,1] neg_hi:[0,1]
	v_pk_add_f32 v[48:49], v[42:43], v[58:59]
	v_pk_add_f32 v[42:43], v[42:43], v[58:59] neg_lo:[0,1] neg_hi:[0,1]
	v_pk_add_f32 v[50:51], v[20:21], v[48:49]
	v_pk_add_f32 v[48:49], v[20:21], v[48:49] neg_lo:[0,1] neg_hi:[0,1]
	v_pk_add_f32 v[56:57], v[24:25], v[42:43] op_sel:[0,1] op_sel_hi:[1,0] neg_hi:[0,1]
	v_pk_add_f32 v[42:43], v[24:25], v[42:43] op_sel:[0,1] op_sel_hi:[1,0] neg_lo:[0,1]
	v_pk_add_f32 v[20:21], v[26:27], v[52:53]
	v_pk_add_f32 v[24:25], v[26:27], v[52:53] neg_lo:[0,1] neg_hi:[0,1]
	v_pk_add_f32 v[26:27], v[44:45], v[60:61]
	v_pk_add_f32 v[44:45], v[44:45], v[60:61] neg_lo:[0,1] neg_hi:[0,1]
	v_pk_add_f32 v[52:53], v[20:21], v[26:27]
	v_pk_add_f32 v[58:59], v[20:21], v[26:27] neg_lo:[0,1] neg_hi:[0,1]
	v_pk_add_f32 v[26:27], v[24:25], v[44:45] op_sel:[0,1] op_sel_hi:[1,0] neg_hi:[0,1]
	v_pk_add_f32 v[44:45], v[24:25], v[44:45] op_sel:[0,1] op_sel_hi:[1,0] neg_lo:[0,1]
	v_pk_mul_f32 v[20:21], v[18:19], s[38:39] op_sel:[0,0] op_sel_hi:[0,1]
	v_mad_i32_i24 v35, v37, s3, 0
	v_pk_fma_f32 v[60:61], v[18:19], s[38:39], v[20:21] op_sel:[1,1,0] op_sel_hi:[1,0,1] neg_lo:[0,1,0]
	v_pk_mul_f32 v[18:19], v[56:57], s[40:41] op_sel:[0,0] op_sel_hi:[0,1]
	v_lshlrev_b32_e32 v39, 3, v34
	v_pk_fma_f32 v[56:57], v[56:57], s[40:41], v[18:19] op_sel:[1,1,0] op_sel_hi:[1,0,1] neg_lo:[0,1,0]
	v_pk_mul_f32 v[66:67], v[26:27], s[44:45] op_sel:[0,0] op_sel_hi:[0,1]
	v_lshlrev_b32_e32 v74, 3, v38
	v_pk_fma_f32 v[66:67], v[26:27], s[44:45], v[66:67] op_sel:[1,1,0] op_sel_hi:[1,0,1] neg_lo:[0,1,0]
	v_pk_mul_f32 v[26:27], v[22:23], s[40:41] op_sel:[0,0] op_sel_hi:[0,1]
	v_add3_u32 v74, v35, v39, v74
	v_pk_fma_f32 v[68:69], v[22:23], s[40:41], v[26:27] op_sel:[1,1,0] op_sel_hi:[1,0,1] neg_lo:[0,1,0]
	v_mov_b64_e32 v[26:27], s[36:37]
	v_pk_mul_f32 v[22:23], v[48:49], v[26:27] op_sel:[0,0] op_sel_hi:[0,1]
	v_lshl_add_u32 v78, v38, 11, v35
	v_pk_fma_f32 v[48:49], v[48:49], v[26:27], v[22:23] op_sel:[1,1,0] op_sel_hi:[1,0,1] neg_lo:[0,1,0]
	v_pk_mul_f32 v[70:71], v[58:59], s[46:47] op_sel:[0,0] op_sel_hi:[0,1]
	v_add_u32_e32 v39, v78, v39
	v_pk_fma_f32 v[58:59], v[58:59], s[46:47], v[70:71] op_sel:[1,1,0] op_sel_hi:[1,0,1] neg_lo:[0,1,0]
	v_pk_mul_f32 v[70:71], v[28:29], s[44:45] op_sel:[0,0] op_sel_hi:[0,1]
	v_pk_fma_f32 v[70:71], v[28:29], s[44:45], v[70:71] op_sel:[1,1,0] op_sel_hi:[1,0,1] neg_lo:[0,1,0]
	v_pk_mul_f32 v[28:29], v[42:43], s[46:47] op_sel:[0,0] op_sel_hi:[0,1]
	v_pk_fma_f32 v[42:43], v[42:43], s[46:47], v[28:29] op_sel:[1,1,0] op_sel_hi:[1,0,1] neg_lo:[0,1,0]
	v_pk_mul_f32 v[72:73], v[44:45], s[48:49] op_sel:[0,0] op_sel_hi:[0,1]
	v_pk_fma_f32 v[44:45], v[44:45], s[48:49], v[72:73] op_sel:[1,1,0] op_sel_hi:[1,0,1] neg_lo:[0,1,0]
	v_pk_add_f32 v[72:73], v[54:55], v[50:51]
	v_pk_add_f32 v[50:51], v[54:55], v[50:51] neg_lo:[0,1] neg_hi:[0,1]
	v_pk_add_f32 v[54:55], v[40:41], v[52:53]
	v_pk_add_f32 v[40:41], v[40:41], v[52:53] neg_lo:[0,1] neg_hi:[0,1]
	v_pk_add_f32 v[52:53], v[72:73], v[54:55]
	v_pk_add_f32 v[54:55], v[72:73], v[54:55] neg_lo:[0,1] neg_hi:[0,1]
	v_pk_add_f32 v[72:73], v[50:51], v[40:41] op_sel:[0,1] op_sel_hi:[1,0] neg_hi:[0,1]
	v_pk_add_f32 v[40:41], v[50:51], v[40:41] op_sel:[0,1] op_sel_hi:[1,0] neg_lo:[0,1]
	v_pk_add_f32 v[50:51], v[62:63], v[56:57]
	v_pk_add_f32 v[56:57], v[62:63], v[56:57] neg_lo:[0,1] neg_hi:[0,1]
	v_pk_add_f32 v[62:63], v[60:61], v[66:67]
	v_pk_add_f32 v[60:61], v[60:61], v[66:67] neg_lo:[0,1] neg_hi:[0,1]
	v_pk_add_f32 v[66:67], v[50:51], v[62:63]
	v_pk_add_f32 v[50:51], v[50:51], v[62:63] neg_lo:[0,1] neg_hi:[0,1]
	v_pk_add_f32 v[62:63], v[56:57], v[60:61] op_sel:[0,1] op_sel_hi:[1,0] neg_hi:[0,1]
	v_pk_add_f32 v[56:57], v[56:57], v[60:61] op_sel:[0,1] op_sel_hi:[1,0] neg_lo:[0,1]
	v_pk_add_f32 v[60:61], v[46:47], v[48:49]
	v_pk_add_f32 v[46:47], v[46:47], v[48:49] neg_lo:[0,1] neg_hi:[0,1]
	v_pk_add_f32 v[48:49], v[68:69], v[58:59]
	v_pk_add_f32 v[58:59], v[68:69], v[58:59] neg_lo:[0,1] neg_hi:[0,1]
	v_pk_add_f32 v[68:69], v[60:61], v[48:49]
	v_pk_add_f32 v[48:49], v[60:61], v[48:49] neg_lo:[0,1] neg_hi:[0,1]
	v_pk_add_f32 v[60:61], v[46:47], v[58:59] op_sel:[0,1] op_sel_hi:[1,0] neg_hi:[0,1]
	v_pk_add_f32 v[46:47], v[46:47], v[58:59] op_sel:[0,1] op_sel_hi:[1,0] neg_lo:[0,1]
	v_pk_add_f32 v[58:59], v[64:65], v[42:43]
	v_pk_add_f32 v[42:43], v[64:65], v[42:43] neg_lo:[0,1] neg_hi:[0,1]
	v_pk_add_f32 v[64:65], v[70:71], v[44:45]
	v_pk_add_f32 v[44:45], v[70:71], v[44:45] neg_lo:[0,1] neg_hi:[0,1]
	v_pk_add_f32 v[70:71], v[58:59], v[64:65]
	v_pk_add_f32 v[58:59], v[58:59], v[64:65] neg_lo:[0,1] neg_hi:[0,1]
	v_pk_add_f32 v[64:65], v[42:43], v[44:45] op_sel:[0,1] op_sel_hi:[1,0] neg_hi:[0,1]
	v_pk_add_f32 v[42:43], v[42:43], v[44:45] op_sel:[0,1] op_sel_hi:[1,0] neg_lo:[0,1]
	v_mov_b32_e32 v44, v1
	v_mov_b32_e32 v45, v31
	ds_write_b64 v74, v[52:53]
	v_pk_mul_f32 v[52:53], v[66:67], v[44:45] op_sel:[0,0] op_sel_hi:[0,1]
	v_pk_fma_f32 v[52:53], v[66:67], v[44:45], v[52:53] op_sel:[1,1,0] op_sel_hi:[1,0,1] neg_lo:[0,1,0]
	ds_write_b64 v74, v[52:53] offset:2176
	v_pk_mul_f32 v[52:53], v[44:45], v[44:45] op_sel:[0,0] op_sel_hi:[0,1]
	v_pk_fma_f32 v[52:53], v[44:45], v[44:45], v[52:53] op_sel:[1,1,0] op_sel_hi:[1,0,1] neg_lo:[0,1,0]
	v_pk_mul_f32 v[66:67], v[68:69], v[52:53] op_sel:[0,0] op_sel_hi:[0,1]
	v_pk_fma_f32 v[66:67], v[68:69], v[52:53], v[66:67] op_sel:[1,1,0] op_sel_hi:[1,0,1] neg_lo:[0,1,0]
	ds_write_b64 v74, v[66:67] offset:4352
	v_pk_mul_f32 v[66:67], v[52:53], v[44:45] op_sel:[0,0] op_sel_hi:[0,1]
	v_pk_fma_f32 v[52:53], v[52:53], v[44:45], v[66:67] op_sel:[1,1,0] op_sel_hi:[1,0,1] neg_lo:[0,1,0]
	v_pk_mul_f32 v[66:67], v[70:71], v[52:53] op_sel:[0,0] op_sel_hi:[0,1]
	v_pk_fma_f32 v[66:67], v[70:71], v[52:53], v[66:67] op_sel:[1,1,0] op_sel_hi:[1,0,1] neg_lo:[0,1,0]
	ds_write_b64 v74, v[66:67] offset:6528
	v_pk_mul_f32 v[66:67], v[52:53], v[44:45] op_sel:[0,0] op_sel_hi:[0,1]
	v_pk_fma_f32 v[52:53], v[52:53], v[44:45], v[66:67] op_sel:[1,1,0] op_sel_hi:[1,0,1] neg_lo:[0,1,0]
	v_pk_mul_f32 v[66:67], v[72:73], v[52:53] op_sel:[0,0] op_sel_hi:[0,1]
	v_pk_fma_f32 v[66:67], v[72:73], v[52:53], v[66:67] op_sel:[1,1,0] op_sel_hi:[1,0,1] neg_lo:[0,1,0]
	ds_write_b64 v74, v[66:67] offset:8704
	v_pk_mul_f32 v[66:67], v[52:53], v[44:45] op_sel:[0,0] op_sel_hi:[0,1]
	v_pk_fma_f32 v[52:53], v[52:53], v[44:45], v[66:67] op_sel:[1,1,0] op_sel_hi:[1,0,1] neg_lo:[0,1,0]
	v_pk_mul_f32 v[66:67], v[62:63], v[52:53] op_sel:[0,0] op_sel_hi:[0,1]
	v_pk_fma_f32 v[62:63], v[62:63], v[52:53], v[66:67] op_sel:[1,1,0] op_sel_hi:[1,0,1] neg_lo:[0,1,0]
	ds_write_b64 v74, v[62:63] offset:10880
	v_pk_mul_f32 v[62:63], v[52:53], v[44:45] op_sel:[0,0] op_sel_hi:[0,1]
	v_pk_fma_f32 v[52:53], v[52:53], v[44:45], v[62:63] op_sel:[1,1,0] op_sel_hi:[1,0,1] neg_lo:[0,1,0]
	v_pk_mul_f32 v[62:63], v[60:61], v[52:53] op_sel:[0,0] op_sel_hi:[0,1]
	v_pk_fma_f32 v[60:61], v[60:61], v[52:53], v[62:63] op_sel:[1,1,0] op_sel_hi:[1,0,1] neg_lo:[0,1,0]
	ds_write_b64 v74, v[60:61] offset:13056
	v_pk_mul_f32 v[60:61], v[52:53], v[44:45] op_sel:[0,0] op_sel_hi:[0,1]
	v_pk_fma_f32 v[52:53], v[52:53], v[44:45], v[60:61] op_sel:[1,1,0] op_sel_hi:[1,0,1] neg_lo:[0,1,0]
	v_pk_mul_f32 v[60:61], v[64:65], v[52:53] op_sel:[0,0] op_sel_hi:[0,1]
	v_pk_fma_f32 v[60:61], v[64:65], v[52:53], v[60:61] op_sel:[1,1,0] op_sel_hi:[1,0,1] neg_lo:[0,1,0]
	ds_write_b64 v74, v[60:61] offset:15232
	v_pk_mul_f32 v[60:61], v[52:53], v[44:45] op_sel:[0,0] op_sel_hi:[0,1]
	v_pk_fma_f32 v[52:53], v[52:53], v[44:45], v[60:61] op_sel:[1,1,0] op_sel_hi:[1,0,1] neg_lo:[0,1,0]
	v_pk_mul_f32 v[60:61], v[54:55], v[52:53] op_sel:[0,0] op_sel_hi:[0,1]
	v_pk_fma_f32 v[54:55], v[54:55], v[52:53], v[60:61] op_sel:[1,1,0] op_sel_hi:[1,0,1] neg_lo:[0,1,0]
	ds_write_b64 v74, v[54:55] offset:17408
	v_pk_mul_f32 v[54:55], v[52:53], v[44:45] op_sel:[0,0] op_sel_hi:[0,1]
	v_pk_fma_f32 v[52:53], v[52:53], v[44:45], v[54:55] op_sel:[1,1,0] op_sel_hi:[1,0,1] neg_lo:[0,1,0]
	v_pk_mul_f32 v[54:55], v[50:51], v[52:53] op_sel:[0,0] op_sel_hi:[0,1]
	v_pk_fma_f32 v[50:51], v[50:51], v[52:53], v[54:55] op_sel:[1,1,0] op_sel_hi:[1,0,1] neg_lo:[0,1,0]
	ds_write_b64 v74, v[50:51] offset:19584
	v_pk_mul_f32 v[50:51], v[52:53], v[44:45] op_sel:[0,0] op_sel_hi:[0,1]
	v_pk_fma_f32 v[50:51], v[52:53], v[44:45], v[50:51] op_sel:[1,1,0] op_sel_hi:[1,0,1] neg_lo:[0,1,0]
	v_pk_mul_f32 v[52:53], v[48:49], v[50:51] op_sel:[0,0] op_sel_hi:[0,1]
	v_pk_fma_f32 v[48:49], v[48:49], v[50:51], v[52:53] op_sel:[1,1,0] op_sel_hi:[1,0,1] neg_lo:[0,1,0]
	ds_write_b64 v74, v[48:49] offset:21760
	v_pk_mul_f32 v[48:49], v[50:51], v[44:45] op_sel:[0,0] op_sel_hi:[0,1]
	v_pk_fma_f32 v[48:49], v[50:51], v[44:45], v[48:49] op_sel:[1,1,0] op_sel_hi:[1,0,1] neg_lo:[0,1,0]
	v_pk_mul_f32 v[50:51], v[58:59], v[48:49] op_sel:[0,0] op_sel_hi:[0,1]
	v_pk_fma_f32 v[50:51], v[58:59], v[48:49], v[50:51] op_sel:[1,1,0] op_sel_hi:[1,0,1] neg_lo:[0,1,0]
	ds_write_b64 v74, v[50:51] offset:23936
	v_pk_mul_f32 v[50:51], v[48:49], v[44:45] op_sel:[0,0] op_sel_hi:[0,1]
	v_pk_fma_f32 v[48:49], v[48:49], v[44:45], v[50:51] op_sel:[1,1,0] op_sel_hi:[1,0,1] neg_lo:[0,1,0]
	v_pk_mul_f32 v[50:51], v[40:41], v[48:49] op_sel:[0,0] op_sel_hi:[0,1]
	v_pk_fma_f32 v[40:41], v[40:41], v[48:49], v[50:51] op_sel:[1,1,0] op_sel_hi:[1,0,1] neg_lo:[0,1,0]
	ds_write_b64 v74, v[40:41] offset:26112
	v_pk_mul_f32 v[40:41], v[48:49], v[44:45] op_sel:[0,0] op_sel_hi:[0,1]
	v_pk_fma_f32 v[40:41], v[48:49], v[44:45], v[40:41] op_sel:[1,1,0] op_sel_hi:[1,0,1] neg_lo:[0,1,0]
	v_pk_mul_f32 v[48:49], v[56:57], v[40:41] op_sel:[0,0] op_sel_hi:[0,1]
	v_pk_fma_f32 v[48:49], v[56:57], v[40:41], v[48:49] op_sel:[1,1,0] op_sel_hi:[1,0,1] neg_lo:[0,1,0]
	ds_write_b64 v74, v[48:49] offset:28288
	v_pk_mul_f32 v[48:49], v[40:41], v[44:45] op_sel:[0,0] op_sel_hi:[0,1]
	v_pk_fma_f32 v[40:41], v[40:41], v[44:45], v[48:49] op_sel:[1,1,0] op_sel_hi:[1,0,1] neg_lo:[0,1,0]
	v_pk_mul_f32 v[48:49], v[46:47], v[40:41] op_sel:[0,0] op_sel_hi:[0,1]
	v_pk_fma_f32 v[46:47], v[46:47], v[40:41], v[48:49] op_sel:[1,1,0] op_sel_hi:[1,0,1] neg_lo:[0,1,0]
	ds_write_b64 v74, v[46:47] offset:30464
	v_pk_mul_f32 v[46:47], v[40:41], v[44:45] op_sel:[0,0] op_sel_hi:[0,1]
	v_pk_fma_f32 v[40:41], v[40:41], v[44:45], v[46:47] op_sel:[1,1,0] op_sel_hi:[1,0,1] neg_lo:[0,1,0]
	v_pk_mul_f32 v[44:45], v[42:43], v[40:41] op_sel:[0,0] op_sel_hi:[0,1]
	v_pk_fma_f32 v[40:41], v[42:43], v[40:41], v[44:45] op_sel:[1,1,0] op_sel_hi:[1,0,1] neg_lo:[0,1,0]
	ds_write_b64 v74, v[40:41] offset:32640
	s_waitcnt lgkmcnt(0)
	s_barrier
	ds_read2_b64 v[40:43], v39 offset1:17
	ds_read2_b64 v[44:47], v39 offset0:34 offset1:51
	ds_read2_b64 v[48:51], v39 offset0:68 offset1:85
	ds_read2_b64 v[52:55], v39 offset0:136 offset1:153
	ds_read2_b64 v[56:59], v39 offset0:102 offset1:119
	ds_read2_b64 v[60:63], v39 offset0:204 offset1:221
	ds_read2_b64 v[64:67], v39 offset0:170 offset1:187
	ds_read2_b64 v[68:71], v39 offset0:238 offset1:255
	s_waitcnt lgkmcnt(4)
	v_pk_add_f32 v[72:73], v[40:41], v[52:53]
	v_pk_add_f32 v[40:41], v[40:41], v[52:53] neg_lo:[0,1] neg_hi:[0,1]
	s_waitcnt lgkmcnt(2)
	v_pk_add_f32 v[52:53], v[48:49], v[60:61]
	v_pk_add_f32 v[48:49], v[48:49], v[60:61] neg_lo:[0,1] neg_hi:[0,1]
	v_pk_add_f32 v[60:61], v[72:73], v[52:53]
	v_pk_add_f32 v[52:53], v[72:73], v[52:53] neg_lo:[0,1] neg_hi:[0,1]
	v_pk_add_f32 v[72:73], v[40:41], v[48:49] op_sel:[0,1] op_sel_hi:[1,0] neg_hi:[0,1]
	v_pk_add_f32 v[40:41], v[40:41], v[48:49] op_sel:[0,1] op_sel_hi:[1,0] neg_lo:[0,1]
	v_pk_add_f32 v[48:49], v[42:43], v[54:55]
	v_pk_add_f32 v[42:43], v[42:43], v[54:55] neg_lo:[0,1] neg_hi:[0,1]
	v_pk_add_f32 v[54:55], v[50:51], v[62:63]
	v_pk_add_f32 v[50:51], v[50:51], v[62:63] neg_lo:[0,1] neg_hi:[0,1]
	v_pk_add_f32 v[62:63], v[48:49], v[54:55]
	v_pk_add_f32 v[48:49], v[48:49], v[54:55] neg_lo:[0,1] neg_hi:[0,1]
	v_pk_add_f32 v[54:55], v[42:43], v[50:51] op_sel:[0,1] op_sel_hi:[1,0] neg_hi:[0,1]
	v_pk_add_f32 v[42:43], v[42:43], v[50:51] op_sel:[0,1] op_sel_hi:[1,0] neg_lo:[0,1]
	s_waitcnt lgkmcnt(1)
	v_pk_add_f32 v[50:51], v[44:45], v[64:65]
	v_pk_add_f32 v[44:45], v[44:45], v[64:65] neg_lo:[0,1] neg_hi:[0,1]
	s_waitcnt lgkmcnt(0)
	v_pk_add_f32 v[64:65], v[56:57], v[68:69]
	v_pk_add_f32 v[56:57], v[56:57], v[68:69] neg_lo:[0,1] neg_hi:[0,1]
	v_pk_add_f32 v[68:69], v[50:51], v[64:65]
	v_pk_add_f32 v[50:51], v[50:51], v[64:65] neg_lo:[0,1] neg_hi:[0,1]
	v_pk_add_f32 v[64:65], v[44:45], v[56:57] op_sel:[0,1] op_sel_hi:[1,0] neg_hi:[0,1]
	v_pk_add_f32 v[44:45], v[44:45], v[56:57] op_sel:[0,1] op_sel_hi:[1,0] neg_lo:[0,1]
	v_pk_add_f32 v[56:57], v[46:47], v[66:67]
	v_pk_add_f32 v[46:47], v[46:47], v[66:67] neg_lo:[0,1] neg_hi:[0,1]
	v_pk_add_f32 v[66:67], v[58:59], v[70:71]
	v_pk_add_f32 v[58:59], v[58:59], v[70:71] neg_lo:[0,1] neg_hi:[0,1]
	v_pk_add_f32 v[70:71], v[56:57], v[66:67]
	v_pk_add_f32 v[56:57], v[56:57], v[66:67] neg_lo:[0,1] neg_hi:[0,1]
	v_pk_add_f32 v[66:67], v[46:47], v[58:59] op_sel:[0,1] op_sel_hi:[1,0] neg_hi:[0,1]
	v_pk_add_f32 v[46:47], v[46:47], v[58:59] op_sel:[0,1] op_sel_hi:[1,0] neg_lo:[0,1]
	v_pk_mul_f32 v[58:59], v[54:55], s[38:39] op_sel:[0,0] op_sel_hi:[0,1]
	v_pk_fma_f32 v[54:55], v[54:55], s[38:39], v[58:59] op_sel:[1,1,0] op_sel_hi:[1,0,1] neg_lo:[0,1,0]
	v_pk_mul_f32 v[58:59], v[64:65], s[40:41] op_sel:[0,0] op_sel_hi:[0,1]
	v_pk_fma_f32 v[58:59], v[64:65], s[40:41], v[58:59] op_sel:[1,1,0] op_sel_hi:[1,0,1] neg_lo:[0,1,0]
	v_pk_mul_f32 v[64:65], v[66:67], s[44:45] op_sel:[0,0] op_sel_hi:[0,1]
	v_pk_fma_f32 v[64:65], v[66:67], s[44:45], v[64:65] op_sel:[1,1,0] op_sel_hi:[1,0,1] neg_lo:[0,1,0]
	v_pk_mul_f32 v[66:67], v[48:49], s[40:41] op_sel:[0,0] op_sel_hi:[0,1]
	v_pk_fma_f32 v[48:49], v[48:49], s[40:41], v[66:67] op_sel:[1,1,0] op_sel_hi:[1,0,1] neg_lo:[0,1,0]
	v_pk_mul_f32 v[66:67], v[50:51], v[26:27] op_sel:[0,0] op_sel_hi:[0,1]
	v_pk_fma_f32 v[50:51], v[50:51], v[26:27], v[66:67] op_sel:[1,1,0] op_sel_hi:[1,0,1] neg_lo:[0,1,0]
	v_pk_mul_f32 v[66:67], v[56:57], s[46:47] op_sel:[0,0] op_sel_hi:[0,1]
	v_pk_fma_f32 v[56:57], v[56:57], s[46:47], v[66:67] op_sel:[1,1,0] op_sel_hi:[1,0,1] neg_lo:[0,1,0]
	v_pk_mul_f32 v[66:67], v[42:43], s[44:45] op_sel:[0,0] op_sel_hi:[0,1]
	v_pk_fma_f32 v[42:43], v[42:43], s[44:45], v[66:67] op_sel:[1,1,0] op_sel_hi:[1,0,1] neg_lo:[0,1,0]
	v_pk_mul_f32 v[66:67], v[44:45], s[46:47] op_sel:[0,0] op_sel_hi:[0,1]
	v_pk_fma_f32 v[44:45], v[44:45], s[46:47], v[66:67] op_sel:[1,1,0] op_sel_hi:[1,0,1] neg_lo:[0,1,0]
	v_pk_mul_f32 v[66:67], v[46:47], s[48:49] op_sel:[0,0] op_sel_hi:[0,1]
	v_pk_fma_f32 v[46:47], v[46:47], s[48:49], v[66:67] op_sel:[1,1,0] op_sel_hi:[1,0,1] neg_lo:[0,1,0]
	v_pk_add_f32 v[66:67], v[60:61], v[68:69]
	v_pk_add_f32 v[60:61], v[60:61], v[68:69] neg_lo:[0,1] neg_hi:[0,1]
	v_pk_add_f32 v[68:69], v[62:63], v[70:71]
	v_pk_add_f32 v[62:63], v[62:63], v[70:71] neg_lo:[0,1] neg_hi:[0,1]
	v_pk_add_f32 v[70:71], v[66:67], v[68:69]
	v_pk_add_f32 v[66:67], v[66:67], v[68:69] neg_lo:[0,1] neg_hi:[0,1]
	v_pk_add_f32 v[68:69], v[60:61], v[62:63] op_sel:[0,1] op_sel_hi:[1,0] neg_hi:[0,1]
	v_pk_add_f32 v[60:61], v[60:61], v[62:63] op_sel:[0,1] op_sel_hi:[1,0] neg_lo:[0,1]
	v_pk_add_f32 v[62:63], v[72:73], v[58:59]
	v_pk_add_f32 v[58:59], v[72:73], v[58:59] neg_lo:[0,1] neg_hi:[0,1]
	v_pk_add_f32 v[72:73], v[54:55], v[64:65]
	v_pk_add_f32 v[54:55], v[54:55], v[64:65] neg_lo:[0,1] neg_hi:[0,1]
	v_pk_add_f32 v[64:65], v[62:63], v[72:73]
	v_pk_add_f32 v[62:63], v[62:63], v[72:73] neg_lo:[0,1] neg_hi:[0,1]
	v_pk_add_f32 v[72:73], v[58:59], v[54:55] op_sel:[0,1] op_sel_hi:[1,0] neg_hi:[0,1]
	v_pk_add_f32 v[54:55], v[58:59], v[54:55] op_sel:[0,1] op_sel_hi:[1,0] neg_lo:[0,1]
	v_pk_add_f32 v[58:59], v[52:53], v[50:51]
	v_pk_add_f32 v[50:51], v[52:53], v[50:51] neg_lo:[0,1] neg_hi:[0,1]
	v_pk_add_f32 v[52:53], v[48:49], v[56:57]
	v_pk_add_f32 v[48:49], v[48:49], v[56:57] neg_lo:[0,1] neg_hi:[0,1]
	v_pk_add_f32 v[56:57], v[58:59], v[52:53]
	v_pk_add_f32 v[52:53], v[58:59], v[52:53] neg_lo:[0,1] neg_hi:[0,1]
	v_pk_add_f32 v[58:59], v[50:51], v[48:49] op_sel:[0,1] op_sel_hi:[1,0] neg_hi:[0,1]
	v_pk_add_f32 v[48:49], v[50:51], v[48:49] op_sel:[0,1] op_sel_hi:[1,0] neg_lo:[0,1]
	v_pk_add_f32 v[50:51], v[40:41], v[44:45]
	v_pk_add_f32 v[40:41], v[40:41], v[44:45] neg_lo:[0,1] neg_hi:[0,1]
	v_pk_add_f32 v[44:45], v[42:43], v[46:47]
	v_pk_add_f32 v[42:43], v[42:43], v[46:47] neg_lo:[0,1] neg_hi:[0,1]
	v_pk_add_f32 v[46:47], v[50:51], v[44:45]
	v_pk_add_f32 v[44:45], v[50:51], v[44:45] neg_lo:[0,1] neg_hi:[0,1]
	v_pk_add_f32 v[50:51], v[40:41], v[42:43] op_sel:[0,1] op_sel_hi:[1,0] neg_hi:[0,1]
	v_pk_add_f32 v[40:41], v[40:41], v[42:43] op_sel:[0,1] op_sel_hi:[1,0] neg_lo:[0,1]
	v_mov_b32_e32 v42, v30
	v_mov_b32_e32 v43, v32
	s_nop 0
	v_pk_mul_f32 v[74:75], v[64:65], v[42:43] op_sel:[0,0] op_sel_hi:[0,1]
	v_pk_fma_f32 v[64:65], v[64:65], v[42:43], v[74:75] op_sel:[1,1,0] op_sel_hi:[1,0,1] neg_lo:[0,1,0]
	ds_write2_b64 v39, v[70:71], v[64:65] offset1:17
	v_pk_mul_f32 v[64:65], v[42:43], v[42:43] op_sel:[0,0] op_sel_hi:[0,1]
	v_pk_fma_f32 v[64:65], v[42:43], v[42:43], v[64:65] op_sel:[1,1,0] op_sel_hi:[1,0,1] neg_lo:[0,1,0]
	v_pk_mul_f32 v[70:71], v[56:57], v[64:65] op_sel:[0,0] op_sel_hi:[0,1]
	v_pk_fma_f32 v[56:57], v[56:57], v[64:65], v[70:71] op_sel:[1,1,0] op_sel_hi:[1,0,1] neg_lo:[0,1,0]
	v_pk_mul_f32 v[70:71], v[64:65], v[42:43] op_sel:[0,0] op_sel_hi:[0,1]
	v_pk_fma_f32 v[64:65], v[64:65], v[42:43], v[70:71] op_sel:[1,1,0] op_sel_hi:[1,0,1] neg_lo:[0,1,0]
	v_pk_mul_f32 v[70:71], v[46:47], v[64:65] op_sel:[0,0] op_sel_hi:[0,1]
	v_pk_fma_f32 v[46:47], v[46:47], v[64:65], v[70:71] op_sel:[1,1,0] op_sel_hi:[1,0,1] neg_lo:[0,1,0]
	ds_write2_b64 v39, v[56:57], v[46:47] offset0:34 offset1:51
	v_pk_mul_f32 v[46:47], v[64:65], v[42:43] op_sel:[0,0] op_sel_hi:[0,1]
	v_pk_fma_f32 v[46:47], v[64:65], v[42:43], v[46:47] op_sel:[1,1,0] op_sel_hi:[1,0,1] neg_lo:[0,1,0]
	v_pk_mul_f32 v[56:57], v[68:69], v[46:47] op_sel:[0,0] op_sel_hi:[0,1]
	v_pk_mul_f32 v[64:65], v[46:47], v[42:43] op_sel:[0,0] op_sel_hi:[0,1]
	v_pk_fma_f32 v[56:57], v[68:69], v[46:47], v[56:57] op_sel:[1,1,0] op_sel_hi:[1,0,1] neg_lo:[0,1,0]
	v_pk_fma_f32 v[46:47], v[46:47], v[42:43], v[64:65] op_sel:[1,1,0] op_sel_hi:[1,0,1] neg_lo:[0,1,0]
	v_pk_mul_f32 v[64:65], v[72:73], v[46:47] op_sel:[0,0] op_sel_hi:[0,1]
	v_pk_fma_f32 v[64:65], v[72:73], v[46:47], v[64:65] op_sel:[1,1,0] op_sel_hi:[1,0,1] neg_lo:[0,1,0]
	ds_write2_b64 v39, v[56:57], v[64:65] offset0:68 offset1:85
	v_pk_mul_f32 v[56:57], v[46:47], v[42:43] op_sel:[0,0] op_sel_hi:[0,1]
	v_pk_fma_f32 v[46:47], v[46:47], v[42:43], v[56:57] op_sel:[1,1,0] op_sel_hi:[1,0,1] neg_lo:[0,1,0]
	v_pk_mul_f32 v[56:57], v[58:59], v[46:47] op_sel:[0,0] op_sel_hi:[0,1]
	v_pk_fma_f32 v[56:57], v[58:59], v[46:47], v[56:57] op_sel:[1,1,0] op_sel_hi:[1,0,1] neg_lo:[0,1,0]
	v_pk_mul_f32 v[58:59], v[46:47], v[42:43] op_sel:[0,0] op_sel_hi:[0,1]
	v_pk_fma_f32 v[46:47], v[46:47], v[42:43], v[58:59] op_sel:[1,1,0] op_sel_hi:[1,0,1] neg_lo:[0,1,0]
	v_pk_mul_f32 v[58:59], v[50:51], v[46:47] op_sel:[0,0] op_sel_hi:[0,1]
	v_pk_fma_f32 v[50:51], v[50:51], v[46:47], v[58:59] op_sel:[1,1,0] op_sel_hi:[1,0,1] neg_lo:[0,1,0]
	ds_write2_b64 v39, v[56:57], v[50:51] offset0:102 offset1:119
	v_pk_mul_f32 v[50:51], v[46:47], v[42:43] op_sel:[0,0] op_sel_hi:[0,1]
	v_pk_fma_f32 v[46:47], v[46:47], v[42:43], v[50:51] op_sel:[1,1,0] op_sel_hi:[1,0,1] neg_lo:[0,1,0]
	v_pk_mul_f32 v[50:51], v[66:67], v[46:47] op_sel:[0,0] op_sel_hi:[0,1]
	v_pk_mul_f32 v[56:57], v[46:47], v[42:43] op_sel:[0,0] op_sel_hi:[0,1]
	v_pk_fma_f32 v[50:51], v[66:67], v[46:47], v[50:51] op_sel:[1,1,0] op_sel_hi:[1,0,1] neg_lo:[0,1,0]
	v_pk_fma_f32 v[46:47], v[46:47], v[42:43], v[56:57] op_sel:[1,1,0] op_sel_hi:[1,0,1] neg_lo:[0,1,0]
	v_pk_mul_f32 v[56:57], v[62:63], v[46:47] op_sel:[0,0] op_sel_hi:[0,1]
	v_pk_fma_f32 v[56:57], v[62:63], v[46:47], v[56:57] op_sel:[1,1,0] op_sel_hi:[1,0,1] neg_lo:[0,1,0]
	ds_write2_b64 v39, v[50:51], v[56:57] offset0:136 offset1:153
	v_pk_mul_f32 v[50:51], v[46:47], v[42:43] op_sel:[0,0] op_sel_hi:[0,1]
	v_pk_fma_f32 v[46:47], v[46:47], v[42:43], v[50:51] op_sel:[1,1,0] op_sel_hi:[1,0,1] neg_lo:[0,1,0]
	v_pk_mul_f32 v[50:51], v[52:53], v[46:47] op_sel:[0,0] op_sel_hi:[0,1]
	v_pk_fma_f32 v[50:51], v[52:53], v[46:47], v[50:51] op_sel:[1,1,0] op_sel_hi:[1,0,1] neg_lo:[0,1,0]
	v_pk_mul_f32 v[52:53], v[46:47], v[42:43] op_sel:[0,0] op_sel_hi:[0,1]
	v_pk_fma_f32 v[46:47], v[46:47], v[42:43], v[52:53] op_sel:[1,1,0] op_sel_hi:[1,0,1] neg_lo:[0,1,0]
	v_pk_mul_f32 v[52:53], v[44:45], v[46:47] op_sel:[0,0] op_sel_hi:[0,1]
	v_pk_fma_f32 v[44:45], v[44:45], v[46:47], v[52:53] op_sel:[1,1,0] op_sel_hi:[1,0,1] neg_lo:[0,1,0]
	ds_write2_b64 v39, v[50:51], v[44:45] offset0:170 offset1:187
	v_pk_mul_f32 v[44:45], v[46:47], v[42:43] op_sel:[0,0] op_sel_hi:[0,1]
	v_pk_fma_f32 v[44:45], v[46:47], v[42:43], v[44:45] op_sel:[1,1,0] op_sel_hi:[1,0,1] neg_lo:[0,1,0]
	v_pk_mul_f32 v[46:47], v[60:61], v[44:45] op_sel:[0,0] op_sel_hi:[0,1]
	v_pk_mul_f32 v[50:51], v[44:45], v[42:43] op_sel:[0,0] op_sel_hi:[0,1]
	v_pk_fma_f32 v[46:47], v[60:61], v[44:45], v[46:47] op_sel:[1,1,0] op_sel_hi:[1,0,1] neg_lo:[0,1,0]
	v_pk_fma_f32 v[44:45], v[44:45], v[42:43], v[50:51] op_sel:[1,1,0] op_sel_hi:[1,0,1] neg_lo:[0,1,0]
	v_pk_mul_f32 v[50:51], v[54:55], v[44:45] op_sel:[0,0] op_sel_hi:[0,1]
	v_pk_fma_f32 v[50:51], v[54:55], v[44:45], v[50:51] op_sel:[1,1,0] op_sel_hi:[1,0,1] neg_lo:[0,1,0]
	ds_write2_b64 v39, v[46:47], v[50:51] offset0:204 offset1:221
	v_pk_mul_f32 v[46:47], v[44:45], v[42:43] op_sel:[0,0] op_sel_hi:[0,1]
	v_pk_fma_f32 v[44:45], v[44:45], v[42:43], v[46:47] op_sel:[1,1,0] op_sel_hi:[1,0,1] neg_lo:[0,1,0]
	v_pk_mul_f32 v[46:47], v[48:49], v[44:45] op_sel:[0,0] op_sel_hi:[0,1]
	v_pk_fma_f32 v[46:47], v[48:49], v[44:45], v[46:47] op_sel:[1,1,0] op_sel_hi:[1,0,1] neg_lo:[0,1,0]
	v_pk_mul_f32 v[48:49], v[44:45], v[42:43] op_sel:[0,0] op_sel_hi:[0,1]
	v_pk_fma_f32 v[42:43], v[44:45], v[42:43], v[48:49] op_sel:[1,1,0] op_sel_hi:[1,0,1] neg_lo:[0,1,0]
	v_pk_mul_f32 v[44:45], v[40:41], v[42:43] op_sel:[0,0] op_sel_hi:[0,1]
	v_pk_fma_f32 v[40:41], v[40:41], v[42:43], v[44:45] op_sel:[1,1,0] op_sel_hi:[1,0,1] neg_lo:[0,1,0]
	ds_write2_b64 v39, v[46:47], v[40:41] offset0:238 offset1:255
	v_mad_u32_u24 v39, v34, s55, v35
	s_waitcnt lgkmcnt(0)
	s_barrier
	ds_read2_b64 v[40:43], v39 offset1:1
	ds_read2_b64 v[44:47], v39 offset0:2 offset1:3
	ds_read2_b64 v[48:51], v39 offset0:8 offset1:9
	ds_read2_b64 v[52:55], v39 offset0:4 offset1:5
	ds_read2_b64 v[56:59], v39 offset0:6 offset1:7
	ds_read2_b64 v[60:63], v39 offset0:12 offset1:13
	ds_read2_b64 v[64:67], v39 offset0:10 offset1:11
	ds_read2_b64 v[68:71], v39 offset0:14 offset1:15
	s_waitcnt lgkmcnt(5)
	v_pk_add_f32 v[72:73], v[40:41], v[48:49]
	v_pk_add_f32 v[40:41], v[40:41], v[48:49] neg_lo:[0,1] neg_hi:[0,1]
	s_waitcnt lgkmcnt(2)
	v_pk_add_f32 v[48:49], v[52:53], v[60:61]
	v_pk_add_f32 v[52:53], v[52:53], v[60:61] neg_lo:[0,1] neg_hi:[0,1]
	v_pk_add_f32 v[60:61], v[72:73], v[48:49]
	v_pk_add_f32 v[48:49], v[72:73], v[48:49] neg_lo:[0,1] neg_hi:[0,1]
	v_pk_add_f32 v[72:73], v[40:41], v[52:53] op_sel:[0,1] op_sel_hi:[1,0] neg_hi:[0,1]
	v_pk_add_f32 v[40:41], v[40:41], v[52:53] op_sel:[0,1] op_sel_hi:[1,0] neg_lo:[0,1]
	v_pk_add_f32 v[52:53], v[42:43], v[50:51]
	v_pk_add_f32 v[42:43], v[42:43], v[50:51] neg_lo:[0,1] neg_hi:[0,1]
	v_pk_add_f32 v[50:51], v[54:55], v[62:63]
	v_pk_add_f32 v[54:55], v[54:55], v[62:63] neg_lo:[0,1] neg_hi:[0,1]
	v_pk_add_f32 v[62:63], v[52:53], v[50:51]
	v_pk_add_f32 v[50:51], v[52:53], v[50:51] neg_lo:[0,1] neg_hi:[0,1]
	v_pk_add_f32 v[52:53], v[42:43], v[54:55] op_sel:[0,1] op_sel_hi:[1,0] neg_hi:[0,1]
	v_pk_add_f32 v[42:43], v[42:43], v[54:55] op_sel:[0,1] op_sel_hi:[1,0] neg_lo:[0,1]
	s_waitcnt lgkmcnt(1)
	v_pk_add_f32 v[54:55], v[44:45], v[64:65]
	v_pk_add_f32 v[44:45], v[44:45], v[64:65] neg_lo:[0,1] neg_hi:[0,1]
	s_waitcnt lgkmcnt(0)
	v_pk_add_f32 v[64:65], v[56:57], v[68:69]
	v_pk_add_f32 v[56:57], v[56:57], v[68:69] neg_lo:[0,1] neg_hi:[0,1]
	v_pk_add_f32 v[68:69], v[54:55], v[64:65]
	v_pk_add_f32 v[54:55], v[54:55], v[64:65] neg_lo:[0,1] neg_hi:[0,1]
	v_pk_add_f32 v[64:65], v[44:45], v[56:57] op_sel:[0,1] op_sel_hi:[1,0] neg_hi:[0,1]
	v_pk_add_f32 v[44:45], v[44:45], v[56:57] op_sel:[0,1] op_sel_hi:[1,0] neg_lo:[0,1]
	v_pk_add_f32 v[56:57], v[46:47], v[66:67]
	v_pk_add_f32 v[46:47], v[46:47], v[66:67] neg_lo:[0,1] neg_hi:[0,1]
	v_pk_add_f32 v[66:67], v[58:59], v[70:71]
	v_pk_add_f32 v[58:59], v[58:59], v[70:71] neg_lo:[0,1] neg_hi:[0,1]
	v_pk_add_f32 v[70:71], v[56:57], v[66:67]
	v_pk_add_f32 v[56:57], v[56:57], v[66:67] neg_lo:[0,1] neg_hi:[0,1]
	v_pk_add_f32 v[66:67], v[46:47], v[58:59] op_sel:[0,1] op_sel_hi:[1,0] neg_hi:[0,1]
	v_pk_add_f32 v[46:47], v[46:47], v[58:59] op_sel:[0,1] op_sel_hi:[1,0] neg_lo:[0,1]
	v_pk_mul_f32 v[58:59], v[52:53], s[38:39] op_sel:[0,0] op_sel_hi:[0,1]
	v_pk_fma_f32 v[24:25], v[52:53], s[38:39], v[58:59] op_sel:[1,1,0] op_sel_hi:[1,0,1] neg_lo:[0,1,0]
	v_pk_mul_f32 v[52:53], v[64:65], s[40:41] op_sel:[0,0] op_sel_hi:[0,1]
	v_pk_mul_f32 v[58:59], v[66:67], s[44:45] op_sel:[0,0] op_sel_hi:[0,1]
	s_barrier
	v_pk_fma_f32 v[52:53], v[64:65], s[40:41], v[52:53] op_sel:[1,1,0] op_sel_hi:[1,0,1] neg_lo:[0,1,0]
	v_pk_mul_f32 v[64:65], v[50:51], s[40:41] op_sel:[0,0] op_sel_hi:[0,1]
	v_pk_fma_f32 v[58:59], v[66:67], s[44:45], v[58:59] op_sel:[1,1,0] op_sel_hi:[1,0,1] neg_lo:[0,1,0]
	v_pk_fma_f32 v[20:21], v[50:51], s[40:41], v[64:65] op_sel:[1,1,0] op_sel_hi:[1,0,1] neg_lo:[0,1,0]
	v_pk_mul_f32 v[50:51], v[54:55], v[26:27] op_sel:[0,0] op_sel_hi:[0,1]
	v_pk_fma_f32 v[26:27], v[54:55], v[26:27], v[50:51] op_sel:[1,1,0] op_sel_hi:[1,0,1] neg_lo:[0,1,0]
	v_pk_mul_f32 v[50:51], v[56:57], s[46:47] op_sel:[0,0] op_sel_hi:[0,1]
	v_pk_mul_f32 v[54:55], v[42:43], s[44:45] op_sel:[0,0] op_sel_hi:[0,1]
	v_pk_fma_f32 v[18:19], v[42:43], s[44:45], v[54:55] op_sel:[1,1,0] op_sel_hi:[1,0,1] neg_lo:[0,1,0]
	v_pk_mul_f32 v[42:43], v[44:45], s[46:47] op_sel:[0,0] op_sel_hi:[0,1]
	v_pk_fma_f32 v[50:51], v[56:57], s[46:47], v[50:51] op_sel:[1,1,0] op_sel_hi:[1,0,1] neg_lo:[0,1,0]
	v_pk_add_f32 v[54:55], v[24:25], v[58:59] neg_lo:[0,1] neg_hi:[0,1]
	v_pk_fma_f32 v[22:23], v[44:45], s[46:47], v[42:43] op_sel:[1,1,0] op_sel_hi:[1,0,1] neg_lo:[0,1,0]
	v_pk_mul_f32 v[42:43], v[46:47], s[48:49] op_sel:[0,0] op_sel_hi:[0,1]
	v_pk_add_f32 v[44:45], v[62:63], v[70:71] neg_lo:[0,1] neg_hi:[0,1]
	v_pk_fma_f32 v[28:29], v[46:47], s[48:49], v[42:43] op_sel:[1,1,0] op_sel_hi:[1,0,1] neg_lo:[0,1,0]
	v_pk_add_f32 v[42:43], v[60:61], v[68:69] neg_lo:[0,1] neg_hi:[0,1]
	v_pk_add_f32 v[74:75], v[18:19], v[28:29] neg_lo:[0,1] neg_hi:[0,1]
	v_pk_add_f32 v[46:47], v[42:43], v[44:45] op_sel:[0,1] op_sel_hi:[1,0] neg_hi:[0,1]
	v_pk_add_f32 v[42:43], v[42:43], v[44:45] op_sel:[0,1] op_sel_hi:[1,0] neg_lo:[0,1]
	v_pk_add_f32 v[44:45], v[72:73], v[52:53] neg_lo:[0,1] neg_hi:[0,1]
	v_and_b32_e32 v19, 0xf0, v36
	v_pk_add_f32 v[56:57], v[44:45], v[54:55] op_sel:[0,1] op_sel_hi:[1,0] neg_hi:[0,1]
	v_pk_add_f32 v[44:45], v[44:45], v[54:55] op_sel:[0,1] op_sel_hi:[1,0] neg_lo:[0,1]
	v_pk_add_f32 v[54:55], v[48:49], v[26:27] neg_lo:[0,1] neg_hi:[0,1]
	v_pk_add_f32 v[64:65], v[20:21], v[50:51] neg_lo:[0,1] neg_hi:[0,1]
	v_mul_i32_i24_e32 v21, 0xfffff804, v38
	v_lshlrev_b32_e32 v19, 2, v19
	v_pk_add_f32 v[66:67], v[54:55], v[64:65] op_sel:[0,1] op_sel_hi:[1,0] neg_hi:[0,1]
	v_pk_add_f32 v[54:55], v[54:55], v[64:65] op_sel:[0,1] op_sel_hi:[1,0] neg_lo:[0,1]
	v_pk_add_f32 v[64:65], v[40:41], v[22:23] neg_lo:[0,1] neg_hi:[0,1]
	v_add3_u32 v19, v78, v21, v19
	v_add_f32_e32 v21, v62, v70
	v_add_f32_e32 v23, v60, v68
	v_add_f32_e32 v24, v24, v58
	v_add_f32_e32 v27, v72, v52
	v_add_f32_e32 v25, v23, v21
	v_add_f32_e32 v29, v27, v24
	v_mul_f32_e32 v25, 0x3a800000, v25
	v_mul_f32_e32 v29, 0x3a800000, v29
	ds_write2st64_b32 v19, v25, v29 offset1:4
	v_add_f32_e32 v20, v20, v50
	v_add_f32_e32 v25, v48, v26
	v_add_f32_e32 v18, v18, v28
	v_add_f32_e32 v22, v40, v22
	v_add_f32_e32 v26, v25, v20
	v_add_f32_e32 v28, v22, v18
	v_sub_f32_e32 v20, v25, v20
	v_sub_f32_e32 v18, v22, v18
	v_mul_f32_e32 v26, 0x3a800000, v26
	v_mul_f32_e32 v28, 0x3a800000, v28
	v_mul_f32_e32 v20, 0x3a800000, v20
	v_mul_f32_e32 v18, 0x3a800000, v18
	ds_write2st64_b32 v19, v26, v28 offset0:8 offset1:12
	v_mul_f32_e32 v26, 0x3a800000, v46
	v_mul_f32_e32 v28, 0x3a800000, v56
	v_sub_f32_e32 v21, v23, v21
	v_sub_f32_e32 v23, v27, v24
	ds_write2st64_b32 v19, v20, v18 offset0:40 offset1:44
	v_mul_f32_e32 v18, 0x3a800000, v42
	v_mul_f32_e32 v20, 0x3a800000, v44
	v_pk_add_f32 v[76:77], v[64:65], v[74:75] op_sel:[0,1] op_sel_hi:[1,0] neg_hi:[0,1]
	v_pk_add_f32 v[64:65], v[64:65], v[74:75] op_sel:[0,1] op_sel_hi:[1,0] neg_lo:[0,1]
	ds_write2st64_b32 v19, v26, v28 offset0:16 offset1:20
	v_mul_f32_e32 v26, 0x3a800000, v66
	v_mul_f32_e32 v28, 0x3a800000, v76
	v_mul_f32_e32 v21, 0x3a800000, v21
	v_mul_f32_e32 v23, 0x3a800000, v23
	ds_write2st64_b32 v19, v18, v20 offset0:48 offset1:52
	v_mul_f32_e32 v18, 0x3a800000, v54
	v_mul_f32_e32 v20, 0x3a800000, v64
	v_mov_b32_e32 v22, v34
	ds_write2st64_b32 v19, v26, v28 offset0:24 offset1:28
	ds_write2st64_b32 v19, v21, v23 offset0:32 offset1:36
	ds_write2st64_b32 v19, v18, v20 offset0:56 offset1:60
	s_waitcnt lgkmcnt(0)
	s_barrier
	v_lshlrev_b32_e32 v26, 12, v37
	v_lshl_add_u32 v23, v22, 5, v35
	ds_read_b128 v[18:21], v23
	v_lshlrev_b32_e32 v28, 3, v22
	ds_read_b128 v[22:25], v23 offset:16
	v_ashrrev_i32_e32 v27, 31, v26
	v_lshlrev_b64 v[26:27], 1, v[26:27]
	s_waitcnt lgkmcnt(1)
	v_cvt_pk_bf16_f32 v18, v18, v18
	v_lshrrev_b32_e32 v18, 16, v18
	v_cvt_pk_bf16_f32 v19, v19, v19
	v_and_or_b32 v18, v19, s57, v18
	v_cvt_pk_bf16_f32 v19, v20, v21
	s_waitcnt lgkmcnt(0)
	v_cvt_pk_bf16_f32 v20, v22, v23
	v_cvt_pk_bf16_f32 v21, v24, v25
	v_ashrrev_i32_e32 v29, 31, v28
	v_lshl_add_u64 v[22:23], v[28:29], 1, v[26:27]
	v_lshl_add_u64 v[22:23], s[26:27], 0, v[22:23]
	global_store_dwordx4 v[22:23], v[18:21], off
	s_nop 0
	v_lshl_add_u32 v22, v34, 5, v35
	ds_read_b128 v[18:21], v22 offset:8192
	ds_read_b128 v[22:25], v22 offset:8208
	v_lshl_add_u32 v28, v34, 3, v33
	s_waitcnt lgkmcnt(1)
	v_cvt_pk_bf16_f32 v18, v18, v18
	v_lshrrev_b32_e32 v18, 16, v18
	v_cvt_pk_bf16_f32 v19, v19, v19
	v_and_or_b32 v18, v19, s57, v18
	v_cvt_pk_bf16_f32 v19, v20, v21
	s_waitcnt lgkmcnt(0)
	v_cvt_pk_bf16_f32 v20, v22, v23
	v_cvt_pk_bf16_f32 v21, v24, v25
	v_ashrrev_i32_e32 v29, 31, v28
	v_lshl_add_u64 v[22:23], v[28:29], 1, v[26:27]
	v_lshl_add_u64 v[22:23], s[26:27], 0, v[22:23]
	s_add_u32 s26, s26, s34
	s_addc_u32 s27, s27, s35
	s_andn2_b64 vcc, exec, s[50:51]
	global_store_dwordx4 v[22:23], v[18:21], off
	s_barrier
	s_cbranch_vccz .LBB0_1712

.LBB0_3100:
	s_or_b64 exec, exec, s[50:51]
	v_mov_b32_e32 v16, v6
	v_mov_b32_e32 v17, v2
	v_mov_b32_e32 v2, v7
	v_mov_b32_e32 v6, v8
	v_mov_b32_e32 v7, v4
	v_mov_b32_e32 v4, v9
	v_pk_add_f32 v[2:3], v[16:17], v[2:3]
	v_pk_add_f32 v[4:5], v[6:7], v[4:5]
	v_pk_add_f32 v[6:7], v[24:25], v[40:41]
	v_pk_add_f32 v[2:3], v[2:3], v[4:5]
	v_pk_add_f32 v[4:5], v[14:15], v[32:33] neg_lo:[0,1] neg_hi:[0,1]
	v_add_f32_e32 v10, v2, v3
	v_pk_add_f32 v[2:3], v[14:15], v[32:33]
	v_pk_add_f32 v[8:9], v[24:25], v[40:41] neg_lo:[0,1] neg_hi:[0,1]
	v_pk_add_f32 v[24:25], v[2:3], v[6:7]
	v_pk_add_f32 v[32:33], v[2:3], v[6:7] neg_lo:[0,1] neg_hi:[0,1]
	v_pk_add_f32 v[40:41], v[4:5], v[8:9] op_sel:[0,1] op_sel_hi:[1,0] neg_hi:[0,1]
	s_waitcnt lgkmcnt(1)
	v_pk_add_f32 v[48:49], v[4:5], v[8:9] op_sel:[0,1] op_sel_hi:[1,0] neg_lo:[0,1]
	v_pk_add_f32 v[2:3], v[18:19], v[34:35]
	v_pk_add_f32 v[4:5], v[18:19], v[34:35] neg_lo:[0,1] neg_hi:[0,1]
	v_pk_add_f32 v[6:7], v[26:27], v[42:43]
	v_pk_add_f32 v[8:9], v[26:27], v[42:43] neg_lo:[0,1] neg_hi:[0,1]
	v_pk_add_f32 v[18:19], v[2:3], v[6:7]
	v_pk_add_f32 v[6:7], v[2:3], v[6:7] neg_lo:[0,1] neg_hi:[0,1]
	v_pk_add_f32 v[2:3], v[4:5], v[8:9] op_sel:[0,1] op_sel_hi:[1,0] neg_hi:[0,1]
	v_pk_add_f32 v[16:17], v[4:5], v[8:9] op_sel:[0,1] op_sel_hi:[1,0] neg_lo:[0,1]
	v_pk_add_f32 v[4:5], v[20:21], v[36:37]
	v_pk_add_f32 v[8:9], v[20:21], v[36:37] neg_lo:[0,1] neg_hi:[0,1]
	v_pk_add_f32 v[14:15], v[28:29], v[44:45]
	v_pk_add_f32 v[20:21], v[28:29], v[44:45] neg_lo:[0,1] neg_hi:[0,1]
	v_pk_add_f32 v[26:27], v[4:5], v[14:15]
	v_pk_add_f32 v[28:29], v[4:5], v[14:15] neg_lo:[0,1] neg_hi:[0,1]
	v_pk_add_f32 v[14:15], v[8:9], v[20:21] op_sel:[0,1] op_sel_hi:[1,0] neg_hi:[0,1]
	v_pk_add_f32 v[20:21], v[8:9], v[20:21] op_sel:[0,1] op_sel_hi:[1,0] neg_lo:[0,1]
	v_pk_add_f32 v[4:5], v[22:23], v[38:39]
	v_pk_add_f32 v[8:9], v[22:23], v[38:39] neg_lo:[0,1] neg_hi:[0,1]
	v_pk_add_f32 v[22:23], v[30:31], v[46:47]
	v_pk_add_f32 v[30:31], v[30:31], v[46:47] neg_lo:[0,1] neg_hi:[0,1]
	v_pk_add_f32 v[34:35], v[4:5], v[22:23]
	v_pk_add_f32 v[22:23], v[4:5], v[22:23] neg_lo:[0,1] neg_hi:[0,1]
	v_pk_add_f32 v[36:37], v[8:9], v[30:31] op_sel:[0,1] op_sel_hi:[1,0] neg_hi:[0,1]
	v_pk_add_f32 v[30:31], v[8:9], v[30:31] op_sel:[0,1] op_sel_hi:[1,0] neg_lo:[0,1]
	v_pk_mul_f32 v[4:5], v[2:3], s[20:21] op_sel:[0,0] op_sel_hi:[0,1]
	s_waitcnt lgkmcnt(0)
	v_pk_fma_f32 v[38:39], v[2:3], s[20:21], v[4:5] op_sel:[1,1,0] op_sel_hi:[1,0,1] neg_lo:[0,1,0]
	v_mov_b64_e32 v[4:5], s[26:27]
	v_pk_mul_f32 v[2:3], v[14:15], v[4:5] op_sel:[0,0] op_sel_hi:[0,1]
	s_barrier
	v_pk_fma_f32 v[42:43], v[14:15], v[4:5], v[2:3] op_sel:[1,1,0] op_sel_hi:[1,0,1] neg_lo:[0,1,0]
	v_mov_b64_e32 v[2:3], s[36:37]
	v_pk_mul_f32 v[14:15], v[36:37], v[2:3] op_sel:[0,0] op_sel_hi:[0,1]
	v_pk_fma_f32 v[36:37], v[36:37], v[2:3], v[14:15] op_sel:[1,1,0] op_sel_hi:[1,0,1] neg_lo:[0,1,0]
	v_pk_mul_f32 v[14:15], v[6:7], v[4:5] op_sel:[0,0] op_sel_hi:[0,1]
	s_lshl_b32 s12, s9, 13
	v_pk_fma_f32 v[44:45], v[6:7], v[4:5], v[14:15] op_sel:[1,1,0] op_sel_hi:[1,0,1] neg_lo:[0,1,0]
	v_mov_b64_e32 v[14:15], s[40:41]
	v_pk_mul_f32 v[6:7], v[28:29], v[14:15] op_sel:[0,0] op_sel_hi:[0,1]
	s_xor_b64 s[50:51], s[48:49], -1
	v_pk_fma_f32 v[28:29], v[28:29], v[14:15], v[6:7] op_sel:[1,1,0] op_sel_hi:[1,0,1] neg_lo:[0,1,0]
	v_mov_b64_e32 v[6:7], s[44:45]
	v_pk_mul_f32 v[46:47], v[22:23], v[6:7] op_sel:[0,0] op_sel_hi:[0,1]
	s_mov_b32 s9, 1
	v_pk_fma_f32 v[22:23], v[22:23], v[6:7], v[46:47] op_sel:[1,1,0] op_sel_hi:[1,0,1] neg_lo:[0,1,0]
	v_pk_mul_f32 v[46:47], v[16:17], v[2:3] op_sel:[0,0] op_sel_hi:[0,1]
	s_mov_b64 s[48:49], 0
	v_pk_fma_f32 v[46:47], v[16:17], v[2:3], v[46:47] op_sel:[1,1,0] op_sel_hi:[1,0,1] neg_lo:[0,1,0]
	v_pk_mul_f32 v[16:17], v[20:21], v[6:7] op_sel:[0,0] op_sel_hi:[0,1]
	v_pk_fma_f32 v[20:21], v[20:21], v[6:7], v[16:17] op_sel:[1,1,0] op_sel_hi:[1,0,1] neg_lo:[0,1,0]
	v_pk_mul_f32 v[50:51], v[30:31], s[46:47] op_sel:[0,0] op_sel_hi:[0,1]
	v_pk_fma_f32 v[30:31], v[30:31], s[46:47], v[50:51] op_sel:[1,1,0] op_sel_hi:[1,0,1] neg_lo:[0,1,0]
	v_pk_add_f32 v[50:51], v[24:25], v[26:27]
	v_pk_add_f32 v[24:25], v[24:25], v[26:27] neg_lo:[0,1] neg_hi:[0,1]
	v_pk_add_f32 v[26:27], v[18:19], v[34:35]
	v_pk_add_f32 v[18:19], v[18:19], v[34:35] neg_lo:[0,1] neg_hi:[0,1]
	v_pk_add_f32 v[34:35], v[50:51], v[26:27]
	v_pk_add_f32 v[26:27], v[50:51], v[26:27] neg_lo:[0,1] neg_hi:[0,1]
	v_pk_add_f32 v[50:51], v[24:25], v[18:19] op_sel:[0,1] op_sel_hi:[1,0] neg_hi:[0,1]
	v_pk_add_f32 v[18:19], v[24:25], v[18:19] op_sel:[0,1] op_sel_hi:[1,0] neg_lo:[0,1]
	v_pk_add_f32 v[24:25], v[40:41], v[42:43]
	v_pk_add_f32 v[40:41], v[40:41], v[42:43] neg_lo:[0,1] neg_hi:[0,1]
	v_pk_add_f32 v[42:43], v[38:39], v[36:37]
	v_pk_add_f32 v[36:37], v[38:39], v[36:37] neg_lo:[0,1] neg_hi:[0,1]
	v_pk_add_f32 v[38:39], v[24:25], v[42:43]
	v_pk_add_f32 v[24:25], v[24:25], v[42:43] neg_lo:[0,1] neg_hi:[0,1]
	v_pk_add_f32 v[42:43], v[40:41], v[36:37] op_sel:[0,1] op_sel_hi:[1,0] neg_hi:[0,1]
	v_pk_add_f32 v[36:37], v[40:41], v[36:37] op_sel:[0,1] op_sel_hi:[1,0] neg_lo:[0,1]
	v_pk_add_f32 v[40:41], v[32:33], v[28:29]
	v_pk_add_f32 v[28:29], v[32:33], v[28:29] neg_lo:[0,1] neg_hi:[0,1]
	v_pk_add_f32 v[32:33], v[44:45], v[22:23]
	v_pk_add_f32 v[22:23], v[44:45], v[22:23] neg_lo:[0,1] neg_hi:[0,1]
	v_pk_add_f32 v[44:45], v[40:41], v[32:33]
	v_pk_add_f32 v[32:33], v[40:41], v[32:33] neg_lo:[0,1] neg_hi:[0,1]
	v_pk_add_f32 v[40:41], v[28:29], v[22:23] op_sel:[0,1] op_sel_hi:[1,0] neg_hi:[0,1]
	v_pk_add_f32 v[22:23], v[28:29], v[22:23] op_sel:[0,1] op_sel_hi:[1,0] neg_lo:[0,1]
	v_pk_add_f32 v[28:29], v[48:49], v[20:21]
	v_pk_add_f32 v[20:21], v[48:49], v[20:21] neg_lo:[0,1] neg_hi:[0,1]
	v_pk_add_f32 v[48:49], v[46:47], v[30:31]
	v_pk_add_f32 v[30:31], v[46:47], v[30:31] neg_lo:[0,1] neg_hi:[0,1]
	v_pk_add_f32 v[46:47], v[28:29], v[48:49]
	v_pk_add_f32 v[28:29], v[28:29], v[48:49] neg_lo:[0,1] neg_hi:[0,1]
	v_pk_add_f32 v[48:49], v[20:21], v[30:31] op_sel:[0,1] op_sel_hi:[1,0] neg_hi:[0,1]
	v_pk_add_f32 v[20:21], v[20:21], v[30:31] op_sel:[0,1] op_sel_hi:[1,0] neg_lo:[0,1]
	v_mov_b32_e32 v30, v53
	v_mov_b32_e32 v31, v62
	ds_write_b64 v59, v[34:35]
	v_pk_mul_f32 v[34:35], v[38:39], v[30:31] op_sel:[0,0] op_sel_hi:[0,1]
	v_pk_fma_f32 v[34:35], v[38:39], v[30:31], v[34:35] op_sel:[1,1,0] op_sel_hi:[1,0,1] neg_lo:[0,1,0]
	ds_write_b64 v59, v[34:35] offset:2176
	v_pk_mul_f32 v[34:35], v[30:31], v[30:31] op_sel:[0,0] op_sel_hi:[0,1]
	v_pk_fma_f32 v[34:35], v[30:31], v[30:31], v[34:35] op_sel:[1,1,0] op_sel_hi:[1,0,1] neg_lo:[0,1,0]
	v_pk_mul_f32 v[38:39], v[44:45], v[34:35] op_sel:[0,0] op_sel_hi:[0,1]
	v_pk_fma_f32 v[38:39], v[44:45], v[34:35], v[38:39] op_sel:[1,1,0] op_sel_hi:[1,0,1] neg_lo:[0,1,0]
	ds_write_b64 v59, v[38:39] offset:4352
	v_pk_mul_f32 v[38:39], v[34:35], v[30:31] op_sel:[0,0] op_sel_hi:[0,1]
	v_pk_fma_f32 v[34:35], v[34:35], v[30:31], v[38:39] op_sel:[1,1,0] op_sel_hi:[1,0,1] neg_lo:[0,1,0]
	v_pk_mul_f32 v[38:39], v[46:47], v[34:35] op_sel:[0,0] op_sel_hi:[0,1]
	v_pk_fma_f32 v[38:39], v[46:47], v[34:35], v[38:39] op_sel:[1,1,0] op_sel_hi:[1,0,1] neg_lo:[0,1,0]
	ds_write_b64 v59, v[38:39] offset:6528
	v_pk_mul_f32 v[38:39], v[34:35], v[30:31] op_sel:[0,0] op_sel_hi:[0,1]
	v_pk_fma_f32 v[34:35], v[34:35], v[30:31], v[38:39] op_sel:[1,1,0] op_sel_hi:[1,0,1] neg_lo:[0,1,0]
	v_pk_mul_f32 v[38:39], v[50:51], v[34:35] op_sel:[0,0] op_sel_hi:[0,1]
	v_pk_fma_f32 v[38:39], v[50:51], v[34:35], v[38:39] op_sel:[1,1,0] op_sel_hi:[1,0,1] neg_lo:[0,1,0]
	ds_write_b64 v59, v[38:39] offset:8704
	v_pk_mul_f32 v[38:39], v[34:35], v[30:31] op_sel:[0,0] op_sel_hi:[0,1]
	v_pk_fma_f32 v[34:35], v[34:35], v[30:31], v[38:39] op_sel:[1,1,0] op_sel_hi:[1,0,1] neg_lo:[0,1,0]
	v_pk_mul_f32 v[38:39], v[42:43], v[34:35] op_sel:[0,0] op_sel_hi:[0,1]
	v_pk_fma_f32 v[38:39], v[42:43], v[34:35], v[38:39] op_sel:[1,1,0] op_sel_hi:[1,0,1] neg_lo:[0,1,0]
	ds_write_b64 v59, v[38:39] offset:10880
	v_pk_mul_f32 v[38:39], v[34:35], v[30:31] op_sel:[0,0] op_sel_hi:[0,1]
	v_pk_fma_f32 v[34:35], v[34:35], v[30:31], v[38:39] op_sel:[1,1,0] op_sel_hi:[1,0,1] neg_lo:[0,1,0]
	v_pk_mul_f32 v[38:39], v[40:41], v[34:35] op_sel:[0,0] op_sel_hi:[0,1]
	v_pk_fma_f32 v[38:39], v[40:41], v[34:35], v[38:39] op_sel:[1,1,0] op_sel_hi:[1,0,1] neg_lo:[0,1,0]
	ds_write_b64 v59, v[38:39] offset:13056
	v_pk_mul_f32 v[38:39], v[34:35], v[30:31] op_sel:[0,0] op_sel_hi:[0,1]
	v_pk_fma_f32 v[34:35], v[34:35], v[30:31], v[38:39] op_sel:[1,1,0] op_sel_hi:[1,0,1] neg_lo:[0,1,0]
	v_pk_mul_f32 v[38:39], v[48:49], v[34:35] op_sel:[0,0] op_sel_hi:[0,1]
	v_pk_fma_f32 v[38:39], v[48:49], v[34:35], v[38:39] op_sel:[1,1,0] op_sel_hi:[1,0,1] neg_lo:[0,1,0]
	ds_write_b64 v59, v[38:39] offset:15232
	v_pk_mul_f32 v[38:39], v[34:35], v[30:31] op_sel:[0,0] op_sel_hi:[0,1]
	v_pk_fma_f32 v[34:35], v[34:35], v[30:31], v[38:39] op_sel:[1,1,0] op_sel_hi:[1,0,1] neg_lo:[0,1,0]
	v_pk_mul_f32 v[38:39], v[26:27], v[34:35] op_sel:[0,0] op_sel_hi:[0,1]
	v_pk_fma_f32 v[26:27], v[26:27], v[34:35], v[38:39] op_sel:[1,1,0] op_sel_hi:[1,0,1] neg_lo:[0,1,0]
	ds_write_b64 v59, v[26:27] offset:17408
	v_pk_mul_f32 v[26:27], v[34:35], v[30:31] op_sel:[0,0] op_sel_hi:[0,1]
	v_pk_fma_f32 v[26:27], v[34:35], v[30:31], v[26:27] op_sel:[1,1,0] op_sel_hi:[1,0,1] neg_lo:[0,1,0]
	v_pk_mul_f32 v[34:35], v[24:25], v[26:27] op_sel:[0,0] op_sel_hi:[0,1]
	v_pk_fma_f32 v[24:25], v[24:25], v[26:27], v[34:35] op_sel:[1,1,0] op_sel_hi:[1,0,1] neg_lo:[0,1,0]
	ds_write_b64 v59, v[24:25] offset:19584
	v_pk_mul_f32 v[24:25], v[26:27], v[30:31] op_sel:[0,0] op_sel_hi:[0,1]
	v_pk_fma_f32 v[24:25], v[26:27], v[30:31], v[24:25] op_sel:[1,1,0] op_sel_hi:[1,0,1] neg_lo:[0,1,0]
	v_pk_mul_f32 v[26:27], v[32:33], v[24:25] op_sel:[0,0] op_sel_hi:[0,1]
	v_pk_fma_f32 v[26:27], v[32:33], v[24:25], v[26:27] op_sel:[1,1,0] op_sel_hi:[1,0,1] neg_lo:[0,1,0]
	ds_write_b64 v59, v[26:27] offset:21760
	v_pk_mul_f32 v[26:27], v[24:25], v[30:31] op_sel:[0,0] op_sel_hi:[0,1]
	v_pk_fma_f32 v[24:25], v[24:25], v[30:31], v[26:27] op_sel:[1,1,0] op_sel_hi:[1,0,1] neg_lo:[0,1,0]
	v_pk_mul_f32 v[26:27], v[28:29], v[24:25] op_sel:[0,0] op_sel_hi:[0,1]
	v_pk_fma_f32 v[26:27], v[28:29], v[24:25], v[26:27] op_sel:[1,1,0] op_sel_hi:[1,0,1] neg_lo:[0,1,0]
	ds_write_b64 v59, v[26:27] offset:23936
	v_pk_mul_f32 v[26:27], v[24:25], v[30:31] op_sel:[0,0] op_sel_hi:[0,1]
	v_pk_fma_f32 v[24:25], v[24:25], v[30:31], v[26:27] op_sel:[1,1,0] op_sel_hi:[1,0,1] neg_lo:[0,1,0]
	v_pk_mul_f32 v[26:27], v[18:19], v[24:25] op_sel:[0,0] op_sel_hi:[0,1]
	v_pk_fma_f32 v[18:19], v[18:19], v[24:25], v[26:27] op_sel:[1,1,0] op_sel_hi:[1,0,1] neg_lo:[0,1,0]
	ds_write_b64 v59, v[18:19] offset:26112
	v_pk_mul_f32 v[18:19], v[24:25], v[30:31] op_sel:[0,0] op_sel_hi:[0,1]
	v_pk_fma_f32 v[18:19], v[24:25], v[30:31], v[18:19] op_sel:[1,1,0] op_sel_hi:[1,0,1] neg_lo:[0,1,0]
	v_pk_mul_f32 v[24:25], v[36:37], v[18:19] op_sel:[0,0] op_sel_hi:[0,1]
	v_pk_fma_f32 v[24:25], v[36:37], v[18:19], v[24:25] op_sel:[1,1,0] op_sel_hi:[1,0,1] neg_lo:[0,1,0]
	ds_write_b64 v59, v[24:25] offset:28288
	v_pk_mul_f32 v[24:25], v[18:19], v[30:31] op_sel:[0,0] op_sel_hi:[0,1]
	v_pk_fma_f32 v[18:19], v[18:19], v[30:31], v[24:25] op_sel:[1,1,0] op_sel_hi:[1,0,1] neg_lo:[0,1,0]
	v_pk_mul_f32 v[24:25], v[22:23], v[18:19] op_sel:[0,0] op_sel_hi:[0,1]
	v_pk_fma_f32 v[22:23], v[22:23], v[18:19], v[24:25] op_sel:[1,1,0] op_sel_hi:[1,0,1] neg_lo:[0,1,0]
	ds_write_b64 v59, v[22:23] offset:30464
	v_pk_mul_f32 v[22:23], v[18:19], v[30:31] op_sel:[0,0] op_sel_hi:[0,1]
	v_pk_fma_f32 v[18:19], v[18:19], v[30:31], v[22:23] op_sel:[1,1,0] op_sel_hi:[1,0,1] neg_lo:[0,1,0]
	v_pk_mul_f32 v[22:23], v[20:21], v[18:19] op_sel:[0,0] op_sel_hi:[0,1]
	v_pk_fma_f32 v[18:19], v[20:21], v[18:19], v[22:23] op_sel:[1,1,0] op_sel_hi:[1,0,1] neg_lo:[0,1,0]
	ds_write_b64 v59, v[18:19] offset:32640
	s_waitcnt lgkmcnt(0)
	s_barrier
	ds_read2_b64 v[18:21], v60 offset1:17
	ds_read2_b64 v[22:25], v60 offset0:34 offset1:51
	ds_read2_b64 v[26:29], v60 offset0:68 offset1:85
	ds_read2_b64 v[30:33], v60 offset0:136 offset1:153
	ds_read2_b64 v[34:37], v60 offset0:102 offset1:119
	ds_read2_b64 v[38:41], v60 offset0:204 offset1:221
	ds_read2_b64 v[42:45], v60 offset0:170 offset1:187
	ds_read2_b64 v[46:49], v60 offset0:238 offset1:255
	s_waitcnt lgkmcnt(4)
	v_pk_add_f32 v[50:51], v[18:19], v[30:31]
	v_pk_add_f32 v[18:19], v[18:19], v[30:31] neg_lo:[0,1] neg_hi:[0,1]
	s_waitcnt lgkmcnt(2)
	v_pk_add_f32 v[30:31], v[26:27], v[38:39]
	v_pk_add_f32 v[26:27], v[26:27], v[38:39] neg_lo:[0,1] neg_hi:[0,1]
	v_pk_add_f32 v[38:39], v[50:51], v[30:31]
	v_pk_add_f32 v[30:31], v[50:51], v[30:31] neg_lo:[0,1] neg_hi:[0,1]
	v_pk_add_f32 v[50:51], v[18:19], v[26:27] op_sel:[0,1] op_sel_hi:[1,0] neg_hi:[0,1]
	v_pk_add_f32 v[18:19], v[18:19], v[26:27] op_sel:[0,1] op_sel_hi:[1,0] neg_lo:[0,1]
	v_pk_add_f32 v[26:27], v[20:21], v[32:33]
	v_pk_add_f32 v[20:21], v[20:21], v[32:33] neg_lo:[0,1] neg_hi:[0,1]
	v_pk_add_f32 v[32:33], v[28:29], v[40:41]
	v_pk_add_f32 v[28:29], v[28:29], v[40:41] neg_lo:[0,1] neg_hi:[0,1]
	v_pk_add_f32 v[40:41], v[26:27], v[32:33]
	v_pk_add_f32 v[26:27], v[26:27], v[32:33] neg_lo:[0,1] neg_hi:[0,1]
	v_pk_add_f32 v[32:33], v[20:21], v[28:29] op_sel:[0,1] op_sel_hi:[1,0] neg_hi:[0,1]
	v_pk_add_f32 v[20:21], v[20:21], v[28:29] op_sel:[0,1] op_sel_hi:[1,0] neg_lo:[0,1]
	s_waitcnt lgkmcnt(1)
	v_pk_add_f32 v[28:29], v[22:23], v[42:43]
	v_pk_add_f32 v[22:23], v[22:23], v[42:43] neg_lo:[0,1] neg_hi:[0,1]
	s_waitcnt lgkmcnt(0)
	v_pk_add_f32 v[42:43], v[34:35], v[46:47]
	v_pk_add_f32 v[34:35], v[34:35], v[46:47] neg_lo:[0,1] neg_hi:[0,1]
	v_pk_add_f32 v[46:47], v[28:29], v[42:43]
	v_pk_add_f32 v[28:29], v[28:29], v[42:43] neg_lo:[0,1] neg_hi:[0,1]
	v_pk_add_f32 v[42:43], v[22:23], v[34:35] op_sel:[0,1] op_sel_hi:[1,0] neg_hi:[0,1]
	v_pk_add_f32 v[22:23], v[22:23], v[34:35] op_sel:[0,1] op_sel_hi:[1,0] neg_lo:[0,1]
	v_pk_add_f32 v[34:35], v[24:25], v[44:45]
	v_pk_add_f32 v[24:25], v[24:25], v[44:45] neg_lo:[0,1] neg_hi:[0,1]
	v_pk_add_f32 v[44:45], v[36:37], v[48:49]
	v_pk_add_f32 v[36:37], v[36:37], v[48:49] neg_lo:[0,1] neg_hi:[0,1]
	v_pk_add_f32 v[48:49], v[34:35], v[44:45]
	v_pk_add_f32 v[34:35], v[34:35], v[44:45] neg_lo:[0,1] neg_hi:[0,1]
	v_pk_add_f32 v[44:45], v[24:25], v[36:37] op_sel:[0,1] op_sel_hi:[1,0] neg_hi:[0,1]
	v_pk_add_f32 v[24:25], v[24:25], v[36:37] op_sel:[0,1] op_sel_hi:[1,0] neg_lo:[0,1]
	v_pk_mul_f32 v[36:37], v[32:33], s[20:21] op_sel:[0,0] op_sel_hi:[0,1]
	v_pk_fma_f32 v[32:33], v[32:33], s[20:21], v[36:37] op_sel:[1,1,0] op_sel_hi:[1,0,1] neg_lo:[0,1,0]
	v_pk_mul_f32 v[36:37], v[42:43], v[4:5] op_sel:[0,0] op_sel_hi:[0,1]
	v_pk_fma_f32 v[36:37], v[42:43], v[4:5], v[36:37] op_sel:[1,1,0] op_sel_hi:[1,0,1] neg_lo:[0,1,0]
	v_pk_mul_f32 v[42:43], v[44:45], v[2:3] op_sel:[0,0] op_sel_hi:[0,1]
	v_pk_fma_f32 v[42:43], v[44:45], v[2:3], v[42:43] op_sel:[1,1,0] op_sel_hi:[1,0,1] neg_lo:[0,1,0]
	v_pk_mul_f32 v[44:45], v[26:27], v[4:5] op_sel:[0,0] op_sel_hi:[0,1]
	v_pk_fma_f32 v[26:27], v[26:27], v[4:5], v[44:45] op_sel:[1,1,0] op_sel_hi:[1,0,1] neg_lo:[0,1,0]
	v_pk_mul_f32 v[44:45], v[28:29], v[14:15] op_sel:[0,0] op_sel_hi:[0,1]
	v_pk_fma_f32 v[28:29], v[28:29], v[14:15], v[44:45] op_sel:[1,1,0] op_sel_hi:[1,0,1] neg_lo:[0,1,0]
	v_pk_mul_f32 v[44:45], v[34:35], v[6:7] op_sel:[0,0] op_sel_hi:[0,1]
	v_pk_fma_f32 v[34:35], v[34:35], v[6:7], v[44:45] op_sel:[1,1,0] op_sel_hi:[1,0,1] neg_lo:[0,1,0]
	v_pk_mul_f32 v[44:45], v[20:21], v[2:3] op_sel:[0,0] op_sel_hi:[0,1]
	v_pk_fma_f32 v[20:21], v[20:21], v[2:3], v[44:45] op_sel:[1,1,0] op_sel_hi:[1,0,1] neg_lo:[0,1,0]
	v_pk_mul_f32 v[44:45], v[22:23], v[6:7] op_sel:[0,0] op_sel_hi:[0,1]
	v_pk_fma_f32 v[22:23], v[22:23], v[6:7], v[44:45] op_sel:[1,1,0] op_sel_hi:[1,0,1] neg_lo:[0,1,0]
	v_pk_mul_f32 v[44:45], v[24:25], s[46:47] op_sel:[0,0] op_sel_hi:[0,1]
	v_pk_fma_f32 v[24:25], v[24:25], s[46:47], v[44:45] op_sel:[1,1,0] op_sel_hi:[1,0,1] neg_lo:[0,1,0]
	v_pk_add_f32 v[44:45], v[38:39], v[46:47]
	v_pk_add_f32 v[38:39], v[38:39], v[46:47] neg_lo:[0,1] neg_hi:[0,1]
	v_pk_add_f32 v[46:47], v[40:41], v[48:49]
	v_pk_add_f32 v[40:41], v[40:41], v[48:49] neg_lo:[0,1] neg_hi:[0,1]
	v_pk_add_f32 v[48:49], v[44:45], v[46:47]
	v_pk_add_f32 v[44:45], v[44:45], v[46:47] neg_lo:[0,1] neg_hi:[0,1]
	v_pk_add_f32 v[46:47], v[38:39], v[40:41] op_sel:[0,1] op_sel_hi:[1,0] neg_hi:[0,1]
	v_pk_add_f32 v[38:39], v[38:39], v[40:41] op_sel:[0,1] op_sel_hi:[1,0] neg_lo:[0,1]
	v_pk_add_f32 v[40:41], v[50:51], v[36:37]
	v_pk_add_f32 v[36:37], v[50:51], v[36:37] neg_lo:[0,1] neg_hi:[0,1]
	v_pk_add_f32 v[50:51], v[32:33], v[42:43]
	v_pk_add_f32 v[32:33], v[32:33], v[42:43] neg_lo:[0,1] neg_hi:[0,1]
	v_pk_add_f32 v[42:43], v[40:41], v[50:51]
	v_pk_add_f32 v[40:41], v[40:41], v[50:51] neg_lo:[0,1] neg_hi:[0,1]
	v_pk_add_f32 v[50:51], v[36:37], v[32:33] op_sel:[0,1] op_sel_hi:[1,0] neg_hi:[0,1]
	v_pk_add_f32 v[32:33], v[36:37], v[32:33] op_sel:[0,1] op_sel_hi:[1,0] neg_lo:[0,1]
	v_pk_add_f32 v[36:37], v[30:31], v[28:29]
	v_pk_add_f32 v[28:29], v[30:31], v[28:29] neg_lo:[0,1] neg_hi:[0,1]
	v_pk_add_f32 v[30:31], v[26:27], v[34:35]
	v_pk_add_f32 v[26:27], v[26:27], v[34:35] neg_lo:[0,1] neg_hi:[0,1]
	v_pk_add_f32 v[34:35], v[36:37], v[30:31]
	v_pk_add_f32 v[30:31], v[36:37], v[30:31] neg_lo:[0,1] neg_hi:[0,1]
	v_pk_add_f32 v[36:37], v[28:29], v[26:27] op_sel:[0,1] op_sel_hi:[1,0] neg_hi:[0,1]
	v_pk_add_f32 v[26:27], v[28:29], v[26:27] op_sel:[0,1] op_sel_hi:[1,0] neg_lo:[0,1]
	v_pk_add_f32 v[28:29], v[18:19], v[22:23]
	v_pk_add_f32 v[18:19], v[18:19], v[22:23] neg_lo:[0,1] neg_hi:[0,1]
	v_pk_add_f32 v[22:23], v[20:21], v[24:25]
	v_pk_add_f32 v[20:21], v[20:21], v[24:25] neg_lo:[0,1] neg_hi:[0,1]
	v_pk_add_f32 v[24:25], v[28:29], v[22:23]
	v_pk_add_f32 v[22:23], v[28:29], v[22:23] neg_lo:[0,1] neg_hi:[0,1]
	v_pk_add_f32 v[28:29], v[18:19], v[20:21] op_sel:[0,1] op_sel_hi:[1,0] neg_hi:[0,1]
	v_pk_add_f32 v[18:19], v[18:19], v[20:21] op_sel:[0,1] op_sel_hi:[1,0] neg_lo:[0,1]
	v_mov_b32_e32 v21, v63
	v_mov_b32_e32 v20, v54
	s_nop 0
	v_pk_mul_f32 v[66:67], v[42:43], v[20:21] op_sel:[0,0] op_sel_hi:[0,1]
	v_pk_fma_f32 v[42:43], v[42:43], v[20:21], v[66:67] op_sel:[1,1,0] op_sel_hi:[1,0,1] neg_lo:[0,1,0]
	ds_write2_b64 v60, v[48:49], v[42:43] offset1:17
	v_pk_mul_f32 v[42:43], v[20:21], v[20:21] op_sel:[0,0] op_sel_hi:[0,1]
	v_pk_fma_f32 v[42:43], v[20:21], v[20:21], v[42:43] op_sel:[1,1,0] op_sel_hi:[1,0,1] neg_lo:[0,1,0]
	v_pk_mul_f32 v[48:49], v[34:35], v[42:43] op_sel:[0,0] op_sel_hi:[0,1]
	v_pk_fma_f32 v[34:35], v[34:35], v[42:43], v[48:49] op_sel:[1,1,0] op_sel_hi:[1,0,1] neg_lo:[0,1,0]
	v_pk_mul_f32 v[48:49], v[42:43], v[20:21] op_sel:[0,0] op_sel_hi:[0,1]
	v_pk_fma_f32 v[42:43], v[42:43], v[20:21], v[48:49] op_sel:[1,1,0] op_sel_hi:[1,0,1] neg_lo:[0,1,0]
	v_pk_mul_f32 v[48:49], v[24:25], v[42:43] op_sel:[0,0] op_sel_hi:[0,1]
	v_pk_fma_f32 v[24:25], v[24:25], v[42:43], v[48:49] op_sel:[1,1,0] op_sel_hi:[1,0,1] neg_lo:[0,1,0]
	ds_write2_b64 v60, v[34:35], v[24:25] offset0:34 offset1:51
	v_pk_mul_f32 v[24:25], v[42:43], v[20:21] op_sel:[0,0] op_sel_hi:[0,1]
	v_pk_fma_f32 v[24:25], v[42:43], v[20:21], v[24:25] op_sel:[1,1,0] op_sel_hi:[1,0,1] neg_lo:[0,1,0]
	v_pk_mul_f32 v[34:35], v[46:47], v[24:25] op_sel:[0,0] op_sel_hi:[0,1]
	v_pk_mul_f32 v[42:43], v[24:25], v[20:21] op_sel:[0,0] op_sel_hi:[0,1]
	v_pk_fma_f32 v[34:35], v[46:47], v[24:25], v[34:35] op_sel:[1,1,0] op_sel_hi:[1,0,1] neg_lo:[0,1,0]
	v_pk_fma_f32 v[24:25], v[24:25], v[20:21], v[42:43] op_sel:[1,1,0] op_sel_hi:[1,0,1] neg_lo:[0,1,0]
	v_pk_mul_f32 v[42:43], v[50:51], v[24:25] op_sel:[0,0] op_sel_hi:[0,1]
	v_pk_fma_f32 v[42:43], v[50:51], v[24:25], v[42:43] op_sel:[1,1,0] op_sel_hi:[1,0,1] neg_lo:[0,1,0]
	ds_write2_b64 v60, v[34:35], v[42:43] offset0:68 offset1:85
	v_pk_mul_f32 v[34:35], v[24:25], v[20:21] op_sel:[0,0] op_sel_hi:[0,1]
	v_pk_fma_f32 v[24:25], v[24:25], v[20:21], v[34:35] op_sel:[1,1,0] op_sel_hi:[1,0,1] neg_lo:[0,1,0]
	v_pk_mul_f32 v[34:35], v[36:37], v[24:25] op_sel:[0,0] op_sel_hi:[0,1]
	v_pk_fma_f32 v[34:35], v[36:37], v[24:25], v[34:35] op_sel:[1,1,0] op_sel_hi:[1,0,1] neg_lo:[0,1,0]
	v_pk_mul_f32 v[36:37], v[24:25], v[20:21] op_sel:[0,0] op_sel_hi:[0,1]
	v_pk_fma_f32 v[24:25], v[24:25], v[20:21], v[36:37] op_sel:[1,1,0] op_sel_hi:[1,0,1] neg_lo:[0,1,0]
	v_pk_mul_f32 v[36:37], v[28:29], v[24:25] op_sel:[0,0] op_sel_hi:[0,1]
	v_pk_fma_f32 v[28:29], v[28:29], v[24:25], v[36:37] op_sel:[1,1,0] op_sel_hi:[1,0,1] neg_lo:[0,1,0]
	ds_write2_b64 v60, v[34:35], v[28:29] offset0:102 offset1:119
	v_pk_mul_f32 v[28:29], v[24:25], v[20:21] op_sel:[0,0] op_sel_hi:[0,1]
	v_pk_fma_f32 v[24:25], v[24:25], v[20:21], v[28:29] op_sel:[1,1,0] op_sel_hi:[1,0,1] neg_lo:[0,1,0]
	v_pk_mul_f32 v[28:29], v[44:45], v[24:25] op_sel:[0,0] op_sel_hi:[0,1]
	v_pk_mul_f32 v[34:35], v[24:25], v[20:21] op_sel:[0,0] op_sel_hi:[0,1]
	v_pk_fma_f32 v[28:29], v[44:45], v[24:25], v[28:29] op_sel:[1,1,0] op_sel_hi:[1,0,1] neg_lo:[0,1,0]
	v_pk_fma_f32 v[24:25], v[24:25], v[20:21], v[34:35] op_sel:[1,1,0] op_sel_hi:[1,0,1] neg_lo:[0,1,0]
	v_pk_mul_f32 v[34:35], v[40:41], v[24:25] op_sel:[0,0] op_sel_hi:[0,1]
	v_pk_fma_f32 v[34:35], v[40:41], v[24:25], v[34:35] op_sel:[1,1,0] op_sel_hi:[1,0,1] neg_lo:[0,1,0]
	ds_write2_b64 v60, v[28:29], v[34:35] offset0:136 offset1:153
	v_pk_mul_f32 v[28:29], v[24:25], v[20:21] op_sel:[0,0] op_sel_hi:[0,1]
	v_pk_fma_f32 v[24:25], v[24:25], v[20:21], v[28:29] op_sel:[1,1,0] op_sel_hi:[1,0,1] neg_lo:[0,1,0]
	v_pk_mul_f32 v[28:29], v[30:31], v[24:25] op_sel:[0,0] op_sel_hi:[0,1]
	v_pk_fma_f32 v[28:29], v[30:31], v[24:25], v[28:29] op_sel:[1,1,0] op_sel_hi:[1,0,1] neg_lo:[0,1,0]
	v_pk_mul_f32 v[30:31], v[24:25], v[20:21] op_sel:[0,0] op_sel_hi:[0,1]
	v_pk_fma_f32 v[24:25], v[24:25], v[20:21], v[30:31] op_sel:[1,1,0] op_sel_hi:[1,0,1] neg_lo:[0,1,0]
	v_pk_mul_f32 v[30:31], v[22:23], v[24:25] op_sel:[0,0] op_sel_hi:[0,1]
	v_pk_fma_f32 v[22:23], v[22:23], v[24:25], v[30:31] op_sel:[1,1,0] op_sel_hi:[1,0,1] neg_lo:[0,1,0]
	ds_write2_b64 v60, v[28:29], v[22:23] offset0:170 offset1:187
	v_pk_mul_f32 v[22:23], v[24:25], v[20:21] op_sel:[0,0] op_sel_hi:[0,1]
	v_pk_fma_f32 v[22:23], v[24:25], v[20:21], v[22:23] op_sel:[1,1,0] op_sel_hi:[1,0,1] neg_lo:[0,1,0]
	v_pk_mul_f32 v[24:25], v[38:39], v[22:23] op_sel:[0,0] op_sel_hi:[0,1]
	v_pk_mul_f32 v[28:29], v[22:23], v[20:21] op_sel:[0,0] op_sel_hi:[0,1]
	v_pk_fma_f32 v[24:25], v[38:39], v[22:23], v[24:25] op_sel:[1,1,0] op_sel_hi:[1,0,1] neg_lo:[0,1,0]
	v_pk_fma_f32 v[22:23], v[22:23], v[20:21], v[28:29] op_sel:[1,1,0] op_sel_hi:[1,0,1] neg_lo:[0,1,0]
	v_pk_mul_f32 v[28:29], v[32:33], v[22:23] op_sel:[0,0] op_sel_hi:[0,1]
	v_pk_fma_f32 v[28:29], v[32:33], v[22:23], v[28:29] op_sel:[1,1,0] op_sel_hi:[1,0,1] neg_lo:[0,1,0]
	ds_write2_b64 v60, v[24:25], v[28:29] offset0:204 offset1:221
	v_pk_mul_f32 v[24:25], v[22:23], v[20:21] op_sel:[0,0] op_sel_hi:[0,1]
	v_pk_fma_f32 v[22:23], v[22:23], v[20:21], v[24:25] op_sel:[1,1,0] op_sel_hi:[1,0,1] neg_lo:[0,1,0]
	v_pk_mul_f32 v[24:25], v[26:27], v[22:23] op_sel:[0,0] op_sel_hi:[0,1]
	v_pk_fma_f32 v[24:25], v[26:27], v[22:23], v[24:25] op_sel:[1,1,0] op_sel_hi:[1,0,1] neg_lo:[0,1,0]
	v_pk_mul_f32 v[26:27], v[22:23], v[20:21] op_sel:[0,0] op_sel_hi:[0,1]
	v_pk_fma_f32 v[20:21], v[22:23], v[20:21], v[26:27] op_sel:[1,1,0] op_sel_hi:[1,0,1] neg_lo:[0,1,0]
	v_pk_mul_f32 v[22:23], v[18:19], v[20:21] op_sel:[0,0] op_sel_hi:[0,1]
	v_pk_fma_f32 v[18:19], v[18:19], v[20:21], v[22:23] op_sel:[1,1,0] op_sel_hi:[1,0,1] neg_lo:[0,1,0]
	ds_write2_b64 v60, v[24:25], v[18:19] offset0:238 offset1:255
	s_waitcnt lgkmcnt(0)
	s_barrier
	ds_read2_b64 v[18:21], v64 offset1:1
	ds_read2_b64 v[22:25], v64 offset0:2 offset1:3
	ds_read2_b64 v[26:29], v64 offset0:8 offset1:9
	ds_read2_b64 v[30:33], v64 offset0:4 offset1:5
	ds_read2_b64 v[34:37], v64 offset0:6 offset1:7
	ds_read2_b64 v[38:41], v64 offset0:12 offset1:13
	ds_read2_b64 v[42:45], v64 offset0:10 offset1:11
	ds_read2_b64 v[46:49], v64 offset0:14 offset1:15
	s_waitcnt lgkmcnt(5)
	v_pk_add_f32 v[50:51], v[18:19], v[26:27]
	v_pk_add_f32 v[18:19], v[18:19], v[26:27] neg_lo:[0,1] neg_hi:[0,1]
	s_waitcnt lgkmcnt(2)
	v_pk_add_f32 v[26:27], v[30:31], v[38:39]
	v_pk_add_f32 v[30:31], v[30:31], v[38:39] neg_lo:[0,1] neg_hi:[0,1]
	v_pk_add_f32 v[38:39], v[50:51], v[26:27]
	v_pk_add_f32 v[26:27], v[50:51], v[26:27] neg_lo:[0,1] neg_hi:[0,1]
	v_pk_add_f32 v[50:51], v[18:19], v[30:31] op_sel:[0,1] op_sel_hi:[1,0] neg_hi:[0,1]
	v_pk_add_f32 v[18:19], v[18:19], v[30:31] op_sel:[0,1] op_sel_hi:[1,0] neg_lo:[0,1]
	v_pk_add_f32 v[30:31], v[20:21], v[28:29]
	v_pk_add_f32 v[20:21], v[20:21], v[28:29] neg_lo:[0,1] neg_hi:[0,1]
	v_pk_add_f32 v[28:29], v[32:33], v[40:41]
	v_pk_add_f32 v[32:33], v[32:33], v[40:41] neg_lo:[0,1] neg_hi:[0,1]
	v_pk_add_f32 v[40:41], v[30:31], v[28:29]
	v_pk_add_f32 v[28:29], v[30:31], v[28:29] neg_lo:[0,1] neg_hi:[0,1]
	v_pk_add_f32 v[30:31], v[20:21], v[32:33] op_sel:[0,1] op_sel_hi:[1,0] neg_hi:[0,1]
	v_pk_add_f32 v[20:21], v[20:21], v[32:33] op_sel:[0,1] op_sel_hi:[1,0] neg_lo:[0,1]
	s_waitcnt lgkmcnt(1)
	v_pk_add_f32 v[32:33], v[22:23], v[42:43]
	v_pk_add_f32 v[22:23], v[22:23], v[42:43] neg_lo:[0,1] neg_hi:[0,1]
	s_waitcnt lgkmcnt(0)
	v_pk_add_f32 v[42:43], v[34:35], v[46:47]
	v_pk_add_f32 v[34:35], v[34:35], v[46:47] neg_lo:[0,1] neg_hi:[0,1]
	v_pk_add_f32 v[46:47], v[32:33], v[42:43]
	v_pk_add_f32 v[32:33], v[32:33], v[42:43] neg_lo:[0,1] neg_hi:[0,1]
	v_pk_add_f32 v[42:43], v[22:23], v[34:35] op_sel:[0,1] op_sel_hi:[1,0] neg_hi:[0,1]
	v_pk_add_f32 v[22:23], v[22:23], v[34:35] op_sel:[0,1] op_sel_hi:[1,0] neg_lo:[0,1]
	v_pk_add_f32 v[34:35], v[24:25], v[44:45]
	v_pk_add_f32 v[24:25], v[24:25], v[44:45] neg_lo:[0,1] neg_hi:[0,1]
	v_pk_add_f32 v[44:45], v[36:37], v[48:49]
	v_pk_add_f32 v[36:37], v[36:37], v[48:49] neg_lo:[0,1] neg_hi:[0,1]
	v_pk_add_f32 v[48:49], v[34:35], v[44:45]
	v_pk_add_f32 v[34:35], v[34:35], v[44:45] neg_lo:[0,1] neg_hi:[0,1]
	v_pk_add_f32 v[44:45], v[24:25], v[36:37] op_sel:[0,1] op_sel_hi:[1,0] neg_hi:[0,1]
	v_pk_add_f32 v[24:25], v[24:25], v[36:37] op_sel:[0,1] op_sel_hi:[1,0] neg_lo:[0,1]
	v_pk_mul_f32 v[36:37], v[30:31], s[20:21] op_sel:[0,0] op_sel_hi:[0,1]
	v_pk_fma_f32 v[8:9], v[30:31], s[20:21], v[36:37] op_sel:[1,1,0] op_sel_hi:[1,0,1] neg_lo:[0,1,0]
	v_pk_mul_f32 v[30:31], v[42:43], v[4:5] op_sel:[0,0] op_sel_hi:[0,1]
	v_pk_mul_f32 v[36:37], v[44:45], v[2:3] op_sel:[0,0] op_sel_hi:[0,1]
	s_barrier
	v_pk_fma_f32 v[30:31], v[42:43], v[4:5], v[30:31] op_sel:[1,1,0] op_sel_hi:[1,0,1] neg_lo:[0,1,0]
	v_pk_mul_f32 v[42:43], v[28:29], v[4:5] op_sel:[0,0] op_sel_hi:[0,1]
	v_pk_fma_f32 v[36:37], v[44:45], v[2:3], v[36:37] op_sel:[1,1,0] op_sel_hi:[1,0,1] neg_lo:[0,1,0]
	v_pk_fma_f32 v[4:5], v[28:29], v[4:5], v[42:43] op_sel:[1,1,0] op_sel_hi:[1,0,1] neg_lo:[0,1,0]
	v_pk_mul_f32 v[28:29], v[32:33], v[14:15] op_sel:[0,0] op_sel_hi:[0,1]
	v_pk_fma_f32 v[14:15], v[32:33], v[14:15], v[28:29] op_sel:[1,1,0] op_sel_hi:[1,0,1] neg_lo:[0,1,0]
	v_pk_mul_f32 v[28:29], v[34:35], v[6:7] op_sel:[0,0] op_sel_hi:[0,1]
	v_pk_mul_f32 v[32:33], v[20:21], v[2:3] op_sel:[0,0] op_sel_hi:[0,1]
	v_pk_fma_f32 v[2:3], v[20:21], v[2:3], v[32:33] op_sel:[1,1,0] op_sel_hi:[1,0,1] neg_lo:[0,1,0]
	v_pk_mul_f32 v[20:21], v[22:23], v[6:7] op_sel:[0,0] op_sel_hi:[0,1]
	v_pk_fma_f32 v[28:29], v[34:35], v[6:7], v[28:29] op_sel:[1,1,0] op_sel_hi:[1,0,1] neg_lo:[0,1,0]
	v_pk_add_f32 v[32:33], v[40:41], v[48:49] neg_lo:[0,1] neg_hi:[0,1]
	v_pk_fma_f32 v[6:7], v[22:23], v[6:7], v[20:21] op_sel:[1,1,0] op_sel_hi:[1,0,1] neg_lo:[0,1,0]
	v_pk_mul_f32 v[20:21], v[24:25], s[46:47] op_sel:[0,0] op_sel_hi:[0,1]
	v_pk_add_f32 v[22:23], v[38:39], v[46:47] neg_lo:[0,1] neg_hi:[0,1]
	v_pk_fma_f32 v[16:17], v[24:25], s[46:47], v[20:21] op_sel:[1,1,0] op_sel_hi:[1,0,1] neg_lo:[0,1,0]
	v_pk_add_f32 v[20:21], v[38:39], v[46:47]
	v_pk_add_f32 v[24:25], v[40:41], v[48:49]
	v_pk_add_f32 v[38:39], v[8:9], v[36:37]
	v_pk_add_f32 v[34:35], v[20:21], v[24:25]
	v_pk_add_f32 v[20:21], v[20:21], v[24:25] neg_lo:[0,1] neg_hi:[0,1]
	v_pk_add_f32 v[24:25], v[22:23], v[32:33] op_sel:[0,1] op_sel_hi:[1,0] neg_hi:[0,1]
	v_pk_add_f32 v[22:23], v[22:23], v[32:33] op_sel:[0,1] op_sel_hi:[1,0] neg_lo:[0,1]
	v_pk_add_f32 v[32:33], v[50:51], v[30:31]
	v_pk_add_f32 v[30:31], v[50:51], v[30:31] neg_lo:[0,1] neg_hi:[0,1]
	v_pk_add_f32 v[8:9], v[8:9], v[36:37] neg_lo:[0,1] neg_hi:[0,1]
	v_pk_add_f32 v[36:37], v[32:33], v[38:39]
	v_pk_add_f32 v[32:33], v[32:33], v[38:39] neg_lo:[0,1] neg_hi:[0,1]
	v_pk_add_f32 v[38:39], v[30:31], v[8:9] op_sel:[0,1] op_sel_hi:[1,0] neg_hi:[0,1]
	v_pk_add_f32 v[8:9], v[30:31], v[8:9] op_sel:[0,1] op_sel_hi:[1,0] neg_lo:[0,1]
	v_pk_add_f32 v[30:31], v[26:27], v[14:15]
	v_pk_add_f32 v[14:15], v[26:27], v[14:15] neg_lo:[0,1] neg_hi:[0,1]
	v_pk_add_f32 v[26:27], v[4:5], v[28:29]
	v_pk_add_f32 v[4:5], v[4:5], v[28:29] neg_lo:[0,1] neg_hi:[0,1]
	v_pk_add_f32 v[28:29], v[30:31], v[26:27]
	v_pk_add_f32 v[26:27], v[30:31], v[26:27] neg_lo:[0,1] neg_hi:[0,1]
	v_pk_add_f32 v[30:31], v[14:15], v[4:5] op_sel:[0,1] op_sel_hi:[1,0] neg_hi:[0,1]
	v_pk_add_f32 v[4:5], v[14:15], v[4:5] op_sel:[0,1] op_sel_hi:[1,0] neg_lo:[0,1]
	v_pk_add_f32 v[14:15], v[18:19], v[6:7]
	v_pk_add_f32 v[6:7], v[18:19], v[6:7] neg_lo:[0,1] neg_hi:[0,1]
	v_pk_add_f32 v[18:19], v[2:3], v[16:17]
	v_pk_add_f32 v[2:3], v[2:3], v[16:17] neg_lo:[0,1] neg_hi:[0,1]
	v_pk_add_f32 v[16:17], v[14:15], v[18:19]
	v_pk_add_f32 v[14:15], v[14:15], v[18:19] neg_lo:[0,1] neg_hi:[0,1]
	v_pk_add_f32 v[18:19], v[6:7], v[2:3] op_sel:[0,1] op_sel_hi:[1,0] neg_hi:[0,1]
	v_pk_add_f32 v[2:3], v[6:7], v[2:3] op_sel:[0,1] op_sel_hi:[1,0] neg_lo:[0,1]
	v_add_f32_e32 v6, 0x358637bd, v10
	v_mul_f32_e32 v6, 0x46000000, v6
	v_div_scale_f32 v7, s[28:29], v6, v6, 1.0
	v_rcp_f32_e32 v10, v7
	s_nop 0
	v_fma_f32 v40, -v7, v10, 1.0
	v_fmac_f32_e32 v10, v40, v10
	v_div_scale_f32 v40, vcc, 1.0, v6, 1.0
	v_mul_f32_e32 v41, v40, v10
	v_fma_f32 v42, -v7, v41, v40
	v_fmac_f32_e32 v41, v42, v10
	v_fma_f32 v7, -v7, v41, v40
	v_div_fmas_f32 v7, v7, v10, v41
	v_div_fixup_f32 v6, v7, v6, 1.0
	v_pk_mul_f32 v[34:35], v[6:7], v[34:35] op_sel_hi:[0,1]
	v_pk_mul_f32 v[24:25], v[6:7], v[24:25] op_sel_hi:[0,1]
	v_pk_mul_f32 v[20:21], v[6:7], v[20:21] op_sel_hi:[0,1]
	v_pk_mul_f32 v[22:23], v[6:7], v[22:23] op_sel_hi:[0,1]
	v_pk_mul_f32 v[36:37], v[6:7], v[36:37] op_sel_hi:[0,1]
	v_pk_mul_f32 v[38:39], v[6:7], v[38:39] op_sel_hi:[0,1]
	v_pk_mul_f32 v[32:33], v[6:7], v[32:33] op_sel_hi:[0,1]
	v_pk_mul_f32 v[8:9], v[6:7], v[8:9] op_sel_hi:[0,1]
	v_pk_mul_f32 v[28:29], v[6:7], v[28:29] op_sel_hi:[0,1]
	v_pk_mul_f32 v[30:31], v[6:7], v[30:31] op_sel_hi:[0,1]
	v_pk_mul_f32 v[26:27], v[6:7], v[26:27] op_sel_hi:[0,1]
	v_pk_mul_f32 v[4:5], v[6:7], v[4:5] op_sel_hi:[0,1]
	v_pk_mul_f32 v[16:17], v[6:7], v[16:17] op_sel_hi:[0,1]
	v_pk_mul_f32 v[18:19], v[6:7], v[18:19] op_sel_hi:[0,1]
	v_pk_mul_f32 v[14:15], v[6:7], v[14:15] op_sel_hi:[0,1]
	v_pk_mul_f32 v[2:3], v[6:7], v[2:3] op_sel_hi:[0,1]
	v_lshl_add_u64 v[6:7], s[12:13], 3, v[12:13]
	global_store_dwordx2 v[6:7], v[34:35], off
	v_add_co_u32_e32 v34, vcc, s57, v6
	s_nop 1
	v_addc_co_u32_e32 v35, vcc, 0, v7, vcc
	global_store_dwordx2 v[34:35], v[24:25], off offset:-4096
	global_store_dwordx2 v[34:35], v[20:21], off
	v_add_co_u32_e32 v20, vcc, s58, v6
	s_nop 1
	v_addc_co_u32_e32 v21, vcc, 0, v7, vcc
	global_store_dwordx2 v[20:21], v[22:23], off offset:-4096
	global_store_dwordx2 v[20:21], v[36:37], off
	v_add_co_u32_e32 v20, vcc, s59, v6
	s_nop 1
	v_addc_co_u32_e32 v21, vcc, 0, v7, vcc
	global_store_dwordx2 v[20:21], v[38:39], off offset:-4096
	global_store_dwordx2 v[20:21], v[32:33], off
	v_add_co_u32_e32 v20, vcc, s60, v6
	s_nop 1
	v_addc_co_u32_e32 v21, vcc, 0, v7, vcc
	global_store_dwordx2 v[20:21], v[8:9], off offset:-4096
	global_store_dwordx2 v[20:21], v[28:29], off
	v_add_co_u32_e32 v8, vcc, s61, v6
	s_nop 1
	v_addc_co_u32_e32 v9, vcc, 0, v7, vcc
	global_store_dwordx2 v[8:9], v[30:31], off offset:-4096
	global_store_dwordx2 v[8:9], v[26:27], off
	v_add_co_u32_e32 v8, vcc, s62, v6
	s_nop 1
	v_addc_co_u32_e32 v9, vcc, 0, v7, vcc
	global_store_dwordx2 v[8:9], v[4:5], off offset:-4096
	global_store_dwordx2 v[8:9], v[16:17], off
	v_add_co_u32_e32 v4, vcc, s63, v6
	s_nop 1
	v_addc_co_u32_e32 v5, vcc, 0, v7, vcc
	global_store_dwordx2 v[4:5], v[18:19], off
	v_add_co_u32_e32 v4, vcc, 0xe000, v6
	s_nop 1
	v_addc_co_u32_e32 v5, vcc, 0, v7, vcc
	global_store_dwordx2 v[4:5], v[14:15], off
	v_add_co_u32_e32 v4, vcc, 0xf000, v6
	s_nop 1
	v_addc_co_u32_e32 v5, vcc, 0, v7, vcc
	s_and_b64 vcc, exec, s[50:51]
	global_store_dwordx2 v[4:5], v[2:3], off
	s_barrier
	s_cbranch_vccnz .LBB0_3098

.LBB0_3363:
	s_or_b64 exec, exec, s[0:1]
	v_pk_add_f32 v[44:45], v[42:43], v[60:61]
	v_pk_add_f32 v[42:43], v[42:43], v[60:61] neg_lo:[0,1] neg_hi:[0,1]
	v_pk_add_f32 v[60:61], v[52:53], v[68:69]
	v_pk_add_f32 v[52:53], v[52:53], v[68:69] neg_lo:[0,1] neg_hi:[0,1]
	v_pk_add_f32 v[68:69], v[44:45], v[60:61]
	v_pk_add_f32 v[60:61], v[44:45], v[60:61] neg_lo:[0,1] neg_hi:[0,1]
	s_waitcnt lgkmcnt(1)
	v_pk_add_f32 v[76:77], v[42:43], v[52:53] op_sel:[0,1] op_sel_hi:[1,0] neg_hi:[0,1]
	s_waitcnt lgkmcnt(0)
	v_pk_add_f32 v[78:79], v[42:43], v[52:53] op_sel:[0,1] op_sel_hi:[1,0] neg_lo:[0,1]
	v_pk_add_f32 v[42:43], v[46:47], v[62:63]
	v_pk_add_f32 v[44:45], v[46:47], v[62:63] neg_lo:[0,1] neg_hi:[0,1]
	v_pk_add_f32 v[46:47], v[54:55], v[70:71]
	v_pk_add_f32 v[52:53], v[54:55], v[70:71] neg_lo:[0,1] neg_hi:[0,1]
	v_pk_add_f32 v[54:55], v[42:43], v[46:47]
	v_pk_add_f32 v[46:47], v[42:43], v[46:47] neg_lo:[0,1] neg_hi:[0,1]
	v_pk_add_f32 v[42:43], v[44:45], v[52:53] op_sel:[0,1] op_sel_hi:[1,0] neg_hi:[0,1]
	v_pk_add_f32 v[52:53], v[44:45], v[52:53] op_sel:[0,1] op_sel_hi:[1,0] neg_lo:[0,1]
	v_pk_add_f32 v[44:45], v[48:49], v[64:65]
	v_pk_add_f32 v[48:49], v[48:49], v[64:65] neg_lo:[0,1] neg_hi:[0,1]
	v_pk_add_f32 v[62:63], v[56:57], v[72:73]
	v_pk_add_f32 v[56:57], v[56:57], v[72:73] neg_lo:[0,1] neg_hi:[0,1]
	v_pk_add_f32 v[64:65], v[44:45], v[62:63]
	v_pk_add_f32 v[62:63], v[44:45], v[62:63] neg_lo:[0,1] neg_hi:[0,1]
	v_pk_add_f32 v[70:71], v[48:49], v[56:57] op_sel:[0,1] op_sel_hi:[1,0] neg_hi:[0,1]
	v_pk_add_f32 v[56:57], v[48:49], v[56:57] op_sel:[0,1] op_sel_hi:[1,0] neg_lo:[0,1]
	v_pk_add_f32 v[44:45], v[50:51], v[66:67]
	v_pk_add_f32 v[48:49], v[50:51], v[66:67] neg_lo:[0,1] neg_hi:[0,1]
	v_pk_add_f32 v[50:51], v[58:59], v[74:75]
	v_pk_add_f32 v[58:59], v[58:59], v[74:75] neg_lo:[0,1] neg_hi:[0,1]
	v_pk_add_f32 v[66:67], v[44:45], v[50:51]
	v_pk_add_f32 v[72:73], v[44:45], v[50:51] neg_lo:[0,1] neg_hi:[0,1]
	v_pk_add_f32 v[50:51], v[48:49], v[58:59] op_sel:[0,1] op_sel_hi:[1,0] neg_hi:[0,1]
	v_pk_add_f32 v[58:59], v[48:49], v[58:59] op_sel:[0,1] op_sel_hi:[1,0] neg_lo:[0,1]
	v_pk_mul_f32 v[44:45], v[42:43], s[20:21] op_sel:[0,0] op_sel_hi:[0,1]
	v_pk_fma_f32 v[74:75], v[42:43], s[20:21], v[44:45] op_sel:[1,1,0] op_sel_hi:[1,0,1] neg_lo:[0,1,0]
	v_mov_b64_e32 v[44:45], s[46:47]
	v_pk_mul_f32 v[42:43], v[70:71], v[44:45] op_sel:[0,0] op_sel_hi:[0,1]
	s_barrier
	v_pk_fma_f32 v[70:71], v[70:71], v[44:45], v[42:43] op_sel:[1,1,0] op_sel_hi:[1,0,1] neg_lo:[0,1,0]
	v_mov_b64_e32 v[42:43], s[50:51]
	s_waitcnt vmcnt(5)
	v_pk_mul_f32 v[80:81], v[50:51], v[42:43] op_sel:[0,0] op_sel_hi:[0,1]
	v_pk_fma_f32 v[80:81], v[50:51], v[42:43], v[80:81] op_sel:[1,1,0] op_sel_hi:[1,0,1] neg_lo:[0,1,0]
	v_pk_mul_f32 v[50:51], v[46:47], v[44:45] op_sel:[0,0] op_sel_hi:[0,1]
	s_lshl_b64 s[0:1], s[70:71], 14
	v_pk_fma_f32 v[82:83], v[46:47], v[44:45], v[50:51] op_sel:[1,1,0] op_sel_hi:[1,0,1] neg_lo:[0,1,0]
	v_pk_mul_f32 v[46:47], v[62:63], s[8:9] op_sel:[0,0] op_sel_hi:[0,1]
	s_add_u32 s0, s96, s0
	v_pk_fma_f32 v[62:63], v[62:63], s[8:9], v[46:47] op_sel:[1,1,0] op_sel_hi:[1,0,1] neg_lo:[0,1,0]
	s_waitcnt vmcnt(4)
	v_pk_mul_f32 v[84:85], v[72:73], s[54:55] op_sel:[0,0] op_sel_hi:[0,1]
	v_lshlrev_b32_e32 v34, 14, v133
	v_pk_fma_f32 v[72:73], v[72:73], s[54:55], v[84:85] op_sel:[1,1,0] op_sel_hi:[1,0,1] neg_lo:[0,1,0]
	v_pk_mul_f32 v[84:85], v[52:53], v[42:43] op_sel:[0,0] op_sel_hi:[0,1]
	s_addc_u32 s1, s97, s1
	v_pk_fma_f32 v[84:85], v[52:53], v[42:43], v[84:85] op_sel:[1,1,0] op_sel_hi:[1,0,1] neg_lo:[0,1,0]
	v_pk_mul_f32 v[52:53], v[56:57], s[54:55] op_sel:[0,0] op_sel_hi:[0,1]
	v_and_b32_e32 v139, 0xffc00000, v34
	v_pk_fma_f32 v[56:57], v[56:57], s[54:55], v[52:53] op_sel:[1,1,0] op_sel_hi:[1,0,1] neg_lo:[0,1,0]
	v_pk_mul_f32 v[86:87], v[58:59], s[56:57] op_sel:[0,0] op_sel_hi:[0,1]
	s_add_u32 s0, s0, 0x2000000
	v_pk_fma_f32 v[58:59], v[58:59], s[56:57], v[86:87] op_sel:[1,1,0] op_sel_hi:[1,0,1] neg_lo:[0,1,0]
	v_pk_add_f32 v[86:87], v[68:69], v[64:65]
	v_pk_add_f32 v[64:65], v[68:69], v[64:65] neg_lo:[0,1] neg_hi:[0,1]
	v_pk_add_f32 v[68:69], v[54:55], v[66:67]
	v_pk_add_f32 v[54:55], v[54:55], v[66:67] neg_lo:[0,1] neg_hi:[0,1]
	v_pk_add_f32 v[66:67], v[86:87], v[68:69]
	v_pk_add_f32 v[68:69], v[86:87], v[68:69] neg_lo:[0,1] neg_hi:[0,1]
	v_pk_add_f32 v[86:87], v[64:65], v[54:55] op_sel:[0,1] op_sel_hi:[1,0] neg_hi:[0,1]
	v_pk_add_f32 v[54:55], v[64:65], v[54:55] op_sel:[0,1] op_sel_hi:[1,0] neg_lo:[0,1]
	v_pk_add_f32 v[64:65], v[76:77], v[70:71]
	v_pk_add_f32 v[70:71], v[76:77], v[70:71] neg_lo:[0,1] neg_hi:[0,1]
	v_pk_add_f32 v[76:77], v[74:75], v[80:81]
	v_pk_add_f32 v[74:75], v[74:75], v[80:81] neg_lo:[0,1] neg_hi:[0,1]
	v_pk_add_f32 v[80:81], v[64:65], v[76:77]
	v_pk_add_f32 v[64:65], v[64:65], v[76:77] neg_lo:[0,1] neg_hi:[0,1]
	v_pk_add_f32 v[76:77], v[70:71], v[74:75] op_sel:[0,1] op_sel_hi:[1,0] neg_hi:[0,1]
	v_pk_add_f32 v[70:71], v[70:71], v[74:75] op_sel:[0,1] op_sel_hi:[1,0] neg_lo:[0,1]
	v_pk_add_f32 v[74:75], v[60:61], v[62:63]
	v_pk_add_f32 v[60:61], v[60:61], v[62:63] neg_lo:[0,1] neg_hi:[0,1]
	v_pk_add_f32 v[62:63], v[82:83], v[72:73]
	v_pk_add_f32 v[72:73], v[82:83], v[72:73] neg_lo:[0,1] neg_hi:[0,1]
	v_pk_add_f32 v[82:83], v[74:75], v[62:63]
	v_pk_add_f32 v[62:63], v[74:75], v[62:63] neg_lo:[0,1] neg_hi:[0,1]
	v_pk_add_f32 v[74:75], v[60:61], v[72:73] op_sel:[0,1] op_sel_hi:[1,0] neg_hi:[0,1]
	v_pk_add_f32 v[60:61], v[60:61], v[72:73] op_sel:[0,1] op_sel_hi:[1,0] neg_lo:[0,1]
	v_pk_add_f32 v[72:73], v[78:79], v[56:57]
	v_pk_add_f32 v[56:57], v[78:79], v[56:57] neg_lo:[0,1] neg_hi:[0,1]
	v_pk_add_f32 v[78:79], v[84:85], v[58:59]
	v_pk_add_f32 v[58:59], v[84:85], v[58:59] neg_lo:[0,1] neg_hi:[0,1]
	v_pk_add_f32 v[84:85], v[72:73], v[78:79]
	v_pk_add_f32 v[72:73], v[72:73], v[78:79] neg_lo:[0,1] neg_hi:[0,1]
	v_pk_add_f32 v[78:79], v[56:57], v[58:59] op_sel:[0,1] op_sel_hi:[1,0] neg_hi:[0,1]
	v_pk_add_f32 v[56:57], v[56:57], v[58:59] op_sel:[0,1] op_sel_hi:[1,0] neg_lo:[0,1]
	v_xor_b32_e32 v59, 0x80000000, v39
	v_mov_b32_e32 v58, v38
	ds_write_b64 v132, v[66:67]
	v_pk_mul_f32 v[66:67], v[80:81], v[58:59] op_sel:[0,0] op_sel_hi:[0,1]
	s_addc_u32 s1, s1, 0
	v_pk_fma_f32 v[66:67], v[80:81], v[58:59], v[66:67] op_sel:[1,1,0] op_sel_hi:[1,0,1] neg_lo:[0,1,0]
	ds_write_b64 v132, v[66:67] offset:2176
	v_pk_mul_f32 v[66:67], v[58:59], v[58:59] op_sel:[0,0] op_sel_hi:[0,1]
	v_pk_fma_f32 v[66:67], v[58:59], v[58:59], v[66:67] op_sel:[1,1,0] op_sel_hi:[1,0,1] neg_lo:[0,1,0]
	v_pk_mul_f32 v[80:81], v[82:83], v[66:67] op_sel:[0,0] op_sel_hi:[0,1]
	v_pk_fma_f32 v[80:81], v[82:83], v[66:67], v[80:81] op_sel:[1,1,0] op_sel_hi:[1,0,1] neg_lo:[0,1,0]
	ds_write_b64 v132, v[80:81] offset:4352
	v_pk_mul_f32 v[80:81], v[66:67], v[58:59] op_sel:[0,0] op_sel_hi:[0,1]
	v_pk_fma_f32 v[66:67], v[66:67], v[58:59], v[80:81] op_sel:[1,1,0] op_sel_hi:[1,0,1] neg_lo:[0,1,0]
	v_pk_mul_f32 v[80:81], v[84:85], v[66:67] op_sel:[0,0] op_sel_hi:[0,1]
	v_pk_fma_f32 v[80:81], v[84:85], v[66:67], v[80:81] op_sel:[1,1,0] op_sel_hi:[1,0,1] neg_lo:[0,1,0]
	ds_write_b64 v132, v[80:81] offset:6528
	v_pk_mul_f32 v[80:81], v[66:67], v[58:59] op_sel:[0,0] op_sel_hi:[0,1]
	v_pk_fma_f32 v[66:67], v[66:67], v[58:59], v[80:81] op_sel:[1,1,0] op_sel_hi:[1,0,1] neg_lo:[0,1,0]
	v_pk_mul_f32 v[80:81], v[86:87], v[66:67] op_sel:[0,0] op_sel_hi:[0,1]
	v_pk_fma_f32 v[80:81], v[86:87], v[66:67], v[80:81] op_sel:[1,1,0] op_sel_hi:[1,0,1] neg_lo:[0,1,0]
	ds_write_b64 v132, v[80:81] offset:8704
	v_pk_mul_f32 v[80:81], v[66:67], v[58:59] op_sel:[0,0] op_sel_hi:[0,1]
	v_pk_fma_f32 v[66:67], v[66:67], v[58:59], v[80:81] op_sel:[1,1,0] op_sel_hi:[1,0,1] neg_lo:[0,1,0]
	v_pk_mul_f32 v[80:81], v[76:77], v[66:67] op_sel:[0,0] op_sel_hi:[0,1]
	v_pk_fma_f32 v[76:77], v[76:77], v[66:67], v[80:81] op_sel:[1,1,0] op_sel_hi:[1,0,1] neg_lo:[0,1,0]
	ds_write_b64 v132, v[76:77] offset:10880
	v_pk_mul_f32 v[76:77], v[66:67], v[58:59] op_sel:[0,0] op_sel_hi:[0,1]
	v_pk_fma_f32 v[66:67], v[66:67], v[58:59], v[76:77] op_sel:[1,1,0] op_sel_hi:[1,0,1] neg_lo:[0,1,0]
	v_pk_mul_f32 v[76:77], v[74:75], v[66:67] op_sel:[0,0] op_sel_hi:[0,1]
	v_pk_fma_f32 v[74:75], v[74:75], v[66:67], v[76:77] op_sel:[1,1,0] op_sel_hi:[1,0,1] neg_lo:[0,1,0]
	ds_write_b64 v132, v[74:75] offset:13056
	v_pk_mul_f32 v[74:75], v[66:67], v[58:59] op_sel:[0,0] op_sel_hi:[0,1]
	v_pk_fma_f32 v[66:67], v[66:67], v[58:59], v[74:75] op_sel:[1,1,0] op_sel_hi:[1,0,1] neg_lo:[0,1,0]
	v_pk_mul_f32 v[74:75], v[78:79], v[66:67] op_sel:[0,0] op_sel_hi:[0,1]
	v_pk_fma_f32 v[74:75], v[78:79], v[66:67], v[74:75] op_sel:[1,1,0] op_sel_hi:[1,0,1] neg_lo:[0,1,0]
	ds_write_b64 v132, v[74:75] offset:15232
	v_pk_mul_f32 v[74:75], v[66:67], v[58:59] op_sel:[0,0] op_sel_hi:[0,1]
	v_pk_fma_f32 v[66:67], v[66:67], v[58:59], v[74:75] op_sel:[1,1,0] op_sel_hi:[1,0,1] neg_lo:[0,1,0]
	v_pk_mul_f32 v[74:75], v[68:69], v[66:67] op_sel:[0,0] op_sel_hi:[0,1]
	v_pk_fma_f32 v[68:69], v[68:69], v[66:67], v[74:75] op_sel:[1,1,0] op_sel_hi:[1,0,1] neg_lo:[0,1,0]
	ds_write_b64 v132, v[68:69] offset:17408
	v_pk_mul_f32 v[68:69], v[66:67], v[58:59] op_sel:[0,0] op_sel_hi:[0,1]
	v_pk_fma_f32 v[66:67], v[66:67], v[58:59], v[68:69] op_sel:[1,1,0] op_sel_hi:[1,0,1] neg_lo:[0,1,0]
	v_pk_mul_f32 v[68:69], v[64:65], v[66:67] op_sel:[0,0] op_sel_hi:[0,1]
	v_pk_fma_f32 v[64:65], v[64:65], v[66:67], v[68:69] op_sel:[1,1,0] op_sel_hi:[1,0,1] neg_lo:[0,1,0]
	ds_write_b64 v132, v[64:65] offset:19584
	v_pk_mul_f32 v[64:65], v[66:67], v[58:59] op_sel:[0,0] op_sel_hi:[0,1]
	v_pk_fma_f32 v[64:65], v[66:67], v[58:59], v[64:65] op_sel:[1,1,0] op_sel_hi:[1,0,1] neg_lo:[0,1,0]
	v_pk_mul_f32 v[66:67], v[62:63], v[64:65] op_sel:[0,0] op_sel_hi:[0,1]
	v_pk_fma_f32 v[62:63], v[62:63], v[64:65], v[66:67] op_sel:[1,1,0] op_sel_hi:[1,0,1] neg_lo:[0,1,0]
	ds_write_b64 v132, v[62:63] offset:21760
	v_pk_mul_f32 v[62:63], v[64:65], v[58:59] op_sel:[0,0] op_sel_hi:[0,1]
	v_pk_fma_f32 v[62:63], v[64:65], v[58:59], v[62:63] op_sel:[1,1,0] op_sel_hi:[1,0,1] neg_lo:[0,1,0]
	v_pk_mul_f32 v[64:65], v[72:73], v[62:63] op_sel:[0,0] op_sel_hi:[0,1]
	v_pk_fma_f32 v[64:65], v[72:73], v[62:63], v[64:65] op_sel:[1,1,0] op_sel_hi:[1,0,1] neg_lo:[0,1,0]
	ds_write_b64 v132, v[64:65] offset:23936
	v_pk_mul_f32 v[64:65], v[62:63], v[58:59] op_sel:[0,0] op_sel_hi:[0,1]
	v_pk_fma_f32 v[62:63], v[62:63], v[58:59], v[64:65] op_sel:[1,1,0] op_sel_hi:[1,0,1] neg_lo:[0,1,0]
	v_pk_mul_f32 v[64:65], v[54:55], v[62:63] op_sel:[0,0] op_sel_hi:[0,1]
	v_pk_fma_f32 v[54:55], v[54:55], v[62:63], v[64:65] op_sel:[1,1,0] op_sel_hi:[1,0,1] neg_lo:[0,1,0]
	ds_write_b64 v132, v[54:55] offset:26112
	v_pk_mul_f32 v[54:55], v[62:63], v[58:59] op_sel:[0,0] op_sel_hi:[0,1]
	v_pk_fma_f32 v[54:55], v[62:63], v[58:59], v[54:55] op_sel:[1,1,0] op_sel_hi:[1,0,1] neg_lo:[0,1,0]
	v_pk_mul_f32 v[62:63], v[70:71], v[54:55] op_sel:[0,0] op_sel_hi:[0,1]
	v_pk_fma_f32 v[62:63], v[70:71], v[54:55], v[62:63] op_sel:[1,1,0] op_sel_hi:[1,0,1] neg_lo:[0,1,0]
	ds_write_b64 v132, v[62:63] offset:28288
	v_pk_mul_f32 v[62:63], v[54:55], v[58:59] op_sel:[0,0] op_sel_hi:[0,1]
	v_pk_fma_f32 v[54:55], v[54:55], v[58:59], v[62:63] op_sel:[1,1,0] op_sel_hi:[1,0,1] neg_lo:[0,1,0]
	v_pk_mul_f32 v[62:63], v[60:61], v[54:55] op_sel:[0,0] op_sel_hi:[0,1]
	v_pk_fma_f32 v[60:61], v[60:61], v[54:55], v[62:63] op_sel:[1,1,0] op_sel_hi:[1,0,1] neg_lo:[0,1,0]
	ds_write_b64 v132, v[60:61] offset:30464
	v_pk_mul_f32 v[60:61], v[54:55], v[58:59] op_sel:[0,0] op_sel_hi:[0,1]
	v_pk_fma_f32 v[54:55], v[54:55], v[58:59], v[60:61] op_sel:[1,1,0] op_sel_hi:[1,0,1] neg_lo:[0,1,0]
	v_pk_mul_f32 v[58:59], v[56:57], v[54:55] op_sel:[0,0] op_sel_hi:[0,1]
	v_pk_fma_f32 v[54:55], v[56:57], v[54:55], v[58:59] op_sel:[1,1,0] op_sel_hi:[1,0,1] neg_lo:[0,1,0]
	ds_write_b64 v132, v[54:55] offset:32640
	s_waitcnt lgkmcnt(0)
	s_barrier
	ds_read2_b64 v[54:57], v134 offset1:17
	ds_read2_b64 v[58:61], v134 offset0:34 offset1:51
	ds_read2_b64 v[62:65], v134 offset0:68 offset1:85
	ds_read2_b64 v[66:69], v134 offset0:136 offset1:153
	ds_read2_b64 v[70:73], v134 offset0:102 offset1:119
	ds_read2_b64 v[74:77], v134 offset0:204 offset1:221
	ds_read2_b64 v[78:81], v134 offset0:170 offset1:187
	ds_read2_b64 v[82:85], v134 offset0:238 offset1:255
	s_waitcnt lgkmcnt(4)
	v_pk_add_f32 v[86:87], v[54:55], v[66:67]
	v_pk_add_f32 v[54:55], v[54:55], v[66:67] neg_lo:[0,1] neg_hi:[0,1]
	s_waitcnt lgkmcnt(2)
	v_pk_add_f32 v[66:67], v[62:63], v[74:75]
	v_pk_add_f32 v[62:63], v[62:63], v[74:75] neg_lo:[0,1] neg_hi:[0,1]
	v_pk_add_f32 v[74:75], v[86:87], v[66:67]
	v_pk_add_f32 v[66:67], v[86:87], v[66:67] neg_lo:[0,1] neg_hi:[0,1]
	v_pk_add_f32 v[86:87], v[54:55], v[62:63] op_sel:[0,1] op_sel_hi:[1,0] neg_hi:[0,1]
	v_pk_add_f32 v[54:55], v[54:55], v[62:63] op_sel:[0,1] op_sel_hi:[1,0] neg_lo:[0,1]
	v_pk_add_f32 v[62:63], v[56:57], v[68:69]
	v_pk_add_f32 v[56:57], v[56:57], v[68:69] neg_lo:[0,1] neg_hi:[0,1]
	v_pk_add_f32 v[68:69], v[64:65], v[76:77]
	v_pk_add_f32 v[64:65], v[64:65], v[76:77] neg_lo:[0,1] neg_hi:[0,1]
	v_pk_add_f32 v[76:77], v[62:63], v[68:69]
	v_pk_add_f32 v[62:63], v[62:63], v[68:69] neg_lo:[0,1] neg_hi:[0,1]
	v_pk_add_f32 v[68:69], v[56:57], v[64:65] op_sel:[0,1] op_sel_hi:[1,0] neg_hi:[0,1]
	v_pk_add_f32 v[56:57], v[56:57], v[64:65] op_sel:[0,1] op_sel_hi:[1,0] neg_lo:[0,1]
	s_waitcnt lgkmcnt(1)
	v_pk_add_f32 v[64:65], v[58:59], v[78:79]
	v_pk_add_f32 v[58:59], v[58:59], v[78:79] neg_lo:[0,1] neg_hi:[0,1]
	s_waitcnt lgkmcnt(0)
	v_pk_add_f32 v[78:79], v[70:71], v[82:83]
	v_pk_add_f32 v[70:71], v[70:71], v[82:83] neg_lo:[0,1] neg_hi:[0,1]
	v_pk_add_f32 v[82:83], v[64:65], v[78:79]
	v_pk_add_f32 v[64:65], v[64:65], v[78:79] neg_lo:[0,1] neg_hi:[0,1]
	v_pk_add_f32 v[78:79], v[58:59], v[70:71] op_sel:[0,1] op_sel_hi:[1,0] neg_hi:[0,1]
	v_pk_add_f32 v[58:59], v[58:59], v[70:71] op_sel:[0,1] op_sel_hi:[1,0] neg_lo:[0,1]
	v_pk_add_f32 v[70:71], v[60:61], v[80:81]
	v_pk_add_f32 v[60:61], v[60:61], v[80:81] neg_lo:[0,1] neg_hi:[0,1]
	v_pk_add_f32 v[80:81], v[72:73], v[84:85]
	v_pk_add_f32 v[72:73], v[72:73], v[84:85] neg_lo:[0,1] neg_hi:[0,1]
	v_pk_add_f32 v[84:85], v[70:71], v[80:81]
	v_pk_add_f32 v[70:71], v[70:71], v[80:81] neg_lo:[0,1] neg_hi:[0,1]
	v_pk_add_f32 v[80:81], v[60:61], v[72:73] op_sel:[0,1] op_sel_hi:[1,0] neg_hi:[0,1]
	v_pk_add_f32 v[60:61], v[60:61], v[72:73] op_sel:[0,1] op_sel_hi:[1,0] neg_lo:[0,1]
	v_pk_mul_f32 v[72:73], v[68:69], s[20:21] op_sel:[0,0] op_sel_hi:[0,1]
	v_pk_fma_f32 v[68:69], v[68:69], s[20:21], v[72:73] op_sel:[1,1,0] op_sel_hi:[1,0,1] neg_lo:[0,1,0]
	v_pk_mul_f32 v[72:73], v[78:79], v[44:45] op_sel:[0,0] op_sel_hi:[0,1]
	v_pk_fma_f32 v[72:73], v[78:79], v[44:45], v[72:73] op_sel:[1,1,0] op_sel_hi:[1,0,1] neg_lo:[0,1,0]
	v_pk_mul_f32 v[78:79], v[80:81], v[42:43] op_sel:[0,0] op_sel_hi:[0,1]
	v_pk_fma_f32 v[78:79], v[80:81], v[42:43], v[78:79] op_sel:[1,1,0] op_sel_hi:[1,0,1] neg_lo:[0,1,0]
	v_pk_mul_f32 v[80:81], v[62:63], v[44:45] op_sel:[0,0] op_sel_hi:[0,1]
	v_pk_fma_f32 v[62:63], v[62:63], v[44:45], v[80:81] op_sel:[1,1,0] op_sel_hi:[1,0,1] neg_lo:[0,1,0]
	v_pk_mul_f32 v[80:81], v[64:65], s[8:9] op_sel:[0,0] op_sel_hi:[0,1]
	v_pk_fma_f32 v[64:65], v[64:65], s[8:9], v[80:81] op_sel:[1,1,0] op_sel_hi:[1,0,1] neg_lo:[0,1,0]
	v_pk_mul_f32 v[80:81], v[70:71], s[54:55] op_sel:[0,0] op_sel_hi:[0,1]
	v_pk_fma_f32 v[70:71], v[70:71], s[54:55], v[80:81] op_sel:[1,1,0] op_sel_hi:[1,0,1] neg_lo:[0,1,0]
	v_pk_mul_f32 v[80:81], v[56:57], v[42:43] op_sel:[0,0] op_sel_hi:[0,1]
	v_pk_fma_f32 v[56:57], v[56:57], v[42:43], v[80:81] op_sel:[1,1,0] op_sel_hi:[1,0,1] neg_lo:[0,1,0]
	v_pk_mul_f32 v[80:81], v[58:59], s[54:55] op_sel:[0,0] op_sel_hi:[0,1]
	v_pk_fma_f32 v[58:59], v[58:59], s[54:55], v[80:81] op_sel:[1,1,0] op_sel_hi:[1,0,1] neg_lo:[0,1,0]
	v_pk_mul_f32 v[80:81], v[60:61], s[56:57] op_sel:[0,0] op_sel_hi:[0,1]
	v_pk_fma_f32 v[60:61], v[60:61], s[56:57], v[80:81] op_sel:[1,1,0] op_sel_hi:[1,0,1] neg_lo:[0,1,0]
	v_pk_add_f32 v[80:81], v[74:75], v[82:83]
	v_pk_add_f32 v[74:75], v[74:75], v[82:83] neg_lo:[0,1] neg_hi:[0,1]
	v_pk_add_f32 v[82:83], v[76:77], v[84:85]
	v_pk_add_f32 v[76:77], v[76:77], v[84:85] neg_lo:[0,1] neg_hi:[0,1]
	v_pk_add_f32 v[84:85], v[80:81], v[82:83]
	v_pk_add_f32 v[80:81], v[80:81], v[82:83] neg_lo:[0,1] neg_hi:[0,1]
	v_pk_add_f32 v[82:83], v[74:75], v[76:77] op_sel:[0,1] op_sel_hi:[1,0] neg_hi:[0,1]
	v_pk_add_f32 v[74:75], v[74:75], v[76:77] op_sel:[0,1] op_sel_hi:[1,0] neg_lo:[0,1]
	v_pk_add_f32 v[76:77], v[86:87], v[72:73]
	v_pk_add_f32 v[72:73], v[86:87], v[72:73] neg_lo:[0,1] neg_hi:[0,1]
	v_pk_add_f32 v[86:87], v[68:69], v[78:79]
	v_pk_add_f32 v[68:69], v[68:69], v[78:79] neg_lo:[0,1] neg_hi:[0,1]
	v_pk_add_f32 v[78:79], v[76:77], v[86:87]
	v_pk_add_f32 v[76:77], v[76:77], v[86:87] neg_lo:[0,1] neg_hi:[0,1]
	v_pk_add_f32 v[86:87], v[72:73], v[68:69] op_sel:[0,1] op_sel_hi:[1,0] neg_hi:[0,1]
	v_pk_add_f32 v[68:69], v[72:73], v[68:69] op_sel:[0,1] op_sel_hi:[1,0] neg_lo:[0,1]
	v_pk_add_f32 v[72:73], v[66:67], v[64:65]
	v_pk_add_f32 v[64:65], v[66:67], v[64:65] neg_lo:[0,1] neg_hi:[0,1]
	v_pk_add_f32 v[66:67], v[62:63], v[70:71]
	v_pk_add_f32 v[62:63], v[62:63], v[70:71] neg_lo:[0,1] neg_hi:[0,1]
	v_pk_add_f32 v[70:71], v[72:73], v[66:67]
	v_pk_add_f32 v[66:67], v[72:73], v[66:67] neg_lo:[0,1] neg_hi:[0,1]
	v_pk_add_f32 v[72:73], v[64:65], v[62:63] op_sel:[0,1] op_sel_hi:[1,0] neg_hi:[0,1]
	v_pk_add_f32 v[62:63], v[64:65], v[62:63] op_sel:[0,1] op_sel_hi:[1,0] neg_lo:[0,1]
	v_pk_add_f32 v[64:65], v[54:55], v[58:59]
	v_pk_add_f32 v[54:55], v[54:55], v[58:59] neg_lo:[0,1] neg_hi:[0,1]
	v_pk_add_f32 v[58:59], v[56:57], v[60:61]
	v_pk_add_f32 v[56:57], v[56:57], v[60:61] neg_lo:[0,1] neg_hi:[0,1]
	v_pk_add_f32 v[60:61], v[64:65], v[58:59]
	v_pk_add_f32 v[58:59], v[64:65], v[58:59] neg_lo:[0,1] neg_hi:[0,1]
	v_pk_add_f32 v[64:65], v[54:55], v[56:57] op_sel:[0,1] op_sel_hi:[1,0] neg_hi:[0,1]
	v_pk_add_f32 v[54:55], v[54:55], v[56:57] op_sel:[0,1] op_sel_hi:[1,0] neg_lo:[0,1]
	v_xor_b32_e32 v57, 0x80000000, v41
	v_mov_b32_e32 v56, v40
	s_waitcnt vmcnt(1)
	v_pk_mul_f32 v[88:89], v[78:79], v[56:57] op_sel:[0,0] op_sel_hi:[0,1]
	v_pk_fma_f32 v[78:79], v[78:79], v[56:57], v[88:89] op_sel:[1,1,0] op_sel_hi:[1,0,1] neg_lo:[0,1,0]
	ds_write2_b64 v134, v[84:85], v[78:79] offset1:17
	v_pk_mul_f32 v[78:79], v[56:57], v[56:57] op_sel:[0,0] op_sel_hi:[0,1]
	v_pk_fma_f32 v[78:79], v[56:57], v[56:57], v[78:79] op_sel:[1,1,0] op_sel_hi:[1,0,1] neg_lo:[0,1,0]
	v_pk_mul_f32 v[84:85], v[70:71], v[78:79] op_sel:[0,0] op_sel_hi:[0,1]
	v_pk_fma_f32 v[70:71], v[70:71], v[78:79], v[84:85] op_sel:[1,1,0] op_sel_hi:[1,0,1] neg_lo:[0,1,0]
	v_pk_mul_f32 v[84:85], v[78:79], v[56:57] op_sel:[0,0] op_sel_hi:[0,1]
	v_pk_fma_f32 v[78:79], v[78:79], v[56:57], v[84:85] op_sel:[1,1,0] op_sel_hi:[1,0,1] neg_lo:[0,1,0]
	v_pk_mul_f32 v[84:85], v[60:61], v[78:79] op_sel:[0,0] op_sel_hi:[0,1]
	v_pk_fma_f32 v[60:61], v[60:61], v[78:79], v[84:85] op_sel:[1,1,0] op_sel_hi:[1,0,1] neg_lo:[0,1,0]
	ds_write2_b64 v134, v[70:71], v[60:61] offset0:34 offset1:51
	v_pk_mul_f32 v[60:61], v[78:79], v[56:57] op_sel:[0,0] op_sel_hi:[0,1]
	v_pk_fma_f32 v[60:61], v[78:79], v[56:57], v[60:61] op_sel:[1,1,0] op_sel_hi:[1,0,1] neg_lo:[0,1,0]
	v_pk_mul_f32 v[70:71], v[82:83], v[60:61] op_sel:[0,0] op_sel_hi:[0,1]
	v_pk_mul_f32 v[78:79], v[60:61], v[56:57] op_sel:[0,0] op_sel_hi:[0,1]
	v_pk_fma_f32 v[70:71], v[82:83], v[60:61], v[70:71] op_sel:[1,1,0] op_sel_hi:[1,0,1] neg_lo:[0,1,0]
	v_pk_fma_f32 v[60:61], v[60:61], v[56:57], v[78:79] op_sel:[1,1,0] op_sel_hi:[1,0,1] neg_lo:[0,1,0]
	v_pk_mul_f32 v[78:79], v[86:87], v[60:61] op_sel:[0,0] op_sel_hi:[0,1]
	v_pk_fma_f32 v[78:79], v[86:87], v[60:61], v[78:79] op_sel:[1,1,0] op_sel_hi:[1,0,1] neg_lo:[0,1,0]
	ds_write2_b64 v134, v[70:71], v[78:79] offset0:68 offset1:85
	v_pk_mul_f32 v[70:71], v[60:61], v[56:57] op_sel:[0,0] op_sel_hi:[0,1]
	v_pk_fma_f32 v[60:61], v[60:61], v[56:57], v[70:71] op_sel:[1,1,0] op_sel_hi:[1,0,1] neg_lo:[0,1,0]
	v_pk_mul_f32 v[70:71], v[72:73], v[60:61] op_sel:[0,0] op_sel_hi:[0,1]
	v_pk_fma_f32 v[70:71], v[72:73], v[60:61], v[70:71] op_sel:[1,1,0] op_sel_hi:[1,0,1] neg_lo:[0,1,0]
	v_pk_mul_f32 v[72:73], v[60:61], v[56:57] op_sel:[0,0] op_sel_hi:[0,1]
	v_pk_fma_f32 v[60:61], v[60:61], v[56:57], v[72:73] op_sel:[1,1,0] op_sel_hi:[1,0,1] neg_lo:[0,1,0]
	v_pk_mul_f32 v[72:73], v[64:65], v[60:61] op_sel:[0,0] op_sel_hi:[0,1]
	v_pk_fma_f32 v[64:65], v[64:65], v[60:61], v[72:73] op_sel:[1,1,0] op_sel_hi:[1,0,1] neg_lo:[0,1,0]
	ds_write2_b64 v134, v[70:71], v[64:65] offset0:102 offset1:119
	v_pk_mul_f32 v[64:65], v[60:61], v[56:57] op_sel:[0,0] op_sel_hi:[0,1]
	v_pk_fma_f32 v[60:61], v[60:61], v[56:57], v[64:65] op_sel:[1,1,0] op_sel_hi:[1,0,1] neg_lo:[0,1,0]
	v_pk_mul_f32 v[64:65], v[80:81], v[60:61] op_sel:[0,0] op_sel_hi:[0,1]
	v_pk_mul_f32 v[70:71], v[60:61], v[56:57] op_sel:[0,0] op_sel_hi:[0,1]
	v_pk_fma_f32 v[64:65], v[80:81], v[60:61], v[64:65] op_sel:[1,1,0] op_sel_hi:[1,0,1] neg_lo:[0,1,0]
	v_pk_fma_f32 v[60:61], v[60:61], v[56:57], v[70:71] op_sel:[1,1,0] op_sel_hi:[1,0,1] neg_lo:[0,1,0]
	v_pk_mul_f32 v[70:71], v[76:77], v[60:61] op_sel:[0,0] op_sel_hi:[0,1]
	v_pk_fma_f32 v[70:71], v[76:77], v[60:61], v[70:71] op_sel:[1,1,0] op_sel_hi:[1,0,1] neg_lo:[0,1,0]
	ds_write2_b64 v134, v[64:65], v[70:71] offset0:136 offset1:153
	v_pk_mul_f32 v[64:65], v[60:61], v[56:57] op_sel:[0,0] op_sel_hi:[0,1]
	v_pk_fma_f32 v[60:61], v[60:61], v[56:57], v[64:65] op_sel:[1,1,0] op_sel_hi:[1,0,1] neg_lo:[0,1,0]
	v_pk_mul_f32 v[64:65], v[66:67], v[60:61] op_sel:[0,0] op_sel_hi:[0,1]
	v_pk_fma_f32 v[64:65], v[66:67], v[60:61], v[64:65] op_sel:[1,1,0] op_sel_hi:[1,0,1] neg_lo:[0,1,0]
	v_pk_mul_f32 v[66:67], v[60:61], v[56:57] op_sel:[0,0] op_sel_hi:[0,1]
	v_pk_fma_f32 v[60:61], v[60:61], v[56:57], v[66:67] op_sel:[1,1,0] op_sel_hi:[1,0,1] neg_lo:[0,1,0]
	v_pk_mul_f32 v[66:67], v[58:59], v[60:61] op_sel:[0,0] op_sel_hi:[0,1]
	v_pk_fma_f32 v[58:59], v[58:59], v[60:61], v[66:67] op_sel:[1,1,0] op_sel_hi:[1,0,1] neg_lo:[0,1,0]
	ds_write2_b64 v134, v[64:65], v[58:59] offset0:170 offset1:187
	v_pk_mul_f32 v[58:59], v[60:61], v[56:57] op_sel:[0,0] op_sel_hi:[0,1]
	v_pk_fma_f32 v[58:59], v[60:61], v[56:57], v[58:59] op_sel:[1,1,0] op_sel_hi:[1,0,1] neg_lo:[0,1,0]
	v_pk_mul_f32 v[60:61], v[74:75], v[58:59] op_sel:[0,0] op_sel_hi:[0,1]
	v_pk_mul_f32 v[64:65], v[58:59], v[56:57] op_sel:[0,0] op_sel_hi:[0,1]
	v_pk_fma_f32 v[60:61], v[74:75], v[58:59], v[60:61] op_sel:[1,1,0] op_sel_hi:[1,0,1] neg_lo:[0,1,0]
	v_pk_fma_f32 v[58:59], v[58:59], v[56:57], v[64:65] op_sel:[1,1,0] op_sel_hi:[1,0,1] neg_lo:[0,1,0]
	v_pk_mul_f32 v[64:65], v[68:69], v[58:59] op_sel:[0,0] op_sel_hi:[0,1]
	v_pk_fma_f32 v[64:65], v[68:69], v[58:59], v[64:65] op_sel:[1,1,0] op_sel_hi:[1,0,1] neg_lo:[0,1,0]
	ds_write2_b64 v134, v[60:61], v[64:65] offset0:204 offset1:221
	v_pk_mul_f32 v[60:61], v[58:59], v[56:57] op_sel:[0,0] op_sel_hi:[0,1]
	v_pk_fma_f32 v[58:59], v[58:59], v[56:57], v[60:61] op_sel:[1,1,0] op_sel_hi:[1,0,1] neg_lo:[0,1,0]
	v_pk_mul_f32 v[60:61], v[62:63], v[58:59] op_sel:[0,0] op_sel_hi:[0,1]
	v_pk_fma_f32 v[60:61], v[62:63], v[58:59], v[60:61] op_sel:[1,1,0] op_sel_hi:[1,0,1] neg_lo:[0,1,0]
	v_pk_mul_f32 v[62:63], v[58:59], v[56:57] op_sel:[0,0] op_sel_hi:[0,1]
	v_pk_fma_f32 v[56:57], v[58:59], v[56:57], v[62:63] op_sel:[1,1,0] op_sel_hi:[1,0,1] neg_lo:[0,1,0]
	v_pk_mul_f32 v[58:59], v[54:55], v[56:57] op_sel:[0,0] op_sel_hi:[0,1]
	v_pk_fma_f32 v[54:55], v[54:55], v[56:57], v[58:59] op_sel:[1,1,0] op_sel_hi:[1,0,1] neg_lo:[0,1,0]
	ds_write2_b64 v134, v[60:61], v[54:55] offset0:238 offset1:255
	s_waitcnt lgkmcnt(0)
	s_barrier
	ds_read2_b64 v[54:57], v135 offset1:1
	ds_read2_b64 v[58:61], v135 offset0:2 offset1:3
	ds_read2_b64 v[62:65], v135 offset0:8 offset1:9
	ds_read2_b64 v[66:69], v135 offset0:4 offset1:5
	ds_read2_b64 v[80:83], v135 offset0:6 offset1:7
	ds_read2_b64 v[76:79], v135 offset0:12 offset1:13
	ds_read2_b64 v[84:87], v135 offset0:10 offset1:11
	ds_read2_b64 v[88:91], v135 offset0:14 offset1:15
	s_waitcnt lgkmcnt(5)
	v_pk_add_f32 v[70:71], v[54:55], v[62:63]
	v_pk_add_f32 v[54:55], v[54:55], v[62:63] neg_lo:[0,1] neg_hi:[0,1]
	s_waitcnt lgkmcnt(2)
	v_pk_add_f32 v[62:63], v[66:67], v[76:77]
	v_pk_add_f32 v[66:67], v[66:67], v[76:77] neg_lo:[0,1] neg_hi:[0,1]
	v_pk_add_f32 v[76:77], v[70:71], v[62:63]
	v_pk_add_f32 v[70:71], v[70:71], v[62:63] neg_lo:[0,1] neg_hi:[0,1]
	v_pk_add_f32 v[74:75], v[54:55], v[66:67] op_sel:[0,1] op_sel_hi:[1,0] neg_hi:[0,1]
	v_pk_add_f32 v[72:73], v[54:55], v[66:67] op_sel:[0,1] op_sel_hi:[1,0] neg_lo:[0,1]
	v_pk_add_f32 v[54:55], v[56:57], v[64:65]
	v_pk_add_f32 v[56:57], v[56:57], v[64:65] neg_lo:[0,1] neg_hi:[0,1]
	v_pk_add_f32 v[62:63], v[68:69], v[78:79]
	v_pk_add_f32 v[64:65], v[68:69], v[78:79] neg_lo:[0,1] neg_hi:[0,1]
	v_pk_add_f32 v[78:79], v[54:55], v[62:63]
	v_pk_add_f32 v[54:55], v[54:55], v[62:63] neg_lo:[0,1] neg_hi:[0,1]
	v_pk_add_f32 v[62:63], v[56:57], v[64:65] op_sel:[0,1] op_sel_hi:[1,0] neg_hi:[0,1]
	v_pk_add_f32 v[56:57], v[56:57], v[64:65] op_sel:[0,1] op_sel_hi:[1,0] neg_lo:[0,1]
	s_waitcnt lgkmcnt(1)
	v_pk_add_f32 v[64:65], v[58:59], v[84:85]
	v_pk_add_f32 v[58:59], v[58:59], v[84:85] neg_lo:[0,1] neg_hi:[0,1]
	s_waitcnt lgkmcnt(0)
	v_pk_add_f32 v[66:67], v[80:81], v[88:89]
	v_pk_add_f32 v[68:69], v[80:81], v[88:89] neg_lo:[0,1] neg_hi:[0,1]
	v_pk_add_f32 v[80:81], v[64:65], v[66:67]
	v_pk_add_f32 v[64:65], v[64:65], v[66:67] neg_lo:[0,1] neg_hi:[0,1]
	v_pk_add_f32 v[66:67], v[58:59], v[68:69] op_sel:[0,1] op_sel_hi:[1,0] neg_hi:[0,1]
	v_pk_add_f32 v[58:59], v[58:59], v[68:69] op_sel:[0,1] op_sel_hi:[1,0] neg_lo:[0,1]
	v_pk_add_f32 v[68:69], v[60:61], v[86:87]
	v_pk_add_f32 v[84:85], v[82:83], v[90:91]
	v_pk_add_f32 v[60:61], v[60:61], v[86:87] neg_lo:[0,1] neg_hi:[0,1]
	v_pk_add_f32 v[86:87], v[82:83], v[90:91] neg_lo:[0,1] neg_hi:[0,1]
	v_pk_add_f32 v[82:83], v[68:69], v[84:85]
	v_pk_add_f32 v[68:69], v[68:69], v[84:85] neg_lo:[0,1] neg_hi:[0,1]
	v_pk_mul_f32 v[84:85], v[62:63], s[20:21] op_sel:[0,0] op_sel_hi:[0,1]
	v_pk_add_f32 v[88:89], v[60:61], v[86:87] op_sel:[0,1] op_sel_hi:[1,0] neg_hi:[0,1]
	v_pk_add_f32 v[60:61], v[60:61], v[86:87] op_sel:[0,1] op_sel_hi:[1,0] neg_lo:[0,1]
	v_pk_fma_f32 v[84:85], v[62:63], s[20:21], v[84:85] op_sel:[1,1,0] op_sel_hi:[1,0,1] neg_lo:[0,1,0]
	v_pk_mul_f32 v[48:49], v[66:67], v[44:45] op_sel:[0,0] op_sel_hi:[0,1]
	s_barrier
	v_pk_fma_f32 v[86:87], v[66:67], v[44:45], v[48:49] op_sel:[1,1,0] op_sel_hi:[1,0,1] neg_lo:[0,1,0]
	v_pk_mul_f32 v[48:49], v[88:89], v[42:43] op_sel:[0,0] op_sel_hi:[0,1]
	v_pk_fma_f32 v[90:91], v[88:89], v[42:43], v[48:49] op_sel:[1,1,0] op_sel_hi:[1,0,1] neg_lo:[0,1,0]
	v_pk_mul_f32 v[48:49], v[54:55], v[44:45] op_sel:[0,0] op_sel_hi:[0,1]
	v_pk_fma_f32 v[88:89], v[54:55], v[44:45], v[48:49] op_sel:[1,1,0] op_sel_hi:[1,0,1] neg_lo:[0,1,0]
	v_pk_mul_f32 v[44:45], v[64:65], s[8:9] op_sel:[0,0] op_sel_hi:[0,1]
	s_waitcnt vmcnt(0)
	v_pk_fma_f32 v[92:93], v[64:65], s[8:9], v[44:45] op_sel:[1,1,0] op_sel_hi:[1,0,1] neg_lo:[0,1,0]
	v_pk_mul_f32 v[44:45], v[68:69], s[54:55] op_sel:[0,0] op_sel_hi:[0,1]
	v_pk_fma_f32 v[96:97], v[68:69], s[54:55], v[44:45] op_sel:[1,1,0] op_sel_hi:[1,0,1] neg_lo:[0,1,0]
	v_pk_mul_f32 v[44:45], v[56:57], v[42:43] op_sel:[0,0] op_sel_hi:[0,1]
	v_pk_fma_f32 v[94:95], v[56:57], v[42:43], v[44:45] op_sel:[1,1,0] op_sel_hi:[1,0,1] neg_lo:[0,1,0]
	v_pk_mul_f32 v[42:43], v[58:59], s[54:55] op_sel:[0,0] op_sel_hi:[0,1]
	v_pk_add_f32 v[44:45], v[78:79], v[82:83] neg_lo:[0,1] neg_hi:[0,1]
	v_pk_fma_f32 v[100:101], v[58:59], s[54:55], v[42:43] op_sel:[1,1,0] op_sel_hi:[1,0,1] neg_lo:[0,1,0]
	v_pk_mul_f32 v[42:43], v[60:61], s[56:57] op_sel:[0,0] op_sel_hi:[0,1]
	v_pk_fma_f32 v[106:107], v[60:61], s[56:57], v[42:43] op_sel:[1,1,0] op_sel_hi:[1,0,1] neg_lo:[0,1,0]
	v_pk_add_f32 v[42:43], v[76:77], v[80:81] neg_lo:[0,1] neg_hi:[0,1]
	s_nop 0
	v_pk_add_f32 v[98:99], v[42:43], v[44:45] op_sel:[0,1] op_sel_hi:[1,0] neg_hi:[0,1]
	v_pk_add_f32 v[102:103], v[42:43], v[44:45] op_sel:[0,1] op_sel_hi:[1,0] neg_lo:[0,1]
	v_pk_add_f32 v[42:43], v[74:75], v[86:87] neg_lo:[0,1] neg_hi:[0,1]
	v_pk_add_f32 v[44:45], v[84:85], v[90:91] neg_lo:[0,1] neg_hi:[0,1]
	s_nop 0
	v_pk_add_f32 v[104:105], v[42:43], v[44:45] op_sel:[0,1] op_sel_hi:[1,0] neg_hi:[0,1]
	v_pk_add_f32 v[108:109], v[42:43], v[44:45] op_sel:[0,1] op_sel_hi:[1,0] neg_lo:[0,1]
	v_pk_add_f32 v[42:43], v[70:71], v[92:93] neg_lo:[0,1] neg_hi:[0,1]
	v_pk_add_f32 v[44:45], v[88:89], v[96:97] neg_lo:[0,1] neg_hi:[0,1]
	s_nop 0
	v_pk_add_f32 v[110:111], v[42:43], v[44:45] op_sel:[0,1] op_sel_hi:[1,0] neg_hi:[0,1]
	v_pk_add_f32 v[112:113], v[42:43], v[44:45] op_sel:[0,1] op_sel_hi:[1,0] neg_lo:[0,1]
	v_pk_add_f32 v[42:43], v[72:73], v[100:101] neg_lo:[0,1] neg_hi:[0,1]
	v_pk_add_f32 v[44:45], v[94:95], v[106:107] neg_lo:[0,1] neg_hi:[0,1]
	s_nop 0
	v_pk_add_f32 v[114:115], v[42:43], v[44:45] op_sel:[0,1] op_sel_hi:[1,0] neg_hi:[0,1]
	v_pk_add_f32 v[116:117], v[42:43], v[44:45] op_sel:[0,1] op_sel_hi:[1,0] neg_lo:[0,1]
	v_mov_b32_e32 v43, v126
	v_mov_b32_e32 v44, 0
	v_sub_u32_e32 v34, 0x1000, v43
	v_cndmask_b32_e64 v42, v34, v43, s[6:7]
	v_cmp_gt_i32_e32 vcc, s86, v42
	v_mov_b32_e32 v34, 0
	s_and_saveexec_b64 s[82:83], vcc
	s_cbranch_execz .LBB0_3365
	v_add_u32_e32 v46, v42, v139
	v_ashrrev_i32_e32 v47, 31, v46
	v_lshl_add_u64 v[46:47], v[46:47], 2, s[0:1]
	global_load_dword v34, v[46:47], off

.LBB0_3400:
	ds_read_b64 v[96:97], v132
	ds_read_b64 v[98:99], v132 offset:2176
	ds_read_b64 v[100:101], v132 offset:4352
	ds_read_b64 v[102:103], v132 offset:6528
	ds_read_b64 v[104:105], v132 offset:8704
	ds_read_b64 v[106:107], v132 offset:10880
	ds_read_b64 v[110:111], v132 offset:13056
	ds_read_b64 v[112:113], v132 offset:15232
	ds_read_b64 v[114:115], v132 offset:17408
	ds_read_b64 v[116:117], v132 offset:19584
	ds_read_b64 v[140:141], v132 offset:21760
	ds_read_b64 v[142:143], v132 offset:23936
	ds_read_b64 v[144:145], v132 offset:26112
	ds_read_b64 v[146:147], v132 offset:28288
	ds_read_b64 v[148:149], v132 offset:30464
	ds_read_b64 v[150:151], v132 offset:32640
	s_waitcnt lgkmcnt(7)
	v_pk_add_f32 v[152:153], v[96:97], v[114:115]
	v_pk_add_f32 v[96:97], v[96:97], v[114:115] neg_lo:[0,1] neg_hi:[0,1]
	s_waitcnt lgkmcnt(3)
	v_pk_add_f32 v[114:115], v[104:105], v[144:145]
	v_pk_add_f32 v[104:105], v[104:105], v[144:145] neg_lo:[0,1] neg_hi:[0,1]
	v_pk_add_f32 v[144:145], v[152:153], v[114:115]
	v_pk_add_f32 v[114:115], v[152:153], v[114:115] neg_lo:[0,1] neg_hi:[0,1]
	v_pk_add_f32 v[152:153], v[96:97], v[104:105] op_sel:[0,1] op_sel_hi:[1,0] neg_hi:[0,1]
	v_pk_add_f32 v[154:155], v[96:97], v[104:105] op_sel:[0,1] op_sel_hi:[1,0] neg_lo:[0,1]
	v_pk_add_f32 v[96:97], v[98:99], v[116:117]
	v_pk_add_f32 v[98:99], v[98:99], v[116:117] neg_lo:[0,1] neg_hi:[0,1]
	s_waitcnt lgkmcnt(2)
	v_pk_add_f32 v[104:105], v[106:107], v[146:147]
	v_pk_add_f32 v[106:107], v[106:107], v[146:147] neg_lo:[0,1] neg_hi:[0,1]
	v_pk_add_f32 v[116:117], v[96:97], v[104:105]
	v_pk_add_f32 v[104:105], v[96:97], v[104:105] neg_lo:[0,1] neg_hi:[0,1]
	v_pk_add_f32 v[96:97], v[98:99], v[106:107] op_sel:[0,1] op_sel_hi:[1,0] neg_hi:[0,1]
	v_pk_add_f32 v[106:107], v[98:99], v[106:107] op_sel:[0,1] op_sel_hi:[1,0] neg_lo:[0,1]
	v_pk_add_f32 v[98:99], v[100:101], v[140:141]
	v_pk_add_f32 v[100:101], v[100:101], v[140:141] neg_lo:[0,1] neg_hi:[0,1]
	s_waitcnt lgkmcnt(1)
	v_pk_add_f32 v[140:141], v[110:111], v[148:149]
	v_pk_add_f32 v[110:111], v[110:111], v[148:149] neg_lo:[0,1] neg_hi:[0,1]
	v_pk_add_f32 v[146:147], v[98:99], v[140:141]
	v_pk_add_f32 v[140:141], v[98:99], v[140:141] neg_lo:[0,1] neg_hi:[0,1]
	v_pk_add_f32 v[148:149], v[100:101], v[110:111] op_sel:[0,1] op_sel_hi:[1,0] neg_hi:[0,1]
	v_pk_add_f32 v[110:111], v[100:101], v[110:111] op_sel:[0,1] op_sel_hi:[1,0] neg_lo:[0,1]
	v_pk_add_f32 v[98:99], v[102:103], v[142:143]
	v_pk_add_f32 v[100:101], v[102:103], v[142:143] neg_lo:[0,1] neg_hi:[0,1]
	s_waitcnt lgkmcnt(0)
	v_pk_add_f32 v[102:103], v[112:113], v[150:151]
	v_pk_add_f32 v[112:113], v[112:113], v[150:151] neg_lo:[0,1] neg_hi:[0,1]
	v_pk_add_f32 v[142:143], v[98:99], v[102:103]
	v_pk_add_f32 v[150:151], v[98:99], v[102:103] neg_lo:[0,1] neg_hi:[0,1]
	v_pk_mul_f32 v[98:99], v[96:97], s[20:21] op_sel:[0,0] op_sel_hi:[0,1]
	v_pk_add_f32 v[156:157], v[100:101], v[112:113] op_sel:[0,1] op_sel_hi:[1,0] neg_hi:[0,1]
	v_pk_add_f32 v[112:113], v[100:101], v[112:113] op_sel:[0,1] op_sel_hi:[1,0] neg_lo:[0,1]
	v_xor_b32_e32 v39, 0x80000000, v39
	v_pk_fma_f32 v[158:159], v[96:97], s[20:21], v[98:99] op_sel:[1,1,0] op_sel_hi:[1,0,1] neg_lo:[0,1,0]
	v_pk_mul_f32 v[96:97], v[148:149], s[46:47] op_sel:[0,0] op_sel_hi:[0,1]
	v_xor_b32_e32 v41, 0x80000000, v41
	v_pk_fma_f32 v[148:149], v[148:149], s[46:47], v[96:97] op_sel:[1,1,0] op_sel_hi:[1,0,1] neg_lo:[0,1,0]
	v_pk_mul_f32 v[100:101], v[156:157], s[50:51] op_sel:[0,0] op_sel_hi:[0,1]
	v_pk_fma_f32 v[156:157], v[156:157], s[50:51], v[100:101] op_sel:[1,1,0] op_sel_hi:[1,0,1] neg_lo:[0,1,0]
	v_pk_mul_f32 v[100:101], v[104:105], s[46:47] op_sel:[0,0] op_sel_hi:[0,1]
	v_pk_fma_f32 v[160:161], v[104:105], s[46:47], v[100:101] op_sel:[1,1,0] op_sel_hi:[1,0,1] neg_lo:[0,1,0]
	v_pk_mul_f32 v[100:101], v[140:141], s[8:9] op_sel:[0,0] op_sel_hi:[0,1]
	v_pk_fma_f32 v[140:141], v[140:141], s[8:9], v[100:101] op_sel:[1,1,0] op_sel_hi:[1,0,1] neg_lo:[0,1,0]
	v_pk_mul_f32 v[162:163], v[150:151], s[54:55] op_sel:[0,0] op_sel_hi:[0,1]
	v_pk_fma_f32 v[150:151], v[150:151], s[54:55], v[162:163] op_sel:[1,1,0] op_sel_hi:[1,0,1] neg_lo:[0,1,0]
	v_pk_mul_f32 v[162:163], v[106:107], s[50:51] op_sel:[0,0] op_sel_hi:[0,1]
	v_pk_fma_f32 v[162:163], v[106:107], s[50:51], v[162:163] op_sel:[1,1,0] op_sel_hi:[1,0,1] neg_lo:[0,1,0]
	v_pk_mul_f32 v[106:107], v[110:111], s[54:55] op_sel:[0,0] op_sel_hi:[0,1]
	v_pk_fma_f32 v[110:111], v[110:111], s[54:55], v[106:107] op_sel:[1,1,0] op_sel_hi:[1,0,1] neg_lo:[0,1,0]
	v_pk_mul_f32 v[164:165], v[112:113], s[56:57] op_sel:[0,0] op_sel_hi:[0,1]
	v_pk_fma_f32 v[112:113], v[112:113], s[56:57], v[164:165] op_sel:[1,1,0] op_sel_hi:[1,0,1] neg_lo:[0,1,0]
	v_pk_add_f32 v[164:165], v[144:145], v[146:147]
	v_pk_add_f32 v[144:145], v[144:145], v[146:147] neg_lo:[0,1] neg_hi:[0,1]
	v_pk_add_f32 v[146:147], v[116:117], v[142:143]
	v_pk_add_f32 v[116:117], v[116:117], v[142:143] neg_lo:[0,1] neg_hi:[0,1]
	v_pk_add_f32 v[142:143], v[164:165], v[146:147]
	v_pk_add_f32 v[146:147], v[164:165], v[146:147] neg_lo:[0,1] neg_hi:[0,1]
	v_pk_add_f32 v[164:165], v[144:145], v[116:117] op_sel:[0,1] op_sel_hi:[1,0] neg_hi:[0,1]
	v_pk_add_f32 v[116:117], v[144:145], v[116:117] op_sel:[0,1] op_sel_hi:[1,0] neg_lo:[0,1]
	v_pk_add_f32 v[144:145], v[152:153], v[148:149]
	v_pk_add_f32 v[148:149], v[152:153], v[148:149] neg_lo:[0,1] neg_hi:[0,1]
	v_pk_add_f32 v[152:153], v[158:159], v[156:157]
	v_pk_add_f32 v[156:157], v[158:159], v[156:157] neg_lo:[0,1] neg_hi:[0,1]
	v_pk_add_f32 v[158:159], v[144:145], v[152:153]
	v_pk_add_f32 v[144:145], v[144:145], v[152:153] neg_lo:[0,1] neg_hi:[0,1]
	v_pk_add_f32 v[152:153], v[148:149], v[156:157] op_sel:[0,1] op_sel_hi:[1,0] neg_hi:[0,1]
	v_pk_add_f32 v[148:149], v[148:149], v[156:157] op_sel:[0,1] op_sel_hi:[1,0] neg_lo:[0,1]
	v_pk_add_f32 v[156:157], v[114:115], v[140:141]
	v_pk_add_f32 v[114:115], v[114:115], v[140:141] neg_lo:[0,1] neg_hi:[0,1]
	v_pk_add_f32 v[140:141], v[160:161], v[150:151]
	v_pk_add_f32 v[150:151], v[160:161], v[150:151] neg_lo:[0,1] neg_hi:[0,1]
	v_pk_add_f32 v[160:161], v[156:157], v[140:141]
	v_pk_add_f32 v[140:141], v[156:157], v[140:141] neg_lo:[0,1] neg_hi:[0,1]
	v_pk_add_f32 v[156:157], v[114:115], v[150:151] op_sel:[0,1] op_sel_hi:[1,0] neg_hi:[0,1]
	v_pk_add_f32 v[114:115], v[114:115], v[150:151] op_sel:[0,1] op_sel_hi:[1,0] neg_lo:[0,1]
	v_pk_add_f32 v[150:151], v[154:155], v[110:111]
	v_pk_add_f32 v[110:111], v[154:155], v[110:111] neg_lo:[0,1] neg_hi:[0,1]
	v_pk_add_f32 v[154:155], v[162:163], v[112:113]
	v_pk_add_f32 v[112:113], v[162:163], v[112:113] neg_lo:[0,1] neg_hi:[0,1]
	v_pk_add_f32 v[162:163], v[150:151], v[154:155]
	v_pk_add_f32 v[150:151], v[150:151], v[154:155] neg_lo:[0,1] neg_hi:[0,1]
	v_pk_add_f32 v[154:155], v[110:111], v[112:113] op_sel:[0,1] op_sel_hi:[1,0] neg_hi:[0,1]
	v_pk_add_f32 v[110:111], v[110:111], v[112:113] op_sel:[0,1] op_sel_hi:[1,0] neg_lo:[0,1]
	v_mov_b32_e32 v113, v39
	v_mov_b32_e32 v112, v38
	ds_write_b64 v132, v[142:143]
	v_pk_mul_f32 v[142:143], v[158:159], v[112:113] op_sel:[0,0] op_sel_hi:[0,1]
	v_pk_fma_f32 v[142:143], v[158:159], v[112:113], v[142:143] op_sel:[1,1,0] op_sel_hi:[1,0,1] neg_lo:[0,1,0]
	ds_write_b64 v132, v[142:143] offset:2176
	v_pk_mul_f32 v[142:143], v[112:113], v[112:113] op_sel:[0,0] op_sel_hi:[0,1]
	v_pk_fma_f32 v[142:143], v[112:113], v[112:113], v[142:143] op_sel:[1,1,0] op_sel_hi:[1,0,1] neg_lo:[0,1,0]
	v_pk_mul_f32 v[158:159], v[160:161], v[142:143] op_sel:[0,0] op_sel_hi:[0,1]
	v_pk_fma_f32 v[158:159], v[160:161], v[142:143], v[158:159] op_sel:[1,1,0] op_sel_hi:[1,0,1] neg_lo:[0,1,0]
	ds_write_b64 v132, v[158:159] offset:4352
	v_pk_mul_f32 v[158:159], v[142:143], v[112:113] op_sel:[0,0] op_sel_hi:[0,1]
	v_pk_fma_f32 v[142:143], v[142:143], v[112:113], v[158:159] op_sel:[1,1,0] op_sel_hi:[1,0,1] neg_lo:[0,1,0]
	v_pk_mul_f32 v[158:159], v[162:163], v[142:143] op_sel:[0,0] op_sel_hi:[0,1]
	v_pk_fma_f32 v[158:159], v[162:163], v[142:143], v[158:159] op_sel:[1,1,0] op_sel_hi:[1,0,1] neg_lo:[0,1,0]
	ds_write_b64 v132, v[158:159] offset:6528
	v_pk_mul_f32 v[158:159], v[142:143], v[112:113] op_sel:[0,0] op_sel_hi:[0,1]
	v_pk_fma_f32 v[142:143], v[142:143], v[112:113], v[158:159] op_sel:[1,1,0] op_sel_hi:[1,0,1] neg_lo:[0,1,0]
	v_pk_mul_f32 v[158:159], v[164:165], v[142:143] op_sel:[0,0] op_sel_hi:[0,1]
	v_pk_fma_f32 v[158:159], v[164:165], v[142:143], v[158:159] op_sel:[1,1,0] op_sel_hi:[1,0,1] neg_lo:[0,1,0]
	ds_write_b64 v132, v[158:159] offset:8704
	v_pk_mul_f32 v[158:159], v[142:143], v[112:113] op_sel:[0,0] op_sel_hi:[0,1]
	v_pk_fma_f32 v[142:143], v[142:143], v[112:113], v[158:159] op_sel:[1,1,0] op_sel_hi:[1,0,1] neg_lo:[0,1,0]
	v_pk_mul_f32 v[158:159], v[152:153], v[142:143] op_sel:[0,0] op_sel_hi:[0,1]
	v_pk_fma_f32 v[152:153], v[152:153], v[142:143], v[158:159] op_sel:[1,1,0] op_sel_hi:[1,0,1] neg_lo:[0,1,0]
	ds_write_b64 v132, v[152:153] offset:10880
	v_pk_mul_f32 v[152:153], v[142:143], v[112:113] op_sel:[0,0] op_sel_hi:[0,1]
	v_pk_fma_f32 v[142:143], v[142:143], v[112:113], v[152:153] op_sel:[1,1,0] op_sel_hi:[1,0,1] neg_lo:[0,1,0]
	v_pk_mul_f32 v[152:153], v[156:157], v[142:143] op_sel:[0,0] op_sel_hi:[0,1]
	v_pk_fma_f32 v[152:153], v[156:157], v[142:143], v[152:153] op_sel:[1,1,0] op_sel_hi:[1,0,1] neg_lo:[0,1,0]
	ds_write_b64 v132, v[152:153] offset:13056
	v_pk_mul_f32 v[152:153], v[142:143], v[112:113] op_sel:[0,0] op_sel_hi:[0,1]
	v_pk_fma_f32 v[142:143], v[142:143], v[112:113], v[152:153] op_sel:[1,1,0] op_sel_hi:[1,0,1] neg_lo:[0,1,0]
	v_pk_mul_f32 v[152:153], v[154:155], v[142:143] op_sel:[0,0] op_sel_hi:[0,1]
	v_pk_fma_f32 v[152:153], v[154:155], v[142:143], v[152:153] op_sel:[1,1,0] op_sel_hi:[1,0,1] neg_lo:[0,1,0]
	ds_write_b64 v132, v[152:153] offset:15232
	v_pk_mul_f32 v[152:153], v[142:143], v[112:113] op_sel:[0,0] op_sel_hi:[0,1]
	v_pk_fma_f32 v[142:143], v[142:143], v[112:113], v[152:153] op_sel:[1,1,0] op_sel_hi:[1,0,1] neg_lo:[0,1,0]
	v_pk_mul_f32 v[152:153], v[146:147], v[142:143] op_sel:[0,0] op_sel_hi:[0,1]
	v_pk_fma_f32 v[146:147], v[146:147], v[142:143], v[152:153] op_sel:[1,1,0] op_sel_hi:[1,0,1] neg_lo:[0,1,0]
	ds_write_b64 v132, v[146:147] offset:17408
	v_pk_mul_f32 v[146:147], v[142:143], v[112:113] op_sel:[0,0] op_sel_hi:[0,1]
	v_pk_fma_f32 v[142:143], v[142:143], v[112:113], v[146:147] op_sel:[1,1,0] op_sel_hi:[1,0,1] neg_lo:[0,1,0]
	v_pk_mul_f32 v[146:147], v[144:145], v[142:143] op_sel:[0,0] op_sel_hi:[0,1]
	v_pk_fma_f32 v[144:145], v[144:145], v[142:143], v[146:147] op_sel:[1,1,0] op_sel_hi:[1,0,1] neg_lo:[0,1,0]
	ds_write_b64 v132, v[144:145] offset:19584
	v_pk_mul_f32 v[144:145], v[142:143], v[112:113] op_sel:[0,0] op_sel_hi:[0,1]
	v_pk_fma_f32 v[142:143], v[142:143], v[112:113], v[144:145] op_sel:[1,1,0] op_sel_hi:[1,0,1] neg_lo:[0,1,0]
	v_pk_mul_f32 v[144:145], v[140:141], v[142:143] op_sel:[0,0] op_sel_hi:[0,1]
	v_pk_fma_f32 v[140:141], v[140:141], v[142:143], v[144:145] op_sel:[1,1,0] op_sel_hi:[1,0,1] neg_lo:[0,1,0]
	ds_write_b64 v132, v[140:141] offset:21760
	v_pk_mul_f32 v[140:141], v[142:143], v[112:113] op_sel:[0,0] op_sel_hi:[0,1]
	v_pk_fma_f32 v[140:141], v[142:143], v[112:113], v[140:141] op_sel:[1,1,0] op_sel_hi:[1,0,1] neg_lo:[0,1,0]
	v_pk_mul_f32 v[142:143], v[150:151], v[140:141] op_sel:[0,0] op_sel_hi:[0,1]
	v_pk_fma_f32 v[142:143], v[150:151], v[140:141], v[142:143] op_sel:[1,1,0] op_sel_hi:[1,0,1] neg_lo:[0,1,0]
	ds_write_b64 v132, v[142:143] offset:23936
	v_pk_mul_f32 v[142:143], v[140:141], v[112:113] op_sel:[0,0] op_sel_hi:[0,1]
	v_pk_fma_f32 v[140:141], v[140:141], v[112:113], v[142:143] op_sel:[1,1,0] op_sel_hi:[1,0,1] neg_lo:[0,1,0]
	v_pk_mul_f32 v[142:143], v[116:117], v[140:141] op_sel:[0,0] op_sel_hi:[0,1]
	v_pk_fma_f32 v[116:117], v[116:117], v[140:141], v[142:143] op_sel:[1,1,0] op_sel_hi:[1,0,1] neg_lo:[0,1,0]
	ds_write_b64 v132, v[116:117] offset:26112
	v_pk_mul_f32 v[116:117], v[140:141], v[112:113] op_sel:[0,0] op_sel_hi:[0,1]
	v_pk_fma_f32 v[116:117], v[140:141], v[112:113], v[116:117] op_sel:[1,1,0] op_sel_hi:[1,0,1] neg_lo:[0,1,0]
	v_pk_mul_f32 v[140:141], v[148:149], v[116:117] op_sel:[0,0] op_sel_hi:[0,1]
	v_pk_fma_f32 v[140:141], v[148:149], v[116:117], v[140:141] op_sel:[1,1,0] op_sel_hi:[1,0,1] neg_lo:[0,1,0]
	ds_write_b64 v132, v[140:141] offset:28288
	v_pk_mul_f32 v[140:141], v[116:117], v[112:113] op_sel:[0,0] op_sel_hi:[0,1]
	v_pk_fma_f32 v[116:117], v[116:117], v[112:113], v[140:141] op_sel:[1,1,0] op_sel_hi:[1,0,1] neg_lo:[0,1,0]
	v_pk_mul_f32 v[140:141], v[114:115], v[116:117] op_sel:[0,0] op_sel_hi:[0,1]
	v_pk_fma_f32 v[114:115], v[114:115], v[116:117], v[140:141] op_sel:[1,1,0] op_sel_hi:[1,0,1] neg_lo:[0,1,0]
	ds_write_b64 v132, v[114:115] offset:30464
	v_pk_mul_f32 v[114:115], v[116:117], v[112:113] op_sel:[0,0] op_sel_hi:[0,1]
	v_pk_fma_f32 v[112:113], v[116:117], v[112:113], v[114:115] op_sel:[1,1,0] op_sel_hi:[1,0,1] neg_lo:[0,1,0]
	v_pk_mul_f32 v[114:115], v[110:111], v[112:113] op_sel:[0,0] op_sel_hi:[0,1]
	v_pk_fma_f32 v[110:111], v[110:111], v[112:113], v[114:115] op_sel:[1,1,0] op_sel_hi:[1,0,1] neg_lo:[0,1,0]
	ds_write_b64 v132, v[110:111] offset:32640
	s_waitcnt lgkmcnt(0)
	s_barrier
	ds_read2_b64 v[110:113], v134 offset1:17
	ds_read2_b64 v[114:117], v134 offset0:34 offset1:51
	ds_read2_b64 v[140:143], v134 offset0:68 offset1:85
	ds_read2_b64 v[144:147], v134 offset0:136 offset1:153
	ds_read2_b64 v[148:151], v134 offset0:102 offset1:119
	ds_read2_b64 v[152:155], v134 offset0:204 offset1:221
	ds_read2_b64 v[156:159], v134 offset0:170 offset1:187
	ds_read2_b64 v[160:163], v134 offset0:238 offset1:255
	s_waitcnt lgkmcnt(4)
	v_pk_add_f32 v[164:165], v[110:111], v[144:145]
	v_pk_add_f32 v[110:111], v[110:111], v[144:145] neg_lo:[0,1] neg_hi:[0,1]
	s_waitcnt lgkmcnt(2)
	v_pk_add_f32 v[144:145], v[140:141], v[152:153]
	v_pk_add_f32 v[140:141], v[140:141], v[152:153] neg_lo:[0,1] neg_hi:[0,1]
	v_pk_add_f32 v[152:153], v[164:165], v[144:145]
	v_pk_add_f32 v[144:145], v[164:165], v[144:145] neg_lo:[0,1] neg_hi:[0,1]
	v_pk_add_f32 v[164:165], v[110:111], v[140:141] op_sel:[0,1] op_sel_hi:[1,0] neg_hi:[0,1]
	v_pk_add_f32 v[110:111], v[110:111], v[140:141] op_sel:[0,1] op_sel_hi:[1,0] neg_lo:[0,1]
	v_pk_add_f32 v[140:141], v[112:113], v[146:147]
	v_pk_add_f32 v[112:113], v[112:113], v[146:147] neg_lo:[0,1] neg_hi:[0,1]
	v_pk_add_f32 v[146:147], v[142:143], v[154:155]
	v_pk_add_f32 v[142:143], v[142:143], v[154:155] neg_lo:[0,1] neg_hi:[0,1]
	v_pk_add_f32 v[154:155], v[140:141], v[146:147]
	v_pk_add_f32 v[140:141], v[140:141], v[146:147] neg_lo:[0,1] neg_hi:[0,1]
	v_pk_add_f32 v[146:147], v[112:113], v[142:143] op_sel:[0,1] op_sel_hi:[1,0] neg_hi:[0,1]
	v_pk_add_f32 v[112:113], v[112:113], v[142:143] op_sel:[0,1] op_sel_hi:[1,0] neg_lo:[0,1]
	s_waitcnt lgkmcnt(1)
	v_pk_add_f32 v[142:143], v[114:115], v[156:157]
	v_pk_add_f32 v[114:115], v[114:115], v[156:157] neg_lo:[0,1] neg_hi:[0,1]
	s_waitcnt lgkmcnt(0)
	v_pk_add_f32 v[156:157], v[148:149], v[160:161]
	v_pk_add_f32 v[148:149], v[148:149], v[160:161] neg_lo:[0,1] neg_hi:[0,1]
	v_pk_add_f32 v[160:161], v[142:143], v[156:157]
	v_pk_add_f32 v[142:143], v[142:143], v[156:157] neg_lo:[0,1] neg_hi:[0,1]
	v_pk_add_f32 v[156:157], v[114:115], v[148:149] op_sel:[0,1] op_sel_hi:[1,0] neg_hi:[0,1]
	v_pk_add_f32 v[114:115], v[114:115], v[148:149] op_sel:[0,1] op_sel_hi:[1,0] neg_lo:[0,1]
	v_pk_add_f32 v[148:149], v[116:117], v[158:159]
	v_pk_add_f32 v[116:117], v[116:117], v[158:159] neg_lo:[0,1] neg_hi:[0,1]
	v_pk_add_f32 v[158:159], v[150:151], v[162:163]
	v_pk_add_f32 v[150:151], v[150:151], v[162:163] neg_lo:[0,1] neg_hi:[0,1]
	v_pk_add_f32 v[162:163], v[148:149], v[158:159]
	v_pk_add_f32 v[148:149], v[148:149], v[158:159] neg_lo:[0,1] neg_hi:[0,1]
	v_pk_add_f32 v[158:159], v[116:117], v[150:151] op_sel:[0,1] op_sel_hi:[1,0] neg_hi:[0,1]
	v_pk_add_f32 v[116:117], v[116:117], v[150:151] op_sel:[0,1] op_sel_hi:[1,0] neg_lo:[0,1]
	v_pk_mul_f32 v[150:151], v[146:147], s[20:21] op_sel:[0,0] op_sel_hi:[0,1]
	v_pk_fma_f32 v[146:147], v[146:147], s[20:21], v[150:151] op_sel:[1,1,0] op_sel_hi:[1,0,1] neg_lo:[0,1,0]
	v_pk_mul_f32 v[150:151], v[156:157], s[46:47] op_sel:[0,0] op_sel_hi:[0,1]
	v_pk_fma_f32 v[150:151], v[156:157], s[46:47], v[150:151] op_sel:[1,1,0] op_sel_hi:[1,0,1] neg_lo:[0,1,0]
	v_pk_mul_f32 v[156:157], v[158:159], s[50:51] op_sel:[0,0] op_sel_hi:[0,1]
	v_pk_fma_f32 v[156:157], v[158:159], s[50:51], v[156:157] op_sel:[1,1,0] op_sel_hi:[1,0,1] neg_lo:[0,1,0]
	v_pk_mul_f32 v[158:159], v[140:141], s[46:47] op_sel:[0,0] op_sel_hi:[0,1]
	v_pk_fma_f32 v[140:141], v[140:141], s[46:47], v[158:159] op_sel:[1,1,0] op_sel_hi:[1,0,1] neg_lo:[0,1,0]
	v_pk_mul_f32 v[158:159], v[142:143], s[8:9] op_sel:[0,0] op_sel_hi:[0,1]
	v_pk_fma_f32 v[142:143], v[142:143], s[8:9], v[158:159] op_sel:[1,1,0] op_sel_hi:[1,0,1] neg_lo:[0,1,0]
	v_pk_mul_f32 v[158:159], v[148:149], s[54:55] op_sel:[0,0] op_sel_hi:[0,1]
	v_pk_fma_f32 v[148:149], v[148:149], s[54:55], v[158:159] op_sel:[1,1,0] op_sel_hi:[1,0,1] neg_lo:[0,1,0]
	v_pk_mul_f32 v[158:159], v[112:113], s[50:51] op_sel:[0,0] op_sel_hi:[0,1]
	v_pk_fma_f32 v[112:113], v[112:113], s[50:51], v[158:159] op_sel:[1,1,0] op_sel_hi:[1,0,1] neg_lo:[0,1,0]
	v_pk_mul_f32 v[158:159], v[114:115], s[54:55] op_sel:[0,0] op_sel_hi:[0,1]
	v_pk_fma_f32 v[114:115], v[114:115], s[54:55], v[158:159] op_sel:[1,1,0] op_sel_hi:[1,0,1] neg_lo:[0,1,0]
	v_pk_mul_f32 v[158:159], v[116:117], s[56:57] op_sel:[0,0] op_sel_hi:[0,1]
	v_pk_fma_f32 v[116:117], v[116:117], s[56:57], v[158:159] op_sel:[1,1,0] op_sel_hi:[1,0,1] neg_lo:[0,1,0]
	v_pk_add_f32 v[158:159], v[152:153], v[160:161]
	v_pk_add_f32 v[152:153], v[152:153], v[160:161] neg_lo:[0,1] neg_hi:[0,1]
	v_pk_add_f32 v[160:161], v[154:155], v[162:163]
	v_pk_add_f32 v[154:155], v[154:155], v[162:163] neg_lo:[0,1] neg_hi:[0,1]
	v_pk_add_f32 v[162:163], v[158:159], v[160:161]
	v_pk_add_f32 v[158:159], v[158:159], v[160:161] neg_lo:[0,1] neg_hi:[0,1]
	v_pk_add_f32 v[160:161], v[152:153], v[154:155] op_sel:[0,1] op_sel_hi:[1,0] neg_hi:[0,1]
	v_pk_add_f32 v[152:153], v[152:153], v[154:155] op_sel:[0,1] op_sel_hi:[1,0] neg_lo:[0,1]
	v_pk_add_f32 v[154:155], v[164:165], v[150:151]
	v_pk_add_f32 v[150:151], v[164:165], v[150:151] neg_lo:[0,1] neg_hi:[0,1]
	v_pk_add_f32 v[164:165], v[146:147], v[156:157]
	v_pk_add_f32 v[146:147], v[146:147], v[156:157] neg_lo:[0,1] neg_hi:[0,1]
	v_pk_add_f32 v[156:157], v[154:155], v[164:165]
	v_pk_add_f32 v[154:155], v[154:155], v[164:165] neg_lo:[0,1] neg_hi:[0,1]
	v_pk_add_f32 v[164:165], v[150:151], v[146:147] op_sel:[0,1] op_sel_hi:[1,0] neg_hi:[0,1]
	v_pk_add_f32 v[146:147], v[150:151], v[146:147] op_sel:[0,1] op_sel_hi:[1,0] neg_lo:[0,1]
	v_pk_add_f32 v[150:151], v[144:145], v[142:143]
	v_pk_add_f32 v[142:143], v[144:145], v[142:143] neg_lo:[0,1] neg_hi:[0,1]
	v_pk_add_f32 v[144:145], v[140:141], v[148:149]
	v_pk_add_f32 v[140:141], v[140:141], v[148:149] neg_lo:[0,1] neg_hi:[0,1]
	v_pk_add_f32 v[148:149], v[150:151], v[144:145]
	v_pk_add_f32 v[144:145], v[150:151], v[144:145] neg_lo:[0,1] neg_hi:[0,1]
	v_pk_add_f32 v[150:151], v[142:143], v[140:141] op_sel:[0,1] op_sel_hi:[1,0] neg_hi:[0,1]
	v_pk_add_f32 v[140:141], v[142:143], v[140:141] op_sel:[0,1] op_sel_hi:[1,0] neg_lo:[0,1]
	v_pk_add_f32 v[142:143], v[110:111], v[114:115]
	v_pk_add_f32 v[110:111], v[110:111], v[114:115] neg_lo:[0,1] neg_hi:[0,1]
	v_pk_add_f32 v[114:115], v[112:113], v[116:117]
	v_pk_add_f32 v[112:113], v[112:113], v[116:117] neg_lo:[0,1] neg_hi:[0,1]
	v_pk_add_f32 v[116:117], v[142:143], v[114:115]
	v_pk_add_f32 v[114:115], v[142:143], v[114:115] neg_lo:[0,1] neg_hi:[0,1]
	v_pk_add_f32 v[142:143], v[110:111], v[112:113] op_sel:[0,1] op_sel_hi:[1,0] neg_hi:[0,1]
	v_pk_add_f32 v[110:111], v[110:111], v[112:113] op_sel:[0,1] op_sel_hi:[1,0] neg_lo:[0,1]
	v_mov_b32_e32 v112, v40
	v_mov_b32_e32 v113, v41
	s_nop 0
	v_pk_mul_f32 v[166:167], v[156:157], v[112:113] op_sel:[0,0] op_sel_hi:[0,1]
	v_pk_fma_f32 v[156:157], v[156:157], v[112:113], v[166:167] op_sel:[1,1,0] op_sel_hi:[1,0,1] neg_lo:[0,1,0]
	ds_write2_b64 v134, v[162:163], v[156:157] offset1:17
	v_pk_mul_f32 v[156:157], v[112:113], v[112:113] op_sel:[0,0] op_sel_hi:[0,1]
	v_pk_fma_f32 v[156:157], v[112:113], v[112:113], v[156:157] op_sel:[1,1,0] op_sel_hi:[1,0,1] neg_lo:[0,1,0]
	v_pk_mul_f32 v[162:163], v[148:149], v[156:157] op_sel:[0,0] op_sel_hi:[0,1]
	v_pk_fma_f32 v[148:149], v[148:149], v[156:157], v[162:163] op_sel:[1,1,0] op_sel_hi:[1,0,1] neg_lo:[0,1,0]
	v_pk_mul_f32 v[162:163], v[156:157], v[112:113] op_sel:[0,0] op_sel_hi:[0,1]
	v_pk_fma_f32 v[156:157], v[156:157], v[112:113], v[162:163] op_sel:[1,1,0] op_sel_hi:[1,0,1] neg_lo:[0,1,0]
	v_pk_mul_f32 v[162:163], v[116:117], v[156:157] op_sel:[0,0] op_sel_hi:[0,1]
	v_pk_fma_f32 v[116:117], v[116:117], v[156:157], v[162:163] op_sel:[1,1,0] op_sel_hi:[1,0,1] neg_lo:[0,1,0]
	ds_write2_b64 v134, v[148:149], v[116:117] offset0:34 offset1:51
	v_pk_mul_f32 v[116:117], v[156:157], v[112:113] op_sel:[0,0] op_sel_hi:[0,1]
	v_pk_fma_f32 v[116:117], v[156:157], v[112:113], v[116:117] op_sel:[1,1,0] op_sel_hi:[1,0,1] neg_lo:[0,1,0]
	v_pk_mul_f32 v[148:149], v[160:161], v[116:117] op_sel:[0,0] op_sel_hi:[0,1]
	v_pk_mul_f32 v[156:157], v[116:117], v[112:113] op_sel:[0,0] op_sel_hi:[0,1]
	v_pk_fma_f32 v[148:149], v[160:161], v[116:117], v[148:149] op_sel:[1,1,0] op_sel_hi:[1,0,1] neg_lo:[0,1,0]
	v_pk_fma_f32 v[116:117], v[116:117], v[112:113], v[156:157] op_sel:[1,1,0] op_sel_hi:[1,0,1] neg_lo:[0,1,0]
	v_pk_mul_f32 v[156:157], v[164:165], v[116:117] op_sel:[0,0] op_sel_hi:[0,1]
	v_pk_fma_f32 v[156:157], v[164:165], v[116:117], v[156:157] op_sel:[1,1,0] op_sel_hi:[1,0,1] neg_lo:[0,1,0]
	ds_write2_b64 v134, v[148:149], v[156:157] offset0:68 offset1:85
	v_pk_mul_f32 v[148:149], v[116:117], v[112:113] op_sel:[0,0] op_sel_hi:[0,1]
	v_pk_fma_f32 v[116:117], v[116:117], v[112:113], v[148:149] op_sel:[1,1,0] op_sel_hi:[1,0,1] neg_lo:[0,1,0]
	v_pk_mul_f32 v[148:149], v[150:151], v[116:117] op_sel:[0,0] op_sel_hi:[0,1]
	v_pk_fma_f32 v[148:149], v[150:151], v[116:117], v[148:149] op_sel:[1,1,0] op_sel_hi:[1,0,1] neg_lo:[0,1,0]
	v_pk_mul_f32 v[150:151], v[116:117], v[112:113] op_sel:[0,0] op_sel_hi:[0,1]
	v_pk_fma_f32 v[116:117], v[116:117], v[112:113], v[150:151] op_sel:[1,1,0] op_sel_hi:[1,0,1] neg_lo:[0,1,0]
	v_pk_mul_f32 v[150:151], v[142:143], v[116:117] op_sel:[0,0] op_sel_hi:[0,1]
	v_pk_fma_f32 v[142:143], v[142:143], v[116:117], v[150:151] op_sel:[1,1,0] op_sel_hi:[1,0,1] neg_lo:[0,1,0]
	ds_write2_b64 v134, v[148:149], v[142:143] offset0:102 offset1:119
	v_pk_mul_f32 v[142:143], v[116:117], v[112:113] op_sel:[0,0] op_sel_hi:[0,1]
	v_pk_fma_f32 v[116:117], v[116:117], v[112:113], v[142:143] op_sel:[1,1,0] op_sel_hi:[1,0,1] neg_lo:[0,1,0]
	v_pk_mul_f32 v[142:143], v[158:159], v[116:117] op_sel:[0,0] op_sel_hi:[0,1]
	v_pk_mul_f32 v[148:149], v[116:117], v[112:113] op_sel:[0,0] op_sel_hi:[0,1]
	v_pk_fma_f32 v[142:143], v[158:159], v[116:117], v[142:143] op_sel:[1,1,0] op_sel_hi:[1,0,1] neg_lo:[0,1,0]
	v_pk_fma_f32 v[116:117], v[116:117], v[112:113], v[148:149] op_sel:[1,1,0] op_sel_hi:[1,0,1] neg_lo:[0,1,0]
	v_pk_mul_f32 v[148:149], v[154:155], v[116:117] op_sel:[0,0] op_sel_hi:[0,1]
	v_pk_fma_f32 v[148:149], v[154:155], v[116:117], v[148:149] op_sel:[1,1,0] op_sel_hi:[1,0,1] neg_lo:[0,1,0]
	ds_write2_b64 v134, v[142:143], v[148:149] offset0:136 offset1:153
	v_pk_mul_f32 v[142:143], v[116:117], v[112:113] op_sel:[0,0] op_sel_hi:[0,1]
	v_pk_fma_f32 v[116:117], v[116:117], v[112:113], v[142:143] op_sel:[1,1,0] op_sel_hi:[1,0,1] neg_lo:[0,1,0]
	v_pk_mul_f32 v[142:143], v[144:145], v[116:117] op_sel:[0,0] op_sel_hi:[0,1]
	v_pk_fma_f32 v[142:143], v[144:145], v[116:117], v[142:143] op_sel:[1,1,0] op_sel_hi:[1,0,1] neg_lo:[0,1,0]
	v_pk_mul_f32 v[144:145], v[116:117], v[112:113] op_sel:[0,0] op_sel_hi:[0,1]
	v_pk_fma_f32 v[116:117], v[116:117], v[112:113], v[144:145] op_sel:[1,1,0] op_sel_hi:[1,0,1] neg_lo:[0,1,0]
	v_pk_mul_f32 v[144:145], v[114:115], v[116:117] op_sel:[0,0] op_sel_hi:[0,1]
	v_pk_fma_f32 v[114:115], v[114:115], v[116:117], v[144:145] op_sel:[1,1,0] op_sel_hi:[1,0,1] neg_lo:[0,1,0]
	ds_write2_b64 v134, v[142:143], v[114:115] offset0:170 offset1:187
	v_pk_mul_f32 v[114:115], v[116:117], v[112:113] op_sel:[0,0] op_sel_hi:[0,1]
	v_pk_fma_f32 v[114:115], v[116:117], v[112:113], v[114:115] op_sel:[1,1,0] op_sel_hi:[1,0,1] neg_lo:[0,1,0]
	v_pk_mul_f32 v[116:117], v[152:153], v[114:115] op_sel:[0,0] op_sel_hi:[0,1]
	v_pk_mul_f32 v[142:143], v[114:115], v[112:113] op_sel:[0,0] op_sel_hi:[0,1]
	v_pk_fma_f32 v[116:117], v[152:153], v[114:115], v[116:117] op_sel:[1,1,0] op_sel_hi:[1,0,1] neg_lo:[0,1,0]
	v_pk_fma_f32 v[114:115], v[114:115], v[112:113], v[142:143] op_sel:[1,1,0] op_sel_hi:[1,0,1] neg_lo:[0,1,0]
	v_pk_mul_f32 v[142:143], v[146:147], v[114:115] op_sel:[0,0] op_sel_hi:[0,1]
	v_pk_fma_f32 v[142:143], v[146:147], v[114:115], v[142:143] op_sel:[1,1,0] op_sel_hi:[1,0,1] neg_lo:[0,1,0]
	ds_write2_b64 v134, v[116:117], v[142:143] offset0:204 offset1:221
	v_pk_mul_f32 v[116:117], v[114:115], v[112:113] op_sel:[0,0] op_sel_hi:[0,1]
	v_pk_fma_f32 v[114:115], v[114:115], v[112:113], v[116:117] op_sel:[1,1,0] op_sel_hi:[1,0,1] neg_lo:[0,1,0]
	v_pk_mul_f32 v[116:117], v[140:141], v[114:115] op_sel:[0,0] op_sel_hi:[0,1]
	v_pk_fma_f32 v[116:117], v[140:141], v[114:115], v[116:117] op_sel:[1,1,0] op_sel_hi:[1,0,1] neg_lo:[0,1,0]
	v_pk_mul_f32 v[140:141], v[114:115], v[112:113] op_sel:[0,0] op_sel_hi:[0,1]
	v_pk_fma_f32 v[112:113], v[114:115], v[112:113], v[140:141] op_sel:[1,1,0] op_sel_hi:[1,0,1] neg_lo:[0,1,0]
	v_pk_mul_f32 v[114:115], v[110:111], v[112:113] op_sel:[0,0] op_sel_hi:[0,1]
	v_pk_fma_f32 v[110:111], v[110:111], v[112:113], v[114:115] op_sel:[1,1,0] op_sel_hi:[1,0,1] neg_lo:[0,1,0]
	ds_write2_b64 v134, v[116:117], v[110:111] offset0:238 offset1:255
	s_waitcnt lgkmcnt(0)
	s_barrier
	ds_read2_b64 v[110:113], v135 offset1:1
	ds_read2_b64 v[114:117], v135 offset0:2 offset1:3
	ds_read2_b64 v[140:143], v135 offset0:8 offset1:9
	ds_read2_b64 v[144:147], v135 offset0:4 offset1:5
	ds_read2_b64 v[148:151], v135 offset0:6 offset1:7
	ds_read2_b64 v[152:155], v135 offset0:12 offset1:13
	ds_read2_b64 v[156:159], v135 offset0:10 offset1:11
	ds_read2_b64 v[160:163], v135 offset0:14 offset1:15
	s_waitcnt lgkmcnt(5)
	v_pk_add_f32 v[164:165], v[110:111], v[140:141]
	v_pk_add_f32 v[110:111], v[110:111], v[140:141] neg_lo:[0,1] neg_hi:[0,1]
	s_waitcnt lgkmcnt(2)
	v_pk_add_f32 v[140:141], v[144:145], v[152:153]
	v_pk_add_f32 v[144:145], v[144:145], v[152:153] neg_lo:[0,1] neg_hi:[0,1]
	v_pk_add_f32 v[152:153], v[164:165], v[140:141]
	v_pk_add_f32 v[140:141], v[164:165], v[140:141] neg_lo:[0,1] neg_hi:[0,1]
	v_pk_add_f32 v[164:165], v[110:111], v[144:145] op_sel:[0,1] op_sel_hi:[1,0] neg_hi:[0,1]
	v_pk_add_f32 v[110:111], v[110:111], v[144:145] op_sel:[0,1] op_sel_hi:[1,0] neg_lo:[0,1]
	v_pk_add_f32 v[144:145], v[112:113], v[142:143]
	v_pk_add_f32 v[112:113], v[112:113], v[142:143] neg_lo:[0,1] neg_hi:[0,1]
	v_pk_add_f32 v[142:143], v[146:147], v[154:155]
	v_pk_add_f32 v[146:147], v[146:147], v[154:155] neg_lo:[0,1] neg_hi:[0,1]
	v_pk_add_f32 v[154:155], v[144:145], v[142:143]
	v_pk_add_f32 v[142:143], v[144:145], v[142:143] neg_lo:[0,1] neg_hi:[0,1]
	v_pk_add_f32 v[144:145], v[112:113], v[146:147] op_sel:[0,1] op_sel_hi:[1,0] neg_hi:[0,1]
	v_pk_add_f32 v[112:113], v[112:113], v[146:147] op_sel:[0,1] op_sel_hi:[1,0] neg_lo:[0,1]
	s_waitcnt lgkmcnt(1)
	v_pk_add_f32 v[146:147], v[114:115], v[156:157]
	v_pk_add_f32 v[114:115], v[114:115], v[156:157] neg_lo:[0,1] neg_hi:[0,1]
	s_waitcnt lgkmcnt(0)
	v_pk_add_f32 v[156:157], v[148:149], v[160:161]
	v_pk_add_f32 v[148:149], v[148:149], v[160:161] neg_lo:[0,1] neg_hi:[0,1]
	v_pk_add_f32 v[160:161], v[146:147], v[156:157]
	v_pk_add_f32 v[146:147], v[146:147], v[156:157] neg_lo:[0,1] neg_hi:[0,1]
	v_pk_add_f32 v[156:157], v[114:115], v[148:149] op_sel:[0,1] op_sel_hi:[1,0] neg_hi:[0,1]
	v_pk_add_f32 v[114:115], v[114:115], v[148:149] op_sel:[0,1] op_sel_hi:[1,0] neg_lo:[0,1]
	v_pk_add_f32 v[148:149], v[116:117], v[158:159]
	v_pk_add_f32 v[116:117], v[116:117], v[158:159] neg_lo:[0,1] neg_hi:[0,1]
	v_pk_add_f32 v[158:159], v[150:151], v[162:163]
	v_pk_add_f32 v[150:151], v[150:151], v[162:163] neg_lo:[0,1] neg_hi:[0,1]
	v_pk_add_f32 v[162:163], v[148:149], v[158:159]
	v_pk_add_f32 v[148:149], v[148:149], v[158:159] neg_lo:[0,1] neg_hi:[0,1]
	v_pk_add_f32 v[158:159], v[116:117], v[150:151] op_sel:[0,1] op_sel_hi:[1,0] neg_hi:[0,1]
	v_pk_add_f32 v[116:117], v[116:117], v[150:151] op_sel:[0,1] op_sel_hi:[1,0] neg_lo:[0,1]
	v_pk_mul_f32 v[150:151], v[144:145], s[20:21] op_sel:[0,0] op_sel_hi:[0,1]
	v_pk_fma_f32 v[102:103], v[144:145], s[20:21], v[150:151] op_sel:[1,1,0] op_sel_hi:[1,0,1] neg_lo:[0,1,0]
	v_pk_mul_f32 v[144:145], v[156:157], s[46:47] op_sel:[0,0] op_sel_hi:[0,1]
	v_pk_mul_f32 v[150:151], v[158:159], s[50:51] op_sel:[0,0] op_sel_hi:[0,1]
	v_pk_fma_f32 v[144:145], v[156:157], s[46:47], v[144:145] op_sel:[1,1,0] op_sel_hi:[1,0,1] neg_lo:[0,1,0]
	v_pk_mul_f32 v[156:157], v[142:143], s[46:47] op_sel:[0,0] op_sel_hi:[0,1]
	v_pk_fma_f32 v[150:151], v[158:159], s[50:51], v[150:151] op_sel:[1,1,0] op_sel_hi:[1,0,1] neg_lo:[0,1,0]
	v_pk_fma_f32 v[98:99], v[142:143], s[46:47], v[156:157] op_sel:[1,1,0] op_sel_hi:[1,0,1] neg_lo:[0,1,0]
	v_pk_mul_f32 v[142:143], v[146:147], s[8:9] op_sel:[0,0] op_sel_hi:[0,1]
	v_pk_fma_f32 v[104:105], v[146:147], s[8:9], v[142:143] op_sel:[1,1,0] op_sel_hi:[1,0,1] neg_lo:[0,1,0]
	v_pk_mul_f32 v[142:143], v[148:149], s[54:55] op_sel:[0,0] op_sel_hi:[0,1]
	v_pk_mul_f32 v[146:147], v[112:113], s[50:51] op_sel:[0,0] op_sel_hi:[0,1]
	v_pk_fma_f32 v[96:97], v[112:113], s[50:51], v[146:147] op_sel:[1,1,0] op_sel_hi:[1,0,1] neg_lo:[0,1,0]
	v_pk_mul_f32 v[112:113], v[114:115], s[54:55] op_sel:[0,0] op_sel_hi:[0,1]
	v_pk_fma_f32 v[142:143], v[148:149], s[54:55], v[142:143] op_sel:[1,1,0] op_sel_hi:[1,0,1] neg_lo:[0,1,0]
	v_pk_add_f32 v[146:147], v[154:155], v[162:163] neg_lo:[0,1] neg_hi:[0,1]
	v_pk_fma_f32 v[100:101], v[114:115], s[54:55], v[112:113] op_sel:[1,1,0] op_sel_hi:[1,0,1] neg_lo:[0,1,0]
	v_pk_mul_f32 v[112:113], v[116:117], s[56:57] op_sel:[0,0] op_sel_hi:[0,1]
	v_pk_add_f32 v[114:115], v[152:153], v[160:161] neg_lo:[0,1] neg_hi:[0,1]
	v_pk_fma_f32 v[106:107], v[116:117], s[56:57], v[112:113] op_sel:[1,1,0] op_sel_hi:[1,0,1] neg_lo:[0,1,0]
	v_pk_add_f32 v[112:113], v[152:153], v[160:161]
	v_pk_add_f32 v[116:117], v[154:155], v[162:163]
	v_pk_add_f32 v[152:153], v[102:103], v[150:151]
	v_pk_add_f32 v[148:149], v[112:113], v[116:117]
	v_pk_add_f32 v[112:113], v[112:113], v[116:117] neg_lo:[0,1] neg_hi:[0,1]
	v_pk_add_f32 v[116:117], v[114:115], v[146:147] op_sel:[0,1] op_sel_hi:[1,0] neg_hi:[0,1]
	v_pk_add_f32 v[114:115], v[114:115], v[146:147] op_sel:[0,1] op_sel_hi:[1,0] neg_lo:[0,1]
	v_pk_add_f32 v[146:147], v[164:165], v[144:145]
	v_pk_add_f32 v[144:145], v[164:165], v[144:145] neg_lo:[0,1] neg_hi:[0,1]
	v_pk_add_f32 v[102:103], v[102:103], v[150:151] neg_lo:[0,1] neg_hi:[0,1]
	v_pk_add_f32 v[150:151], v[146:147], v[152:153]
	v_pk_add_f32 v[146:147], v[146:147], v[152:153] neg_lo:[0,1] neg_hi:[0,1]
	v_pk_add_f32 v[152:153], v[144:145], v[102:103] op_sel:[0,1] op_sel_hi:[1,0] neg_hi:[0,1]
	v_pk_add_f32 v[102:103], v[144:145], v[102:103] op_sel:[0,1] op_sel_hi:[1,0] neg_lo:[0,1]
	v_pk_add_f32 v[144:145], v[140:141], v[104:105]
	v_pk_add_f32 v[104:105], v[140:141], v[104:105] neg_lo:[0,1] neg_hi:[0,1]
	v_pk_add_f32 v[140:141], v[98:99], v[142:143]
	v_pk_add_f32 v[98:99], v[98:99], v[142:143] neg_lo:[0,1] neg_hi:[0,1]
	v_pk_add_f32 v[142:143], v[144:145], v[140:141]
	v_pk_add_f32 v[140:141], v[144:145], v[140:141] neg_lo:[0,1] neg_hi:[0,1]
	v_pk_add_f32 v[144:145], v[104:105], v[98:99] op_sel:[0,1] op_sel_hi:[1,0] neg_hi:[0,1]
	v_pk_add_f32 v[98:99], v[104:105], v[98:99] op_sel:[0,1] op_sel_hi:[1,0] neg_lo:[0,1]
	v_pk_add_f32 v[104:105], v[110:111], v[100:101]
	v_pk_add_f32 v[100:101], v[110:111], v[100:101] neg_lo:[0,1] neg_hi:[0,1]
	v_pk_add_f32 v[110:111], v[96:97], v[106:107]
	v_pk_add_f32 v[96:97], v[96:97], v[106:107] neg_lo:[0,1] neg_hi:[0,1]
	v_pk_add_f32 v[106:107], v[104:105], v[110:111]
	v_pk_add_f32 v[104:105], v[104:105], v[110:111] neg_lo:[0,1] neg_hi:[0,1]
	v_pk_add_f32 v[110:111], v[100:101], v[96:97] op_sel:[0,1] op_sel_hi:[1,0] neg_hi:[0,1]
	v_pk_add_f32 v[96:97], v[100:101], v[96:97] op_sel:[0,1] op_sel_hi:[1,0] neg_lo:[0,1]
	s_waitcnt vmcnt(15)
	v_pk_mul_f32 v[100:101], v[148:149], v[70:71] op_sel:[0,0] op_sel_hi:[0,1]
	v_pk_fma_f32 v[70:71], v[148:149], v[70:71], v[100:101] op_sel:[1,1,0] op_sel_hi:[1,0,1] neg_lo:[0,1,0]
	s_waitcnt vmcnt(14)
	v_pk_mul_f32 v[100:101], v[116:117], v[30:31] op_sel:[0,0] op_sel_hi:[0,1]
	v_pk_fma_f32 v[30:31], v[116:117], v[30:31], v[100:101] op_sel:[1,1,0] op_sel_hi:[1,0,1] neg_lo:[0,1,0]
	s_waitcnt vmcnt(13)
	v_pk_mul_f32 v[100:101], v[112:113], v[28:29] op_sel:[0,0] op_sel_hi:[0,1]
	v_pk_fma_f32 v[28:29], v[112:113], v[28:29], v[100:101] op_sel:[1,1,0] op_sel_hi:[1,0,1] neg_lo:[0,1,0]
	s_waitcnt vmcnt(12)
	v_pk_mul_f32 v[100:101], v[114:115], v[32:33] op_sel:[0,0] op_sel_hi:[0,1]
	v_pk_fma_f32 v[32:33], v[114:115], v[32:33], v[100:101] op_sel:[1,1,0] op_sel_hi:[1,0,1] neg_lo:[0,1,0]
	s_waitcnt vmcnt(11)
	v_pk_mul_f32 v[100:101], v[150:151], v[78:79] op_sel:[0,0] op_sel_hi:[0,1]
	v_pk_fma_f32 v[78:79], v[150:151], v[78:79], v[100:101] op_sel:[1,1,0] op_sel_hi:[1,0,1] neg_lo:[0,1,0]
	s_waitcnt vmcnt(10)
	v_pk_mul_f32 v[100:101], v[152:153], v[74:75] op_sel:[0,0] op_sel_hi:[0,1]
	v_pk_fma_f32 v[74:75], v[152:153], v[74:75], v[100:101] op_sel:[1,1,0] op_sel_hi:[1,0,1] neg_lo:[0,1,0]
	s_waitcnt vmcnt(9)
	v_pk_mul_f32 v[100:101], v[146:147], v[72:73] op_sel:[0,0] op_sel_hi:[0,1]
	v_pk_fma_f32 v[72:73], v[146:147], v[72:73], v[100:101] op_sel:[1,1,0] op_sel_hi:[1,0,1] neg_lo:[0,1,0]
	s_waitcnt vmcnt(8)
	v_pk_mul_f32 v[100:101], v[102:103], v[76:77] op_sel:[0,0] op_sel_hi:[0,1]
	v_pk_fma_f32 v[76:77], v[102:103], v[76:77], v[100:101] op_sel:[1,1,0] op_sel_hi:[1,0,1] neg_lo:[0,1,0]
	s_waitcnt vmcnt(7)
	v_pk_mul_f32 v[100:101], v[142:143], v[86:87] op_sel:[0,0] op_sel_hi:[0,1]
	v_pk_fma_f32 v[86:87], v[142:143], v[86:87], v[100:101] op_sel:[1,1,0] op_sel_hi:[1,0,1] neg_lo:[0,1,0]
	s_waitcnt vmcnt(6)
	v_pk_mul_f32 v[100:101], v[144:145], v[82:83] op_sel:[0,0] op_sel_hi:[0,1]
	v_pk_fma_f32 v[82:83], v[144:145], v[82:83], v[100:101] op_sel:[1,1,0] op_sel_hi:[1,0,1] neg_lo:[0,1,0]
	s_waitcnt vmcnt(5)
	v_pk_mul_f32 v[100:101], v[140:141], v[80:81] op_sel:[0,0] op_sel_hi:[0,1]
	v_pk_fma_f32 v[80:81], v[140:141], v[80:81], v[100:101] op_sel:[1,1,0] op_sel_hi:[1,0,1] neg_lo:[0,1,0]
	s_waitcnt vmcnt(4)
	v_pk_mul_f32 v[100:101], v[98:99], v[84:85] op_sel:[0,0] op_sel_hi:[0,1]
	v_pk_fma_f32 v[84:85], v[98:99], v[84:85], v[100:101] op_sel:[1,1,0] op_sel_hi:[1,0,1] neg_lo:[0,1,0]
	s_waitcnt vmcnt(3)
	v_pk_mul_f32 v[98:99], v[106:107], v[94:95] op_sel:[0,0] op_sel_hi:[0,1]
	v_pk_fma_f32 v[94:95], v[106:107], v[94:95], v[98:99] op_sel:[1,1,0] op_sel_hi:[1,0,1] neg_lo:[0,1,0]
	s_waitcnt vmcnt(2)
	v_pk_mul_f32 v[98:99], v[110:111], v[90:91] op_sel:[0,0] op_sel_hi:[0,1]
	v_pk_fma_f32 v[90:91], v[110:111], v[90:91], v[98:99] op_sel:[1,1,0] op_sel_hi:[1,0,1] neg_lo:[0,1,0]
	s_waitcnt vmcnt(1)
	v_pk_mul_f32 v[98:99], v[104:105], v[88:89] op_sel:[0,0] op_sel_hi:[0,1]
	v_pk_fma_f32 v[88:89], v[104:105], v[88:89], v[98:99] op_sel:[1,1,0] op_sel_hi:[1,0,1] neg_lo:[0,1,0]
	s_waitcnt vmcnt(0)
	v_pk_mul_f32 v[98:99], v[96:97], v[92:93] op_sel:[0,0] op_sel_hi:[0,1]
	v_pk_fma_f32 v[92:93], v[96:97], v[92:93], v[98:99] op_sel:[1,1,0] op_sel_hi:[1,0,1] neg_lo:[0,1,0]
	v_pk_add_f32 v[96:97], v[70:71], v[28:29]
	v_pk_add_f32 v[28:29], v[70:71], v[28:29] neg_lo:[0,1] neg_hi:[0,1]
	v_pk_add_f32 v[70:71], v[30:31], v[32:33]
	v_pk_add_f32 v[30:31], v[30:31], v[32:33] neg_lo:[0,1] neg_hi:[0,1]
	v_pk_add_f32 v[98:99], v[96:97], v[70:71]
	v_pk_add_f32 v[96:97], v[96:97], v[70:71] neg_lo:[0,1] neg_hi:[0,1]
	v_pk_add_f32 v[100:101], v[28:29], v[30:31] op_sel:[0,1] op_sel_hi:[1,0] neg_lo:[0,1]
	v_pk_add_f32 v[102:103], v[28:29], v[30:31] op_sel:[0,1] op_sel_hi:[1,0] neg_hi:[0,1]
	v_pk_add_f32 v[28:29], v[78:79], v[72:73]
	v_pk_add_f32 v[30:31], v[78:79], v[72:73] neg_lo:[0,1] neg_hi:[0,1]
	v_pk_add_f32 v[32:33], v[74:75], v[76:77]
	v_pk_add_f32 v[70:71], v[74:75], v[76:77] neg_lo:[0,1] neg_hi:[0,1]
	v_pk_add_f32 v[76:77], v[28:29], v[32:33]
	v_pk_add_f32 v[32:33], v[28:29], v[32:33] neg_lo:[0,1] neg_hi:[0,1]
	v_pk_add_f32 v[28:29], v[30:31], v[70:71] op_sel:[0,1] op_sel_hi:[1,0] neg_lo:[0,1]
	v_pk_add_f32 v[74:75], v[30:31], v[70:71] op_sel:[0,1] op_sel_hi:[1,0] neg_hi:[0,1]
	v_pk_add_f32 v[30:31], v[86:87], v[80:81]
	v_pk_add_f32 v[70:71], v[86:87], v[80:81] neg_lo:[0,1] neg_hi:[0,1]
	v_pk_add_f32 v[72:73], v[82:83], v[84:85]
	v_pk_add_f32 v[78:79], v[82:83], v[84:85] neg_lo:[0,1] neg_hi:[0,1]
	v_pk_add_f32 v[80:81], v[30:31], v[72:73]
	v_pk_add_f32 v[82:83], v[30:31], v[72:73] neg_lo:[0,1] neg_hi:[0,1]
	v_pk_add_f32 v[72:73], v[70:71], v[78:79] op_sel:[0,1] op_sel_hi:[1,0] neg_lo:[0,1]
	v_pk_add_f32 v[78:79], v[70:71], v[78:79] op_sel:[0,1] op_sel_hi:[1,0] neg_hi:[0,1]
	v_pk_add_f32 v[30:31], v[94:95], v[88:89]
	v_pk_add_f32 v[70:71], v[94:95], v[88:89] neg_lo:[0,1] neg_hi:[0,1]
	v_pk_add_f32 v[84:85], v[90:91], v[92:93]
	v_pk_add_f32 v[86:87], v[90:91], v[92:93] neg_lo:[0,1] neg_hi:[0,1]
	v_pk_add_f32 v[88:89], v[30:31], v[84:85]
	v_pk_add_f32 v[84:85], v[30:31], v[84:85] neg_lo:[0,1] neg_hi:[0,1]
	v_pk_add_f32 v[90:91], v[70:71], v[86:87] op_sel:[0,1] op_sel_hi:[1,0] neg_lo:[0,1]
	v_pk_add_f32 v[86:87], v[70:71], v[86:87] op_sel:[0,1] op_sel_hi:[1,0] neg_hi:[0,1]
	v_pk_mul_f32 v[30:31], v[28:29], s[58:59] op_sel:[0,0] op_sel_hi:[0,1]
	v_pk_fma_f32 v[92:93], v[28:29], s[58:59], v[30:31] op_sel:[1,1,0] op_sel_hi:[1,0,1] neg_lo:[0,1,0]
	v_pk_mul_f32 v[28:29], v[72:73], s[60:61] op_sel:[0,0] op_sel_hi:[0,1]
	v_pk_fma_f32 v[94:95], v[72:73], s[60:61], v[28:29] op_sel:[1,1,0] op_sel_hi:[1,0,1] neg_lo:[0,1,0]
	v_pk_mul_f32 v[72:73], v[90:91], s[62:63] op_sel:[0,0] op_sel_hi:[0,1]
	v_pk_fma_f32 v[90:91], v[90:91], s[62:63], v[72:73] op_sel:[1,1,0] op_sel_hi:[1,0,1] neg_lo:[0,1,0]
	v_pk_mul_f32 v[72:73], v[32:33], s[60:61] op_sel:[0,0] op_sel_hi:[0,1]
	v_pk_fma_f32 v[104:105], v[32:33], s[60:61], v[72:73] op_sel:[1,1,0] op_sel_hi:[1,0,1] neg_lo:[0,1,0]
	v_pk_mul_f32 v[32:33], v[82:83], s[64:65] op_sel:[0,0] op_sel_hi:[0,1]
	v_pk_fma_f32 v[82:83], v[82:83], s[64:65], v[32:33] op_sel:[1,1,0] op_sel_hi:[1,0,1] neg_lo:[0,1,0]
	v_pk_mul_f32 v[106:107], v[84:85], s[66:67] op_sel:[0,0] op_sel_hi:[0,1]
	v_pk_fma_f32 v[84:85], v[84:85], s[66:67], v[106:107] op_sel:[1,1,0] op_sel_hi:[1,0,1] neg_lo:[0,1,0]
	v_pk_mul_f32 v[106:107], v[74:75], s[62:63] op_sel:[0,0] op_sel_hi:[0,1]
	v_pk_fma_f32 v[106:107], v[74:75], s[62:63], v[106:107] op_sel:[1,1,0] op_sel_hi:[1,0,1] neg_lo:[0,1,0]
	v_pk_mul_f32 v[74:75], v[78:79], s[66:67] op_sel:[0,0] op_sel_hi:[0,1]
	v_pk_fma_f32 v[78:79], v[78:79], s[66:67], v[74:75] op_sel:[1,1,0] op_sel_hi:[1,0,1] neg_lo:[0,1,0]
	v_pk_mul_f32 v[110:111], v[86:87], s[68:69] op_sel:[0,0] op_sel_hi:[0,1]
	v_pk_fma_f32 v[86:87], v[86:87], s[68:69], v[110:111] op_sel:[1,1,0] op_sel_hi:[1,0,1] neg_lo:[0,1,0]
	v_pk_add_f32 v[110:111], v[98:99], v[80:81]
	v_pk_add_f32 v[80:81], v[98:99], v[80:81] neg_lo:[0,1] neg_hi:[0,1]
	v_pk_add_f32 v[98:99], v[76:77], v[88:89]
	v_pk_add_f32 v[76:77], v[76:77], v[88:89] neg_lo:[0,1] neg_hi:[0,1]
	v_pk_add_f32 v[88:89], v[110:111], v[98:99]
	v_pk_add_f32 v[98:99], v[110:111], v[98:99] neg_lo:[0,1] neg_hi:[0,1]
	v_pk_add_f32 v[110:111], v[80:81], v[76:77] op_sel:[0,1] op_sel_hi:[1,0] neg_lo:[0,1]
	v_pk_add_f32 v[76:77], v[80:81], v[76:77] op_sel:[0,1] op_sel_hi:[1,0] neg_hi:[0,1]
	v_pk_add_f32 v[80:81], v[100:101], v[94:95]
	v_pk_add_f32 v[94:95], v[100:101], v[94:95] neg_lo:[0,1] neg_hi:[0,1]
	v_pk_add_f32 v[100:101], v[92:93], v[90:91]
	v_pk_add_f32 v[90:91], v[92:93], v[90:91] neg_lo:[0,1] neg_hi:[0,1]
	v_pk_add_f32 v[92:93], v[80:81], v[100:101]
	v_pk_add_f32 v[80:81], v[80:81], v[100:101] neg_lo:[0,1] neg_hi:[0,1]
	v_pk_add_f32 v[100:101], v[94:95], v[90:91] op_sel:[0,1] op_sel_hi:[1,0] neg_lo:[0,1]
	v_pk_add_f32 v[90:91], v[94:95], v[90:91] op_sel:[0,1] op_sel_hi:[1,0] neg_hi:[0,1]
	v_pk_add_f32 v[94:95], v[96:97], v[82:83]
	v_pk_add_f32 v[82:83], v[96:97], v[82:83] neg_lo:[0,1] neg_hi:[0,1]
	v_pk_add_f32 v[96:97], v[104:105], v[84:85]
	v_pk_add_f32 v[84:85], v[104:105], v[84:85] neg_lo:[0,1] neg_hi:[0,1]
	v_pk_add_f32 v[104:105], v[94:95], v[96:97]
	v_pk_add_f32 v[94:95], v[94:95], v[96:97] neg_lo:[0,1] neg_hi:[0,1]
	v_pk_add_f32 v[96:97], v[82:83], v[84:85] op_sel:[0,1] op_sel_hi:[1,0] neg_lo:[0,1]
	v_pk_add_f32 v[82:83], v[82:83], v[84:85] op_sel:[0,1] op_sel_hi:[1,0] neg_hi:[0,1]
	v_pk_add_f32 v[84:85], v[102:103], v[78:79]
	v_pk_add_f32 v[78:79], v[102:103], v[78:79] neg_lo:[0,1] neg_hi:[0,1]
	v_pk_add_f32 v[102:103], v[106:107], v[86:87]
	v_pk_add_f32 v[86:87], v[106:107], v[86:87] neg_lo:[0,1] neg_hi:[0,1]
	v_pk_add_f32 v[106:107], v[84:85], v[102:103]
	v_pk_add_f32 v[84:85], v[84:85], v[102:103] neg_lo:[0,1] neg_hi:[0,1]
	v_pk_add_f32 v[102:103], v[78:79], v[86:87] op_sel:[0,1] op_sel_hi:[1,0] neg_lo:[0,1]
	v_pk_add_f32 v[78:79], v[78:79], v[86:87] op_sel:[0,1] op_sel_hi:[1,0] neg_hi:[0,1]
	v_mov_b32_e32 v86, v40
	v_mov_b32_e32 v87, v41
	ds_write2_b64 v135, v[88:89], v[92:93] offset1:1
	ds_write2_b64 v135, v[104:105], v[106:107] offset0:2 offset1:3
	ds_write2_b64 v135, v[110:111], v[100:101] offset0:4 offset1:5
	ds_write2_b64 v135, v[96:97], v[102:103] offset0:6 offset1:7
	ds_write2_b64 v135, v[98:99], v[80:81] offset0:8 offset1:9
	ds_write2_b64 v135, v[94:95], v[84:85] offset0:10 offset1:11
	ds_write2_b64 v135, v[76:77], v[90:91] offset0:12 offset1:13
	ds_write2_b64 v135, v[82:83], v[78:79] offset0:14 offset1:15
	s_waitcnt lgkmcnt(0)
	s_barrier
	ds_read2_b64 v[76:79], v134 offset1:17
	ds_read2_b64 v[80:83], v134 offset0:34 offset1:51
	s_waitcnt lgkmcnt(1)
	v_pk_mul_f32 v[84:85], v[78:79], v[86:87] op_sel:[0,0] op_sel_hi:[0,1] neg_hi:[0,1]
	v_pk_fma_f32 v[88:89], v[78:79], v[86:87], v[84:85] op_sel:[1,1,0] op_sel_hi:[1,0,1]
	v_pk_mul_f32 v[78:79], v[86:87], v[86:87] op_sel:[0,0] op_sel_hi:[0,1]
	v_pk_fma_f32 v[78:79], v[86:87], v[86:87], v[78:79] op_sel:[1,1,0] op_sel_hi:[1,0,1] neg_lo:[0,1,0]
	s_waitcnt lgkmcnt(0)
	v_pk_mul_f32 v[84:85], v[80:81], v[78:79] op_sel:[0,0] op_sel_hi:[0,1] neg_hi:[0,1]
	v_pk_fma_f32 v[90:91], v[80:81], v[78:79], v[84:85] op_sel:[1,1,0] op_sel_hi:[1,0,1]
	v_pk_mul_f32 v[80:81], v[78:79], v[86:87] op_sel:[0,0] op_sel_hi:[0,1]
	v_pk_fma_f32 v[84:85], v[78:79], v[86:87], v[80:81] op_sel:[1,1,0] op_sel_hi:[1,0,1] neg_lo:[0,1,0]
	ds_read2_b64 v[78:81], v134 offset0:68 offset1:85
	v_pk_mul_f32 v[92:93], v[82:83], v[84:85] op_sel:[0,0] op_sel_hi:[0,1] neg_hi:[0,1]
	v_pk_fma_f32 v[92:93], v[82:83], v[84:85], v[92:93] op_sel:[1,1,0] op_sel_hi:[1,0,1]
	v_pk_mul_f32 v[82:83], v[84:85], v[86:87] op_sel:[0,0] op_sel_hi:[0,1]
	v_pk_fma_f32 v[82:83], v[84:85], v[86:87], v[82:83] op_sel:[1,1,0] op_sel_hi:[1,0,1] neg_lo:[0,1,0]
	s_waitcnt lgkmcnt(0)
	v_pk_mul_f32 v[84:85], v[78:79], v[82:83] op_sel:[0,0] op_sel_hi:[0,1] neg_hi:[0,1]
	v_pk_fma_f32 v[94:95], v[78:79], v[82:83], v[84:85] op_sel:[1,1,0] op_sel_hi:[1,0,1]
	v_pk_mul_f32 v[78:79], v[82:83], v[86:87] op_sel:[0,0] op_sel_hi:[0,1]
	v_pk_fma_f32 v[78:79], v[82:83], v[86:87], v[78:79] op_sel:[1,1,0] op_sel_hi:[1,0,1] neg_lo:[0,1,0]
	ds_read2_b64 v[82:85], v134 offset0:102 offset1:119
	v_pk_mul_f32 v[96:97], v[80:81], v[78:79] op_sel:[0,0] op_sel_hi:[0,1] neg_hi:[0,1]
	v_pk_fma_f32 v[96:97], v[80:81], v[78:79], v[96:97] op_sel:[1,1,0] op_sel_hi:[1,0,1]
	v_pk_mul_f32 v[80:81], v[78:79], v[86:87] op_sel:[0,0] op_sel_hi:[0,1]
	v_pk_fma_f32 v[78:79], v[78:79], v[86:87], v[80:81] op_sel:[1,1,0] op_sel_hi:[1,0,1] neg_lo:[0,1,0]
	s_waitcnt lgkmcnt(0)
	v_pk_mul_f32 v[80:81], v[82:83], v[78:79] op_sel:[0,0] op_sel_hi:[0,1] neg_hi:[0,1]
	v_pk_fma_f32 v[98:99], v[82:83], v[78:79], v[80:81] op_sel:[1,1,0] op_sel_hi:[1,0,1]
	v_pk_mul_f32 v[80:81], v[78:79], v[86:87] op_sel:[0,0] op_sel_hi:[0,1]
	v_pk_fma_f32 v[82:83], v[78:79], v[86:87], v[80:81] op_sel:[1,1,0] op_sel_hi:[1,0,1] neg_lo:[0,1,0]
	ds_read2_b64 v[78:81], v134 offset0:136 offset1:153
	v_pk_mul_f32 v[100:101], v[84:85], v[82:83] op_sel:[0,0] op_sel_hi:[0,1] neg_hi:[0,1]
	v_pk_fma_f32 v[100:101], v[84:85], v[82:83], v[100:101] op_sel:[1,1,0] op_sel_hi:[1,0,1]
	v_pk_mul_f32 v[84:85], v[82:83], v[86:87] op_sel:[0,0] op_sel_hi:[0,1]
	v_pk_fma_f32 v[82:83], v[82:83], v[86:87], v[84:85] op_sel:[1,1,0] op_sel_hi:[1,0,1] neg_lo:[0,1,0]
	s_waitcnt lgkmcnt(0)
	v_pk_mul_f32 v[84:85], v[78:79], v[82:83] op_sel:[0,0] op_sel_hi:[0,1] neg_hi:[0,1]
	v_pk_fma_f32 v[102:103], v[78:79], v[82:83], v[84:85] op_sel:[1,1,0] op_sel_hi:[1,0,1]
	v_pk_mul_f32 v[78:79], v[82:83], v[86:87] op_sel:[0,0] op_sel_hi:[0,1]
	v_pk_fma_f32 v[78:79], v[82:83], v[86:87], v[78:79] op_sel:[1,1,0] op_sel_hi:[1,0,1] neg_lo:[0,1,0]
	ds_read2_b64 v[82:85], v134 offset0:170 offset1:187
	v_pk_mul_f32 v[104:105], v[80:81], v[78:79] op_sel:[0,0] op_sel_hi:[0,1] neg_hi:[0,1]
	v_pk_fma_f32 v[104:105], v[80:81], v[78:79], v[104:105] op_sel:[1,1,0] op_sel_hi:[1,0,1]
	v_pk_mul_f32 v[80:81], v[78:79], v[86:87] op_sel:[0,0] op_sel_hi:[0,1]
	v_pk_fma_f32 v[78:79], v[78:79], v[86:87], v[80:81] op_sel:[1,1,0] op_sel_hi:[1,0,1] neg_lo:[0,1,0]
	s_waitcnt lgkmcnt(0)
	v_pk_mul_f32 v[80:81], v[82:83], v[78:79] op_sel:[0,0] op_sel_hi:[0,1] neg_hi:[0,1]
	v_pk_fma_f32 v[106:107], v[82:83], v[78:79], v[80:81] op_sel:[1,1,0] op_sel_hi:[1,0,1]
	v_pk_mul_f32 v[80:81], v[78:79], v[86:87] op_sel:[0,0] op_sel_hi:[0,1]
	v_pk_fma_f32 v[82:83], v[78:79], v[86:87], v[80:81] op_sel:[1,1,0] op_sel_hi:[1,0,1] neg_lo:[0,1,0]
	ds_read2_b64 v[78:81], v134 offset0:204 offset1:221
	v_pk_mul_f32 v[110:111], v[84:85], v[82:83] op_sel:[0,0] op_sel_hi:[0,1] neg_hi:[0,1]
	v_pk_fma_f32 v[110:111], v[84:85], v[82:83], v[110:111] op_sel:[1,1,0] op_sel_hi:[1,0,1]
	v_pk_mul_f32 v[84:85], v[82:83], v[86:87] op_sel:[0,0] op_sel_hi:[0,1]
	v_pk_fma_f32 v[82:83], v[82:83], v[86:87], v[84:85] op_sel:[1,1,0] op_sel_hi:[1,0,1] neg_lo:[0,1,0]
	s_waitcnt lgkmcnt(0)
	v_pk_mul_f32 v[84:85], v[78:79], v[82:83] op_sel:[0,0] op_sel_hi:[0,1] neg_hi:[0,1]
	v_pk_fma_f32 v[78:79], v[78:79], v[82:83], v[84:85] op_sel:[1,1,0] op_sel_hi:[1,0,1]
	v_pk_mul_f32 v[84:85], v[82:83], v[86:87] op_sel:[0,0] op_sel_hi:[0,1]
	v_pk_fma_f32 v[112:113], v[82:83], v[86:87], v[84:85] op_sel:[1,1,0] op_sel_hi:[1,0,1] neg_lo:[0,1,0]
	ds_read2_b64 v[82:85], v134 offset0:238 offset1:255
	v_pk_mul_f32 v[114:115], v[80:81], v[112:113] op_sel:[0,0] op_sel_hi:[0,1] neg_hi:[0,1]
	v_pk_fma_f32 v[80:81], v[80:81], v[112:113], v[114:115] op_sel:[1,1,0] op_sel_hi:[1,0,1]
	v_pk_mul_f32 v[114:115], v[112:113], v[86:87] op_sel:[0,0] op_sel_hi:[0,1]
	v_pk_fma_f32 v[112:113], v[112:113], v[86:87], v[114:115] op_sel:[1,1,0] op_sel_hi:[1,0,1] neg_lo:[0,1,0]
	s_waitcnt lgkmcnt(0)
	v_pk_mul_f32 v[114:115], v[82:83], v[112:113] op_sel:[0,0] op_sel_hi:[0,1] neg_hi:[0,1]
	v_pk_fma_f32 v[82:83], v[82:83], v[112:113], v[114:115] op_sel:[1,1,0] op_sel_hi:[1,0,1]
	v_pk_mul_f32 v[114:115], v[112:113], v[86:87] op_sel:[0,0] op_sel_hi:[0,1]
	v_pk_fma_f32 v[86:87], v[112:113], v[86:87], v[114:115] op_sel:[1,1,0] op_sel_hi:[1,0,1] neg_lo:[0,1,0]
	v_pk_mul_f32 v[112:113], v[84:85], v[86:87] op_sel:[0,0] op_sel_hi:[0,1] neg_hi:[0,1]
	v_pk_fma_f32 v[84:85], v[84:85], v[86:87], v[112:113] op_sel:[1,1,0] op_sel_hi:[1,0,1]
	v_pk_add_f32 v[86:87], v[76:77], v[102:103]
	v_pk_add_f32 v[76:77], v[76:77], v[102:103] neg_lo:[0,1] neg_hi:[0,1]
	v_pk_add_f32 v[102:103], v[94:95], v[78:79]
	v_pk_add_f32 v[78:79], v[94:95], v[78:79] neg_lo:[0,1] neg_hi:[0,1]
	v_pk_add_f32 v[94:95], v[86:87], v[102:103]
	v_pk_add_f32 v[86:87], v[86:87], v[102:103] neg_lo:[0,1] neg_hi:[0,1]
	v_pk_add_f32 v[102:103], v[76:77], v[78:79] op_sel:[0,1] op_sel_hi:[1,0] neg_lo:[0,1]
	v_pk_add_f32 v[76:77], v[76:77], v[78:79] op_sel:[0,1] op_sel_hi:[1,0] neg_hi:[0,1]
	v_pk_add_f32 v[78:79], v[88:89], v[104:105]
	v_pk_add_f32 v[88:89], v[88:89], v[104:105] neg_lo:[0,1] neg_hi:[0,1]
	v_pk_add_f32 v[104:105], v[96:97], v[80:81]
	v_pk_add_f32 v[80:81], v[96:97], v[80:81] neg_lo:[0,1] neg_hi:[0,1]
	v_pk_add_f32 v[96:97], v[78:79], v[104:105]
	v_pk_add_f32 v[78:79], v[78:79], v[104:105] neg_lo:[0,1] neg_hi:[0,1]
	v_pk_add_f32 v[104:105], v[88:89], v[80:81] op_sel:[0,1] op_sel_hi:[1,0] neg_lo:[0,1]
	v_pk_add_f32 v[80:81], v[88:89], v[80:81] op_sel:[0,1] op_sel_hi:[1,0] neg_hi:[0,1]
	v_pk_add_f32 v[88:89], v[90:91], v[106:107]
	v_pk_add_f32 v[90:91], v[90:91], v[106:107] neg_lo:[0,1] neg_hi:[0,1]
	v_pk_add_f32 v[106:107], v[98:99], v[82:83]
	v_pk_add_f32 v[82:83], v[98:99], v[82:83] neg_lo:[0,1] neg_hi:[0,1]
	v_pk_add_f32 v[98:99], v[88:89], v[106:107]
	v_pk_add_f32 v[88:89], v[88:89], v[106:107] neg_lo:[0,1] neg_hi:[0,1]
	v_pk_add_f32 v[106:107], v[90:91], v[82:83] op_sel:[0,1] op_sel_hi:[1,0] neg_lo:[0,1]
	v_pk_add_f32 v[82:83], v[90:91], v[82:83] op_sel:[0,1] op_sel_hi:[1,0] neg_hi:[0,1]
	v_pk_add_f32 v[90:91], v[92:93], v[110:111]
	v_pk_add_f32 v[92:93], v[92:93], v[110:111] neg_lo:[0,1] neg_hi:[0,1]
	v_pk_add_f32 v[110:111], v[100:101], v[84:85]
	v_pk_add_f32 v[84:85], v[100:101], v[84:85] neg_lo:[0,1] neg_hi:[0,1]
	v_pk_add_f32 v[100:101], v[90:91], v[110:111]
	v_pk_add_f32 v[90:91], v[90:91], v[110:111] neg_lo:[0,1] neg_hi:[0,1]
	v_pk_add_f32 v[110:111], v[92:93], v[84:85] op_sel:[0,1] op_sel_hi:[1,0] neg_lo:[0,1]
	v_pk_add_f32 v[84:85], v[92:93], v[84:85] op_sel:[0,1] op_sel_hi:[1,0] neg_hi:[0,1]
	v_pk_mul_f32 v[92:93], v[104:105], s[58:59] op_sel:[0,0] op_sel_hi:[0,1]
	v_pk_fma_f32 v[92:93], v[104:105], s[58:59], v[92:93] op_sel:[1,1,0] op_sel_hi:[1,0,1] neg_lo:[0,1,0]
	v_pk_mul_f32 v[104:105], v[106:107], s[60:61] op_sel:[0,0] op_sel_hi:[0,1]
	v_pk_fma_f32 v[104:105], v[106:107], s[60:61], v[104:105] op_sel:[1,1,0] op_sel_hi:[1,0,1] neg_lo:[0,1,0]
	v_pk_mul_f32 v[106:107], v[110:111], s[62:63] op_sel:[0,0] op_sel_hi:[0,1]
	v_pk_fma_f32 v[106:107], v[110:111], s[62:63], v[106:107] op_sel:[1,1,0] op_sel_hi:[1,0,1] neg_lo:[0,1,0]
	v_pk_mul_f32 v[110:111], v[78:79], s[60:61] op_sel:[0,0] op_sel_hi:[0,1]
	v_pk_fma_f32 v[78:79], v[78:79], s[60:61], v[110:111] op_sel:[1,1,0] op_sel_hi:[1,0,1] neg_lo:[0,1,0]
	v_pk_mul_f32 v[110:111], v[88:89], s[64:65] op_sel:[0,0] op_sel_hi:[0,1]
	v_pk_fma_f32 v[88:89], v[88:89], s[64:65], v[110:111] op_sel:[1,1,0] op_sel_hi:[1,0,1] neg_lo:[0,1,0]
	v_pk_mul_f32 v[110:111], v[90:91], s[66:67] op_sel:[0,0] op_sel_hi:[0,1]
	v_pk_fma_f32 v[90:91], v[90:91], s[66:67], v[110:111] op_sel:[1,1,0] op_sel_hi:[1,0,1] neg_lo:[0,1,0]
	v_pk_mul_f32 v[110:111], v[80:81], s[62:63] op_sel:[0,0] op_sel_hi:[0,1]
	v_pk_fma_f32 v[80:81], v[80:81], s[62:63], v[110:111] op_sel:[1,1,0] op_sel_hi:[1,0,1] neg_lo:[0,1,0]
	v_pk_mul_f32 v[110:111], v[82:83], s[66:67] op_sel:[0,0] op_sel_hi:[0,1]
	v_pk_fma_f32 v[82:83], v[82:83], s[66:67], v[110:111] op_sel:[1,1,0] op_sel_hi:[1,0,1] neg_lo:[0,1,0]
	v_pk_mul_f32 v[110:111], v[84:85], s[68:69] op_sel:[0,0] op_sel_hi:[0,1]
	v_pk_fma_f32 v[84:85], v[84:85], s[68:69], v[110:111] op_sel:[1,1,0] op_sel_hi:[1,0,1] neg_lo:[0,1,0]
	v_pk_add_f32 v[110:111], v[94:95], v[98:99]
	v_pk_add_f32 v[94:95], v[94:95], v[98:99] neg_lo:[0,1] neg_hi:[0,1]
	v_pk_add_f32 v[98:99], v[96:97], v[100:101]
	v_pk_add_f32 v[96:97], v[96:97], v[100:101] neg_lo:[0,1] neg_hi:[0,1]
	v_pk_add_f32 v[100:101], v[110:111], v[98:99]
	v_pk_add_f32 v[98:99], v[110:111], v[98:99] neg_lo:[0,1] neg_hi:[0,1]
	v_pk_add_f32 v[110:111], v[94:95], v[96:97] op_sel:[0,1] op_sel_hi:[1,0] neg_lo:[0,1]
	v_pk_add_f32 v[94:95], v[94:95], v[96:97] op_sel:[0,1] op_sel_hi:[1,0] neg_hi:[0,1]
	v_pk_add_f32 v[96:97], v[102:103], v[104:105]
	v_pk_add_f32 v[102:103], v[102:103], v[104:105] neg_lo:[0,1] neg_hi:[0,1]
	v_pk_add_f32 v[104:105], v[92:93], v[106:107]
	v_pk_add_f32 v[92:93], v[92:93], v[106:107] neg_lo:[0,1] neg_hi:[0,1]
	v_pk_add_f32 v[106:107], v[96:97], v[104:105]
	v_pk_add_f32 v[96:97], v[96:97], v[104:105] neg_lo:[0,1] neg_hi:[0,1]
	v_pk_add_f32 v[104:105], v[102:103], v[92:93] op_sel:[0,1] op_sel_hi:[1,0] neg_lo:[0,1]
	v_pk_add_f32 v[92:93], v[102:103], v[92:93] op_sel:[0,1] op_sel_hi:[1,0] neg_hi:[0,1]
	v_pk_add_f32 v[102:103], v[86:87], v[88:89]
	v_pk_add_f32 v[86:87], v[86:87], v[88:89] neg_lo:[0,1] neg_hi:[0,1]
	v_pk_add_f32 v[88:89], v[78:79], v[90:91]
	v_pk_add_f32 v[78:79], v[78:79], v[90:91] neg_lo:[0,1] neg_hi:[0,1]
	v_pk_add_f32 v[90:91], v[102:103], v[88:89]
	v_pk_add_f32 v[88:89], v[102:103], v[88:89] neg_lo:[0,1] neg_hi:[0,1]
	v_pk_add_f32 v[102:103], v[86:87], v[78:79] op_sel:[0,1] op_sel_hi:[1,0] neg_lo:[0,1]
	v_pk_add_f32 v[78:79], v[86:87], v[78:79] op_sel:[0,1] op_sel_hi:[1,0] neg_hi:[0,1]
	v_pk_add_f32 v[86:87], v[76:77], v[82:83]
	v_pk_add_f32 v[76:77], v[76:77], v[82:83] neg_lo:[0,1] neg_hi:[0,1]
	v_pk_add_f32 v[82:83], v[80:81], v[84:85]
	v_pk_add_f32 v[80:81], v[80:81], v[84:85] neg_lo:[0,1] neg_hi:[0,1]
	v_pk_add_f32 v[84:85], v[86:87], v[82:83]
	v_pk_add_f32 v[82:83], v[86:87], v[82:83] neg_lo:[0,1] neg_hi:[0,1]
	v_pk_add_f32 v[86:87], v[76:77], v[80:81] op_sel:[0,1] op_sel_hi:[1,0] neg_lo:[0,1]
	v_pk_add_f32 v[76:77], v[76:77], v[80:81] op_sel:[0,1] op_sel_hi:[1,0] neg_hi:[0,1]
	ds_write2_b64 v134, v[100:101], v[106:107] offset1:17
	ds_write2_b64 v134, v[90:91], v[84:85] offset0:34 offset1:51
	ds_write2_b64 v134, v[110:111], v[104:105] offset0:68 offset1:85
	ds_write2_b64 v134, v[102:103], v[86:87] offset0:102 offset1:119
	ds_write2_b64 v134, v[98:99], v[96:97] offset0:136 offset1:153
	ds_write2_b64 v134, v[88:89], v[82:83] offset0:170 offset1:187
	ds_write2_b64 v134, v[94:95], v[92:93] offset0:204 offset1:221
	ds_write2_b64 v134, v[78:79], v[76:77] offset0:238 offset1:255
	v_mov_b32_e32 v77, v39
	v_mov_b32_e32 v76, v38
	s_waitcnt lgkmcnt(0)
	s_barrier
	ds_read_b64 v[78:79], v132 offset:2176
	ds_read_b64 v[80:81], v132 offset:4352
	ds_read_b64 v[82:83], v132 offset:6528
	ds_read_b64 v[84:85], v132
	s_waitcnt lgkmcnt(3)
	v_pk_mul_f32 v[86:87], v[78:79], v[76:77] op_sel:[0,0] op_sel_hi:[0,1] neg_hi:[0,1]
	v_pk_fma_f32 v[78:79], v[78:79], v[76:77], v[86:87] op_sel:[1,1,0] op_sel_hi:[1,0,1]
	v_pk_mul_f32 v[86:87], v[76:77], v[76:77] op_sel:[0,0] op_sel_hi:[0,1]
	ds_read_b64 v[90:91], v132 offset:8704
	v_pk_fma_f32 v[86:87], v[76:77], v[76:77], v[86:87] op_sel:[1,1,0] op_sel_hi:[1,0,1] neg_lo:[0,1,0]
	s_waitcnt lgkmcnt(3)
	v_pk_mul_f32 v[88:89], v[80:81], v[86:87] op_sel:[0,0] op_sel_hi:[0,1] neg_hi:[0,1]
	v_pk_fma_f32 v[80:81], v[80:81], v[86:87], v[88:89] op_sel:[1,1,0] op_sel_hi:[1,0,1]
	v_pk_mul_f32 v[88:89], v[86:87], v[76:77] op_sel:[0,0] op_sel_hi:[0,1]
	v_pk_fma_f32 v[86:87], v[86:87], v[76:77], v[88:89] op_sel:[1,1,0] op_sel_hi:[1,0,1] neg_lo:[0,1,0]
	s_waitcnt lgkmcnt(2)
	v_pk_mul_f32 v[88:89], v[82:83], v[86:87] op_sel:[0,0] op_sel_hi:[0,1] neg_hi:[0,1]
	v_pk_fma_f32 v[82:83], v[82:83], v[86:87], v[88:89] op_sel:[1,1,0] op_sel_hi:[1,0,1]
	v_pk_mul_f32 v[88:89], v[86:87], v[76:77] op_sel:[0,0] op_sel_hi:[0,1]
	v_pk_fma_f32 v[86:87], v[86:87], v[76:77], v[88:89] op_sel:[1,1,0] op_sel_hi:[1,0,1] neg_lo:[0,1,0]
	ds_read_b64 v[88:89], v132 offset:10880
	ds_read_b64 v[92:93], v132 offset:13056
	ds_read_b64 v[94:95], v132 offset:15232
	s_waitcnt lgkmcnt(3)
	v_pk_mul_f32 v[96:97], v[90:91], v[86:87] op_sel:[0,0] op_sel_hi:[0,1] neg_hi:[0,1]
	ds_read_b64 v[98:99], v132 offset:17408
	v_pk_fma_f32 v[90:91], v[90:91], v[86:87], v[96:97] op_sel:[1,1,0] op_sel_hi:[1,0,1]
	v_pk_mul_f32 v[96:97], v[86:87], v[76:77] op_sel:[0,0] op_sel_hi:[0,1]
	v_pk_fma_f32 v[86:87], v[86:87], v[76:77], v[96:97] op_sel:[1,1,0] op_sel_hi:[1,0,1] neg_lo:[0,1,0]
	s_waitcnt lgkmcnt(3)
	v_pk_mul_f32 v[96:97], v[88:89], v[86:87] op_sel:[0,0] op_sel_hi:[0,1] neg_hi:[0,1]
	v_pk_fma_f32 v[88:89], v[88:89], v[86:87], v[96:97] op_sel:[1,1,0] op_sel_hi:[1,0,1]
	v_pk_mul_f32 v[96:97], v[86:87], v[76:77] op_sel:[0,0] op_sel_hi:[0,1]
	v_pk_fma_f32 v[86:87], v[86:87], v[76:77], v[96:97] op_sel:[1,1,0] op_sel_hi:[1,0,1] neg_lo:[0,1,0]
	s_waitcnt lgkmcnt(2)
	v_pk_mul_f32 v[96:97], v[92:93], v[86:87] op_sel:[0,0] op_sel_hi:[0,1] neg_hi:[0,1]
	v_pk_fma_f32 v[92:93], v[92:93], v[86:87], v[96:97] op_sel:[1,1,0] op_sel_hi:[1,0,1]
	v_pk_mul_f32 v[96:97], v[86:87], v[76:77] op_sel:[0,0] op_sel_hi:[0,1]
	v_pk_fma_f32 v[86:87], v[86:87], v[76:77], v[96:97] op_sel:[1,1,0] op_sel_hi:[1,0,1] neg_lo:[0,1,0]
	s_waitcnt lgkmcnt(1)
	v_pk_mul_f32 v[96:97], v[94:95], v[86:87] op_sel:[0,0] op_sel_hi:[0,1] neg_hi:[0,1]
	v_pk_fma_f32 v[94:95], v[94:95], v[86:87], v[96:97] op_sel:[1,1,0] op_sel_hi:[1,0,1]
	v_pk_mul_f32 v[96:97], v[86:87], v[76:77] op_sel:[0,0] op_sel_hi:[0,1]
	v_pk_fma_f32 v[86:87], v[86:87], v[76:77], v[96:97] op_sel:[1,1,0] op_sel_hi:[1,0,1] neg_lo:[0,1,0]
	ds_read_b64 v[96:97], v132 offset:19584
	ds_read_b64 v[100:101], v132 offset:21760
	ds_read_b64 v[102:103], v132 offset:23936
	s_waitcnt lgkmcnt(3)
	v_pk_mul_f32 v[104:105], v[98:99], v[86:87] op_sel:[0,0] op_sel_hi:[0,1] neg_hi:[0,1]
	ds_read_b64 v[106:107], v132 offset:26112
	v_pk_fma_f32 v[98:99], v[98:99], v[86:87], v[104:105] op_sel:[1,1,0] op_sel_hi:[1,0,1]
	v_pk_mul_f32 v[104:105], v[86:87], v[76:77] op_sel:[0,0] op_sel_hi:[0,1]
	v_pk_fma_f32 v[86:87], v[86:87], v[76:77], v[104:105] op_sel:[1,1,0] op_sel_hi:[1,0,1] neg_lo:[0,1,0]
	s_waitcnt lgkmcnt(3)
	v_pk_mul_f32 v[104:105], v[96:97], v[86:87] op_sel:[0,0] op_sel_hi:[0,1] neg_hi:[0,1]
	v_pk_fma_f32 v[96:97], v[96:97], v[86:87], v[104:105] op_sel:[1,1,0] op_sel_hi:[1,0,1]
	v_pk_mul_f32 v[104:105], v[86:87], v[76:77] op_sel:[0,0] op_sel_hi:[0,1]
	v_pk_fma_f32 v[86:87], v[86:87], v[76:77], v[104:105] op_sel:[1,1,0] op_sel_hi:[1,0,1] neg_lo:[0,1,0]
	s_waitcnt lgkmcnt(2)
	v_pk_mul_f32 v[104:105], v[100:101], v[86:87] op_sel:[0,0] op_sel_hi:[0,1] neg_hi:[0,1]
	v_pk_fma_f32 v[100:101], v[100:101], v[86:87], v[104:105] op_sel:[1,1,0] op_sel_hi:[1,0,1]
	v_pk_mul_f32 v[104:105], v[86:87], v[76:77] op_sel:[0,0] op_sel_hi:[0,1]
	v_pk_fma_f32 v[86:87], v[86:87], v[76:77], v[104:105] op_sel:[1,1,0] op_sel_hi:[1,0,1] neg_lo:[0,1,0]
	s_waitcnt lgkmcnt(1)
	v_pk_mul_f32 v[104:105], v[102:103], v[86:87] op_sel:[0,0] op_sel_hi:[0,1] neg_hi:[0,1]
	v_pk_fma_f32 v[102:103], v[102:103], v[86:87], v[104:105] op_sel:[1,1,0] op_sel_hi:[1,0,1]
	v_pk_mul_f32 v[104:105], v[86:87], v[76:77] op_sel:[0,0] op_sel_hi:[0,1]
	v_pk_fma_f32 v[86:87], v[86:87], v[76:77], v[104:105] op_sel:[1,1,0] op_sel_hi:[1,0,1] neg_lo:[0,1,0]
	ds_read_b64 v[104:105], v132 offset:28288
	ds_read_b64 v[110:111], v132 offset:30464
	ds_read_b64 v[112:113], v132 offset:32640
	s_waitcnt lgkmcnt(3)
	v_pk_mul_f32 v[114:115], v[106:107], v[86:87] op_sel:[0,0] op_sel_hi:[0,1] neg_hi:[0,1]
	v_pk_fma_f32 v[106:107], v[106:107], v[86:87], v[114:115] op_sel:[1,1,0] op_sel_hi:[1,0,1]
	v_pk_mul_f32 v[114:115], v[86:87], v[76:77] op_sel:[0,0] op_sel_hi:[0,1]
	v_pk_fma_f32 v[86:87], v[86:87], v[76:77], v[114:115] op_sel:[1,1,0] op_sel_hi:[1,0,1] neg_lo:[0,1,0]
	s_waitcnt lgkmcnt(2)
	v_pk_mul_f32 v[114:115], v[104:105], v[86:87] op_sel:[0,0] op_sel_hi:[0,1] neg_hi:[0,1]
	v_pk_fma_f32 v[104:105], v[104:105], v[86:87], v[114:115] op_sel:[1,1,0] op_sel_hi:[1,0,1]
	v_pk_mul_f32 v[114:115], v[86:87], v[76:77] op_sel:[0,0] op_sel_hi:[0,1]
	v_pk_fma_f32 v[86:87], v[86:87], v[76:77], v[114:115] op_sel:[1,1,0] op_sel_hi:[1,0,1] neg_lo:[0,1,0]
	s_waitcnt lgkmcnt(1)
	v_pk_mul_f32 v[114:115], v[110:111], v[86:87] op_sel:[0,0] op_sel_hi:[0,1] neg_hi:[0,1]
	v_pk_fma_f32 v[110:111], v[110:111], v[86:87], v[114:115] op_sel:[1,1,0] op_sel_hi:[1,0,1]
	v_pk_mul_f32 v[114:115], v[86:87], v[76:77] op_sel:[0,0] op_sel_hi:[0,1]
	v_pk_fma_f32 v[76:77], v[86:87], v[76:77], v[114:115] op_sel:[1,1,0] op_sel_hi:[1,0,1] neg_lo:[0,1,0]
	s_waitcnt lgkmcnt(0)
	v_pk_mul_f32 v[86:87], v[112:113], v[76:77] op_sel:[0,0] op_sel_hi:[0,1] neg_hi:[0,1]
	v_pk_fma_f32 v[76:77], v[112:113], v[76:77], v[86:87] op_sel:[1,1,0] op_sel_hi:[1,0,1]
	v_pk_add_f32 v[86:87], v[84:85], v[98:99]
	v_pk_add_f32 v[84:85], v[84:85], v[98:99] neg_lo:[0,1] neg_hi:[0,1]
	v_pk_add_f32 v[98:99], v[90:91], v[106:107]
	v_pk_add_f32 v[90:91], v[90:91], v[106:107] neg_lo:[0,1] neg_hi:[0,1]
	v_pk_add_f32 v[106:107], v[86:87], v[98:99]
	v_pk_add_f32 v[98:99], v[86:87], v[98:99] neg_lo:[0,1] neg_hi:[0,1]
	v_pk_add_f32 v[86:87], v[84:85], v[90:91] op_sel:[0,1] op_sel_hi:[1,0] neg_lo:[0,1]
	v_pk_add_f32 v[112:113], v[84:85], v[90:91] op_sel:[0,1] op_sel_hi:[1,0] neg_hi:[0,1]
	v_pk_add_f32 v[84:85], v[78:79], v[96:97]
	v_pk_add_f32 v[78:79], v[78:79], v[96:97] neg_lo:[0,1] neg_hi:[0,1]
	v_pk_add_f32 v[90:91], v[88:89], v[104:105]
	v_pk_add_f32 v[88:89], v[88:89], v[104:105] neg_lo:[0,1] neg_hi:[0,1]
	v_pk_add_f32 v[96:97], v[84:85], v[90:91]
	v_pk_add_f32 v[84:85], v[84:85], v[90:91] neg_lo:[0,1] neg_hi:[0,1]
	v_pk_add_f32 v[90:91], v[78:79], v[88:89] op_sel:[0,1] op_sel_hi:[1,0] neg_lo:[0,1]
	v_pk_add_f32 v[78:79], v[78:79], v[88:89] op_sel:[0,1] op_sel_hi:[1,0] neg_hi:[0,1]
	v_pk_add_f32 v[88:89], v[80:81], v[100:101]
	v_pk_add_f32 v[80:81], v[80:81], v[100:101] neg_lo:[0,1] neg_hi:[0,1]
	v_pk_add_f32 v[100:101], v[92:93], v[110:111]
	v_pk_add_f32 v[92:93], v[92:93], v[110:111] neg_lo:[0,1] neg_hi:[0,1]
	v_pk_add_f32 v[104:105], v[88:89], v[100:101]
	v_pk_add_f32 v[88:89], v[88:89], v[100:101] neg_lo:[0,1] neg_hi:[0,1]
	v_pk_add_f32 v[100:101], v[80:81], v[92:93] op_sel:[0,1] op_sel_hi:[1,0] neg_lo:[0,1]
	v_pk_add_f32 v[80:81], v[80:81], v[92:93] op_sel:[0,1] op_sel_hi:[1,0] neg_hi:[0,1]
	v_pk_add_f32 v[92:93], v[82:83], v[102:103]
	v_pk_add_f32 v[82:83], v[82:83], v[102:103] neg_lo:[0,1] neg_hi:[0,1]
	v_pk_add_f32 v[102:103], v[94:95], v[76:77]
	v_pk_add_f32 v[76:77], v[94:95], v[76:77] neg_lo:[0,1] neg_hi:[0,1]
	v_pk_add_f32 v[94:95], v[92:93], v[102:103]
	v_pk_add_f32 v[92:93], v[92:93], v[102:103] neg_lo:[0,1] neg_hi:[0,1]
	v_pk_add_f32 v[102:103], v[82:83], v[76:77] op_sel:[0,1] op_sel_hi:[1,0] neg_lo:[0,1]
	v_pk_add_f32 v[76:77], v[82:83], v[76:77] op_sel:[0,1] op_sel_hi:[1,0] neg_hi:[0,1]
	v_pk_mul_f32 v[82:83], v[90:91], s[58:59] op_sel:[0,0] op_sel_hi:[0,1]
	v_pk_fma_f32 v[70:71], v[90:91], s[58:59], v[82:83] op_sel:[1,1,0] op_sel_hi:[1,0,1] neg_lo:[0,1,0]
	v_pk_mul_f32 v[82:83], v[100:101], s[60:61] op_sel:[0,0] op_sel_hi:[0,1]
	v_pk_mul_f32 v[90:91], v[102:103], s[62:63] op_sel:[0,0] op_sel_hi:[0,1]
	v_pk_fma_f32 v[82:83], v[100:101], s[60:61], v[82:83] op_sel:[1,1,0] op_sel_hi:[1,0,1] neg_lo:[0,1,0]
	v_pk_mul_f32 v[100:101], v[84:85], s[60:61] op_sel:[0,0] op_sel_hi:[0,1]
	v_pk_fma_f32 v[90:91], v[102:103], s[62:63], v[90:91] op_sel:[1,1,0] op_sel_hi:[1,0,1] neg_lo:[0,1,0]
	v_pk_fma_f32 v[110:111], v[84:85], s[60:61], v[100:101] op_sel:[1,1,0] op_sel_hi:[1,0,1] neg_lo:[0,1,0]
	v_pk_mul_f32 v[30:31], v[88:89], s[64:65] op_sel:[0,0] op_sel_hi:[0,1]
	v_pk_add_f32 v[84:85], v[70:71], v[90:91]
	v_pk_fma_f32 v[72:73], v[88:89], s[64:65], v[30:31] op_sel:[1,1,0] op_sel_hi:[1,0,1] neg_lo:[0,1,0]
	v_pk_mul_f32 v[30:31], v[92:93], s[66:67] op_sel:[0,0] op_sel_hi:[0,1]
	v_pk_fma_f32 v[88:89], v[92:93], s[66:67], v[30:31] op_sel:[1,1,0] op_sel_hi:[1,0,1] neg_lo:[0,1,0]
	v_pk_mul_f32 v[30:31], v[78:79], s[62:63] op_sel:[0,0] op_sel_hi:[0,1]
	v_pk_fma_f32 v[114:115], v[78:79], s[62:63], v[30:31] op_sel:[1,1,0] op_sel_hi:[1,0,1] neg_lo:[0,1,0]
	v_pk_mul_f32 v[28:29], v[80:81], s[66:67] op_sel:[0,0] op_sel_hi:[0,1]
	v_pk_add_f32 v[30:31], v[96:97], v[94:95] neg_lo:[0,1] neg_hi:[0,1]
	v_pk_fma_f32 v[116:117], v[80:81], s[66:67], v[28:29] op_sel:[1,1,0] op_sel_hi:[1,0,1] neg_lo:[0,1,0]
	v_pk_mul_f32 v[28:29], v[76:77], s[68:69] op_sel:[0,0] op_sel_hi:[0,1]
	v_pk_add_f32 v[32:33], v[70:71], v[90:91] neg_lo:[0,1] neg_hi:[0,1]
	v_pk_fma_f32 v[140:141], v[76:77], s[68:69], v[28:29] op_sel:[1,1,0] op_sel_hi:[1,0,1] neg_lo:[0,1,0]
	v_pk_add_f32 v[28:29], v[106:107], v[104:105] neg_lo:[0,1] neg_hi:[0,1]
	v_pk_add_f32 v[80:81], v[86:87], v[82:83]
	v_pk_add_f32 v[76:77], v[28:29], v[30:31] op_sel:[0,1] op_sel_hi:[1,0] neg_lo:[0,1]
	v_pk_add_f32 v[28:29], v[28:29], v[30:31] op_sel:[0,1] op_sel_hi:[1,0] neg_hi:[0,1]
	v_pk_add_f32 v[30:31], v[86:87], v[82:83] neg_lo:[0,1] neg_hi:[0,1]
	v_pk_add_f32 v[70:71], v[110:111], v[88:89] neg_lo:[0,1] neg_hi:[0,1]
	v_pk_add_f32 v[82:83], v[30:31], v[32:33] op_sel:[0,1] op_sel_hi:[1,0] neg_lo:[0,1]
	v_pk_add_f32 v[30:31], v[30:31], v[32:33] op_sel:[0,1] op_sel_hi:[1,0] neg_hi:[0,1]
	v_pk_add_f32 v[32:33], v[98:99], v[72:73] neg_lo:[0,1] neg_hi:[0,1]
	v_pk_add_f32 v[74:75], v[106:107], v[104:105]
	v_pk_add_f32 v[78:79], v[96:97], v[94:95]
	v_pk_add_f32 v[86:87], v[98:99], v[72:73]
	v_pk_add_f32 v[90:91], v[110:111], v[88:89]
	v_pk_add_f32 v[88:89], v[32:33], v[70:71] op_sel:[0,1] op_sel_hi:[1,0] neg_lo:[0,1]
	v_pk_add_f32 v[32:33], v[32:33], v[70:71] op_sel:[0,1] op_sel_hi:[1,0] neg_hi:[0,1]
	v_pk_add_f32 v[92:93], v[112:113], v[116:117]
	v_pk_add_f32 v[70:71], v[112:113], v[116:117] neg_lo:[0,1] neg_hi:[0,1]
	v_pk_add_f32 v[96:97], v[114:115], v[140:141]
	v_pk_add_f32 v[72:73], v[114:115], v[140:141] neg_lo:[0,1] neg_hi:[0,1]
	v_pk_add_f32 v[100:101], v[74:75], v[78:79]
	v_pk_add_f32 v[102:103], v[80:81], v[84:85]
	v_pk_add_f32 v[104:105], v[86:87], v[90:91]
	v_pk_add_f32 v[98:99], v[92:93], v[96:97]
	v_pk_add_f32 v[94:95], v[70:71], v[72:73] op_sel:[0,1] op_sel_hi:[1,0] neg_lo:[0,1]
	v_pk_add_f32 v[70:71], v[70:71], v[72:73] op_sel:[0,1] op_sel_hi:[1,0] neg_hi:[0,1]
	v_mov_b32_e32 v73, v37
	v_mov_b32_e32 v72, v36
	s_and_saveexec_b64 s[0:1], s[4:5]
	s_xor_b64 s[0:1], exec, s[0:1]
	s_cbranch_execz .LBB0_3402
	v_mov_b64_e32 v[106:107], s[12:13]
	v_pk_mul_f32 v[110:111], v[72:73], v[106:107] op_sel:[0,0] op_sel_hi:[0,1]
	v_pk_fma_f32 v[106:107], v[72:73], v[106:107], v[110:111] op_sel:[1,1,0] op_sel_hi:[1,0,1] neg_lo:[0,1,0]
	v_pk_mul_f32 v[110:111], v[100:101], v[106:107] op_sel:[0,0] op_sel_hi:[0,1] neg_hi:[0,1]
	v_pk_fma_f32 v[100:101], v[100:101], v[106:107], v[110:111] op_sel:[1,1,0] op_sel_hi:[1,0,1]
	v_pk_mul_f32 v[110:111], v[72:73], s[16:17] op_sel:[0,0] op_sel_hi:[0,1]
	v_pk_fma_f32 v[106:107], v[72:73], s[16:17], v[110:111] op_sel:[1,1,0] op_sel_hi:[1,0,1] neg_lo:[0,1,0]
	v_pk_mul_f32 v[110:111], v[102:103], v[106:107] op_sel:[0,0] op_sel_hi:[0,1] neg_hi:[0,1]
	v_pk_fma_f32 v[102:103], v[102:103], v[106:107], v[110:111] op_sel:[1,1,0] op_sel_hi:[1,0,1]
	v_pk_mul_f32 v[110:111], v[72:73], s[20:21] op_sel:[0,0] op_sel_hi:[0,1]
	v_pk_fma_f32 v[106:107], v[72:73], s[20:21], v[110:111] op_sel:[1,1,0] op_sel_hi:[1,0,1] neg_lo:[0,1,0]
	v_pk_mul_f32 v[110:111], v[104:105], v[106:107] op_sel:[0,0] op_sel_hi:[0,1] neg_hi:[0,1]
	v_pk_fma_f32 v[104:105], v[104:105], v[106:107], v[110:111] op_sel:[1,1,0] op_sel_hi:[1,0,1]
	v_pk_mul_f32 v[110:111], v[72:73], s[22:23] op_sel:[0,0] op_sel_hi:[0,1]
	v_pk_fma_f32 v[106:107], v[72:73], s[22:23], v[110:111] op_sel:[1,1,0] op_sel_hi:[1,0,1] neg_lo:[0,1,0]
	v_pk_mul_f32 v[110:111], v[98:99], v[106:107] op_sel:[0,0] op_sel_hi:[0,1] neg_hi:[0,1]
	v_pk_fma_f32 v[98:99], v[98:99], v[106:107], v[110:111] op_sel:[1,1,0] op_sel_hi:[1,0,1]
	ds_write_b64 v132, v[100:101]
	ds_write_b64 v132, v[102:103] offset:2176
	ds_write_b64 v132, v[104:105] offset:4352
	ds_write_b64 v132, v[98:99] offset:6528
	v_mov_b64_e32 v[98:99], s[46:47]
	v_pk_mul_f32 v[100:101], v[72:73], v[98:99] op_sel:[0,0] op_sel_hi:[0,1]
	s_nop 0
	v_pk_fma_f32 v[98:99], v[72:73], v[98:99], v[100:101] op_sel:[1,1,0] op_sel_hi:[1,0,1] neg_lo:[0,1,0]
	v_pk_mul_f32 v[100:101], v[76:77], v[98:99] op_sel:[0,0] op_sel_hi:[0,1] neg_hi:[0,1]
	v_pk_fma_f32 v[76:77], v[76:77], v[98:99], v[100:101] op_sel:[1,1,0] op_sel_hi:[1,0,1]
	v_pk_mul_f32 v[100:101], v[72:73], s[48:49] op_sel:[0,0] op_sel_hi:[0,1]
	v_pk_fma_f32 v[98:99], v[72:73], s[48:49], v[100:101] op_sel:[1,1,0] op_sel_hi:[1,0,1] neg_lo:[0,1,0]
	v_pk_mul_f32 v[100:101], v[82:83], v[98:99] op_sel:[0,0] op_sel_hi:[0,1] neg_hi:[0,1]
	v_pk_fma_f32 v[82:83], v[82:83], v[98:99], v[100:101] op_sel:[1,1,0] op_sel_hi:[1,0,1]
	v_pk_mul_f32 v[100:101], v[72:73], s[50:51] op_sel:[0,0] op_sel_hi:[0,1]
	v_pk_fma_f32 v[98:99], v[72:73], s[50:51], v[100:101] op_sel:[1,1,0] op_sel_hi:[1,0,1] neg_lo:[0,1,0]
	v_pk_mul_f32 v[100:101], v[88:89], v[98:99] op_sel:[0,0] op_sel_hi:[0,1] neg_hi:[0,1]
	v_pk_fma_f32 v[88:89], v[88:89], v[98:99], v[100:101] op_sel:[1,1,0] op_sel_hi:[1,0,1]
	v_pk_mul_f32 v[100:101], v[72:73], s[52:53] op_sel:[0,0] op_sel_hi:[0,1]
	v_pk_fma_f32 v[98:99], v[72:73], s[52:53], v[100:101] op_sel:[1,1,0] op_sel_hi:[1,0,1] neg_lo:[0,1,0]
	v_pk_mul_f32 v[100:101], v[94:95], v[98:99] op_sel:[0,0] op_sel_hi:[0,1] neg_hi:[0,1]
	s_nop 0
	v_pk_fma_f32 v[94:95], v[94:95], v[98:99], v[100:101] op_sel:[1,1,0] op_sel_hi:[1,0,1]

.LBB0_3404:
	s_or_b64 exec, exec, s[0:1]
	v_pk_add_f32 v[98:99], v[74:75], v[78:79] neg_lo:[0,1] neg_hi:[0,1]
	v_pk_add_f32 v[80:81], v[80:81], v[84:85] neg_lo:[0,1] neg_hi:[0,1]
	v_pk_add_f32 v[78:79], v[86:87], v[90:91] neg_lo:[0,1] neg_hi:[0,1]
	v_pk_add_f32 v[74:75], v[92:93], v[96:97] neg_lo:[0,1] neg_hi:[0,1]
	ds_write_b64 v132, v[76:77] offset:8704
	ds_write_b64 v132, v[82:83] offset:10880
	ds_write_b64 v132, v[88:89] offset:13056
	ds_write_b64 v132, v[94:95] offset:15232
	s_and_saveexec_b64 s[0:1], s[4:5]
	s_xor_b64 s[0:1], exec, s[0:1]
	s_cbranch_execz .LBB0_3406
	v_mov_b64_e32 v[76:77], s[8:9]
	v_pk_mul_f32 v[82:83], v[72:73], v[76:77] op_sel:[0,0] op_sel_hi:[0,1]
	s_mov_b32 s15, s53
	v_pk_fma_f32 v[76:77], v[72:73], v[76:77], v[82:83] op_sel:[1,1,0] op_sel_hi:[1,0,1] neg_lo:[0,1,0]
	s_mov_b32 s6, s23
	v_pk_mul_f32 v[82:83], v[98:99], v[76:77] op_sel:[0,0] op_sel_hi:[0,1] neg_hi:[0,1]
	s_mov_b32 s7, s49
	v_pk_fma_f32 v[76:77], v[98:99], v[76:77], v[82:83] op_sel:[1,1,0] op_sel_hi:[1,0,1]
	v_mov_b64_e32 v[82:83], s[14:15]
	v_pk_mul_f32 v[84:85], v[72:73], v[82:83] op_sel:[0,0] op_sel_hi:[0,1]
	s_nop 0
	v_pk_fma_f32 v[82:83], v[72:73], v[82:83], v[84:85] op_sel:[1,1,0] op_sel_hi:[1,0,1] neg_lo:[0,1,0]
	v_pk_mul_f32 v[84:85], v[80:81], v[82:83] op_sel:[0,0] op_sel_hi:[0,1] neg_hi:[0,1]
	v_pk_fma_f32 v[80:81], v[80:81], v[82:83], v[84:85] op_sel:[1,1,0] op_sel_hi:[1,0,1]
	v_pk_mul_f32 v[84:85], v[72:73], s[18:19] op_sel:[0,0] op_sel_hi:[0,1]
	v_pk_fma_f32 v[82:83], v[72:73], s[18:19], v[84:85] op_sel:[1,1,0] op_sel_hi:[1,0,1] neg_lo:[0,1,0]
	v_pk_mul_f32 v[84:85], v[78:79], v[82:83] op_sel:[0,0] op_sel_hi:[0,1] neg_hi:[0,1]
	v_pk_fma_f32 v[78:79], v[78:79], v[82:83], v[84:85] op_sel:[1,1,0] op_sel_hi:[1,0,1]
	v_mov_b64_e32 v[82:83], s[6:7]
	v_pk_mul_f32 v[84:85], v[72:73], v[82:83] op_sel:[0,0] op_sel_hi:[0,1]
	s_mov_b32 s6, s49
	v_pk_fma_f32 v[82:83], v[72:73], v[82:83], v[84:85] op_sel:[1,1,0] op_sel_hi:[1,0,1] neg_lo:[0,1,0]
	s_mov_b32 s7, s23
	v_pk_mul_f32 v[84:85], v[74:75], v[82:83] op_sel:[0,0] op_sel_hi:[0,1] neg_hi:[0,1]
	v_pk_fma_f32 v[74:75], v[74:75], v[82:83], v[84:85] op_sel:[1,1,0] op_sel_hi:[1,0,1]
	ds_write_b64 v132, v[76:77] offset:17408
	ds_write_b64 v132, v[80:81] offset:19584
	ds_write_b64 v132, v[78:79] offset:21760
	ds_write_b64 v132, v[74:75] offset:23936
	v_mov_b64_e32 v[74:75], s[54:55]
	v_pk_mul_f32 v[76:77], v[72:73], v[74:75] op_sel:[0,0] op_sel_hi:[0,1]
	s_nop 0
	v_pk_fma_f32 v[74:75], v[72:73], v[74:75], v[76:77] op_sel:[1,1,0] op_sel_hi:[1,0,1] neg_lo:[0,1,0]
	v_pk_mul_f32 v[76:77], v[28:29], v[74:75] op_sel:[0,0] op_sel_hi:[0,1] neg_hi:[0,1]
	v_pk_fma_f32 v[28:29], v[28:29], v[74:75], v[76:77] op_sel:[1,1,0] op_sel_hi:[1,0,1]
	v_mov_b64_e32 v[74:75], s[6:7]
	v_pk_mul_f32 v[76:77], v[72:73], v[74:75] op_sel:[0,0] op_sel_hi:[0,1]
	s_mov_b32 s6, s53
	v_pk_fma_f32 v[74:75], v[72:73], v[74:75], v[76:77] op_sel:[1,1,0] op_sel_hi:[1,0,1] neg_lo:[0,1,0]
	s_mov_b32 s7, s14
	v_pk_mul_f32 v[76:77], v[30:31], v[74:75] op_sel:[0,0] op_sel_hi:[0,1] neg_hi:[0,1]
	v_pk_fma_f32 v[30:31], v[30:31], v[74:75], v[76:77] op_sel:[1,1,0] op_sel_hi:[1,0,1]
	v_pk_mul_f32 v[76:77], v[72:73], s[68:69] op_sel:[0,0] op_sel_hi:[0,1]
	v_pk_fma_f32 v[74:75], v[72:73], s[68:69], v[76:77] op_sel:[1,1,0] op_sel_hi:[1,0,1] neg_lo:[0,1,0]
	v_pk_mul_f32 v[76:77], v[32:33], v[74:75] op_sel:[0,0] op_sel_hi:[0,1] neg_hi:[0,1]
	v_pk_fma_f32 v[32:33], v[32:33], v[74:75], v[76:77] op_sel:[1,1,0] op_sel_hi:[1,0,1]
	v_pk_mul_f32 v[76:77], v[72:73], s[6:7] op_sel:[0,0] op_sel_hi:[0,1]
	v_pk_fma_f32 v[72:73], v[72:73], s[6:7], v[76:77] op_sel:[1,1,0] op_sel_hi:[1,0,1] neg_lo:[0,1,0]
	v_pk_mul_f32 v[74:75], v[70:71], v[72:73] op_sel:[0,0] op_sel_hi:[0,1] neg_hi:[0,1]
	s_nop 0
	v_pk_fma_f32 v[70:71], v[70:71], v[72:73], v[74:75] op_sel:[1,1,0] op_sel_hi:[1,0,1]

.LBB0_3479:
	s_or_b64 exec, exec, s[0:1]
	v_mov_b32_e32 v44, v30
	v_mov_b32_e32 v45, v26
	v_mov_b32_e32 v26, v31
	v_mov_b32_e32 v30, v32
	v_mov_b32_e32 v31, v28
	v_mov_b32_e32 v28, v33
	v_pk_add_f32 v[26:27], v[44:45], v[26:27]
	v_pk_add_f32 v[28:29], v[30:31], v[28:29]
	v_pk_add_f32 v[30:31], v[52:53], v[68:69]
	v_pk_add_f32 v[26:27], v[26:27], v[28:29]
	v_pk_add_f32 v[28:29], v[42:43], v[60:61] neg_lo:[0,1] neg_hi:[0,1]
	v_add_f32_e32 v34, v26, v27
	v_pk_add_f32 v[26:27], v[42:43], v[60:61]
	v_pk_add_f32 v[32:33], v[52:53], v[68:69] neg_lo:[0,1] neg_hi:[0,1]
	v_pk_add_f32 v[52:53], v[26:27], v[30:31]
	v_pk_add_f32 v[60:61], v[26:27], v[30:31] neg_lo:[0,1] neg_hi:[0,1]
	v_pk_add_f32 v[68:69], v[28:29], v[32:33] op_sel:[0,1] op_sel_hi:[1,0] neg_hi:[0,1]
	s_waitcnt lgkmcnt(1)
	v_pk_add_f32 v[76:77], v[28:29], v[32:33] op_sel:[0,1] op_sel_hi:[1,0] neg_lo:[0,1]
	v_pk_add_f32 v[26:27], v[46:47], v[62:63]
	v_pk_add_f32 v[28:29], v[46:47], v[62:63] neg_lo:[0,1] neg_hi:[0,1]
	v_pk_add_f32 v[30:31], v[54:55], v[70:71]
	v_pk_add_f32 v[32:33], v[54:55], v[70:71] neg_lo:[0,1] neg_hi:[0,1]
	v_pk_add_f32 v[46:47], v[26:27], v[30:31]
	v_pk_add_f32 v[30:31], v[26:27], v[30:31] neg_lo:[0,1] neg_hi:[0,1]
	v_pk_add_f32 v[26:27], v[28:29], v[32:33] op_sel:[0,1] op_sel_hi:[1,0] neg_hi:[0,1]
	v_pk_add_f32 v[44:45], v[28:29], v[32:33] op_sel:[0,1] op_sel_hi:[1,0] neg_lo:[0,1]
	v_pk_add_f32 v[28:29], v[48:49], v[64:65]
	v_pk_add_f32 v[32:33], v[48:49], v[64:65] neg_lo:[0,1] neg_hi:[0,1]
	v_pk_add_f32 v[42:43], v[56:57], v[72:73]
	v_pk_add_f32 v[48:49], v[56:57], v[72:73] neg_lo:[0,1] neg_hi:[0,1]
	v_pk_add_f32 v[54:55], v[28:29], v[42:43]
	v_pk_add_f32 v[56:57], v[28:29], v[42:43] neg_lo:[0,1] neg_hi:[0,1]
	v_pk_add_f32 v[42:43], v[32:33], v[48:49] op_sel:[0,1] op_sel_hi:[1,0] neg_hi:[0,1]
	v_pk_add_f32 v[48:49], v[32:33], v[48:49] op_sel:[0,1] op_sel_hi:[1,0] neg_lo:[0,1]
	v_pk_add_f32 v[28:29], v[50:51], v[66:67]
	v_pk_add_f32 v[32:33], v[50:51], v[66:67] neg_lo:[0,1] neg_hi:[0,1]
	v_pk_add_f32 v[50:51], v[58:59], v[74:75]
	v_pk_add_f32 v[58:59], v[58:59], v[74:75] neg_lo:[0,1] neg_hi:[0,1]
	v_pk_add_f32 v[62:63], v[28:29], v[50:51]
	v_pk_add_f32 v[50:51], v[28:29], v[50:51] neg_lo:[0,1] neg_hi:[0,1]
	v_pk_add_f32 v[64:65], v[32:33], v[58:59] op_sel:[0,1] op_sel_hi:[1,0] neg_hi:[0,1]
	v_pk_add_f32 v[58:59], v[32:33], v[58:59] op_sel:[0,1] op_sel_hi:[1,0] neg_lo:[0,1]
	v_pk_mul_f32 v[28:29], v[26:27], s[20:21] op_sel:[0,0] op_sel_hi:[0,1]
	s_waitcnt lgkmcnt(0)
	v_pk_fma_f32 v[66:67], v[26:27], s[20:21], v[28:29] op_sel:[1,1,0] op_sel_hi:[1,0,1] neg_lo:[0,1,0]
	v_mov_b64_e32 v[28:29], s[46:47]
	v_pk_mul_f32 v[26:27], v[42:43], v[28:29] op_sel:[0,0] op_sel_hi:[0,1]
	s_barrier
	v_pk_fma_f32 v[70:71], v[42:43], v[28:29], v[26:27] op_sel:[1,1,0] op_sel_hi:[1,0,1] neg_lo:[0,1,0]
	v_mov_b64_e32 v[26:27], s[50:51]
	v_pk_mul_f32 v[42:43], v[64:65], v[26:27] op_sel:[0,0] op_sel_hi:[0,1]
	v_pk_fma_f32 v[64:65], v[64:65], v[26:27], v[42:43] op_sel:[1,1,0] op_sel_hi:[1,0,1] neg_lo:[0,1,0]
	v_pk_mul_f32 v[42:43], v[30:31], v[28:29] op_sel:[0,0] op_sel_hi:[0,1]
	v_pk_fma_f32 v[72:73], v[30:31], v[28:29], v[42:43] op_sel:[1,1,0] op_sel_hi:[1,0,1] neg_lo:[0,1,0]
	v_pk_mul_f32 v[30:31], v[56:57], s[8:9] op_sel:[0,0] op_sel_hi:[0,1]
	v_pk_fma_f32 v[56:57], v[56:57], s[8:9], v[30:31] op_sel:[1,1,0] op_sel_hi:[1,0,1] neg_lo:[0,1,0]
	v_pk_mul_f32 v[74:75], v[50:51], s[54:55] op_sel:[0,0] op_sel_hi:[0,1]
	v_pk_fma_f32 v[50:51], v[50:51], s[54:55], v[74:75] op_sel:[1,1,0] op_sel_hi:[1,0,1] neg_lo:[0,1,0]
	v_pk_mul_f32 v[74:75], v[44:45], v[26:27] op_sel:[0,0] op_sel_hi:[0,1]
	v_pk_fma_f32 v[74:75], v[44:45], v[26:27], v[74:75] op_sel:[1,1,0] op_sel_hi:[1,0,1] neg_lo:[0,1,0]
	v_pk_mul_f32 v[44:45], v[48:49], s[54:55] op_sel:[0,0] op_sel_hi:[0,1]
	v_pk_fma_f32 v[48:49], v[48:49], s[54:55], v[44:45] op_sel:[1,1,0] op_sel_hi:[1,0,1] neg_lo:[0,1,0]
	v_pk_mul_f32 v[78:79], v[58:59], s[56:57] op_sel:[0,0] op_sel_hi:[0,1]
	v_pk_fma_f32 v[58:59], v[58:59], s[56:57], v[78:79] op_sel:[1,1,0] op_sel_hi:[1,0,1] neg_lo:[0,1,0]
	v_pk_add_f32 v[78:79], v[52:53], v[54:55]
	v_pk_add_f32 v[52:53], v[52:53], v[54:55] neg_lo:[0,1] neg_hi:[0,1]
	v_pk_add_f32 v[54:55], v[46:47], v[62:63]
	v_pk_add_f32 v[46:47], v[46:47], v[62:63] neg_lo:[0,1] neg_hi:[0,1]
	v_pk_add_f32 v[62:63], v[78:79], v[54:55]
	v_pk_add_f32 v[54:55], v[78:79], v[54:55] neg_lo:[0,1] neg_hi:[0,1]
	v_pk_add_f32 v[78:79], v[52:53], v[46:47] op_sel:[0,1] op_sel_hi:[1,0] neg_hi:[0,1]
	v_pk_add_f32 v[46:47], v[52:53], v[46:47] op_sel:[0,1] op_sel_hi:[1,0] neg_lo:[0,1]
	v_pk_add_f32 v[52:53], v[68:69], v[70:71]
	v_pk_add_f32 v[68:69], v[68:69], v[70:71] neg_lo:[0,1] neg_hi:[0,1]
	v_pk_add_f32 v[70:71], v[66:67], v[64:65]
	v_pk_add_f32 v[64:65], v[66:67], v[64:65] neg_lo:[0,1] neg_hi:[0,1]
	v_pk_add_f32 v[66:67], v[52:53], v[70:71]
	v_pk_add_f32 v[52:53], v[52:53], v[70:71] neg_lo:[0,1] neg_hi:[0,1]
	v_pk_add_f32 v[70:71], v[68:69], v[64:65] op_sel:[0,1] op_sel_hi:[1,0] neg_hi:[0,1]
	v_pk_add_f32 v[64:65], v[68:69], v[64:65] op_sel:[0,1] op_sel_hi:[1,0] neg_lo:[0,1]
	v_pk_add_f32 v[68:69], v[60:61], v[56:57]
	v_pk_add_f32 v[56:57], v[60:61], v[56:57] neg_lo:[0,1] neg_hi:[0,1]
	v_pk_add_f32 v[60:61], v[72:73], v[50:51]
	v_pk_add_f32 v[50:51], v[72:73], v[50:51] neg_lo:[0,1] neg_hi:[0,1]
	v_pk_add_f32 v[72:73], v[68:69], v[60:61]
	v_pk_add_f32 v[60:61], v[68:69], v[60:61] neg_lo:[0,1] neg_hi:[0,1]
	v_pk_add_f32 v[68:69], v[56:57], v[50:51] op_sel:[0,1] op_sel_hi:[1,0] neg_hi:[0,1]
	v_pk_add_f32 v[50:51], v[56:57], v[50:51] op_sel:[0,1] op_sel_hi:[1,0] neg_lo:[0,1]
	v_pk_add_f32 v[56:57], v[76:77], v[48:49]
	v_pk_add_f32 v[48:49], v[76:77], v[48:49] neg_lo:[0,1] neg_hi:[0,1]
	v_pk_add_f32 v[76:77], v[74:75], v[58:59]
	v_pk_add_f32 v[58:59], v[74:75], v[58:59] neg_lo:[0,1] neg_hi:[0,1]
	v_pk_add_f32 v[74:75], v[56:57], v[76:77]
	v_pk_add_f32 v[56:57], v[56:57], v[76:77] neg_lo:[0,1] neg_hi:[0,1]
	v_pk_add_f32 v[76:77], v[48:49], v[58:59] op_sel:[0,1] op_sel_hi:[1,0] neg_hi:[0,1]
	v_pk_add_f32 v[48:49], v[48:49], v[58:59] op_sel:[0,1] op_sel_hi:[1,0] neg_lo:[0,1]
	v_mov_b32_e32 v58, v38
	v_mov_b32_e32 v59, v39
	ds_write_b64 v132, v[62:63]
	v_pk_mul_f32 v[62:63], v[66:67], v[58:59] op_sel:[0,0] op_sel_hi:[0,1]
	v_pk_fma_f32 v[62:63], v[66:67], v[58:59], v[62:63] op_sel:[1,1,0] op_sel_hi:[1,0,1] neg_lo:[0,1,0]
	ds_write_b64 v132, v[62:63] offset:2176
	v_pk_mul_f32 v[62:63], v[58:59], v[58:59] op_sel:[0,0] op_sel_hi:[0,1]
	v_pk_fma_f32 v[62:63], v[58:59], v[58:59], v[62:63] op_sel:[1,1,0] op_sel_hi:[1,0,1] neg_lo:[0,1,0]
	v_pk_mul_f32 v[66:67], v[72:73], v[62:63] op_sel:[0,0] op_sel_hi:[0,1]
	v_pk_fma_f32 v[66:67], v[72:73], v[62:63], v[66:67] op_sel:[1,1,0] op_sel_hi:[1,0,1] neg_lo:[0,1,0]
	ds_write_b64 v132, v[66:67] offset:4352
	v_pk_mul_f32 v[66:67], v[62:63], v[58:59] op_sel:[0,0] op_sel_hi:[0,1]
	v_pk_fma_f32 v[62:63], v[62:63], v[58:59], v[66:67] op_sel:[1,1,0] op_sel_hi:[1,0,1] neg_lo:[0,1,0]
	v_pk_mul_f32 v[66:67], v[74:75], v[62:63] op_sel:[0,0] op_sel_hi:[0,1]
	v_pk_fma_f32 v[66:67], v[74:75], v[62:63], v[66:67] op_sel:[1,1,0] op_sel_hi:[1,0,1] neg_lo:[0,1,0]
	ds_write_b64 v132, v[66:67] offset:6528
	v_pk_mul_f32 v[66:67], v[62:63], v[58:59] op_sel:[0,0] op_sel_hi:[0,1]
	v_pk_fma_f32 v[62:63], v[62:63], v[58:59], v[66:67] op_sel:[1,1,0] op_sel_hi:[1,0,1] neg_lo:[0,1,0]
	v_pk_mul_f32 v[66:67], v[78:79], v[62:63] op_sel:[0,0] op_sel_hi:[0,1]
	v_pk_fma_f32 v[66:67], v[78:79], v[62:63], v[66:67] op_sel:[1,1,0] op_sel_hi:[1,0,1] neg_lo:[0,1,0]
	ds_write_b64 v132, v[66:67] offset:8704
	v_pk_mul_f32 v[66:67], v[62:63], v[58:59] op_sel:[0,0] op_sel_hi:[0,1]
	v_pk_fma_f32 v[62:63], v[62:63], v[58:59], v[66:67] op_sel:[1,1,0] op_sel_hi:[1,0,1] neg_lo:[0,1,0]
	v_pk_mul_f32 v[66:67], v[70:71], v[62:63] op_sel:[0,0] op_sel_hi:[0,1]
	v_pk_fma_f32 v[66:67], v[70:71], v[62:63], v[66:67] op_sel:[1,1,0] op_sel_hi:[1,0,1] neg_lo:[0,1,0]
	ds_write_b64 v132, v[66:67] offset:10880
	v_pk_mul_f32 v[66:67], v[62:63], v[58:59] op_sel:[0,0] op_sel_hi:[0,1]
	v_pk_fma_f32 v[62:63], v[62:63], v[58:59], v[66:67] op_sel:[1,1,0] op_sel_hi:[1,0,1] neg_lo:[0,1,0]
	v_pk_mul_f32 v[66:67], v[68:69], v[62:63] op_sel:[0,0] op_sel_hi:[0,1]
	v_pk_fma_f32 v[66:67], v[68:69], v[62:63], v[66:67] op_sel:[1,1,0] op_sel_hi:[1,0,1] neg_lo:[0,1,0]
	ds_write_b64 v132, v[66:67] offset:13056
	v_pk_mul_f32 v[66:67], v[62:63], v[58:59] op_sel:[0,0] op_sel_hi:[0,1]
	v_pk_fma_f32 v[62:63], v[62:63], v[58:59], v[66:67] op_sel:[1,1,0] op_sel_hi:[1,0,1] neg_lo:[0,1,0]
	v_pk_mul_f32 v[66:67], v[76:77], v[62:63] op_sel:[0,0] op_sel_hi:[0,1]
	v_pk_fma_f32 v[66:67], v[76:77], v[62:63], v[66:67] op_sel:[1,1,0] op_sel_hi:[1,0,1] neg_lo:[0,1,0]
	ds_write_b64 v132, v[66:67] offset:15232
	v_pk_mul_f32 v[66:67], v[62:63], v[58:59] op_sel:[0,0] op_sel_hi:[0,1]
	v_pk_fma_f32 v[62:63], v[62:63], v[58:59], v[66:67] op_sel:[1,1,0] op_sel_hi:[1,0,1] neg_lo:[0,1,0]
	v_pk_mul_f32 v[66:67], v[54:55], v[62:63] op_sel:[0,0] op_sel_hi:[0,1]
	v_pk_fma_f32 v[54:55], v[54:55], v[62:63], v[66:67] op_sel:[1,1,0] op_sel_hi:[1,0,1] neg_lo:[0,1,0]
	ds_write_b64 v132, v[54:55] offset:17408
	v_pk_mul_f32 v[54:55], v[62:63], v[58:59] op_sel:[0,0] op_sel_hi:[0,1]
	v_pk_fma_f32 v[54:55], v[62:63], v[58:59], v[54:55] op_sel:[1,1,0] op_sel_hi:[1,0,1] neg_lo:[0,1,0]
	v_pk_mul_f32 v[62:63], v[52:53], v[54:55] op_sel:[0,0] op_sel_hi:[0,1]
	v_pk_fma_f32 v[52:53], v[52:53], v[54:55], v[62:63] op_sel:[1,1,0] op_sel_hi:[1,0,1] neg_lo:[0,1,0]
	ds_write_b64 v132, v[52:53] offset:19584
	v_pk_mul_f32 v[52:53], v[54:55], v[58:59] op_sel:[0,0] op_sel_hi:[0,1]
	v_pk_fma_f32 v[52:53], v[54:55], v[58:59], v[52:53] op_sel:[1,1,0] op_sel_hi:[1,0,1] neg_lo:[0,1,0]
	v_pk_mul_f32 v[54:55], v[60:61], v[52:53] op_sel:[0,0] op_sel_hi:[0,1]
	v_pk_fma_f32 v[54:55], v[60:61], v[52:53], v[54:55] op_sel:[1,1,0] op_sel_hi:[1,0,1] neg_lo:[0,1,0]
	ds_write_b64 v132, v[54:55] offset:21760
	v_pk_mul_f32 v[54:55], v[52:53], v[58:59] op_sel:[0,0] op_sel_hi:[0,1]
	v_pk_fma_f32 v[52:53], v[52:53], v[58:59], v[54:55] op_sel:[1,1,0] op_sel_hi:[1,0,1] neg_lo:[0,1,0]
	v_pk_mul_f32 v[54:55], v[56:57], v[52:53] op_sel:[0,0] op_sel_hi:[0,1]
	v_pk_fma_f32 v[54:55], v[56:57], v[52:53], v[54:55] op_sel:[1,1,0] op_sel_hi:[1,0,1] neg_lo:[0,1,0]
	ds_write_b64 v132, v[54:55] offset:23936
	v_pk_mul_f32 v[54:55], v[52:53], v[58:59] op_sel:[0,0] op_sel_hi:[0,1]
	v_pk_fma_f32 v[52:53], v[52:53], v[58:59], v[54:55] op_sel:[1,1,0] op_sel_hi:[1,0,1] neg_lo:[0,1,0]
	v_pk_mul_f32 v[54:55], v[46:47], v[52:53] op_sel:[0,0] op_sel_hi:[0,1]
	v_pk_fma_f32 v[46:47], v[46:47], v[52:53], v[54:55] op_sel:[1,1,0] op_sel_hi:[1,0,1] neg_lo:[0,1,0]
	ds_write_b64 v132, v[46:47] offset:26112
	v_pk_mul_f32 v[46:47], v[52:53], v[58:59] op_sel:[0,0] op_sel_hi:[0,1]
	v_pk_fma_f32 v[46:47], v[52:53], v[58:59], v[46:47] op_sel:[1,1,0] op_sel_hi:[1,0,1] neg_lo:[0,1,0]
	v_pk_mul_f32 v[52:53], v[64:65], v[46:47] op_sel:[0,0] op_sel_hi:[0,1]
	v_pk_fma_f32 v[52:53], v[64:65], v[46:47], v[52:53] op_sel:[1,1,0] op_sel_hi:[1,0,1] neg_lo:[0,1,0]
	ds_write_b64 v132, v[52:53] offset:28288
	v_pk_mul_f32 v[52:53], v[46:47], v[58:59] op_sel:[0,0] op_sel_hi:[0,1]
	v_pk_fma_f32 v[46:47], v[46:47], v[58:59], v[52:53] op_sel:[1,1,0] op_sel_hi:[1,0,1] neg_lo:[0,1,0]
	v_pk_mul_f32 v[52:53], v[50:51], v[46:47] op_sel:[0,0] op_sel_hi:[0,1]
	v_pk_fma_f32 v[50:51], v[50:51], v[46:47], v[52:53] op_sel:[1,1,0] op_sel_hi:[1,0,1] neg_lo:[0,1,0]
	ds_write_b64 v132, v[50:51] offset:30464
	v_pk_mul_f32 v[50:51], v[46:47], v[58:59] op_sel:[0,0] op_sel_hi:[0,1]
	v_pk_fma_f32 v[46:47], v[46:47], v[58:59], v[50:51] op_sel:[1,1,0] op_sel_hi:[1,0,1] neg_lo:[0,1,0]
	v_pk_mul_f32 v[50:51], v[48:49], v[46:47] op_sel:[0,0] op_sel_hi:[0,1]
	v_pk_fma_f32 v[46:47], v[48:49], v[46:47], v[50:51] op_sel:[1,1,0] op_sel_hi:[1,0,1] neg_lo:[0,1,0]
	ds_write_b64 v132, v[46:47] offset:32640
	s_waitcnt lgkmcnt(0)
	s_barrier
	ds_read2_b64 v[46:49], v134 offset1:17
	ds_read2_b64 v[50:53], v134 offset0:34 offset1:51
	ds_read2_b64 v[54:57], v134 offset0:68 offset1:85
	ds_read2_b64 v[58:61], v134 offset0:136 offset1:153
	ds_read2_b64 v[62:65], v134 offset0:102 offset1:119
	ds_read2_b64 v[66:69], v134 offset0:204 offset1:221
	ds_read2_b64 v[70:73], v134 offset0:170 offset1:187
	ds_read2_b64 v[74:77], v134 offset0:238 offset1:255
	s_waitcnt lgkmcnt(4)
	v_pk_add_f32 v[78:79], v[46:47], v[58:59]
	v_pk_add_f32 v[46:47], v[46:47], v[58:59] neg_lo:[0,1] neg_hi:[0,1]
	s_waitcnt lgkmcnt(2)
	v_pk_add_f32 v[58:59], v[54:55], v[66:67]
	v_pk_add_f32 v[54:55], v[54:55], v[66:67] neg_lo:[0,1] neg_hi:[0,1]
	v_pk_add_f32 v[66:67], v[78:79], v[58:59]
	v_pk_add_f32 v[58:59], v[78:79], v[58:59] neg_lo:[0,1] neg_hi:[0,1]
	v_pk_add_f32 v[78:79], v[46:47], v[54:55] op_sel:[0,1] op_sel_hi:[1,0] neg_hi:[0,1]
	v_pk_add_f32 v[46:47], v[46:47], v[54:55] op_sel:[0,1] op_sel_hi:[1,0] neg_lo:[0,1]
	v_pk_add_f32 v[54:55], v[48:49], v[60:61]
	v_pk_add_f32 v[48:49], v[48:49], v[60:61] neg_lo:[0,1] neg_hi:[0,1]
	v_pk_add_f32 v[60:61], v[56:57], v[68:69]
	v_pk_add_f32 v[56:57], v[56:57], v[68:69] neg_lo:[0,1] neg_hi:[0,1]
	v_pk_add_f32 v[68:69], v[54:55], v[60:61]
	v_pk_add_f32 v[54:55], v[54:55], v[60:61] neg_lo:[0,1] neg_hi:[0,1]
	v_pk_add_f32 v[60:61], v[48:49], v[56:57] op_sel:[0,1] op_sel_hi:[1,0] neg_hi:[0,1]
	v_pk_add_f32 v[48:49], v[48:49], v[56:57] op_sel:[0,1] op_sel_hi:[1,0] neg_lo:[0,1]
	s_waitcnt lgkmcnt(1)
	v_pk_add_f32 v[56:57], v[50:51], v[70:71]
	v_pk_add_f32 v[50:51], v[50:51], v[70:71] neg_lo:[0,1] neg_hi:[0,1]
	s_waitcnt lgkmcnt(0)
	v_pk_add_f32 v[70:71], v[62:63], v[74:75]
	v_pk_add_f32 v[62:63], v[62:63], v[74:75] neg_lo:[0,1] neg_hi:[0,1]
	v_pk_add_f32 v[74:75], v[56:57], v[70:71]
	v_pk_add_f32 v[56:57], v[56:57], v[70:71] neg_lo:[0,1] neg_hi:[0,1]
	v_pk_add_f32 v[70:71], v[50:51], v[62:63] op_sel:[0,1] op_sel_hi:[1,0] neg_hi:[0,1]
	v_pk_add_f32 v[50:51], v[50:51], v[62:63] op_sel:[0,1] op_sel_hi:[1,0] neg_lo:[0,1]
	v_pk_add_f32 v[62:63], v[52:53], v[72:73]
	v_pk_add_f32 v[52:53], v[52:53], v[72:73] neg_lo:[0,1] neg_hi:[0,1]
	v_pk_add_f32 v[72:73], v[64:65], v[76:77]
	v_pk_add_f32 v[64:65], v[64:65], v[76:77] neg_lo:[0,1] neg_hi:[0,1]
	v_pk_add_f32 v[76:77], v[62:63], v[72:73]
	v_pk_add_f32 v[62:63], v[62:63], v[72:73] neg_lo:[0,1] neg_hi:[0,1]
	v_pk_add_f32 v[72:73], v[52:53], v[64:65] op_sel:[0,1] op_sel_hi:[1,0] neg_hi:[0,1]
	v_pk_add_f32 v[52:53], v[52:53], v[64:65] op_sel:[0,1] op_sel_hi:[1,0] neg_lo:[0,1]
	v_pk_mul_f32 v[64:65], v[60:61], s[20:21] op_sel:[0,0] op_sel_hi:[0,1]
	v_pk_fma_f32 v[60:61], v[60:61], s[20:21], v[64:65] op_sel:[1,1,0] op_sel_hi:[1,0,1] neg_lo:[0,1,0]
	v_pk_mul_f32 v[64:65], v[70:71], v[28:29] op_sel:[0,0] op_sel_hi:[0,1]
	v_pk_fma_f32 v[64:65], v[70:71], v[28:29], v[64:65] op_sel:[1,1,0] op_sel_hi:[1,0,1] neg_lo:[0,1,0]
	v_pk_mul_f32 v[70:71], v[72:73], v[26:27] op_sel:[0,0] op_sel_hi:[0,1]
	v_pk_fma_f32 v[70:71], v[72:73], v[26:27], v[70:71] op_sel:[1,1,0] op_sel_hi:[1,0,1] neg_lo:[0,1,0]
	v_pk_mul_f32 v[72:73], v[54:55], v[28:29] op_sel:[0,0] op_sel_hi:[0,1]
	v_pk_fma_f32 v[54:55], v[54:55], v[28:29], v[72:73] op_sel:[1,1,0] op_sel_hi:[1,0,1] neg_lo:[0,1,0]
	v_pk_mul_f32 v[72:73], v[56:57], s[8:9] op_sel:[0,0] op_sel_hi:[0,1]
	v_pk_fma_f32 v[56:57], v[56:57], s[8:9], v[72:73] op_sel:[1,1,0] op_sel_hi:[1,0,1] neg_lo:[0,1,0]
	v_pk_mul_f32 v[72:73], v[62:63], s[54:55] op_sel:[0,0] op_sel_hi:[0,1]
	v_pk_fma_f32 v[62:63], v[62:63], s[54:55], v[72:73] op_sel:[1,1,0] op_sel_hi:[1,0,1] neg_lo:[0,1,0]
	v_pk_mul_f32 v[72:73], v[48:49], v[26:27] op_sel:[0,0] op_sel_hi:[0,1]
	v_pk_fma_f32 v[48:49], v[48:49], v[26:27], v[72:73] op_sel:[1,1,0] op_sel_hi:[1,0,1] neg_lo:[0,1,0]
	v_pk_mul_f32 v[72:73], v[50:51], s[54:55] op_sel:[0,0] op_sel_hi:[0,1]
	v_pk_fma_f32 v[50:51], v[50:51], s[54:55], v[72:73] op_sel:[1,1,0] op_sel_hi:[1,0,1] neg_lo:[0,1,0]
	v_pk_mul_f32 v[72:73], v[52:53], s[56:57] op_sel:[0,0] op_sel_hi:[0,1]
	v_pk_fma_f32 v[52:53], v[52:53], s[56:57], v[72:73] op_sel:[1,1,0] op_sel_hi:[1,0,1] neg_lo:[0,1,0]
	v_pk_add_f32 v[72:73], v[66:67], v[74:75]
	v_pk_add_f32 v[66:67], v[66:67], v[74:75] neg_lo:[0,1] neg_hi:[0,1]
	v_pk_add_f32 v[74:75], v[68:69], v[76:77]
	v_pk_add_f32 v[68:69], v[68:69], v[76:77] neg_lo:[0,1] neg_hi:[0,1]
	v_pk_add_f32 v[76:77], v[72:73], v[74:75]
	v_pk_add_f32 v[72:73], v[72:73], v[74:75] neg_lo:[0,1] neg_hi:[0,1]
	v_pk_add_f32 v[74:75], v[66:67], v[68:69] op_sel:[0,1] op_sel_hi:[1,0] neg_hi:[0,1]
	v_pk_add_f32 v[66:67], v[66:67], v[68:69] op_sel:[0,1] op_sel_hi:[1,0] neg_lo:[0,1]
	v_pk_add_f32 v[68:69], v[78:79], v[64:65]
	v_pk_add_f32 v[64:65], v[78:79], v[64:65] neg_lo:[0,1] neg_hi:[0,1]
	v_pk_add_f32 v[78:79], v[60:61], v[70:71]
	v_pk_add_f32 v[60:61], v[60:61], v[70:71] neg_lo:[0,1] neg_hi:[0,1]
	v_pk_add_f32 v[70:71], v[68:69], v[78:79]
	v_pk_add_f32 v[68:69], v[68:69], v[78:79] neg_lo:[0,1] neg_hi:[0,1]
	v_pk_add_f32 v[78:79], v[64:65], v[60:61] op_sel:[0,1] op_sel_hi:[1,0] neg_hi:[0,1]
	v_pk_add_f32 v[60:61], v[64:65], v[60:61] op_sel:[0,1] op_sel_hi:[1,0] neg_lo:[0,1]
	v_pk_add_f32 v[64:65], v[58:59], v[56:57]
	v_pk_add_f32 v[56:57], v[58:59], v[56:57] neg_lo:[0,1] neg_hi:[0,1]
	v_pk_add_f32 v[58:59], v[54:55], v[62:63]
	v_pk_add_f32 v[54:55], v[54:55], v[62:63] neg_lo:[0,1] neg_hi:[0,1]
	v_pk_add_f32 v[62:63], v[64:65], v[58:59]
	v_pk_add_f32 v[58:59], v[64:65], v[58:59] neg_lo:[0,1] neg_hi:[0,1]
	v_pk_add_f32 v[64:65], v[56:57], v[54:55] op_sel:[0,1] op_sel_hi:[1,0] neg_hi:[0,1]
	v_pk_add_f32 v[54:55], v[56:57], v[54:55] op_sel:[0,1] op_sel_hi:[1,0] neg_lo:[0,1]
	v_pk_add_f32 v[56:57], v[46:47], v[50:51]
	v_pk_add_f32 v[46:47], v[46:47], v[50:51] neg_lo:[0,1] neg_hi:[0,1]
	v_pk_add_f32 v[50:51], v[48:49], v[52:53]
	v_pk_add_f32 v[48:49], v[48:49], v[52:53] neg_lo:[0,1] neg_hi:[0,1]
	v_pk_add_f32 v[52:53], v[56:57], v[50:51]
	v_pk_add_f32 v[50:51], v[56:57], v[50:51] neg_lo:[0,1] neg_hi:[0,1]
	v_pk_add_f32 v[56:57], v[46:47], v[48:49] op_sel:[0,1] op_sel_hi:[1,0] neg_hi:[0,1]
	v_pk_add_f32 v[46:47], v[46:47], v[48:49] op_sel:[0,1] op_sel_hi:[1,0] neg_lo:[0,1]
	v_mov_b32_e32 v48, v40
	v_mov_b32_e32 v49, v41
	s_waitcnt vmcnt(5)
	v_pk_mul_f32 v[80:81], v[70:71], v[48:49] op_sel:[0,0] op_sel_hi:[0,1]
	v_pk_fma_f32 v[70:71], v[70:71], v[48:49], v[80:81] op_sel:[1,1,0] op_sel_hi:[1,0,1] neg_lo:[0,1,0]
	ds_write2_b64 v134, v[76:77], v[70:71] offset1:17
	v_pk_mul_f32 v[70:71], v[48:49], v[48:49] op_sel:[0,0] op_sel_hi:[0,1]
	v_pk_fma_f32 v[70:71], v[48:49], v[48:49], v[70:71] op_sel:[1,1,0] op_sel_hi:[1,0,1] neg_lo:[0,1,0]
	v_pk_mul_f32 v[76:77], v[62:63], v[70:71] op_sel:[0,0] op_sel_hi:[0,1]
	v_pk_fma_f32 v[62:63], v[62:63], v[70:71], v[76:77] op_sel:[1,1,0] op_sel_hi:[1,0,1] neg_lo:[0,1,0]
	v_pk_mul_f32 v[76:77], v[70:71], v[48:49] op_sel:[0,0] op_sel_hi:[0,1]
	v_pk_fma_f32 v[70:71], v[70:71], v[48:49], v[76:77] op_sel:[1,1,0] op_sel_hi:[1,0,1] neg_lo:[0,1,0]
	v_pk_mul_f32 v[76:77], v[52:53], v[70:71] op_sel:[0,0] op_sel_hi:[0,1]
	v_pk_fma_f32 v[52:53], v[52:53], v[70:71], v[76:77] op_sel:[1,1,0] op_sel_hi:[1,0,1] neg_lo:[0,1,0]
	ds_write2_b64 v134, v[62:63], v[52:53] offset0:34 offset1:51
	v_pk_mul_f32 v[52:53], v[70:71], v[48:49] op_sel:[0,0] op_sel_hi:[0,1]
	v_pk_fma_f32 v[52:53], v[70:71], v[48:49], v[52:53] op_sel:[1,1,0] op_sel_hi:[1,0,1] neg_lo:[0,1,0]
	v_pk_mul_f32 v[62:63], v[74:75], v[52:53] op_sel:[0,0] op_sel_hi:[0,1]
	v_pk_mul_f32 v[70:71], v[52:53], v[48:49] op_sel:[0,0] op_sel_hi:[0,1]
	v_pk_fma_f32 v[62:63], v[74:75], v[52:53], v[62:63] op_sel:[1,1,0] op_sel_hi:[1,0,1] neg_lo:[0,1,0]
	v_pk_fma_f32 v[52:53], v[52:53], v[48:49], v[70:71] op_sel:[1,1,0] op_sel_hi:[1,0,1] neg_lo:[0,1,0]
	v_pk_mul_f32 v[70:71], v[78:79], v[52:53] op_sel:[0,0] op_sel_hi:[0,1]
	v_pk_fma_f32 v[70:71], v[78:79], v[52:53], v[70:71] op_sel:[1,1,0] op_sel_hi:[1,0,1] neg_lo:[0,1,0]
	ds_write2_b64 v134, v[62:63], v[70:71] offset0:68 offset1:85
	v_pk_mul_f32 v[62:63], v[52:53], v[48:49] op_sel:[0,0] op_sel_hi:[0,1]
	v_pk_fma_f32 v[52:53], v[52:53], v[48:49], v[62:63] op_sel:[1,1,0] op_sel_hi:[1,0,1] neg_lo:[0,1,0]
	v_pk_mul_f32 v[62:63], v[64:65], v[52:53] op_sel:[0,0] op_sel_hi:[0,1]
	v_pk_fma_f32 v[62:63], v[64:65], v[52:53], v[62:63] op_sel:[1,1,0] op_sel_hi:[1,0,1] neg_lo:[0,1,0]
	v_pk_mul_f32 v[64:65], v[52:53], v[48:49] op_sel:[0,0] op_sel_hi:[0,1]
	v_pk_fma_f32 v[52:53], v[52:53], v[48:49], v[64:65] op_sel:[1,1,0] op_sel_hi:[1,0,1] neg_lo:[0,1,0]
	v_pk_mul_f32 v[64:65], v[56:57], v[52:53] op_sel:[0,0] op_sel_hi:[0,1]
	v_pk_fma_f32 v[56:57], v[56:57], v[52:53], v[64:65] op_sel:[1,1,0] op_sel_hi:[1,0,1] neg_lo:[0,1,0]
	ds_write2_b64 v134, v[62:63], v[56:57] offset0:102 offset1:119
	v_pk_mul_f32 v[56:57], v[52:53], v[48:49] op_sel:[0,0] op_sel_hi:[0,1]
	v_pk_fma_f32 v[52:53], v[52:53], v[48:49], v[56:57] op_sel:[1,1,0] op_sel_hi:[1,0,1] neg_lo:[0,1,0]
	v_pk_mul_f32 v[56:57], v[72:73], v[52:53] op_sel:[0,0] op_sel_hi:[0,1]
	v_pk_mul_f32 v[62:63], v[52:53], v[48:49] op_sel:[0,0] op_sel_hi:[0,1]
	v_pk_fma_f32 v[56:57], v[72:73], v[52:53], v[56:57] op_sel:[1,1,0] op_sel_hi:[1,0,1] neg_lo:[0,1,0]
	v_pk_fma_f32 v[52:53], v[52:53], v[48:49], v[62:63] op_sel:[1,1,0] op_sel_hi:[1,0,1] neg_lo:[0,1,0]
	v_pk_mul_f32 v[62:63], v[68:69], v[52:53] op_sel:[0,0] op_sel_hi:[0,1]
	v_pk_fma_f32 v[62:63], v[68:69], v[52:53], v[62:63] op_sel:[1,1,0] op_sel_hi:[1,0,1] neg_lo:[0,1,0]
	ds_write2_b64 v134, v[56:57], v[62:63] offset0:136 offset1:153
	v_pk_mul_f32 v[56:57], v[52:53], v[48:49] op_sel:[0,0] op_sel_hi:[0,1]
	v_pk_fma_f32 v[52:53], v[52:53], v[48:49], v[56:57] op_sel:[1,1,0] op_sel_hi:[1,0,1] neg_lo:[0,1,0]
	v_pk_mul_f32 v[56:57], v[58:59], v[52:53] op_sel:[0,0] op_sel_hi:[0,1]
	v_pk_fma_f32 v[56:57], v[58:59], v[52:53], v[56:57] op_sel:[1,1,0] op_sel_hi:[1,0,1] neg_lo:[0,1,0]
	v_pk_mul_f32 v[58:59], v[52:53], v[48:49] op_sel:[0,0] op_sel_hi:[0,1]
	v_pk_fma_f32 v[52:53], v[52:53], v[48:49], v[58:59] op_sel:[1,1,0] op_sel_hi:[1,0,1] neg_lo:[0,1,0]
	v_pk_mul_f32 v[58:59], v[50:51], v[52:53] op_sel:[0,0] op_sel_hi:[0,1]
	v_pk_fma_f32 v[50:51], v[50:51], v[52:53], v[58:59] op_sel:[1,1,0] op_sel_hi:[1,0,1] neg_lo:[0,1,0]
	ds_write2_b64 v134, v[56:57], v[50:51] offset0:170 offset1:187
	v_pk_mul_f32 v[50:51], v[52:53], v[48:49] op_sel:[0,0] op_sel_hi:[0,1]
	v_pk_fma_f32 v[50:51], v[52:53], v[48:49], v[50:51] op_sel:[1,1,0] op_sel_hi:[1,0,1] neg_lo:[0,1,0]
	v_pk_mul_f32 v[52:53], v[66:67], v[50:51] op_sel:[0,0] op_sel_hi:[0,1]
	v_pk_mul_f32 v[56:57], v[50:51], v[48:49] op_sel:[0,0] op_sel_hi:[0,1]
	v_pk_fma_f32 v[52:53], v[66:67], v[50:51], v[52:53] op_sel:[1,1,0] op_sel_hi:[1,0,1] neg_lo:[0,1,0]
	v_pk_fma_f32 v[50:51], v[50:51], v[48:49], v[56:57] op_sel:[1,1,0] op_sel_hi:[1,0,1] neg_lo:[0,1,0]
	v_pk_mul_f32 v[56:57], v[60:61], v[50:51] op_sel:[0,0] op_sel_hi:[0,1]
	v_pk_fma_f32 v[56:57], v[60:61], v[50:51], v[56:57] op_sel:[1,1,0] op_sel_hi:[1,0,1] neg_lo:[0,1,0]
	ds_write2_b64 v134, v[52:53], v[56:57] offset0:204 offset1:221
	v_pk_mul_f32 v[52:53], v[50:51], v[48:49] op_sel:[0,0] op_sel_hi:[0,1]
	v_pk_fma_f32 v[50:51], v[50:51], v[48:49], v[52:53] op_sel:[1,1,0] op_sel_hi:[1,0,1] neg_lo:[0,1,0]
	v_pk_mul_f32 v[52:53], v[54:55], v[50:51] op_sel:[0,0] op_sel_hi:[0,1]
	v_pk_fma_f32 v[52:53], v[54:55], v[50:51], v[52:53] op_sel:[1,1,0] op_sel_hi:[1,0,1] neg_lo:[0,1,0]
	v_pk_mul_f32 v[54:55], v[50:51], v[48:49] op_sel:[0,0] op_sel_hi:[0,1]
	v_pk_fma_f32 v[48:49], v[50:51], v[48:49], v[54:55] op_sel:[1,1,0] op_sel_hi:[1,0,1] neg_lo:[0,1,0]
	v_pk_mul_f32 v[50:51], v[46:47], v[48:49] op_sel:[0,0] op_sel_hi:[0,1]
	v_pk_fma_f32 v[46:47], v[46:47], v[48:49], v[50:51] op_sel:[1,1,0] op_sel_hi:[1,0,1] neg_lo:[0,1,0]
	ds_write2_b64 v134, v[52:53], v[46:47] offset0:238 offset1:255
	s_waitcnt lgkmcnt(0)
	s_barrier
	ds_read2_b64 v[46:49], v135 offset1:1
	ds_read2_b64 v[50:53], v135 offset0:2 offset1:3
	ds_read2_b64 v[54:57], v135 offset0:8 offset1:9
	ds_read2_b64 v[58:61], v135 offset0:4 offset1:5
	ds_read2_b64 v[62:65], v135 offset0:6 offset1:7
	ds_read2_b64 v[66:69], v135 offset0:12 offset1:13
	ds_read2_b64 v[70:73], v135 offset0:10 offset1:11
	ds_read2_b64 v[74:77], v135 offset0:14 offset1:15
	s_waitcnt lgkmcnt(5)
	v_pk_add_f32 v[78:79], v[46:47], v[54:55]
	v_pk_add_f32 v[46:47], v[46:47], v[54:55] neg_lo:[0,1] neg_hi:[0,1]
	s_waitcnt lgkmcnt(2)
	v_pk_add_f32 v[54:55], v[58:59], v[66:67]
	v_pk_add_f32 v[58:59], v[58:59], v[66:67] neg_lo:[0,1] neg_hi:[0,1]
	v_pk_add_f32 v[66:67], v[78:79], v[54:55]
	v_pk_add_f32 v[54:55], v[78:79], v[54:55] neg_lo:[0,1] neg_hi:[0,1]
	v_pk_add_f32 v[78:79], v[46:47], v[58:59] op_sel:[0,1] op_sel_hi:[1,0] neg_hi:[0,1]
	v_pk_add_f32 v[46:47], v[46:47], v[58:59] op_sel:[0,1] op_sel_hi:[1,0] neg_lo:[0,1]
	v_pk_add_f32 v[58:59], v[48:49], v[56:57]
	v_pk_add_f32 v[48:49], v[48:49], v[56:57] neg_lo:[0,1] neg_hi:[0,1]
	v_pk_add_f32 v[56:57], v[60:61], v[68:69]
	v_pk_add_f32 v[60:61], v[60:61], v[68:69] neg_lo:[0,1] neg_hi:[0,1]
	v_pk_add_f32 v[68:69], v[58:59], v[56:57]
	v_pk_add_f32 v[56:57], v[58:59], v[56:57] neg_lo:[0,1] neg_hi:[0,1]
	v_pk_add_f32 v[58:59], v[48:49], v[60:61] op_sel:[0,1] op_sel_hi:[1,0] neg_hi:[0,1]
	v_pk_add_f32 v[48:49], v[48:49], v[60:61] op_sel:[0,1] op_sel_hi:[1,0] neg_lo:[0,1]
	s_waitcnt lgkmcnt(1)
	v_pk_add_f32 v[60:61], v[50:51], v[70:71]
	v_pk_add_f32 v[50:51], v[50:51], v[70:71] neg_lo:[0,1] neg_hi:[0,1]
	s_waitcnt lgkmcnt(0)
	v_pk_add_f32 v[70:71], v[62:63], v[74:75]
	v_pk_add_f32 v[62:63], v[62:63], v[74:75] neg_lo:[0,1] neg_hi:[0,1]
	v_pk_add_f32 v[74:75], v[60:61], v[70:71]
	v_pk_add_f32 v[60:61], v[60:61], v[70:71] neg_lo:[0,1] neg_hi:[0,1]
	v_pk_add_f32 v[70:71], v[50:51], v[62:63] op_sel:[0,1] op_sel_hi:[1,0] neg_hi:[0,1]
	v_pk_add_f32 v[50:51], v[50:51], v[62:63] op_sel:[0,1] op_sel_hi:[1,0] neg_lo:[0,1]
	v_pk_add_f32 v[62:63], v[52:53], v[72:73]
	v_pk_add_f32 v[52:53], v[52:53], v[72:73] neg_lo:[0,1] neg_hi:[0,1]
	v_pk_add_f32 v[72:73], v[64:65], v[76:77]
	v_pk_add_f32 v[64:65], v[64:65], v[76:77] neg_lo:[0,1] neg_hi:[0,1]
	v_pk_add_f32 v[76:77], v[62:63], v[72:73]
	v_pk_add_f32 v[62:63], v[62:63], v[72:73] neg_lo:[0,1] neg_hi:[0,1]
	v_pk_add_f32 v[72:73], v[52:53], v[64:65] op_sel:[0,1] op_sel_hi:[1,0] neg_hi:[0,1]
	v_pk_add_f32 v[52:53], v[52:53], v[64:65] op_sel:[0,1] op_sel_hi:[1,0] neg_lo:[0,1]
	v_pk_mul_f32 v[64:65], v[58:59], s[20:21] op_sel:[0,0] op_sel_hi:[0,1]
	v_pk_fma_f32 v[32:33], v[58:59], s[20:21], v[64:65] op_sel:[1,1,0] op_sel_hi:[1,0,1] neg_lo:[0,1,0]
	v_pk_mul_f32 v[58:59], v[70:71], v[28:29] op_sel:[0,0] op_sel_hi:[0,1]
	v_pk_mul_f32 v[64:65], v[72:73], v[26:27] op_sel:[0,0] op_sel_hi:[0,1]
	s_barrier
	v_pk_fma_f32 v[58:59], v[70:71], v[28:29], v[58:59] op_sel:[1,1,0] op_sel_hi:[1,0,1] neg_lo:[0,1,0]
	v_pk_mul_f32 v[70:71], v[56:57], v[28:29] op_sel:[0,0] op_sel_hi:[0,1]
	v_pk_fma_f32 v[64:65], v[72:73], v[26:27], v[64:65] op_sel:[1,1,0] op_sel_hi:[1,0,1] neg_lo:[0,1,0]
	v_pk_fma_f32 v[28:29], v[56:57], v[28:29], v[70:71] op_sel:[1,1,0] op_sel_hi:[1,0,1] neg_lo:[0,1,0]
	v_pk_mul_f32 v[56:57], v[60:61], s[8:9] op_sel:[0,0] op_sel_hi:[0,1]
	v_pk_fma_f32 v[42:43], v[60:61], s[8:9], v[56:57] op_sel:[1,1,0] op_sel_hi:[1,0,1] neg_lo:[0,1,0]
	v_pk_mul_f32 v[56:57], v[62:63], s[54:55] op_sel:[0,0] op_sel_hi:[0,1]
	v_pk_mul_f32 v[60:61], v[48:49], v[26:27] op_sel:[0,0] op_sel_hi:[0,1]
	v_pk_fma_f32 v[26:27], v[48:49], v[26:27], v[60:61] op_sel:[1,1,0] op_sel_hi:[1,0,1] neg_lo:[0,1,0]
	v_pk_mul_f32 v[48:49], v[50:51], s[54:55] op_sel:[0,0] op_sel_hi:[0,1]
	v_pk_fma_f32 v[56:57], v[62:63], s[54:55], v[56:57] op_sel:[1,1,0] op_sel_hi:[1,0,1] neg_lo:[0,1,0]
	v_pk_add_f32 v[60:61], v[68:69], v[76:77] neg_lo:[0,1] neg_hi:[0,1]
	v_pk_fma_f32 v[30:31], v[50:51], s[54:55], v[48:49] op_sel:[1,1,0] op_sel_hi:[1,0,1] neg_lo:[0,1,0]
	v_pk_mul_f32 v[48:49], v[52:53], s[56:57] op_sel:[0,0] op_sel_hi:[0,1]
	v_pk_add_f32 v[50:51], v[66:67], v[74:75] neg_lo:[0,1] neg_hi:[0,1]
	v_pk_fma_f32 v[44:45], v[52:53], s[56:57], v[48:49] op_sel:[1,1,0] op_sel_hi:[1,0,1] neg_lo:[0,1,0]
	v_pk_add_f32 v[48:49], v[66:67], v[74:75]
	v_pk_add_f32 v[52:53], v[68:69], v[76:77]
	v_pk_add_f32 v[66:67], v[32:33], v[64:65]
	v_pk_add_f32 v[62:63], v[48:49], v[52:53]
	v_pk_add_f32 v[48:49], v[48:49], v[52:53] neg_lo:[0,1] neg_hi:[0,1]
	v_pk_add_f32 v[52:53], v[50:51], v[60:61] op_sel:[0,1] op_sel_hi:[1,0] neg_hi:[0,1]
	v_pk_add_f32 v[50:51], v[50:51], v[60:61] op_sel:[0,1] op_sel_hi:[1,0] neg_lo:[0,1]
	v_pk_add_f32 v[60:61], v[78:79], v[58:59]
	v_pk_add_f32 v[58:59], v[78:79], v[58:59] neg_lo:[0,1] neg_hi:[0,1]
	v_pk_add_f32 v[32:33], v[32:33], v[64:65] neg_lo:[0,1] neg_hi:[0,1]
	v_pk_add_f32 v[64:65], v[60:61], v[66:67]
	v_pk_add_f32 v[60:61], v[60:61], v[66:67] neg_lo:[0,1] neg_hi:[0,1]
	v_pk_add_f32 v[66:67], v[58:59], v[32:33] op_sel:[0,1] op_sel_hi:[1,0] neg_hi:[0,1]
	v_pk_add_f32 v[58:59], v[58:59], v[32:33] op_sel:[0,1] op_sel_hi:[1,0] neg_lo:[0,1]
	v_pk_add_f32 v[32:33], v[54:55], v[42:43]
	v_pk_add_f32 v[42:43], v[54:55], v[42:43] neg_lo:[0,1] neg_hi:[0,1]
	v_pk_add_f32 v[54:55], v[28:29], v[56:57]
	v_pk_add_f32 v[28:29], v[28:29], v[56:57] neg_lo:[0,1] neg_hi:[0,1]
	v_pk_add_f32 v[56:57], v[32:33], v[54:55]
	v_pk_add_f32 v[54:55], v[32:33], v[54:55] neg_lo:[0,1] neg_hi:[0,1]
	v_pk_add_f32 v[68:69], v[42:43], v[28:29] op_sel:[0,1] op_sel_hi:[1,0] neg_hi:[0,1]
	v_pk_add_f32 v[42:43], v[42:43], v[28:29] op_sel:[0,1] op_sel_hi:[1,0] neg_lo:[0,1]
	v_pk_add_f32 v[28:29], v[46:47], v[30:31]
	v_pk_add_f32 v[32:33], v[26:27], v[44:45]
	v_pk_add_f32 v[30:31], v[46:47], v[30:31] neg_lo:[0,1] neg_hi:[0,1]
	v_pk_add_f32 v[26:27], v[26:27], v[44:45] neg_lo:[0,1] neg_hi:[0,1]
	v_pk_add_f32 v[44:45], v[28:29], v[32:33]
	v_pk_add_f32 v[46:47], v[28:29], v[32:33] neg_lo:[0,1] neg_hi:[0,1]
	v_add_f32_e32 v28, 0x358637bd, v34
	v_mul_f32_e32 v28, 0x46000000, v28
	v_div_scale_f32 v29, s[0:1], v28, v28, 1.0
	s_waitcnt vmcnt(1)
	v_pk_add_f32 v[88:89], v[30:31], v[26:27] op_sel:[0,1] op_sel_hi:[1,0] neg_hi:[0,1]
	v_pk_add_f32 v[26:27], v[30:31], v[26:27] op_sel:[0,1] op_sel_hi:[1,0] neg_lo:[0,1]
	v_rcp_f32_e32 v30, v29
	s_nop 0
	v_fma_f32 v31, -v29, v30, 1.0
	v_fmac_f32_e32 v30, v31, v30
	v_div_scale_f32 v31, vcc, 1.0, v28, 1.0
	v_mul_f32_e32 v32, v31, v30
	v_fma_f32 v33, -v29, v32, v31
	v_fmac_f32_e32 v32, v33, v30
	v_fma_f32 v29, -v29, v32, v31
	v_div_fmas_f32 v29, v29, v30, v32
	v_div_fixup_f32 v34, v29, v28, 1.0
	v_pk_mul_f32 v[70:71], v[34:35], v[62:63] op_sel_hi:[0,1]
	v_pk_mul_f32 v[30:31], v[34:35], v[52:53] op_sel_hi:[0,1]
	v_pk_mul_f32 v[28:29], v[34:35], v[48:49] op_sel_hi:[0,1]
	v_pk_mul_f32 v[32:33], v[34:35], v[50:51] op_sel_hi:[0,1]
	v_pk_mul_f32 v[78:79], v[34:35], v[64:65] op_sel_hi:[0,1]
	v_pk_mul_f32 v[74:75], v[34:35], v[66:67] op_sel_hi:[0,1]
	v_pk_mul_f32 v[72:73], v[34:35], v[60:61] op_sel_hi:[0,1]
	v_pk_mul_f32 v[76:77], v[34:35], v[58:59] op_sel_hi:[0,1]
	v_pk_mul_f32 v[86:87], v[34:35], v[56:57] op_sel_hi:[0,1]
	v_pk_mul_f32 v[82:83], v[34:35], v[68:69] op_sel_hi:[0,1]
	v_pk_mul_f32 v[80:81], v[34:35], v[54:55] op_sel_hi:[0,1]
	v_pk_mul_f32 v[84:85], v[34:35], v[42:43] op_sel_hi:[0,1]
	v_pk_mul_f32 v[94:95], v[34:35], v[44:45] op_sel_hi:[0,1]
	v_pk_mul_f32 v[90:91], v[34:35], v[88:89] op_sel_hi:[0,1]
	v_pk_mul_f32 v[88:89], v[34:35], v[46:47] op_sel_hi:[0,1]
	s_waitcnt vmcnt(0)
	v_pk_mul_f32 v[92:93], v[34:35], v[26:27] op_sel_hi:[0,1]

.LBB0_3484:
	ds_read_b64 v[26:27], v132
	ds_read_b64 v[42:43], v132 offset:2176
	ds_read_b64 v[44:45], v132 offset:4352
	ds_read_b64 v[46:47], v132 offset:6528
	ds_read_b64 v[48:49], v132 offset:8704
	ds_read_b64 v[50:51], v132 offset:10880
	ds_read_b64 v[52:53], v132 offset:13056
	ds_read_b64 v[54:55], v132 offset:15232
	ds_read_b64 v[56:57], v132 offset:17408
	ds_read_b64 v[58:59], v132 offset:19584
	ds_read_b64 v[60:61], v132 offset:21760
	ds_read_b64 v[62:63], v132 offset:23936
	ds_read_b64 v[64:65], v132 offset:26112
	ds_read_b64 v[66:67], v132 offset:28288
	ds_read_b64 v[68:69], v132 offset:30464
	ds_read_b64 v[98:99], v132 offset:32640
	s_waitcnt lgkmcnt(7)
	v_pk_add_f32 v[100:101], v[26:27], v[56:57]
	v_pk_add_f32 v[26:27], v[26:27], v[56:57] neg_lo:[0,1] neg_hi:[0,1]
	s_waitcnt lgkmcnt(3)
	v_pk_add_f32 v[56:57], v[48:49], v[64:65]
	v_pk_add_f32 v[48:49], v[48:49], v[64:65] neg_lo:[0,1] neg_hi:[0,1]
	v_pk_add_f32 v[64:65], v[100:101], v[56:57]
	v_pk_add_f32 v[56:57], v[100:101], v[56:57] neg_lo:[0,1] neg_hi:[0,1]
	v_pk_add_f32 v[100:101], v[26:27], v[48:49] op_sel:[0,1] op_sel_hi:[1,0] neg_hi:[0,1]
	v_pk_add_f32 v[102:103], v[26:27], v[48:49] op_sel:[0,1] op_sel_hi:[1,0] neg_lo:[0,1]
	v_pk_add_f32 v[26:27], v[42:43], v[58:59]
	v_pk_add_f32 v[42:43], v[42:43], v[58:59] neg_lo:[0,1] neg_hi:[0,1]
	s_waitcnt lgkmcnt(2)
	v_pk_add_f32 v[48:49], v[50:51], v[66:67]
	v_pk_add_f32 v[50:51], v[50:51], v[66:67] neg_lo:[0,1] neg_hi:[0,1]
	v_pk_add_f32 v[58:59], v[26:27], v[48:49]
	v_pk_add_f32 v[48:49], v[26:27], v[48:49] neg_lo:[0,1] neg_hi:[0,1]
	v_pk_add_f32 v[26:27], v[42:43], v[50:51] op_sel:[0,1] op_sel_hi:[1,0] neg_hi:[0,1]
	v_pk_add_f32 v[50:51], v[42:43], v[50:51] op_sel:[0,1] op_sel_hi:[1,0] neg_lo:[0,1]
	v_pk_add_f32 v[42:43], v[44:45], v[60:61]
	v_pk_add_f32 v[44:45], v[44:45], v[60:61] neg_lo:[0,1] neg_hi:[0,1]
	s_waitcnt lgkmcnt(1)
	v_pk_add_f32 v[60:61], v[52:53], v[68:69]
	v_pk_add_f32 v[52:53], v[52:53], v[68:69] neg_lo:[0,1] neg_hi:[0,1]
	v_pk_add_f32 v[66:67], v[42:43], v[60:61]
	v_pk_add_f32 v[60:61], v[42:43], v[60:61] neg_lo:[0,1] neg_hi:[0,1]
	v_pk_add_f32 v[68:69], v[44:45], v[52:53] op_sel:[0,1] op_sel_hi:[1,0] neg_hi:[0,1]
	v_pk_add_f32 v[52:53], v[44:45], v[52:53] op_sel:[0,1] op_sel_hi:[1,0] neg_lo:[0,1]
	v_pk_add_f32 v[42:43], v[46:47], v[62:63]
	v_pk_add_f32 v[44:45], v[46:47], v[62:63] neg_lo:[0,1] neg_hi:[0,1]
	s_waitcnt lgkmcnt(0)
	v_pk_add_f32 v[46:47], v[54:55], v[98:99]
	v_pk_add_f32 v[54:55], v[54:55], v[98:99] neg_lo:[0,1] neg_hi:[0,1]
	v_pk_add_f32 v[62:63], v[42:43], v[46:47]
	v_pk_add_f32 v[98:99], v[42:43], v[46:47] neg_lo:[0,1] neg_hi:[0,1]
	v_pk_mul_f32 v[42:43], v[26:27], s[20:21] op_sel:[0,0] op_sel_hi:[0,1]
	v_pk_add_f32 v[104:105], v[44:45], v[54:55] op_sel:[0,1] op_sel_hi:[1,0] neg_hi:[0,1]
	v_pk_add_f32 v[54:55], v[44:45], v[54:55] op_sel:[0,1] op_sel_hi:[1,0] neg_lo:[0,1]
	s_add_i32 s78, s70, s24
	v_pk_fma_f32 v[106:107], v[26:27], s[20:21], v[42:43] op_sel:[1,1,0] op_sel_hi:[1,0,1] neg_lo:[0,1,0]
	v_pk_mul_f32 v[26:27], v[68:69], s[46:47] op_sel:[0,0] op_sel_hi:[0,1]
	s_cmpk_gt_i32 s78, 0x3ff
	v_pk_fma_f32 v[68:69], v[68:69], s[46:47], v[26:27] op_sel:[1,1,0] op_sel_hi:[1,0,1] neg_lo:[0,1,0]
	v_mov_b64_e32 v[26:27], s[50:51]
	v_pk_mul_f32 v[44:45], v[104:105], v[26:27] op_sel:[0,0] op_sel_hi:[0,1]
	s_cselect_b64 s[76:77], -1, 0
	v_pk_fma_f32 v[104:105], v[104:105], v[26:27], v[44:45] op_sel:[1,1,0] op_sel_hi:[1,0,1] neg_lo:[0,1,0]
	v_pk_mul_f32 v[44:45], v[48:49], s[46:47] op_sel:[0,0] op_sel_hi:[0,1]
	s_cmpk_lt_i32 s78, 0x400
	v_pk_fma_f32 v[110:111], v[48:49], s[46:47], v[44:45] op_sel:[1,1,0] op_sel_hi:[1,0,1] neg_lo:[0,1,0]
	v_mov_b64_e32 v[48:49], s[8:9]
	v_pk_mul_f32 v[44:45], v[60:61], v[48:49] op_sel:[0,0] op_sel_hi:[0,1]
	s_cselect_b32 s0, s78, -1
	v_pk_fma_f32 v[60:61], v[60:61], v[48:49], v[44:45] op_sel:[1,1,0] op_sel_hi:[1,0,1] neg_lo:[0,1,0]
	v_mov_b64_e32 v[44:45], s[54:55]
	v_pk_mul_f32 v[112:113], v[98:99], v[44:45] op_sel:[0,0] op_sel_hi:[0,1]
	s_cmp_lt_i32 s0, 0
	v_pk_fma_f32 v[98:99], v[98:99], v[44:45], v[112:113] op_sel:[1,1,0] op_sel_hi:[1,0,1] neg_lo:[0,1,0]
	v_pk_mul_f32 v[112:113], v[50:51], v[26:27] op_sel:[0,0] op_sel_hi:[0,1]
	v_pk_fma_f32 v[112:113], v[50:51], v[26:27], v[112:113] op_sel:[1,1,0] op_sel_hi:[1,0,1] neg_lo:[0,1,0]
	v_pk_mul_f32 v[50:51], v[52:53], v[44:45] op_sel:[0,0] op_sel_hi:[0,1]
	v_pk_fma_f32 v[52:53], v[52:53], v[44:45], v[50:51] op_sel:[1,1,0] op_sel_hi:[1,0,1] neg_lo:[0,1,0]
	v_pk_mul_f32 v[114:115], v[54:55], s[56:57] op_sel:[0,0] op_sel_hi:[0,1]
	v_pk_fma_f32 v[54:55], v[54:55], s[56:57], v[114:115] op_sel:[1,1,0] op_sel_hi:[1,0,1] neg_lo:[0,1,0]
	v_pk_add_f32 v[114:115], v[64:65], v[66:67]
	v_pk_add_f32 v[64:65], v[64:65], v[66:67] neg_lo:[0,1] neg_hi:[0,1]
	v_pk_add_f32 v[66:67], v[58:59], v[62:63]
	v_pk_add_f32 v[58:59], v[58:59], v[62:63] neg_lo:[0,1] neg_hi:[0,1]
	v_pk_add_f32 v[62:63], v[114:115], v[66:67]
	v_pk_add_f32 v[66:67], v[114:115], v[66:67] neg_lo:[0,1] neg_hi:[0,1]
	v_pk_add_f32 v[114:115], v[64:65], v[58:59] op_sel:[0,1] op_sel_hi:[1,0] neg_hi:[0,1]
	v_pk_add_f32 v[58:59], v[64:65], v[58:59] op_sel:[0,1] op_sel_hi:[1,0] neg_lo:[0,1]
	v_pk_add_f32 v[64:65], v[100:101], v[68:69]
	v_pk_add_f32 v[68:69], v[100:101], v[68:69] neg_lo:[0,1] neg_hi:[0,1]
	v_pk_add_f32 v[100:101], v[106:107], v[104:105]
	v_pk_add_f32 v[104:105], v[106:107], v[104:105] neg_lo:[0,1] neg_hi:[0,1]
	v_pk_add_f32 v[106:107], v[64:65], v[100:101]
	v_pk_add_f32 v[64:65], v[64:65], v[100:101] neg_lo:[0,1] neg_hi:[0,1]
	v_pk_add_f32 v[100:101], v[68:69], v[104:105] op_sel:[0,1] op_sel_hi:[1,0] neg_hi:[0,1]
	v_pk_add_f32 v[68:69], v[68:69], v[104:105] op_sel:[0,1] op_sel_hi:[1,0] neg_lo:[0,1]
	v_pk_add_f32 v[104:105], v[56:57], v[60:61]
	v_pk_add_f32 v[56:57], v[56:57], v[60:61] neg_lo:[0,1] neg_hi:[0,1]
	v_pk_add_f32 v[60:61], v[110:111], v[98:99]
	v_pk_add_f32 v[98:99], v[110:111], v[98:99] neg_lo:[0,1] neg_hi:[0,1]
	v_pk_add_f32 v[110:111], v[104:105], v[60:61]
	v_pk_add_f32 v[60:61], v[104:105], v[60:61] neg_lo:[0,1] neg_hi:[0,1]
	v_pk_add_f32 v[104:105], v[56:57], v[98:99] op_sel:[0,1] op_sel_hi:[1,0] neg_hi:[0,1]
	v_pk_add_f32 v[56:57], v[56:57], v[98:99] op_sel:[0,1] op_sel_hi:[1,0] neg_lo:[0,1]
	v_pk_add_f32 v[98:99], v[102:103], v[52:53]
	v_pk_add_f32 v[52:53], v[102:103], v[52:53] neg_lo:[0,1] neg_hi:[0,1]
	v_pk_add_f32 v[102:103], v[112:113], v[54:55]
	v_pk_add_f32 v[54:55], v[112:113], v[54:55] neg_lo:[0,1] neg_hi:[0,1]
	v_pk_add_f32 v[112:113], v[98:99], v[102:103]
	v_pk_add_f32 v[98:99], v[98:99], v[102:103] neg_lo:[0,1] neg_hi:[0,1]
	v_pk_add_f32 v[102:103], v[52:53], v[54:55] op_sel:[0,1] op_sel_hi:[1,0] neg_hi:[0,1]
	v_pk_add_f32 v[52:53], v[52:53], v[54:55] op_sel:[0,1] op_sel_hi:[1,0] neg_lo:[0,1]
	v_mov_b32_e32 v55, v39
	v_mov_b32_e32 v54, v38
	ds_write_b64 v132, v[62:63]
	v_pk_mul_f32 v[62:63], v[106:107], v[54:55] op_sel:[0,0] op_sel_hi:[0,1]
	v_pk_fma_f32 v[62:63], v[106:107], v[54:55], v[62:63] op_sel:[1,1,0] op_sel_hi:[1,0,1] neg_lo:[0,1,0]
	ds_write_b64 v132, v[62:63] offset:2176
	v_pk_mul_f32 v[62:63], v[54:55], v[54:55] op_sel:[0,0] op_sel_hi:[0,1]
	v_pk_fma_f32 v[62:63], v[54:55], v[54:55], v[62:63] op_sel:[1,1,0] op_sel_hi:[1,0,1] neg_lo:[0,1,0]
	v_pk_mul_f32 v[106:107], v[110:111], v[62:63] op_sel:[0,0] op_sel_hi:[0,1]
	v_pk_fma_f32 v[106:107], v[110:111], v[62:63], v[106:107] op_sel:[1,1,0] op_sel_hi:[1,0,1] neg_lo:[0,1,0]
	ds_write_b64 v132, v[106:107] offset:4352
	v_pk_mul_f32 v[106:107], v[62:63], v[54:55] op_sel:[0,0] op_sel_hi:[0,1]
	v_pk_fma_f32 v[62:63], v[62:63], v[54:55], v[106:107] op_sel:[1,1,0] op_sel_hi:[1,0,1] neg_lo:[0,1,0]
	v_pk_mul_f32 v[106:107], v[112:113], v[62:63] op_sel:[0,0] op_sel_hi:[0,1]
	v_pk_fma_f32 v[106:107], v[112:113], v[62:63], v[106:107] op_sel:[1,1,0] op_sel_hi:[1,0,1] neg_lo:[0,1,0]
	ds_write_b64 v132, v[106:107] offset:6528
	v_pk_mul_f32 v[106:107], v[62:63], v[54:55] op_sel:[0,0] op_sel_hi:[0,1]
	v_pk_fma_f32 v[62:63], v[62:63], v[54:55], v[106:107] op_sel:[1,1,0] op_sel_hi:[1,0,1] neg_lo:[0,1,0]
	v_pk_mul_f32 v[106:107], v[114:115], v[62:63] op_sel:[0,0] op_sel_hi:[0,1]
	v_pk_fma_f32 v[106:107], v[114:115], v[62:63], v[106:107] op_sel:[1,1,0] op_sel_hi:[1,0,1] neg_lo:[0,1,0]
	ds_write_b64 v132, v[106:107] offset:8704
	v_pk_mul_f32 v[106:107], v[62:63], v[54:55] op_sel:[0,0] op_sel_hi:[0,1]
	v_pk_fma_f32 v[62:63], v[62:63], v[54:55], v[106:107] op_sel:[1,1,0] op_sel_hi:[1,0,1] neg_lo:[0,1,0]
	v_pk_mul_f32 v[106:107], v[100:101], v[62:63] op_sel:[0,0] op_sel_hi:[0,1]
	v_pk_fma_f32 v[100:101], v[100:101], v[62:63], v[106:107] op_sel:[1,1,0] op_sel_hi:[1,0,1] neg_lo:[0,1,0]
	ds_write_b64 v132, v[100:101] offset:10880
	v_pk_mul_f32 v[100:101], v[62:63], v[54:55] op_sel:[0,0] op_sel_hi:[0,1]
	v_pk_fma_f32 v[62:63], v[62:63], v[54:55], v[100:101] op_sel:[1,1,0] op_sel_hi:[1,0,1] neg_lo:[0,1,0]
	v_pk_mul_f32 v[100:101], v[104:105], v[62:63] op_sel:[0,0] op_sel_hi:[0,1]
	v_pk_fma_f32 v[100:101], v[104:105], v[62:63], v[100:101] op_sel:[1,1,0] op_sel_hi:[1,0,1] neg_lo:[0,1,0]
	ds_write_b64 v132, v[100:101] offset:13056
	v_pk_mul_f32 v[100:101], v[62:63], v[54:55] op_sel:[0,0] op_sel_hi:[0,1]
	v_pk_fma_f32 v[62:63], v[62:63], v[54:55], v[100:101] op_sel:[1,1,0] op_sel_hi:[1,0,1] neg_lo:[0,1,0]
	v_pk_mul_f32 v[100:101], v[102:103], v[62:63] op_sel:[0,0] op_sel_hi:[0,1]
	v_pk_fma_f32 v[100:101], v[102:103], v[62:63], v[100:101] op_sel:[1,1,0] op_sel_hi:[1,0,1] neg_lo:[0,1,0]
	ds_write_b64 v132, v[100:101] offset:15232
	v_pk_mul_f32 v[100:101], v[62:63], v[54:55] op_sel:[0,0] op_sel_hi:[0,1]
	v_pk_fma_f32 v[62:63], v[62:63], v[54:55], v[100:101] op_sel:[1,1,0] op_sel_hi:[1,0,1] neg_lo:[0,1,0]
	v_pk_mul_f32 v[100:101], v[66:67], v[62:63] op_sel:[0,0] op_sel_hi:[0,1]
	v_pk_fma_f32 v[66:67], v[66:67], v[62:63], v[100:101] op_sel:[1,1,0] op_sel_hi:[1,0,1] neg_lo:[0,1,0]
	ds_write_b64 v132, v[66:67] offset:17408
	v_pk_mul_f32 v[66:67], v[62:63], v[54:55] op_sel:[0,0] op_sel_hi:[0,1]
	v_pk_fma_f32 v[62:63], v[62:63], v[54:55], v[66:67] op_sel:[1,1,0] op_sel_hi:[1,0,1] neg_lo:[0,1,0]
	v_pk_mul_f32 v[66:67], v[64:65], v[62:63] op_sel:[0,0] op_sel_hi:[0,1]
	v_pk_fma_f32 v[64:65], v[64:65], v[62:63], v[66:67] op_sel:[1,1,0] op_sel_hi:[1,0,1] neg_lo:[0,1,0]
	ds_write_b64 v132, v[64:65] offset:19584
	v_pk_mul_f32 v[64:65], v[62:63], v[54:55] op_sel:[0,0] op_sel_hi:[0,1]
	v_pk_fma_f32 v[62:63], v[62:63], v[54:55], v[64:65] op_sel:[1,1,0] op_sel_hi:[1,0,1] neg_lo:[0,1,0]
	v_pk_mul_f32 v[64:65], v[60:61], v[62:63] op_sel:[0,0] op_sel_hi:[0,1]
	v_pk_fma_f32 v[60:61], v[60:61], v[62:63], v[64:65] op_sel:[1,1,0] op_sel_hi:[1,0,1] neg_lo:[0,1,0]
	ds_write_b64 v132, v[60:61] offset:21760
	v_pk_mul_f32 v[60:61], v[62:63], v[54:55] op_sel:[0,0] op_sel_hi:[0,1]
	v_pk_fma_f32 v[60:61], v[62:63], v[54:55], v[60:61] op_sel:[1,1,0] op_sel_hi:[1,0,1] neg_lo:[0,1,0]
	v_pk_mul_f32 v[62:63], v[98:99], v[60:61] op_sel:[0,0] op_sel_hi:[0,1]
	v_pk_fma_f32 v[62:63], v[98:99], v[60:61], v[62:63] op_sel:[1,1,0] op_sel_hi:[1,0,1] neg_lo:[0,1,0]
	ds_write_b64 v132, v[62:63] offset:23936
	v_pk_mul_f32 v[62:63], v[60:61], v[54:55] op_sel:[0,0] op_sel_hi:[0,1]
	v_pk_fma_f32 v[60:61], v[60:61], v[54:55], v[62:63] op_sel:[1,1,0] op_sel_hi:[1,0,1] neg_lo:[0,1,0]
	v_pk_mul_f32 v[62:63], v[58:59], v[60:61] op_sel:[0,0] op_sel_hi:[0,1]
	v_pk_fma_f32 v[58:59], v[58:59], v[60:61], v[62:63] op_sel:[1,1,0] op_sel_hi:[1,0,1] neg_lo:[0,1,0]
	ds_write_b64 v132, v[58:59] offset:26112
	v_pk_mul_f32 v[58:59], v[60:61], v[54:55] op_sel:[0,0] op_sel_hi:[0,1]
	v_pk_fma_f32 v[58:59], v[60:61], v[54:55], v[58:59] op_sel:[1,1,0] op_sel_hi:[1,0,1] neg_lo:[0,1,0]
	v_pk_mul_f32 v[60:61], v[68:69], v[58:59] op_sel:[0,0] op_sel_hi:[0,1]
	v_pk_fma_f32 v[60:61], v[68:69], v[58:59], v[60:61] op_sel:[1,1,0] op_sel_hi:[1,0,1] neg_lo:[0,1,0]
	ds_write_b64 v132, v[60:61] offset:28288
	v_pk_mul_f32 v[60:61], v[58:59], v[54:55] op_sel:[0,0] op_sel_hi:[0,1]
	v_pk_fma_f32 v[58:59], v[58:59], v[54:55], v[60:61] op_sel:[1,1,0] op_sel_hi:[1,0,1] neg_lo:[0,1,0]
	v_pk_mul_f32 v[60:61], v[56:57], v[58:59] op_sel:[0,0] op_sel_hi:[0,1]
	v_pk_fma_f32 v[56:57], v[56:57], v[58:59], v[60:61] op_sel:[1,1,0] op_sel_hi:[1,0,1] neg_lo:[0,1,0]
	ds_write_b64 v132, v[56:57] offset:30464
	v_pk_mul_f32 v[56:57], v[58:59], v[54:55] op_sel:[0,0] op_sel_hi:[0,1]
	v_pk_fma_f32 v[54:55], v[58:59], v[54:55], v[56:57] op_sel:[1,1,0] op_sel_hi:[1,0,1] neg_lo:[0,1,0]
	v_pk_mul_f32 v[56:57], v[52:53], v[54:55] op_sel:[0,0] op_sel_hi:[0,1]
	v_pk_fma_f32 v[52:53], v[52:53], v[54:55], v[56:57] op_sel:[1,1,0] op_sel_hi:[1,0,1] neg_lo:[0,1,0]
	ds_write_b64 v132, v[52:53] offset:32640
	s_waitcnt lgkmcnt(0)
	s_barrier
	ds_read2_b64 v[52:55], v134 offset1:17
	ds_read2_b64 v[56:59], v134 offset0:34 offset1:51
	ds_read2_b64 v[60:63], v134 offset0:68 offset1:85
	ds_read2_b64 v[64:67], v134 offset0:136 offset1:153
	ds_read2_b64 v[98:101], v134 offset0:102 offset1:119
	ds_read2_b64 v[102:105], v134 offset0:204 offset1:221
	ds_read2_b64 v[110:113], v134 offset0:170 offset1:187
	ds_read2_b64 v[114:117], v134 offset0:238 offset1:255
	s_waitcnt lgkmcnt(4)
	v_pk_add_f32 v[68:69], v[52:53], v[64:65]
	v_pk_add_f32 v[52:53], v[52:53], v[64:65] neg_lo:[0,1] neg_hi:[0,1]
	s_waitcnt lgkmcnt(2)
	v_pk_add_f32 v[64:65], v[60:61], v[102:103]
	v_pk_add_f32 v[60:61], v[60:61], v[102:103] neg_lo:[0,1] neg_hi:[0,1]
	v_pk_add_f32 v[102:103], v[68:69], v[64:65]
	v_pk_add_f32 v[64:65], v[68:69], v[64:65] neg_lo:[0,1] neg_hi:[0,1]
	v_pk_add_f32 v[68:69], v[52:53], v[60:61] op_sel:[0,1] op_sel_hi:[1,0] neg_hi:[0,1]
	v_pk_add_f32 v[52:53], v[52:53], v[60:61] op_sel:[0,1] op_sel_hi:[1,0] neg_lo:[0,1]
	v_pk_add_f32 v[60:61], v[54:55], v[66:67]
	v_pk_add_f32 v[54:55], v[54:55], v[66:67] neg_lo:[0,1] neg_hi:[0,1]
	v_pk_add_f32 v[66:67], v[62:63], v[104:105]
	v_pk_add_f32 v[62:63], v[62:63], v[104:105] neg_lo:[0,1] neg_hi:[0,1]
	v_pk_add_f32 v[104:105], v[60:61], v[66:67]
	v_pk_add_f32 v[60:61], v[60:61], v[66:67] neg_lo:[0,1] neg_hi:[0,1]
	v_pk_add_f32 v[66:67], v[54:55], v[62:63] op_sel:[0,1] op_sel_hi:[1,0] neg_hi:[0,1]
	v_pk_add_f32 v[54:55], v[54:55], v[62:63] op_sel:[0,1] op_sel_hi:[1,0] neg_lo:[0,1]
	s_waitcnt lgkmcnt(1)
	v_pk_add_f32 v[62:63], v[56:57], v[110:111]
	v_pk_add_f32 v[56:57], v[56:57], v[110:111] neg_lo:[0,1] neg_hi:[0,1]
	s_waitcnt lgkmcnt(0)
	v_pk_add_f32 v[106:107], v[98:99], v[114:115]
	v_pk_add_f32 v[98:99], v[98:99], v[114:115] neg_lo:[0,1] neg_hi:[0,1]
	v_pk_add_f32 v[110:111], v[62:63], v[106:107]
	v_pk_add_f32 v[62:63], v[62:63], v[106:107] neg_lo:[0,1] neg_hi:[0,1]
	v_pk_add_f32 v[106:107], v[56:57], v[98:99] op_sel:[0,1] op_sel_hi:[1,0] neg_hi:[0,1]
	v_pk_add_f32 v[56:57], v[56:57], v[98:99] op_sel:[0,1] op_sel_hi:[1,0] neg_lo:[0,1]
	v_pk_add_f32 v[98:99], v[58:59], v[112:113]
	v_pk_add_f32 v[58:59], v[58:59], v[112:113] neg_lo:[0,1] neg_hi:[0,1]
	v_pk_add_f32 v[112:113], v[100:101], v[116:117]
	v_pk_add_f32 v[100:101], v[100:101], v[116:117] neg_lo:[0,1] neg_hi:[0,1]
	v_pk_add_f32 v[114:115], v[98:99], v[112:113]
	v_pk_add_f32 v[98:99], v[98:99], v[112:113] neg_lo:[0,1] neg_hi:[0,1]
	v_pk_add_f32 v[112:113], v[58:59], v[100:101] op_sel:[0,1] op_sel_hi:[1,0] neg_hi:[0,1]
	v_pk_add_f32 v[58:59], v[58:59], v[100:101] op_sel:[0,1] op_sel_hi:[1,0] neg_lo:[0,1]
	v_pk_mul_f32 v[100:101], v[66:67], s[20:21] op_sel:[0,0] op_sel_hi:[0,1]
	v_pk_fma_f32 v[66:67], v[66:67], s[20:21], v[100:101] op_sel:[1,1,0] op_sel_hi:[1,0,1] neg_lo:[0,1,0]
	v_pk_mul_f32 v[100:101], v[106:107], s[46:47] op_sel:[0,0] op_sel_hi:[0,1]
	v_pk_fma_f32 v[100:101], v[106:107], s[46:47], v[100:101] op_sel:[1,1,0] op_sel_hi:[1,0,1] neg_lo:[0,1,0]
	v_pk_mul_f32 v[106:107], v[112:113], v[26:27] op_sel:[0,0] op_sel_hi:[0,1]
	v_pk_fma_f32 v[106:107], v[112:113], v[26:27], v[106:107] op_sel:[1,1,0] op_sel_hi:[1,0,1] neg_lo:[0,1,0]
	v_pk_mul_f32 v[112:113], v[60:61], s[46:47] op_sel:[0,0] op_sel_hi:[0,1]
	v_pk_fma_f32 v[60:61], v[60:61], s[46:47], v[112:113] op_sel:[1,1,0] op_sel_hi:[1,0,1] neg_lo:[0,1,0]
	v_pk_mul_f32 v[112:113], v[62:63], v[48:49] op_sel:[0,0] op_sel_hi:[0,1]
	v_pk_fma_f32 v[62:63], v[62:63], v[48:49], v[112:113] op_sel:[1,1,0] op_sel_hi:[1,0,1] neg_lo:[0,1,0]
	v_pk_mul_f32 v[112:113], v[98:99], v[44:45] op_sel:[0,0] op_sel_hi:[0,1]
	v_pk_fma_f32 v[98:99], v[98:99], v[44:45], v[112:113] op_sel:[1,1,0] op_sel_hi:[1,0,1] neg_lo:[0,1,0]
	v_pk_mul_f32 v[112:113], v[54:55], v[26:27] op_sel:[0,0] op_sel_hi:[0,1]
	v_pk_fma_f32 v[54:55], v[54:55], v[26:27], v[112:113] op_sel:[1,1,0] op_sel_hi:[1,0,1] neg_lo:[0,1,0]
	v_pk_mul_f32 v[112:113], v[56:57], v[44:45] op_sel:[0,0] op_sel_hi:[0,1]
	v_pk_fma_f32 v[56:57], v[56:57], v[44:45], v[112:113] op_sel:[1,1,0] op_sel_hi:[1,0,1] neg_lo:[0,1,0]
	v_pk_mul_f32 v[112:113], v[58:59], s[56:57] op_sel:[0,0] op_sel_hi:[0,1]
	v_pk_fma_f32 v[58:59], v[58:59], s[56:57], v[112:113] op_sel:[1,1,0] op_sel_hi:[1,0,1] neg_lo:[0,1,0]
	v_pk_add_f32 v[112:113], v[102:103], v[110:111]
	v_pk_add_f32 v[102:103], v[102:103], v[110:111] neg_lo:[0,1] neg_hi:[0,1]
	v_pk_add_f32 v[110:111], v[104:105], v[114:115]
	v_pk_add_f32 v[104:105], v[104:105], v[114:115] neg_lo:[0,1] neg_hi:[0,1]
	v_pk_add_f32 v[114:115], v[112:113], v[110:111]
	v_pk_add_f32 v[110:111], v[112:113], v[110:111] neg_lo:[0,1] neg_hi:[0,1]
	v_pk_add_f32 v[112:113], v[102:103], v[104:105] op_sel:[0,1] op_sel_hi:[1,0] neg_hi:[0,1]
	v_pk_add_f32 v[102:103], v[102:103], v[104:105] op_sel:[0,1] op_sel_hi:[1,0] neg_lo:[0,1]
	v_pk_add_f32 v[104:105], v[68:69], v[100:101]
	v_pk_add_f32 v[68:69], v[68:69], v[100:101] neg_lo:[0,1] neg_hi:[0,1]
	v_pk_add_f32 v[100:101], v[66:67], v[106:107]
	v_pk_add_f32 v[66:67], v[66:67], v[106:107] neg_lo:[0,1] neg_hi:[0,1]
	v_pk_add_f32 v[106:107], v[104:105], v[100:101]
	v_pk_add_f32 v[100:101], v[104:105], v[100:101] neg_lo:[0,1] neg_hi:[0,1]
	v_pk_add_f32 v[104:105], v[68:69], v[66:67] op_sel:[0,1] op_sel_hi:[1,0] neg_hi:[0,1]
	v_pk_add_f32 v[66:67], v[68:69], v[66:67] op_sel:[0,1] op_sel_hi:[1,0] neg_lo:[0,1]
	v_pk_add_f32 v[68:69], v[64:65], v[62:63]
	v_pk_add_f32 v[62:63], v[64:65], v[62:63] neg_lo:[0,1] neg_hi:[0,1]
	v_pk_add_f32 v[64:65], v[60:61], v[98:99]
	v_pk_add_f32 v[60:61], v[60:61], v[98:99] neg_lo:[0,1] neg_hi:[0,1]
	v_pk_add_f32 v[98:99], v[68:69], v[64:65]
	v_pk_add_f32 v[64:65], v[68:69], v[64:65] neg_lo:[0,1] neg_hi:[0,1]
	v_pk_add_f32 v[68:69], v[62:63], v[60:61] op_sel:[0,1] op_sel_hi:[1,0] neg_hi:[0,1]
	v_pk_add_f32 v[60:61], v[62:63], v[60:61] op_sel:[0,1] op_sel_hi:[1,0] neg_lo:[0,1]
	v_pk_add_f32 v[62:63], v[52:53], v[56:57]
	v_pk_add_f32 v[52:53], v[52:53], v[56:57] neg_lo:[0,1] neg_hi:[0,1]
	v_pk_add_f32 v[56:57], v[54:55], v[58:59]
	v_pk_add_f32 v[54:55], v[54:55], v[58:59] neg_lo:[0,1] neg_hi:[0,1]
	v_pk_add_f32 v[58:59], v[62:63], v[56:57]
	v_pk_add_f32 v[56:57], v[62:63], v[56:57] neg_lo:[0,1] neg_hi:[0,1]
	v_pk_add_f32 v[62:63], v[52:53], v[54:55] op_sel:[0,1] op_sel_hi:[1,0] neg_hi:[0,1]
	v_pk_add_f32 v[52:53], v[52:53], v[54:55] op_sel:[0,1] op_sel_hi:[1,0] neg_lo:[0,1]
	v_mov_b32_e32 v55, v41
	v_mov_b32_e32 v54, v40
	s_nop 0
	v_pk_mul_f32 v[116:117], v[106:107], v[54:55] op_sel:[0,0] op_sel_hi:[0,1]
	v_pk_fma_f32 v[106:107], v[106:107], v[54:55], v[116:117] op_sel:[1,1,0] op_sel_hi:[1,0,1] neg_lo:[0,1,0]
	ds_write2_b64 v134, v[114:115], v[106:107] offset1:17
	v_pk_mul_f32 v[106:107], v[54:55], v[54:55] op_sel:[0,0] op_sel_hi:[0,1]
	v_pk_fma_f32 v[106:107], v[54:55], v[54:55], v[106:107] op_sel:[1,1,0] op_sel_hi:[1,0,1] neg_lo:[0,1,0]
	v_pk_mul_f32 v[114:115], v[98:99], v[106:107] op_sel:[0,0] op_sel_hi:[0,1]
	v_pk_fma_f32 v[98:99], v[98:99], v[106:107], v[114:115] op_sel:[1,1,0] op_sel_hi:[1,0,1] neg_lo:[0,1,0]
	v_pk_mul_f32 v[114:115], v[106:107], v[54:55] op_sel:[0,0] op_sel_hi:[0,1]
	v_pk_fma_f32 v[106:107], v[106:107], v[54:55], v[114:115] op_sel:[1,1,0] op_sel_hi:[1,0,1] neg_lo:[0,1,0]
	v_pk_mul_f32 v[114:115], v[58:59], v[106:107] op_sel:[0,0] op_sel_hi:[0,1]
	v_pk_fma_f32 v[58:59], v[58:59], v[106:107], v[114:115] op_sel:[1,1,0] op_sel_hi:[1,0,1] neg_lo:[0,1,0]
	ds_write2_b64 v134, v[98:99], v[58:59] offset0:34 offset1:51
	v_pk_mul_f32 v[58:59], v[106:107], v[54:55] op_sel:[0,0] op_sel_hi:[0,1]
	v_pk_fma_f32 v[58:59], v[106:107], v[54:55], v[58:59] op_sel:[1,1,0] op_sel_hi:[1,0,1] neg_lo:[0,1,0]
	v_pk_mul_f32 v[98:99], v[112:113], v[58:59] op_sel:[0,0] op_sel_hi:[0,1]
	v_pk_mul_f32 v[106:107], v[58:59], v[54:55] op_sel:[0,0] op_sel_hi:[0,1]
	v_pk_fma_f32 v[98:99], v[112:113], v[58:59], v[98:99] op_sel:[1,1,0] op_sel_hi:[1,0,1] neg_lo:[0,1,0]
	v_pk_fma_f32 v[58:59], v[58:59], v[54:55], v[106:107] op_sel:[1,1,0] op_sel_hi:[1,0,1] neg_lo:[0,1,0]
	v_pk_mul_f32 v[106:107], v[104:105], v[58:59] op_sel:[0,0] op_sel_hi:[0,1]
	v_pk_fma_f32 v[104:105], v[104:105], v[58:59], v[106:107] op_sel:[1,1,0] op_sel_hi:[1,0,1] neg_lo:[0,1,0]
	ds_write2_b64 v134, v[98:99], v[104:105] offset0:68 offset1:85
	v_pk_mul_f32 v[98:99], v[58:59], v[54:55] op_sel:[0,0] op_sel_hi:[0,1]
	v_pk_fma_f32 v[58:59], v[58:59], v[54:55], v[98:99] op_sel:[1,1,0] op_sel_hi:[1,0,1] neg_lo:[0,1,0]
	v_pk_mul_f32 v[98:99], v[68:69], v[58:59] op_sel:[0,0] op_sel_hi:[0,1]
	v_pk_fma_f32 v[68:69], v[68:69], v[58:59], v[98:99] op_sel:[1,1,0] op_sel_hi:[1,0,1] neg_lo:[0,1,0]
	v_pk_mul_f32 v[98:99], v[58:59], v[54:55] op_sel:[0,0] op_sel_hi:[0,1]
	v_pk_fma_f32 v[58:59], v[58:59], v[54:55], v[98:99] op_sel:[1,1,0] op_sel_hi:[1,0,1] neg_lo:[0,1,0]
	v_pk_mul_f32 v[98:99], v[62:63], v[58:59] op_sel:[0,0] op_sel_hi:[0,1]
	v_pk_fma_f32 v[62:63], v[62:63], v[58:59], v[98:99] op_sel:[1,1,0] op_sel_hi:[1,0,1] neg_lo:[0,1,0]
	ds_write2_b64 v134, v[68:69], v[62:63] offset0:102 offset1:119
	v_pk_mul_f32 v[62:63], v[58:59], v[54:55] op_sel:[0,0] op_sel_hi:[0,1]
	v_pk_fma_f32 v[58:59], v[58:59], v[54:55], v[62:63] op_sel:[1,1,0] op_sel_hi:[1,0,1] neg_lo:[0,1,0]
	v_pk_mul_f32 v[62:63], v[110:111], v[58:59] op_sel:[0,0] op_sel_hi:[0,1]
	v_pk_mul_f32 v[68:69], v[58:59], v[54:55] op_sel:[0,0] op_sel_hi:[0,1]
	v_pk_fma_f32 v[62:63], v[110:111], v[58:59], v[62:63] op_sel:[1,1,0] op_sel_hi:[1,0,1] neg_lo:[0,1,0]
	v_pk_fma_f32 v[58:59], v[58:59], v[54:55], v[68:69] op_sel:[1,1,0] op_sel_hi:[1,0,1] neg_lo:[0,1,0]
	v_pk_mul_f32 v[68:69], v[100:101], v[58:59] op_sel:[0,0] op_sel_hi:[0,1]
	v_pk_fma_f32 v[68:69], v[100:101], v[58:59], v[68:69] op_sel:[1,1,0] op_sel_hi:[1,0,1] neg_lo:[0,1,0]
	ds_write2_b64 v134, v[62:63], v[68:69] offset0:136 offset1:153
	v_pk_mul_f32 v[62:63], v[58:59], v[54:55] op_sel:[0,0] op_sel_hi:[0,1]
	v_pk_fma_f32 v[58:59], v[58:59], v[54:55], v[62:63] op_sel:[1,1,0] op_sel_hi:[1,0,1] neg_lo:[0,1,0]
	v_pk_mul_f32 v[62:63], v[64:65], v[58:59] op_sel:[0,0] op_sel_hi:[0,1]
	v_pk_fma_f32 v[62:63], v[64:65], v[58:59], v[62:63] op_sel:[1,1,0] op_sel_hi:[1,0,1] neg_lo:[0,1,0]
	v_pk_mul_f32 v[64:65], v[58:59], v[54:55] op_sel:[0,0] op_sel_hi:[0,1]
	v_pk_fma_f32 v[58:59], v[58:59], v[54:55], v[64:65] op_sel:[1,1,0] op_sel_hi:[1,0,1] neg_lo:[0,1,0]
	v_pk_mul_f32 v[64:65], v[56:57], v[58:59] op_sel:[0,0] op_sel_hi:[0,1]
	v_pk_fma_f32 v[56:57], v[56:57], v[58:59], v[64:65] op_sel:[1,1,0] op_sel_hi:[1,0,1] neg_lo:[0,1,0]
	ds_write2_b64 v134, v[62:63], v[56:57] offset0:170 offset1:187
	v_pk_mul_f32 v[56:57], v[58:59], v[54:55] op_sel:[0,0] op_sel_hi:[0,1]
	v_pk_fma_f32 v[56:57], v[58:59], v[54:55], v[56:57] op_sel:[1,1,0] op_sel_hi:[1,0,1] neg_lo:[0,1,0]
	v_pk_mul_f32 v[58:59], v[102:103], v[56:57] op_sel:[0,0] op_sel_hi:[0,1]
	v_pk_mul_f32 v[62:63], v[56:57], v[54:55] op_sel:[0,0] op_sel_hi:[0,1]
	v_pk_fma_f32 v[58:59], v[102:103], v[56:57], v[58:59] op_sel:[1,1,0] op_sel_hi:[1,0,1] neg_lo:[0,1,0]
	v_pk_fma_f32 v[56:57], v[56:57], v[54:55], v[62:63] op_sel:[1,1,0] op_sel_hi:[1,0,1] neg_lo:[0,1,0]
	v_pk_mul_f32 v[62:63], v[66:67], v[56:57] op_sel:[0,0] op_sel_hi:[0,1]
	v_pk_fma_f32 v[62:63], v[66:67], v[56:57], v[62:63] op_sel:[1,1,0] op_sel_hi:[1,0,1] neg_lo:[0,1,0]
	ds_write2_b64 v134, v[58:59], v[62:63] offset0:204 offset1:221
	v_pk_mul_f32 v[58:59], v[56:57], v[54:55] op_sel:[0,0] op_sel_hi:[0,1]
	v_pk_fma_f32 v[56:57], v[56:57], v[54:55], v[58:59] op_sel:[1,1,0] op_sel_hi:[1,0,1] neg_lo:[0,1,0]
	v_pk_mul_f32 v[58:59], v[60:61], v[56:57] op_sel:[0,0] op_sel_hi:[0,1]
	v_pk_fma_f32 v[58:59], v[60:61], v[56:57], v[58:59] op_sel:[1,1,0] op_sel_hi:[1,0,1] neg_lo:[0,1,0]
	v_pk_mul_f32 v[60:61], v[56:57], v[54:55] op_sel:[0,0] op_sel_hi:[0,1]
	v_pk_fma_f32 v[54:55], v[56:57], v[54:55], v[60:61] op_sel:[1,1,0] op_sel_hi:[1,0,1] neg_lo:[0,1,0]
	v_pk_mul_f32 v[56:57], v[52:53], v[54:55] op_sel:[0,0] op_sel_hi:[0,1]
	v_pk_fma_f32 v[52:53], v[52:53], v[54:55], v[56:57] op_sel:[1,1,0] op_sel_hi:[1,0,1] neg_lo:[0,1,0]
	ds_write2_b64 v134, v[58:59], v[52:53] offset0:238 offset1:255
	s_waitcnt lgkmcnt(0)
	s_barrier
	ds_read2_b64 v[52:55], v135 offset1:1
	ds_read2_b64 v[56:59], v135 offset0:2 offset1:3
	ds_read2_b64 v[60:63], v135 offset0:8 offset1:9
	ds_read2_b64 v[64:67], v135 offset0:4 offset1:5
	ds_read2_b64 v[98:101], v135 offset0:6 offset1:7
	ds_read2_b64 v[102:105], v135 offset0:12 offset1:13
	ds_read2_b64 v[110:113], v135 offset0:10 offset1:11
	ds_read2_b64 v[114:117], v135 offset0:14 offset1:15
	s_waitcnt lgkmcnt(5)
	v_pk_add_f32 v[68:69], v[52:53], v[60:61]
	v_pk_add_f32 v[52:53], v[52:53], v[60:61] neg_lo:[0,1] neg_hi:[0,1]
	s_waitcnt lgkmcnt(2)
	v_pk_add_f32 v[60:61], v[64:65], v[102:103]
	v_pk_add_f32 v[64:65], v[64:65], v[102:103] neg_lo:[0,1] neg_hi:[0,1]
	v_pk_add_f32 v[102:103], v[68:69], v[60:61]
	v_pk_add_f32 v[60:61], v[68:69], v[60:61] neg_lo:[0,1] neg_hi:[0,1]
	v_pk_add_f32 v[68:69], v[52:53], v[64:65] op_sel:[0,1] op_sel_hi:[1,0] neg_hi:[0,1]
	v_pk_add_f32 v[52:53], v[52:53], v[64:65] op_sel:[0,1] op_sel_hi:[1,0] neg_lo:[0,1]
	v_pk_add_f32 v[64:65], v[54:55], v[62:63]
	v_pk_add_f32 v[54:55], v[54:55], v[62:63] neg_lo:[0,1] neg_hi:[0,1]
	v_pk_add_f32 v[62:63], v[66:67], v[104:105]
	v_pk_add_f32 v[66:67], v[66:67], v[104:105] neg_lo:[0,1] neg_hi:[0,1]
	v_pk_add_f32 v[104:105], v[64:65], v[62:63]
	v_pk_add_f32 v[62:63], v[64:65], v[62:63] neg_lo:[0,1] neg_hi:[0,1]
	v_pk_add_f32 v[64:65], v[54:55], v[66:67] op_sel:[0,1] op_sel_hi:[1,0] neg_hi:[0,1]
	v_pk_add_f32 v[54:55], v[54:55], v[66:67] op_sel:[0,1] op_sel_hi:[1,0] neg_lo:[0,1]
	s_waitcnt lgkmcnt(1)
	v_pk_add_f32 v[66:67], v[56:57], v[110:111]
	v_pk_add_f32 v[56:57], v[56:57], v[110:111] neg_lo:[0,1] neg_hi:[0,1]
	s_waitcnt lgkmcnt(0)
	v_pk_add_f32 v[106:107], v[98:99], v[114:115]
	v_pk_add_f32 v[98:99], v[98:99], v[114:115] neg_lo:[0,1] neg_hi:[0,1]
	v_pk_add_f32 v[110:111], v[66:67], v[106:107]
	v_pk_add_f32 v[66:67], v[66:67], v[106:107] neg_lo:[0,1] neg_hi:[0,1]
	v_pk_add_f32 v[106:107], v[56:57], v[98:99] op_sel:[0,1] op_sel_hi:[1,0] neg_hi:[0,1]
	v_pk_add_f32 v[56:57], v[56:57], v[98:99] op_sel:[0,1] op_sel_hi:[1,0] neg_lo:[0,1]
	v_pk_add_f32 v[98:99], v[58:59], v[112:113]
	v_pk_add_f32 v[58:59], v[58:59], v[112:113] neg_lo:[0,1] neg_hi:[0,1]
	v_pk_add_f32 v[112:113], v[100:101], v[116:117]
	v_pk_add_f32 v[100:101], v[100:101], v[116:117] neg_lo:[0,1] neg_hi:[0,1]
	v_pk_add_f32 v[114:115], v[98:99], v[112:113]
	v_pk_add_f32 v[98:99], v[98:99], v[112:113] neg_lo:[0,1] neg_hi:[0,1]
	v_pk_add_f32 v[112:113], v[58:59], v[100:101] op_sel:[0,1] op_sel_hi:[1,0] neg_hi:[0,1]
	v_pk_add_f32 v[58:59], v[58:59], v[100:101] op_sel:[0,1] op_sel_hi:[1,0] neg_lo:[0,1]
	v_pk_mul_f32 v[100:101], v[64:65], s[20:21] op_sel:[0,0] op_sel_hi:[0,1]
	v_pk_fma_f32 v[46:47], v[64:65], s[20:21], v[100:101] op_sel:[1,1,0] op_sel_hi:[1,0,1] neg_lo:[0,1,0]
	v_pk_mul_f32 v[64:65], v[106:107], s[46:47] op_sel:[0,0] op_sel_hi:[0,1]
	v_pk_mul_f32 v[100:101], v[112:113], v[26:27] op_sel:[0,0] op_sel_hi:[0,1]
	v_pk_fma_f32 v[64:65], v[106:107], s[46:47], v[64:65] op_sel:[1,1,0] op_sel_hi:[1,0,1] neg_lo:[0,1,0]
	v_pk_mul_f32 v[106:107], v[62:63], s[46:47] op_sel:[0,0] op_sel_hi:[0,1]
	v_pk_fma_f32 v[100:101], v[112:113], v[26:27], v[100:101] op_sel:[1,1,0] op_sel_hi:[1,0,1] neg_lo:[0,1,0]
	v_pk_fma_f32 v[42:43], v[62:63], s[46:47], v[106:107] op_sel:[1,1,0] op_sel_hi:[1,0,1] neg_lo:[0,1,0]
	v_pk_mul_f32 v[62:63], v[66:67], v[48:49] op_sel:[0,0] op_sel_hi:[0,1]
	v_pk_fma_f32 v[48:49], v[66:67], v[48:49], v[62:63] op_sel:[1,1,0] op_sel_hi:[1,0,1] neg_lo:[0,1,0]
	v_pk_mul_f32 v[62:63], v[98:99], v[44:45] op_sel:[0,0] op_sel_hi:[0,1]
	v_pk_mul_f32 v[66:67], v[54:55], v[26:27] op_sel:[0,0] op_sel_hi:[0,1]
	v_pk_fma_f32 v[26:27], v[54:55], v[26:27], v[66:67] op_sel:[1,1,0] op_sel_hi:[1,0,1] neg_lo:[0,1,0]
	v_pk_mul_f32 v[54:55], v[56:57], v[44:45] op_sel:[0,0] op_sel_hi:[0,1]
	v_pk_fma_f32 v[62:63], v[98:99], v[44:45], v[62:63] op_sel:[1,1,0] op_sel_hi:[1,0,1] neg_lo:[0,1,0]
	v_pk_add_f32 v[66:67], v[104:105], v[114:115] neg_lo:[0,1] neg_hi:[0,1]
	v_pk_fma_f32 v[44:45], v[56:57], v[44:45], v[54:55] op_sel:[1,1,0] op_sel_hi:[1,0,1] neg_lo:[0,1,0]
	v_pk_mul_f32 v[54:55], v[58:59], s[56:57] op_sel:[0,0] op_sel_hi:[0,1]
	v_pk_add_f32 v[56:57], v[102:103], v[110:111] neg_lo:[0,1] neg_hi:[0,1]
	v_pk_fma_f32 v[50:51], v[58:59], s[56:57], v[54:55] op_sel:[1,1,0] op_sel_hi:[1,0,1] neg_lo:[0,1,0]
	v_pk_add_f32 v[54:55], v[102:103], v[110:111]
	v_pk_add_f32 v[58:59], v[104:105], v[114:115]
	s_nop 0
	v_pk_add_f32 v[98:99], v[54:55], v[58:59]
	v_pk_add_f32 v[54:55], v[54:55], v[58:59] neg_lo:[0,1] neg_hi:[0,1]
	v_pk_add_f32 v[58:59], v[56:57], v[66:67] op_sel:[0,1] op_sel_hi:[1,0] neg_hi:[0,1]
	v_pk_add_f32 v[56:57], v[56:57], v[66:67] op_sel:[0,1] op_sel_hi:[1,0] neg_lo:[0,1]
	v_pk_add_f32 v[66:67], v[68:69], v[64:65]
	v_pk_add_f32 v[64:65], v[68:69], v[64:65] neg_lo:[0,1] neg_hi:[0,1]
	v_pk_add_f32 v[68:69], v[46:47], v[100:101]
	v_pk_add_f32 v[46:47], v[46:47], v[100:101] neg_lo:[0,1] neg_hi:[0,1]
	v_pk_add_f32 v[100:101], v[66:67], v[68:69]
	v_pk_add_f32 v[66:67], v[66:67], v[68:69] neg_lo:[0,1] neg_hi:[0,1]
	v_pk_add_f32 v[68:69], v[64:65], v[46:47] op_sel:[0,1] op_sel_hi:[1,0] neg_hi:[0,1]
	v_pk_add_f32 v[46:47], v[64:65], v[46:47] op_sel:[0,1] op_sel_hi:[1,0] neg_lo:[0,1]
	v_pk_add_f32 v[64:65], v[60:61], v[48:49]
	v_pk_add_f32 v[48:49], v[60:61], v[48:49] neg_lo:[0,1] neg_hi:[0,1]
	v_pk_add_f32 v[60:61], v[42:43], v[62:63]
	v_pk_add_f32 v[42:43], v[42:43], v[62:63] neg_lo:[0,1] neg_hi:[0,1]
	v_pk_add_f32 v[62:63], v[64:65], v[60:61]
	v_pk_add_f32 v[60:61], v[64:65], v[60:61] neg_lo:[0,1] neg_hi:[0,1]
	v_pk_add_f32 v[64:65], v[48:49], v[42:43] op_sel:[0,1] op_sel_hi:[1,0] neg_hi:[0,1]
	v_pk_add_f32 v[102:103], v[48:49], v[42:43] op_sel:[0,1] op_sel_hi:[1,0] neg_lo:[0,1]
	v_pk_add_f32 v[42:43], v[52:53], v[44:45]
	v_pk_add_f32 v[48:49], v[26:27], v[50:51]
	v_pk_add_f32 v[44:45], v[52:53], v[44:45] neg_lo:[0,1] neg_hi:[0,1]
	v_pk_add_f32 v[104:105], v[42:43], v[48:49]
	v_pk_add_f32 v[106:107], v[42:43], v[48:49] neg_lo:[0,1] neg_hi:[0,1]
	s_waitcnt vmcnt(14)
	v_pk_mul_f32 v[42:43], v[58:59], v[30:31] op_sel:[0,0] op_sel_hi:[0,1]
	v_pk_add_f32 v[26:27], v[26:27], v[50:51] neg_lo:[0,1] neg_hi:[0,1]
	v_pk_fma_f32 v[30:31], v[58:59], v[30:31], v[42:43] op_sel:[1,1,0] op_sel_hi:[1,0,1] neg_lo:[0,1,0]
	s_waitcnt vmcnt(13)
	v_pk_mul_f32 v[42:43], v[54:55], v[28:29] op_sel:[0,0] op_sel_hi:[0,1]
	s_waitcnt vmcnt(8)
	v_pk_mul_f32 v[50:51], v[46:47], v[76:77] op_sel:[0,0] op_sel_hi:[0,1]
	v_pk_mul_f32 v[48:49], v[66:67], v[72:73] op_sel:[0,0] op_sel_hi:[0,1]
	v_pk_fma_f32 v[42:43], v[54:55], v[28:29], v[42:43] op_sel:[1,1,0] op_sel_hi:[1,0,1] neg_lo:[0,1,0]
	s_waitcnt vmcnt(5)
	v_pk_mul_f32 v[54:55], v[60:61], v[80:81] op_sel:[0,0] op_sel_hi:[0,1]
	v_pk_add_f32 v[110:111], v[44:45], v[26:27] op_sel:[0,1] op_sel_hi:[1,0] neg_hi:[0,1]
	v_pk_add_f32 v[112:113], v[44:45], v[26:27] op_sel:[0,1] op_sel_hi:[1,0] neg_lo:[0,1]
	v_pk_mul_f32 v[28:29], v[56:57], v[32:33] op_sel:[0,0] op_sel_hi:[0,1]
	v_pk_fma_f32 v[52:53], v[46:47], v[76:77], v[50:51] op_sel:[1,1,0] op_sel_hi:[1,0,1] neg_lo:[0,1,0]
	v_pk_mul_f32 v[46:47], v[62:63], v[86:87] op_sel:[0,0] op_sel_hi:[0,1]
	v_pk_mul_f32 v[50:51], v[64:65], v[82:83] op_sel:[0,0] op_sel_hi:[0,1]
	v_pk_mul_f32 v[26:27], v[98:99], v[70:71] op_sel:[0,0] op_sel_hi:[0,1]
	s_waitcnt vmcnt(2)
	v_pk_mul_f32 v[58:59], v[110:111], v[90:91] op_sel:[0,0] op_sel_hi:[0,1]
	v_pk_fma_f32 v[44:45], v[56:57], v[32:33], v[28:29] op_sel:[1,1,0] op_sel_hi:[1,0,1] neg_lo:[0,1,0]
	v_pk_fma_f32 v[56:57], v[60:61], v[80:81], v[54:55] op_sel:[1,1,0] op_sel_hi:[1,0,1] neg_lo:[0,1,0]
	v_pk_mul_f32 v[54:55], v[102:103], v[84:85] op_sel:[0,0] op_sel_hi:[0,1]
	v_pk_mul_f32 v[28:29], v[100:101], v[78:79] op_sel:[0,0] op_sel_hi:[0,1]
	v_pk_mul_f32 v[32:33], v[68:69], v[74:75] op_sel:[0,0] op_sel_hi:[0,1]
	v_pk_fma_f32 v[46:47], v[62:63], v[86:87], v[46:47] op_sel:[1,1,0] op_sel_hi:[1,0,1] neg_lo:[0,1,0]
	v_pk_fma_f32 v[50:51], v[64:65], v[82:83], v[50:51] op_sel:[1,1,0] op_sel_hi:[1,0,1] neg_lo:[0,1,0]
	s_waitcnt vmcnt(1)
	v_pk_mul_f32 v[62:63], v[106:107], v[88:89] op_sel:[0,0] op_sel_hi:[0,1]
	v_pk_fma_f32 v[60:61], v[102:103], v[84:85], v[54:55] op_sel:[1,1,0] op_sel_hi:[1,0,1] neg_lo:[0,1,0]
	v_pk_mul_f32 v[54:55], v[104:105], v[94:95] op_sel:[0,0] op_sel_hi:[0,1]
	s_waitcnt vmcnt(0)
	v_pk_mul_f32 v[64:65], v[112:113], v[92:93] op_sel:[0,0] op_sel_hi:[0,1]
	v_pk_fma_f32 v[26:27], v[98:99], v[70:71], v[26:27] op_sel:[1,1,0] op_sel_hi:[1,0,1] neg_lo:[0,1,0]
	v_pk_fma_f32 v[28:29], v[100:101], v[78:79], v[28:29] op_sel:[1,1,0] op_sel_hi:[1,0,1] neg_lo:[0,1,0]
	v_pk_fma_f32 v[32:33], v[68:69], v[74:75], v[32:33] op_sel:[1,1,0] op_sel_hi:[1,0,1] neg_lo:[0,1,0]
	v_pk_fma_f32 v[48:49], v[66:67], v[72:73], v[48:49] op_sel:[1,1,0] op_sel_hi:[1,0,1] neg_lo:[0,1,0]
	v_pk_fma_f32 v[54:55], v[104:105], v[94:95], v[54:55] op_sel:[1,1,0] op_sel_hi:[1,0,1] neg_lo:[0,1,0]
	v_pk_fma_f32 v[58:59], v[110:111], v[90:91], v[58:59] op_sel:[1,1,0] op_sel_hi:[1,0,1] neg_lo:[0,1,0]
	v_pk_fma_f32 v[62:63], v[106:107], v[88:89], v[62:63] op_sel:[1,1,0] op_sel_hi:[1,0,1] neg_lo:[0,1,0]
	v_pk_fma_f32 v[64:65], v[112:113], v[92:93], v[64:65] op_sel:[1,1,0] op_sel_hi:[1,0,1] neg_lo:[0,1,0]
	s_cbranch_scc1 .LBB0_3486
	s_mul_i32 s15, s0, 0x4400
	s_mul_hi_u32 s1, s0, 0x4400
	s_add_u32 s28, s11, s15
	s_addc_u32 s29, s10, s1
	s_add_i32 s1, s0, 0x400
	s_add_i32 s79, s15, 0x1100000
	s_mul_hi_u32 s1, s1, 0x4400
	v_lshlrev_b32_e32 v2, 3, v133
	s_add_u32 s80, s11, s79
	v_ashrrev_i32_e32 v3, 31, v2
	s_addc_u32 s81, s10, s1
	s_addk_i32 s0, 0x800
	s_add_i32 s15, s15, 0x2200000
	v_lshlrev_b64 v[18:19], 1, v[2:3]
	v_add_u32_e32 v2, 0x1000, v2
	s_mul_hi_u32 s1, s0, 0x4400
	s_add_u32 s0, s11, s15
	v_ashrrev_i32_e32 v3, 31, v2
	s_addc_u32 s1, s10, s1
	v_lshlrev_b64 v[20:21], 1, v[2:3]
	v_lshl_add_u64 v[4:5], s[28:29], 0, v[18:19]
	v_lshl_add_u64 v[6:7], s[28:29], 0, v[20:21]
	v_lshl_add_u64 v[10:11], s[80:81], 0, v[18:19]
	v_lshl_add_u64 v[14:15], s[80:81], 0, v[20:21]
	v_lshl_add_u64 v[18:19], s[0:1], 0, v[18:19]
	v_lshl_add_u64 v[22:23], s[0:1], 0, v[20:21]
	global_load_dwordx4 v[2:5], v[4:5], off
	s_nop 0
	global_load_dwordx4 v[6:9], v[6:7], off
	s_nop 0
	global_load_dwordx4 v[10:13], v[10:11], off
	s_nop 0
	global_load_dwordx4 v[14:17], v[14:15], off
	s_nop 0
	global_load_dwordx4 v[18:21], v[18:19], off
	s_nop 0
	global_load_dwordx4 v[22:25], v[22:23], off
.LBB0_3486:
	v_pk_add_f32 v[66:67], v[26:27], v[42:43]
	v_pk_add_f32 v[26:27], v[26:27], v[42:43] neg_lo:[0,1] neg_hi:[0,1]
	v_pk_add_f32 v[42:43], v[30:31], v[44:45]
	v_pk_add_f32 v[30:31], v[30:31], v[44:45] neg_lo:[0,1] neg_hi:[0,1]
	v_pk_add_f32 v[68:69], v[66:67], v[42:43]
	v_pk_add_f32 v[70:71], v[26:27], v[30:31] op_sel:[0,1] op_sel_hi:[1,0] neg_lo:[0,1]
	v_pk_add_f32 v[72:73], v[26:27], v[30:31] op_sel:[0,1] op_sel_hi:[1,0] neg_hi:[0,1]
	v_pk_add_f32 v[26:27], v[28:29], v[48:49]
	v_pk_add_f32 v[28:29], v[28:29], v[48:49] neg_lo:[0,1] neg_hi:[0,1]
	v_pk_add_f32 v[30:31], v[32:33], v[52:53]
	v_pk_add_f32 v[32:33], v[32:33], v[52:53] neg_lo:[0,1] neg_hi:[0,1]
	v_pk_add_f32 v[66:67], v[66:67], v[42:43] neg_lo:[0,1] neg_hi:[0,1]
	v_pk_add_f32 v[48:49], v[26:27], v[30:31]
	v_pk_add_f32 v[30:31], v[26:27], v[30:31] neg_lo:[0,1] neg_hi:[0,1]
	v_pk_add_f32 v[26:27], v[28:29], v[32:33] op_sel:[0,1] op_sel_hi:[1,0] neg_lo:[0,1]
	v_pk_add_f32 v[44:45], v[28:29], v[32:33] op_sel:[0,1] op_sel_hi:[1,0] neg_hi:[0,1]
	v_pk_add_f32 v[28:29], v[46:47], v[56:57]
	v_pk_add_f32 v[32:33], v[46:47], v[56:57] neg_lo:[0,1] neg_hi:[0,1]
	v_pk_add_f32 v[42:43], v[50:51], v[60:61]
	v_pk_add_f32 v[46:47], v[50:51], v[60:61] neg_lo:[0,1] neg_hi:[0,1]
	v_pk_add_f32 v[50:51], v[28:29], v[42:43]
	v_pk_add_f32 v[52:53], v[28:29], v[42:43] neg_lo:[0,1] neg_hi:[0,1]
	v_pk_add_f32 v[42:43], v[32:33], v[46:47] op_sel:[0,1] op_sel_hi:[1,0] neg_lo:[0,1]
	v_pk_add_f32 v[46:47], v[32:33], v[46:47] op_sel:[0,1] op_sel_hi:[1,0] neg_hi:[0,1]
	v_pk_add_f32 v[28:29], v[54:55], v[62:63]
	v_pk_add_f32 v[32:33], v[54:55], v[62:63] neg_lo:[0,1] neg_hi:[0,1]
	v_pk_add_f32 v[54:55], v[58:59], v[64:65]
	v_pk_add_f32 v[56:57], v[58:59], v[64:65] neg_lo:[0,1] neg_hi:[0,1]
	v_pk_add_f32 v[58:59], v[28:29], v[54:55]
	v_pk_add_f32 v[54:55], v[28:29], v[54:55] neg_lo:[0,1] neg_hi:[0,1]
	v_pk_add_f32 v[60:61], v[32:33], v[56:57] op_sel:[0,1] op_sel_hi:[1,0] neg_lo:[0,1]
	v_pk_add_f32 v[56:57], v[32:33], v[56:57] op_sel:[0,1] op_sel_hi:[1,0] neg_hi:[0,1]
	v_pk_mul_f32 v[28:29], v[26:27], s[58:59] op_sel:[0,0] op_sel_hi:[0,1]
	v_pk_fma_f32 v[62:63], v[26:27], s[58:59], v[28:29] op_sel:[1,1,0] op_sel_hi:[1,0,1] neg_lo:[0,1,0]
	v_pk_mul_f32 v[26:27], v[42:43], s[60:61] op_sel:[0,0] op_sel_hi:[0,1]
	v_pk_fma_f32 v[64:65], v[42:43], s[60:61], v[26:27] op_sel:[1,1,0] op_sel_hi:[1,0,1] neg_lo:[0,1,0]
	v_pk_mul_f32 v[42:43], v[60:61], s[62:63] op_sel:[0,0] op_sel_hi:[0,1]
	v_pk_fma_f32 v[60:61], v[60:61], s[62:63], v[42:43] op_sel:[1,1,0] op_sel_hi:[1,0,1] neg_lo:[0,1,0]
	v_pk_mul_f32 v[42:43], v[30:31], s[60:61] op_sel:[0,0] op_sel_hi:[0,1]
	v_pk_fma_f32 v[74:75], v[30:31], s[60:61], v[42:43] op_sel:[1,1,0] op_sel_hi:[1,0,1] neg_lo:[0,1,0]
	v_pk_mul_f32 v[30:31], v[52:53], s[64:65] op_sel:[0,0] op_sel_hi:[0,1]
	v_pk_fma_f32 v[52:53], v[52:53], s[64:65], v[30:31] op_sel:[1,1,0] op_sel_hi:[1,0,1] neg_lo:[0,1,0]
	v_pk_mul_f32 v[76:77], v[54:55], s[66:67] op_sel:[0,0] op_sel_hi:[0,1]
	v_pk_fma_f32 v[54:55], v[54:55], s[66:67], v[76:77] op_sel:[1,1,0] op_sel_hi:[1,0,1] neg_lo:[0,1,0]
	v_pk_mul_f32 v[76:77], v[44:45], s[62:63] op_sel:[0,0] op_sel_hi:[0,1]
	v_pk_fma_f32 v[76:77], v[44:45], s[62:63], v[76:77] op_sel:[1,1,0] op_sel_hi:[1,0,1] neg_lo:[0,1,0]
	v_pk_mul_f32 v[44:45], v[46:47], s[66:67] op_sel:[0,0] op_sel_hi:[0,1]
	v_pk_fma_f32 v[46:47], v[46:47], s[66:67], v[44:45] op_sel:[1,1,0] op_sel_hi:[1,0,1] neg_lo:[0,1,0]
	v_pk_mul_f32 v[78:79], v[56:57], s[68:69] op_sel:[0,0] op_sel_hi:[0,1]
	v_pk_fma_f32 v[56:57], v[56:57], s[68:69], v[78:79] op_sel:[1,1,0] op_sel_hi:[1,0,1] neg_lo:[0,1,0]
	v_pk_add_f32 v[78:79], v[68:69], v[50:51]
	v_pk_add_f32 v[50:51], v[68:69], v[50:51] neg_lo:[0,1] neg_hi:[0,1]
	v_pk_add_f32 v[68:69], v[48:49], v[58:59]
	v_pk_add_f32 v[48:49], v[48:49], v[58:59] neg_lo:[0,1] neg_hi:[0,1]
	v_pk_add_f32 v[58:59], v[78:79], v[68:69]
	v_pk_add_f32 v[68:69], v[78:79], v[68:69] neg_lo:[0,1] neg_hi:[0,1]
	v_pk_add_f32 v[78:79], v[50:51], v[48:49] op_sel:[0,1] op_sel_hi:[1,0] neg_lo:[0,1]
	v_pk_add_f32 v[48:49], v[50:51], v[48:49] op_sel:[0,1] op_sel_hi:[1,0] neg_hi:[0,1]
	v_pk_add_f32 v[50:51], v[70:71], v[64:65]
	v_pk_add_f32 v[64:65], v[70:71], v[64:65] neg_lo:[0,1] neg_hi:[0,1]
	v_pk_add_f32 v[70:71], v[62:63], v[60:61]
	v_pk_add_f32 v[60:61], v[62:63], v[60:61] neg_lo:[0,1] neg_hi:[0,1]
	v_pk_add_f32 v[62:63], v[50:51], v[70:71]
	v_pk_add_f32 v[50:51], v[50:51], v[70:71] neg_lo:[0,1] neg_hi:[0,1]
	v_pk_add_f32 v[70:71], v[64:65], v[60:61] op_sel:[0,1] op_sel_hi:[1,0] neg_lo:[0,1]
	v_pk_add_f32 v[60:61], v[64:65], v[60:61] op_sel:[0,1] op_sel_hi:[1,0] neg_hi:[0,1]
	v_pk_add_f32 v[64:65], v[66:67], v[52:53]
	v_pk_add_f32 v[52:53], v[66:67], v[52:53] neg_lo:[0,1] neg_hi:[0,1]
	v_pk_add_f32 v[66:67], v[74:75], v[54:55]
	v_pk_add_f32 v[54:55], v[74:75], v[54:55] neg_lo:[0,1] neg_hi:[0,1]
	v_pk_add_f32 v[74:75], v[64:65], v[66:67]
	v_pk_add_f32 v[64:65], v[64:65], v[66:67] neg_lo:[0,1] neg_hi:[0,1]
	v_pk_add_f32 v[66:67], v[52:53], v[54:55] op_sel:[0,1] op_sel_hi:[1,0] neg_lo:[0,1]
	v_pk_add_f32 v[52:53], v[52:53], v[54:55] op_sel:[0,1] op_sel_hi:[1,0] neg_hi:[0,1]
	v_pk_add_f32 v[54:55], v[72:73], v[46:47]
	v_pk_add_f32 v[46:47], v[72:73], v[46:47] neg_lo:[0,1] neg_hi:[0,1]
	v_pk_add_f32 v[72:73], v[76:77], v[56:57]
	v_pk_add_f32 v[56:57], v[76:77], v[56:57] neg_lo:[0,1] neg_hi:[0,1]
	v_pk_add_f32 v[76:77], v[54:55], v[72:73]
	v_pk_add_f32 v[54:55], v[54:55], v[72:73] neg_lo:[0,1] neg_hi:[0,1]
	v_pk_add_f32 v[72:73], v[46:47], v[56:57] op_sel:[0,1] op_sel_hi:[1,0] neg_lo:[0,1]
	v_pk_add_f32 v[46:47], v[46:47], v[56:57] op_sel:[0,1] op_sel_hi:[1,0] neg_hi:[0,1]
	ds_write2_b64 v135, v[58:59], v[62:63] offset1:1
	ds_write2_b64 v135, v[74:75], v[76:77] offset0:2 offset1:3
	ds_write2_b64 v135, v[78:79], v[70:71] offset0:4 offset1:5
	ds_write2_b64 v135, v[66:67], v[72:73] offset0:6 offset1:7
	ds_write2_b64 v135, v[68:69], v[50:51] offset0:8 offset1:9
	ds_write2_b64 v135, v[64:65], v[54:55] offset0:10 offset1:11
	ds_write2_b64 v135, v[48:49], v[60:61] offset0:12 offset1:13
	ds_write2_b64 v135, v[52:53], v[46:47] offset0:14 offset1:15
	s_waitcnt lgkmcnt(0)
	s_barrier
	ds_read2_b64 v[46:49], v134 offset1:17
	ds_read2_b64 v[50:53], v134 offset0:34 offset1:51
	s_waitcnt lgkmcnt(1)
	v_pk_mul_f32 v[54:55], v[48:49], v[40:41] op_sel:[0,0] op_sel_hi:[0,1] neg_hi:[0,1]
	v_pk_fma_f32 v[56:57], v[48:49], v[40:41], v[54:55] op_sel:[1,1,0] op_sel_hi:[1,0,1]
	v_pk_mul_f32 v[48:49], v[40:41], v[40:41] op_sel:[0,0] op_sel_hi:[0,1]
	v_pk_fma_f32 v[48:49], v[40:41], v[40:41], v[48:49] op_sel:[1,1,0] op_sel_hi:[1,0,1] neg_lo:[0,1,0]
	s_waitcnt lgkmcnt(0)
	v_pk_mul_f32 v[54:55], v[50:51], v[48:49] op_sel:[0,0] op_sel_hi:[0,1] neg_hi:[0,1]
	v_pk_fma_f32 v[58:59], v[50:51], v[48:49], v[54:55] op_sel:[1,1,0] op_sel_hi:[1,0,1]
	v_pk_mul_f32 v[50:51], v[48:49], v[40:41] op_sel:[0,0] op_sel_hi:[0,1]
	v_pk_fma_f32 v[54:55], v[48:49], v[40:41], v[50:51] op_sel:[1,1,0] op_sel_hi:[1,0,1] neg_lo:[0,1,0]
	ds_read2_b64 v[48:51], v134 offset0:68 offset1:85
	v_pk_mul_f32 v[60:61], v[52:53], v[54:55] op_sel:[0,0] op_sel_hi:[0,1] neg_hi:[0,1]
	v_pk_fma_f32 v[60:61], v[52:53], v[54:55], v[60:61] op_sel:[1,1,0] op_sel_hi:[1,0,1]
	v_pk_mul_f32 v[52:53], v[54:55], v[40:41] op_sel:[0,0] op_sel_hi:[0,1]
	v_pk_fma_f32 v[52:53], v[54:55], v[40:41], v[52:53] op_sel:[1,1,0] op_sel_hi:[1,0,1] neg_lo:[0,1,0]
	s_waitcnt lgkmcnt(0)
	v_pk_mul_f32 v[54:55], v[48:49], v[52:53] op_sel:[0,0] op_sel_hi:[0,1] neg_hi:[0,1]
	v_pk_fma_f32 v[62:63], v[48:49], v[52:53], v[54:55] op_sel:[1,1,0] op_sel_hi:[1,0,1]
	v_pk_mul_f32 v[48:49], v[52:53], v[40:41] op_sel:[0,0] op_sel_hi:[0,1]
	v_pk_fma_f32 v[48:49], v[52:53], v[40:41], v[48:49] op_sel:[1,1,0] op_sel_hi:[1,0,1] neg_lo:[0,1,0]
	ds_read2_b64 v[52:55], v134 offset0:102 offset1:119
	v_pk_mul_f32 v[64:65], v[50:51], v[48:49] op_sel:[0,0] op_sel_hi:[0,1] neg_hi:[0,1]
	v_pk_fma_f32 v[64:65], v[50:51], v[48:49], v[64:65] op_sel:[1,1,0] op_sel_hi:[1,0,1]
	v_pk_mul_f32 v[50:51], v[48:49], v[40:41] op_sel:[0,0] op_sel_hi:[0,1]
	v_pk_fma_f32 v[48:49], v[48:49], v[40:41], v[50:51] op_sel:[1,1,0] op_sel_hi:[1,0,1] neg_lo:[0,1,0]
	s_waitcnt lgkmcnt(0)
	v_pk_mul_f32 v[50:51], v[52:53], v[48:49] op_sel:[0,0] op_sel_hi:[0,1] neg_hi:[0,1]
	v_pk_fma_f32 v[66:67], v[52:53], v[48:49], v[50:51] op_sel:[1,1,0] op_sel_hi:[1,0,1]
	v_pk_mul_f32 v[50:51], v[48:49], v[40:41] op_sel:[0,0] op_sel_hi:[0,1]
	v_pk_fma_f32 v[52:53], v[48:49], v[40:41], v[50:51] op_sel:[1,1,0] op_sel_hi:[1,0,1] neg_lo:[0,1,0]
	ds_read2_b64 v[48:51], v134 offset0:136 offset1:153
	v_pk_mul_f32 v[68:69], v[54:55], v[52:53] op_sel:[0,0] op_sel_hi:[0,1] neg_hi:[0,1]
	v_pk_fma_f32 v[68:69], v[54:55], v[52:53], v[68:69] op_sel:[1,1,0] op_sel_hi:[1,0,1]
	v_pk_mul_f32 v[54:55], v[52:53], v[40:41] op_sel:[0,0] op_sel_hi:[0,1]
	v_pk_fma_f32 v[52:53], v[52:53], v[40:41], v[54:55] op_sel:[1,1,0] op_sel_hi:[1,0,1] neg_lo:[0,1,0]
	s_waitcnt lgkmcnt(0)
	v_pk_mul_f32 v[54:55], v[48:49], v[52:53] op_sel:[0,0] op_sel_hi:[0,1] neg_hi:[0,1]
	v_pk_fma_f32 v[70:71], v[48:49], v[52:53], v[54:55] op_sel:[1,1,0] op_sel_hi:[1,0,1]
	v_pk_mul_f32 v[48:49], v[52:53], v[40:41] op_sel:[0,0] op_sel_hi:[0,1]
	v_pk_fma_f32 v[48:49], v[52:53], v[40:41], v[48:49] op_sel:[1,1,0] op_sel_hi:[1,0,1] neg_lo:[0,1,0]
	ds_read2_b64 v[52:55], v134 offset0:170 offset1:187
	v_pk_mul_f32 v[72:73], v[50:51], v[48:49] op_sel:[0,0] op_sel_hi:[0,1] neg_hi:[0,1]
	v_pk_fma_f32 v[72:73], v[50:51], v[48:49], v[72:73] op_sel:[1,1,0] op_sel_hi:[1,0,1]
	v_pk_mul_f32 v[50:51], v[48:49], v[40:41] op_sel:[0,0] op_sel_hi:[0,1]
	v_pk_fma_f32 v[48:49], v[48:49], v[40:41], v[50:51] op_sel:[1,1,0] op_sel_hi:[1,0,1] neg_lo:[0,1,0]
	s_waitcnt lgkmcnt(0)
	v_pk_mul_f32 v[50:51], v[52:53], v[48:49] op_sel:[0,0] op_sel_hi:[0,1] neg_hi:[0,1]
	v_pk_fma_f32 v[74:75], v[52:53], v[48:49], v[50:51] op_sel:[1,1,0] op_sel_hi:[1,0,1]
	v_pk_mul_f32 v[50:51], v[48:49], v[40:41] op_sel:[0,0] op_sel_hi:[0,1]
	v_pk_fma_f32 v[52:53], v[48:49], v[40:41], v[50:51] op_sel:[1,1,0] op_sel_hi:[1,0,1] neg_lo:[0,1,0]
	ds_read2_b64 v[48:51], v134 offset0:204 offset1:221
	v_pk_mul_f32 v[76:77], v[54:55], v[52:53] op_sel:[0,0] op_sel_hi:[0,1] neg_hi:[0,1]
	v_pk_fma_f32 v[76:77], v[54:55], v[52:53], v[76:77] op_sel:[1,1,0] op_sel_hi:[1,0,1]
	v_pk_mul_f32 v[54:55], v[52:53], v[40:41] op_sel:[0,0] op_sel_hi:[0,1]
	v_pk_fma_f32 v[52:53], v[52:53], v[40:41], v[54:55] op_sel:[1,1,0] op_sel_hi:[1,0,1] neg_lo:[0,1,0]
	s_waitcnt lgkmcnt(0)
	v_pk_mul_f32 v[54:55], v[48:49], v[52:53] op_sel:[0,0] op_sel_hi:[0,1] neg_hi:[0,1]
	v_pk_fma_f32 v[48:49], v[48:49], v[52:53], v[54:55] op_sel:[1,1,0] op_sel_hi:[1,0,1]
	v_pk_mul_f32 v[54:55], v[52:53], v[40:41] op_sel:[0,0] op_sel_hi:[0,1]
	v_pk_fma_f32 v[78:79], v[52:53], v[40:41], v[54:55] op_sel:[1,1,0] op_sel_hi:[1,0,1] neg_lo:[0,1,0]
	ds_read2_b64 v[52:55], v134 offset0:238 offset1:255
	v_pk_mul_f32 v[80:81], v[50:51], v[78:79] op_sel:[0,0] op_sel_hi:[0,1] neg_hi:[0,1]
	v_pk_fma_f32 v[50:51], v[50:51], v[78:79], v[80:81] op_sel:[1,1,0] op_sel_hi:[1,0,1]
	v_pk_mul_f32 v[80:81], v[78:79], v[40:41] op_sel:[0,0] op_sel_hi:[0,1]
	v_pk_fma_f32 v[78:79], v[78:79], v[40:41], v[80:81] op_sel:[1,1,0] op_sel_hi:[1,0,1] neg_lo:[0,1,0]
	s_waitcnt lgkmcnt(0)
	v_pk_mul_f32 v[80:81], v[52:53], v[78:79] op_sel:[0,0] op_sel_hi:[0,1] neg_hi:[0,1]
	v_pk_fma_f32 v[52:53], v[52:53], v[78:79], v[80:81] op_sel:[1,1,0] op_sel_hi:[1,0,1]
	v_pk_mul_f32 v[80:81], v[78:79], v[40:41] op_sel:[0,0] op_sel_hi:[0,1]
	v_pk_fma_f32 v[40:41], v[78:79], v[40:41], v[80:81] op_sel:[1,1,0] op_sel_hi:[1,0,1] neg_lo:[0,1,0]
	v_pk_mul_f32 v[78:79], v[54:55], v[40:41] op_sel:[0,0] op_sel_hi:[0,1] neg_hi:[0,1]
	v_pk_fma_f32 v[40:41], v[54:55], v[40:41], v[78:79] op_sel:[1,1,0] op_sel_hi:[1,0,1]
	v_pk_add_f32 v[54:55], v[46:47], v[70:71]
	v_pk_add_f32 v[46:47], v[46:47], v[70:71] neg_lo:[0,1] neg_hi:[0,1]
	v_pk_add_f32 v[70:71], v[62:63], v[48:49]
	v_pk_add_f32 v[48:49], v[62:63], v[48:49] neg_lo:[0,1] neg_hi:[0,1]
	v_pk_add_f32 v[62:63], v[54:55], v[70:71]
	v_pk_add_f32 v[54:55], v[54:55], v[70:71] neg_lo:[0,1] neg_hi:[0,1]
	v_pk_add_f32 v[70:71], v[46:47], v[48:49] op_sel:[0,1] op_sel_hi:[1,0] neg_lo:[0,1]
	v_pk_add_f32 v[46:47], v[46:47], v[48:49] op_sel:[0,1] op_sel_hi:[1,0] neg_hi:[0,1]
	v_pk_add_f32 v[48:49], v[56:57], v[72:73]
	v_pk_add_f32 v[56:57], v[56:57], v[72:73] neg_lo:[0,1] neg_hi:[0,1]
	v_pk_add_f32 v[72:73], v[64:65], v[50:51]
	v_pk_add_f32 v[50:51], v[64:65], v[50:51] neg_lo:[0,1] neg_hi:[0,1]
	v_pk_add_f32 v[64:65], v[48:49], v[72:73]
	v_pk_add_f32 v[48:49], v[48:49], v[72:73] neg_lo:[0,1] neg_hi:[0,1]
	v_pk_add_f32 v[72:73], v[56:57], v[50:51] op_sel:[0,1] op_sel_hi:[1,0] neg_lo:[0,1]
	v_pk_add_f32 v[50:51], v[56:57], v[50:51] op_sel:[0,1] op_sel_hi:[1,0] neg_hi:[0,1]
	v_pk_add_f32 v[56:57], v[58:59], v[74:75]
	v_pk_add_f32 v[58:59], v[58:59], v[74:75] neg_lo:[0,1] neg_hi:[0,1]
	v_pk_add_f32 v[74:75], v[66:67], v[52:53]
	v_pk_add_f32 v[52:53], v[66:67], v[52:53] neg_lo:[0,1] neg_hi:[0,1]
	v_pk_add_f32 v[66:67], v[56:57], v[74:75]
	v_pk_add_f32 v[56:57], v[56:57], v[74:75] neg_lo:[0,1] neg_hi:[0,1]
	v_pk_add_f32 v[74:75], v[58:59], v[52:53] op_sel:[0,1] op_sel_hi:[1,0] neg_lo:[0,1]
	v_pk_add_f32 v[52:53], v[58:59], v[52:53] op_sel:[0,1] op_sel_hi:[1,0] neg_hi:[0,1]
	v_pk_add_f32 v[58:59], v[60:61], v[76:77]
	v_pk_add_f32 v[60:61], v[60:61], v[76:77] neg_lo:[0,1] neg_hi:[0,1]
	v_pk_add_f32 v[76:77], v[68:69], v[40:41]
	v_pk_add_f32 v[40:41], v[68:69], v[40:41] neg_lo:[0,1] neg_hi:[0,1]
	v_pk_add_f32 v[68:69], v[58:59], v[76:77]
	v_pk_add_f32 v[58:59], v[58:59], v[76:77] neg_lo:[0,1] neg_hi:[0,1]
	v_pk_add_f32 v[76:77], v[60:61], v[40:41] op_sel:[0,1] op_sel_hi:[1,0] neg_lo:[0,1]
	v_pk_add_f32 v[40:41], v[60:61], v[40:41] op_sel:[0,1] op_sel_hi:[1,0] neg_hi:[0,1]
	v_pk_mul_f32 v[60:61], v[72:73], s[58:59] op_sel:[0,0] op_sel_hi:[0,1]
	v_pk_fma_f32 v[60:61], v[72:73], s[58:59], v[60:61] op_sel:[1,1,0] op_sel_hi:[1,0,1] neg_lo:[0,1,0]
	v_pk_mul_f32 v[72:73], v[74:75], s[60:61] op_sel:[0,0] op_sel_hi:[0,1]
	v_pk_fma_f32 v[72:73], v[74:75], s[60:61], v[72:73] op_sel:[1,1,0] op_sel_hi:[1,0,1] neg_lo:[0,1,0]
	v_pk_mul_f32 v[74:75], v[76:77], s[62:63] op_sel:[0,0] op_sel_hi:[0,1]
	v_pk_fma_f32 v[74:75], v[76:77], s[62:63], v[74:75] op_sel:[1,1,0] op_sel_hi:[1,0,1] neg_lo:[0,1,0]
	v_pk_mul_f32 v[76:77], v[48:49], s[60:61] op_sel:[0,0] op_sel_hi:[0,1]
	v_pk_fma_f32 v[48:49], v[48:49], s[60:61], v[76:77] op_sel:[1,1,0] op_sel_hi:[1,0,1] neg_lo:[0,1,0]
	v_pk_mul_f32 v[76:77], v[56:57], s[64:65] op_sel:[0,0] op_sel_hi:[0,1]
	v_pk_fma_f32 v[56:57], v[56:57], s[64:65], v[76:77] op_sel:[1,1,0] op_sel_hi:[1,0,1] neg_lo:[0,1,0]
	v_pk_mul_f32 v[76:77], v[58:59], s[66:67] op_sel:[0,0] op_sel_hi:[0,1]
	v_pk_fma_f32 v[58:59], v[58:59], s[66:67], v[76:77] op_sel:[1,1,0] op_sel_hi:[1,0,1] neg_lo:[0,1,0]
	v_pk_mul_f32 v[76:77], v[50:51], s[62:63] op_sel:[0,0] op_sel_hi:[0,1]
	v_pk_fma_f32 v[50:51], v[50:51], s[62:63], v[76:77] op_sel:[1,1,0] op_sel_hi:[1,0,1] neg_lo:[0,1,0]
	v_pk_mul_f32 v[76:77], v[52:53], s[66:67] op_sel:[0,0] op_sel_hi:[0,1]
	v_pk_fma_f32 v[52:53], v[52:53], s[66:67], v[76:77] op_sel:[1,1,0] op_sel_hi:[1,0,1] neg_lo:[0,1,0]
	v_pk_mul_f32 v[76:77], v[40:41], s[68:69] op_sel:[0,0] op_sel_hi:[0,1]
	v_pk_fma_f32 v[40:41], v[40:41], s[68:69], v[76:77] op_sel:[1,1,0] op_sel_hi:[1,0,1] neg_lo:[0,1,0]
	v_pk_add_f32 v[76:77], v[62:63], v[66:67]
	v_pk_add_f32 v[62:63], v[62:63], v[66:67] neg_lo:[0,1] neg_hi:[0,1]
	v_pk_add_f32 v[66:67], v[64:65], v[68:69]
	v_pk_add_f32 v[64:65], v[64:65], v[68:69] neg_lo:[0,1] neg_hi:[0,1]
	v_pk_add_f32 v[68:69], v[76:77], v[66:67]
	v_pk_add_f32 v[66:67], v[76:77], v[66:67] neg_lo:[0,1] neg_hi:[0,1]
	v_pk_add_f32 v[76:77], v[62:63], v[64:65] op_sel:[0,1] op_sel_hi:[1,0] neg_lo:[0,1]
	v_pk_add_f32 v[62:63], v[62:63], v[64:65] op_sel:[0,1] op_sel_hi:[1,0] neg_hi:[0,1]
	v_pk_add_f32 v[64:65], v[70:71], v[72:73]
	v_pk_add_f32 v[70:71], v[70:71], v[72:73] neg_lo:[0,1] neg_hi:[0,1]
	v_pk_add_f32 v[72:73], v[60:61], v[74:75]
	v_pk_add_f32 v[60:61], v[60:61], v[74:75] neg_lo:[0,1] neg_hi:[0,1]
	v_pk_add_f32 v[74:75], v[64:65], v[72:73]
	v_pk_add_f32 v[64:65], v[64:65], v[72:73] neg_lo:[0,1] neg_hi:[0,1]
	v_pk_add_f32 v[72:73], v[70:71], v[60:61] op_sel:[0,1] op_sel_hi:[1,0] neg_lo:[0,1]
	v_pk_add_f32 v[60:61], v[70:71], v[60:61] op_sel:[0,1] op_sel_hi:[1,0] neg_hi:[0,1]
	v_pk_add_f32 v[70:71], v[54:55], v[56:57]
	v_pk_add_f32 v[54:55], v[54:55], v[56:57] neg_lo:[0,1] neg_hi:[0,1]
	v_pk_add_f32 v[56:57], v[48:49], v[58:59]
	v_pk_add_f32 v[48:49], v[48:49], v[58:59] neg_lo:[0,1] neg_hi:[0,1]
	v_pk_add_f32 v[58:59], v[70:71], v[56:57]
	v_pk_add_f32 v[56:57], v[70:71], v[56:57] neg_lo:[0,1] neg_hi:[0,1]
	v_pk_add_f32 v[70:71], v[54:55], v[48:49] op_sel:[0,1] op_sel_hi:[1,0] neg_lo:[0,1]
	v_pk_add_f32 v[48:49], v[54:55], v[48:49] op_sel:[0,1] op_sel_hi:[1,0] neg_hi:[0,1]
	v_pk_add_f32 v[54:55], v[46:47], v[52:53]
	v_pk_add_f32 v[46:47], v[46:47], v[52:53] neg_lo:[0,1] neg_hi:[0,1]
	v_pk_add_f32 v[52:53], v[50:51], v[40:41]
	v_pk_add_f32 v[40:41], v[50:51], v[40:41] neg_lo:[0,1] neg_hi:[0,1]
	v_pk_add_f32 v[50:51], v[54:55], v[52:53]
	v_pk_add_f32 v[52:53], v[54:55], v[52:53] neg_lo:[0,1] neg_hi:[0,1]
	v_pk_add_f32 v[54:55], v[46:47], v[40:41] op_sel:[0,1] op_sel_hi:[1,0] neg_lo:[0,1]
	v_pk_add_f32 v[40:41], v[46:47], v[40:41] op_sel:[0,1] op_sel_hi:[1,0] neg_hi:[0,1]
	ds_write2_b64 v134, v[68:69], v[74:75] offset1:17
	ds_write2_b64 v134, v[58:59], v[50:51] offset0:34 offset1:51
	ds_write2_b64 v134, v[76:77], v[72:73] offset0:68 offset1:85
	ds_write2_b64 v134, v[70:71], v[54:55] offset0:102 offset1:119
	ds_write2_b64 v134, v[66:67], v[64:65] offset0:136 offset1:153
	ds_write2_b64 v134, v[56:57], v[52:53] offset0:170 offset1:187
	ds_write2_b64 v134, v[62:63], v[60:61] offset0:204 offset1:221
	ds_write2_b64 v134, v[48:49], v[40:41] offset0:238 offset1:255
	s_waitcnt lgkmcnt(0)
	s_barrier
	ds_read_b64 v[40:41], v132 offset:2176
	ds_read_b64 v[46:47], v132 offset:4352
	ds_read_b64 v[48:49], v132 offset:6528
	ds_read_b64 v[50:51], v132
	s_waitcnt lgkmcnt(3)
	v_pk_mul_f32 v[52:53], v[40:41], v[38:39] op_sel:[0,0] op_sel_hi:[0,1] neg_hi:[0,1]
	v_pk_fma_f32 v[40:41], v[40:41], v[38:39], v[52:53] op_sel:[1,1,0] op_sel_hi:[1,0,1]
	v_pk_mul_f32 v[52:53], v[38:39], v[38:39] op_sel:[0,0] op_sel_hi:[0,1]
	ds_read_b64 v[56:57], v132 offset:8704
	v_pk_fma_f32 v[52:53], v[38:39], v[38:39], v[52:53] op_sel:[1,1,0] op_sel_hi:[1,0,1] neg_lo:[0,1,0]
	s_waitcnt lgkmcnt(3)
	v_pk_mul_f32 v[54:55], v[46:47], v[52:53] op_sel:[0,0] op_sel_hi:[0,1] neg_hi:[0,1]
	v_pk_fma_f32 v[46:47], v[46:47], v[52:53], v[54:55] op_sel:[1,1,0] op_sel_hi:[1,0,1]
	v_pk_mul_f32 v[54:55], v[52:53], v[38:39] op_sel:[0,0] op_sel_hi:[0,1]
	v_pk_fma_f32 v[52:53], v[52:53], v[38:39], v[54:55] op_sel:[1,1,0] op_sel_hi:[1,0,1] neg_lo:[0,1,0]
	s_waitcnt lgkmcnt(2)
	v_pk_mul_f32 v[54:55], v[48:49], v[52:53] op_sel:[0,0] op_sel_hi:[0,1] neg_hi:[0,1]
	v_pk_fma_f32 v[48:49], v[48:49], v[52:53], v[54:55] op_sel:[1,1,0] op_sel_hi:[1,0,1]
	v_pk_mul_f32 v[54:55], v[52:53], v[38:39] op_sel:[0,0] op_sel_hi:[0,1]
	v_pk_fma_f32 v[52:53], v[52:53], v[38:39], v[54:55] op_sel:[1,1,0] op_sel_hi:[1,0,1] neg_lo:[0,1,0]
	ds_read_b64 v[54:55], v132 offset:10880
	ds_read_b64 v[58:59], v132 offset:13056
	ds_read_b64 v[60:61], v132 offset:15232
	s_waitcnt lgkmcnt(3)
	v_pk_mul_f32 v[62:63], v[56:57], v[52:53] op_sel:[0,0] op_sel_hi:[0,1] neg_hi:[0,1]
	ds_read_b64 v[64:65], v132 offset:17408
	v_pk_fma_f32 v[56:57], v[56:57], v[52:53], v[62:63] op_sel:[1,1,0] op_sel_hi:[1,0,1]
	v_pk_mul_f32 v[62:63], v[52:53], v[38:39] op_sel:[0,0] op_sel_hi:[0,1]
	v_pk_fma_f32 v[52:53], v[52:53], v[38:39], v[62:63] op_sel:[1,1,0] op_sel_hi:[1,0,1] neg_lo:[0,1,0]
	s_waitcnt lgkmcnt(3)
	v_pk_mul_f32 v[62:63], v[54:55], v[52:53] op_sel:[0,0] op_sel_hi:[0,1] neg_hi:[0,1]
	v_pk_fma_f32 v[54:55], v[54:55], v[52:53], v[62:63] op_sel:[1,1,0] op_sel_hi:[1,0,1]
	v_pk_mul_f32 v[62:63], v[52:53], v[38:39] op_sel:[0,0] op_sel_hi:[0,1]
	v_pk_fma_f32 v[52:53], v[52:53], v[38:39], v[62:63] op_sel:[1,1,0] op_sel_hi:[1,0,1] neg_lo:[0,1,0]
	s_waitcnt lgkmcnt(2)
	v_pk_mul_f32 v[62:63], v[58:59], v[52:53] op_sel:[0,0] op_sel_hi:[0,1] neg_hi:[0,1]
	v_pk_fma_f32 v[58:59], v[58:59], v[52:53], v[62:63] op_sel:[1,1,0] op_sel_hi:[1,0,1]
	v_pk_mul_f32 v[62:63], v[52:53], v[38:39] op_sel:[0,0] op_sel_hi:[0,1]
	v_pk_fma_f32 v[52:53], v[52:53], v[38:39], v[62:63] op_sel:[1,1,0] op_sel_hi:[1,0,1] neg_lo:[0,1,0]
	s_waitcnt lgkmcnt(1)
	v_pk_mul_f32 v[62:63], v[60:61], v[52:53] op_sel:[0,0] op_sel_hi:[0,1] neg_hi:[0,1]
	v_pk_fma_f32 v[60:61], v[60:61], v[52:53], v[62:63] op_sel:[1,1,0] op_sel_hi:[1,0,1]
	v_pk_mul_f32 v[62:63], v[52:53], v[38:39] op_sel:[0,0] op_sel_hi:[0,1]
	v_pk_fma_f32 v[52:53], v[52:53], v[38:39], v[62:63] op_sel:[1,1,0] op_sel_hi:[1,0,1] neg_lo:[0,1,0]
	ds_read_b64 v[62:63], v132 offset:19584
	ds_read_b64 v[66:67], v132 offset:21760
	ds_read_b64 v[68:69], v132 offset:23936
	s_waitcnt lgkmcnt(3)
	v_pk_mul_f32 v[70:71], v[64:65], v[52:53] op_sel:[0,0] op_sel_hi:[0,1] neg_hi:[0,1]
	ds_read_b64 v[72:73], v132 offset:26112
	v_pk_fma_f32 v[64:65], v[64:65], v[52:53], v[70:71] op_sel:[1,1,0] op_sel_hi:[1,0,1]
	v_pk_mul_f32 v[70:71], v[52:53], v[38:39] op_sel:[0,0] op_sel_hi:[0,1]
	v_pk_fma_f32 v[52:53], v[52:53], v[38:39], v[70:71] op_sel:[1,1,0] op_sel_hi:[1,0,1] neg_lo:[0,1,0]
	s_waitcnt lgkmcnt(3)
	v_pk_mul_f32 v[70:71], v[62:63], v[52:53] op_sel:[0,0] op_sel_hi:[0,1] neg_hi:[0,1]
	v_pk_fma_f32 v[62:63], v[62:63], v[52:53], v[70:71] op_sel:[1,1,0] op_sel_hi:[1,0,1]
	v_pk_mul_f32 v[70:71], v[52:53], v[38:39] op_sel:[0,0] op_sel_hi:[0,1]
	v_pk_fma_f32 v[52:53], v[52:53], v[38:39], v[70:71] op_sel:[1,1,0] op_sel_hi:[1,0,1] neg_lo:[0,1,0]
	s_waitcnt lgkmcnt(2)
	v_pk_mul_f32 v[70:71], v[66:67], v[52:53] op_sel:[0,0] op_sel_hi:[0,1] neg_hi:[0,1]
	v_pk_fma_f32 v[66:67], v[66:67], v[52:53], v[70:71] op_sel:[1,1,0] op_sel_hi:[1,0,1]
	v_pk_mul_f32 v[70:71], v[52:53], v[38:39] op_sel:[0,0] op_sel_hi:[0,1]
	v_pk_fma_f32 v[52:53], v[52:53], v[38:39], v[70:71] op_sel:[1,1,0] op_sel_hi:[1,0,1] neg_lo:[0,1,0]
	s_waitcnt lgkmcnt(1)
	v_pk_mul_f32 v[70:71], v[68:69], v[52:53] op_sel:[0,0] op_sel_hi:[0,1] neg_hi:[0,1]
	v_pk_fma_f32 v[68:69], v[68:69], v[52:53], v[70:71] op_sel:[1,1,0] op_sel_hi:[1,0,1]
	v_pk_mul_f32 v[70:71], v[52:53], v[38:39] op_sel:[0,0] op_sel_hi:[0,1]
	v_pk_fma_f32 v[52:53], v[52:53], v[38:39], v[70:71] op_sel:[1,1,0] op_sel_hi:[1,0,1] neg_lo:[0,1,0]
	ds_read_b64 v[70:71], v132 offset:28288
	ds_read_b64 v[74:75], v132 offset:30464
	ds_read_b64 v[76:77], v132 offset:32640
	s_waitcnt lgkmcnt(3)
	v_pk_mul_f32 v[78:79], v[72:73], v[52:53] op_sel:[0,0] op_sel_hi:[0,1] neg_hi:[0,1]
	s_nop 0
	v_pk_fma_f32 v[72:73], v[72:73], v[52:53], v[78:79] op_sel:[1,1,0] op_sel_hi:[1,0,1]
	v_pk_mul_f32 v[78:79], v[52:53], v[38:39] op_sel:[0,0] op_sel_hi:[0,1]
	v_pk_fma_f32 v[52:53], v[52:53], v[38:39], v[78:79] op_sel:[1,1,0] op_sel_hi:[1,0,1] neg_lo:[0,1,0]
	s_waitcnt lgkmcnt(2)
	v_pk_mul_f32 v[78:79], v[70:71], v[52:53] op_sel:[0,0] op_sel_hi:[0,1] neg_hi:[0,1]
	v_pk_fma_f32 v[70:71], v[70:71], v[52:53], v[78:79] op_sel:[1,1,0] op_sel_hi:[1,0,1]
	v_pk_mul_f32 v[78:79], v[52:53], v[38:39] op_sel:[0,0] op_sel_hi:[0,1]
	v_pk_fma_f32 v[52:53], v[52:53], v[38:39], v[78:79] op_sel:[1,1,0] op_sel_hi:[1,0,1] neg_lo:[0,1,0]
	s_waitcnt lgkmcnt(1)
	v_pk_mul_f32 v[78:79], v[74:75], v[52:53] op_sel:[0,0] op_sel_hi:[0,1] neg_hi:[0,1]
	v_pk_fma_f32 v[74:75], v[74:75], v[52:53], v[78:79] op_sel:[1,1,0] op_sel_hi:[1,0,1]
	v_pk_mul_f32 v[78:79], v[52:53], v[38:39] op_sel:[0,0] op_sel_hi:[0,1]
	v_pk_fma_f32 v[38:39], v[52:53], v[38:39], v[78:79] op_sel:[1,1,0] op_sel_hi:[1,0,1] neg_lo:[0,1,0]
	s_waitcnt lgkmcnt(0)
	v_pk_mul_f32 v[52:53], v[76:77], v[38:39] op_sel:[0,0] op_sel_hi:[0,1] neg_hi:[0,1]
	v_pk_fma_f32 v[38:39], v[76:77], v[38:39], v[52:53] op_sel:[1,1,0] op_sel_hi:[1,0,1]
	v_pk_add_f32 v[52:53], v[50:51], v[64:65]
	v_pk_add_f32 v[50:51], v[50:51], v[64:65] neg_lo:[0,1] neg_hi:[0,1]
	v_pk_add_f32 v[64:65], v[56:57], v[72:73]
	v_pk_add_f32 v[56:57], v[56:57], v[72:73] neg_lo:[0,1] neg_hi:[0,1]
	v_pk_add_f32 v[72:73], v[52:53], v[64:65]
	v_pk_add_f32 v[76:77], v[50:51], v[56:57] op_sel:[0,1] op_sel_hi:[1,0] neg_lo:[0,1]
	v_pk_add_f32 v[78:79], v[50:51], v[56:57] op_sel:[0,1] op_sel_hi:[1,0] neg_hi:[0,1]
	v_pk_add_f32 v[50:51], v[40:41], v[62:63]
	v_pk_add_f32 v[40:41], v[40:41], v[62:63] neg_lo:[0,1] neg_hi:[0,1]
	v_pk_add_f32 v[56:57], v[54:55], v[70:71]
	v_pk_add_f32 v[54:55], v[54:55], v[70:71] neg_lo:[0,1] neg_hi:[0,1]
	v_pk_add_f32 v[52:53], v[52:53], v[64:65] neg_lo:[0,1] neg_hi:[0,1]
	v_pk_add_f32 v[62:63], v[50:51], v[56:57]
	v_pk_add_f32 v[50:51], v[50:51], v[56:57] neg_lo:[0,1] neg_hi:[0,1]
	v_pk_add_f32 v[56:57], v[40:41], v[54:55] op_sel:[0,1] op_sel_hi:[1,0] neg_lo:[0,1]
	v_pk_add_f32 v[40:41], v[40:41], v[54:55] op_sel:[0,1] op_sel_hi:[1,0] neg_hi:[0,1]
	v_pk_add_f32 v[54:55], v[46:47], v[66:67]
	v_pk_add_f32 v[46:47], v[46:47], v[66:67] neg_lo:[0,1] neg_hi:[0,1]
	v_pk_add_f32 v[64:65], v[58:59], v[74:75]
	v_pk_add_f32 v[58:59], v[58:59], v[74:75] neg_lo:[0,1] neg_hi:[0,1]
	v_pk_add_f32 v[66:67], v[54:55], v[64:65]
	v_pk_add_f32 v[54:55], v[54:55], v[64:65] neg_lo:[0,1] neg_hi:[0,1]
	v_pk_add_f32 v[64:65], v[46:47], v[58:59] op_sel:[0,1] op_sel_hi:[1,0] neg_lo:[0,1]
	v_pk_add_f32 v[46:47], v[46:47], v[58:59] op_sel:[0,1] op_sel_hi:[1,0] neg_hi:[0,1]
	v_pk_add_f32 v[58:59], v[48:49], v[68:69]
	v_pk_add_f32 v[48:49], v[48:49], v[68:69] neg_lo:[0,1] neg_hi:[0,1]
	v_pk_add_f32 v[68:69], v[60:61], v[38:39]
	v_pk_add_f32 v[38:39], v[60:61], v[38:39] neg_lo:[0,1] neg_hi:[0,1]
	v_pk_add_f32 v[60:61], v[58:59], v[68:69]
	v_pk_add_f32 v[58:59], v[58:59], v[68:69] neg_lo:[0,1] neg_hi:[0,1]
	v_pk_add_f32 v[68:69], v[48:49], v[38:39] op_sel:[0,1] op_sel_hi:[1,0] neg_lo:[0,1]
	v_pk_add_f32 v[38:39], v[48:49], v[38:39] op_sel:[0,1] op_sel_hi:[1,0] neg_hi:[0,1]
	v_pk_mul_f32 v[48:49], v[56:57], s[58:59] op_sel:[0,0] op_sel_hi:[0,1]
	v_pk_fma_f32 v[32:33], v[56:57], s[58:59], v[48:49] op_sel:[1,1,0] op_sel_hi:[1,0,1] neg_lo:[0,1,0]
	v_pk_mul_f32 v[48:49], v[64:65], s[60:61] op_sel:[0,0] op_sel_hi:[0,1]
	v_pk_mul_f32 v[56:57], v[68:69], s[62:63] op_sel:[0,0] op_sel_hi:[0,1]
	v_pk_fma_f32 v[48:49], v[64:65], s[60:61], v[48:49] op_sel:[1,1,0] op_sel_hi:[1,0,1] neg_lo:[0,1,0]
	v_pk_fma_f32 v[56:57], v[68:69], s[62:63], v[56:57] op_sel:[1,1,0] op_sel_hi:[1,0,1] neg_lo:[0,1,0]
	v_pk_mul_f32 v[64:65], v[50:51], s[60:61] op_sel:[0,0] op_sel_hi:[0,1]
	v_pk_fma_f32 v[68:69], v[50:51], s[60:61], v[64:65] op_sel:[1,1,0] op_sel_hi:[1,0,1] neg_lo:[0,1,0]
	v_pk_mul_f32 v[28:29], v[54:55], s[64:65] op_sel:[0,0] op_sel_hi:[0,1]
	v_pk_fma_f32 v[54:55], v[54:55], s[64:65], v[28:29] op_sel:[1,1,0] op_sel_hi:[1,0,1] neg_lo:[0,1,0]
	v_pk_mul_f32 v[28:29], v[58:59], s[66:67] op_sel:[0,0] op_sel_hi:[0,1]
	v_pk_add_f32 v[42:43], v[62:63], v[60:61]
	v_pk_fma_f32 v[58:59], v[58:59], s[66:67], v[28:29] op_sel:[1,1,0] op_sel_hi:[1,0,1] neg_lo:[0,1,0]
	v_pk_mul_f32 v[28:29], v[40:41], s[62:63] op_sel:[0,0] op_sel_hi:[0,1]
	v_pk_add_f32 v[50:51], v[52:53], v[54:55]
	v_pk_fma_f32 v[70:71], v[40:41], s[62:63], v[28:29] op_sel:[1,1,0] op_sel_hi:[1,0,1] neg_lo:[0,1,0]
	v_pk_mul_f32 v[26:27], v[46:47], s[66:67] op_sel:[0,0] op_sel_hi:[0,1]
	v_pk_add_f32 v[28:29], v[62:63], v[60:61] neg_lo:[0,1] neg_hi:[0,1]
	v_pk_fma_f32 v[74:75], v[46:47], s[66:67], v[26:27] op_sel:[1,1,0] op_sel_hi:[1,0,1] neg_lo:[0,1,0]
	v_pk_mul_f32 v[26:27], v[38:39], s[68:69] op_sel:[0,0] op_sel_hi:[0,1]
	v_pk_add_f32 v[30:31], v[32:33], v[56:57] neg_lo:[0,1] neg_hi:[0,1]
	v_pk_fma_f32 v[80:81], v[38:39], s[68:69], v[26:27] op_sel:[1,1,0] op_sel_hi:[1,0,1] neg_lo:[0,1,0]
	v_pk_add_f32 v[26:27], v[72:73], v[66:67] neg_lo:[0,1] neg_hi:[0,1]
	v_pk_add_f32 v[38:39], v[72:73], v[66:67]
	v_pk_add_f32 v[40:41], v[26:27], v[28:29] op_sel:[0,1] op_sel_hi:[1,0] neg_lo:[0,1]
	v_pk_add_f32 v[26:27], v[26:27], v[28:29] op_sel:[0,1] op_sel_hi:[1,0] neg_hi:[0,1]
	v_pk_add_f32 v[28:29], v[76:77], v[48:49] neg_lo:[0,1] neg_hi:[0,1]
	v_pk_add_f32 v[44:45], v[76:77], v[48:49]
	v_pk_add_f32 v[48:49], v[32:33], v[56:57]
	v_pk_add_f32 v[46:47], v[28:29], v[30:31] op_sel:[0,1] op_sel_hi:[1,0] neg_lo:[0,1]
	v_pk_add_f32 v[28:29], v[28:29], v[30:31] op_sel:[0,1] op_sel_hi:[1,0] neg_hi:[0,1]
	v_pk_add_f32 v[30:31], v[52:53], v[54:55] neg_lo:[0,1] neg_hi:[0,1]
	v_pk_add_f32 v[54:55], v[68:69], v[58:59]
	v_pk_add_f32 v[32:33], v[68:69], v[58:59] neg_lo:[0,1] neg_hi:[0,1]
	v_pk_add_f32 v[56:57], v[78:79], v[74:75]
	v_pk_add_f32 v[60:61], v[70:71], v[80:81]
	v_pk_add_f32 v[64:65], v[38:39], v[42:43]
	v_pk_add_f32 v[66:67], v[44:45], v[48:49]
	v_pk_add_f32 v[68:69], v[50:51], v[54:55]
	v_pk_add_f32 v[52:53], v[30:31], v[32:33] op_sel:[0,1] op_sel_hi:[1,0] neg_lo:[0,1]
	v_pk_add_f32 v[30:31], v[30:31], v[32:33] op_sel:[0,1] op_sel_hi:[1,0] neg_hi:[0,1]
	v_pk_add_f32 v[32:33], v[78:79], v[74:75] neg_lo:[0,1] neg_hi:[0,1]
	v_pk_add_f32 v[62:63], v[56:57], v[60:61]
	v_pk_add_f32 v[70:71], v[70:71], v[80:81] neg_lo:[0,1] neg_hi:[0,1]
	s_nop 0
	v_pk_add_f32 v[58:59], v[32:33], v[70:71] op_sel:[0,1] op_sel_hi:[1,0] neg_lo:[0,1]
	v_pk_add_f32 v[32:33], v[32:33], v[70:71] op_sel:[0,1] op_sel_hi:[1,0] neg_hi:[0,1]
	s_and_saveexec_b64 s[0:1], s[4:5]
	s_xor_b64 s[0:1], exec, s[0:1]
	s_cbranch_execz .LBB0_3488
	v_mov_b64_e32 v[70:71], s[12:13]
	v_pk_mul_f32 v[72:73], v[36:37], v[70:71] op_sel:[0,0] op_sel_hi:[0,1]
	v_pk_fma_f32 v[70:71], v[36:37], v[70:71], v[72:73] op_sel:[1,1,0] op_sel_hi:[1,0,1] neg_lo:[0,1,0]
	v_pk_mul_f32 v[72:73], v[64:65], v[70:71] op_sel:[0,0] op_sel_hi:[0,1] neg_hi:[0,1]
	v_pk_fma_f32 v[64:65], v[64:65], v[70:71], v[72:73] op_sel:[1,1,0] op_sel_hi:[1,0,1]
	v_pk_mul_f32 v[72:73], v[36:37], s[16:17] op_sel:[0,0] op_sel_hi:[0,1]
	v_pk_fma_f32 v[70:71], v[36:37], s[16:17], v[72:73] op_sel:[1,1,0] op_sel_hi:[1,0,1] neg_lo:[0,1,0]
	v_pk_mul_f32 v[72:73], v[66:67], v[70:71] op_sel:[0,0] op_sel_hi:[0,1] neg_hi:[0,1]
	v_pk_fma_f32 v[66:67], v[66:67], v[70:71], v[72:73] op_sel:[1,1,0] op_sel_hi:[1,0,1]
	v_pk_mul_f32 v[72:73], v[36:37], s[20:21] op_sel:[0,0] op_sel_hi:[0,1]
	v_pk_fma_f32 v[70:71], v[36:37], s[20:21], v[72:73] op_sel:[1,1,0] op_sel_hi:[1,0,1] neg_lo:[0,1,0]
	v_pk_mul_f32 v[72:73], v[68:69], v[70:71] op_sel:[0,0] op_sel_hi:[0,1] neg_hi:[0,1]
	v_pk_fma_f32 v[68:69], v[68:69], v[70:71], v[72:73] op_sel:[1,1,0] op_sel_hi:[1,0,1]
	v_pk_mul_f32 v[72:73], v[36:37], s[22:23] op_sel:[0,0] op_sel_hi:[0,1]
	v_pk_fma_f32 v[70:71], v[36:37], s[22:23], v[72:73] op_sel:[1,1,0] op_sel_hi:[1,0,1] neg_lo:[0,1,0]
	v_pk_mul_f32 v[72:73], v[62:63], v[70:71] op_sel:[0,0] op_sel_hi:[0,1] neg_hi:[0,1]
	v_pk_fma_f32 v[62:63], v[62:63], v[70:71], v[72:73] op_sel:[1,1,0] op_sel_hi:[1,0,1]
	ds_write_b64 v132, v[64:65]
	ds_write_b64 v132, v[66:67] offset:2176
	ds_write_b64 v132, v[68:69] offset:4352
	ds_write_b64 v132, v[62:63] offset:6528
	v_mov_b64_e32 v[62:63], s[46:47]
	v_pk_mul_f32 v[64:65], v[36:37], v[62:63] op_sel:[0,0] op_sel_hi:[0,1]
	s_nop 0
	v_pk_fma_f32 v[62:63], v[36:37], v[62:63], v[64:65] op_sel:[1,1,0] op_sel_hi:[1,0,1] neg_lo:[0,1,0]
	v_pk_mul_f32 v[64:65], v[40:41], v[62:63] op_sel:[0,0] op_sel_hi:[0,1] neg_hi:[0,1]
	v_pk_fma_f32 v[40:41], v[40:41], v[62:63], v[64:65] op_sel:[1,1,0] op_sel_hi:[1,0,1]
	v_pk_mul_f32 v[64:65], v[36:37], s[48:49] op_sel:[0,0] op_sel_hi:[0,1]
	v_pk_fma_f32 v[62:63], v[36:37], s[48:49], v[64:65] op_sel:[1,1,0] op_sel_hi:[1,0,1] neg_lo:[0,1,0]
	v_pk_mul_f32 v[64:65], v[46:47], v[62:63] op_sel:[0,0] op_sel_hi:[0,1] neg_hi:[0,1]
	v_pk_fma_f32 v[46:47], v[46:47], v[62:63], v[64:65] op_sel:[1,1,0] op_sel_hi:[1,0,1]
	v_pk_mul_f32 v[64:65], v[36:37], s[50:51] op_sel:[0,0] op_sel_hi:[0,1]
	v_pk_fma_f32 v[62:63], v[36:37], s[50:51], v[64:65] op_sel:[1,1,0] op_sel_hi:[1,0,1] neg_lo:[0,1,0]
	v_pk_mul_f32 v[64:65], v[52:53], v[62:63] op_sel:[0,0] op_sel_hi:[0,1] neg_hi:[0,1]
	v_pk_fma_f32 v[52:53], v[52:53], v[62:63], v[64:65] op_sel:[1,1,0] op_sel_hi:[1,0,1]
	v_pk_mul_f32 v[64:65], v[36:37], s[52:53] op_sel:[0,0] op_sel_hi:[0,1]
	v_pk_fma_f32 v[62:63], v[36:37], s[52:53], v[64:65] op_sel:[1,1,0] op_sel_hi:[1,0,1] neg_lo:[0,1,0]
	v_pk_mul_f32 v[64:65], v[58:59], v[62:63] op_sel:[0,0] op_sel_hi:[0,1] neg_hi:[0,1]
	s_nop 0
	v_pk_fma_f32 v[58:59], v[58:59], v[62:63], v[64:65] op_sel:[1,1,0] op_sel_hi:[1,0,1]

.LBB0_3490:
	s_or_b64 exec, exec, s[0:1]
	v_pk_add_f32 v[62:63], v[38:39], v[42:43] neg_lo:[0,1] neg_hi:[0,1]
	v_pk_add_f32 v[44:45], v[44:45], v[48:49] neg_lo:[0,1] neg_hi:[0,1]
	v_pk_add_f32 v[42:43], v[50:51], v[54:55] neg_lo:[0,1] neg_hi:[0,1]
	v_pk_add_f32 v[38:39], v[56:57], v[60:61] neg_lo:[0,1] neg_hi:[0,1]
	ds_write_b64 v132, v[40:41] offset:8704
	ds_write_b64 v132, v[46:47] offset:10880
	ds_write_b64 v132, v[52:53] offset:13056
	ds_write_b64 v132, v[58:59] offset:15232
	s_and_saveexec_b64 s[0:1], s[4:5]
	s_xor_b64 s[0:1], exec, s[0:1]
	s_cbranch_execz .LBB0_3492
	v_mov_b64_e32 v[40:41], s[8:9]
	v_pk_mul_f32 v[46:47], v[36:37], v[40:41] op_sel:[0,0] op_sel_hi:[0,1]
	s_mov_b32 s15, s53
	v_pk_fma_f32 v[40:41], v[36:37], v[40:41], v[46:47] op_sel:[1,1,0] op_sel_hi:[1,0,1] neg_lo:[0,1,0]
	s_mov_b32 s4, s23
	v_pk_mul_f32 v[46:47], v[62:63], v[40:41] op_sel:[0,0] op_sel_hi:[0,1] neg_hi:[0,1]
	s_mov_b32 s5, s49
	v_pk_fma_f32 v[40:41], v[62:63], v[40:41], v[46:47] op_sel:[1,1,0] op_sel_hi:[1,0,1]
	v_mov_b64_e32 v[46:47], s[14:15]
	v_pk_mul_f32 v[48:49], v[36:37], v[46:47] op_sel:[0,0] op_sel_hi:[0,1]
	s_nop 0
	v_pk_fma_f32 v[46:47], v[36:37], v[46:47], v[48:49] op_sel:[1,1,0] op_sel_hi:[1,0,1] neg_lo:[0,1,0]
	v_pk_mul_f32 v[48:49], v[44:45], v[46:47] op_sel:[0,0] op_sel_hi:[0,1] neg_hi:[0,1]
	v_pk_fma_f32 v[44:45], v[44:45], v[46:47], v[48:49] op_sel:[1,1,0] op_sel_hi:[1,0,1]
	v_pk_mul_f32 v[48:49], v[36:37], s[18:19] op_sel:[0,0] op_sel_hi:[0,1]
	v_pk_fma_f32 v[46:47], v[36:37], s[18:19], v[48:49] op_sel:[1,1,0] op_sel_hi:[1,0,1] neg_lo:[0,1,0]
	v_pk_mul_f32 v[48:49], v[42:43], v[46:47] op_sel:[0,0] op_sel_hi:[0,1] neg_hi:[0,1]
	v_pk_fma_f32 v[42:43], v[42:43], v[46:47], v[48:49] op_sel:[1,1,0] op_sel_hi:[1,0,1]
	v_mov_b64_e32 v[46:47], s[4:5]
	v_pk_mul_f32 v[48:49], v[36:37], v[46:47] op_sel:[0,0] op_sel_hi:[0,1]
	s_mov_b32 s4, s49
	v_pk_fma_f32 v[46:47], v[36:37], v[46:47], v[48:49] op_sel:[1,1,0] op_sel_hi:[1,0,1] neg_lo:[0,1,0]
	s_mov_b32 s5, s23
	v_pk_mul_f32 v[48:49], v[38:39], v[46:47] op_sel:[0,0] op_sel_hi:[0,1] neg_hi:[0,1]
	v_pk_fma_f32 v[38:39], v[38:39], v[46:47], v[48:49] op_sel:[1,1,0] op_sel_hi:[1,0,1]
	ds_write_b64 v132, v[40:41] offset:17408
	ds_write_b64 v132, v[44:45] offset:19584
	ds_write_b64 v132, v[42:43] offset:21760
	ds_write_b64 v132, v[38:39] offset:23936
	v_mov_b64_e32 v[38:39], s[54:55]
	v_pk_mul_f32 v[40:41], v[36:37], v[38:39] op_sel:[0,0] op_sel_hi:[0,1]
	s_nop 0
	v_pk_fma_f32 v[38:39], v[36:37], v[38:39], v[40:41] op_sel:[1,1,0] op_sel_hi:[1,0,1] neg_lo:[0,1,0]
	v_pk_mul_f32 v[40:41], v[26:27], v[38:39] op_sel:[0,0] op_sel_hi:[0,1] neg_hi:[0,1]
	v_pk_fma_f32 v[26:27], v[26:27], v[38:39], v[40:41] op_sel:[1,1,0] op_sel_hi:[1,0,1]
	v_mov_b64_e32 v[38:39], s[4:5]
	v_pk_mul_f32 v[40:41], v[36:37], v[38:39] op_sel:[0,0] op_sel_hi:[0,1]
	s_mov_b32 s4, s53
	v_pk_fma_f32 v[38:39], v[36:37], v[38:39], v[40:41] op_sel:[1,1,0] op_sel_hi:[1,0,1] neg_lo:[0,1,0]
	s_mov_b32 s5, s14
	v_pk_mul_f32 v[40:41], v[28:29], v[38:39] op_sel:[0,0] op_sel_hi:[0,1] neg_hi:[0,1]
	v_pk_fma_f32 v[28:29], v[28:29], v[38:39], v[40:41] op_sel:[1,1,0] op_sel_hi:[1,0,1]
	v_pk_mul_f32 v[40:41], v[36:37], s[68:69] op_sel:[0,0] op_sel_hi:[0,1]
	v_pk_fma_f32 v[38:39], v[36:37], s[68:69], v[40:41] op_sel:[1,1,0] op_sel_hi:[1,0,1] neg_lo:[0,1,0]
	v_pk_mul_f32 v[40:41], v[30:31], v[38:39] op_sel:[0,0] op_sel_hi:[0,1] neg_hi:[0,1]
	v_pk_fma_f32 v[30:31], v[30:31], v[38:39], v[40:41] op_sel:[1,1,0] op_sel_hi:[1,0,1]
	v_pk_mul_f32 v[40:41], v[36:37], s[4:5] op_sel:[0,0] op_sel_hi:[0,1]
	v_pk_fma_f32 v[36:37], v[36:37], s[4:5], v[40:41] op_sel:[1,1,0] op_sel_hi:[1,0,1] neg_lo:[0,1,0]
	v_pk_mul_f32 v[38:39], v[32:33], v[36:37] op_sel:[0,0] op_sel_hi:[0,1] neg_hi:[0,1]
	s_nop 0
	v_pk_fma_f32 v[32:33], v[32:33], v[36:37], v[38:39] op_sel:[1,1,0] op_sel_hi:[1,0,1]

.LBB0_3752:
	v_ashrrev_i32_e32 v37, 8, v18
	v_and_b32_e32 v34, 0xff, v18
	v_lshlrev_b32_e32 v19, 13, v37
	v_lshlrev_b32_e32 v20, 1, v34
	v_add3_u32 v38, s25, v19, v20
	v_add3_u32 v19, s53, v19, v20
	ds_read_u16 v20, v38
	ds_read_u16 v22, v38 offset:512
	ds_read_u16 v24, v38 offset:1024
	ds_read_u16 v26, v38 offset:1536
	ds_read_u16 v28, v38 offset:2048
	ds_read_u16 v39, v38 offset:2560
	ds_read_u16 v42, v38 offset:3072
	ds_read_u16 v44, v38 offset:3584
	ds_read_u16 v21, v19
	ds_read_u16 v23, v19 offset:512
	ds_read_u16 v25, v19 offset:1024
	ds_read_u16 v27, v19 offset:1536
	ds_read_u16 v29, v19 offset:2048
	ds_read_u16 v41, v19 offset:2560
	ds_read_u16 v43, v19 offset:3072
	ds_read_u16 v45, v19 offset:3584
	s_waitcnt lgkmcnt(7)
	v_lshlrev_b32_e32 v21, 16, v21
	v_lshlrev_b32_e32 v40, 16, v39
	s_waitcnt lgkmcnt(2)
	v_lshlrev_b32_e32 v39, 16, v41
	v_xor_b32_e32 v41, 0x80000000, v39
	s_waitcnt lgkmcnt(1)
	v_lshlrev_b32_e32 v39, 16, v43
	v_xor_b32_e32 v43, 0x80000000, v39
	s_waitcnt lgkmcnt(0)
	v_lshlrev_b32_e32 v39, 16, v45
	v_xor_b32_e32 v45, 0x80000000, v39
	ds_read_u16 v39, v38 offset:4096
	ds_read_u16 v48, v38 offset:4608
	ds_read_u16 v50, v38 offset:5120
	ds_read_u16 v52, v38 offset:5632
	ds_read_u16 v54, v38 offset:6144
	ds_read_u16 v56, v38 offset:6656
	ds_read_u16 v58, v38 offset:7168
	ds_read_u16 v38, v38 offset:7680
	s_waitcnt lgkmcnt(7)
	v_lshlrev_b32_e32 v46, 16, v39
	ds_read_u16 v39, v19 offset:4096
	ds_read_u16 v49, v19 offset:4608
	ds_read_u16 v51, v19 offset:5120
	ds_read_u16 v53, v19 offset:5632
	ds_read_u16 v55, v19 offset:6144
	ds_read_u16 v57, v19 offset:6656
	ds_read_u16 v59, v19 offset:7168
	ds_read_u16 v19, v19 offset:7680
	s_waitcnt lgkmcnt(7)
	v_lshlrev_b32_e32 v39, 16, v39
	v_xor_b32_e32 v47, 0x80000000, v39
	s_waitcnt lgkmcnt(6)
	v_lshlrev_b32_e32 v39, 16, v49
	v_xor_b32_e32 v49, 0x80000000, v39
	s_waitcnt lgkmcnt(5)
	v_lshlrev_b32_e32 v39, 16, v51
	v_xor_b32_e32 v51, 0x80000000, v39
	s_waitcnt lgkmcnt(4)
	v_lshlrev_b32_e32 v39, 16, v53
	v_lshlrev_b32_e32 v29, 16, v29
	v_xor_b32_e32 v53, 0x80000000, v39
	s_waitcnt lgkmcnt(3)
	v_lshlrev_b32_e32 v39, 16, v55
	v_lshlrev_b32_e32 v20, 16, v20
	v_xor_b32_e32 v21, 0x80000000, v21
	v_lshlrev_b32_e32 v23, 16, v23
	v_lshlrev_b32_e32 v28, 16, v28
	v_xor_b32_e32 v29, 0x80000000, v29
	v_lshlrev_b32_e32 v54, 16, v54
	v_xor_b32_e32 v55, 0x80000000, v39
	s_waitcnt lgkmcnt(2)
	v_lshlrev_b32_e32 v39, 16, v57
	s_waitcnt lgkmcnt(0)
	v_lshlrev_b32_e32 v19, 16, v19
	v_lshlrev_b32_e32 v22, 16, v22
	v_xor_b32_e32 v23, 0x80000000, v23
	v_lshlrev_b32_e32 v25, 16, v25
	v_lshlrev_b32_e32 v48, 16, v48
	v_lshlrev_b32_e32 v56, 16, v56
	v_xor_b32_e32 v57, 0x80000000, v39
	v_lshlrev_b32_e32 v39, 16, v59
	v_lshlrev_b32_e32 v60, 16, v38
	v_xor_b32_e32 v61, 0x80000000, v19
	v_bfe_u32 v38, v18, 4, 4
	v_pk_add_f32 v[18:19], v[20:21], v[46:47]
	v_pk_add_f32 v[20:21], v[20:21], v[46:47] neg_lo:[0,1] neg_hi:[0,1]
	v_pk_add_f32 v[46:47], v[28:29], v[54:55]
	v_pk_add_f32 v[28:29], v[28:29], v[54:55] neg_lo:[0,1] neg_hi:[0,1]
	v_lshlrev_b32_e32 v24, 16, v24
	v_xor_b32_e32 v25, 0x80000000, v25
	v_lshlrev_b32_e32 v27, 16, v27
	v_lshlrev_b32_e32 v42, 16, v42
	v_lshlrev_b32_e32 v50, 16, v50
	v_lshlrev_b32_e32 v58, 16, v58
	v_xor_b32_e32 v59, 0x80000000, v39
	v_pk_add_f32 v[54:55], v[18:19], v[46:47]
	v_pk_add_f32 v[46:47], v[18:19], v[46:47] neg_lo:[0,1] neg_hi:[0,1]
	v_pk_add_f32 v[62:63], v[20:21], v[28:29] op_sel:[0,1] op_sel_hi:[1,0] neg_hi:[0,1]
	v_pk_add_f32 v[64:65], v[20:21], v[28:29] op_sel:[0,1] op_sel_hi:[1,0] neg_lo:[0,1]
	v_pk_add_f32 v[18:19], v[22:23], v[48:49]
	v_pk_add_f32 v[20:21], v[22:23], v[48:49] neg_lo:[0,1] neg_hi:[0,1]
	v_pk_add_f32 v[22:23], v[40:41], v[56:57]
	v_pk_add_f32 v[28:29], v[40:41], v[56:57] neg_lo:[0,1] neg_hi:[0,1]
	v_lshlrev_b32_e32 v26, 16, v26
	v_xor_b32_e32 v27, 0x80000000, v27
	v_lshlrev_b32_e32 v44, 16, v44
	v_lshlrev_b32_e32 v52, 16, v52
	v_pk_add_f32 v[40:41], v[18:19], v[22:23]
	v_pk_add_f32 v[22:23], v[18:19], v[22:23] neg_lo:[0,1] neg_hi:[0,1]
	v_pk_add_f32 v[18:19], v[20:21], v[28:29] op_sel:[0,1] op_sel_hi:[1,0] neg_hi:[0,1]
	v_pk_add_f32 v[28:29], v[20:21], v[28:29] op_sel:[0,1] op_sel_hi:[1,0] neg_lo:[0,1]
	v_pk_add_f32 v[20:21], v[24:25], v[50:51]
	v_pk_add_f32 v[24:25], v[24:25], v[50:51] neg_lo:[0,1] neg_hi:[0,1]
	v_pk_add_f32 v[48:49], v[42:43], v[58:59]
	v_pk_add_f32 v[42:43], v[42:43], v[58:59] neg_lo:[0,1] neg_hi:[0,1]
	v_pk_add_f32 v[50:51], v[20:21], v[48:49]
	v_pk_add_f32 v[48:49], v[20:21], v[48:49] neg_lo:[0,1] neg_hi:[0,1]
	v_pk_add_f32 v[56:57], v[24:25], v[42:43] op_sel:[0,1] op_sel_hi:[1,0] neg_hi:[0,1]
	v_pk_add_f32 v[42:43], v[24:25], v[42:43] op_sel:[0,1] op_sel_hi:[1,0] neg_lo:[0,1]
	v_pk_add_f32 v[20:21], v[26:27], v[52:53]
	v_pk_add_f32 v[24:25], v[26:27], v[52:53] neg_lo:[0,1] neg_hi:[0,1]
	v_pk_add_f32 v[26:27], v[44:45], v[60:61]
	v_pk_add_f32 v[44:45], v[44:45], v[60:61] neg_lo:[0,1] neg_hi:[0,1]
	v_pk_add_f32 v[52:53], v[20:21], v[26:27]
	v_pk_add_f32 v[58:59], v[20:21], v[26:27] neg_lo:[0,1] neg_hi:[0,1]
	v_pk_add_f32 v[26:27], v[24:25], v[44:45] op_sel:[0,1] op_sel_hi:[1,0] neg_hi:[0,1]
	v_pk_add_f32 v[44:45], v[24:25], v[44:45] op_sel:[0,1] op_sel_hi:[1,0] neg_lo:[0,1]
	v_pk_mul_f32 v[20:21], v[18:19], s[26:27] op_sel:[0,0] op_sel_hi:[0,1]
	v_mad_i32_i24 v35, v37, s3, 0
	v_pk_fma_f32 v[60:61], v[18:19], s[26:27], v[20:21] op_sel:[1,1,0] op_sel_hi:[1,0,1] neg_lo:[0,1,0]
	v_pk_mul_f32 v[18:19], v[56:57], s[34:35] op_sel:[0,0] op_sel_hi:[0,1]
	v_lshlrev_b32_e32 v39, 3, v34
	v_pk_fma_f32 v[56:57], v[56:57], s[34:35], v[18:19] op_sel:[1,1,0] op_sel_hi:[1,0,1] neg_lo:[0,1,0]
	v_pk_mul_f32 v[66:67], v[26:27], s[36:37] op_sel:[0,0] op_sel_hi:[0,1]
	v_lshlrev_b32_e32 v74, 3, v38
	v_pk_fma_f32 v[66:67], v[26:27], s[36:37], v[66:67] op_sel:[1,1,0] op_sel_hi:[1,0,1] neg_lo:[0,1,0]
	v_pk_mul_f32 v[26:27], v[22:23], s[34:35] op_sel:[0,0] op_sel_hi:[0,1]
	v_add3_u32 v74, v35, v39, v74
	v_pk_fma_f32 v[68:69], v[22:23], s[34:35], v[26:27] op_sel:[1,1,0] op_sel_hi:[1,0,1] neg_lo:[0,1,0]
	v_mov_b64_e32 v[26:27], s[22:23]
	v_pk_mul_f32 v[22:23], v[48:49], v[26:27] op_sel:[0,0] op_sel_hi:[0,1]
	v_lshl_add_u32 v78, v38, 11, v35
	v_pk_fma_f32 v[48:49], v[48:49], v[26:27], v[22:23] op_sel:[1,1,0] op_sel_hi:[1,0,1] neg_lo:[0,1,0]
	v_pk_mul_f32 v[70:71], v[58:59], s[38:39] op_sel:[0,0] op_sel_hi:[0,1]
	v_add_u32_e32 v39, v78, v39
	v_pk_fma_f32 v[58:59], v[58:59], s[38:39], v[70:71] op_sel:[1,1,0] op_sel_hi:[1,0,1] neg_lo:[0,1,0]
	v_pk_mul_f32 v[70:71], v[28:29], s[36:37] op_sel:[0,0] op_sel_hi:[0,1]
	v_pk_fma_f32 v[70:71], v[28:29], s[36:37], v[70:71] op_sel:[1,1,0] op_sel_hi:[1,0,1] neg_lo:[0,1,0]
	v_pk_mul_f32 v[28:29], v[42:43], s[38:39] op_sel:[0,0] op_sel_hi:[0,1]
	v_pk_fma_f32 v[42:43], v[42:43], s[38:39], v[28:29] op_sel:[1,1,0] op_sel_hi:[1,0,1] neg_lo:[0,1,0]
	v_pk_mul_f32 v[72:73], v[44:45], s[40:41] op_sel:[0,0] op_sel_hi:[0,1]
	v_pk_fma_f32 v[44:45], v[44:45], s[40:41], v[72:73] op_sel:[1,1,0] op_sel_hi:[1,0,1] neg_lo:[0,1,0]
	v_pk_add_f32 v[72:73], v[54:55], v[50:51]
	v_pk_add_f32 v[50:51], v[54:55], v[50:51] neg_lo:[0,1] neg_hi:[0,1]
	v_pk_add_f32 v[54:55], v[40:41], v[52:53]
	v_pk_add_f32 v[40:41], v[40:41], v[52:53] neg_lo:[0,1] neg_hi:[0,1]
	v_pk_add_f32 v[52:53], v[72:73], v[54:55]
	v_pk_add_f32 v[54:55], v[72:73], v[54:55] neg_lo:[0,1] neg_hi:[0,1]
	v_pk_add_f32 v[72:73], v[50:51], v[40:41] op_sel:[0,1] op_sel_hi:[1,0] neg_hi:[0,1]
	v_pk_add_f32 v[40:41], v[50:51], v[40:41] op_sel:[0,1] op_sel_hi:[1,0] neg_lo:[0,1]
	v_pk_add_f32 v[50:51], v[62:63], v[56:57]
	v_pk_add_f32 v[56:57], v[62:63], v[56:57] neg_lo:[0,1] neg_hi:[0,1]
	v_pk_add_f32 v[62:63], v[60:61], v[66:67]
	v_pk_add_f32 v[60:61], v[60:61], v[66:67] neg_lo:[0,1] neg_hi:[0,1]
	v_pk_add_f32 v[66:67], v[50:51], v[62:63]
	v_pk_add_f32 v[50:51], v[50:51], v[62:63] neg_lo:[0,1] neg_hi:[0,1]
	v_pk_add_f32 v[62:63], v[56:57], v[60:61] op_sel:[0,1] op_sel_hi:[1,0] neg_hi:[0,1]
	v_pk_add_f32 v[56:57], v[56:57], v[60:61] op_sel:[0,1] op_sel_hi:[1,0] neg_lo:[0,1]
	v_pk_add_f32 v[60:61], v[46:47], v[48:49]
	v_pk_add_f32 v[46:47], v[46:47], v[48:49] neg_lo:[0,1] neg_hi:[0,1]
	v_pk_add_f32 v[48:49], v[68:69], v[58:59]
	v_pk_add_f32 v[58:59], v[68:69], v[58:59] neg_lo:[0,1] neg_hi:[0,1]
	v_pk_add_f32 v[68:69], v[60:61], v[48:49]
	v_pk_add_f32 v[48:49], v[60:61], v[48:49] neg_lo:[0,1] neg_hi:[0,1]
	v_pk_add_f32 v[60:61], v[46:47], v[58:59] op_sel:[0,1] op_sel_hi:[1,0] neg_hi:[0,1]
	v_pk_add_f32 v[46:47], v[46:47], v[58:59] op_sel:[0,1] op_sel_hi:[1,0] neg_lo:[0,1]
	v_pk_add_f32 v[58:59], v[64:65], v[42:43]
	v_pk_add_f32 v[42:43], v[64:65], v[42:43] neg_lo:[0,1] neg_hi:[0,1]
	v_pk_add_f32 v[64:65], v[70:71], v[44:45]
	v_pk_add_f32 v[44:45], v[70:71], v[44:45] neg_lo:[0,1] neg_hi:[0,1]
	v_pk_add_f32 v[70:71], v[58:59], v[64:65]
	v_pk_add_f32 v[58:59], v[58:59], v[64:65] neg_lo:[0,1] neg_hi:[0,1]
	v_pk_add_f32 v[64:65], v[42:43], v[44:45] op_sel:[0,1] op_sel_hi:[1,0] neg_hi:[0,1]
	v_pk_add_f32 v[42:43], v[42:43], v[44:45] op_sel:[0,1] op_sel_hi:[1,0] neg_lo:[0,1]
	v_mov_b32_e32 v45, v31
	v_mov_b32_e32 v44, v1
	ds_write_b64 v74, v[52:53]
	v_pk_mul_f32 v[52:53], v[66:67], v[44:45] op_sel:[0,0] op_sel_hi:[0,1]
	v_pk_fma_f32 v[52:53], v[66:67], v[44:45], v[52:53] op_sel:[1,1,0] op_sel_hi:[1,0,1] neg_lo:[0,1,0]
	ds_write_b64 v74, v[52:53] offset:2176
	v_pk_mul_f32 v[52:53], v[44:45], v[44:45] op_sel:[0,0] op_sel_hi:[0,1]
	v_pk_fma_f32 v[52:53], v[44:45], v[44:45], v[52:53] op_sel:[1,1,0] op_sel_hi:[1,0,1] neg_lo:[0,1,0]
	v_pk_mul_f32 v[66:67], v[68:69], v[52:53] op_sel:[0,0] op_sel_hi:[0,1]
	v_pk_fma_f32 v[66:67], v[68:69], v[52:53], v[66:67] op_sel:[1,1,0] op_sel_hi:[1,0,1] neg_lo:[0,1,0]
	ds_write_b64 v74, v[66:67] offset:4352
	v_pk_mul_f32 v[66:67], v[52:53], v[44:45] op_sel:[0,0] op_sel_hi:[0,1]
	v_pk_fma_f32 v[52:53], v[52:53], v[44:45], v[66:67] op_sel:[1,1,0] op_sel_hi:[1,0,1] neg_lo:[0,1,0]
	v_pk_mul_f32 v[66:67], v[70:71], v[52:53] op_sel:[0,0] op_sel_hi:[0,1]
	v_pk_fma_f32 v[66:67], v[70:71], v[52:53], v[66:67] op_sel:[1,1,0] op_sel_hi:[1,0,1] neg_lo:[0,1,0]
	ds_write_b64 v74, v[66:67] offset:6528
	v_pk_mul_f32 v[66:67], v[52:53], v[44:45] op_sel:[0,0] op_sel_hi:[0,1]
	v_pk_fma_f32 v[52:53], v[52:53], v[44:45], v[66:67] op_sel:[1,1,0] op_sel_hi:[1,0,1] neg_lo:[0,1,0]
	v_pk_mul_f32 v[66:67], v[72:73], v[52:53] op_sel:[0,0] op_sel_hi:[0,1]
	v_pk_fma_f32 v[66:67], v[72:73], v[52:53], v[66:67] op_sel:[1,1,0] op_sel_hi:[1,0,1] neg_lo:[0,1,0]
	ds_write_b64 v74, v[66:67] offset:8704
	v_pk_mul_f32 v[66:67], v[52:53], v[44:45] op_sel:[0,0] op_sel_hi:[0,1]
	v_pk_fma_f32 v[52:53], v[52:53], v[44:45], v[66:67] op_sel:[1,1,0] op_sel_hi:[1,0,1] neg_lo:[0,1,0]
	v_pk_mul_f32 v[66:67], v[62:63], v[52:53] op_sel:[0,0] op_sel_hi:[0,1]
	v_pk_fma_f32 v[62:63], v[62:63], v[52:53], v[66:67] op_sel:[1,1,0] op_sel_hi:[1,0,1] neg_lo:[0,1,0]
	ds_write_b64 v74, v[62:63] offset:10880
	v_pk_mul_f32 v[62:63], v[52:53], v[44:45] op_sel:[0,0] op_sel_hi:[0,1]
	v_pk_fma_f32 v[52:53], v[52:53], v[44:45], v[62:63] op_sel:[1,1,0] op_sel_hi:[1,0,1] neg_lo:[0,1,0]
	v_pk_mul_f32 v[62:63], v[60:61], v[52:53] op_sel:[0,0] op_sel_hi:[0,1]
	v_pk_fma_f32 v[60:61], v[60:61], v[52:53], v[62:63] op_sel:[1,1,0] op_sel_hi:[1,0,1] neg_lo:[0,1,0]
	ds_write_b64 v74, v[60:61] offset:13056
	v_pk_mul_f32 v[60:61], v[52:53], v[44:45] op_sel:[0,0] op_sel_hi:[0,1]
	v_pk_fma_f32 v[52:53], v[52:53], v[44:45], v[60:61] op_sel:[1,1,0] op_sel_hi:[1,0,1] neg_lo:[0,1,0]
	v_pk_mul_f32 v[60:61], v[64:65], v[52:53] op_sel:[0,0] op_sel_hi:[0,1]
	v_pk_fma_f32 v[60:61], v[64:65], v[52:53], v[60:61] op_sel:[1,1,0] op_sel_hi:[1,0,1] neg_lo:[0,1,0]
	ds_write_b64 v74, v[60:61] offset:15232
	v_pk_mul_f32 v[60:61], v[52:53], v[44:45] op_sel:[0,0] op_sel_hi:[0,1]
	v_pk_fma_f32 v[52:53], v[52:53], v[44:45], v[60:61] op_sel:[1,1,0] op_sel_hi:[1,0,1] neg_lo:[0,1,0]
	v_pk_mul_f32 v[60:61], v[54:55], v[52:53] op_sel:[0,0] op_sel_hi:[0,1]
	v_pk_fma_f32 v[54:55], v[54:55], v[52:53], v[60:61] op_sel:[1,1,0] op_sel_hi:[1,0,1] neg_lo:[0,1,0]
	ds_write_b64 v74, v[54:55] offset:17408
	v_pk_mul_f32 v[54:55], v[52:53], v[44:45] op_sel:[0,0] op_sel_hi:[0,1]
	v_pk_fma_f32 v[52:53], v[52:53], v[44:45], v[54:55] op_sel:[1,1,0] op_sel_hi:[1,0,1] neg_lo:[0,1,0]
	v_pk_mul_f32 v[54:55], v[50:51], v[52:53] op_sel:[0,0] op_sel_hi:[0,1]
	v_pk_fma_f32 v[50:51], v[50:51], v[52:53], v[54:55] op_sel:[1,1,0] op_sel_hi:[1,0,1] neg_lo:[0,1,0]
	ds_write_b64 v74, v[50:51] offset:19584
	v_pk_mul_f32 v[50:51], v[52:53], v[44:45] op_sel:[0,0] op_sel_hi:[0,1]
	v_pk_fma_f32 v[50:51], v[52:53], v[44:45], v[50:51] op_sel:[1,1,0] op_sel_hi:[1,0,1] neg_lo:[0,1,0]
	v_pk_mul_f32 v[52:53], v[48:49], v[50:51] op_sel:[0,0] op_sel_hi:[0,1]
	v_pk_fma_f32 v[48:49], v[48:49], v[50:51], v[52:53] op_sel:[1,1,0] op_sel_hi:[1,0,1] neg_lo:[0,1,0]
	ds_write_b64 v74, v[48:49] offset:21760
	v_pk_mul_f32 v[48:49], v[50:51], v[44:45] op_sel:[0,0] op_sel_hi:[0,1]
	v_pk_fma_f32 v[48:49], v[50:51], v[44:45], v[48:49] op_sel:[1,1,0] op_sel_hi:[1,0,1] neg_lo:[0,1,0]
	v_pk_mul_f32 v[50:51], v[58:59], v[48:49] op_sel:[0,0] op_sel_hi:[0,1]
	v_pk_fma_f32 v[50:51], v[58:59], v[48:49], v[50:51] op_sel:[1,1,0] op_sel_hi:[1,0,1] neg_lo:[0,1,0]
	ds_write_b64 v74, v[50:51] offset:23936
	v_pk_mul_f32 v[50:51], v[48:49], v[44:45] op_sel:[0,0] op_sel_hi:[0,1]
	v_pk_fma_f32 v[48:49], v[48:49], v[44:45], v[50:51] op_sel:[1,1,0] op_sel_hi:[1,0,1] neg_lo:[0,1,0]
	v_pk_mul_f32 v[50:51], v[40:41], v[48:49] op_sel:[0,0] op_sel_hi:[0,1]
	v_pk_fma_f32 v[40:41], v[40:41], v[48:49], v[50:51] op_sel:[1,1,0] op_sel_hi:[1,0,1] neg_lo:[0,1,0]
	ds_write_b64 v74, v[40:41] offset:26112
	v_pk_mul_f32 v[40:41], v[48:49], v[44:45] op_sel:[0,0] op_sel_hi:[0,1]
	v_pk_fma_f32 v[40:41], v[48:49], v[44:45], v[40:41] op_sel:[1,1,0] op_sel_hi:[1,0,1] neg_lo:[0,1,0]
	v_pk_mul_f32 v[48:49], v[56:57], v[40:41] op_sel:[0,0] op_sel_hi:[0,1]
	v_pk_fma_f32 v[48:49], v[56:57], v[40:41], v[48:49] op_sel:[1,1,0] op_sel_hi:[1,0,1] neg_lo:[0,1,0]
	ds_write_b64 v74, v[48:49] offset:28288
	v_pk_mul_f32 v[48:49], v[40:41], v[44:45] op_sel:[0,0] op_sel_hi:[0,1]
	v_pk_fma_f32 v[40:41], v[40:41], v[44:45], v[48:49] op_sel:[1,1,0] op_sel_hi:[1,0,1] neg_lo:[0,1,0]
	v_pk_mul_f32 v[48:49], v[46:47], v[40:41] op_sel:[0,0] op_sel_hi:[0,1]
	v_pk_fma_f32 v[46:47], v[46:47], v[40:41], v[48:49] op_sel:[1,1,0] op_sel_hi:[1,0,1] neg_lo:[0,1,0]
	ds_write_b64 v74, v[46:47] offset:30464
	v_pk_mul_f32 v[46:47], v[40:41], v[44:45] op_sel:[0,0] op_sel_hi:[0,1]
	v_pk_fma_f32 v[40:41], v[40:41], v[44:45], v[46:47] op_sel:[1,1,0] op_sel_hi:[1,0,1] neg_lo:[0,1,0]
	v_pk_mul_f32 v[44:45], v[42:43], v[40:41] op_sel:[0,0] op_sel_hi:[0,1]
	v_pk_fma_f32 v[40:41], v[42:43], v[40:41], v[44:45] op_sel:[1,1,0] op_sel_hi:[1,0,1] neg_lo:[0,1,0]
	ds_write_b64 v74, v[40:41] offset:32640
	s_waitcnt lgkmcnt(0)
	s_barrier
	ds_read2_b64 v[40:43], v39 offset1:17
	ds_read2_b64 v[44:47], v39 offset0:34 offset1:51
	ds_read2_b64 v[48:51], v39 offset0:68 offset1:85
	ds_read2_b64 v[52:55], v39 offset0:136 offset1:153
	ds_read2_b64 v[56:59], v39 offset0:102 offset1:119
	ds_read2_b64 v[60:63], v39 offset0:204 offset1:221
	ds_read2_b64 v[64:67], v39 offset0:170 offset1:187
	ds_read2_b64 v[68:71], v39 offset0:238 offset1:255
	s_waitcnt lgkmcnt(4)
	v_pk_add_f32 v[72:73], v[40:41], v[52:53]
	v_pk_add_f32 v[40:41], v[40:41], v[52:53] neg_lo:[0,1] neg_hi:[0,1]
	s_waitcnt lgkmcnt(2)
	v_pk_add_f32 v[52:53], v[48:49], v[60:61]
	v_pk_add_f32 v[48:49], v[48:49], v[60:61] neg_lo:[0,1] neg_hi:[0,1]
	v_pk_add_f32 v[60:61], v[72:73], v[52:53]
	v_pk_add_f32 v[52:53], v[72:73], v[52:53] neg_lo:[0,1] neg_hi:[0,1]
	v_pk_add_f32 v[72:73], v[40:41], v[48:49] op_sel:[0,1] op_sel_hi:[1,0] neg_hi:[0,1]
	v_pk_add_f32 v[40:41], v[40:41], v[48:49] op_sel:[0,1] op_sel_hi:[1,0] neg_lo:[0,1]
	v_pk_add_f32 v[48:49], v[42:43], v[54:55]
	v_pk_add_f32 v[42:43], v[42:43], v[54:55] neg_lo:[0,1] neg_hi:[0,1]
	v_pk_add_f32 v[54:55], v[50:51], v[62:63]
	v_pk_add_f32 v[50:51], v[50:51], v[62:63] neg_lo:[0,1] neg_hi:[0,1]
	v_pk_add_f32 v[62:63], v[48:49], v[54:55]
	v_pk_add_f32 v[48:49], v[48:49], v[54:55] neg_lo:[0,1] neg_hi:[0,1]
	v_pk_add_f32 v[54:55], v[42:43], v[50:51] op_sel:[0,1] op_sel_hi:[1,0] neg_hi:[0,1]
	v_pk_add_f32 v[42:43], v[42:43], v[50:51] op_sel:[0,1] op_sel_hi:[1,0] neg_lo:[0,1]
	s_waitcnt lgkmcnt(1)
	v_pk_add_f32 v[50:51], v[44:45], v[64:65]
	v_pk_add_f32 v[44:45], v[44:45], v[64:65] neg_lo:[0,1] neg_hi:[0,1]
	s_waitcnt lgkmcnt(0)
	v_pk_add_f32 v[64:65], v[56:57], v[68:69]
	v_pk_add_f32 v[56:57], v[56:57], v[68:69] neg_lo:[0,1] neg_hi:[0,1]
	v_pk_add_f32 v[68:69], v[50:51], v[64:65]
	v_pk_add_f32 v[50:51], v[50:51], v[64:65] neg_lo:[0,1] neg_hi:[0,1]
	v_pk_add_f32 v[64:65], v[44:45], v[56:57] op_sel:[0,1] op_sel_hi:[1,0] neg_hi:[0,1]
	v_pk_add_f32 v[44:45], v[44:45], v[56:57] op_sel:[0,1] op_sel_hi:[1,0] neg_lo:[0,1]
	v_pk_add_f32 v[56:57], v[46:47], v[66:67]
	v_pk_add_f32 v[46:47], v[46:47], v[66:67] neg_lo:[0,1] neg_hi:[0,1]
	v_pk_add_f32 v[66:67], v[58:59], v[70:71]
	v_pk_add_f32 v[58:59], v[58:59], v[70:71] neg_lo:[0,1] neg_hi:[0,1]
	v_pk_add_f32 v[70:71], v[56:57], v[66:67]
	v_pk_add_f32 v[56:57], v[56:57], v[66:67] neg_lo:[0,1] neg_hi:[0,1]
	v_pk_add_f32 v[66:67], v[46:47], v[58:59] op_sel:[0,1] op_sel_hi:[1,0] neg_hi:[0,1]
	v_pk_add_f32 v[46:47], v[46:47], v[58:59] op_sel:[0,1] op_sel_hi:[1,0] neg_lo:[0,1]
	v_pk_mul_f32 v[58:59], v[54:55], s[26:27] op_sel:[0,0] op_sel_hi:[0,1]
	v_pk_fma_f32 v[54:55], v[54:55], s[26:27], v[58:59] op_sel:[1,1,0] op_sel_hi:[1,0,1] neg_lo:[0,1,0]
	v_pk_mul_f32 v[58:59], v[64:65], s[34:35] op_sel:[0,0] op_sel_hi:[0,1]
	v_pk_fma_f32 v[58:59], v[64:65], s[34:35], v[58:59] op_sel:[1,1,0] op_sel_hi:[1,0,1] neg_lo:[0,1,0]
	v_pk_mul_f32 v[64:65], v[66:67], s[36:37] op_sel:[0,0] op_sel_hi:[0,1]
	v_pk_fma_f32 v[64:65], v[66:67], s[36:37], v[64:65] op_sel:[1,1,0] op_sel_hi:[1,0,1] neg_lo:[0,1,0]
	v_pk_mul_f32 v[66:67], v[48:49], s[34:35] op_sel:[0,0] op_sel_hi:[0,1]
	v_pk_fma_f32 v[48:49], v[48:49], s[34:35], v[66:67] op_sel:[1,1,0] op_sel_hi:[1,0,1] neg_lo:[0,1,0]
	v_pk_mul_f32 v[66:67], v[50:51], v[26:27] op_sel:[0,0] op_sel_hi:[0,1]
	v_pk_fma_f32 v[50:51], v[50:51], v[26:27], v[66:67] op_sel:[1,1,0] op_sel_hi:[1,0,1] neg_lo:[0,1,0]
	v_pk_mul_f32 v[66:67], v[56:57], s[38:39] op_sel:[0,0] op_sel_hi:[0,1]
	v_pk_fma_f32 v[56:57], v[56:57], s[38:39], v[66:67] op_sel:[1,1,0] op_sel_hi:[1,0,1] neg_lo:[0,1,0]
	v_pk_mul_f32 v[66:67], v[42:43], s[36:37] op_sel:[0,0] op_sel_hi:[0,1]
	v_pk_fma_f32 v[42:43], v[42:43], s[36:37], v[66:67] op_sel:[1,1,0] op_sel_hi:[1,0,1] neg_lo:[0,1,0]
	v_pk_mul_f32 v[66:67], v[44:45], s[38:39] op_sel:[0,0] op_sel_hi:[0,1]
	v_pk_fma_f32 v[44:45], v[44:45], s[38:39], v[66:67] op_sel:[1,1,0] op_sel_hi:[1,0,1] neg_lo:[0,1,0]
	v_pk_mul_f32 v[66:67], v[46:47], s[40:41] op_sel:[0,0] op_sel_hi:[0,1]
	v_pk_fma_f32 v[46:47], v[46:47], s[40:41], v[66:67] op_sel:[1,1,0] op_sel_hi:[1,0,1] neg_lo:[0,1,0]
	v_pk_add_f32 v[66:67], v[60:61], v[68:69]
	v_pk_add_f32 v[60:61], v[60:61], v[68:69] neg_lo:[0,1] neg_hi:[0,1]
	v_pk_add_f32 v[68:69], v[62:63], v[70:71]
	v_pk_add_f32 v[62:63], v[62:63], v[70:71] neg_lo:[0,1] neg_hi:[0,1]
	v_pk_add_f32 v[70:71], v[66:67], v[68:69]
	v_pk_add_f32 v[66:67], v[66:67], v[68:69] neg_lo:[0,1] neg_hi:[0,1]
	v_pk_add_f32 v[68:69], v[60:61], v[62:63] op_sel:[0,1] op_sel_hi:[1,0] neg_hi:[0,1]
	v_pk_add_f32 v[60:61], v[60:61], v[62:63] op_sel:[0,1] op_sel_hi:[1,0] neg_lo:[0,1]
	v_pk_add_f32 v[62:63], v[72:73], v[58:59]
	v_pk_add_f32 v[58:59], v[72:73], v[58:59] neg_lo:[0,1] neg_hi:[0,1]
	v_pk_add_f32 v[72:73], v[54:55], v[64:65]
	v_pk_add_f32 v[54:55], v[54:55], v[64:65] neg_lo:[0,1] neg_hi:[0,1]
	v_pk_add_f32 v[64:65], v[62:63], v[72:73]
	v_pk_add_f32 v[62:63], v[62:63], v[72:73] neg_lo:[0,1] neg_hi:[0,1]
	v_pk_add_f32 v[72:73], v[58:59], v[54:55] op_sel:[0,1] op_sel_hi:[1,0] neg_hi:[0,1]
	v_pk_add_f32 v[54:55], v[58:59], v[54:55] op_sel:[0,1] op_sel_hi:[1,0] neg_lo:[0,1]
	v_pk_add_f32 v[58:59], v[52:53], v[50:51]
	v_pk_add_f32 v[50:51], v[52:53], v[50:51] neg_lo:[0,1] neg_hi:[0,1]
	v_pk_add_f32 v[52:53], v[48:49], v[56:57]
	v_pk_add_f32 v[48:49], v[48:49], v[56:57] neg_lo:[0,1] neg_hi:[0,1]
	v_pk_add_f32 v[56:57], v[58:59], v[52:53]
	v_pk_add_f32 v[52:53], v[58:59], v[52:53] neg_lo:[0,1] neg_hi:[0,1]
	v_pk_add_f32 v[58:59], v[50:51], v[48:49] op_sel:[0,1] op_sel_hi:[1,0] neg_hi:[0,1]
	v_pk_add_f32 v[48:49], v[50:51], v[48:49] op_sel:[0,1] op_sel_hi:[1,0] neg_lo:[0,1]
	v_pk_add_f32 v[50:51], v[40:41], v[44:45]
	v_pk_add_f32 v[40:41], v[40:41], v[44:45] neg_lo:[0,1] neg_hi:[0,1]
	v_pk_add_f32 v[44:45], v[42:43], v[46:47]
	v_pk_add_f32 v[42:43], v[42:43], v[46:47] neg_lo:[0,1] neg_hi:[0,1]
	v_pk_add_f32 v[46:47], v[50:51], v[44:45]
	v_pk_add_f32 v[44:45], v[50:51], v[44:45] neg_lo:[0,1] neg_hi:[0,1]
	v_pk_add_f32 v[50:51], v[40:41], v[42:43] op_sel:[0,1] op_sel_hi:[1,0] neg_hi:[0,1]
	v_pk_add_f32 v[40:41], v[40:41], v[42:43] op_sel:[0,1] op_sel_hi:[1,0] neg_lo:[0,1]
	v_mov_b32_e32 v42, v30
	v_mov_b32_e32 v43, v32
	s_nop 0
	v_pk_mul_f32 v[74:75], v[64:65], v[42:43] op_sel:[0,0] op_sel_hi:[0,1]
	v_pk_fma_f32 v[64:65], v[64:65], v[42:43], v[74:75] op_sel:[1,1,0] op_sel_hi:[1,0,1] neg_lo:[0,1,0]
	ds_write2_b64 v39, v[70:71], v[64:65] offset1:17
	v_pk_mul_f32 v[64:65], v[42:43], v[42:43] op_sel:[0,0] op_sel_hi:[0,1]
	v_pk_fma_f32 v[64:65], v[42:43], v[42:43], v[64:65] op_sel:[1,1,0] op_sel_hi:[1,0,1] neg_lo:[0,1,0]
	v_pk_mul_f32 v[70:71], v[56:57], v[64:65] op_sel:[0,0] op_sel_hi:[0,1]
	v_pk_fma_f32 v[56:57], v[56:57], v[64:65], v[70:71] op_sel:[1,1,0] op_sel_hi:[1,0,1] neg_lo:[0,1,0]
	v_pk_mul_f32 v[70:71], v[64:65], v[42:43] op_sel:[0,0] op_sel_hi:[0,1]
	v_pk_fma_f32 v[64:65], v[64:65], v[42:43], v[70:71] op_sel:[1,1,0] op_sel_hi:[1,0,1] neg_lo:[0,1,0]
	v_pk_mul_f32 v[70:71], v[46:47], v[64:65] op_sel:[0,0] op_sel_hi:[0,1]
	v_pk_fma_f32 v[46:47], v[46:47], v[64:65], v[70:71] op_sel:[1,1,0] op_sel_hi:[1,0,1] neg_lo:[0,1,0]
	ds_write2_b64 v39, v[56:57], v[46:47] offset0:34 offset1:51
	v_pk_mul_f32 v[46:47], v[64:65], v[42:43] op_sel:[0,0] op_sel_hi:[0,1]
	v_pk_fma_f32 v[46:47], v[64:65], v[42:43], v[46:47] op_sel:[1,1,0] op_sel_hi:[1,0,1] neg_lo:[0,1,0]
	v_pk_mul_f32 v[56:57], v[68:69], v[46:47] op_sel:[0,0] op_sel_hi:[0,1]
	v_pk_mul_f32 v[64:65], v[46:47], v[42:43] op_sel:[0,0] op_sel_hi:[0,1]
	v_pk_fma_f32 v[56:57], v[68:69], v[46:47], v[56:57] op_sel:[1,1,0] op_sel_hi:[1,0,1] neg_lo:[0,1,0]
	v_pk_fma_f32 v[46:47], v[46:47], v[42:43], v[64:65] op_sel:[1,1,0] op_sel_hi:[1,0,1] neg_lo:[0,1,0]
	v_pk_mul_f32 v[64:65], v[72:73], v[46:47] op_sel:[0,0] op_sel_hi:[0,1]
	v_pk_fma_f32 v[64:65], v[72:73], v[46:47], v[64:65] op_sel:[1,1,0] op_sel_hi:[1,0,1] neg_lo:[0,1,0]
	ds_write2_b64 v39, v[56:57], v[64:65] offset0:68 offset1:85
	v_pk_mul_f32 v[56:57], v[46:47], v[42:43] op_sel:[0,0] op_sel_hi:[0,1]
	v_pk_fma_f32 v[46:47], v[46:47], v[42:43], v[56:57] op_sel:[1,1,0] op_sel_hi:[1,0,1] neg_lo:[0,1,0]
	v_pk_mul_f32 v[56:57], v[58:59], v[46:47] op_sel:[0,0] op_sel_hi:[0,1]
	v_pk_fma_f32 v[56:57], v[58:59], v[46:47], v[56:57] op_sel:[1,1,0] op_sel_hi:[1,0,1] neg_lo:[0,1,0]
	v_pk_mul_f32 v[58:59], v[46:47], v[42:43] op_sel:[0,0] op_sel_hi:[0,1]
	v_pk_fma_f32 v[46:47], v[46:47], v[42:43], v[58:59] op_sel:[1,1,0] op_sel_hi:[1,0,1] neg_lo:[0,1,0]
	v_pk_mul_f32 v[58:59], v[50:51], v[46:47] op_sel:[0,0] op_sel_hi:[0,1]
	v_pk_fma_f32 v[50:51], v[50:51], v[46:47], v[58:59] op_sel:[1,1,0] op_sel_hi:[1,0,1] neg_lo:[0,1,0]
	ds_write2_b64 v39, v[56:57], v[50:51] offset0:102 offset1:119
	v_pk_mul_f32 v[50:51], v[46:47], v[42:43] op_sel:[0,0] op_sel_hi:[0,1]
	v_pk_fma_f32 v[46:47], v[46:47], v[42:43], v[50:51] op_sel:[1,1,0] op_sel_hi:[1,0,1] neg_lo:[0,1,0]
	v_pk_mul_f32 v[50:51], v[66:67], v[46:47] op_sel:[0,0] op_sel_hi:[0,1]
	v_pk_mul_f32 v[56:57], v[46:47], v[42:43] op_sel:[0,0] op_sel_hi:[0,1]
	v_pk_fma_f32 v[50:51], v[66:67], v[46:47], v[50:51] op_sel:[1,1,0] op_sel_hi:[1,0,1] neg_lo:[0,1,0]
	v_pk_fma_f32 v[46:47], v[46:47], v[42:43], v[56:57] op_sel:[1,1,0] op_sel_hi:[1,0,1] neg_lo:[0,1,0]
	v_pk_mul_f32 v[56:57], v[62:63], v[46:47] op_sel:[0,0] op_sel_hi:[0,1]
	v_pk_fma_f32 v[56:57], v[62:63], v[46:47], v[56:57] op_sel:[1,1,0] op_sel_hi:[1,0,1] neg_lo:[0,1,0]
	ds_write2_b64 v39, v[50:51], v[56:57] offset0:136 offset1:153
	v_pk_mul_f32 v[50:51], v[46:47], v[42:43] op_sel:[0,0] op_sel_hi:[0,1]
	v_pk_fma_f32 v[46:47], v[46:47], v[42:43], v[50:51] op_sel:[1,1,0] op_sel_hi:[1,0,1] neg_lo:[0,1,0]
	v_pk_mul_f32 v[50:51], v[52:53], v[46:47] op_sel:[0,0] op_sel_hi:[0,1]
	v_pk_fma_f32 v[50:51], v[52:53], v[46:47], v[50:51] op_sel:[1,1,0] op_sel_hi:[1,0,1] neg_lo:[0,1,0]
	v_pk_mul_f32 v[52:53], v[46:47], v[42:43] op_sel:[0,0] op_sel_hi:[0,1]
	v_pk_fma_f32 v[46:47], v[46:47], v[42:43], v[52:53] op_sel:[1,1,0] op_sel_hi:[1,0,1] neg_lo:[0,1,0]
	v_pk_mul_f32 v[52:53], v[44:45], v[46:47] op_sel:[0,0] op_sel_hi:[0,1]
	v_pk_fma_f32 v[44:45], v[44:45], v[46:47], v[52:53] op_sel:[1,1,0] op_sel_hi:[1,0,1] neg_lo:[0,1,0]
	ds_write2_b64 v39, v[50:51], v[44:45] offset0:170 offset1:187
	v_pk_mul_f32 v[44:45], v[46:47], v[42:43] op_sel:[0,0] op_sel_hi:[0,1]
	v_pk_fma_f32 v[44:45], v[46:47], v[42:43], v[44:45] op_sel:[1,1,0] op_sel_hi:[1,0,1] neg_lo:[0,1,0]
	v_pk_mul_f32 v[46:47], v[60:61], v[44:45] op_sel:[0,0] op_sel_hi:[0,1]
	v_pk_mul_f32 v[50:51], v[44:45], v[42:43] op_sel:[0,0] op_sel_hi:[0,1]
	v_pk_fma_f32 v[46:47], v[60:61], v[44:45], v[46:47] op_sel:[1,1,0] op_sel_hi:[1,0,1] neg_lo:[0,1,0]
	v_pk_fma_f32 v[44:45], v[44:45], v[42:43], v[50:51] op_sel:[1,1,0] op_sel_hi:[1,0,1] neg_lo:[0,1,0]
	v_pk_mul_f32 v[50:51], v[54:55], v[44:45] op_sel:[0,0] op_sel_hi:[0,1]
	v_pk_fma_f32 v[50:51], v[54:55], v[44:45], v[50:51] op_sel:[1,1,0] op_sel_hi:[1,0,1] neg_lo:[0,1,0]
	ds_write2_b64 v39, v[46:47], v[50:51] offset0:204 offset1:221
	v_pk_mul_f32 v[46:47], v[44:45], v[42:43] op_sel:[0,0] op_sel_hi:[0,1]
	v_pk_fma_f32 v[44:45], v[44:45], v[42:43], v[46:47] op_sel:[1,1,0] op_sel_hi:[1,0,1] neg_lo:[0,1,0]
	v_pk_mul_f32 v[46:47], v[48:49], v[44:45] op_sel:[0,0] op_sel_hi:[0,1]
	v_pk_fma_f32 v[46:47], v[48:49], v[44:45], v[46:47] op_sel:[1,1,0] op_sel_hi:[1,0,1] neg_lo:[0,1,0]
	v_pk_mul_f32 v[48:49], v[44:45], v[42:43] op_sel:[0,0] op_sel_hi:[0,1]
	v_pk_fma_f32 v[42:43], v[44:45], v[42:43], v[48:49] op_sel:[1,1,0] op_sel_hi:[1,0,1] neg_lo:[0,1,0]
	v_pk_mul_f32 v[44:45], v[40:41], v[42:43] op_sel:[0,0] op_sel_hi:[0,1]
	v_pk_fma_f32 v[40:41], v[40:41], v[42:43], v[44:45] op_sel:[1,1,0] op_sel_hi:[1,0,1] neg_lo:[0,1,0]
	ds_write2_b64 v39, v[46:47], v[40:41] offset0:238 offset1:255
	v_mad_u32_u24 v39, v34, s54, v35
	s_waitcnt lgkmcnt(0)
	s_barrier
	ds_read2_b64 v[40:43], v39 offset1:1
	ds_read2_b64 v[44:47], v39 offset0:2 offset1:3
	ds_read2_b64 v[48:51], v39 offset0:8 offset1:9
	ds_read2_b64 v[52:55], v39 offset0:4 offset1:5
	ds_read2_b64 v[56:59], v39 offset0:6 offset1:7
	ds_read2_b64 v[60:63], v39 offset0:12 offset1:13
	ds_read2_b64 v[64:67], v39 offset0:10 offset1:11
	ds_read2_b64 v[68:71], v39 offset0:14 offset1:15
	s_waitcnt lgkmcnt(5)
	v_pk_add_f32 v[72:73], v[40:41], v[48:49]
	v_pk_add_f32 v[40:41], v[40:41], v[48:49] neg_lo:[0,1] neg_hi:[0,1]
	s_waitcnt lgkmcnt(2)
	v_pk_add_f32 v[48:49], v[52:53], v[60:61]
	v_pk_add_f32 v[52:53], v[52:53], v[60:61] neg_lo:[0,1] neg_hi:[0,1]
	v_pk_add_f32 v[60:61], v[72:73], v[48:49]
	v_pk_add_f32 v[48:49], v[72:73], v[48:49] neg_lo:[0,1] neg_hi:[0,1]
	v_pk_add_f32 v[72:73], v[40:41], v[52:53] op_sel:[0,1] op_sel_hi:[1,0] neg_hi:[0,1]
	v_pk_add_f32 v[40:41], v[40:41], v[52:53] op_sel:[0,1] op_sel_hi:[1,0] neg_lo:[0,1]
	v_pk_add_f32 v[52:53], v[42:43], v[50:51]
	v_pk_add_f32 v[42:43], v[42:43], v[50:51] neg_lo:[0,1] neg_hi:[0,1]
	v_pk_add_f32 v[50:51], v[54:55], v[62:63]
	v_pk_add_f32 v[54:55], v[54:55], v[62:63] neg_lo:[0,1] neg_hi:[0,1]
	v_pk_add_f32 v[62:63], v[52:53], v[50:51]
	v_pk_add_f32 v[50:51], v[52:53], v[50:51] neg_lo:[0,1] neg_hi:[0,1]
	v_pk_add_f32 v[52:53], v[42:43], v[54:55] op_sel:[0,1] op_sel_hi:[1,0] neg_hi:[0,1]
	v_pk_add_f32 v[42:43], v[42:43], v[54:55] op_sel:[0,1] op_sel_hi:[1,0] neg_lo:[0,1]
	s_waitcnt lgkmcnt(1)
	v_pk_add_f32 v[54:55], v[44:45], v[64:65]
	v_pk_add_f32 v[44:45], v[44:45], v[64:65] neg_lo:[0,1] neg_hi:[0,1]
	s_waitcnt lgkmcnt(0)
	v_pk_add_f32 v[64:65], v[56:57], v[68:69]
	v_pk_add_f32 v[56:57], v[56:57], v[68:69] neg_lo:[0,1] neg_hi:[0,1]
	v_pk_add_f32 v[68:69], v[54:55], v[64:65]
	v_pk_add_f32 v[54:55], v[54:55], v[64:65] neg_lo:[0,1] neg_hi:[0,1]
	v_pk_add_f32 v[64:65], v[44:45], v[56:57] op_sel:[0,1] op_sel_hi:[1,0] neg_hi:[0,1]
	v_pk_add_f32 v[44:45], v[44:45], v[56:57] op_sel:[0,1] op_sel_hi:[1,0] neg_lo:[0,1]
	v_pk_add_f32 v[56:57], v[46:47], v[66:67]
	v_pk_add_f32 v[46:47], v[46:47], v[66:67] neg_lo:[0,1] neg_hi:[0,1]
	v_pk_add_f32 v[66:67], v[58:59], v[70:71]
	v_pk_add_f32 v[58:59], v[58:59], v[70:71] neg_lo:[0,1] neg_hi:[0,1]
	v_pk_add_f32 v[70:71], v[56:57], v[66:67]
	v_pk_add_f32 v[56:57], v[56:57], v[66:67] neg_lo:[0,1] neg_hi:[0,1]
	v_pk_add_f32 v[66:67], v[46:47], v[58:59] op_sel:[0,1] op_sel_hi:[1,0] neg_hi:[0,1]
	v_pk_add_f32 v[46:47], v[46:47], v[58:59] op_sel:[0,1] op_sel_hi:[1,0] neg_lo:[0,1]
	v_pk_mul_f32 v[58:59], v[52:53], s[26:27] op_sel:[0,0] op_sel_hi:[0,1]
	v_pk_fma_f32 v[24:25], v[52:53], s[26:27], v[58:59] op_sel:[1,1,0] op_sel_hi:[1,0,1] neg_lo:[0,1,0]
	v_pk_mul_f32 v[52:53], v[64:65], s[34:35] op_sel:[0,0] op_sel_hi:[0,1]
	v_pk_mul_f32 v[58:59], v[66:67], s[36:37] op_sel:[0,0] op_sel_hi:[0,1]
	s_barrier
	v_pk_fma_f32 v[52:53], v[64:65], s[34:35], v[52:53] op_sel:[1,1,0] op_sel_hi:[1,0,1] neg_lo:[0,1,0]
	v_pk_mul_f32 v[64:65], v[50:51], s[34:35] op_sel:[0,0] op_sel_hi:[0,1]
	v_pk_fma_f32 v[58:59], v[66:67], s[36:37], v[58:59] op_sel:[1,1,0] op_sel_hi:[1,0,1] neg_lo:[0,1,0]
	v_pk_fma_f32 v[20:21], v[50:51], s[34:35], v[64:65] op_sel:[1,1,0] op_sel_hi:[1,0,1] neg_lo:[0,1,0]
	v_pk_mul_f32 v[50:51], v[54:55], v[26:27] op_sel:[0,0] op_sel_hi:[0,1]
	v_pk_fma_f32 v[26:27], v[54:55], v[26:27], v[50:51] op_sel:[1,1,0] op_sel_hi:[1,0,1] neg_lo:[0,1,0]
	v_pk_mul_f32 v[50:51], v[56:57], s[38:39] op_sel:[0,0] op_sel_hi:[0,1]
	v_pk_mul_f32 v[54:55], v[42:43], s[36:37] op_sel:[0,0] op_sel_hi:[0,1]
	v_pk_fma_f32 v[18:19], v[42:43], s[36:37], v[54:55] op_sel:[1,1,0] op_sel_hi:[1,0,1] neg_lo:[0,1,0]
	v_pk_mul_f32 v[42:43], v[44:45], s[38:39] op_sel:[0,0] op_sel_hi:[0,1]
	v_pk_fma_f32 v[50:51], v[56:57], s[38:39], v[50:51] op_sel:[1,1,0] op_sel_hi:[1,0,1] neg_lo:[0,1,0]
	v_pk_add_f32 v[54:55], v[24:25], v[58:59] neg_lo:[0,1] neg_hi:[0,1]
	v_pk_fma_f32 v[22:23], v[44:45], s[38:39], v[42:43] op_sel:[1,1,0] op_sel_hi:[1,0,1] neg_lo:[0,1,0]
	v_pk_mul_f32 v[42:43], v[46:47], s[40:41] op_sel:[0,0] op_sel_hi:[0,1]
	v_pk_add_f32 v[44:45], v[62:63], v[70:71] neg_lo:[0,1] neg_hi:[0,1]
	v_pk_fma_f32 v[28:29], v[46:47], s[40:41], v[42:43] op_sel:[1,1,0] op_sel_hi:[1,0,1] neg_lo:[0,1,0]
	v_pk_add_f32 v[42:43], v[60:61], v[68:69] neg_lo:[0,1] neg_hi:[0,1]
	v_pk_add_f32 v[74:75], v[18:19], v[28:29] neg_lo:[0,1] neg_hi:[0,1]
	v_pk_add_f32 v[46:47], v[42:43], v[44:45] op_sel:[0,1] op_sel_hi:[1,0] neg_hi:[0,1]
	v_pk_add_f32 v[42:43], v[42:43], v[44:45] op_sel:[0,1] op_sel_hi:[1,0] neg_lo:[0,1]
	v_pk_add_f32 v[44:45], v[72:73], v[52:53] neg_lo:[0,1] neg_hi:[0,1]
	v_and_b32_e32 v19, 0xf0, v36
	v_pk_add_f32 v[56:57], v[44:45], v[54:55] op_sel:[0,1] op_sel_hi:[1,0] neg_hi:[0,1]
	v_pk_add_f32 v[44:45], v[44:45], v[54:55] op_sel:[0,1] op_sel_hi:[1,0] neg_lo:[0,1]
	v_pk_add_f32 v[54:55], v[48:49], v[26:27] neg_lo:[0,1] neg_hi:[0,1]
	v_pk_add_f32 v[64:65], v[20:21], v[50:51] neg_lo:[0,1] neg_hi:[0,1]
	v_mul_i32_i24_e32 v21, 0xfffff804, v38
	v_lshlrev_b32_e32 v19, 2, v19
	v_pk_add_f32 v[66:67], v[54:55], v[64:65] op_sel:[0,1] op_sel_hi:[1,0] neg_hi:[0,1]
	v_pk_add_f32 v[54:55], v[54:55], v[64:65] op_sel:[0,1] op_sel_hi:[1,0] neg_lo:[0,1]
	v_pk_add_f32 v[64:65], v[40:41], v[22:23] neg_lo:[0,1] neg_hi:[0,1]
	v_add3_u32 v19, v78, v21, v19
	v_add_f32_e32 v21, v62, v70
	v_add_f32_e32 v23, v60, v68
	v_add_f32_e32 v24, v24, v58
	v_add_f32_e32 v27, v72, v52
	v_add_f32_e32 v25, v23, v21
	v_add_f32_e32 v29, v27, v24
	v_mul_f32_e32 v25, 0x3a800000, v25
	v_mul_f32_e32 v29, 0x3a800000, v29
	ds_write2st64_b32 v19, v25, v29 offset1:4
	v_add_f32_e32 v20, v20, v50
	v_add_f32_e32 v25, v48, v26
	v_add_f32_e32 v18, v18, v28
	v_add_f32_e32 v22, v40, v22
	v_add_f32_e32 v26, v25, v20
	v_add_f32_e32 v28, v22, v18
	v_sub_f32_e32 v20, v25, v20
	v_sub_f32_e32 v18, v22, v18
	v_mul_f32_e32 v26, 0x3a800000, v26
	v_mul_f32_e32 v28, 0x3a800000, v28
	v_mul_f32_e32 v20, 0x3a800000, v20
	v_mul_f32_e32 v18, 0x3a800000, v18
	ds_write2st64_b32 v19, v26, v28 offset0:8 offset1:12
	v_mul_f32_e32 v26, 0x3a800000, v46
	v_mul_f32_e32 v28, 0x3a800000, v56
	v_sub_f32_e32 v21, v23, v21
	v_sub_f32_e32 v23, v27, v24
	ds_write2st64_b32 v19, v20, v18 offset0:40 offset1:44
	v_mul_f32_e32 v18, 0x3a800000, v42
	v_mul_f32_e32 v20, 0x3a800000, v44
	v_pk_add_f32 v[76:77], v[64:65], v[74:75] op_sel:[0,1] op_sel_hi:[1,0] neg_hi:[0,1]
	v_pk_add_f32 v[64:65], v[64:65], v[74:75] op_sel:[0,1] op_sel_hi:[1,0] neg_lo:[0,1]
	ds_write2st64_b32 v19, v26, v28 offset0:16 offset1:20
	v_mul_f32_e32 v26, 0x3a800000, v66
	v_mul_f32_e32 v28, 0x3a800000, v76
	v_mul_f32_e32 v21, 0x3a800000, v21
	v_mul_f32_e32 v23, 0x3a800000, v23
	ds_write2st64_b32 v19, v18, v20 offset0:48 offset1:52
	v_mul_f32_e32 v18, 0x3a800000, v54
	v_mul_f32_e32 v20, 0x3a800000, v64
	v_mov_b32_e32 v22, v34
	ds_write2st64_b32 v19, v26, v28 offset0:24 offset1:28
	ds_write2st64_b32 v19, v21, v23 offset0:32 offset1:36
	ds_write2st64_b32 v19, v18, v20 offset0:56 offset1:60
	s_waitcnt lgkmcnt(0)
	s_barrier
	v_lshlrev_b32_e32 v26, 12, v37
	v_lshl_add_u32 v23, v22, 5, v35
	ds_read_b128 v[18:21], v23
	v_lshlrev_b32_e32 v28, 3, v22
	ds_read_b128 v[22:25], v23 offset:16
	v_ashrrev_i32_e32 v27, 31, v26
	v_lshlrev_b64 v[26:27], 1, v[26:27]
	s_waitcnt lgkmcnt(1)
	v_cvt_pk_bf16_f32 v18, v18, v18
	v_lshrrev_b32_e32 v18, 16, v18
	v_cvt_pk_bf16_f32 v19, v19, v19
	v_and_or_b32 v18, v19, s56, v18
	v_cvt_pk_bf16_f32 v19, v20, v21
	s_waitcnt lgkmcnt(0)
	v_cvt_pk_bf16_f32 v20, v22, v23
	v_cvt_pk_bf16_f32 v21, v24, v25
	v_ashrrev_i32_e32 v29, 31, v28
	v_lshl_add_u64 v[22:23], v[28:29], 1, v[26:27]
	v_lshl_add_u64 v[22:23], s[6:7], 0, v[22:23]
	global_store_dwordx4 v[22:23], v[18:21], off
	s_nop 0
	v_lshl_add_u32 v22, v34, 5, v35
	ds_read_b128 v[18:21], v22 offset:8192
	ds_read_b128 v[22:25], v22 offset:8208
	v_lshl_add_u32 v28, v34, 3, v33
	s_waitcnt lgkmcnt(1)
	v_cvt_pk_bf16_f32 v18, v18, v18
	v_lshrrev_b32_e32 v18, 16, v18
	v_cvt_pk_bf16_f32 v19, v19, v19
	v_and_or_b32 v18, v19, s56, v18
	v_cvt_pk_bf16_f32 v19, v20, v21
	s_waitcnt lgkmcnt(0)
	v_cvt_pk_bf16_f32 v20, v22, v23
	v_cvt_pk_bf16_f32 v21, v24, v25
	v_ashrrev_i32_e32 v29, 31, v28
	v_lshl_add_u64 v[22:23], v[28:29], 1, v[26:27]
	v_lshl_add_u64 v[22:23], s[6:7], 0, v[22:23]
	s_add_u32 s6, s6, s20
	s_addc_u32 s7, s7, s21
	s_and_b64 vcc, exec, s[44:45]
	global_store_dwordx4 v[22:23], v[18:21], off
	s_barrier
	s_cbranch_vccnz .LBB0_3755
